# GEMM phases: LDS-DMA pieces in saddr form (tile bases advanced in SGPRs per k-step), 8 fewer 64-bit VALU adds per k-step per wave
# speedup vs baseline: 1.0571x; 1.0098x over previous
.LBB0_121:
	s_mul_hi_i32 s10, s68, 0x2aaaaaab
	s_lshr_b32 s11, s10, 31
	s_ashr_i32 s10, s10, 2
	s_add_i32 s11, s10, s11
	s_lshl_b32 s10, s11, 7
	s_mul_i32 s14, s11, 0xffffffe8
	s_mulk_i32 s11, 0xf400
	s_add_i32 s69, s68, s14
	s_add_i32 s14, s3, s11
	s_ashr_i32 s11, s10, 31
	v_readlane_b32 s72, v245, 37
	s_lshl_b64 s[28:29], s[10:11], 11
	v_readlane_b32 s84, v245, 49
	v_readlane_b32 s73, v245, 38
	v_readlane_b32 s74, v245, 39
	v_readlane_b32 s75, v245, 40
	v_readlane_b32 s76, v245, 41
	v_readlane_b32 s77, v245, 42
	v_readlane_b32 s78, v245, 43
	v_readlane_b32 s79, v245, 44
	v_readlane_b32 s80, v245, 45
	v_readlane_b32 s81, v245, 46
	v_readlane_b32 s82, v245, 47
	v_readlane_b32 s83, v245, 48
	v_readlane_b32 s85, v245, 50
	v_readlane_b32 s86, v245, 51
	v_readlane_b32 s87, v245, 52
	s_add_u32 s28, s84, s28
	s_addc_u32 s29, s85, s29
	s_ashr_i32 s15, s14, 31
	v_readlane_b32 s72, v245, 21
	s_lshl_b64 s[30:31], s[14:15], 11
	v_readlane_b32 s86, v245, 35
	v_readlane_b32 s87, v245, 36
	s_add_u32 s30, s86, s30
	s_addc_u32 s31, s87, s31
	v_readfirstlane_b32 s70, v92
	v_mov_b32_e32 v2, s31
	v_mov_b32_e32 v3, s29
	v_mov_b32_e32 v4, s30
	v_mov_b32_e32 v5, s28
	s_add_u32 s98, s28, 0x80
	s_addc_u32 s99, s29, 0
	v_lshl_add_u64 v[76:77], s[28:29], 0, v[64:65]
	s_mov_b32 m0, s70
	v_cndmask_b32_e64 v1, v2, v3, s[4:5]
	v_cndmask_b32_e64 v0, v4, v5, s[4:5]
	v_readfirstlane_b32 s71, v95
	v_readlane_b32 s78, v245, 27
	global_load_lds_dwordx4 v[76:77], off
	v_lshl_add_u64 v[78:79], v[0:1], 0, v[66:67]
	s_mov_b32 m0, s71
	v_cndmask_b32_e64 v1, v2, v3, s[6:7]
	v_cndmask_b32_e64 v0, v4, v5, s[6:7]
	v_readfirstlane_b32 s72, v96
	v_readlane_b32 s79, v245, 28
	global_load_lds_dwordx4 v[78:79], off
	v_lshl_add_u64 v[80:81], v[0:1], 0, v[68:69]
	s_mov_b32 m0, s72
	v_cndmask_b32_e64 v1, v2, v3, s[8:9]
	v_cndmask_b32_e64 v0, v4, v5, s[8:9]
	v_readfirstlane_b32 s78, v97
	v_readlane_b32 s80, v245, 29
	global_load_lds_dwordx4 v[80:81], off
	v_lshl_add_u64 v[84:85], v[0:1], 0, v[70:71]
	s_mov_b32 m0, s78
	v_readfirstlane_b32 s79, v98
	v_readlane_b32 s81, v245, 30
	global_load_lds_dwordx4 v[84:85], off
	s_add_u32 s100, s30, 0x80
	s_addc_u32 s101, s31, 0
	v_lshl_add_u64 v[86:87], s[30:31], 0, v[64:65]
	s_mov_b32 m0, s79
	v_readfirstlane_b32 s80, v99
	v_readlane_b32 s73, v245, 22
	global_load_lds_dwordx4 v[86:87], off
	v_lshl_add_u64 v[88:89], s[30:31], 0, v[66:67]
	s_mov_b32 m0, s80
	v_readfirstlane_b32 s81, v100
	global_load_lds_dwordx4 v[88:89], off
	v_lshl_add_u64 v[90:91], s[30:31], 0, v[68:69]
	s_mov_b32 m0, s81
	v_readfirstlane_b32 s73, v101
	global_load_lds_dwordx4 v[90:91], off
	v_lshl_add_u64 v[82:83], s[30:31], 0, v[70:71]
	s_mov_b32 m0, s73
	v_readfirstlane_b32 s11, v102
	global_load_lds_dwordx4 v[82:83], off
	s_mov_b32 m0, s11
	v_readfirstlane_b32 s15, v103
	s_waitcnt vmcnt(0)
	s_waitcnt vmcnt(0) lgkmcnt(0)
	s_barrier
	global_load_lds_dwordx4 v64, s[98:99]
	s_mov_b32 m0, s15
	v_readfirstlane_b32 s28, v104
	global_load_lds_dwordx4 v66, s[98:99]
	s_mov_b32 m0, s28
	v_readfirstlane_b32 s29, v105
	global_load_lds_dwordx4 v68, s[98:99]
	s_mov_b32 m0, s29
	v_readfirstlane_b32 s30, v106
	global_load_lds_dwordx4 v70, s[98:99]
	s_mov_b32 m0, s30
	v_readfirstlane_b32 s31, v107
	global_load_lds_dwordx4 v64, s[100:101]
	s_mov_b32 m0, s31
	v_readfirstlane_b32 s34, v108
	global_load_lds_dwordx4 v66, s[100:101]
	ds_read_b128 v[0:3], v111 offset:16384
	ds_read_b128 v[24:27], v111 offset:20480
	s_mov_b32 m0, s34
	v_readfirstlane_b32 s35, v109
	global_load_lds_dwordx4 v68, s[100:101]
	s_mov_b32 m0, s35
	ds_read_b128 v[16:19], v110
	global_load_lds_dwordx4 v70, s[100:101]
	s_add_u32 s98, s98, 0x80
	s_addc_u32 s99, s99, 0
	s_add_u32 s100, s100, 0x80
	s_addc_u32 s101, s101, 0
	ds_read_b128 v[20:23], v110 offset:4096
	s_waitcnt lgkmcnt(0)
	v_mfma_f32_32x32x16_bf16 v[32:47], v[0:3], v[16:19], 0
	ds_read_b128 v[118:121], v113 offset:16384
	ds_read_b128 v[122:125], v112
	ds_read_b128 v[126:129], v112 offset:4096
	s_mov_b32 m0, s70
	s_cmp_lt_i32 s69, 16
	s_cselect_b64 vcc, -1, 0
	s_cmp_gt_i32 s69, 15
	v_readlane_b32 s74, v245, 23
	v_mfma_f32_32x32x16_bf16 v[0:15], v[0:3], v[20:23], 0
	v_readlane_b32 s75, v245, 24
	v_readlane_b32 s76, v245, 25
	v_readlane_b32 s77, v245, 26
	v_readlane_b32 s82, v245, 31
	v_readlane_b32 s83, v245, 32
	v_readlane_b32 s84, v245, 33
	v_readlane_b32 s85, v245, 34
	s_waitcnt lgkmcnt(0)
	v_mfma_f32_32x32x16_bf16 v[32:47], v[118:121], v[122:125], v[32:47]
	v_mfma_f32_32x32x16_bf16 v[0:15], v[118:121], v[126:129], v[0:15]
	ds_read_b128 v[118:121], v113 offset:20480
	v_mfma_f32_32x32x16_bf16 v[48:63], v[24:27], v[16:19], 0
	v_mfma_f32_32x32x16_bf16 v[16:31], v[24:27], v[20:23], 0
	s_waitcnt lgkmcnt(0)
	v_mfma_f32_32x32x16_bf16 v[48:63], v[118:121], v[122:125], v[48:63]
	v_mfma_f32_32x32x16_bf16 v[16:31], v[118:121], v[126:129], v[16:31]
	ds_read_b128 v[118:121], v115 offset:16384
	ds_read_b128 v[122:125], v114
	ds_read_b128 v[126:129], v114 offset:4096
	s_waitcnt lgkmcnt(0)
	v_mfma_f32_32x32x16_bf16 v[32:47], v[118:121], v[122:125], v[32:47]
	v_mfma_f32_32x32x16_bf16 v[0:15], v[118:121], v[126:129], v[0:15]
	ds_read_b128 v[118:121], v115 offset:20480
	s_waitcnt lgkmcnt(0)
	v_mfma_f32_32x32x16_bf16 v[48:63], v[118:121], v[122:125], v[48:63]
	v_mfma_f32_32x32x16_bf16 v[16:31], v[118:121], v[126:129], v[16:31]
	ds_read_b128 v[118:121], v117 offset:16384
	ds_read_b128 v[122:125], v116
	ds_read_b128 v[126:129], v116 offset:4096
	s_waitcnt lgkmcnt(0)
	v_mfma_f32_32x32x16_bf16 v[32:47], v[118:121], v[122:125], v[32:47]
	v_mfma_f32_32x32x16_bf16 v[0:15], v[118:121], v[126:129], v[0:15]
	ds_read_b128 v[118:121], v117 offset:20480
	s_waitcnt vmcnt(0)
	s_waitcnt vmcnt(0) lgkmcnt(0)
	s_barrier
	v_mfma_f32_32x32x16_bf16 v[48:63], v[118:121], v[122:125], v[48:63]
	v_mfma_f32_32x32x16_bf16 v[16:31], v[118:121], v[126:129], v[16:31]
	global_load_lds_dwordx4 v64, s[98:99]
	s_mov_b32 m0, s71
	s_nop 0
	global_load_lds_dwordx4 v66, s[98:99]
	s_mov_b32 m0, s72
	s_nop 0
	global_load_lds_dwordx4 v68, s[98:99]
	s_mov_b32 m0, s78
	s_nop 0
	global_load_lds_dwordx4 v70, s[98:99]
	s_mov_b32 m0, s79
	s_nop 0
	global_load_lds_dwordx4 v64, s[100:101]
	s_mov_b32 m0, s80
	s_nop 0
	global_load_lds_dwordx4 v66, s[100:101]
	s_mov_b32 m0, s81
	s_nop 0
	global_load_lds_dwordx4 v68, s[100:101]
	ds_read_b128 v[118:121], v111 offset:49152
	s_mov_b32 m0, s73
	s_nop 0
	global_load_lds_dwordx4 v70, s[100:101]
	s_add_u32 s98, s98, 0x80
	s_addc_u32 s99, s99, 0
	s_add_u32 s100, s100, 0x80
	s_addc_u32 s101, s101, 0
	ds_read_b128 v[122:125], v110 offset:32768
	ds_read_b128 v[126:129], v110 offset:36864
	s_waitcnt lgkmcnt(0)
	v_mfma_f32_32x32x16_bf16 v[32:47], v[118:121], v[122:125], v[32:47]
	s_mov_b32 m0, s11
	v_mfma_f32_32x32x16_bf16 v[0:15], v[118:121], v[126:129], v[0:15]
	ds_read_b128 v[118:121], v111 offset:53248
	s_waitcnt lgkmcnt(0)
	v_mfma_f32_32x32x16_bf16 v[48:63], v[118:121], v[122:125], v[48:63]
	v_mfma_f32_32x32x16_bf16 v[16:31], v[118:121], v[126:129], v[16:31]
	ds_read_b128 v[118:121], v113 offset:49152
	ds_read_b128 v[122:125], v112 offset:32768
	ds_read_b128 v[126:129], v112 offset:36864
	s_waitcnt lgkmcnt(0)
	v_mfma_f32_32x32x16_bf16 v[32:47], v[118:121], v[122:125], v[32:47]
	v_mfma_f32_32x32x16_bf16 v[0:15], v[118:121], v[126:129], v[0:15]
	ds_read_b128 v[118:121], v113 offset:53248
	s_waitcnt lgkmcnt(0)
	v_mfma_f32_32x32x16_bf16 v[48:63], v[118:121], v[122:125], v[48:63]
	v_mfma_f32_32x32x16_bf16 v[16:31], v[118:121], v[126:129], v[16:31]
	ds_read_b128 v[118:121], v115 offset:49152
	ds_read_b128 v[122:125], v114 offset:32768
	ds_read_b128 v[126:129], v114 offset:36864
	s_waitcnt lgkmcnt(0)
	v_mfma_f32_32x32x16_bf16 v[32:47], v[118:121], v[122:125], v[32:47]
	v_mfma_f32_32x32x16_bf16 v[0:15], v[118:121], v[126:129], v[0:15]
	ds_read_b128 v[118:121], v115 offset:53248
	s_waitcnt lgkmcnt(0)
	v_mfma_f32_32x32x16_bf16 v[48:63], v[118:121], v[122:125], v[48:63]
	v_mfma_f32_32x32x16_bf16 v[16:31], v[118:121], v[126:129], v[16:31]
	ds_read_b128 v[118:121], v117 offset:49152
	ds_read_b128 v[122:125], v116 offset:32768
	ds_read_b128 v[126:129], v116 offset:36864
	s_waitcnt lgkmcnt(0)
	v_mfma_f32_32x32x16_bf16 v[32:47], v[118:121], v[122:125], v[32:47]
	v_mfma_f32_32x32x16_bf16 v[0:15], v[118:121], v[126:129], v[0:15]
	ds_read_b128 v[118:121], v117 offset:53248
	s_waitcnt vmcnt(0)
	s_waitcnt vmcnt(0) lgkmcnt(0)
	s_barrier
	v_mfma_f32_32x32x16_bf16 v[48:63], v[118:121], v[122:125], v[48:63]
	v_mfma_f32_32x32x16_bf16 v[16:31], v[118:121], v[126:129], v[16:31]
	global_load_lds_dwordx4 v64, s[98:99]
	s_mov_b32 m0, s15
	s_nop 0
	global_load_lds_dwordx4 v66, s[98:99]
	s_mov_b32 m0, s28
	s_nop 0
	global_load_lds_dwordx4 v68, s[98:99]
	s_mov_b32 m0, s29
	s_nop 0
	global_load_lds_dwordx4 v70, s[98:99]
	s_mov_b32 m0, s30
	s_nop 0
	global_load_lds_dwordx4 v64, s[100:101]
	s_mov_b32 m0, s31
	s_nop 0
	global_load_lds_dwordx4 v66, s[100:101]
	ds_read_b128 v[118:121], v111 offset:16384
	s_mov_b32 m0, s34
	s_nop 0
	global_load_lds_dwordx4 v68, s[100:101]
	s_mov_b32 m0, s35
	ds_read_b128 v[122:125], v110
	global_load_lds_dwordx4 v70, s[100:101]
	s_add_u32 s98, s98, 0x80
	s_addc_u32 s99, s99, 0
	s_add_u32 s100, s100, 0x80
	s_addc_u32 s101, s101, 0
	ds_read_b128 v[126:129], v110 offset:4096
	s_waitcnt lgkmcnt(0)
	v_mfma_f32_32x32x16_bf16 v[32:47], v[118:121], v[122:125], v[32:47]
	s_mov_b32 m0, s70
	v_mfma_f32_32x32x16_bf16 v[0:15], v[118:121], v[126:129], v[0:15]
	ds_read_b128 v[118:121], v111 offset:20480
	s_waitcnt lgkmcnt(0)
	v_mfma_f32_32x32x16_bf16 v[48:63], v[118:121], v[122:125], v[48:63]
	v_mfma_f32_32x32x16_bf16 v[16:31], v[118:121], v[126:129], v[16:31]
	ds_read_b128 v[118:121], v113 offset:16384
	ds_read_b128 v[122:125], v112
	ds_read_b128 v[126:129], v112 offset:4096
	s_waitcnt lgkmcnt(0)
	v_mfma_f32_32x32x16_bf16 v[32:47], v[118:121], v[122:125], v[32:47]
	v_mfma_f32_32x32x16_bf16 v[0:15], v[118:121], v[126:129], v[0:15]
	ds_read_b128 v[118:121], v113 offset:20480
	s_waitcnt lgkmcnt(0)
	v_mfma_f32_32x32x16_bf16 v[48:63], v[118:121], v[122:125], v[48:63]
	v_mfma_f32_32x32x16_bf16 v[16:31], v[118:121], v[126:129], v[16:31]
	ds_read_b128 v[118:121], v115 offset:16384
	ds_read_b128 v[122:125], v114
	ds_read_b128 v[126:129], v114 offset:4096
	s_waitcnt lgkmcnt(0)
	v_mfma_f32_32x32x16_bf16 v[32:47], v[118:121], v[122:125], v[32:47]
	v_mfma_f32_32x32x16_bf16 v[0:15], v[118:121], v[126:129], v[0:15]
	ds_read_b128 v[118:121], v115 offset:20480
	s_waitcnt lgkmcnt(0)
	v_mfma_f32_32x32x16_bf16 v[48:63], v[118:121], v[122:125], v[48:63]
	v_mfma_f32_32x32x16_bf16 v[16:31], v[118:121], v[126:129], v[16:31]
	ds_read_b128 v[118:121], v117 offset:16384
	ds_read_b128 v[122:125], v116
	ds_read_b128 v[126:129], v116 offset:4096
	s_waitcnt lgkmcnt(0)
	v_mfma_f32_32x32x16_bf16 v[32:47], v[118:121], v[122:125], v[32:47]
	v_mfma_f32_32x32x16_bf16 v[0:15], v[118:121], v[126:129], v[0:15]
	ds_read_b128 v[118:121], v117 offset:20480
	s_waitcnt vmcnt(0)
	s_waitcnt vmcnt(0) lgkmcnt(0)
	s_barrier
	v_mfma_f32_32x32x16_bf16 v[48:63], v[118:121], v[122:125], v[48:63]
	v_mfma_f32_32x32x16_bf16 v[16:31], v[118:121], v[126:129], v[16:31]
	global_load_lds_dwordx4 v64, s[98:99]
	s_mov_b32 m0, s71
	s_nop 0
	global_load_lds_dwordx4 v66, s[98:99]
	s_mov_b32 m0, s72
	s_nop 0
	global_load_lds_dwordx4 v68, s[98:99]
	s_mov_b32 m0, s78
	s_nop 0
	global_load_lds_dwordx4 v70, s[98:99]
	s_mov_b32 m0, s79
	s_nop 0
	global_load_lds_dwordx4 v64, s[100:101]
	s_mov_b32 m0, s80
	s_nop 0
	global_load_lds_dwordx4 v66, s[100:101]
	s_mov_b32 m0, s81
	s_nop 0
	global_load_lds_dwordx4 v68, s[100:101]
	ds_read_b128 v[118:121], v111 offset:49152
	s_mov_b32 m0, s73
	s_nop 0
	global_load_lds_dwordx4 v70, s[100:101]
	s_add_u32 s98, s98, 0x80
	s_addc_u32 s99, s99, 0
	s_add_u32 s100, s100, 0x80
	s_addc_u32 s101, s101, 0
	ds_read_b128 v[122:125], v110 offset:32768
	ds_read_b128 v[126:129], v110 offset:36864
	s_waitcnt lgkmcnt(0)
	v_mfma_f32_32x32x16_bf16 v[32:47], v[118:121], v[122:125], v[32:47]
	s_mov_b32 m0, s11
	v_mfma_f32_32x32x16_bf16 v[0:15], v[118:121], v[126:129], v[0:15]
	ds_read_b128 v[118:121], v111 offset:53248
	s_waitcnt lgkmcnt(0)
	v_mfma_f32_32x32x16_bf16 v[48:63], v[118:121], v[122:125], v[48:63]
	v_mfma_f32_32x32x16_bf16 v[16:31], v[118:121], v[126:129], v[16:31]
	ds_read_b128 v[118:121], v113 offset:49152
	ds_read_b128 v[122:125], v112 offset:32768
	ds_read_b128 v[126:129], v112 offset:36864
	s_waitcnt lgkmcnt(0)
	v_mfma_f32_32x32x16_bf16 v[32:47], v[118:121], v[122:125], v[32:47]
	v_mfma_f32_32x32x16_bf16 v[0:15], v[118:121], v[126:129], v[0:15]
	ds_read_b128 v[118:121], v113 offset:53248
	s_waitcnt lgkmcnt(0)
	v_mfma_f32_32x32x16_bf16 v[48:63], v[118:121], v[122:125], v[48:63]
	v_mfma_f32_32x32x16_bf16 v[16:31], v[118:121], v[126:129], v[16:31]
	ds_read_b128 v[118:121], v115 offset:49152
	ds_read_b128 v[122:125], v114 offset:32768
	ds_read_b128 v[126:129], v114 offset:36864
	s_waitcnt lgkmcnt(0)
	v_mfma_f32_32x32x16_bf16 v[32:47], v[118:121], v[122:125], v[32:47]
	v_mfma_f32_32x32x16_bf16 v[0:15], v[118:121], v[126:129], v[0:15]
	ds_read_b128 v[118:121], v115 offset:53248
	s_waitcnt lgkmcnt(0)
	v_mfma_f32_32x32x16_bf16 v[48:63], v[118:121], v[122:125], v[48:63]
	v_mfma_f32_32x32x16_bf16 v[16:31], v[118:121], v[126:129], v[16:31]
	ds_read_b128 v[118:121], v117 offset:49152
	ds_read_b128 v[122:125], v116 offset:32768
	ds_read_b128 v[126:129], v116 offset:36864
	s_waitcnt lgkmcnt(0)
	v_mfma_f32_32x32x16_bf16 v[32:47], v[118:121], v[122:125], v[32:47]
	v_mfma_f32_32x32x16_bf16 v[0:15], v[118:121], v[126:129], v[0:15]
	ds_read_b128 v[118:121], v117 offset:53248
	s_waitcnt vmcnt(0)
	s_waitcnt vmcnt(0) lgkmcnt(0)
	s_barrier
	v_mfma_f32_32x32x16_bf16 v[48:63], v[118:121], v[122:125], v[48:63]
	v_mfma_f32_32x32x16_bf16 v[16:31], v[118:121], v[126:129], v[16:31]
	global_load_lds_dwordx4 v64, s[98:99]
	s_mov_b32 m0, s15
	s_nop 0
	global_load_lds_dwordx4 v66, s[98:99]
	s_mov_b32 m0, s28
	s_nop 0
	global_load_lds_dwordx4 v68, s[98:99]
	s_mov_b32 m0, s29
	s_nop 0
	global_load_lds_dwordx4 v70, s[98:99]
	s_mov_b32 m0, s30
	s_nop 0
	global_load_lds_dwordx4 v64, s[100:101]
	s_mov_b32 m0, s31
	s_nop 0
	global_load_lds_dwordx4 v66, s[100:101]
	ds_read_b128 v[118:121], v111 offset:16384
	s_mov_b32 m0, s34
	s_nop 0
	global_load_lds_dwordx4 v68, s[100:101]
	s_mov_b32 m0, s35
	ds_read_b128 v[122:125], v110
	global_load_lds_dwordx4 v70, s[100:101]
	s_add_u32 s98, s98, 0x80
	s_addc_u32 s99, s99, 0
	s_add_u32 s100, s100, 0x80
	s_addc_u32 s101, s101, 0
	ds_read_b128 v[126:129], v110 offset:4096
	s_waitcnt lgkmcnt(0)
	v_mfma_f32_32x32x16_bf16 v[32:47], v[118:121], v[122:125], v[32:47]
	s_mov_b32 m0, s70
	v_mfma_f32_32x32x16_bf16 v[0:15], v[118:121], v[126:129], v[0:15]
	ds_read_b128 v[118:121], v111 offset:20480
	s_waitcnt lgkmcnt(0)
	v_mfma_f32_32x32x16_bf16 v[48:63], v[118:121], v[122:125], v[48:63]
	v_mfma_f32_32x32x16_bf16 v[16:31], v[118:121], v[126:129], v[16:31]
	ds_read_b128 v[118:121], v113 offset:16384
	ds_read_b128 v[122:125], v112
	ds_read_b128 v[126:129], v112 offset:4096
	s_waitcnt lgkmcnt(0)
	v_mfma_f32_32x32x16_bf16 v[32:47], v[118:121], v[122:125], v[32:47]
	v_mfma_f32_32x32x16_bf16 v[0:15], v[118:121], v[126:129], v[0:15]
	ds_read_b128 v[118:121], v113 offset:20480
	s_waitcnt lgkmcnt(0)
	v_mfma_f32_32x32x16_bf16 v[48:63], v[118:121], v[122:125], v[48:63]
	v_mfma_f32_32x32x16_bf16 v[16:31], v[118:121], v[126:129], v[16:31]
	ds_read_b128 v[118:121], v115 offset:16384
	ds_read_b128 v[122:125], v114
	ds_read_b128 v[126:129], v114 offset:4096
	s_waitcnt lgkmcnt(0)
	v_mfma_f32_32x32x16_bf16 v[32:47], v[118:121], v[122:125], v[32:47]
	v_mfma_f32_32x32x16_bf16 v[0:15], v[118:121], v[126:129], v[0:15]
	ds_read_b128 v[118:121], v115 offset:20480
	s_waitcnt lgkmcnt(0)
	v_mfma_f32_32x32x16_bf16 v[48:63], v[118:121], v[122:125], v[48:63]
	v_mfma_f32_32x32x16_bf16 v[16:31], v[118:121], v[126:129], v[16:31]
	ds_read_b128 v[118:121], v117 offset:16384
	ds_read_b128 v[122:125], v116
	ds_read_b128 v[126:129], v116 offset:4096
	s_waitcnt lgkmcnt(0)
	v_mfma_f32_32x32x16_bf16 v[32:47], v[118:121], v[122:125], v[32:47]
	v_mfma_f32_32x32x16_bf16 v[0:15], v[118:121], v[126:129], v[0:15]
	ds_read_b128 v[118:121], v117 offset:20480
	s_waitcnt vmcnt(0)
	s_waitcnt vmcnt(0) lgkmcnt(0)
	s_barrier
	v_mfma_f32_32x32x16_bf16 v[48:63], v[118:121], v[122:125], v[48:63]
	v_mfma_f32_32x32x16_bf16 v[16:31], v[118:121], v[126:129], v[16:31]
	global_load_lds_dwordx4 v64, s[98:99]
	s_mov_b32 m0, s71
	s_nop 0
	global_load_lds_dwordx4 v66, s[98:99]
	s_mov_b32 m0, s72
	s_nop 0
	global_load_lds_dwordx4 v68, s[98:99]
	s_mov_b32 m0, s78
	s_nop 0
	global_load_lds_dwordx4 v70, s[98:99]
	s_mov_b32 m0, s79
	s_nop 0
	global_load_lds_dwordx4 v64, s[100:101]
	s_mov_b32 m0, s80
	s_nop 0
	global_load_lds_dwordx4 v66, s[100:101]
	s_mov_b32 m0, s81
	s_nop 0
	global_load_lds_dwordx4 v68, s[100:101]
	ds_read_b128 v[118:121], v111 offset:49152
	s_mov_b32 m0, s73
	s_nop 0
	global_load_lds_dwordx4 v70, s[100:101]
	s_add_u32 s98, s98, 0x80
	s_addc_u32 s99, s99, 0
	s_add_u32 s100, s100, 0x80
	s_addc_u32 s101, s101, 0
	ds_read_b128 v[122:125], v110 offset:32768
	ds_read_b128 v[126:129], v110 offset:36864
	s_waitcnt lgkmcnt(0)
	v_mfma_f32_32x32x16_bf16 v[32:47], v[118:121], v[122:125], v[32:47]
	s_mov_b32 m0, s11
	v_mfma_f32_32x32x16_bf16 v[0:15], v[118:121], v[126:129], v[0:15]
	ds_read_b128 v[118:121], v111 offset:53248
	s_waitcnt lgkmcnt(0)
	v_mfma_f32_32x32x16_bf16 v[48:63], v[118:121], v[122:125], v[48:63]
	v_mfma_f32_32x32x16_bf16 v[16:31], v[118:121], v[126:129], v[16:31]
	ds_read_b128 v[118:121], v113 offset:49152
	ds_read_b128 v[122:125], v112 offset:32768
	ds_read_b128 v[126:129], v112 offset:36864
	s_waitcnt lgkmcnt(0)
	v_mfma_f32_32x32x16_bf16 v[32:47], v[118:121], v[122:125], v[32:47]
	v_mfma_f32_32x32x16_bf16 v[0:15], v[118:121], v[126:129], v[0:15]
	ds_read_b128 v[118:121], v113 offset:53248
	s_waitcnt lgkmcnt(0)
	v_mfma_f32_32x32x16_bf16 v[48:63], v[118:121], v[122:125], v[48:63]
	v_mfma_f32_32x32x16_bf16 v[16:31], v[118:121], v[126:129], v[16:31]
	ds_read_b128 v[118:121], v115 offset:49152
	ds_read_b128 v[122:125], v114 offset:32768
	ds_read_b128 v[126:129], v114 offset:36864
	s_waitcnt lgkmcnt(0)
	v_mfma_f32_32x32x16_bf16 v[32:47], v[118:121], v[122:125], v[32:47]
	v_mfma_f32_32x32x16_bf16 v[0:15], v[118:121], v[126:129], v[0:15]
	ds_read_b128 v[118:121], v115 offset:53248
	s_waitcnt lgkmcnt(0)
	v_mfma_f32_32x32x16_bf16 v[48:63], v[118:121], v[122:125], v[48:63]
	v_mfma_f32_32x32x16_bf16 v[16:31], v[118:121], v[126:129], v[16:31]
	ds_read_b128 v[118:121], v117 offset:49152
	ds_read_b128 v[122:125], v116 offset:32768
	ds_read_b128 v[126:129], v116 offset:36864
	s_waitcnt lgkmcnt(0)
	v_mfma_f32_32x32x16_bf16 v[32:47], v[118:121], v[122:125], v[32:47]
	v_mfma_f32_32x32x16_bf16 v[0:15], v[118:121], v[126:129], v[0:15]
	ds_read_b128 v[118:121], v117 offset:53248
	s_waitcnt vmcnt(0)
	s_waitcnt vmcnt(0) lgkmcnt(0)
	s_barrier
	v_mfma_f32_32x32x16_bf16 v[48:63], v[118:121], v[122:125], v[48:63]
	v_mfma_f32_32x32x16_bf16 v[16:31], v[118:121], v[126:129], v[16:31]
	global_load_lds_dwordx4 v64, s[98:99]
	s_mov_b32 m0, s15
	s_nop 0
	global_load_lds_dwordx4 v66, s[98:99]
	s_mov_b32 m0, s28
	s_nop 0
	global_load_lds_dwordx4 v68, s[98:99]
	s_mov_b32 m0, s29
	s_nop 0
	global_load_lds_dwordx4 v70, s[98:99]
	s_mov_b32 m0, s30
	s_nop 0
	global_load_lds_dwordx4 v64, s[100:101]
	s_mov_b32 m0, s31
	s_nop 0
	global_load_lds_dwordx4 v66, s[100:101]
	ds_read_b128 v[118:121], v111 offset:16384
	s_mov_b32 m0, s34
	s_nop 0
	global_load_lds_dwordx4 v68, s[100:101]
	s_mov_b32 m0, s35
	ds_read_b128 v[122:125], v110
	global_load_lds_dwordx4 v70, s[100:101]
	s_add_u32 s98, s98, 0x80
	s_addc_u32 s99, s99, 0
	s_add_u32 s100, s100, 0x80
	s_addc_u32 s101, s101, 0
	ds_read_b128 v[126:129], v110 offset:4096
	s_waitcnt lgkmcnt(0)
	v_mfma_f32_32x32x16_bf16 v[32:47], v[118:121], v[122:125], v[32:47]
	s_mov_b32 m0, s70
	v_readfirstlane_b32 s70, v102
	v_mfma_f32_32x32x16_bf16 v[0:15], v[118:121], v[126:129], v[0:15]
	ds_read_b128 v[118:121], v111 offset:20480
	s_waitcnt lgkmcnt(0)
	v_mfma_f32_32x32x16_bf16 v[48:63], v[118:121], v[122:125], v[48:63]
	v_mfma_f32_32x32x16_bf16 v[16:31], v[118:121], v[126:129], v[16:31]
	ds_read_b128 v[118:121], v113 offset:16384
	ds_read_b128 v[122:125], v112
	ds_read_b128 v[126:129], v112 offset:4096
	s_waitcnt lgkmcnt(0)
	v_mfma_f32_32x32x16_bf16 v[32:47], v[118:121], v[122:125], v[32:47]
	v_mfma_f32_32x32x16_bf16 v[0:15], v[118:121], v[126:129], v[0:15]
	ds_read_b128 v[118:121], v113 offset:20480
	s_waitcnt lgkmcnt(0)
	v_mfma_f32_32x32x16_bf16 v[48:63], v[118:121], v[122:125], v[48:63]
	v_mfma_f32_32x32x16_bf16 v[16:31], v[118:121], v[126:129], v[16:31]
	ds_read_b128 v[118:121], v115 offset:16384
	ds_read_b128 v[122:125], v114
	ds_read_b128 v[126:129], v114 offset:4096
	s_waitcnt lgkmcnt(0)
	v_mfma_f32_32x32x16_bf16 v[32:47], v[118:121], v[122:125], v[32:47]
	v_mfma_f32_32x32x16_bf16 v[0:15], v[118:121], v[126:129], v[0:15]
	ds_read_b128 v[118:121], v115 offset:20480
	s_waitcnt lgkmcnt(0)
	v_mfma_f32_32x32x16_bf16 v[48:63], v[118:121], v[122:125], v[48:63]
	v_mfma_f32_32x32x16_bf16 v[16:31], v[118:121], v[126:129], v[16:31]
	ds_read_b128 v[118:121], v117 offset:16384
	ds_read_b128 v[122:125], v116
	ds_read_b128 v[126:129], v116 offset:4096
	s_waitcnt lgkmcnt(0)
	v_mfma_f32_32x32x16_bf16 v[32:47], v[118:121], v[122:125], v[32:47]
	v_mfma_f32_32x32x16_bf16 v[0:15], v[118:121], v[126:129], v[0:15]
	ds_read_b128 v[118:121], v117 offset:20480
	s_waitcnt vmcnt(0)
	s_waitcnt vmcnt(0) lgkmcnt(0)
	s_barrier
	v_mfma_f32_32x32x16_bf16 v[48:63], v[118:121], v[122:125], v[48:63]
	v_mfma_f32_32x32x16_bf16 v[16:31], v[118:121], v[126:129], v[16:31]
	global_load_lds_dwordx4 v64, s[98:99]
	s_mov_b32 m0, s71
	v_readfirstlane_b32 s71, v103
	global_load_lds_dwordx4 v66, s[98:99]
	s_mov_b32 m0, s72
	v_readfirstlane_b32 s72, v104
	global_load_lds_dwordx4 v68, s[98:99]
	s_mov_b32 m0, s78
	v_readfirstlane_b32 s78, v106
	global_load_lds_dwordx4 v70, s[98:99]
	s_mov_b32 m0, s79
	v_readfirstlane_b32 s79, v107
	global_load_lds_dwordx4 v64, s[100:101]
	s_mov_b32 m0, s80
	v_readfirstlane_b32 s80, v108
	global_load_lds_dwordx4 v66, s[100:101]
	s_mov_b32 m0, s81
	v_readfirstlane_b32 s81, v109
	global_load_lds_dwordx4 v68, s[100:101]
	ds_read_b128 v[118:121], v111 offset:49152
	s_mov_b32 m0, s73
	v_readfirstlane_b32 s73, v105
	global_load_lds_dwordx4 v70, s[100:101]
	s_add_u32 s98, s98, 0x80
	s_addc_u32 s99, s99, 0
	s_add_u32 s100, s100, 0x80
	s_addc_u32 s101, s101, 0
	ds_read_b128 v[122:125], v110 offset:32768
	ds_read_b128 v[126:129], v110 offset:36864
	s_waitcnt lgkmcnt(0)
	v_mfma_f32_32x32x16_bf16 v[32:47], v[118:121], v[122:125], v[32:47]
	s_mov_b32 m0, s11
	v_readfirstlane_b32 s11, v92
	v_mfma_f32_32x32x16_bf16 v[0:15], v[118:121], v[126:129], v[0:15]
	ds_read_b128 v[118:121], v111 offset:53248
	s_waitcnt lgkmcnt(0)
	v_mfma_f32_32x32x16_bf16 v[48:63], v[118:121], v[122:125], v[48:63]
	v_mfma_f32_32x32x16_bf16 v[16:31], v[118:121], v[126:129], v[16:31]
	ds_read_b128 v[118:121], v113 offset:49152
	ds_read_b128 v[122:125], v112 offset:32768
	ds_read_b128 v[126:129], v112 offset:36864
	s_waitcnt lgkmcnt(0)
	v_mfma_f32_32x32x16_bf16 v[32:47], v[118:121], v[122:125], v[32:47]
	v_mfma_f32_32x32x16_bf16 v[0:15], v[118:121], v[126:129], v[0:15]
	ds_read_b128 v[118:121], v113 offset:53248
	s_waitcnt lgkmcnt(0)
	v_mfma_f32_32x32x16_bf16 v[48:63], v[118:121], v[122:125], v[48:63]
	v_mfma_f32_32x32x16_bf16 v[16:31], v[118:121], v[126:129], v[16:31]
	ds_read_b128 v[118:121], v115 offset:49152
	ds_read_b128 v[122:125], v114 offset:32768
	ds_read_b128 v[126:129], v114 offset:36864
	s_waitcnt lgkmcnt(0)
	v_mfma_f32_32x32x16_bf16 v[32:47], v[118:121], v[122:125], v[32:47]
	v_mfma_f32_32x32x16_bf16 v[0:15], v[118:121], v[126:129], v[0:15]
	ds_read_b128 v[118:121], v115 offset:53248
	s_waitcnt lgkmcnt(0)
	v_mfma_f32_32x32x16_bf16 v[48:63], v[118:121], v[122:125], v[48:63]
	v_mfma_f32_32x32x16_bf16 v[16:31], v[118:121], v[126:129], v[16:31]
	ds_read_b128 v[118:121], v117 offset:49152
	ds_read_b128 v[122:125], v116 offset:32768
	ds_read_b128 v[126:129], v116 offset:36864
	s_waitcnt lgkmcnt(0)
	v_mfma_f32_32x32x16_bf16 v[32:47], v[118:121], v[122:125], v[32:47]
	v_mfma_f32_32x32x16_bf16 v[0:15], v[118:121], v[126:129], v[0:15]
	ds_read_b128 v[118:121], v117 offset:53248
	s_waitcnt vmcnt(0)
	s_waitcnt vmcnt(0) lgkmcnt(0)
	s_barrier
	v_mfma_f32_32x32x16_bf16 v[48:63], v[118:121], v[122:125], v[48:63]
	v_mfma_f32_32x32x16_bf16 v[16:31], v[118:121], v[126:129], v[16:31]
	global_load_lds_dwordx4 v64, s[98:99]
	s_mov_b32 m0, s15
	s_nop 0
	global_load_lds_dwordx4 v66, s[98:99]
	s_mov_b32 m0, s28
	v_readfirstlane_b32 s15, v95
	global_load_lds_dwordx4 v68, s[98:99]
	s_mov_b32 m0, s29
	v_readfirstlane_b32 s28, v96
	global_load_lds_dwordx4 v70, s[98:99]
	s_mov_b32 m0, s30
	v_readfirstlane_b32 s30, v97
	global_load_lds_dwordx4 v64, s[100:101]
	s_mov_b32 m0, s31
	v_readfirstlane_b32 s31, v98
	global_load_lds_dwordx4 v66, s[100:101]
	ds_read_b128 v[118:121], v111 offset:16384
	s_mov_b32 m0, s34
	v_readfirstlane_b32 s34, v99
	global_load_lds_dwordx4 v68, s[100:101]
	s_mov_b32 m0, s35
	ds_read_b128 v[122:125], v110
	global_load_lds_dwordx4 v70, s[100:101]
	s_add_u32 s98, s98, 0x80
	s_addc_u32 s99, s99, 0
	s_add_u32 s100, s100, 0x80
	s_addc_u32 s101, s101, 0
	ds_read_b128 v[126:129], v110 offset:4096
	s_waitcnt lgkmcnt(0)
	v_mfma_f32_32x32x16_bf16 v[32:47], v[118:121], v[122:125], v[32:47]
	s_mov_b32 m0, s11
	v_readfirstlane_b32 s35, v100
	v_readfirstlane_b32 s29, v101
	v_mfma_f32_32x32x16_bf16 v[0:15], v[118:121], v[126:129], v[0:15]
	ds_read_b128 v[118:121], v111 offset:20480
	s_waitcnt lgkmcnt(0)
	v_mfma_f32_32x32x16_bf16 v[48:63], v[118:121], v[122:125], v[48:63]
	v_mfma_f32_32x32x16_bf16 v[16:31], v[118:121], v[126:129], v[16:31]
	ds_read_b128 v[118:121], v113 offset:16384
	ds_read_b128 v[122:125], v112
	ds_read_b128 v[126:129], v112 offset:4096
	s_waitcnt lgkmcnt(0)
	v_mfma_f32_32x32x16_bf16 v[32:47], v[118:121], v[122:125], v[32:47]
	v_mfma_f32_32x32x16_bf16 v[0:15], v[118:121], v[126:129], v[0:15]
	ds_read_b128 v[118:121], v113 offset:20480
	s_waitcnt lgkmcnt(0)
	v_mfma_f32_32x32x16_bf16 v[48:63], v[118:121], v[122:125], v[48:63]
	v_mfma_f32_32x32x16_bf16 v[16:31], v[118:121], v[126:129], v[16:31]
	ds_read_b128 v[118:121], v115 offset:16384
	ds_read_b128 v[122:125], v114
	ds_read_b128 v[126:129], v114 offset:4096
	s_waitcnt lgkmcnt(0)
	v_mfma_f32_32x32x16_bf16 v[32:47], v[118:121], v[122:125], v[32:47]
	v_mfma_f32_32x32x16_bf16 v[0:15], v[118:121], v[126:129], v[0:15]
	ds_read_b128 v[118:121], v115 offset:20480
	s_waitcnt lgkmcnt(0)
	v_mfma_f32_32x32x16_bf16 v[48:63], v[118:121], v[122:125], v[48:63]
	v_mfma_f32_32x32x16_bf16 v[16:31], v[118:121], v[126:129], v[16:31]
	ds_read_b128 v[118:121], v117 offset:16384
	ds_read_b128 v[122:125], v116
	ds_read_b128 v[126:129], v116 offset:4096
	s_waitcnt lgkmcnt(0)
	v_mfma_f32_32x32x16_bf16 v[32:47], v[118:121], v[122:125], v[32:47]
	v_mfma_f32_32x32x16_bf16 v[0:15], v[118:121], v[126:129], v[0:15]
	ds_read_b128 v[118:121], v117 offset:20480
	s_waitcnt vmcnt(0)
	s_waitcnt vmcnt(0) lgkmcnt(0)
	s_barrier
	v_mfma_f32_32x32x16_bf16 v[48:63], v[118:121], v[122:125], v[48:63]
	v_mfma_f32_32x32x16_bf16 v[16:31], v[118:121], v[126:129], v[16:31]
	global_load_lds_dwordx4 v64, s[98:99]
	s_mov_b32 m0, s15
	s_nop 0
	global_load_lds_dwordx4 v66, s[98:99]
	s_mov_b32 m0, s28
	s_nop 0
	global_load_lds_dwordx4 v68, s[98:99]
	s_mov_b32 m0, s30
	s_nop 0
	global_load_lds_dwordx4 v70, s[98:99]
	s_mov_b32 m0, s31
	s_nop 0
	global_load_lds_dwordx4 v64, s[100:101]
	s_mov_b32 m0, s34
	s_nop 0
	global_load_lds_dwordx4 v66, s[100:101]
	s_mov_b32 m0, s35
	s_nop 0
	global_load_lds_dwordx4 v68, s[100:101]
	ds_read_b128 v[118:121], v111 offset:49152
	s_mov_b32 m0, s29
	s_nop 0
	global_load_lds_dwordx4 v70, s[100:101]
	s_add_u32 s98, s98, 0x80
	s_addc_u32 s99, s99, 0
	s_add_u32 s100, s100, 0x80
	s_addc_u32 s101, s101, 0
	ds_read_b128 v[122:125], v110 offset:32768
	ds_read_b128 v[126:129], v110 offset:36864
	s_waitcnt lgkmcnt(0)
	v_mfma_f32_32x32x16_bf16 v[32:47], v[118:121], v[122:125], v[32:47]
	s_mov_b32 m0, s70
	v_mfma_f32_32x32x16_bf16 v[0:15], v[118:121], v[126:129], v[0:15]
	ds_read_b128 v[118:121], v111 offset:53248
	s_waitcnt lgkmcnt(0)
	v_mfma_f32_32x32x16_bf16 v[48:63], v[118:121], v[122:125], v[48:63]
	v_mfma_f32_32x32x16_bf16 v[16:31], v[118:121], v[126:129], v[16:31]
	ds_read_b128 v[118:121], v113 offset:49152
	ds_read_b128 v[122:125], v112 offset:32768
	ds_read_b128 v[126:129], v112 offset:36864
	s_waitcnt lgkmcnt(0)
	v_mfma_f32_32x32x16_bf16 v[32:47], v[118:121], v[122:125], v[32:47]
	v_mfma_f32_32x32x16_bf16 v[0:15], v[118:121], v[126:129], v[0:15]
	ds_read_b128 v[118:121], v113 offset:53248
	s_waitcnt lgkmcnt(0)
	v_mfma_f32_32x32x16_bf16 v[48:63], v[118:121], v[122:125], v[48:63]
	v_mfma_f32_32x32x16_bf16 v[16:31], v[118:121], v[126:129], v[16:31]
	ds_read_b128 v[118:121], v115 offset:49152
	ds_read_b128 v[122:125], v114 offset:32768
	ds_read_b128 v[126:129], v114 offset:36864
	s_waitcnt lgkmcnt(0)
	v_mfma_f32_32x32x16_bf16 v[32:47], v[118:121], v[122:125], v[32:47]
	v_mfma_f32_32x32x16_bf16 v[0:15], v[118:121], v[126:129], v[0:15]
	ds_read_b128 v[118:121], v115 offset:53248
	s_waitcnt lgkmcnt(0)
	v_mfma_f32_32x32x16_bf16 v[48:63], v[118:121], v[122:125], v[48:63]
	v_mfma_f32_32x32x16_bf16 v[16:31], v[118:121], v[126:129], v[16:31]
	ds_read_b128 v[118:121], v117 offset:49152
	ds_read_b128 v[122:125], v116 offset:32768
	ds_read_b128 v[126:129], v116 offset:36864
	s_waitcnt lgkmcnt(0)
	v_mfma_f32_32x32x16_bf16 v[32:47], v[118:121], v[122:125], v[32:47]
	v_mfma_f32_32x32x16_bf16 v[0:15], v[118:121], v[126:129], v[0:15]
	ds_read_b128 v[118:121], v117 offset:53248
	s_waitcnt vmcnt(0)
	s_waitcnt vmcnt(0) lgkmcnt(0)
	s_barrier
	v_mfma_f32_32x32x16_bf16 v[48:63], v[118:121], v[122:125], v[48:63]
	v_mfma_f32_32x32x16_bf16 v[16:31], v[118:121], v[126:129], v[16:31]
	global_load_lds_dwordx4 v64, s[98:99]
	s_mov_b32 m0, s71
	s_nop 0
	global_load_lds_dwordx4 v66, s[98:99]
	s_mov_b32 m0, s72
	s_nop 0
	global_load_lds_dwordx4 v68, s[98:99]
	s_mov_b32 m0, s73
	s_nop 0
	global_load_lds_dwordx4 v70, s[98:99]
	s_mov_b32 m0, s78
	s_nop 0
	global_load_lds_dwordx4 v64, s[100:101]
	s_mov_b32 m0, s79
	s_nop 0
	global_load_lds_dwordx4 v66, s[100:101]
	ds_read_b128 v[118:121], v111 offset:16384
	s_mov_b32 m0, s80
	s_nop 0
	global_load_lds_dwordx4 v68, s[100:101]
	s_mov_b32 m0, s81
	ds_read_b128 v[122:125], v110
	global_load_lds_dwordx4 v70, s[100:101]
	s_add_u32 s98, s98, 0x80
	s_addc_u32 s99, s99, 0
	s_add_u32 s100, s100, 0x80
	s_addc_u32 s101, s101, 0
	ds_read_b128 v[126:129], v110 offset:4096
	s_waitcnt lgkmcnt(0)
	v_mfma_f32_32x32x16_bf16 v[32:47], v[118:121], v[122:125], v[32:47]
	s_mov_b32 m0, s11
	v_mfma_f32_32x32x16_bf16 v[0:15], v[118:121], v[126:129], v[0:15]
	ds_read_b128 v[118:121], v111 offset:20480
	s_waitcnt lgkmcnt(0)
	v_mfma_f32_32x32x16_bf16 v[48:63], v[118:121], v[122:125], v[48:63]
	v_mfma_f32_32x32x16_bf16 v[16:31], v[118:121], v[126:129], v[16:31]
	ds_read_b128 v[118:121], v113 offset:16384
	ds_read_b128 v[122:125], v112
	ds_read_b128 v[126:129], v112 offset:4096
	s_waitcnt lgkmcnt(0)
	v_mfma_f32_32x32x16_bf16 v[32:47], v[118:121], v[122:125], v[32:47]
	v_mfma_f32_32x32x16_bf16 v[0:15], v[118:121], v[126:129], v[0:15]
	ds_read_b128 v[118:121], v113 offset:20480
	s_waitcnt lgkmcnt(0)
	v_mfma_f32_32x32x16_bf16 v[48:63], v[118:121], v[122:125], v[48:63]
	v_mfma_f32_32x32x16_bf16 v[16:31], v[118:121], v[126:129], v[16:31]
	ds_read_b128 v[118:121], v115 offset:16384
	ds_read_b128 v[122:125], v114
	ds_read_b128 v[126:129], v114 offset:4096
	s_waitcnt lgkmcnt(0)
	v_mfma_f32_32x32x16_bf16 v[32:47], v[118:121], v[122:125], v[32:47]
	v_mfma_f32_32x32x16_bf16 v[0:15], v[118:121], v[126:129], v[0:15]
	ds_read_b128 v[118:121], v115 offset:20480
	s_waitcnt lgkmcnt(0)
	v_mfma_f32_32x32x16_bf16 v[48:63], v[118:121], v[122:125], v[48:63]
	v_mfma_f32_32x32x16_bf16 v[16:31], v[118:121], v[126:129], v[16:31]
	ds_read_b128 v[118:121], v117 offset:16384
	ds_read_b128 v[122:125], v116
	ds_read_b128 v[126:129], v116 offset:4096
	s_waitcnt lgkmcnt(0)
	v_mfma_f32_32x32x16_bf16 v[32:47], v[118:121], v[122:125], v[32:47]
	v_mfma_f32_32x32x16_bf16 v[0:15], v[118:121], v[126:129], v[0:15]
	ds_read_b128 v[118:121], v117 offset:20480
	s_waitcnt vmcnt(0)
	s_waitcnt vmcnt(0) lgkmcnt(0)
	s_barrier
	v_mfma_f32_32x32x16_bf16 v[48:63], v[118:121], v[122:125], v[48:63]
	v_mfma_f32_32x32x16_bf16 v[16:31], v[118:121], v[126:129], v[16:31]
	global_load_lds_dwordx4 v64, s[98:99]
	s_mov_b32 m0, s15
	s_nop 0
	global_load_lds_dwordx4 v66, s[98:99]
	s_mov_b32 m0, s28
	s_nop 0
	global_load_lds_dwordx4 v68, s[98:99]
	s_mov_b32 m0, s30
	s_nop 0
	global_load_lds_dwordx4 v70, s[98:99]
	s_mov_b32 m0, s31
	s_nop 0
	global_load_lds_dwordx4 v64, s[100:101]
	s_mov_b32 m0, s34
	s_nop 0
	global_load_lds_dwordx4 v66, s[100:101]
	s_mov_b32 m0, s35
	s_nop 0
	global_load_lds_dwordx4 v68, s[100:101]
	ds_read_b128 v[118:121], v111 offset:49152
	s_mov_b32 m0, s29
	s_nop 0
	global_load_lds_dwordx4 v70, s[100:101]
	s_add_u32 s98, s98, 0x80
	s_addc_u32 s99, s99, 0
	s_add_u32 s100, s100, 0x80
	s_addc_u32 s101, s101, 0
	ds_read_b128 v[122:125], v110 offset:32768
	ds_read_b128 v[126:129], v110 offset:36864
	s_waitcnt lgkmcnt(0)
	v_mfma_f32_32x32x16_bf16 v[32:47], v[118:121], v[122:125], v[32:47]
	s_mov_b32 m0, s70
	v_mfma_f32_32x32x16_bf16 v[0:15], v[118:121], v[126:129], v[0:15]
	ds_read_b128 v[118:121], v111 offset:53248
	s_waitcnt lgkmcnt(0)
	v_mfma_f32_32x32x16_bf16 v[48:63], v[118:121], v[122:125], v[48:63]
	v_mfma_f32_32x32x16_bf16 v[16:31], v[118:121], v[126:129], v[16:31]
	ds_read_b128 v[118:121], v113 offset:49152
	ds_read_b128 v[122:125], v112 offset:32768
	ds_read_b128 v[126:129], v112 offset:36864
	s_waitcnt lgkmcnt(0)
	v_mfma_f32_32x32x16_bf16 v[32:47], v[118:121], v[122:125], v[32:47]
	v_mfma_f32_32x32x16_bf16 v[0:15], v[118:121], v[126:129], v[0:15]
	ds_read_b128 v[118:121], v113 offset:53248
	s_waitcnt lgkmcnt(0)
	v_mfma_f32_32x32x16_bf16 v[48:63], v[118:121], v[122:125], v[48:63]
	v_mfma_f32_32x32x16_bf16 v[16:31], v[118:121], v[126:129], v[16:31]
	ds_read_b128 v[118:121], v115 offset:49152
	ds_read_b128 v[122:125], v114 offset:32768
	ds_read_b128 v[126:129], v114 offset:36864
	s_waitcnt lgkmcnt(0)
	v_mfma_f32_32x32x16_bf16 v[32:47], v[118:121], v[122:125], v[32:47]
	v_mfma_f32_32x32x16_bf16 v[0:15], v[118:121], v[126:129], v[0:15]
	ds_read_b128 v[118:121], v115 offset:53248
	s_waitcnt lgkmcnt(0)
	v_mfma_f32_32x32x16_bf16 v[48:63], v[118:121], v[122:125], v[48:63]
	v_mfma_f32_32x32x16_bf16 v[16:31], v[118:121], v[126:129], v[16:31]
	ds_read_b128 v[118:121], v117 offset:49152
	ds_read_b128 v[122:125], v116 offset:32768
	ds_read_b128 v[126:129], v116 offset:36864
	s_waitcnt lgkmcnt(0)
	v_mfma_f32_32x32x16_bf16 v[32:47], v[118:121], v[122:125], v[32:47]
	v_mfma_f32_32x32x16_bf16 v[0:15], v[118:121], v[126:129], v[0:15]
	ds_read_b128 v[118:121], v117 offset:53248
	s_waitcnt vmcnt(0)
	s_waitcnt vmcnt(0) lgkmcnt(0)
	s_barrier
	v_mfma_f32_32x32x16_bf16 v[48:63], v[118:121], v[122:125], v[48:63]
	v_mfma_f32_32x32x16_bf16 v[16:31], v[118:121], v[126:129], v[16:31]
	global_load_lds_dwordx4 v64, s[98:99]
	s_mov_b32 m0, s71
	s_nop 0
	global_load_lds_dwordx4 v66, s[98:99]
	s_mov_b32 m0, s72
	s_nop 0
	global_load_lds_dwordx4 v68, s[98:99]
	s_mov_b32 m0, s73
	s_nop 0
	global_load_lds_dwordx4 v70, s[98:99]
	s_mov_b32 m0, s78
	s_nop 0
	global_load_lds_dwordx4 v64, s[100:101]
	s_mov_b32 m0, s79
	s_nop 0
	global_load_lds_dwordx4 v66, s[100:101]
	ds_read_b128 v[118:121], v111 offset:16384
	s_mov_b32 m0, s80
	s_nop 0
	global_load_lds_dwordx4 v68, s[100:101]
	s_mov_b32 m0, s81
	ds_read_b128 v[122:125], v110
	global_load_lds_dwordx4 v70, s[100:101]
	s_add_u32 s98, s98, 0x80
	s_addc_u32 s99, s99, 0
	s_add_u32 s100, s100, 0x80
	s_addc_u32 s101, s101, 0
	ds_read_b128 v[126:129], v110 offset:4096
	s_waitcnt lgkmcnt(0)
	v_mfma_f32_32x32x16_bf16 v[32:47], v[118:121], v[122:125], v[32:47]
	s_mov_b32 m0, s11
	v_mfma_f32_32x32x16_bf16 v[0:15], v[118:121], v[126:129], v[0:15]
	ds_read_b128 v[118:121], v111 offset:20480
	s_waitcnt lgkmcnt(0)
	v_mfma_f32_32x32x16_bf16 v[48:63], v[118:121], v[122:125], v[48:63]
	v_mfma_f32_32x32x16_bf16 v[16:31], v[118:121], v[126:129], v[16:31]
	ds_read_b128 v[118:121], v113 offset:16384
	ds_read_b128 v[122:125], v112
	ds_read_b128 v[126:129], v112 offset:4096
	s_waitcnt lgkmcnt(0)
	v_mfma_f32_32x32x16_bf16 v[32:47], v[118:121], v[122:125], v[32:47]
	v_mfma_f32_32x32x16_bf16 v[0:15], v[118:121], v[126:129], v[0:15]
	ds_read_b128 v[118:121], v113 offset:20480
	s_waitcnt lgkmcnt(0)
	v_mfma_f32_32x32x16_bf16 v[48:63], v[118:121], v[122:125], v[48:63]
	v_mfma_f32_32x32x16_bf16 v[16:31], v[118:121], v[126:129], v[16:31]
	ds_read_b128 v[118:121], v115 offset:16384
	ds_read_b128 v[122:125], v114
	ds_read_b128 v[126:129], v114 offset:4096
	s_waitcnt lgkmcnt(0)
	v_mfma_f32_32x32x16_bf16 v[32:47], v[118:121], v[122:125], v[32:47]
	v_mfma_f32_32x32x16_bf16 v[0:15], v[118:121], v[126:129], v[0:15]
	ds_read_b128 v[118:121], v115 offset:20480
	s_waitcnt lgkmcnt(0)
	v_mfma_f32_32x32x16_bf16 v[48:63], v[118:121], v[122:125], v[48:63]
	v_mfma_f32_32x32x16_bf16 v[16:31], v[118:121], v[126:129], v[16:31]
	ds_read_b128 v[118:121], v117 offset:16384
	ds_read_b128 v[122:125], v116
	ds_read_b128 v[126:129], v116 offset:4096
	s_waitcnt lgkmcnt(0)
	v_mfma_f32_32x32x16_bf16 v[32:47], v[118:121], v[122:125], v[32:47]
	v_mfma_f32_32x32x16_bf16 v[0:15], v[118:121], v[126:129], v[0:15]
	ds_read_b128 v[118:121], v117 offset:20480
	s_waitcnt vmcnt(0)
	s_waitcnt vmcnt(0) lgkmcnt(0)
	s_barrier
	v_mfma_f32_32x32x16_bf16 v[48:63], v[118:121], v[122:125], v[48:63]
	v_mfma_f32_32x32x16_bf16 v[16:31], v[118:121], v[126:129], v[16:31]
	global_load_lds_dwordx4 v64, s[98:99]
	s_mov_b32 m0, s15
	s_nop 0
	global_load_lds_dwordx4 v66, s[98:99]
	s_mov_b32 m0, s28
	s_nop 0
	global_load_lds_dwordx4 v68, s[98:99]
	s_mov_b32 m0, s30
	s_nop 0
	global_load_lds_dwordx4 v70, s[98:99]
	s_mov_b32 m0, s31
	s_nop 0
	global_load_lds_dwordx4 v64, s[100:101]
	s_mov_b32 m0, s34
	s_nop 0
	global_load_lds_dwordx4 v66, s[100:101]
	s_mov_b32 m0, s35
	s_nop 0
	global_load_lds_dwordx4 v68, s[100:101]
	ds_read_b128 v[118:121], v111 offset:49152
	s_mov_b32 m0, s29
	s_nop 0
	global_load_lds_dwordx4 v70, s[100:101]
	s_add_u32 s98, s98, 0x80
	s_addc_u32 s99, s99, 0
	s_add_u32 s100, s100, 0x80
	s_addc_u32 s101, s101, 0
	ds_read_b128 v[122:125], v110 offset:32768
	ds_read_b128 v[126:129], v110 offset:36864
	s_waitcnt lgkmcnt(0)
	v_mfma_f32_32x32x16_bf16 v[32:47], v[118:121], v[122:125], v[32:47]
	s_mov_b32 m0, s70
	v_mfma_f32_32x32x16_bf16 v[0:15], v[118:121], v[126:129], v[0:15]
	ds_read_b128 v[118:121], v111 offset:53248
	s_waitcnt lgkmcnt(0)
	v_mfma_f32_32x32x16_bf16 v[48:63], v[118:121], v[122:125], v[48:63]
	v_mfma_f32_32x32x16_bf16 v[16:31], v[118:121], v[126:129], v[16:31]
	ds_read_b128 v[118:121], v113 offset:49152
	ds_read_b128 v[122:125], v112 offset:32768
	ds_read_b128 v[126:129], v112 offset:36864
	s_waitcnt lgkmcnt(0)
	v_mfma_f32_32x32x16_bf16 v[32:47], v[118:121], v[122:125], v[32:47]
	v_mfma_f32_32x32x16_bf16 v[0:15], v[118:121], v[126:129], v[0:15]
	ds_read_b128 v[118:121], v113 offset:53248
	s_waitcnt lgkmcnt(0)
	v_mfma_f32_32x32x16_bf16 v[48:63], v[118:121], v[122:125], v[48:63]
	v_mfma_f32_32x32x16_bf16 v[16:31], v[118:121], v[126:129], v[16:31]
	ds_read_b128 v[118:121], v115 offset:49152
	ds_read_b128 v[122:125], v114 offset:32768
	ds_read_b128 v[126:129], v114 offset:36864
	s_waitcnt lgkmcnt(0)
	v_mfma_f32_32x32x16_bf16 v[32:47], v[118:121], v[122:125], v[32:47]
	v_mfma_f32_32x32x16_bf16 v[0:15], v[118:121], v[126:129], v[0:15]
	ds_read_b128 v[118:121], v115 offset:53248
	s_waitcnt lgkmcnt(0)
	v_mfma_f32_32x32x16_bf16 v[48:63], v[118:121], v[122:125], v[48:63]
	v_mfma_f32_32x32x16_bf16 v[16:31], v[118:121], v[126:129], v[16:31]
	ds_read_b128 v[118:121], v117 offset:49152
	ds_read_b128 v[122:125], v116 offset:32768
	ds_read_b128 v[126:129], v116 offset:36864
	s_waitcnt lgkmcnt(0)
	v_mfma_f32_32x32x16_bf16 v[32:47], v[118:121], v[122:125], v[32:47]
	v_mfma_f32_32x32x16_bf16 v[0:15], v[118:121], v[126:129], v[0:15]
	ds_read_b128 v[118:121], v117 offset:53248
	s_waitcnt vmcnt(0)
	s_waitcnt vmcnt(0) lgkmcnt(0)
	s_barrier
	global_load_lds_dwordx4 v64, s[98:99]
	s_mov_b32 m0, s71
	v_mfma_f32_32x32x16_bf16 v[48:63], v[118:121], v[122:125], v[48:63]
	global_load_lds_dwordx4 v66, s[98:99]
	s_mov_b32 m0, s72
	s_nop 0
	global_load_lds_dwordx4 v68, s[98:99]
	s_mov_b32 m0, s73
	v_mfma_f32_32x32x16_bf16 v[16:31], v[118:121], v[126:129], v[16:31]
	global_load_lds_dwordx4 v70, s[98:99]
	s_mov_b32 m0, s78
	s_nop 0
	global_load_lds_dwordx4 v64, s[100:101]
	s_mov_b32 m0, s79
	s_nop 0
	global_load_lds_dwordx4 v66, s[100:101]
	ds_read_b128 v[76:79], v111 offset:16384
	s_mov_b32 m0, s80
	s_nop 0
	global_load_lds_dwordx4 v68, s[100:101]
	s_mov_b32 m0, s81
	ds_read_b128 v[84:87], v110
	global_load_lds_dwordx4 v70, s[100:101]
	ds_read_b128 v[80:83], v110 offset:4096
	s_waitcnt lgkmcnt(0)
	v_mfma_f32_32x32x16_bf16 v[32:47], v[76:79], v[84:87], v[32:47]
	v_mfma_f32_32x32x16_bf16 v[0:15], v[76:79], v[80:83], v[0:15]
	ds_read_b128 v[76:79], v111 offset:20480
	s_waitcnt lgkmcnt(0)
	v_mfma_f32_32x32x16_bf16 v[48:63], v[76:79], v[84:87], v[48:63]
	v_mfma_f32_32x32x16_bf16 v[16:31], v[76:79], v[80:83], v[16:31]
	ds_read_b128 v[76:79], v113 offset:16384
	ds_read_b128 v[80:83], v112
	ds_read_b128 v[84:87], v112 offset:4096
	s_waitcnt lgkmcnt(0)
	v_mfma_f32_32x32x16_bf16 v[32:47], v[76:79], v[80:83], v[32:47]
	v_mfma_f32_32x32x16_bf16 v[0:15], v[76:79], v[84:87], v[0:15]
	ds_read_b128 v[76:79], v113 offset:20480
	s_waitcnt lgkmcnt(0)
	v_mfma_f32_32x32x16_bf16 v[48:63], v[76:79], v[80:83], v[48:63]
	v_mfma_f32_32x32x16_bf16 v[16:31], v[76:79], v[84:87], v[16:31]
	ds_read_b128 v[76:79], v115 offset:16384
	ds_read_b128 v[80:83], v114
	ds_read_b128 v[84:87], v114 offset:4096
	s_waitcnt lgkmcnt(0)
	v_mfma_f32_32x32x16_bf16 v[32:47], v[76:79], v[80:83], v[32:47]
	v_mfma_f32_32x32x16_bf16 v[0:15], v[76:79], v[84:87], v[0:15]
	ds_read_b128 v[76:79], v115 offset:20480
	s_waitcnt lgkmcnt(0)
	v_mfma_f32_32x32x16_bf16 v[48:63], v[76:79], v[80:83], v[48:63]
	v_mfma_f32_32x32x16_bf16 v[16:31], v[76:79], v[84:87], v[16:31]
	ds_read_b128 v[76:79], v117 offset:16384
	ds_read_b128 v[80:83], v116
	ds_read_b128 v[84:87], v116 offset:4096
	s_waitcnt lgkmcnt(0)
	v_mfma_f32_32x32x16_bf16 v[32:47], v[76:79], v[80:83], v[32:47]
	v_mfma_f32_32x32x16_bf16 v[0:15], v[76:79], v[84:87], v[0:15]
	ds_read_b128 v[76:79], v117 offset:20480
	s_waitcnt vmcnt(0)
	s_waitcnt vmcnt(0) lgkmcnt(0)
	s_barrier
	v_mfma_f32_32x32x16_bf16 v[48:63], v[76:79], v[80:83], v[48:63]
	v_mfma_f32_32x32x16_bf16 v[16:31], v[76:79], v[84:87], v[16:31]
	ds_read_b128 v[76:79], v111 offset:49152
	ds_read_b128 v[80:83], v110 offset:32768
	ds_read_b128 v[84:87], v110 offset:36864
	s_waitcnt lgkmcnt(1)
	v_mfma_f32_32x32x16_bf16 v[32:47], v[76:79], v[80:83], v[32:47]
	s_waitcnt lgkmcnt(0)
	v_mfma_f32_32x32x16_bf16 v[0:15], v[76:79], v[84:87], v[0:15]
	ds_read_b128 v[76:79], v111 offset:53248
	s_waitcnt lgkmcnt(0)
	v_mfma_f32_32x32x16_bf16 v[48:63], v[76:79], v[80:83], v[48:63]
	v_mfma_f32_32x32x16_bf16 v[16:31], v[76:79], v[84:87], v[16:31]
	ds_read_b128 v[76:79], v113 offset:49152
	ds_read_b128 v[80:83], v112 offset:32768
	ds_read_b128 v[84:87], v112 offset:36864
	s_waitcnt lgkmcnt(1)
	v_mfma_f32_32x32x16_bf16 v[32:47], v[76:79], v[80:83], v[32:47]
	s_waitcnt lgkmcnt(0)
	v_mfma_f32_32x32x16_bf16 v[0:15], v[76:79], v[84:87], v[0:15]
	ds_read_b128 v[76:79], v113 offset:53248
	s_waitcnt lgkmcnt(0)
	v_mfma_f32_32x32x16_bf16 v[48:63], v[76:79], v[80:83], v[48:63]
	v_mfma_f32_32x32x16_bf16 v[16:31], v[76:79], v[84:87], v[16:31]
	ds_read_b128 v[76:79], v115 offset:49152
	ds_read_b128 v[80:83], v114 offset:32768
	ds_read_b128 v[84:87], v114 offset:36864
	s_waitcnt lgkmcnt(1)
	v_mfma_f32_32x32x16_bf16 v[32:47], v[76:79], v[80:83], v[32:47]
	s_waitcnt lgkmcnt(0)
	v_mfma_f32_32x32x16_bf16 v[0:15], v[76:79], v[84:87], v[0:15]
	ds_read_b128 v[76:79], v115 offset:53248
	s_waitcnt lgkmcnt(0)
	v_mfma_f32_32x32x16_bf16 v[48:63], v[76:79], v[80:83], v[48:63]
	v_mfma_f32_32x32x16_bf16 v[16:31], v[76:79], v[84:87], v[16:31]
	ds_read_b128 v[76:79], v117 offset:49152
	ds_read_b128 v[80:83], v116 offset:32768
	ds_read_b128 v[84:87], v116 offset:36864
	ds_read_b128 v[88:91], v117 offset:53248
	s_waitcnt vmcnt(0)
	s_waitcnt lgkmcnt(0)
	s_barrier
	v_mfma_f32_32x32x16_bf16 v[32:47], v[76:79], v[80:83], v[32:47]
	v_mfma_f32_32x32x16_bf16 v[0:15], v[76:79], v[84:87], v[0:15]
	v_add_u32_e32 v78, s10, v93
	v_lshlrev_b32_e32 v72, 8, v78
	v_and_b32_e32 v72, 0x1fdf00, v72
	v_lshl_add_u64 v[76:77], v[74:75], 0, v[72:73]
	v_mfma_f32_32x32x16_bf16 v[48:63], v[88:91], v[80:83], v[48:63]
	v_mfma_f32_32x32x16_bf16 v[16:31], v[88:91], v[84:87], v[16:31]
	s_cmp_gt_i32 s69, 15
	s_cbranch_scc1 .LBB0_123
	global_load_dwordx4 v[80:83], v[76:77], off offset:128
	global_load_dwordx4 v[84:87], v[76:77], off
	s_waitcnt vmcnt(1)
	s_nop 6
	v_pk_mul_f32 v[88:89], v[50:51], v[82:83]
	v_pk_mul_f32 v[90:91], v[48:49], v[80:81]
	v_pk_mul_f32 v[82:83], v[34:35], v[82:83]
	v_pk_mul_f32 v[80:81], v[32:33], v[80:81]
	s_waitcnt vmcnt(0)
	v_pk_fma_f32 v[34:35], v[34:35], v[86:87], v[88:89] neg_lo:[0,0,1] neg_hi:[0,0,1]
	v_pk_fma_f32 v[32:33], v[32:33], v[84:85], v[90:91] neg_lo:[0,0,1] neg_hi:[0,0,1]
	v_pk_fma_f32 v[50:51], v[50:51], v[86:87], v[82:83]
	v_pk_fma_f32 v[48:49], v[48:49], v[84:85], v[80:81]

.LBB0_252:
	s_lshl_b32 s94, s14, 7
	s_ashr_i32 s95, s94, 31
	s_lshl_b32 s96, s15, 7
	s_lshl_b64 s[14:15], s[94:95], 11
	s_add_u32 s28, s36, s14
	s_addc_u32 s29, s37, s15
	s_ashr_i32 s97, s96, 31
	s_lshl_b64 s[14:15], s[96:97], 11
	v_readlane_b32 s52, v245, 37
	v_readlane_b32 s53, v245, 38
	s_add_u32 s14, s52, s14
	s_addc_u32 s15, s53, s15
	v_readfirstlane_b32 s68, v88
	v_mov_b32_e32 v2, s15
	v_mov_b32_e32 v3, s29
	v_mov_b32_e32 v4, s14
	v_mov_b32_e32 v5, s28
	s_add_u32 s98, s28, 0x80
	s_addc_u32 s99, s29, 0
	v_lshl_add_u64 v[72:73], s[28:29], 0, v[64:65]
	s_mov_b32 m0, s68
	v_cndmask_b32_e64 v1, v2, v3, s[4:5]
	v_cndmask_b32_e64 v0, v4, v5, s[4:5]
	v_readfirstlane_b32 s69, v91
	global_load_lds_dwordx4 v[72:73], off
	v_lshl_add_u64 v[74:75], v[0:1], 0, v[66:67]
	s_mov_b32 m0, s69
	v_cndmask_b32_e64 v1, v2, v3, s[6:7]
	v_cndmask_b32_e64 v0, v4, v5, s[6:7]
	v_readfirstlane_b32 s70, v92
	global_load_lds_dwordx4 v[74:75], off
	v_lshl_add_u64 v[76:77], v[0:1], 0, v[68:69]
	s_mov_b32 m0, s70
	v_cndmask_b32_e64 v1, v2, v3, s[8:9]
	v_cndmask_b32_e64 v0, v4, v5, s[8:9]
	v_readfirstlane_b32 s71, v93
	global_load_lds_dwordx4 v[76:77], off
	v_lshl_add_u64 v[78:79], v[0:1], 0, v[70:71]
	s_mov_b32 m0, s71
	v_readfirstlane_b32 s29, v94
	global_load_lds_dwordx4 v[78:79], off
	s_add_u32 s100, s14, 0x80
	s_addc_u32 s101, s15, 0
	v_lshl_add_u64 v[80:81], s[14:15], 0, v[64:65]
	s_mov_b32 m0, s29
	v_readfirstlane_b32 s85, v95
	global_load_lds_dwordx4 v[80:81], off
	v_lshl_add_u64 v[82:83], s[14:15], 0, v[66:67]
	s_mov_b32 m0, s85
	v_readfirstlane_b32 s86, v96
	global_load_lds_dwordx4 v[82:83], off
	v_lshl_add_u64 v[84:85], s[14:15], 0, v[68:69]
	s_mov_b32 m0, s86
	v_readfirstlane_b32 s87, v97
	global_load_lds_dwordx4 v[84:85], off
	v_lshl_add_u64 v[86:87], s[14:15], 0, v[70:71]
	s_mov_b32 m0, s87
	v_readfirstlane_b32 s14, v98
	global_load_lds_dwordx4 v[86:87], off
	s_mov_b32 m0, s14
	v_readfirstlane_b32 s15, v99
	s_waitcnt vmcnt(0)
	s_waitcnt vmcnt(0) lgkmcnt(0)
	s_barrier
	global_load_lds_dwordx4 v64, s[98:99]
	s_mov_b32 m0, s15
	v_readfirstlane_b32 s72, v100
	global_load_lds_dwordx4 v66, s[98:99]
	s_mov_b32 m0, s72
	v_readfirstlane_b32 s73, v101
	global_load_lds_dwordx4 v68, s[98:99]
	s_mov_b32 m0, s73
	v_readfirstlane_b32 s95, v102
	global_load_lds_dwordx4 v70, s[98:99]
	s_mov_b32 m0, s95
	v_readfirstlane_b32 s97, v103
	global_load_lds_dwordx4 v64, s[100:101]
	s_mov_b32 m0, s97
	v_readfirstlane_b32 s28, v104
	global_load_lds_dwordx4 v66, s[100:101]
	s_mov_b32 m0, s28
	v_readfirstlane_b32 s84, v105
	global_load_lds_dwordx4 v68, s[100:101]
	s_mov_b32 m0, s84
	v_readfirstlane_b32 s34, v94
	global_load_lds_dwordx4 v70, s[100:101]
	s_add_u32 s98, s98, 0x80
	s_addc_u32 s99, s99, 0
	s_add_u32 s100, s100, 0x80
	s_addc_u32 s101, s101, 0
	ds_read_b128 v[0:3], v106
	ds_read_b128 v[4:7], v107 offset:16384
	ds_read_b128 v[8:11], v106 offset:4096
	ds_read_b128 v[12:15], v107 offset:20480
	s_waitcnt lgkmcnt(0)
	v_mfma_f32_32x32x16_bf16 v[48:63], v[4:7], v[0:3], 0
	ds_read_b128 v[114:117], v108
	ds_read_b128 v[118:121], v109 offset:16384
	ds_read_b128 v[122:125], v108 offset:4096
	ds_read_b128 v[126:129], v109 offset:20480
	s_mov_b32 m0, s68
	v_readfirstlane_b32 s35, v95
	v_readlane_b32 s54, v245, 39
	v_readlane_b32 s55, v245, 40
	v_readlane_b32 s56, v245, 41
	v_readlane_b32 s57, v245, 42
	v_mfma_f32_32x32x16_bf16 v[32:47], v[12:15], v[0:3], 0
	v_readlane_b32 s58, v245, 43
	v_readlane_b32 s59, v245, 44
	v_readlane_b32 s60, v245, 45
	v_readlane_b32 s61, v245, 46
	v_readlane_b32 s62, v245, 47
	v_readlane_b32 s63, v245, 48
	v_readlane_b32 s64, v245, 49
	v_mfma_f32_32x32x16_bf16 v[16:31], v[4:7], v[8:11], 0
	v_readlane_b32 s65, v245, 50
	v_readlane_b32 s66, v245, 51
	v_readlane_b32 s67, v245, 52
	v_readlane_b32 s52, v245, 5
	v_readlane_b32 s53, v245, 6
	s_add_i32 s13, s13, s33
	v_readlane_b32 s54, v245, 7
	v_mfma_f32_32x32x16_bf16 v[0:15], v[12:15], v[8:11], 0
	v_readlane_b32 s55, v245, 8
	v_readlane_b32 s56, v245, 9
	v_readlane_b32 s57, v245, 10
	v_readlane_b32 s58, v245, 11
	v_readlane_b32 s59, v245, 12
	v_readlane_b32 s60, v245, 13
	v_readlane_b32 s61, v245, 14
	s_waitcnt lgkmcnt(0)
	v_mfma_f32_32x32x16_bf16 v[48:63], v[118:121], v[114:117], v[48:63]
	v_readlane_b32 s62, v245, 15
	v_readlane_b32 s63, v245, 16
	v_readlane_b32 s64, v245, 17
	v_readlane_b32 s65, v245, 18
	v_readlane_b32 s66, v245, 19
	v_readlane_b32 s67, v245, 20
	v_mfma_f32_32x32x16_bf16 v[32:47], v[126:129], v[114:117], v[32:47]
	v_mfma_f32_32x32x16_bf16 v[16:31], v[118:121], v[122:125], v[16:31]
	v_mfma_f32_32x32x16_bf16 v[0:15], v[126:129], v[122:125], v[0:15]
	ds_read_b128 v[114:117], v110
	ds_read_b128 v[118:121], v111 offset:16384
	ds_read_b128 v[122:125], v110 offset:4096
	ds_read_b128 v[126:129], v111 offset:20480
	s_waitcnt lgkmcnt(0)
	v_mfma_f32_32x32x16_bf16 v[48:63], v[118:121], v[114:117], v[48:63]
	v_mfma_f32_32x32x16_bf16 v[32:47], v[126:129], v[114:117], v[32:47]
	v_mfma_f32_32x32x16_bf16 v[16:31], v[118:121], v[122:125], v[16:31]
	v_mfma_f32_32x32x16_bf16 v[0:15], v[126:129], v[122:125], v[0:15]
	ds_read_b128 v[114:117], v112
	ds_read_b128 v[118:121], v113 offset:16384
	ds_read_b128 v[122:125], v112 offset:4096
	ds_read_b128 v[126:129], v113 offset:20480
	s_waitcnt vmcnt(0)
	s_waitcnt vmcnt(0) lgkmcnt(0)
	s_barrier
	v_mfma_f32_32x32x16_bf16 v[48:63], v[118:121], v[114:117], v[48:63]
	v_mfma_f32_32x32x16_bf16 v[32:47], v[126:129], v[114:117], v[32:47]
	global_load_lds_dwordx4 v64, s[98:99]
	s_mov_b32 m0, s69
	s_nop 0
	global_load_lds_dwordx4 v66, s[98:99]
	s_mov_b32 m0, s70
	v_mfma_f32_32x32x16_bf16 v[16:31], v[118:121], v[122:125], v[16:31]
	global_load_lds_dwordx4 v68, s[98:99]
	s_mov_b32 m0, s71
	s_nop 0
	global_load_lds_dwordx4 v70, s[98:99]
	s_mov_b32 m0, s29
	v_mfma_f32_32x32x16_bf16 v[0:15], v[126:129], v[122:125], v[0:15]
	global_load_lds_dwordx4 v64, s[100:101]
	s_mov_b32 m0, s85
	s_nop 0
	global_load_lds_dwordx4 v66, s[100:101]
	s_mov_b32 m0, s86
	s_nop 0
	global_load_lds_dwordx4 v68, s[100:101]
	s_mov_b32 m0, s87
	s_nop 0
	global_load_lds_dwordx4 v70, s[100:101]
	s_add_u32 s98, s98, 0x80
	s_addc_u32 s99, s99, 0
	s_add_u32 s100, s100, 0x80
	s_addc_u32 s101, s101, 0
	ds_read_b128 v[114:117], v106 offset:32768
	ds_read_b128 v[118:121], v107 offset:49152
	ds_read_b128 v[122:125], v106 offset:36864
	ds_read_b128 v[126:129], v107 offset:53248
	s_waitcnt lgkmcnt(0)
	v_mfma_f32_32x32x16_bf16 v[48:63], v[118:121], v[114:117], v[48:63]
	s_mov_b32 m0, s14
	v_mfma_f32_32x32x16_bf16 v[32:47], v[126:129], v[114:117], v[32:47]
	v_mfma_f32_32x32x16_bf16 v[16:31], v[118:121], v[122:125], v[16:31]
	v_mfma_f32_32x32x16_bf16 v[0:15], v[126:129], v[122:125], v[0:15]
	ds_read_b128 v[114:117], v108 offset:32768
	ds_read_b128 v[118:121], v109 offset:49152
	ds_read_b128 v[122:125], v108 offset:36864
	ds_read_b128 v[126:129], v109 offset:53248
	s_waitcnt lgkmcnt(0)
	v_mfma_f32_32x32x16_bf16 v[48:63], v[118:121], v[114:117], v[48:63]
	v_mfma_f32_32x32x16_bf16 v[32:47], v[126:129], v[114:117], v[32:47]
	v_mfma_f32_32x32x16_bf16 v[16:31], v[118:121], v[122:125], v[16:31]
	v_mfma_f32_32x32x16_bf16 v[0:15], v[126:129], v[122:125], v[0:15]
	ds_read_b128 v[114:117], v110 offset:32768
	ds_read_b128 v[118:121], v111 offset:49152
	ds_read_b128 v[122:125], v110 offset:36864
	ds_read_b128 v[126:129], v111 offset:53248
	s_waitcnt lgkmcnt(0)
	v_mfma_f32_32x32x16_bf16 v[48:63], v[118:121], v[114:117], v[48:63]
	v_mfma_f32_32x32x16_bf16 v[32:47], v[126:129], v[114:117], v[32:47]
	v_mfma_f32_32x32x16_bf16 v[16:31], v[118:121], v[122:125], v[16:31]
	v_mfma_f32_32x32x16_bf16 v[0:15], v[126:129], v[122:125], v[0:15]
	ds_read_b128 v[114:117], v112 offset:32768
	ds_read_b128 v[118:121], v113 offset:49152
	ds_read_b128 v[122:125], v112 offset:36864
	ds_read_b128 v[126:129], v113 offset:53248
	s_waitcnt vmcnt(0)
	s_waitcnt vmcnt(0) lgkmcnt(0)
	s_barrier
	v_mfma_f32_32x32x16_bf16 v[48:63], v[118:121], v[114:117], v[48:63]
	v_mfma_f32_32x32x16_bf16 v[32:47], v[126:129], v[114:117], v[32:47]
	global_load_lds_dwordx4 v64, s[98:99]
	s_mov_b32 m0, s15
	s_nop 0
	global_load_lds_dwordx4 v66, s[98:99]
	s_mov_b32 m0, s72
	v_mfma_f32_32x32x16_bf16 v[16:31], v[118:121], v[122:125], v[16:31]
	global_load_lds_dwordx4 v68, s[98:99]
	s_mov_b32 m0, s73
	s_nop 0
	global_load_lds_dwordx4 v70, s[98:99]
	s_mov_b32 m0, s95
	v_mfma_f32_32x32x16_bf16 v[0:15], v[126:129], v[122:125], v[0:15]
	global_load_lds_dwordx4 v64, s[100:101]
	s_mov_b32 m0, s97
	s_nop 0
	global_load_lds_dwordx4 v66, s[100:101]
	s_mov_b32 m0, s28
	s_nop 0
	global_load_lds_dwordx4 v68, s[100:101]
	s_mov_b32 m0, s84
	s_nop 0
	global_load_lds_dwordx4 v70, s[100:101]
	s_add_u32 s98, s98, 0x80
	s_addc_u32 s99, s99, 0
	s_add_u32 s100, s100, 0x80
	s_addc_u32 s101, s101, 0
	ds_read_b128 v[114:117], v106
	ds_read_b128 v[118:121], v107 offset:16384
	ds_read_b128 v[122:125], v106 offset:4096
	ds_read_b128 v[126:129], v107 offset:20480
	s_waitcnt lgkmcnt(0)
	v_mfma_f32_32x32x16_bf16 v[48:63], v[118:121], v[114:117], v[48:63]
	s_mov_b32 m0, s68
	v_mfma_f32_32x32x16_bf16 v[32:47], v[126:129], v[114:117], v[32:47]
	v_mfma_f32_32x32x16_bf16 v[16:31], v[118:121], v[122:125], v[16:31]
	v_mfma_f32_32x32x16_bf16 v[0:15], v[126:129], v[122:125], v[0:15]
	ds_read_b128 v[114:117], v108
	ds_read_b128 v[118:121], v109 offset:16384
	ds_read_b128 v[122:125], v108 offset:4096
	ds_read_b128 v[126:129], v109 offset:20480
	s_waitcnt lgkmcnt(0)
	v_mfma_f32_32x32x16_bf16 v[48:63], v[118:121], v[114:117], v[48:63]
	v_mfma_f32_32x32x16_bf16 v[32:47], v[126:129], v[114:117], v[32:47]
	v_mfma_f32_32x32x16_bf16 v[16:31], v[118:121], v[122:125], v[16:31]
	v_mfma_f32_32x32x16_bf16 v[0:15], v[126:129], v[122:125], v[0:15]
	ds_read_b128 v[114:117], v110
	ds_read_b128 v[118:121], v111 offset:16384
	ds_read_b128 v[122:125], v110 offset:4096
	ds_read_b128 v[126:129], v111 offset:20480
	s_waitcnt lgkmcnt(0)
	v_mfma_f32_32x32x16_bf16 v[48:63], v[118:121], v[114:117], v[48:63]
	v_mfma_f32_32x32x16_bf16 v[32:47], v[126:129], v[114:117], v[32:47]
	v_mfma_f32_32x32x16_bf16 v[16:31], v[118:121], v[122:125], v[16:31]
	v_mfma_f32_32x32x16_bf16 v[0:15], v[126:129], v[122:125], v[0:15]
	ds_read_b128 v[114:117], v112
	ds_read_b128 v[118:121], v113 offset:16384
	ds_read_b128 v[122:125], v112 offset:4096
	ds_read_b128 v[126:129], v113 offset:20480
	s_waitcnt vmcnt(0)
	s_waitcnt vmcnt(0) lgkmcnt(0)
	s_barrier
	v_mfma_f32_32x32x16_bf16 v[48:63], v[118:121], v[114:117], v[48:63]
	v_mfma_f32_32x32x16_bf16 v[32:47], v[126:129], v[114:117], v[32:47]
	global_load_lds_dwordx4 v64, s[98:99]
	s_mov_b32 m0, s69
	s_nop 0
	global_load_lds_dwordx4 v66, s[98:99]
	s_mov_b32 m0, s70
	v_mfma_f32_32x32x16_bf16 v[16:31], v[118:121], v[122:125], v[16:31]
	global_load_lds_dwordx4 v68, s[98:99]
	s_mov_b32 m0, s71
	s_nop 0
	global_load_lds_dwordx4 v70, s[98:99]
	s_mov_b32 m0, s29
	v_mfma_f32_32x32x16_bf16 v[0:15], v[126:129], v[122:125], v[0:15]
	global_load_lds_dwordx4 v64, s[100:101]
	s_mov_b32 m0, s85
	s_nop 0
	global_load_lds_dwordx4 v66, s[100:101]
	s_mov_b32 m0, s86
	s_nop 0
	global_load_lds_dwordx4 v68, s[100:101]
	s_mov_b32 m0, s87
	s_nop 0
	global_load_lds_dwordx4 v70, s[100:101]
	s_add_u32 s98, s98, 0x80
	s_addc_u32 s99, s99, 0
	s_add_u32 s100, s100, 0x80
	s_addc_u32 s101, s101, 0
	ds_read_b128 v[114:117], v106 offset:32768
	ds_read_b128 v[118:121], v107 offset:49152
	ds_read_b128 v[122:125], v106 offset:36864
	ds_read_b128 v[126:129], v107 offset:53248
	s_waitcnt lgkmcnt(0)
	v_mfma_f32_32x32x16_bf16 v[48:63], v[118:121], v[114:117], v[48:63]
	s_mov_b32 m0, s14
	v_mfma_f32_32x32x16_bf16 v[32:47], v[126:129], v[114:117], v[32:47]
	v_mfma_f32_32x32x16_bf16 v[16:31], v[118:121], v[122:125], v[16:31]
	v_mfma_f32_32x32x16_bf16 v[0:15], v[126:129], v[122:125], v[0:15]
	ds_read_b128 v[114:117], v108 offset:32768
	ds_read_b128 v[118:121], v109 offset:49152
	ds_read_b128 v[122:125], v108 offset:36864
	ds_read_b128 v[126:129], v109 offset:53248
	s_waitcnt lgkmcnt(0)
	v_mfma_f32_32x32x16_bf16 v[48:63], v[118:121], v[114:117], v[48:63]
	v_mfma_f32_32x32x16_bf16 v[32:47], v[126:129], v[114:117], v[32:47]
	v_mfma_f32_32x32x16_bf16 v[16:31], v[118:121], v[122:125], v[16:31]
	v_mfma_f32_32x32x16_bf16 v[0:15], v[126:129], v[122:125], v[0:15]
	ds_read_b128 v[114:117], v110 offset:32768
	ds_read_b128 v[118:121], v111 offset:49152
	ds_read_b128 v[122:125], v110 offset:36864
	ds_read_b128 v[126:129], v111 offset:53248
	s_waitcnt lgkmcnt(0)
	v_mfma_f32_32x32x16_bf16 v[48:63], v[118:121], v[114:117], v[48:63]
	v_mfma_f32_32x32x16_bf16 v[32:47], v[126:129], v[114:117], v[32:47]
	v_mfma_f32_32x32x16_bf16 v[16:31], v[118:121], v[122:125], v[16:31]
	v_mfma_f32_32x32x16_bf16 v[0:15], v[126:129], v[122:125], v[0:15]
	ds_read_b128 v[114:117], v112 offset:32768
	ds_read_b128 v[118:121], v113 offset:49152
	ds_read_b128 v[122:125], v112 offset:36864
	ds_read_b128 v[126:129], v113 offset:53248
	s_waitcnt vmcnt(0)
	s_waitcnt vmcnt(0) lgkmcnt(0)
	s_barrier
	v_mfma_f32_32x32x16_bf16 v[48:63], v[118:121], v[114:117], v[48:63]
	v_mfma_f32_32x32x16_bf16 v[32:47], v[126:129], v[114:117], v[32:47]
	global_load_lds_dwordx4 v64, s[98:99]
	s_mov_b32 m0, s15
	s_nop 0
	global_load_lds_dwordx4 v66, s[98:99]
	s_mov_b32 m0, s72
	v_mfma_f32_32x32x16_bf16 v[16:31], v[118:121], v[122:125], v[16:31]
	global_load_lds_dwordx4 v68, s[98:99]
	s_mov_b32 m0, s73
	s_nop 0
	global_load_lds_dwordx4 v70, s[98:99]
	s_mov_b32 m0, s95
	v_mfma_f32_32x32x16_bf16 v[0:15], v[126:129], v[122:125], v[0:15]
	global_load_lds_dwordx4 v64, s[100:101]
	s_mov_b32 m0, s97
	s_nop 0
	global_load_lds_dwordx4 v66, s[100:101]
	s_mov_b32 m0, s28
	s_nop 0
	global_load_lds_dwordx4 v68, s[100:101]
	s_mov_b32 m0, s84
	s_nop 0
	global_load_lds_dwordx4 v70, s[100:101]
	s_add_u32 s98, s98, 0x80
	s_addc_u32 s99, s99, 0
	s_add_u32 s100, s100, 0x80
	s_addc_u32 s101, s101, 0
	ds_read_b128 v[114:117], v106
	ds_read_b128 v[118:121], v107 offset:16384
	ds_read_b128 v[122:125], v106 offset:4096
	ds_read_b128 v[126:129], v107 offset:20480
	s_waitcnt lgkmcnt(0)
	v_mfma_f32_32x32x16_bf16 v[48:63], v[118:121], v[114:117], v[48:63]
	s_mov_b32 m0, s68
	v_mfma_f32_32x32x16_bf16 v[32:47], v[126:129], v[114:117], v[32:47]
	v_mfma_f32_32x32x16_bf16 v[16:31], v[118:121], v[122:125], v[16:31]
	v_mfma_f32_32x32x16_bf16 v[0:15], v[126:129], v[122:125], v[0:15]
	ds_read_b128 v[114:117], v108
	ds_read_b128 v[118:121], v109 offset:16384
	ds_read_b128 v[122:125], v108 offset:4096
	ds_read_b128 v[126:129], v109 offset:20480
	s_waitcnt lgkmcnt(0)
	v_mfma_f32_32x32x16_bf16 v[48:63], v[118:121], v[114:117], v[48:63]
	v_mfma_f32_32x32x16_bf16 v[32:47], v[126:129], v[114:117], v[32:47]
	v_mfma_f32_32x32x16_bf16 v[16:31], v[118:121], v[122:125], v[16:31]
	v_mfma_f32_32x32x16_bf16 v[0:15], v[126:129], v[122:125], v[0:15]
	ds_read_b128 v[114:117], v110
	ds_read_b128 v[118:121], v111 offset:16384
	ds_read_b128 v[122:125], v110 offset:4096
	ds_read_b128 v[126:129], v111 offset:20480
	s_waitcnt lgkmcnt(0)
	v_mfma_f32_32x32x16_bf16 v[48:63], v[118:121], v[114:117], v[48:63]
	v_mfma_f32_32x32x16_bf16 v[32:47], v[126:129], v[114:117], v[32:47]
	v_mfma_f32_32x32x16_bf16 v[16:31], v[118:121], v[122:125], v[16:31]
	v_mfma_f32_32x32x16_bf16 v[0:15], v[126:129], v[122:125], v[0:15]
	ds_read_b128 v[114:117], v112
	ds_read_b128 v[118:121], v113 offset:16384
	ds_read_b128 v[122:125], v112 offset:4096
	ds_read_b128 v[126:129], v113 offset:20480
	s_waitcnt vmcnt(0)
	s_waitcnt vmcnt(0) lgkmcnt(0)
	s_barrier
	v_mfma_f32_32x32x16_bf16 v[48:63], v[118:121], v[114:117], v[48:63]
	v_mfma_f32_32x32x16_bf16 v[32:47], v[126:129], v[114:117], v[32:47]
	global_load_lds_dwordx4 v64, s[98:99]
	s_mov_b32 m0, s69
	s_nop 0
	global_load_lds_dwordx4 v66, s[98:99]
	s_mov_b32 m0, s70
	v_mfma_f32_32x32x16_bf16 v[16:31], v[118:121], v[122:125], v[16:31]
	global_load_lds_dwordx4 v68, s[98:99]
	s_mov_b32 m0, s71
	s_nop 0
	global_load_lds_dwordx4 v70, s[98:99]
	s_mov_b32 m0, s29
	v_mfma_f32_32x32x16_bf16 v[0:15], v[126:129], v[122:125], v[0:15]
	global_load_lds_dwordx4 v64, s[100:101]
	s_mov_b32 m0, s85
	s_nop 0
	global_load_lds_dwordx4 v66, s[100:101]
	s_mov_b32 m0, s86
	s_nop 0
	global_load_lds_dwordx4 v68, s[100:101]
	s_mov_b32 m0, s87
	s_nop 0
	global_load_lds_dwordx4 v70, s[100:101]
	s_add_u32 s98, s98, 0x80
	s_addc_u32 s99, s99, 0
	s_add_u32 s100, s100, 0x80
	s_addc_u32 s101, s101, 0
	ds_read_b128 v[114:117], v106 offset:32768
	ds_read_b128 v[118:121], v107 offset:49152
	ds_read_b128 v[122:125], v106 offset:36864
	ds_read_b128 v[126:129], v107 offset:53248
	s_waitcnt lgkmcnt(0)
	v_mfma_f32_32x32x16_bf16 v[48:63], v[118:121], v[114:117], v[48:63]
	s_mov_b32 m0, s14
	v_mfma_f32_32x32x16_bf16 v[32:47], v[126:129], v[114:117], v[32:47]
	v_mfma_f32_32x32x16_bf16 v[16:31], v[118:121], v[122:125], v[16:31]
	v_mfma_f32_32x32x16_bf16 v[0:15], v[126:129], v[122:125], v[0:15]
	ds_read_b128 v[114:117], v108 offset:32768
	ds_read_b128 v[118:121], v109 offset:49152
	ds_read_b128 v[122:125], v108 offset:36864
	ds_read_b128 v[126:129], v109 offset:53248
	s_waitcnt lgkmcnt(0)
	v_mfma_f32_32x32x16_bf16 v[48:63], v[118:121], v[114:117], v[48:63]
	v_mfma_f32_32x32x16_bf16 v[32:47], v[126:129], v[114:117], v[32:47]
	v_mfma_f32_32x32x16_bf16 v[16:31], v[118:121], v[122:125], v[16:31]
	v_mfma_f32_32x32x16_bf16 v[0:15], v[126:129], v[122:125], v[0:15]
	ds_read_b128 v[114:117], v110 offset:32768
	ds_read_b128 v[118:121], v111 offset:49152
	ds_read_b128 v[122:125], v110 offset:36864
	ds_read_b128 v[126:129], v111 offset:53248
	s_waitcnt lgkmcnt(0)
	v_mfma_f32_32x32x16_bf16 v[48:63], v[118:121], v[114:117], v[48:63]
	v_mfma_f32_32x32x16_bf16 v[32:47], v[126:129], v[114:117], v[32:47]
	v_mfma_f32_32x32x16_bf16 v[16:31], v[118:121], v[122:125], v[16:31]
	v_mfma_f32_32x32x16_bf16 v[0:15], v[126:129], v[122:125], v[0:15]
	ds_read_b128 v[114:117], v112 offset:32768
	ds_read_b128 v[118:121], v113 offset:49152
	ds_read_b128 v[122:125], v112 offset:36864
	ds_read_b128 v[126:129], v113 offset:53248
	s_waitcnt vmcnt(0)
	s_waitcnt vmcnt(0) lgkmcnt(0)
	s_barrier
	v_mfma_f32_32x32x16_bf16 v[48:63], v[118:121], v[114:117], v[48:63]
	v_mfma_f32_32x32x16_bf16 v[32:47], v[126:129], v[114:117], v[32:47]
	global_load_lds_dwordx4 v64, s[98:99]
	s_mov_b32 m0, s15
	s_nop 0
	global_load_lds_dwordx4 v66, s[98:99]
	s_mov_b32 m0, s72
	v_mfma_f32_32x32x16_bf16 v[16:31], v[118:121], v[122:125], v[16:31]
	global_load_lds_dwordx4 v68, s[98:99]
	s_mov_b32 m0, s73
	s_nop 0
	global_load_lds_dwordx4 v70, s[98:99]
	s_mov_b32 m0, s95
	v_mfma_f32_32x32x16_bf16 v[0:15], v[126:129], v[122:125], v[0:15]
	global_load_lds_dwordx4 v64, s[100:101]
	s_mov_b32 m0, s97
	s_nop 0
	global_load_lds_dwordx4 v66, s[100:101]
	s_mov_b32 m0, s28
	s_nop 0
	global_load_lds_dwordx4 v68, s[100:101]
	s_mov_b32 m0, s84
	s_nop 0
	global_load_lds_dwordx4 v70, s[100:101]
	s_add_u32 s98, s98, 0x80
	s_addc_u32 s99, s99, 0
	s_add_u32 s100, s100, 0x80
	s_addc_u32 s101, s101, 0
	ds_read_b128 v[114:117], v106
	ds_read_b128 v[118:121], v107 offset:16384
	ds_read_b128 v[122:125], v106 offset:4096
	ds_read_b128 v[126:129], v107 offset:20480
	s_waitcnt lgkmcnt(0)
	v_mfma_f32_32x32x16_bf16 v[48:63], v[118:121], v[114:117], v[48:63]
	s_mov_b32 m0, s68
	v_readfirstlane_b32 s68, v96
	v_mfma_f32_32x32x16_bf16 v[32:47], v[126:129], v[114:117], v[32:47]
	v_mfma_f32_32x32x16_bf16 v[16:31], v[118:121], v[122:125], v[16:31]
	v_mfma_f32_32x32x16_bf16 v[0:15], v[126:129], v[122:125], v[0:15]
	ds_read_b128 v[114:117], v108
	ds_read_b128 v[118:121], v109 offset:16384
	ds_read_b128 v[122:125], v108 offset:4096
	ds_read_b128 v[126:129], v109 offset:20480
	s_waitcnt lgkmcnt(0)
	v_mfma_f32_32x32x16_bf16 v[48:63], v[118:121], v[114:117], v[48:63]
	v_mfma_f32_32x32x16_bf16 v[32:47], v[126:129], v[114:117], v[32:47]
	v_mfma_f32_32x32x16_bf16 v[16:31], v[118:121], v[122:125], v[16:31]
	v_mfma_f32_32x32x16_bf16 v[0:15], v[126:129], v[122:125], v[0:15]
	ds_read_b128 v[114:117], v110
	ds_read_b128 v[118:121], v111 offset:16384
	ds_read_b128 v[122:125], v110 offset:4096
	ds_read_b128 v[126:129], v111 offset:20480
	s_waitcnt lgkmcnt(0)
	v_mfma_f32_32x32x16_bf16 v[48:63], v[118:121], v[114:117], v[48:63]
	v_mfma_f32_32x32x16_bf16 v[32:47], v[126:129], v[114:117], v[32:47]
	v_mfma_f32_32x32x16_bf16 v[16:31], v[118:121], v[122:125], v[16:31]
	v_mfma_f32_32x32x16_bf16 v[0:15], v[126:129], v[122:125], v[0:15]
	ds_read_b128 v[114:117], v112
	ds_read_b128 v[118:121], v113 offset:16384
	ds_read_b128 v[122:125], v112 offset:4096
	ds_read_b128 v[126:129], v113 offset:20480
	s_waitcnt vmcnt(0)
	s_waitcnt vmcnt(0) lgkmcnt(0)
	s_barrier
	v_mfma_f32_32x32x16_bf16 v[48:63], v[118:121], v[114:117], v[48:63]
	v_mfma_f32_32x32x16_bf16 v[32:47], v[126:129], v[114:117], v[32:47]
	global_load_lds_dwordx4 v64, s[98:99]
	s_mov_b32 m0, s69
	v_readfirstlane_b32 s69, v97
	global_load_lds_dwordx4 v66, s[98:99]
	s_mov_b32 m0, s70
	v_mfma_f32_32x32x16_bf16 v[16:31], v[118:121], v[122:125], v[16:31]
	global_load_lds_dwordx4 v68, s[98:99]
	s_mov_b32 m0, s71
	v_readfirstlane_b32 s70, v98
	global_load_lds_dwordx4 v70, s[98:99]
	s_mov_b32 m0, s29
	v_mfma_f32_32x32x16_bf16 v[0:15], v[126:129], v[122:125], v[0:15]
	global_load_lds_dwordx4 v64, s[100:101]
	s_mov_b32 m0, s85
	v_readfirstlane_b32 s29, v93
	global_load_lds_dwordx4 v66, s[100:101]
	s_mov_b32 m0, s86
	v_readfirstlane_b32 s71, v99
	global_load_lds_dwordx4 v68, s[100:101]
	s_mov_b32 m0, s87
	v_readfirstlane_b32 s85, v103
	global_load_lds_dwordx4 v70, s[100:101]
	s_add_u32 s98, s98, 0x80
	s_addc_u32 s99, s99, 0
	s_add_u32 s100, s100, 0x80
	s_addc_u32 s101, s101, 0
	ds_read_b128 v[114:117], v106 offset:32768
	ds_read_b128 v[118:121], v107 offset:49152
	ds_read_b128 v[122:125], v106 offset:36864
	ds_read_b128 v[126:129], v107 offset:53248
	s_waitcnt lgkmcnt(0)
	v_mfma_f32_32x32x16_bf16 v[48:63], v[118:121], v[114:117], v[48:63]
	s_mov_b32 m0, s14
	v_readfirstlane_b32 s14, v88
	v_readfirstlane_b32 s86, v104
	v_readfirstlane_b32 s87, v105
	v_mfma_f32_32x32x16_bf16 v[32:47], v[126:129], v[114:117], v[32:47]
	v_mfma_f32_32x32x16_bf16 v[16:31], v[118:121], v[122:125], v[16:31]
	v_mfma_f32_32x32x16_bf16 v[0:15], v[126:129], v[122:125], v[0:15]
	ds_read_b128 v[114:117], v108 offset:32768
	ds_read_b128 v[118:121], v109 offset:49152
	ds_read_b128 v[122:125], v108 offset:36864
	ds_read_b128 v[126:129], v109 offset:53248
	s_waitcnt lgkmcnt(0)
	v_mfma_f32_32x32x16_bf16 v[48:63], v[118:121], v[114:117], v[48:63]
	v_mfma_f32_32x32x16_bf16 v[32:47], v[126:129], v[114:117], v[32:47]
	v_mfma_f32_32x32x16_bf16 v[16:31], v[118:121], v[122:125], v[16:31]
	v_mfma_f32_32x32x16_bf16 v[0:15], v[126:129], v[122:125], v[0:15]
	ds_read_b128 v[114:117], v110 offset:32768
	ds_read_b128 v[118:121], v111 offset:49152
	ds_read_b128 v[122:125], v110 offset:36864
	ds_read_b128 v[126:129], v111 offset:53248
	s_waitcnt lgkmcnt(0)
	v_mfma_f32_32x32x16_bf16 v[48:63], v[118:121], v[114:117], v[48:63]
	v_mfma_f32_32x32x16_bf16 v[32:47], v[126:129], v[114:117], v[32:47]
	v_mfma_f32_32x32x16_bf16 v[16:31], v[118:121], v[122:125], v[16:31]
	v_mfma_f32_32x32x16_bf16 v[0:15], v[126:129], v[122:125], v[0:15]
	ds_read_b128 v[114:117], v112 offset:32768
	ds_read_b128 v[118:121], v113 offset:49152
	ds_read_b128 v[122:125], v112 offset:36864
	ds_read_b128 v[126:129], v113 offset:53248
	s_waitcnt vmcnt(0)
	s_waitcnt vmcnt(0) lgkmcnt(0)
	s_barrier
	v_mfma_f32_32x32x16_bf16 v[48:63], v[118:121], v[114:117], v[48:63]
	v_mfma_f32_32x32x16_bf16 v[32:47], v[126:129], v[114:117], v[32:47]
	global_load_lds_dwordx4 v64, s[98:99]
	s_mov_b32 m0, s15
	v_readfirstlane_b32 s15, v91
	global_load_lds_dwordx4 v66, s[98:99]
	s_mov_b32 m0, s72
	v_mfma_f32_32x32x16_bf16 v[16:31], v[118:121], v[122:125], v[16:31]
	global_load_lds_dwordx4 v68, s[98:99]
	s_mov_b32 m0, s73
	v_readfirstlane_b32 s72, v100
	global_load_lds_dwordx4 v70, s[98:99]
	s_mov_b32 m0, s95
	v_mfma_f32_32x32x16_bf16 v[0:15], v[126:129], v[122:125], v[0:15]
	global_load_lds_dwordx4 v64, s[100:101]
	s_mov_b32 m0, s97
	v_readfirstlane_b32 s73, v101
	global_load_lds_dwordx4 v66, s[100:101]
	s_mov_b32 m0, s28
	v_readfirstlane_b32 s28, v92
	global_load_lds_dwordx4 v68, s[100:101]
	s_mov_b32 m0, s84
	v_readfirstlane_b32 s84, v102
	global_load_lds_dwordx4 v70, s[100:101]
	s_add_u32 s98, s98, 0x80
	s_addc_u32 s99, s99, 0
	s_add_u32 s100, s100, 0x80
	s_addc_u32 s101, s101, 0
	ds_read_b128 v[114:117], v106
	ds_read_b128 v[118:121], v107 offset:16384
	ds_read_b128 v[122:125], v106 offset:4096
	ds_read_b128 v[126:129], v107 offset:20480
	s_waitcnt lgkmcnt(0)
	v_mfma_f32_32x32x16_bf16 v[48:63], v[118:121], v[114:117], v[48:63]
	s_mov_b32 m0, s14
	v_mfma_f32_32x32x16_bf16 v[32:47], v[126:129], v[114:117], v[32:47]
	v_mfma_f32_32x32x16_bf16 v[16:31], v[118:121], v[122:125], v[16:31]
	v_mfma_f32_32x32x16_bf16 v[0:15], v[126:129], v[122:125], v[0:15]
	ds_read_b128 v[114:117], v108
	ds_read_b128 v[118:121], v109 offset:16384
	ds_read_b128 v[122:125], v108 offset:4096
	ds_read_b128 v[126:129], v109 offset:20480
	s_waitcnt lgkmcnt(0)
	v_mfma_f32_32x32x16_bf16 v[48:63], v[118:121], v[114:117], v[48:63]
	v_mfma_f32_32x32x16_bf16 v[32:47], v[126:129], v[114:117], v[32:47]
	v_mfma_f32_32x32x16_bf16 v[16:31], v[118:121], v[122:125], v[16:31]
	v_mfma_f32_32x32x16_bf16 v[0:15], v[126:129], v[122:125], v[0:15]
	ds_read_b128 v[114:117], v110
	ds_read_b128 v[118:121], v111 offset:16384
	ds_read_b128 v[122:125], v110 offset:4096
	ds_read_b128 v[126:129], v111 offset:20480
	s_waitcnt lgkmcnt(0)
	v_mfma_f32_32x32x16_bf16 v[48:63], v[118:121], v[114:117], v[48:63]
	v_mfma_f32_32x32x16_bf16 v[32:47], v[126:129], v[114:117], v[32:47]
	v_mfma_f32_32x32x16_bf16 v[16:31], v[118:121], v[122:125], v[16:31]
	v_mfma_f32_32x32x16_bf16 v[0:15], v[126:129], v[122:125], v[0:15]
	ds_read_b128 v[114:117], v112
	ds_read_b128 v[118:121], v113 offset:16384
	ds_read_b128 v[122:125], v112 offset:4096
	ds_read_b128 v[126:129], v113 offset:20480
	s_waitcnt vmcnt(0)
	s_waitcnt vmcnt(0) lgkmcnt(0)
	s_barrier
	v_mfma_f32_32x32x16_bf16 v[48:63], v[118:121], v[114:117], v[48:63]
	v_mfma_f32_32x32x16_bf16 v[32:47], v[126:129], v[114:117], v[32:47]
	global_load_lds_dwordx4 v64, s[98:99]
	s_mov_b32 m0, s15
	s_nop 0
	global_load_lds_dwordx4 v66, s[98:99]
	s_mov_b32 m0, s28
	v_mfma_f32_32x32x16_bf16 v[16:31], v[118:121], v[122:125], v[16:31]
	global_load_lds_dwordx4 v68, s[98:99]
	s_mov_b32 m0, s29
	s_nop 0
	global_load_lds_dwordx4 v70, s[98:99]
	s_mov_b32 m0, s34
	v_mfma_f32_32x32x16_bf16 v[0:15], v[126:129], v[122:125], v[0:15]
	global_load_lds_dwordx4 v64, s[100:101]
	s_mov_b32 m0, s35
	s_nop 0
	global_load_lds_dwordx4 v66, s[100:101]
	s_mov_b32 m0, s68
	s_nop 0
	global_load_lds_dwordx4 v68, s[100:101]
	s_mov_b32 m0, s69
	s_nop 0
	global_load_lds_dwordx4 v70, s[100:101]
	s_add_u32 s98, s98, 0x80
	s_addc_u32 s99, s99, 0
	s_add_u32 s100, s100, 0x80
	s_addc_u32 s101, s101, 0
	ds_read_b128 v[114:117], v106 offset:32768
	ds_read_b128 v[118:121], v107 offset:49152
	ds_read_b128 v[122:125], v106 offset:36864
	ds_read_b128 v[126:129], v107 offset:53248
	s_waitcnt lgkmcnt(0)
	v_mfma_f32_32x32x16_bf16 v[48:63], v[118:121], v[114:117], v[48:63]
	s_mov_b32 m0, s70
	v_mfma_f32_32x32x16_bf16 v[32:47], v[126:129], v[114:117], v[32:47]
	v_mfma_f32_32x32x16_bf16 v[16:31], v[118:121], v[122:125], v[16:31]
	v_mfma_f32_32x32x16_bf16 v[0:15], v[126:129], v[122:125], v[0:15]
	ds_read_b128 v[114:117], v108 offset:32768
	ds_read_b128 v[118:121], v109 offset:49152
	ds_read_b128 v[122:125], v108 offset:36864
	ds_read_b128 v[126:129], v109 offset:53248
	s_waitcnt lgkmcnt(0)
	v_mfma_f32_32x32x16_bf16 v[48:63], v[118:121], v[114:117], v[48:63]
	v_mfma_f32_32x32x16_bf16 v[32:47], v[126:129], v[114:117], v[32:47]
	v_mfma_f32_32x32x16_bf16 v[16:31], v[118:121], v[122:125], v[16:31]
	v_mfma_f32_32x32x16_bf16 v[0:15], v[126:129], v[122:125], v[0:15]
	ds_read_b128 v[114:117], v110 offset:32768
	ds_read_b128 v[118:121], v111 offset:49152
	ds_read_b128 v[122:125], v110 offset:36864
	ds_read_b128 v[126:129], v111 offset:53248
	s_waitcnt lgkmcnt(0)
	v_mfma_f32_32x32x16_bf16 v[48:63], v[118:121], v[114:117], v[48:63]
	v_mfma_f32_32x32x16_bf16 v[32:47], v[126:129], v[114:117], v[32:47]
	v_mfma_f32_32x32x16_bf16 v[16:31], v[118:121], v[122:125], v[16:31]
	v_mfma_f32_32x32x16_bf16 v[0:15], v[126:129], v[122:125], v[0:15]
	ds_read_b128 v[114:117], v112 offset:32768
	ds_read_b128 v[118:121], v113 offset:49152
	ds_read_b128 v[122:125], v112 offset:36864
	ds_read_b128 v[126:129], v113 offset:53248
	s_waitcnt vmcnt(0)
	s_waitcnt vmcnt(0) lgkmcnt(0)
	s_barrier
	v_mfma_f32_32x32x16_bf16 v[48:63], v[118:121], v[114:117], v[48:63]
	v_mfma_f32_32x32x16_bf16 v[32:47], v[126:129], v[114:117], v[32:47]
	global_load_lds_dwordx4 v64, s[98:99]
	s_mov_b32 m0, s71
	s_nop 0
	global_load_lds_dwordx4 v66, s[98:99]
	s_mov_b32 m0, s72
	v_mfma_f32_32x32x16_bf16 v[16:31], v[118:121], v[122:125], v[16:31]
	global_load_lds_dwordx4 v68, s[98:99]
	s_mov_b32 m0, s73
	s_nop 0
	global_load_lds_dwordx4 v70, s[98:99]
	s_mov_b32 m0, s84
	v_mfma_f32_32x32x16_bf16 v[0:15], v[126:129], v[122:125], v[0:15]
	global_load_lds_dwordx4 v64, s[100:101]
	s_mov_b32 m0, s85
	s_nop 0
	global_load_lds_dwordx4 v66, s[100:101]
	s_mov_b32 m0, s86
	s_nop 0
	global_load_lds_dwordx4 v68, s[100:101]
	s_mov_b32 m0, s87
	s_nop 0
	global_load_lds_dwordx4 v70, s[100:101]
	s_add_u32 s98, s98, 0x80
	s_addc_u32 s99, s99, 0
	s_add_u32 s100, s100, 0x80
	s_addc_u32 s101, s101, 0
	ds_read_b128 v[114:117], v106
	ds_read_b128 v[118:121], v107 offset:16384
	ds_read_b128 v[122:125], v106 offset:4096
	ds_read_b128 v[126:129], v107 offset:20480
	s_waitcnt lgkmcnt(0)
	v_mfma_f32_32x32x16_bf16 v[48:63], v[118:121], v[114:117], v[48:63]
	s_mov_b32 m0, s14
	v_mfma_f32_32x32x16_bf16 v[32:47], v[126:129], v[114:117], v[32:47]
	v_mfma_f32_32x32x16_bf16 v[16:31], v[118:121], v[122:125], v[16:31]
	v_mfma_f32_32x32x16_bf16 v[0:15], v[126:129], v[122:125], v[0:15]
	ds_read_b128 v[114:117], v108
	ds_read_b128 v[118:121], v109 offset:16384
	ds_read_b128 v[122:125], v108 offset:4096
	ds_read_b128 v[126:129], v109 offset:20480
	s_waitcnt lgkmcnt(0)
	v_mfma_f32_32x32x16_bf16 v[48:63], v[118:121], v[114:117], v[48:63]
	v_mfma_f32_32x32x16_bf16 v[32:47], v[126:129], v[114:117], v[32:47]
	v_mfma_f32_32x32x16_bf16 v[16:31], v[118:121], v[122:125], v[16:31]
	v_mfma_f32_32x32x16_bf16 v[0:15], v[126:129], v[122:125], v[0:15]
	ds_read_b128 v[114:117], v110
	ds_read_b128 v[118:121], v111 offset:16384
	ds_read_b128 v[122:125], v110 offset:4096
	ds_read_b128 v[126:129], v111 offset:20480
	s_waitcnt lgkmcnt(0)
	v_mfma_f32_32x32x16_bf16 v[48:63], v[118:121], v[114:117], v[48:63]
	v_mfma_f32_32x32x16_bf16 v[32:47], v[126:129], v[114:117], v[32:47]
	v_mfma_f32_32x32x16_bf16 v[16:31], v[118:121], v[122:125], v[16:31]
	v_mfma_f32_32x32x16_bf16 v[0:15], v[126:129], v[122:125], v[0:15]
	ds_read_b128 v[114:117], v112
	ds_read_b128 v[118:121], v113 offset:16384
	ds_read_b128 v[122:125], v112 offset:4096
	ds_read_b128 v[126:129], v113 offset:20480
	s_waitcnt vmcnt(0)
	s_waitcnt vmcnt(0) lgkmcnt(0)
	s_barrier
	v_mfma_f32_32x32x16_bf16 v[48:63], v[118:121], v[114:117], v[48:63]
	v_mfma_f32_32x32x16_bf16 v[32:47], v[126:129], v[114:117], v[32:47]
	global_load_lds_dwordx4 v64, s[98:99]
	s_mov_b32 m0, s15
	s_nop 0
	global_load_lds_dwordx4 v66, s[98:99]
	s_mov_b32 m0, s28
	v_mfma_f32_32x32x16_bf16 v[16:31], v[118:121], v[122:125], v[16:31]
	global_load_lds_dwordx4 v68, s[98:99]
	s_mov_b32 m0, s29
	s_nop 0
	global_load_lds_dwordx4 v70, s[98:99]
	s_mov_b32 m0, s34
	v_mfma_f32_32x32x16_bf16 v[0:15], v[126:129], v[122:125], v[0:15]
	global_load_lds_dwordx4 v64, s[100:101]
	s_mov_b32 m0, s35
	s_nop 0
	global_load_lds_dwordx4 v66, s[100:101]
	s_mov_b32 m0, s68
	s_nop 0
	global_load_lds_dwordx4 v68, s[100:101]
	s_mov_b32 m0, s69
	s_nop 0
	global_load_lds_dwordx4 v70, s[100:101]
	s_add_u32 s98, s98, 0x80
	s_addc_u32 s99, s99, 0
	s_add_u32 s100, s100, 0x80
	s_addc_u32 s101, s101, 0
	ds_read_b128 v[114:117], v106 offset:32768
	ds_read_b128 v[118:121], v107 offset:49152
	ds_read_b128 v[122:125], v106 offset:36864
	ds_read_b128 v[126:129], v107 offset:53248
	s_waitcnt lgkmcnt(0)
	v_mfma_f32_32x32x16_bf16 v[48:63], v[118:121], v[114:117], v[48:63]
	s_mov_b32 m0, s70
	v_mfma_f32_32x32x16_bf16 v[32:47], v[126:129], v[114:117], v[32:47]
	v_mfma_f32_32x32x16_bf16 v[16:31], v[118:121], v[122:125], v[16:31]
	v_mfma_f32_32x32x16_bf16 v[0:15], v[126:129], v[122:125], v[0:15]
	ds_read_b128 v[114:117], v108 offset:32768
	ds_read_b128 v[118:121], v109 offset:49152
	ds_read_b128 v[122:125], v108 offset:36864
	ds_read_b128 v[126:129], v109 offset:53248
	s_waitcnt lgkmcnt(0)
	v_mfma_f32_32x32x16_bf16 v[48:63], v[118:121], v[114:117], v[48:63]
	v_mfma_f32_32x32x16_bf16 v[32:47], v[126:129], v[114:117], v[32:47]
	v_mfma_f32_32x32x16_bf16 v[16:31], v[118:121], v[122:125], v[16:31]
	v_mfma_f32_32x32x16_bf16 v[0:15], v[126:129], v[122:125], v[0:15]
	ds_read_b128 v[114:117], v110 offset:32768
	ds_read_b128 v[118:121], v111 offset:49152
	ds_read_b128 v[122:125], v110 offset:36864
	ds_read_b128 v[126:129], v111 offset:53248
	s_waitcnt lgkmcnt(0)
	v_mfma_f32_32x32x16_bf16 v[48:63], v[118:121], v[114:117], v[48:63]
	v_mfma_f32_32x32x16_bf16 v[32:47], v[126:129], v[114:117], v[32:47]
	v_mfma_f32_32x32x16_bf16 v[16:31], v[118:121], v[122:125], v[16:31]
	v_mfma_f32_32x32x16_bf16 v[0:15], v[126:129], v[122:125], v[0:15]
	ds_read_b128 v[114:117], v112 offset:32768
	ds_read_b128 v[118:121], v113 offset:49152
	ds_read_b128 v[122:125], v112 offset:36864
	ds_read_b128 v[126:129], v113 offset:53248
	s_waitcnt vmcnt(0)
	s_waitcnt vmcnt(0) lgkmcnt(0)
	s_barrier
	v_mfma_f32_32x32x16_bf16 v[48:63], v[118:121], v[114:117], v[48:63]
	v_mfma_f32_32x32x16_bf16 v[32:47], v[126:129], v[114:117], v[32:47]
	global_load_lds_dwordx4 v64, s[98:99]
	s_mov_b32 m0, s71
	s_nop 0
	global_load_lds_dwordx4 v66, s[98:99]
	s_mov_b32 m0, s72
	v_mfma_f32_32x32x16_bf16 v[16:31], v[118:121], v[122:125], v[16:31]
	global_load_lds_dwordx4 v68, s[98:99]
	s_mov_b32 m0, s73
	s_nop 0
	global_load_lds_dwordx4 v70, s[98:99]
	s_mov_b32 m0, s84
	v_mfma_f32_32x32x16_bf16 v[0:15], v[126:129], v[122:125], v[0:15]
	global_load_lds_dwordx4 v64, s[100:101]
	s_mov_b32 m0, s85
	s_nop 0
	global_load_lds_dwordx4 v66, s[100:101]
	s_mov_b32 m0, s86
	s_nop 0
	global_load_lds_dwordx4 v68, s[100:101]
	s_mov_b32 m0, s87
	s_nop 0
	global_load_lds_dwordx4 v70, s[100:101]
	s_add_u32 s98, s98, 0x80
	s_addc_u32 s99, s99, 0
	s_add_u32 s100, s100, 0x80
	s_addc_u32 s101, s101, 0
	ds_read_b128 v[114:117], v106
	ds_read_b128 v[118:121], v107 offset:16384
	ds_read_b128 v[122:125], v106 offset:4096
	ds_read_b128 v[126:129], v107 offset:20480
	s_waitcnt lgkmcnt(0)
	v_mfma_f32_32x32x16_bf16 v[48:63], v[118:121], v[114:117], v[48:63]
	s_mov_b32 m0, s14
	s_add_i32 s14, s2, s13
	s_cmpk_lt_i32 s14, 0x400
	v_mfma_f32_32x32x16_bf16 v[32:47], v[126:129], v[114:117], v[32:47]
	v_mfma_f32_32x32x16_bf16 v[16:31], v[118:121], v[122:125], v[16:31]
	v_mfma_f32_32x32x16_bf16 v[0:15], v[126:129], v[122:125], v[0:15]
	ds_read_b128 v[114:117], v108
	ds_read_b128 v[118:121], v109 offset:16384
	ds_read_b128 v[122:125], v108 offset:4096
	ds_read_b128 v[126:129], v109 offset:20480
	s_waitcnt lgkmcnt(0)
	v_mfma_f32_32x32x16_bf16 v[48:63], v[118:121], v[114:117], v[48:63]
	v_mfma_f32_32x32x16_bf16 v[32:47], v[126:129], v[114:117], v[32:47]
	v_mfma_f32_32x32x16_bf16 v[16:31], v[118:121], v[122:125], v[16:31]
	v_mfma_f32_32x32x16_bf16 v[0:15], v[126:129], v[122:125], v[0:15]
	ds_read_b128 v[114:117], v110
	ds_read_b128 v[118:121], v111 offset:16384
	ds_read_b128 v[122:125], v110 offset:4096
	ds_read_b128 v[126:129], v111 offset:20480
	s_waitcnt lgkmcnt(0)
	v_mfma_f32_32x32x16_bf16 v[48:63], v[118:121], v[114:117], v[48:63]
	v_mfma_f32_32x32x16_bf16 v[32:47], v[126:129], v[114:117], v[32:47]
	v_mfma_f32_32x32x16_bf16 v[16:31], v[118:121], v[122:125], v[16:31]
	v_mfma_f32_32x32x16_bf16 v[0:15], v[126:129], v[122:125], v[0:15]
	ds_read_b128 v[114:117], v112
	ds_read_b128 v[118:121], v113 offset:16384
	ds_read_b128 v[122:125], v112 offset:4096
	ds_read_b128 v[126:129], v113 offset:20480
	s_waitcnt vmcnt(0)
	s_waitcnt vmcnt(0) lgkmcnt(0)
	s_barrier
	v_mfma_f32_32x32x16_bf16 v[48:63], v[118:121], v[114:117], v[48:63]
	v_mfma_f32_32x32x16_bf16 v[32:47], v[126:129], v[114:117], v[32:47]
	global_load_lds_dwordx4 v64, s[98:99]
	s_mov_b32 m0, s15
	s_nop 0
	global_load_lds_dwordx4 v66, s[98:99]
	s_mov_b32 m0, s28
	v_mfma_f32_32x32x16_bf16 v[16:31], v[118:121], v[122:125], v[16:31]
	global_load_lds_dwordx4 v68, s[98:99]
	s_mov_b32 m0, s29
	s_nop 0
	global_load_lds_dwordx4 v70, s[98:99]
	s_mov_b32 m0, s34
	v_mfma_f32_32x32x16_bf16 v[0:15], v[126:129], v[122:125], v[0:15]
	global_load_lds_dwordx4 v64, s[100:101]
	s_mov_b32 m0, s35
	s_nop 0
	global_load_lds_dwordx4 v66, s[100:101]
	s_mov_b32 m0, s68
	s_nop 0
	global_load_lds_dwordx4 v68, s[100:101]
	s_mov_b32 m0, s69
	s_nop 0
	global_load_lds_dwordx4 v70, s[100:101]
	s_add_u32 s98, s98, 0x80
	s_addc_u32 s99, s99, 0
	s_add_u32 s100, s100, 0x80
	s_addc_u32 s101, s101, 0
	ds_read_b128 v[114:117], v106 offset:32768
	ds_read_b128 v[118:121], v107 offset:49152
	ds_read_b128 v[122:125], v106 offset:36864
	ds_read_b128 v[126:129], v107 offset:53248
	s_waitcnt lgkmcnt(0)
	v_mfma_f32_32x32x16_bf16 v[16:31], v[118:121], v[122:125], v[16:31]
	s_mov_b32 m0, s70
	v_mfma_f32_32x32x16_bf16 v[0:15], v[126:129], v[122:125], v[0:15]
	v_mfma_f32_32x32x16_bf16 v[32:47], v[126:129], v[114:117], v[32:47]
	v_mfma_f32_32x32x16_bf16 v[48:63], v[118:121], v[114:117], v[48:63]
	ds_read_b128 v[114:117], v108 offset:32768
	ds_read_b128 v[118:121], v109 offset:49152
	ds_read_b128 v[122:125], v108 offset:36864
	ds_read_b128 v[126:129], v109 offset:53248
	s_waitcnt lgkmcnt(0)
	v_mfma_f32_32x32x16_bf16 v[16:31], v[118:121], v[122:125], v[16:31]
	v_mfma_f32_32x32x16_bf16 v[0:15], v[126:129], v[122:125], v[0:15]
	v_mfma_f32_32x32x16_bf16 v[32:47], v[126:129], v[114:117], v[32:47]
	v_mfma_f32_32x32x16_bf16 v[48:63], v[118:121], v[114:117], v[48:63]
	ds_read_b128 v[114:117], v110 offset:32768
	ds_read_b128 v[118:121], v111 offset:49152
	ds_read_b128 v[122:125], v110 offset:36864
	ds_read_b128 v[126:129], v111 offset:53248
	s_waitcnt lgkmcnt(0)
	v_mfma_f32_32x32x16_bf16 v[16:31], v[118:121], v[122:125], v[16:31]
	v_mfma_f32_32x32x16_bf16 v[0:15], v[126:129], v[122:125], v[0:15]
	v_mfma_f32_32x32x16_bf16 v[32:47], v[126:129], v[114:117], v[32:47]
	v_mfma_f32_32x32x16_bf16 v[48:63], v[118:121], v[114:117], v[48:63]
	ds_read_b128 v[114:117], v112 offset:32768
	ds_read_b128 v[118:121], v113 offset:49152
	ds_read_b128 v[122:125], v112 offset:36864
	ds_read_b128 v[126:129], v113 offset:53248
	s_waitcnt vmcnt(0)
	s_waitcnt vmcnt(0) lgkmcnt(0)
	s_barrier
	global_load_lds_dwordx4 v64, s[98:99]
	s_mov_b32 m0, s71
	v_mfma_f32_32x32x16_bf16 v[16:31], v[118:121], v[122:125], v[16:31]
	global_load_lds_dwordx4 v66, s[98:99]
	s_mov_b32 m0, s72
	s_nop 0
	global_load_lds_dwordx4 v68, s[98:99]
	s_mov_b32 m0, s73
	v_mfma_f32_32x32x16_bf16 v[0:15], v[126:129], v[122:125], v[0:15]
	global_load_lds_dwordx4 v70, s[98:99]
	s_mov_b32 m0, s84
	s_nop 0
	global_load_lds_dwordx4 v64, s[100:101]
	s_mov_b32 m0, s85
	v_mfma_f32_32x32x16_bf16 v[32:47], v[126:129], v[114:117], v[32:47]
	global_load_lds_dwordx4 v66, s[100:101]
	s_mov_b32 m0, s86
	s_nop 0
	global_load_lds_dwordx4 v68, s[100:101]
	s_mov_b32 m0, s87
	v_mfma_f32_32x32x16_bf16 v[48:63], v[118:121], v[114:117], v[48:63]
	global_load_lds_dwordx4 v70, s[100:101]
	ds_read_b128 v[72:75], v106
	ds_read_b128 v[76:79], v107 offset:16384
	ds_read_b128 v[80:83], v106 offset:4096
	ds_read_b128 v[84:87], v107 offset:20480
	s_waitcnt lgkmcnt(0)
	v_mfma_f32_32x32x16_bf16 v[16:31], v[76:79], v[80:83], v[16:31]
	v_mfma_f32_32x32x16_bf16 v[0:15], v[84:87], v[80:83], v[0:15]
	v_mfma_f32_32x32x16_bf16 v[32:47], v[84:87], v[72:75], v[32:47]
	v_mfma_f32_32x32x16_bf16 v[48:63], v[76:79], v[72:75], v[48:63]
	ds_read_b128 v[72:75], v108
	ds_read_b128 v[76:79], v109 offset:16384
	ds_read_b128 v[80:83], v108 offset:4096
	ds_read_b128 v[84:87], v109 offset:20480
	s_waitcnt lgkmcnt(0)
	v_mfma_f32_32x32x16_bf16 v[16:31], v[76:79], v[80:83], v[16:31]
	v_mfma_f32_32x32x16_bf16 v[0:15], v[84:87], v[80:83], v[0:15]
	v_mfma_f32_32x32x16_bf16 v[32:47], v[84:87], v[72:75], v[32:47]
	v_mfma_f32_32x32x16_bf16 v[48:63], v[76:79], v[72:75], v[48:63]
	ds_read_b128 v[72:75], v110
	ds_read_b128 v[76:79], v111 offset:16384
	ds_read_b128 v[80:83], v110 offset:4096
	ds_read_b128 v[84:87], v111 offset:20480
	s_waitcnt lgkmcnt(0)
	v_mfma_f32_32x32x16_bf16 v[16:31], v[76:79], v[80:83], v[16:31]
	v_mfma_f32_32x32x16_bf16 v[0:15], v[84:87], v[80:83], v[0:15]
	v_mfma_f32_32x32x16_bf16 v[32:47], v[84:87], v[72:75], v[32:47]
	v_mfma_f32_32x32x16_bf16 v[48:63], v[76:79], v[72:75], v[48:63]
	ds_read_b128 v[72:75], v112
	ds_read_b128 v[76:79], v113 offset:16384
	ds_read_b128 v[80:83], v112 offset:4096
	ds_read_b128 v[84:87], v113 offset:20480
	s_waitcnt vmcnt(0)
	s_waitcnt vmcnt(0) lgkmcnt(0)
	s_barrier
	v_mfma_f32_32x32x16_bf16 v[16:31], v[76:79], v[80:83], v[16:31]
	v_mfma_f32_32x32x16_bf16 v[0:15], v[84:87], v[80:83], v[0:15]
	v_mfma_f32_32x32x16_bf16 v[32:47], v[84:87], v[72:75], v[32:47]
	v_mfma_f32_32x32x16_bf16 v[48:63], v[76:79], v[72:75], v[48:63]
	ds_read_b128 v[72:75], v113 offset:53248
	ds_read_b128 v[76:79], v112 offset:36864
	ds_read_b128 v[80:83], v113 offset:49152
	ds_read_b128 v[84:87], v112 offset:32768
	ds_read_b128 v[114:117], v111 offset:53248
	ds_read_b128 v[118:121], v110 offset:36864
	ds_read_b128 v[122:125], v111 offset:49152
	ds_read_b128 v[126:129], v110 offset:32768
	ds_read_b128 v[130:133], v109 offset:53248
	ds_read_b128 v[134:137], v108 offset:36864
	ds_read_b128 v[138:141], v109 offset:49152
	ds_read_b128 v[142:145], v108 offset:32768
	ds_read_b128 v[146:149], v107 offset:53248
	ds_read_b128 v[150:153], v106 offset:36864
	ds_read_b128 v[156:159], v107 offset:49152
	ds_read_b128 v[160:163], v106 offset:32768
	s_waitcnt vmcnt(0)
	s_waitcnt lgkmcnt(0)
	s_barrier
	v_mfma_f32_32x32x16_bf16 v[16:31], v[156:159], v[150:153], v[16:31]
	v_mfma_f32_32x32x16_bf16 v[0:15], v[146:149], v[150:153], v[0:15]
	v_mfma_f32_32x32x16_bf16 v[32:47], v[146:149], v[160:163], v[32:47]
	v_mfma_f32_32x32x16_bf16 v[48:63], v[156:159], v[160:163], v[48:63]
	v_mfma_f32_32x32x16_bf16 v[16:31], v[138:141], v[134:137], v[16:31]
	v_mfma_f32_32x32x16_bf16 v[0:15], v[130:133], v[134:137], v[0:15]
	v_mfma_f32_32x32x16_bf16 v[32:47], v[130:133], v[142:145], v[32:47]
	v_mfma_f32_32x32x16_bf16 v[48:63], v[138:141], v[142:145], v[48:63]
	v_mfma_f32_32x32x16_bf16 v[16:31], v[122:125], v[118:121], v[16:31]
	v_mfma_f32_32x32x16_bf16 v[0:15], v[114:117], v[118:121], v[0:15]
	v_mfma_f32_32x32x16_bf16 v[32:47], v[114:117], v[126:129], v[32:47]
	v_mfma_f32_32x32x16_bf16 v[48:63], v[122:125], v[126:129], v[48:63]
	v_mfma_f32_32x32x16_bf16 v[16:31], v[80:83], v[76:79], v[16:31]
	v_mfma_f32_32x32x16_bf16 v[0:15], v[72:75], v[76:79], v[0:15]
	v_add_u32_e32 v76, s94, v89
	v_ashrrev_i32_e32 v77, 31, v76
	v_mfma_f32_32x32x16_bf16 v[32:47], v[72:75], v[84:87], v[32:47]
	v_or_b32_e32 v72, s96, v90
	v_lshlrev_b64 v[74:75], 12, v[76:77]
	v_ashrrev_i32_e32 v73, 31, v72
	v_lshl_add_u64 v[78:79], s[52:53], 0, v[74:75]
	v_mfma_f32_32x32x16_bf16 v[48:63], v[80:83], v[84:87], v[48:63]
	v_lshlrev_b64 v[82:83], 2, v[72:73]
	v_lshl_add_u64 v[78:79], v[78:79], 0, v[82:83]
	v_lshl_add_u64 v[80:81], s[38:39], 0, v[74:75]
	global_load_dwordx4 v[72:75], v[78:79], off
	s_waitcnt vmcnt(0)
	s_nop 6
	v_pk_fma_f32 v[50:51], v[74:75], s[92:93], v[50:51] op_sel_hi:[1,0,1]
	v_pk_fma_f32 v[48:49], v[72:73], s[92:93], v[48:49] op_sel_hi:[1,0,1]
	v_lshl_add_u64 v[72:73], v[80:81], 0, v[82:83]
	global_store_dwordx4 v[72:73], v[48:51], off
	global_load_dwordx4 v[48:51], v[78:79], off offset:32
	s_waitcnt vmcnt(0)
	v_pk_fma_f32 v[48:49], v[48:49], s[92:93], v[52:53] op_sel_hi:[1,0,1]
	v_pk_fma_f32 v[50:51], v[50:51], s[92:93], v[54:55] op_sel_hi:[1,0,1]
	global_store_dwordx4 v[72:73], v[48:51], off offset:32
	global_load_dwordx4 v[48:51], v[78:79], off offset:64
	s_waitcnt vmcnt(0)
	v_pk_fma_f32 v[48:49], v[48:49], s[92:93], v[56:57] op_sel_hi:[1,0,1]
	v_pk_fma_f32 v[50:51], v[50:51], s[92:93], v[58:59] op_sel_hi:[1,0,1]
	global_store_dwordx4 v[72:73], v[48:51], off offset:64
	global_load_dwordx4 v[48:51], v[78:79], off offset:96
	s_waitcnt vmcnt(0)
	v_pk_fma_f32 v[48:49], v[48:49], s[92:93], v[60:61] op_sel_hi:[1,0,1]
	v_pk_fma_f32 v[50:51], v[50:51], s[92:93], v[62:63] op_sel_hi:[1,0,1]
	global_store_dwordx4 v[72:73], v[48:51], off offset:96
	global_load_dwordx4 v[48:51], v[78:79], off offset:128
	s_waitcnt vmcnt(0)
	v_pk_fma_f32 v[34:35], v[50:51], s[92:93], v[34:35] op_sel_hi:[1,0,1]
	v_pk_fma_f32 v[32:33], v[48:49], s[92:93], v[32:33] op_sel_hi:[1,0,1]
	global_store_dwordx4 v[72:73], v[32:35], off offset:128
	global_load_dwordx4 v[32:35], v[78:79], off offset:160
	s_waitcnt vmcnt(0)
	v_pk_fma_f32 v[32:33], v[32:33], s[92:93], v[36:37] op_sel_hi:[1,0,1]
	v_pk_fma_f32 v[34:35], v[34:35], s[92:93], v[38:39] op_sel_hi:[1,0,1]
	global_store_dwordx4 v[72:73], v[32:35], off offset:160
	global_load_dwordx4 v[32:35], v[78:79], off offset:192
	s_waitcnt vmcnt(0)
	v_pk_fma_f32 v[32:33], v[32:33], s[92:93], v[40:41] op_sel_hi:[1,0,1]
	v_pk_fma_f32 v[34:35], v[34:35], s[92:93], v[42:43] op_sel_hi:[1,0,1]
	global_store_dwordx4 v[72:73], v[32:35], off offset:192
	global_load_dwordx4 v[32:35], v[78:79], off offset:224
	s_waitcnt vmcnt(0)
	v_pk_fma_f32 v[32:33], v[32:33], s[92:93], v[44:45] op_sel_hi:[1,0,1]
	v_pk_fma_f32 v[34:35], v[34:35], s[92:93], v[46:47] op_sel_hi:[1,0,1]
	global_store_dwordx4 v[72:73], v[32:35], off offset:224
	s_nop 1
	v_or_b32_e32 v32, 32, v76
	v_ashrrev_i32_e32 v33, 31, v32
	v_lshlrev_b64 v[32:33], 12, v[32:33]
	v_lshl_add_u64 v[34:35], s[52:53], 0, v[32:33]
	v_lshl_add_u64 v[38:39], v[34:35], 0, v[82:83]
	v_lshl_add_u64 v[36:37], s[38:39], 0, v[32:33]
	global_load_dwordx4 v[32:35], v[38:39], off
	s_waitcnt vmcnt(0)
	v_pk_fma_f32 v[18:19], v[34:35], s[92:93], v[18:19] op_sel_hi:[1,0,1]
	v_pk_fma_f32 v[16:17], v[32:33], s[92:93], v[16:17] op_sel_hi:[1,0,1]
	v_lshl_add_u64 v[32:33], v[36:37], 0, v[82:83]
	global_store_dwordx4 v[32:33], v[16:19], off
	global_load_dwordx4 v[16:19], v[38:39], off offset:32
	s_waitcnt vmcnt(0)
	v_pk_fma_f32 v[16:17], v[16:17], s[92:93], v[20:21] op_sel_hi:[1,0,1]
	v_pk_fma_f32 v[18:19], v[18:19], s[92:93], v[22:23] op_sel_hi:[1,0,1]
	global_store_dwordx4 v[32:33], v[16:19], off offset:32
	global_load_dwordx4 v[16:19], v[38:39], off offset:64
	s_waitcnt vmcnt(0)
	v_pk_fma_f32 v[16:17], v[16:17], s[92:93], v[24:25] op_sel_hi:[1,0,1]
	v_pk_fma_f32 v[18:19], v[18:19], s[92:93], v[26:27] op_sel_hi:[1,0,1]
	global_store_dwordx4 v[32:33], v[16:19], off offset:64
	global_load_dwordx4 v[16:19], v[38:39], off offset:96
	s_waitcnt vmcnt(0)
	v_pk_fma_f32 v[16:17], v[16:17], s[92:93], v[28:29] op_sel_hi:[1,0,1]
	v_pk_fma_f32 v[18:19], v[18:19], s[92:93], v[30:31] op_sel_hi:[1,0,1]
	global_store_dwordx4 v[32:33], v[16:19], off offset:96
	global_load_dwordx4 v[16:19], v[38:39], off offset:128
	s_waitcnt vmcnt(0)
	v_pk_fma_f32 v[2:3], v[18:19], s[92:93], v[2:3] op_sel_hi:[1,0,1]
	v_pk_fma_f32 v[0:1], v[16:17], s[92:93], v[0:1] op_sel_hi:[1,0,1]
	global_store_dwordx4 v[32:33], v[0:3], off offset:128
	global_load_dwordx4 v[0:3], v[38:39], off offset:160
	s_waitcnt vmcnt(0)
	v_pk_fma_f32 v[0:1], v[0:1], s[92:93], v[4:5] op_sel_hi:[1,0,1]
	v_pk_fma_f32 v[2:3], v[2:3], s[92:93], v[6:7] op_sel_hi:[1,0,1]
	global_store_dwordx4 v[32:33], v[0:3], off offset:160
	global_load_dwordx4 v[0:3], v[38:39], off offset:192
	s_waitcnt vmcnt(0)
	v_pk_fma_f32 v[0:1], v[0:1], s[92:93], v[8:9] op_sel_hi:[1,0,1]
	v_pk_fma_f32 v[2:3], v[2:3], s[92:93], v[10:11] op_sel_hi:[1,0,1]
	global_store_dwordx4 v[32:33], v[0:3], off offset:192
	global_load_dwordx4 v[0:3], v[38:39], off offset:224
	s_waitcnt vmcnt(0)
	v_pk_fma_f32 v[0:1], v[0:1], s[92:93], v[12:13] op_sel_hi:[1,0,1]
	v_pk_fma_f32 v[2:3], v[2:3], s[92:93], v[14:15] op_sel_hi:[1,0,1]
	global_store_dwordx4 v[32:33], v[0:3], off offset:224
	s_cmpk_lt_i32 s14, 0x400
	s_cbranch_scc0 .LBB0_255

.LBB0_343:
	s_lshl_b32 s0, s0, 7
	s_ashr_i32 s1, s0, 31
	v_readlane_b32 s52, v245, 37
	s_lshl_b32 s14, s93, 7
	s_lshl_b64 s[28:29], s[0:1], 11
	v_readlane_b32 s64, v245, 49
	v_readlane_b32 s65, v245, 50
	s_add_u32 s28, s64, s28
	s_addc_u32 s29, s65, s29
	s_ashr_i32 s15, s14, 31
	v_readlane_b32 s58, v245, 43
	s_lshl_b64 s[14:15], s[14:15], 11
	v_readlane_b32 s59, v245, 44
	s_add_u32 s14, s58, s14
	s_addc_u32 s15, s59, s15
	v_readfirstlane_b32 s73, v100
	v_mov_b32_e32 v2, s15
	v_mov_b32_e32 v3, s29
	v_mov_b32_e32 v4, s14
	v_mov_b32_e32 v5, s28
	s_add_u32 s98, s28, 0x80
	s_addc_u32 s99, s29, 0
	v_lshl_add_u64 v[84:85], s[28:29], 0, v[64:65]
	s_mov_b32 m0, s73
	v_cndmask_b32_e64 v1, v2, v3, s[4:5]
	v_cndmask_b32_e64 v0, v4, v5, s[4:5]
	v_readfirstlane_b32 s84, v167
	global_load_lds_dwordx4 v[84:85], off
	v_lshl_add_u64 v[86:87], v[0:1], 0, v[66:67]
	s_mov_b32 m0, s84
	v_cndmask_b32_e64 v1, v2, v3, s[6:7]
	v_cndmask_b32_e64 v0, v4, v5, s[6:7]
	v_readfirstlane_b32 s85, v168
	global_load_lds_dwordx4 v[86:87], off
	v_lshl_add_u64 v[88:89], v[0:1], 0, v[68:69]
	s_mov_b32 m0, s85
	v_cndmask_b32_e64 v1, v2, v3, s[8:9]
	v_cndmask_b32_e64 v0, v4, v5, s[8:9]
	v_readfirstlane_b32 s86, v169
	global_load_lds_dwordx4 v[88:89], off
	v_lshl_add_u64 v[90:91], v[0:1], 0, v[70:71]
	s_mov_b32 m0, s86
	v_readfirstlane_b32 s87, v170
	global_load_lds_dwordx4 v[90:91], off
	s_add_u32 s100, s14, 0x80
	s_addc_u32 s101, s15, 0
	v_lshl_add_u64 v[92:93], s[14:15], 0, v[64:65]
	s_mov_b32 m0, s87
	v_readfirstlane_b32 s3, v171
	global_load_lds_dwordx4 v[92:93], off
	v_lshl_add_u64 v[96:97], s[14:15], 0, v[66:67]
	s_mov_b32 m0, s3
	v_readfirstlane_b32 s34, v172
	global_load_lds_dwordx4 v[96:97], off
	v_lshl_add_u64 v[98:99], s[14:15], 0, v[68:69]
	s_mov_b32 m0, s34
	v_readfirstlane_b32 s35, v173
	global_load_lds_dwordx4 v[98:99], off
	v_lshl_add_u64 v[94:95], s[14:15], 0, v[70:71]
	s_mov_b32 m0, s35
	v_readfirstlane_b32 s1, v174
	global_load_lds_dwordx4 v[94:95], off
	s_mov_b32 m0, s1
	v_readfirstlane_b32 s15, v175
	s_waitcnt vmcnt(0)
	s_waitcnt vmcnt(0) lgkmcnt(0)
	s_barrier
	global_load_lds_dwordx4 v64, s[98:99]
	s_mov_b32 m0, s15
	v_readfirstlane_b32 s14, v176
	global_load_lds_dwordx4 v66, s[98:99]
	s_mov_b32 m0, s14
	v_readfirstlane_b32 s70, v177
	global_load_lds_dwordx4 v68, s[98:99]
	s_mov_b32 m0, s70
	v_readfirstlane_b32 s29, v178
	global_load_lds_dwordx4 v70, s[98:99]
	s_mov_b32 m0, s29
	v_readfirstlane_b32 s71, v179
	global_load_lds_dwordx4 v64, s[100:101]
	s_mov_b32 m0, s71
	v_readfirstlane_b32 s72, v180
	global_load_lds_dwordx4 v66, s[100:101]
	ds_read_b128 v[0:3], v183 offset:16384
	s_mov_b32 m0, s72
	v_readfirstlane_b32 s28, v181
	global_load_lds_dwordx4 v68, s[100:101]
	s_mov_b32 m0, s28
	ds_read_b128 v[4:7], v182
	ds_read_b128 v[8:11], v183 offset:20480
	ds_read_b128 v[200:203], v185
	global_load_lds_dwordx4 v70, s[100:101]
	s_add_u32 s98, s98, 0x80
	s_addc_u32 s99, s99, 0
	s_add_u32 s100, s100, 0x80
	s_addc_u32 s101, s101, 0
	ds_read_b128 v[12:15], v184
	ds_read_b128 v[204:207], v187
	s_waitcnt lgkmcnt(0)
	v_mfma_f32_32x32x16_bf16 v[48:63], v[0:3], v[4:7], 0
	ds_read_b128 v[208:211], v186 offset:16384
	ds_read_b128 v[212:215], v186 offset:20480
	s_mov_b32 m0, s73
	v_cmp_lt_i32_e32 vcc, v197, v198
	s_add_i32 s95, s95, s33
	v_readlane_b32 s53, v245, 38
	v_readlane_b32 s54, v245, 39
	v_readlane_b32 s55, v245, 40
	v_mfma_f32_32x32x16_bf16 v[16:31], v[0:3], v[12:15], 0
	v_readlane_b32 s56, v245, 41
	v_readlane_b32 s57, v245, 42
	v_readlane_b32 s60, v245, 45
	v_readlane_b32 s61, v245, 46
	v_readlane_b32 s62, v245, 47
	v_readlane_b32 s63, v245, 48
	v_readlane_b32 s66, v245, 51
	v_mfma_f32_32x32x16_bf16 v[32:47], v[8:11], v[4:7], 0
	v_readlane_b32 s67, v245, 52
	v_mfma_f32_32x32x16_bf16 v[0:15], v[8:11], v[12:15], 0
	s_waitcnt lgkmcnt(0)
	v_mfma_f32_32x32x16_bf16 v[48:63], v[208:211], v[200:203], v[48:63]
	v_mfma_f32_32x32x16_bf16 v[16:31], v[208:211], v[204:207], v[16:31]
	v_mfma_f32_32x32x16_bf16 v[32:47], v[212:215], v[200:203], v[32:47]
	v_mfma_f32_32x32x16_bf16 v[0:15], v[212:215], v[204:207], v[0:15]
	ds_read_b128 v[200:203], v189 offset:16384
	ds_read_b128 v[204:207], v188
	ds_read_b128 v[208:211], v189 offset:20480
	ds_read_b128 v[212:215], v191
	ds_read_b128 v[216:219], v190
	ds_read_b128 v[220:223], v193
	s_waitcnt lgkmcnt(0)
	v_mfma_f32_32x32x16_bf16 v[48:63], v[200:203], v[204:207], v[48:63]
	v_mfma_f32_32x32x16_bf16 v[16:31], v[200:203], v[216:219], v[16:31]
	v_mfma_f32_32x32x16_bf16 v[32:47], v[208:211], v[204:207], v[32:47]
	ds_read_b128 v[200:203], v192 offset:16384
	ds_read_b128 v[204:207], v192 offset:20480
	s_waitcnt vmcnt(0)
	s_waitcnt vmcnt(0) lgkmcnt(0)
	s_barrier
	v_mfma_f32_32x32x16_bf16 v[48:63], v[200:203], v[212:215], v[48:63]
	v_mfma_f32_32x32x16_bf16 v[16:31], v[200:203], v[220:223], v[16:31]
	global_load_lds_dwordx4 v64, s[98:99]
	s_mov_b32 m0, s84
	s_nop 0
	global_load_lds_dwordx4 v66, s[98:99]
	v_mfma_f32_32x32x16_bf16 v[0:15], v[208:211], v[216:219], v[0:15]
	s_mov_b32 m0, s85
	s_nop 0
	global_load_lds_dwordx4 v68, s[98:99]
	s_mov_b32 m0, s86
	v_mfma_f32_32x32x16_bf16 v[32:47], v[204:207], v[212:215], v[32:47]
	global_load_lds_dwordx4 v70, s[98:99]
	s_mov_b32 m0, s87
	s_nop 0
	global_load_lds_dwordx4 v64, s[100:101]
	s_mov_b32 m0, s3
	v_mfma_f32_32x32x16_bf16 v[0:15], v[204:207], v[220:223], v[0:15]
	global_load_lds_dwordx4 v66, s[100:101]
	s_mov_b32 m0, s34
	s_nop 0
	global_load_lds_dwordx4 v68, s[100:101]
	ds_read_b128 v[200:203], v183 offset:49152
	s_mov_b32 m0, s35
	s_nop 0
	global_load_lds_dwordx4 v70, s[100:101]
	s_add_u32 s98, s98, 0x80
	s_addc_u32 s99, s99, 0
	s_add_u32 s100, s100, 0x80
	s_addc_u32 s101, s101, 0
	ds_read_b128 v[204:207], v182 offset:32768
	ds_read_b128 v[208:211], v184 offset:32768
	ds_read_b128 v[212:215], v183 offset:53248
	s_waitcnt lgkmcnt(0)
	v_mfma_f32_32x32x16_bf16 v[48:63], v[200:203], v[204:207], v[48:63]
	s_mov_b32 m0, s1
	v_mfma_f32_32x32x16_bf16 v[16:31], v[200:203], v[208:211], v[16:31]
	v_mfma_f32_32x32x16_bf16 v[32:47], v[212:215], v[204:207], v[32:47]
	v_mfma_f32_32x32x16_bf16 v[0:15], v[212:215], v[208:211], v[0:15]
	ds_read_b128 v[200:203], v186 offset:49152
	ds_read_b128 v[204:207], v185 offset:32768
	ds_read_b128 v[208:211], v187 offset:32768
	ds_read_b128 v[212:215], v186 offset:53248
	s_waitcnt lgkmcnt(0)
	v_mfma_f32_32x32x16_bf16 v[48:63], v[200:203], v[204:207], v[48:63]
	v_mfma_f32_32x32x16_bf16 v[16:31], v[200:203], v[208:211], v[16:31]
	v_mfma_f32_32x32x16_bf16 v[32:47], v[212:215], v[204:207], v[32:47]
	v_mfma_f32_32x32x16_bf16 v[0:15], v[212:215], v[208:211], v[0:15]
	ds_read_b128 v[200:203], v189 offset:49152
	ds_read_b128 v[204:207], v188 offset:32768
	ds_read_b128 v[208:211], v190 offset:32768
	ds_read_b128 v[212:215], v189 offset:53248
	s_waitcnt lgkmcnt(0)
	v_mfma_f32_32x32x16_bf16 v[48:63], v[200:203], v[204:207], v[48:63]
	v_mfma_f32_32x32x16_bf16 v[16:31], v[200:203], v[208:211], v[16:31]
	ds_read_b128 v[200:203], v192 offset:49152
	v_mfma_f32_32x32x16_bf16 v[32:47], v[212:215], v[204:207], v[32:47]
	v_mfma_f32_32x32x16_bf16 v[0:15], v[212:215], v[208:211], v[0:15]
	ds_read_b128 v[204:207], v191 offset:32768
	ds_read_b128 v[208:211], v193 offset:32768
	ds_read_b128 v[212:215], v192 offset:53248
	s_waitcnt vmcnt(0)
	s_waitcnt vmcnt(0) lgkmcnt(0)
	s_barrier
	global_load_lds_dwordx4 v64, s[98:99]
	s_mov_b32 m0, s15
	v_mfma_f32_32x32x16_bf16 v[48:63], v[200:203], v[204:207], v[48:63]
	global_load_lds_dwordx4 v66, s[98:99]
	s_mov_b32 m0, s14
	s_nop 0
	global_load_lds_dwordx4 v68, s[98:99]
	v_mfma_f32_32x32x16_bf16 v[16:31], v[200:203], v[208:211], v[16:31]
	s_mov_b32 m0, s70
	s_nop 0
	global_load_lds_dwordx4 v70, s[98:99]
	s_mov_b32 m0, s29
	v_mfma_f32_32x32x16_bf16 v[32:47], v[212:215], v[204:207], v[32:47]
	global_load_lds_dwordx4 v64, s[100:101]
	s_mov_b32 m0, s71
	s_nop 0
	global_load_lds_dwordx4 v66, s[100:101]
	ds_read_b128 v[200:203], v183 offset:16384
	s_mov_b32 m0, s72
	v_mfma_f32_32x32x16_bf16 v[0:15], v[212:215], v[208:211], v[0:15]
	global_load_lds_dwordx4 v68, s[100:101]
	s_mov_b32 m0, s28
	ds_read_b128 v[204:207], v182
	ds_read_b128 v[208:211], v183 offset:20480
	ds_read_b128 v[212:215], v185
	global_load_lds_dwordx4 v70, s[100:101]
	s_add_u32 s98, s98, 0x80
	s_addc_u32 s99, s99, 0
	s_add_u32 s100, s100, 0x80
	s_addc_u32 s101, s101, 0
	ds_read_b128 v[216:219], v184
	ds_read_b128 v[220:223], v187
	s_waitcnt lgkmcnt(0)
	v_mfma_f32_32x32x16_bf16 v[48:63], v[200:203], v[204:207], v[48:63]
	s_mov_b32 m0, s73
	v_mfma_f32_32x32x16_bf16 v[16:31], v[200:203], v[216:219], v[16:31]
	v_mfma_f32_32x32x16_bf16 v[32:47], v[208:211], v[204:207], v[32:47]
	ds_read_b128 v[200:203], v186 offset:16384
	ds_read_b128 v[204:207], v186 offset:20480
	v_mfma_f32_32x32x16_bf16 v[0:15], v[208:211], v[216:219], v[0:15]
	s_waitcnt lgkmcnt(0)
	v_mfma_f32_32x32x16_bf16 v[48:63], v[200:203], v[212:215], v[48:63]
	v_mfma_f32_32x32x16_bf16 v[16:31], v[200:203], v[220:223], v[16:31]
	v_mfma_f32_32x32x16_bf16 v[32:47], v[204:207], v[212:215], v[32:47]
	v_mfma_f32_32x32x16_bf16 v[0:15], v[204:207], v[220:223], v[0:15]
	ds_read_b128 v[200:203], v189 offset:16384
	ds_read_b128 v[204:207], v188
	ds_read_b128 v[208:211], v189 offset:20480
	ds_read_b128 v[212:215], v191
	ds_read_b128 v[216:219], v190
	ds_read_b128 v[220:223], v193
	s_waitcnt lgkmcnt(0)
	v_mfma_f32_32x32x16_bf16 v[48:63], v[200:203], v[204:207], v[48:63]
	v_mfma_f32_32x32x16_bf16 v[16:31], v[200:203], v[216:219], v[16:31]
	v_mfma_f32_32x32x16_bf16 v[32:47], v[208:211], v[204:207], v[32:47]
	ds_read_b128 v[200:203], v192 offset:16384
	ds_read_b128 v[204:207], v192 offset:20480
	s_waitcnt vmcnt(0)
	s_waitcnt vmcnt(0) lgkmcnt(0)
	s_barrier
	v_mfma_f32_32x32x16_bf16 v[0:15], v[208:211], v[216:219], v[0:15]
	global_load_lds_dwordx4 v64, s[98:99]
	s_mov_b32 m0, s84
	s_nop 0
	global_load_lds_dwordx4 v66, s[98:99]
	s_mov_b32 m0, s85
	v_mfma_f32_32x32x16_bf16 v[48:63], v[200:203], v[212:215], v[48:63]
	global_load_lds_dwordx4 v68, s[98:99]
	s_mov_b32 m0, s86
	s_nop 0
	global_load_lds_dwordx4 v70, s[98:99]
	v_mfma_f32_32x32x16_bf16 v[16:31], v[200:203], v[220:223], v[16:31]
	s_mov_b32 m0, s87
	s_nop 0
	global_load_lds_dwordx4 v64, s[100:101]
	s_mov_b32 m0, s3
	v_mfma_f32_32x32x16_bf16 v[32:47], v[204:207], v[212:215], v[32:47]
	global_load_lds_dwordx4 v66, s[100:101]
	s_mov_b32 m0, s34
	s_nop 0
	global_load_lds_dwordx4 v68, s[100:101]
	ds_read_b128 v[200:203], v183 offset:49152
	s_mov_b32 m0, s35
	v_mfma_f32_32x32x16_bf16 v[0:15], v[204:207], v[220:223], v[0:15]
	global_load_lds_dwordx4 v70, s[100:101]
	s_add_u32 s98, s98, 0x80
	s_addc_u32 s99, s99, 0
	s_add_u32 s100, s100, 0x80
	s_addc_u32 s101, s101, 0
	ds_read_b128 v[204:207], v182 offset:32768
	ds_read_b128 v[208:211], v184 offset:32768
	ds_read_b128 v[212:215], v183 offset:53248
	s_mov_b32 m0, s1
	s_waitcnt lgkmcnt(0)
	v_mfma_f32_32x32x16_bf16 v[48:63], v[200:203], v[204:207], v[48:63]
	v_mfma_f32_32x32x16_bf16 v[16:31], v[200:203], v[208:211], v[16:31]
	v_mfma_f32_32x32x16_bf16 v[32:47], v[212:215], v[204:207], v[32:47]
	v_mfma_f32_32x32x16_bf16 v[0:15], v[212:215], v[208:211], v[0:15]
	ds_read_b128 v[200:203], v186 offset:49152
	ds_read_b128 v[204:207], v185 offset:32768
	ds_read_b128 v[208:211], v187 offset:32768
	ds_read_b128 v[212:215], v186 offset:53248
	s_waitcnt lgkmcnt(0)
	v_mfma_f32_32x32x16_bf16 v[48:63], v[200:203], v[204:207], v[48:63]
	v_mfma_f32_32x32x16_bf16 v[16:31], v[200:203], v[208:211], v[16:31]
	v_mfma_f32_32x32x16_bf16 v[32:47], v[212:215], v[204:207], v[32:47]
	v_mfma_f32_32x32x16_bf16 v[0:15], v[212:215], v[208:211], v[0:15]
	ds_read_b128 v[200:203], v189 offset:49152
	ds_read_b128 v[204:207], v188 offset:32768
	ds_read_b128 v[208:211], v190 offset:32768
	ds_read_b128 v[212:215], v189 offset:53248
	s_waitcnt lgkmcnt(0)
	v_mfma_f32_32x32x16_bf16 v[48:63], v[200:203], v[204:207], v[48:63]
	v_mfma_f32_32x32x16_bf16 v[16:31], v[200:203], v[208:211], v[16:31]
	ds_read_b128 v[200:203], v192 offset:49152
	v_mfma_f32_32x32x16_bf16 v[32:47], v[212:215], v[204:207], v[32:47]
	v_mfma_f32_32x32x16_bf16 v[0:15], v[212:215], v[208:211], v[0:15]
	ds_read_b128 v[204:207], v191 offset:32768
	ds_read_b128 v[208:211], v193 offset:32768
	ds_read_b128 v[212:215], v192 offset:53248
	s_waitcnt vmcnt(0)
	s_waitcnt vmcnt(0) lgkmcnt(0)
	s_barrier
	global_load_lds_dwordx4 v64, s[98:99]
	s_mov_b32 m0, s15
	v_mfma_f32_32x32x16_bf16 v[48:63], v[200:203], v[204:207], v[48:63]
	global_load_lds_dwordx4 v66, s[98:99]
	s_mov_b32 m0, s14
	s_nop 0
	global_load_lds_dwordx4 v68, s[98:99]
	v_mfma_f32_32x32x16_bf16 v[16:31], v[200:203], v[208:211], v[16:31]
	s_mov_b32 m0, s70
	s_nop 0
	global_load_lds_dwordx4 v70, s[98:99]
	s_mov_b32 m0, s29
	v_mfma_f32_32x32x16_bf16 v[32:47], v[212:215], v[204:207], v[32:47]
	global_load_lds_dwordx4 v64, s[100:101]
	s_mov_b32 m0, s71
	s_nop 0
	global_load_lds_dwordx4 v66, s[100:101]
	ds_read_b128 v[200:203], v183 offset:16384
	s_mov_b32 m0, s72
	v_mfma_f32_32x32x16_bf16 v[0:15], v[212:215], v[208:211], v[0:15]
	global_load_lds_dwordx4 v68, s[100:101]
	s_mov_b32 m0, s28
	ds_read_b128 v[204:207], v182
	ds_read_b128 v[208:211], v183 offset:20480
	ds_read_b128 v[212:215], v185
	global_load_lds_dwordx4 v70, s[100:101]
	s_add_u32 s98, s98, 0x80
	s_addc_u32 s99, s99, 0
	s_add_u32 s100, s100, 0x80
	s_addc_u32 s101, s101, 0
	ds_read_b128 v[216:219], v184
	ds_read_b128 v[220:223], v187
	s_waitcnt lgkmcnt(0)
	v_mfma_f32_32x32x16_bf16 v[48:63], v[200:203], v[204:207], v[48:63]
	s_mov_b32 m0, s73
	v_mfma_f32_32x32x16_bf16 v[16:31], v[200:203], v[216:219], v[16:31]
	v_mfma_f32_32x32x16_bf16 v[32:47], v[208:211], v[204:207], v[32:47]
	ds_read_b128 v[200:203], v186 offset:16384
	ds_read_b128 v[204:207], v186 offset:20480
	v_mfma_f32_32x32x16_bf16 v[0:15], v[208:211], v[216:219], v[0:15]
	s_waitcnt lgkmcnt(0)
	v_mfma_f32_32x32x16_bf16 v[48:63], v[200:203], v[212:215], v[48:63]
	v_mfma_f32_32x32x16_bf16 v[16:31], v[200:203], v[220:223], v[16:31]
	v_mfma_f32_32x32x16_bf16 v[32:47], v[204:207], v[212:215], v[32:47]
	v_mfma_f32_32x32x16_bf16 v[0:15], v[204:207], v[220:223], v[0:15]
	ds_read_b128 v[200:203], v189 offset:16384
	ds_read_b128 v[204:207], v188
	ds_read_b128 v[208:211], v189 offset:20480
	ds_read_b128 v[212:215], v191
	ds_read_b128 v[216:219], v190
	ds_read_b128 v[220:223], v193
	s_waitcnt lgkmcnt(0)
	v_mfma_f32_32x32x16_bf16 v[48:63], v[200:203], v[204:207], v[48:63]
	v_mfma_f32_32x32x16_bf16 v[16:31], v[200:203], v[216:219], v[16:31]
	v_mfma_f32_32x32x16_bf16 v[32:47], v[208:211], v[204:207], v[32:47]
	ds_read_b128 v[200:203], v192 offset:16384
	ds_read_b128 v[204:207], v192 offset:20480
	s_waitcnt vmcnt(0)
	s_waitcnt vmcnt(0) lgkmcnt(0)
	s_barrier
	v_mfma_f32_32x32x16_bf16 v[0:15], v[208:211], v[216:219], v[0:15]
	global_load_lds_dwordx4 v64, s[98:99]
	s_mov_b32 m0, s84
	s_nop 0
	global_load_lds_dwordx4 v66, s[98:99]
	s_mov_b32 m0, s85
	v_mfma_f32_32x32x16_bf16 v[48:63], v[200:203], v[212:215], v[48:63]
	global_load_lds_dwordx4 v68, s[98:99]
	s_mov_b32 m0, s86
	s_nop 0
	global_load_lds_dwordx4 v70, s[98:99]
	v_mfma_f32_32x32x16_bf16 v[16:31], v[200:203], v[220:223], v[16:31]
	s_mov_b32 m0, s87
	s_nop 0
	global_load_lds_dwordx4 v64, s[100:101]
	s_mov_b32 m0, s3
	v_mfma_f32_32x32x16_bf16 v[32:47], v[204:207], v[212:215], v[32:47]
	global_load_lds_dwordx4 v66, s[100:101]
	s_mov_b32 m0, s34
	s_nop 0
	global_load_lds_dwordx4 v68, s[100:101]
	ds_read_b128 v[200:203], v183 offset:49152
	s_mov_b32 m0, s35
	v_mfma_f32_32x32x16_bf16 v[0:15], v[204:207], v[220:223], v[0:15]
	global_load_lds_dwordx4 v70, s[100:101]
	s_add_u32 s98, s98, 0x80
	s_addc_u32 s99, s99, 0
	s_add_u32 s100, s100, 0x80
	s_addc_u32 s101, s101, 0
	ds_read_b128 v[204:207], v182 offset:32768
	ds_read_b128 v[208:211], v184 offset:32768
	ds_read_b128 v[212:215], v183 offset:53248
	s_mov_b32 m0, s1
	s_waitcnt lgkmcnt(0)
	v_mfma_f32_32x32x16_bf16 v[48:63], v[200:203], v[204:207], v[48:63]
	v_mfma_f32_32x32x16_bf16 v[16:31], v[200:203], v[208:211], v[16:31]
	v_mfma_f32_32x32x16_bf16 v[32:47], v[212:215], v[204:207], v[32:47]
	v_mfma_f32_32x32x16_bf16 v[0:15], v[212:215], v[208:211], v[0:15]
	ds_read_b128 v[200:203], v186 offset:49152
	ds_read_b128 v[204:207], v185 offset:32768
	ds_read_b128 v[208:211], v187 offset:32768
	ds_read_b128 v[212:215], v186 offset:53248
	s_waitcnt lgkmcnt(0)
	v_mfma_f32_32x32x16_bf16 v[48:63], v[200:203], v[204:207], v[48:63]
	v_mfma_f32_32x32x16_bf16 v[16:31], v[200:203], v[208:211], v[16:31]
	v_mfma_f32_32x32x16_bf16 v[32:47], v[212:215], v[204:207], v[32:47]
	v_mfma_f32_32x32x16_bf16 v[0:15], v[212:215], v[208:211], v[0:15]
	ds_read_b128 v[200:203], v189 offset:49152
	ds_read_b128 v[204:207], v188 offset:32768
	ds_read_b128 v[208:211], v190 offset:32768
	ds_read_b128 v[212:215], v189 offset:53248
	s_waitcnt lgkmcnt(0)
	v_mfma_f32_32x32x16_bf16 v[48:63], v[200:203], v[204:207], v[48:63]
	v_mfma_f32_32x32x16_bf16 v[16:31], v[200:203], v[208:211], v[16:31]
	ds_read_b128 v[200:203], v192 offset:49152
	v_mfma_f32_32x32x16_bf16 v[32:47], v[212:215], v[204:207], v[32:47]
	v_mfma_f32_32x32x16_bf16 v[0:15], v[212:215], v[208:211], v[0:15]
	ds_read_b128 v[204:207], v191 offset:32768
	ds_read_b128 v[208:211], v193 offset:32768
	ds_read_b128 v[212:215], v192 offset:53248
	s_waitcnt vmcnt(0)
	s_waitcnt vmcnt(0) lgkmcnt(0)
	s_barrier
	global_load_lds_dwordx4 v64, s[98:99]
	s_mov_b32 m0, s15
	v_mfma_f32_32x32x16_bf16 v[48:63], v[200:203], v[204:207], v[48:63]
	global_load_lds_dwordx4 v66, s[98:99]
	s_mov_b32 m0, s14
	s_nop 0
	global_load_lds_dwordx4 v68, s[98:99]
	v_mfma_f32_32x32x16_bf16 v[16:31], v[200:203], v[208:211], v[16:31]
	s_mov_b32 m0, s70
	s_nop 0
	global_load_lds_dwordx4 v70, s[98:99]
	s_mov_b32 m0, s29
	v_mfma_f32_32x32x16_bf16 v[32:47], v[212:215], v[204:207], v[32:47]
	global_load_lds_dwordx4 v64, s[100:101]
	s_mov_b32 m0, s71
	s_nop 0
	global_load_lds_dwordx4 v66, s[100:101]
	ds_read_b128 v[200:203], v183 offset:16384
	s_mov_b32 m0, s72
	v_mfma_f32_32x32x16_bf16 v[0:15], v[212:215], v[208:211], v[0:15]
	global_load_lds_dwordx4 v68, s[100:101]
	s_mov_b32 m0, s28
	ds_read_b128 v[204:207], v182
	ds_read_b128 v[208:211], v183 offset:20480
	ds_read_b128 v[212:215], v185
	global_load_lds_dwordx4 v70, s[100:101]
	s_add_u32 s98, s98, 0x80
	s_addc_u32 s99, s99, 0
	s_add_u32 s100, s100, 0x80
	s_addc_u32 s101, s101, 0
	ds_read_b128 v[216:219], v184
	ds_read_b128 v[220:223], v187
	s_waitcnt lgkmcnt(0)
	v_mfma_f32_32x32x16_bf16 v[48:63], v[200:203], v[204:207], v[48:63]
	s_mov_b32 m0, s73
	v_readfirstlane_b32 s73, v177
	v_mfma_f32_32x32x16_bf16 v[16:31], v[200:203], v[216:219], v[16:31]
	v_mfma_f32_32x32x16_bf16 v[32:47], v[208:211], v[204:207], v[32:47]
	ds_read_b128 v[200:203], v186 offset:16384
	ds_read_b128 v[204:207], v186 offset:20480
	v_mfma_f32_32x32x16_bf16 v[0:15], v[208:211], v[216:219], v[0:15]
	s_waitcnt lgkmcnt(0)
	v_mfma_f32_32x32x16_bf16 v[48:63], v[200:203], v[212:215], v[48:63]
	v_mfma_f32_32x32x16_bf16 v[16:31], v[200:203], v[220:223], v[16:31]
	v_mfma_f32_32x32x16_bf16 v[32:47], v[204:207], v[212:215], v[32:47]
	v_mfma_f32_32x32x16_bf16 v[0:15], v[204:207], v[220:223], v[0:15]
	ds_read_b128 v[200:203], v189 offset:16384
	ds_read_b128 v[204:207], v188
	ds_read_b128 v[208:211], v189 offset:20480
	ds_read_b128 v[212:215], v191
	ds_read_b128 v[216:219], v190
	ds_read_b128 v[220:223], v193
	s_waitcnt lgkmcnt(0)
	v_mfma_f32_32x32x16_bf16 v[48:63], v[200:203], v[204:207], v[48:63]
	v_mfma_f32_32x32x16_bf16 v[16:31], v[200:203], v[216:219], v[16:31]
	v_mfma_f32_32x32x16_bf16 v[32:47], v[208:211], v[204:207], v[32:47]
	ds_read_b128 v[200:203], v192 offset:16384
	ds_read_b128 v[204:207], v192 offset:20480
	s_waitcnt vmcnt(0)
	s_waitcnt vmcnt(0) lgkmcnt(0)
	s_barrier
	v_mfma_f32_32x32x16_bf16 v[0:15], v[208:211], v[216:219], v[0:15]
	global_load_lds_dwordx4 v64, s[98:99]
	s_mov_b32 m0, s84
	s_nop 0
	global_load_lds_dwordx4 v66, s[98:99]
	s_mov_b32 m0, s85
	v_mfma_f32_32x32x16_bf16 v[48:63], v[200:203], v[212:215], v[48:63]
	global_load_lds_dwordx4 v68, s[98:99]
	s_mov_b32 m0, s86
	v_readfirstlane_b32 s84, v178
	global_load_lds_dwordx4 v70, s[98:99]
	v_mfma_f32_32x32x16_bf16 v[16:31], v[200:203], v[220:223], v[16:31]
	s_mov_b32 m0, s87
	s_nop 0
	global_load_lds_dwordx4 v64, s[100:101]
	s_mov_b32 m0, s3
	v_mfma_f32_32x32x16_bf16 v[32:47], v[204:207], v[212:215], v[32:47]
	global_load_lds_dwordx4 v66, s[100:101]
	s_mov_b32 m0, s34
	v_readfirstlane_b32 s3, v100
	global_load_lds_dwordx4 v68, s[100:101]
	ds_read_b128 v[200:203], v183 offset:49152
	s_mov_b32 m0, s35
	v_mfma_f32_32x32x16_bf16 v[0:15], v[204:207], v[220:223], v[0:15]
	global_load_lds_dwordx4 v70, s[100:101]
	s_add_u32 s98, s98, 0x80
	s_addc_u32 s99, s99, 0
	s_add_u32 s100, s100, 0x80
	s_addc_u32 s101, s101, 0
	ds_read_b128 v[204:207], v182 offset:32768
	ds_read_b128 v[208:211], v184 offset:32768
	ds_read_b128 v[212:215], v183 offset:53248
	s_mov_b32 m0, s1
	v_readfirstlane_b32 s1, v167
	v_readfirstlane_b32 s34, v171
	v_readfirstlane_b32 s35, v172
	s_waitcnt lgkmcnt(0)
	v_mfma_f32_32x32x16_bf16 v[48:63], v[200:203], v[204:207], v[48:63]
	v_readfirstlane_b32 s85, v179
	v_readfirstlane_b32 s86, v180
	v_readfirstlane_b32 s87, v181
	v_mfma_f32_32x32x16_bf16 v[16:31], v[200:203], v[208:211], v[16:31]
	v_mfma_f32_32x32x16_bf16 v[32:47], v[212:215], v[204:207], v[32:47]
	v_mfma_f32_32x32x16_bf16 v[0:15], v[212:215], v[208:211], v[0:15]
	ds_read_b128 v[200:203], v186 offset:49152
	ds_read_b128 v[204:207], v185 offset:32768
	ds_read_b128 v[208:211], v187 offset:32768
	ds_read_b128 v[212:215], v186 offset:53248
	s_waitcnt lgkmcnt(0)
	v_mfma_f32_32x32x16_bf16 v[48:63], v[200:203], v[204:207], v[48:63]
	v_mfma_f32_32x32x16_bf16 v[16:31], v[200:203], v[208:211], v[16:31]
	v_mfma_f32_32x32x16_bf16 v[32:47], v[212:215], v[204:207], v[32:47]
	v_mfma_f32_32x32x16_bf16 v[0:15], v[212:215], v[208:211], v[0:15]
	ds_read_b128 v[200:203], v189 offset:49152
	ds_read_b128 v[204:207], v188 offset:32768
	ds_read_b128 v[208:211], v190 offset:32768
	ds_read_b128 v[212:215], v189 offset:53248
	s_waitcnt lgkmcnt(0)
	v_mfma_f32_32x32x16_bf16 v[48:63], v[200:203], v[204:207], v[48:63]
	v_mfma_f32_32x32x16_bf16 v[16:31], v[200:203], v[208:211], v[16:31]
	ds_read_b128 v[200:203], v192 offset:49152
	v_mfma_f32_32x32x16_bf16 v[32:47], v[212:215], v[204:207], v[32:47]
	v_mfma_f32_32x32x16_bf16 v[0:15], v[212:215], v[208:211], v[0:15]
	ds_read_b128 v[204:207], v191 offset:32768
	ds_read_b128 v[208:211], v193 offset:32768
	ds_read_b128 v[212:215], v192 offset:53248
	s_waitcnt vmcnt(0)
	s_waitcnt vmcnt(0) lgkmcnt(0)
	s_barrier
	global_load_lds_dwordx4 v64, s[98:99]
	s_mov_b32 m0, s15
	v_mfma_f32_32x32x16_bf16 v[48:63], v[200:203], v[204:207], v[48:63]
	global_load_lds_dwordx4 v66, s[98:99]
	s_mov_b32 m0, s14
	v_readfirstlane_b32 s14, v168
	global_load_lds_dwordx4 v68, s[98:99]
	v_mfma_f32_32x32x16_bf16 v[16:31], v[200:203], v[208:211], v[16:31]
	s_mov_b32 m0, s70
	s_nop 0
	global_load_lds_dwordx4 v70, s[98:99]
	s_mov_b32 m0, s29
	v_mfma_f32_32x32x16_bf16 v[32:47], v[212:215], v[204:207], v[32:47]
	global_load_lds_dwordx4 v64, s[100:101]
	s_mov_b32 m0, s71
	s_nop 0
	global_load_lds_dwordx4 v66, s[100:101]
	ds_read_b128 v[200:203], v183 offset:16384
	s_mov_b32 m0, s72
	v_mfma_f32_32x32x16_bf16 v[0:15], v[212:215], v[208:211], v[0:15]
	global_load_lds_dwordx4 v68, s[100:101]
	s_mov_b32 m0, s28
	ds_read_b128 v[204:207], v182
	ds_read_b128 v[208:211], v183 offset:20480
	ds_read_b128 v[212:215], v185
	global_load_lds_dwordx4 v70, s[100:101]
	s_add_u32 s98, s98, 0x80
	s_addc_u32 s99, s99, 0
	s_add_u32 s100, s100, 0x80
	s_addc_u32 s101, s101, 0
	ds_read_b128 v[216:219], v184
	ds_read_b128 v[220:223], v187
	s_waitcnt lgkmcnt(0)
	v_mfma_f32_32x32x16_bf16 v[48:63], v[200:203], v[204:207], v[48:63]
	s_mov_b32 m0, s3
	v_readfirstlane_b32 s15, v169
	v_readfirstlane_b32 s28, v170
	v_readfirstlane_b32 s29, v173
	v_readfirstlane_b32 s70, v174
	v_readfirstlane_b32 s71, v175
	v_readfirstlane_b32 s72, v176
	v_mfma_f32_32x32x16_bf16 v[16:31], v[200:203], v[216:219], v[16:31]
	v_mfma_f32_32x32x16_bf16 v[32:47], v[208:211], v[204:207], v[32:47]
	ds_read_b128 v[200:203], v186 offset:16384
	ds_read_b128 v[204:207], v186 offset:20480
	v_mfma_f32_32x32x16_bf16 v[0:15], v[208:211], v[216:219], v[0:15]
	s_waitcnt lgkmcnt(0)
	v_mfma_f32_32x32x16_bf16 v[48:63], v[200:203], v[212:215], v[48:63]
	v_mfma_f32_32x32x16_bf16 v[16:31], v[200:203], v[220:223], v[16:31]
	v_mfma_f32_32x32x16_bf16 v[32:47], v[204:207], v[212:215], v[32:47]
	v_mfma_f32_32x32x16_bf16 v[0:15], v[204:207], v[220:223], v[0:15]
	ds_read_b128 v[200:203], v189 offset:16384
	ds_read_b128 v[204:207], v188
	ds_read_b128 v[208:211], v189 offset:20480
	ds_read_b128 v[212:215], v191
	ds_read_b128 v[216:219], v190
	ds_read_b128 v[220:223], v193
	s_waitcnt lgkmcnt(0)
	v_mfma_f32_32x32x16_bf16 v[48:63], v[200:203], v[204:207], v[48:63]
	v_mfma_f32_32x32x16_bf16 v[16:31], v[200:203], v[216:219], v[16:31]
	ds_read_b128 v[200:203], v192 offset:16384
	ds_read_b128 v[224:227], v192 offset:20480
	s_waitcnt vmcnt(0)
	s_waitcnt vmcnt(0) lgkmcnt(0)
	s_barrier
	v_mfma_f32_32x32x16_bf16 v[32:47], v[208:211], v[204:207], v[32:47]
	global_load_lds_dwordx4 v64, s[98:99]
	s_mov_b32 m0, s1
	s_nop 0
	global_load_lds_dwordx4 v66, s[98:99]
	s_mov_b32 m0, s14
	v_mfma_f32_32x32x16_bf16 v[0:15], v[208:211], v[216:219], v[0:15]
	global_load_lds_dwordx4 v68, s[98:99]
	s_mov_b32 m0, s15
	s_nop 0
	global_load_lds_dwordx4 v70, s[98:99]
	s_mov_b32 m0, s28
	v_mfma_f32_32x32x16_bf16 v[48:63], v[200:203], v[212:215], v[48:63]
	global_load_lds_dwordx4 v64, s[100:101]
	s_mov_b32 m0, s34
	v_mfma_f32_32x32x16_bf16 v[16:31], v[200:203], v[220:223], v[16:31]
	global_load_lds_dwordx4 v66, s[100:101]
	s_mov_b32 m0, s35
	s_nop 0
	global_load_lds_dwordx4 v68, s[100:101]
	ds_read_b128 v[200:203], v183 offset:49152
	v_mfma_f32_32x32x16_bf16 v[32:47], v[224:227], v[212:215], v[32:47]
	s_mov_b32 m0, s29
	s_nop 0
	global_load_lds_dwordx4 v70, s[100:101]
	s_add_u32 s98, s98, 0x80
	s_addc_u32 s99, s99, 0
	s_add_u32 s100, s100, 0x80
	s_addc_u32 s101, s101, 0
	ds_read_b128 v[204:207], v182 offset:32768
	ds_read_b128 v[208:211], v184 offset:32768
	ds_read_b128 v[212:215], v183 offset:53248
	s_mov_b32 m0, s70
	v_mfma_f32_32x32x16_bf16 v[0:15], v[224:227], v[220:223], v[0:15]
	s_waitcnt lgkmcnt(0)
	v_mfma_f32_32x32x16_bf16 v[48:63], v[200:203], v[204:207], v[48:63]
	v_mfma_f32_32x32x16_bf16 v[16:31], v[200:203], v[208:211], v[16:31]
	v_mfma_f32_32x32x16_bf16 v[32:47], v[212:215], v[204:207], v[32:47]
	v_mfma_f32_32x32x16_bf16 v[0:15], v[212:215], v[208:211], v[0:15]
	ds_read_b128 v[200:203], v186 offset:49152
	ds_read_b128 v[204:207], v185 offset:32768
	ds_read_b128 v[208:211], v187 offset:32768
	ds_read_b128 v[212:215], v186 offset:53248
	s_waitcnt lgkmcnt(0)
	v_mfma_f32_32x32x16_bf16 v[48:63], v[200:203], v[204:207], v[48:63]
	v_mfma_f32_32x32x16_bf16 v[16:31], v[200:203], v[208:211], v[16:31]
	v_mfma_f32_32x32x16_bf16 v[32:47], v[212:215], v[204:207], v[32:47]
	v_mfma_f32_32x32x16_bf16 v[0:15], v[212:215], v[208:211], v[0:15]
	ds_read_b128 v[200:203], v189 offset:49152
	ds_read_b128 v[204:207], v188 offset:32768
	ds_read_b128 v[208:211], v190 offset:32768
	ds_read_b128 v[212:215], v189 offset:53248
	s_waitcnt lgkmcnt(0)
	v_mfma_f32_32x32x16_bf16 v[48:63], v[200:203], v[204:207], v[48:63]
	v_mfma_f32_32x32x16_bf16 v[16:31], v[200:203], v[208:211], v[16:31]
	ds_read_b128 v[200:203], v191 offset:32768
	ds_read_b128 v[216:219], v193 offset:32768
	v_mfma_f32_32x32x16_bf16 v[32:47], v[212:215], v[204:207], v[32:47]
	ds_read_b128 v[204:207], v192 offset:49152
	ds_read_b128 v[220:223], v192 offset:53248
	s_waitcnt vmcnt(0)
	s_waitcnt vmcnt(0) lgkmcnt(0)
	s_barrier
	global_load_lds_dwordx4 v64, s[98:99]
	v_mfma_f32_32x32x16_bf16 v[0:15], v[212:215], v[208:211], v[0:15]
	s_mov_b32 m0, s71
	s_nop 0
	global_load_lds_dwordx4 v66, s[98:99]
	s_mov_b32 m0, s72
	v_mfma_f32_32x32x16_bf16 v[48:63], v[204:207], v[200:203], v[48:63]
	global_load_lds_dwordx4 v68, s[98:99]
	s_mov_b32 m0, s73
	s_nop 0
	global_load_lds_dwordx4 v70, s[98:99]
	v_mfma_f32_32x32x16_bf16 v[16:31], v[204:207], v[216:219], v[16:31]
	s_mov_b32 m0, s84
	s_nop 0
	global_load_lds_dwordx4 v64, s[100:101]
	s_mov_b32 m0, s85
	v_mfma_f32_32x32x16_bf16 v[32:47], v[220:223], v[200:203], v[32:47]
	global_load_lds_dwordx4 v66, s[100:101]
	ds_read_b128 v[200:203], v183 offset:16384
	s_mov_b32 m0, s86
	s_nop 0
	global_load_lds_dwordx4 v68, s[100:101]
	v_mfma_f32_32x32x16_bf16 v[0:15], v[220:223], v[216:219], v[0:15]
	s_mov_b32 m0, s87
	ds_read_b128 v[204:207], v182
	ds_read_b128 v[208:211], v183 offset:20480
	ds_read_b128 v[212:215], v185
	global_load_lds_dwordx4 v70, s[100:101]
	s_add_u32 s98, s98, 0x80
	s_addc_u32 s99, s99, 0
	s_add_u32 s100, s100, 0x80
	s_addc_u32 s101, s101, 0
	ds_read_b128 v[216:219], v184
	ds_read_b128 v[220:223], v187
	s_waitcnt lgkmcnt(0)
	v_mfma_f32_32x32x16_bf16 v[48:63], v[200:203], v[204:207], v[48:63]
	s_mov_b32 m0, s3
	v_mfma_f32_32x32x16_bf16 v[16:31], v[200:203], v[216:219], v[16:31]
	v_mfma_f32_32x32x16_bf16 v[32:47], v[208:211], v[204:207], v[32:47]
	ds_read_b128 v[200:203], v186 offset:16384
	ds_read_b128 v[204:207], v186 offset:20480
	v_mfma_f32_32x32x16_bf16 v[0:15], v[208:211], v[216:219], v[0:15]
	s_waitcnt lgkmcnt(0)
	v_mfma_f32_32x32x16_bf16 v[48:63], v[200:203], v[212:215], v[48:63]
	v_mfma_f32_32x32x16_bf16 v[16:31], v[200:203], v[220:223], v[16:31]
	v_mfma_f32_32x32x16_bf16 v[32:47], v[204:207], v[212:215], v[32:47]
	v_mfma_f32_32x32x16_bf16 v[0:15], v[204:207], v[220:223], v[0:15]
	ds_read_b128 v[200:203], v189 offset:16384
	ds_read_b128 v[204:207], v188
	ds_read_b128 v[208:211], v189 offset:20480
	ds_read_b128 v[212:215], v191
	ds_read_b128 v[216:219], v190
	ds_read_b128 v[220:223], v193
	s_waitcnt lgkmcnt(0)
	v_mfma_f32_32x32x16_bf16 v[48:63], v[200:203], v[204:207], v[48:63]
	v_mfma_f32_32x32x16_bf16 v[16:31], v[200:203], v[216:219], v[16:31]
	v_mfma_f32_32x32x16_bf16 v[32:47], v[208:211], v[204:207], v[32:47]
	ds_read_b128 v[200:203], v192 offset:16384
	ds_read_b128 v[204:207], v192 offset:20480
	s_waitcnt vmcnt(0)
	s_waitcnt vmcnt(0) lgkmcnt(0)
	s_barrier
	v_mfma_f32_32x32x16_bf16 v[0:15], v[208:211], v[216:219], v[0:15]
	global_load_lds_dwordx4 v64, s[98:99]
	s_mov_b32 m0, s1
	s_nop 0
	global_load_lds_dwordx4 v66, s[98:99]
	s_mov_b32 m0, s14
	v_mfma_f32_32x32x16_bf16 v[48:63], v[200:203], v[212:215], v[48:63]
	global_load_lds_dwordx4 v68, s[98:99]
	s_mov_b32 m0, s15
	s_nop 0
	global_load_lds_dwordx4 v70, s[98:99]
	v_mfma_f32_32x32x16_bf16 v[16:31], v[200:203], v[220:223], v[16:31]
	s_mov_b32 m0, s28
	s_nop 0
	global_load_lds_dwordx4 v64, s[100:101]
	s_mov_b32 m0, s34
	v_mfma_f32_32x32x16_bf16 v[32:47], v[204:207], v[212:215], v[32:47]
	global_load_lds_dwordx4 v66, s[100:101]
	s_mov_b32 m0, s35
	s_nop 0
	global_load_lds_dwordx4 v68, s[100:101]
	ds_read_b128 v[200:203], v183 offset:49152
	s_mov_b32 m0, s29
	v_mfma_f32_32x32x16_bf16 v[0:15], v[204:207], v[220:223], v[0:15]
	global_load_lds_dwordx4 v70, s[100:101]
	s_add_u32 s98, s98, 0x80
	s_addc_u32 s99, s99, 0
	s_add_u32 s100, s100, 0x80
	s_addc_u32 s101, s101, 0
	ds_read_b128 v[204:207], v182 offset:32768
	ds_read_b128 v[208:211], v184 offset:32768
	ds_read_b128 v[212:215], v183 offset:53248
	s_mov_b32 m0, s70
	s_waitcnt lgkmcnt(0)
	v_mfma_f32_32x32x16_bf16 v[48:63], v[200:203], v[204:207], v[48:63]
	v_mfma_f32_32x32x16_bf16 v[16:31], v[200:203], v[208:211], v[16:31]
	v_mfma_f32_32x32x16_bf16 v[32:47], v[212:215], v[204:207], v[32:47]
	v_mfma_f32_32x32x16_bf16 v[0:15], v[212:215], v[208:211], v[0:15]
	ds_read_b128 v[200:203], v186 offset:49152
	ds_read_b128 v[204:207], v185 offset:32768
	ds_read_b128 v[208:211], v187 offset:32768
	ds_read_b128 v[212:215], v186 offset:53248
	s_waitcnt lgkmcnt(0)
	v_mfma_f32_32x32x16_bf16 v[48:63], v[200:203], v[204:207], v[48:63]
	v_mfma_f32_32x32x16_bf16 v[16:31], v[200:203], v[208:211], v[16:31]
	v_mfma_f32_32x32x16_bf16 v[32:47], v[212:215], v[204:207], v[32:47]
	v_mfma_f32_32x32x16_bf16 v[0:15], v[212:215], v[208:211], v[0:15]
	ds_read_b128 v[200:203], v189 offset:49152
	ds_read_b128 v[204:207], v188 offset:32768
	ds_read_b128 v[208:211], v190 offset:32768
	ds_read_b128 v[212:215], v189 offset:53248
	s_waitcnt lgkmcnt(0)
	v_mfma_f32_32x32x16_bf16 v[48:63], v[200:203], v[204:207], v[48:63]
	v_mfma_f32_32x32x16_bf16 v[16:31], v[200:203], v[208:211], v[16:31]
	ds_read_b128 v[200:203], v192 offset:49152
	v_mfma_f32_32x32x16_bf16 v[32:47], v[212:215], v[204:207], v[32:47]
	v_mfma_f32_32x32x16_bf16 v[0:15], v[212:215], v[208:211], v[0:15]
	ds_read_b128 v[204:207], v191 offset:32768
	ds_read_b128 v[208:211], v193 offset:32768
	ds_read_b128 v[212:215], v192 offset:53248
	s_waitcnt vmcnt(0)
	s_waitcnt vmcnt(0) lgkmcnt(0)
	s_barrier
	global_load_lds_dwordx4 v64, s[98:99]
	s_mov_b32 m0, s71
	v_mfma_f32_32x32x16_bf16 v[48:63], v[200:203], v[204:207], v[48:63]
	global_load_lds_dwordx4 v66, s[98:99]
	s_mov_b32 m0, s72
	s_nop 0
	global_load_lds_dwordx4 v68, s[98:99]
	v_mfma_f32_32x32x16_bf16 v[16:31], v[200:203], v[208:211], v[16:31]
	s_mov_b32 m0, s73
	s_nop 0
	global_load_lds_dwordx4 v70, s[98:99]
	s_mov_b32 m0, s84
	v_mfma_f32_32x32x16_bf16 v[32:47], v[212:215], v[204:207], v[32:47]
	global_load_lds_dwordx4 v64, s[100:101]
	s_mov_b32 m0, s85
	s_nop 0
	global_load_lds_dwordx4 v66, s[100:101]
	ds_read_b128 v[200:203], v183 offset:16384
	s_mov_b32 m0, s86
	v_mfma_f32_32x32x16_bf16 v[0:15], v[212:215], v[208:211], v[0:15]
	global_load_lds_dwordx4 v68, s[100:101]
	s_mov_b32 m0, s87
	ds_read_b128 v[204:207], v182
	ds_read_b128 v[208:211], v183 offset:20480
	ds_read_b128 v[212:215], v185
	global_load_lds_dwordx4 v70, s[100:101]
	s_add_u32 s98, s98, 0x80
	s_addc_u32 s99, s99, 0
	s_add_u32 s100, s100, 0x80
	s_addc_u32 s101, s101, 0
	ds_read_b128 v[216:219], v184
	ds_read_b128 v[220:223], v187
	s_waitcnt lgkmcnt(0)
	v_mfma_f32_32x32x16_bf16 v[48:63], v[200:203], v[204:207], v[48:63]
	s_mov_b32 m0, s3
	v_mfma_f32_32x32x16_bf16 v[16:31], v[200:203], v[216:219], v[16:31]
	v_mfma_f32_32x32x16_bf16 v[32:47], v[208:211], v[204:207], v[32:47]
	ds_read_b128 v[200:203], v186 offset:16384
	ds_read_b128 v[204:207], v186 offset:20480
	v_mfma_f32_32x32x16_bf16 v[0:15], v[208:211], v[216:219], v[0:15]
	s_waitcnt lgkmcnt(0)
	v_mfma_f32_32x32x16_bf16 v[48:63], v[200:203], v[212:215], v[48:63]
	v_mfma_f32_32x32x16_bf16 v[16:31], v[200:203], v[220:223], v[16:31]
	v_mfma_f32_32x32x16_bf16 v[32:47], v[204:207], v[212:215], v[32:47]
	v_mfma_f32_32x32x16_bf16 v[0:15], v[204:207], v[220:223], v[0:15]
	ds_read_b128 v[200:203], v189 offset:16384
	ds_read_b128 v[204:207], v188
	ds_read_b128 v[208:211], v189 offset:20480
	ds_read_b128 v[212:215], v191
	ds_read_b128 v[216:219], v190
	ds_read_b128 v[220:223], v193
	s_waitcnt lgkmcnt(0)
	v_mfma_f32_32x32x16_bf16 v[48:63], v[200:203], v[204:207], v[48:63]
	v_mfma_f32_32x32x16_bf16 v[16:31], v[200:203], v[216:219], v[16:31]
	v_mfma_f32_32x32x16_bf16 v[32:47], v[208:211], v[204:207], v[32:47]
	ds_read_b128 v[200:203], v192 offset:16384
	ds_read_b128 v[204:207], v192 offset:20480
	s_waitcnt vmcnt(0)
	s_waitcnt vmcnt(0) lgkmcnt(0)
	s_barrier
	v_mfma_f32_32x32x16_bf16 v[0:15], v[208:211], v[216:219], v[0:15]
	global_load_lds_dwordx4 v64, s[98:99]
	s_mov_b32 m0, s1
	s_nop 0
	global_load_lds_dwordx4 v66, s[98:99]
	s_mov_b32 m0, s14
	v_mfma_f32_32x32x16_bf16 v[48:63], v[200:203], v[212:215], v[48:63]
	global_load_lds_dwordx4 v68, s[98:99]
	s_mov_b32 m0, s15
	s_lshl_b32 s14, s93, 1
	global_load_lds_dwordx4 v70, s[98:99]
	v_mfma_f32_32x32x16_bf16 v[16:31], v[200:203], v[220:223], v[16:31]
	s_mov_b32 m0, s28
	s_nop 0
	global_load_lds_dwordx4 v64, s[100:101]
	s_mov_b32 m0, s34
	v_mfma_f32_32x32x16_bf16 v[32:47], v[204:207], v[212:215], v[32:47]
	global_load_lds_dwordx4 v66, s[100:101]
	s_mov_b32 m0, s35
	s_ashr_i32 s15, s14, 31
	global_load_lds_dwordx4 v68, s[100:101]
	ds_read_b128 v[200:203], v183 offset:49152
	s_mov_b32 m0, s29
	v_mfma_f32_32x32x16_bf16 v[0:15], v[204:207], v[220:223], v[0:15]
	global_load_lds_dwordx4 v70, s[100:101]
	s_add_u32 s98, s98, 0x80
	s_addc_u32 s99, s99, 0
	s_add_u32 s100, s100, 0x80
	s_addc_u32 s101, s101, 0
	ds_read_b128 v[204:207], v182 offset:32768
	ds_read_b128 v[208:211], v184 offset:32768
	ds_read_b128 v[212:215], v183 offset:53248
	s_mov_b32 m0, s70
	s_lshl_b64 s[28:29], s[14:15], 14
	s_waitcnt lgkmcnt(0)
	v_mfma_f32_32x32x16_bf16 v[48:63], v[200:203], v[204:207], v[48:63]
	v_mfma_f32_32x32x16_bf16 v[16:31], v[200:203], v[208:211], v[16:31]
	v_mfma_f32_32x32x16_bf16 v[32:47], v[212:215], v[204:207], v[32:47]
	v_mfma_f32_32x32x16_bf16 v[0:15], v[212:215], v[208:211], v[0:15]
	ds_read_b128 v[200:203], v186 offset:49152
	ds_read_b128 v[204:207], v185 offset:32768
	ds_read_b128 v[208:211], v187 offset:32768
	ds_read_b128 v[212:215], v186 offset:53248
	s_waitcnt lgkmcnt(0)
	v_mfma_f32_32x32x16_bf16 v[48:63], v[200:203], v[204:207], v[48:63]
	v_mfma_f32_32x32x16_bf16 v[16:31], v[200:203], v[208:211], v[16:31]
	v_mfma_f32_32x32x16_bf16 v[32:47], v[212:215], v[204:207], v[32:47]
	v_mfma_f32_32x32x16_bf16 v[0:15], v[212:215], v[208:211], v[0:15]
	ds_read_b128 v[200:203], v189 offset:49152
	ds_read_b128 v[204:207], v188 offset:32768
	ds_read_b128 v[208:211], v190 offset:32768
	ds_read_b128 v[212:215], v189 offset:53248
	s_waitcnt lgkmcnt(0)
	v_mfma_f32_32x32x16_bf16 v[48:63], v[200:203], v[204:207], v[48:63]
	v_mfma_f32_32x32x16_bf16 v[16:31], v[200:203], v[208:211], v[16:31]
	ds_read_b128 v[200:203], v192 offset:49152
	v_mfma_f32_32x32x16_bf16 v[32:47], v[212:215], v[204:207], v[32:47]
	v_mfma_f32_32x32x16_bf16 v[0:15], v[212:215], v[208:211], v[0:15]
	ds_read_b128 v[204:207], v191 offset:32768
	ds_read_b128 v[208:211], v193 offset:32768
	ds_read_b128 v[212:215], v192 offset:53248
	s_waitcnt vmcnt(0)
	s_waitcnt vmcnt(0) lgkmcnt(0)
	s_barrier
	global_load_lds_dwordx4 v64, s[98:99]
	s_mov_b32 m0, s71
	v_mfma_f32_32x32x16_bf16 v[48:63], v[200:203], v[204:207], v[48:63]
	global_load_lds_dwordx4 v66, s[98:99]
	s_mov_b32 m0, s72
	s_nop 0
	global_load_lds_dwordx4 v68, s[98:99]
	s_mov_b32 m0, s73
	v_mfma_f32_32x32x16_bf16 v[16:31], v[200:203], v[208:211], v[16:31]
	global_load_lds_dwordx4 v70, s[98:99]
	s_mov_b32 m0, s84
	s_nop 0
	global_load_lds_dwordx4 v64, s[100:101]
	s_mov_b32 m0, s85
	v_mfma_f32_32x32x16_bf16 v[32:47], v[212:215], v[204:207], v[32:47]
	global_load_lds_dwordx4 v66, s[100:101]
	ds_read_b128 v[84:87], v183 offset:16384
	s_mov_b32 m0, s86
	s_nop 0
	global_load_lds_dwordx4 v68, s[100:101]
	s_mov_b32 m0, s87
	v_mfma_f32_32x32x16_bf16 v[0:15], v[212:215], v[208:211], v[0:15]
	ds_read_b128 v[88:91], v182
	ds_read_b128 v[92:95], v183 offset:20480
	ds_read_b128 v[96:99], v185
	global_load_lds_dwordx4 v70, s[100:101]
	ds_read_b128 v[200:203], v184
	ds_read_b128 v[204:207], v187
	s_waitcnt lgkmcnt(0)
	v_mfma_f32_32x32x16_bf16 v[48:63], v[84:87], v[88:91], v[48:63]
	v_mfma_f32_32x32x16_bf16 v[16:31], v[84:87], v[200:203], v[16:31]
	v_mfma_f32_32x32x16_bf16 v[32:47], v[92:95], v[88:91], v[32:47]
	ds_read_b128 v[84:87], v186 offset:16384
	ds_read_b128 v[88:91], v186 offset:20480
	v_mfma_f32_32x32x16_bf16 v[0:15], v[92:95], v[200:203], v[0:15]
	s_waitcnt lgkmcnt(0)
	v_mfma_f32_32x32x16_bf16 v[48:63], v[84:87], v[96:99], v[48:63]
	v_mfma_f32_32x32x16_bf16 v[16:31], v[84:87], v[204:207], v[16:31]
	v_mfma_f32_32x32x16_bf16 v[32:47], v[88:91], v[96:99], v[32:47]
	v_mfma_f32_32x32x16_bf16 v[0:15], v[88:91], v[204:207], v[0:15]
	ds_read_b128 v[84:87], v189 offset:16384
	ds_read_b128 v[88:91], v188
	ds_read_b128 v[92:95], v189 offset:20480
	ds_read_b128 v[96:99], v191
	ds_read_b128 v[200:203], v190
	ds_read_b128 v[204:207], v193
	s_waitcnt lgkmcnt(0)
	v_mfma_f32_32x32x16_bf16 v[48:63], v[84:87], v[88:91], v[48:63]
	v_mfma_f32_32x32x16_bf16 v[16:31], v[84:87], v[200:203], v[16:31]
	v_mfma_f32_32x32x16_bf16 v[32:47], v[92:95], v[88:91], v[32:47]
	ds_read_b128 v[84:87], v192 offset:16384
	ds_read_b128 v[88:91], v192 offset:20480
	s_waitcnt vmcnt(0)
	s_waitcnt vmcnt(0) lgkmcnt(0)
	s_barrier
	v_mfma_f32_32x32x16_bf16 v[0:15], v[92:95], v[200:203], v[0:15]
	v_mfma_f32_32x32x16_bf16 v[48:63], v[84:87], v[96:99], v[48:63]
	v_mfma_f32_32x32x16_bf16 v[16:31], v[84:87], v[204:207], v[16:31]
	v_mfma_f32_32x32x16_bf16 v[32:47], v[88:91], v[96:99], v[32:47]
	v_mfma_f32_32x32x16_bf16 v[0:15], v[88:91], v[204:207], v[0:15]
	ds_read_b128 v[84:87], v183 offset:49152
	ds_read_b128 v[88:91], v182 offset:32768
	ds_read_b128 v[92:95], v184 offset:32768
	s_waitcnt lgkmcnt(1)
	v_mfma_f32_32x32x16_bf16 v[48:63], v[84:87], v[88:91], v[48:63]
	s_waitcnt lgkmcnt(0)
	v_mfma_f32_32x32x16_bf16 v[16:31], v[84:87], v[92:95], v[16:31]
	ds_read_b128 v[84:87], v183 offset:53248
	s_waitcnt lgkmcnt(0)
	v_mfma_f32_32x32x16_bf16 v[32:47], v[84:87], v[88:91], v[32:47]
	v_mfma_f32_32x32x16_bf16 v[0:15], v[84:87], v[92:95], v[0:15]
	ds_read_b128 v[84:87], v186 offset:49152
	ds_read_b128 v[88:91], v185 offset:32768
	ds_read_b128 v[92:95], v187 offset:32768
	s_waitcnt lgkmcnt(1)
	v_mfma_f32_32x32x16_bf16 v[48:63], v[84:87], v[88:91], v[48:63]
	s_waitcnt lgkmcnt(0)
	v_mfma_f32_32x32x16_bf16 v[16:31], v[84:87], v[92:95], v[16:31]
	ds_read_b128 v[84:87], v186 offset:53248
	s_waitcnt lgkmcnt(0)
	v_mfma_f32_32x32x16_bf16 v[32:47], v[84:87], v[88:91], v[32:47]
	v_mfma_f32_32x32x16_bf16 v[0:15], v[84:87], v[92:95], v[0:15]
	ds_read_b128 v[84:87], v189 offset:49152
	ds_read_b128 v[88:91], v188 offset:32768
	ds_read_b128 v[92:95], v190 offset:32768
	s_waitcnt lgkmcnt(1)
	v_mfma_f32_32x32x16_bf16 v[48:63], v[84:87], v[88:91], v[48:63]
	s_waitcnt lgkmcnt(0)
	v_mfma_f32_32x32x16_bf16 v[16:31], v[84:87], v[92:95], v[16:31]
	ds_read_b128 v[84:87], v192 offset:49152
	ds_read_b128 v[96:99], v191 offset:32768
	ds_read_b128 v[200:203], v189 offset:53248
	ds_read_b128 v[204:207], v192 offset:53248
	ds_read_b128 v[208:211], v193 offset:32768
	s_waitcnt vmcnt(0)
	s_waitcnt lgkmcnt(0)
	s_barrier
	v_mfma_f32_32x32x16_bf16 v[32:47], v[200:203], v[88:91], v[32:47]
	v_mfma_f32_32x32x16_bf16 v[0:15], v[200:203], v[92:95], v[0:15]
	v_mfma_f32_32x32x16_bf16 v[32:47], v[204:207], v[96:99], v[32:47]
	v_mfma_f32_32x32x16_bf16 v[48:63], v[84:87], v[96:99], v[48:63]
	s_nop 10
	v_cvt_pk_bf16_f32 v32, v32, v33
	v_cvt_pk_bf16_f32 v33, v34, v35
	v_cvt_pk_bf16_f32 v34, v36, v37
	v_cvt_pk_bf16_f32 v35, v38, v39
	ds_write2_b64 v194, v[32:33], v[34:35] offset0:8 offset1:10
	v_cvt_pk_bf16_f32 v32, v40, v41
	v_cvt_pk_bf16_f32 v33, v42, v43
	v_mfma_f32_32x32x16_bf16 v[16:31], v[84:87], v[208:211], v[16:31]
	v_cvt_pk_bf16_f32 v48, v48, v49
	v_cvt_pk_bf16_f32 v49, v50, v51
	v_cvt_pk_bf16_f32 v50, v52, v53
	v_cvt_pk_bf16_f32 v51, v54, v55
	v_cvt_pk_bf16_f32 v34, v44, v45
	v_cvt_pk_bf16_f32 v35, v46, v47
	ds_write2_b64 v194, v[48:49], v[50:51] offset1:2
	v_mfma_f32_32x32x16_bf16 v[0:15], v[204:207], v[208:211], v[0:15]
	v_cvt_pk_bf16_f32 v48, v56, v57
	v_cvt_pk_bf16_f32 v49, v58, v59
	v_cvt_pk_bf16_f32 v50, v60, v61
	v_cvt_pk_bf16_f32 v51, v62, v63
	ds_write2_b64 v194, v[32:33], v[34:35] offset0:12 offset1:14
	v_cvt_pk_bf16_f32 v16, v16, v17
	v_cvt_pk_bf16_f32 v17, v18, v19
	v_cvt_pk_bf16_f32 v18, v20, v21
	v_cvt_pk_bf16_f32 v19, v22, v23
	s_nop 2
	v_cvt_pk_bf16_f32 v0, v0, v1
	v_cvt_pk_bf16_f32 v1, v2, v3
	v_cvt_pk_bf16_f32 v2, v4, v5
	v_cvt_pk_bf16_f32 v3, v6, v7
	v_lshl_add_u64 v[34:35], v[72:73], 0, s[28:29]
	ds_write2_b64 v194, v[48:49], v[50:51] offset0:4 offset1:6
	ds_write2_b64 v195, v[16:17], v[18:19] offset1:2
	v_cvt_pk_bf16_f32 v16, v24, v25
	v_cvt_pk_bf16_f32 v17, v26, v27
	v_cvt_pk_bf16_f32 v18, v28, v29
	v_cvt_pk_bf16_f32 v19, v30, v31
	ds_write2_b64 v195, v[0:1], v[2:3] offset0:8 offset1:10
	v_cvt_pk_bf16_f32 v0, v8, v9
	v_cvt_pk_bf16_f32 v1, v10, v11
	v_cvt_pk_bf16_f32 v2, v12, v13
	v_cvt_pk_bf16_f32 v3, v14, v15
	v_lshl_add_u64 v[28:29], v[34:35], 0, v[74:75]
	ds_write2_b64 v195, v[16:17], v[18:19] offset0:4 offset1:6
	ds_write2_b64 v195, v[0:1], v[2:3] offset0:12 offset1:14
	s_waitcnt lgkmcnt(0)
	s_barrier
	global_load_dwordx4 v[0:3], v[28:29], off
	global_load_dwordx4 v[16:19], v[28:29], off offset:32
	ds_read_b128 v[24:27], v199
	ds_read_b128 v[20:23], v199 offset:32
	global_load_dwordx4 v[36:39], v[28:29], off offset:64
	global_load_dwordx4 v[40:43], v[28:29], off offset:96
	s_waitcnt vmcnt(3) lgkmcnt(1)
	v_mfma_f32_32x32x16_bf16 v[0:15], v[0:3], v[24:27], 0
	v_cndmask_b32_e32 v33, v196, v197, vcc
	v_add_u32_e32 v32, s0, v101
	s_or_b32 s0, s14, 1
	s_ashr_i32 s1, s0, 31
	s_lshl_b64 s[0:1], s[0:1], 14
	v_lshlrev_b32_e32 v33, 2, v33
	s_waitcnt vmcnt(2) lgkmcnt(0)
	v_mfma_f32_32x32x16_bf16 v[0:15], v[16:19], v[20:23], v[0:15]
	ds_read_b128 v[28:31], v199 offset:64
	ds_read_b128 v[16:19], v199 offset:96
	s_waitcnt vmcnt(1) lgkmcnt(1)
	v_mfma_f32_32x32x16_bf16 v[0:15], v[36:39], v[28:31], v[0:15]
	s_waitcnt vmcnt(0) lgkmcnt(0)
	v_mfma_f32_32x32x16_bf16 v[0:15], v[40:43], v[16:19], v[0:15]
	s_nop 11
	v_not_b32_e32 v36, v0
	v_or_b32_e32 v37, 0x80000000, v0
	v_cmp_gt_i32_e32 vcc, 0, v0
	v_or_b32_e32 v38, 0x80000000, v3
	v_or_b32_e32 v39, 0x80000000, v7
	v_cndmask_b32_e32 v0, v37, v36, vcc
	v_not_b32_e32 v36, v1
	v_or_b32_e32 v37, 0x80000000, v1
	v_cmp_gt_i32_e32 vcc, 0, v1
	v_and_or_b32 v0, v0, s96, v102
	v_or_b32_e32 v41, 0x80000000, v4
	v_cndmask_b32_e32 v1, v37, v36, vcc
	v_not_b32_e32 v37, v3
	v_cmp_gt_i32_e32 vcc, 0, v3
	v_and_or_b32 v1, v1, s96, v103
	v_max_u32_e32 v36, v0, v1
	v_cndmask_b32_e32 v3, v38, v37, vcc
	v_not_b32_e32 v37, v2
	v_or_b32_e32 v38, 0x80000000, v2
	v_cmp_gt_i32_e32 vcc, 0, v2
	v_and_or_b32 v3, v3, s96, v105
	v_min_u32_e32 v0, v0, v1
	v_cndmask_b32_e32 v2, v38, v37, vcc
	v_and_or_b32 v2, v2, s96, v104
	v_min_u32_e32 v37, v3, v2
	v_max_u32_e32 v1, v3, v2
	v_not_b32_e32 v3, v7
	v_cmp_gt_i32_e32 vcc, 0, v7
	v_not_b32_e32 v7, v6
	v_max_u32_e32 v38, v36, v37
	v_cndmask_b32_e32 v3, v39, v3, vcc
	v_or_b32_e32 v39, 0x80000000, v6
	v_cmp_gt_i32_e32 vcc, 0, v6
	v_and_or_b32 v3, v3, s96, v109
	v_max_u32_e32 v2, v0, v1
	v_cndmask_b32_e32 v6, v39, v7, vcc
	v_not_b32_e32 v39, v4
	v_cmp_gt_i32_e32 vcc, 0, v4
	v_and_or_b32 v6, v6, s96, v108
	v_max_u32_e32 v7, v3, v6
	v_cndmask_b32_e32 v4, v41, v39, vcc
	v_not_b32_e32 v39, v5
	v_or_b32_e32 v41, 0x80000000, v5
	v_cmp_gt_i32_e32 vcc, 0, v5
	v_and_or_b32 v4, v4, s96, v106
	v_min_u32_e32 v3, v3, v6
	v_cndmask_b32_e32 v5, v41, v39, vcc
	v_and_or_b32 v5, v5, s96, v107
	v_min_u32_e32 v39, v4, v5
	v_max_u32_e32 v4, v4, v5
	v_min_u32_e32 v5, v3, v4
	v_min_u32_e32 v36, v36, v37
	v_min_u32_e32 v0, v0, v1
	v_max_u32_e32 v1, v7, v39
	v_max_u32_e32 v3, v3, v4
	v_min_u32_e32 v41, v7, v39
	v_max_u32_e32 v42, v36, v0
	v_min_u32_e32 v7, v1, v3
	v_min_u32_e32 v46, v36, v0
	v_max_u32_e32 v47, v1, v3
	v_not_b32_e32 v0, v15
	v_or_b32_e32 v1, 0x80000000, v15
	v_cmp_gt_i32_e32 vcc, 0, v15
	v_max_u32_e32 v40, v38, v2
	v_min_u32_e32 v44, v38, v2
	v_cndmask_b32_e32 v0, v1, v0, vcc
	v_not_b32_e32 v1, v14
	v_or_b32_e32 v2, 0x80000000, v14
	v_cmp_gt_i32_e32 vcc, 0, v14
	v_not_b32_e32 v3, v12
	v_or_b32_e32 v4, 0x80000000, v12
	v_cndmask_b32_e32 v1, v2, v1, vcc
	v_cmp_gt_i32_e32 vcc, 0, v12
	v_min_u32_e32 v6, v41, v5
	v_max_u32_e32 v45, v41, v5
	v_cndmask_b32_e32 v3, v4, v3, vcc
	v_not_b32_e32 v4, v13
	v_or_b32_e32 v5, 0x80000000, v13
	v_cmp_gt_i32_e32 vcc, 0, v13
	v_and_or_b32 v0, v0, s96, v117
	v_and_or_b32 v1, v1, s96, v116
	v_cndmask_b32_e32 v4, v5, v4, vcc
	v_and_or_b32 v3, v3, s96, v114
	v_and_or_b32 v4, v4, s96, v115
	v_max_u32_e32 v2, v0, v1
	v_min_u32_e32 v5, v3, v4
	v_min_u32_e32 v0, v0, v1
	v_max_u32_e32 v1, v3, v4
	v_not_b32_e32 v3, v8
	v_or_b32_e32 v4, 0x80000000, v8
	v_cmp_gt_i32_e32 vcc, 0, v8
	v_or_b32_e32 v8, 0x80000000, v9
	v_or_b32_e32 v15, 0x80000000, v11
	v_cndmask_b32_e32 v3, v4, v3, vcc
	v_not_b32_e32 v4, v9
	v_cmp_gt_i32_e32 vcc, 0, v9
	v_not_b32_e32 v9, v11
	v_and_or_b32 v3, v3, s96, v110
	v_cndmask_b32_e32 v4, v8, v4, vcc
	v_cmp_gt_i32_e32 vcc, 0, v11
	v_not_b32_e32 v11, v10
	v_and_or_b32 v4, v4, s96, v111
	v_cndmask_b32_e32 v9, v15, v9, vcc
	v_or_b32_e32 v15, 0x80000000, v10
	v_cmp_gt_i32_e32 vcc, 0, v10
	v_and_or_b32 v9, v9, s96, v113
	v_max_u32_e32 v8, v3, v4
	v_cndmask_b32_e32 v10, v15, v11, vcc
	v_and_or_b32 v10, v10, s96, v112
	v_min_u32_e32 v11, v9, v10
	v_min_u32_e32 v3, v3, v4
	v_max_u32_e32 v4, v9, v10
	v_max_u32_e32 v12, v2, v5
	v_min_u32_e32 v15, v8, v11
	v_min_u32_e32 v9, v3, v4
	v_min_u32_e32 v36, v2, v5
	v_max_u32_e32 v8, v8, v11
	v_max_u32_e32 v11, v3, v4
	v_lshl_add_u64 v[4:5], v[34:35], 0, v[76:77]
	v_max_u32_e32 v13, v0, v1
	v_min_u32_e32 v37, v0, v1
	global_load_dwordx4 v[0:3], v[4:5], off
	v_min_u32_e32 v10, v15, v9
	v_max_u32_e32 v56, v36, v37
	v_max_u32_e32 v9, v15, v9
	v_min_u32_e32 v15, v36, v37
	global_load_dwordx4 v[36:39], v[4:5], off offset:32
	v_max_u32_e32 v48, v40, v6
	v_max_u32_e32 v49, v42, v7
	v_min_u32_e32 v6, v40, v6
	v_min_u32_e32 v7, v42, v7
	global_load_dwordx4 v[40:43], v[4:5], off offset:64
	v_max_u32_e32 v51, v44, v45
	v_max_u32_e32 v52, v46, v47
	v_min_u32_e32 v84, v44, v45
	v_min_u32_e32 v85, v46, v47
	global_load_dwordx4 v[44:47], v[4:5], off offset:96
	v_max_u32_e32 v14, v12, v13
	v_min_u32_e32 v57, v8, v11
	v_min_u32_e32 v12, v12, v13
	v_max_u32_e32 v8, v8, v11
	v_min_u32_e32 v55, v14, v10
	v_min_u32_e32 v58, v56, v57
	v_min_u32_e32 v13, v12, v9
	v_min_u32_e32 v11, v15, v8
	v_max_u32_e32 v10, v14, v10
	v_max_u32_e32 v14, v56, v57
	v_max_u32_e32 v5, v12, v9
	v_max_u32_e32 v8, v15, v8
	v_max_u32_e32 v50, v48, v49
	v_max_u32_e32 v53, v51, v52
	v_min_u32_e32 v59, v55, v58
	v_min_u32_e32 v60, v13, v11
	v_max_u32_e32 v63, v6, v7
	v_max_u32_e32 v86, v84, v85
	v_min_u32_e32 v4, v10, v14
	v_min_u32_e32 v9, v5, v8
	v_min_u32_e32 v48, v48, v49
	v_min_u32_e32 v49, v51, v52
	v_max_u32_e32 v52, v55, v58
	v_max_u32_e32 v11, v13, v11
	v_min_u32_e32 v6, v6, v7
	v_min_u32_e32 v7, v84, v85
	v_max_u32_e32 v10, v10, v14
	v_max_u32_e32 v5, v5, v8
	v_max_u32_e32 v54, v50, v53
	v_min_u32_e32 v61, v59, v60
	v_max_u32_e32 v87, v63, v86
	v_min_u32_e32 v12, v4, v9
	v_max_u32_e32 v51, v48, v49
	v_min_u32_e32 v13, v52, v11
	v_max_u32_e32 v57, v6, v7
	v_min_u32_e32 v8, v10, v5
	v_min_u32_e32 v50, v50, v53
	v_max_u32_e32 v53, v59, v60
	v_min_u32_e32 v60, v63, v86
	v_max_u32_e32 v63, v4, v9
	v_min_u32_e32 v48, v48, v49
	v_max_u32_e32 v49, v52, v11
	v_min_u32_e32 v52, v6, v7
	v_max_u32_e32 v85, v10, v5
	v_min_u32_e32 v62, v54, v61
	v_min_u32_e32 v15, v87, v12
	v_min_u32_e32 v55, v51, v13
	v_min_u32_e32 v14, v57, v8
	v_min_u32_e32 v59, v50, v53
	v_min_u32_e32 v4, v60, v63
	v_min_u32_e32 v11, v48, v49
	v_min_u32_e32 v5, v52, v85
	v_min_u32_e32 v56, v62, v15
	v_min_u32_e32 v58, v55, v14
	v_min_u32_e32 v9, v59, v4
	v_min_u32_e32 v6, v11, v5
	v_min_u32_e32 v84, v56, v58
	v_min_u32_e32 v86, v9, v6
	v_max_u32_e32 v56, v56, v58
	v_max_u32_e32 v58, v9, v6
	v_max_u32_e32 v6, v62, v15
	v_max_u32_e32 v7, v55, v14
	v_max_u32_e32 v4, v59, v4
	v_max_u32_e32 v5, v11, v5
	v_min_u32_e32 v55, v6, v7
	v_min_u32_e32 v59, v4, v5
	v_max_u32_e32 v90, v6, v7
	v_max_u32_e32 v91, v4, v5
	v_max_u32_e32 v54, v54, v61
	v_max_u32_e32 v61, v87, v12
	v_max_u32_e32 v51, v51, v13
	v_max_u32_e32 v57, v57, v8
	s_waitcnt vmcnt(3)
	v_mfma_f32_32x32x16_bf16 v[0:15], v[0:3], v[24:27], 0
	v_max_u32_e32 v50, v50, v53
	v_max_u32_e32 v53, v60, v63
	v_min_u32_e32 v93, v51, v57
	v_min_u32_e32 v60, v50, v53
	v_max_u32_e32 v48, v48, v49
	v_max_u32_e32 v49, v52, v85
	v_min_u32_e32 v52, v48, v49
	s_waitcnt vmcnt(2)
	v_mfma_f32_32x32x16_bf16 v[0:15], v[36:39], v[20:23], v[0:15]
	v_max_u32_e32 v36, v54, v61
	v_max_u32_e32 v37, v51, v57
	v_min_u32_e32 v51, v36, v37
	v_max_u32_e32 v38, v50, v53
	v_max_u32_e32 v50, v36, v37
	v_max_u32_e32 v39, v48, v49
	v_min_u32_e32 v48, v38, v39
	s_waitcnt vmcnt(1)
	v_mfma_f32_32x32x16_bf16 v[0:15], v[40:43], v[28:31], v[0:15]
	v_max_u32_e32 v53, v38, v39
	v_min_u32_e32 v87, v54, v61
	v_min_u32_e32 v94, v87, v93
	v_max_u32_e32 v87, v87, v93
	v_min_u32_e32 v63, v60, v52
	v_max_u32_e32 v52, v60, v52
	v_min_u32_e32 v89, v56, v58
	s_waitcnt vmcnt(0)
	v_mfma_f32_32x32x16_bf16 v[0:15], v[44:47], v[16:19], v[0:15]
	v_min_u32_e32 v62, v55, v59
	v_min_u32_e32 v92, v90, v91
	v_min_u32_e32 v60, v87, v52
	v_min_u32_e32 v49, v51, v48
	v_min_u32_e32 v54, v50, v53
	v_min_u32_e32 v88, v84, v86
	v_min_u32_e32 v85, v94, v63
	s_nop 4
	v_not_b32_e32 v36, v0
	v_or_b32_e32 v37, 0x80000000, v0
	v_cmp_gt_i32_e32 vcc, 0, v0
	v_or_b32_e32 v38, 0x80000000, v3
	v_not_b32_e32 v39, v7
	v_cndmask_b32_e32 v0, v37, v36, vcc
	v_not_b32_e32 v36, v1
	v_or_b32_e32 v37, 0x80000000, v1
	v_cmp_gt_i32_e32 vcc, 0, v1
	v_or_b32_e32 v40, 0x80000000, v7
	v_or_b32_e32 v41, 0x80000000, v4
	v_cndmask_b32_e32 v1, v37, v36, vcc
	v_not_b32_e32 v37, v3
	v_cmp_gt_i32_e32 vcc, 0, v3
	v_not_b32_e32 v43, v15
	v_or_b32_e32 v44, 0x80000000, v15
	v_cndmask_b32_e32 v3, v38, v37, vcc
	v_not_b32_e32 v37, v2
	v_or_b32_e32 v38, 0x80000000, v2
	v_cmp_gt_i32_e32 vcc, 0, v2
	v_or_b32_e32 v45, 0x80000000, v12
	v_not_b32_e32 v46, v8
	v_cndmask_b32_e32 v2, v38, v37, vcc
	v_cmp_gt_i32_e32 vcc, 0, v7
	v_or_b32_e32 v47, 0x80000000, v8
	v_or_b32_e32 v57, 0x80000000, v11
	v_cndmask_b32_e32 v7, v40, v39, vcc
	v_not_b32_e32 v39, v6
	v_or_b32_e32 v40, 0x80000000, v6
	v_cmp_gt_i32_e32 vcc, 0, v6
	v_and_or_b32 v0, v0, s96, v118
	v_and_or_b32 v1, v1, s96, v119
	v_cndmask_b32_e32 v6, v40, v39, vcc
	v_not_b32_e32 v40, v4
	v_cmp_gt_i32_e32 vcc, 0, v4
	v_and_or_b32 v3, v3, s96, v121
	v_and_or_b32 v2, v2, s96, v120
	v_cndmask_b32_e32 v4, v41, v40, vcc
	v_not_b32_e32 v40, v5
	v_or_b32_e32 v41, 0x80000000, v5
	v_cmp_gt_i32_e32 vcc, 0, v5
	v_and_or_b32 v7, v7, s96, v125
	v_and_or_b32 v6, v6, s96, v124
	v_cndmask_b32_e32 v5, v41, v40, vcc
	v_cmp_gt_i32_e32 vcc, 0, v15
	v_and_or_b32 v4, v4, s96, v122
	v_and_or_b32 v5, v5, s96, v123
	v_cndmask_b32_e32 v15, v44, v43, vcc
	v_not_b32_e32 v43, v14
	v_or_b32_e32 v44, 0x80000000, v14
	v_cmp_gt_i32_e32 vcc, 0, v14
	v_and_or_b32 v15, v15, s96, v133
	v_max_u32_e32 v36, v0, v1
	v_cndmask_b32_e32 v14, v44, v43, vcc
	v_not_b32_e32 v44, v12
	v_cmp_gt_i32_e32 vcc, 0, v12
	v_and_or_b32 v14, v14, s96, v132
	v_min_u32_e32 v37, v3, v2
	v_cndmask_b32_e32 v12, v45, v44, vcc
	v_not_b32_e32 v44, v13
	v_or_b32_e32 v45, 0x80000000, v13
	v_cmp_gt_i32_e32 vcc, 0, v13
	v_and_or_b32 v12, v12, s96, v130
	v_min_u32_e32 v0, v0, v1
	v_cndmask_b32_e32 v13, v45, v44, vcc
	v_cmp_gt_i32_e32 vcc, 0, v8
	v_and_or_b32 v13, v13, s96, v131
	v_max_u32_e32 v1, v3, v2
	v_cndmask_b32_e32 v8, v47, v46, vcc
	v_not_b32_e32 v46, v9
	v_or_b32_e32 v47, 0x80000000, v9
	v_cmp_gt_i32_e32 vcc, 0, v9
	v_and_or_b32 v8, v8, s96, v126
	v_max_u32_e32 v39, v7, v6
	v_cndmask_b32_e32 v9, v47, v46, vcc
	v_not_b32_e32 v47, v11
	v_cmp_gt_i32_e32 vcc, 0, v11
	v_and_or_b32 v9, v9, s96, v127
	v_min_u32_e32 v40, v4, v5
	v_cndmask_b32_e32 v11, v57, v47, vcc
	v_not_b32_e32 v47, v10
	v_or_b32_e32 v57, 0x80000000, v10
	v_cmp_gt_i32_e32 vcc, 0, v10
	v_and_or_b32 v11, v11, s96, v129
	v_min_u32_e32 v6, v7, v6
	v_cndmask_b32_e32 v10, v57, v47, vcc
	v_and_or_b32 v10, v10, s96, v128
	v_max_u32_e32 v4, v4, v5
	v_max_u32_e32 v43, v15, v14
	v_min_u32_e32 v44, v12, v13
	v_min_u32_e32 v14, v15, v14
	v_max_u32_e32 v12, v12, v13
	v_max_u32_e32 v46, v8, v9
	v_min_u32_e32 v47, v11, v10
	v_min_u32_e32 v8, v8, v9
	v_max_u32_e32 v9, v11, v10
	v_max_u32_e32 v38, v36, v37
	v_max_u32_e32 v2, v0, v1
	v_min_u32_e32 v41, v39, v40
	v_min_u32_e32 v5, v6, v4
	v_min_u32_e32 v36, v36, v37
	v_min_u32_e32 v0, v0, v1
	v_max_u32_e32 v37, v39, v40
	v_max_u32_e32 v4, v6, v4
	v_max_u32_e32 v45, v43, v44
	v_max_u32_e32 v13, v14, v12
	v_min_u32_e32 v57, v46, v47
	v_min_u32_e32 v10, v8, v9
	v_min_u32_e32 v43, v43, v44
	v_min_u32_e32 v12, v14, v12
	v_max_u32_e32 v44, v46, v47
	v_max_u32_e32 v8, v8, v9
	v_max_u32_e32 v3, v38, v2
	v_min_u32_e32 v7, v41, v5
	v_max_u32_e32 v1, v36, v0
	v_min_u32_e32 v6, v37, v4
	v_min_u32_e32 v2, v38, v2
	v_max_u32_e32 v5, v41, v5
	v_min_u32_e32 v0, v36, v0
	v_max_u32_e32 v4, v37, v4
	v_max_u32_e32 v15, v45, v13
	v_min_u32_e32 v11, v57, v10
	v_max_u32_e32 v14, v43, v12
	v_min_u32_e32 v9, v44, v8
	v_min_u32_e32 v13, v45, v13
	v_max_u32_e32 v10, v57, v10
	v_min_u32_e32 v12, v43, v12
	v_max_u32_e32 v8, v44, v8
	v_max_u32_e32 v42, v3, v7
	v_max_u32_e32 v39, v1, v6
	v_max_u32_e32 v38, v2, v5
	v_max_u32_e32 v36, v0, v4
	v_min_u32_e32 v61, v15, v11
	v_min_u32_e32 v46, v14, v9
	v_min_u32_e32 v45, v13, v10
	v_min_u32_e32 v43, v12, v8
	v_min_u32_e32 v3, v3, v7
	v_min_u32_e32 v1, v1, v6
	v_min_u32_e32 v2, v2, v5
	v_min_u32_e32 v0, v0, v4
	v_max_u32_e32 v5, v15, v11
	v_max_u32_e32 v9, v14, v9
	v_max_u32_e32 v10, v13, v10
	v_max_u32_e32 v8, v12, v8
	v_max_u32_e32 v40, v42, v39
	v_max_u32_e32 v37, v38, v36
	v_min_u32_e32 v47, v61, v46
	v_min_u32_e32 v44, v45, v43
	v_max_u32_e32 v6, v3, v1
	v_max_u32_e32 v4, v2, v0
	v_min_u32_e32 v11, v5, v9
	v_min_u32_e32 v12, v10, v8
	v_min_u32_e32 v39, v42, v39
	v_min_u32_e32 v36, v38, v36
	v_max_u32_e32 v42, v61, v46
	v_max_u32_e32 v43, v45, v43
	v_min_u32_e32 v1, v3, v1
	v_min_u32_e32 v0, v2, v0
	v_max_u32_e32 v2, v5, v9
	v_max_u32_e32 v3, v10, v8
	v_max_u32_e32 v41, v40, v37
	v_min_u32_e32 v57, v47, v44
	v_max_u32_e32 v7, v6, v4
	v_min_u32_e32 v13, v11, v12
	v_min_u32_e32 v45, v42, v43
	v_min_u32_e32 v40, v40, v37
	v_max_u32_e32 v44, v47, v44
	v_min_u32_e32 v6, v6, v4
	v_max_u32_e32 v11, v11, v12
	v_min_u32_e32 v47, v39, v36
	v_max_u32_e32 v42, v42, v43
	v_min_u32_e32 v43, v1, v0
	v_max_u32_e32 v95, v2, v3
	v_max_u32_e32 v38, v39, v36
	v_max_u32_e32 v61, v1, v0
	v_min_u32_e32 v8, v2, v3
	v_min_u32_e32 v37, v40, v44
	v_min_u32_e32 v4, v6, v11
	v_min_u32_e32 v36, v47, v42
	v_min_u32_e32 v0, v43, v95
	v_min_u32_e32 v93, v41, v57
	v_min_u32_e32 v14, v7, v13
	v_min_u32_e32 v46, v38, v45
	v_min_u32_e32 v5, v61, v8
	v_min_u32_e32 v12, v37, v4
	v_min_u32_e32 v1, v36, v0
	v_min_u32_e32 v9, v46, v5
	v_min_u32_e32 v96, v12, v1
	v_max_u32_e32 v12, v12, v1
	v_max_u32_e32 v1, v93, v14
	v_max_u32_e32 v2, v46, v5
	v_max_u32_e32 v3, v37, v4
	v_max_u32_e32 v0, v36, v0
	v_lshl_add_u64 v[4:5], v[34:35], 0, v[78:79]
	v_min_u32_e32 v15, v93, v14
	v_min_u32_e32 v14, v1, v2
	v_min_u32_e32 v93, v3, v0
	v_max_u32_e32 v99, v1, v2
	v_max_u32_e32 v200, v3, v0
	global_load_dwordx4 v[0:3], v[4:5], off
	v_max_u32_e32 v45, v38, v45
	global_load_dwordx4 v[36:39], v[4:5], off offset:32
	v_max_u32_e32 v46, v41, v57
	v_max_u32_e32 v202, v40, v44
	v_max_u32_e32 v203, v47, v42
	v_max_u32_e32 v95, v43, v95
	global_load_dwordx4 v[40:43], v[4:5], off offset:64
	v_max_u32_e32 v6, v6, v11
	v_max_u32_e32 v7, v7, v13
	v_max_u32_e32 v8, v61, v8
	v_min_u32_e32 v11, v202, v6
	v_min_u32_e32 v44, v203, v95
	v_min_u32_e32 v13, v46, v7
	v_min_u32_e32 v57, v45, v8
	v_min_u32_e32 v204, v11, v44
	v_max_u32_e32 v11, v11, v44
	v_max_u32_e32 v7, v46, v7
	v_max_u32_e32 v8, v45, v8
	global_load_dwordx4 v[44:47], v[4:5], off offset:96
	v_max_u32_e32 v5, v202, v6
	v_max_u32_e32 v6, v203, v95
	v_min_u32_e32 v10, v15, v9
	v_max_u32_e32 v9, v15, v9
	v_min_u32_e32 v61, v13, v57
	v_max_u32_e32 v13, v13, v57
	v_min_u32_e32 v4, v7, v8
	v_min_u32_e32 v95, v5, v6
	v_max_u32_e32 v7, v7, v8
	v_max_u32_e32 v5, v5, v6
	v_min_u32_e32 v97, v10, v96
	v_min_u32_e32 v15, v9, v12
	v_min_u32_e32 v98, v14, v93
	v_min_u32_e32 v201, v99, v200
	v_min_u32_e32 v205, v61, v204
	v_min_u32_e32 v57, v13, v11
	v_min_u32_e32 v202, v4, v95
	v_min_u32_e32 v6, v7, v5
	v_max3_u32 v8, v50, v53, v97
	v_max3_u32 v10, v54, v10, v96
	v_max3_u32 v15, v51, v48, v15
	v_max3_u32 v9, v49, v9, v12
	v_max3_u32 v12, v87, v52, v98
	v_max3_u32 v14, v60, v14, v93
	v_max3_u32 v48, v94, v63, v201
	v_max3_u32 v50, v90, v91, v205
	v_max3_u32 v51, v92, v61, v204
	v_max3_u32 v52, v55, v59, v57
	v_max3_u32 v11, v62, v13, v11
	v_max3_u32 v13, v56, v58, v202
	v_max3_u32 v4, v89, v4, v95
	v_max3_u32 v6, v84, v86, v6
	v_max3_u32 v49, v85, v99, v200
	v_max3_u32 v5, v88, v7, v5
	v_max_u32_e32 v7, v8, v50
	v_min_u32_e32 v8, v8, v50
	v_max_u32_e32 v50, v10, v51
	v_min_u32_e32 v10, v10, v51
	v_max_u32_e32 v51, v15, v52
	v_min_u32_e32 v15, v15, v52
	v_max_u32_e32 v52, v9, v11
	v_min_u32_e32 v9, v9, v11
	v_max_u32_e32 v11, v12, v13
	v_min_u32_e32 v12, v12, v13
	v_max_u32_e32 v13, v14, v4
	v_min_u32_e32 v4, v14, v4
	v_max_u32_e32 v14, v48, v6
	v_min_u32_e32 v6, v48, v6
	v_max_u32_e32 v48, v49, v5
	v_min_u32_e32 v5, v49, v5
	v_max_u32_e32 v49, v7, v11
	v_min_u32_e32 v53, v7, v11
	v_max_u32_e32 v7, v51, v14
	v_max_u32_e32 v54, v50, v13
	v_min_u32_e32 v50, v50, v13
	v_min_u32_e32 v51, v51, v14
	v_max_u32_e32 v55, v52, v48
	v_min_u32_e32 v48, v52, v48
	v_max_u32_e32 v52, v8, v12
	v_min_u32_e32 v56, v8, v12
	v_max_u32_e32 v57, v10, v4
	v_min_u32_e32 v58, v10, v4
	v_max_u32_e32 v59, v15, v6
	v_min_u32_e32 v60, v15, v6
	v_max_u32_e32 v61, v9, v5
	v_min_u32_e32 v62, v9, v5
	v_max_u32_e32 v63, v49, v7
	v_min_u32_e32 v49, v49, v7
	s_waitcnt vmcnt(3)
	v_mfma_f32_32x32x16_bf16 v[0:15], v[0:3], v[24:27], 0
	v_max_u32_e32 v84, v54, v55
	v_min_u32_e32 v54, v54, v55
	v_max_u32_e32 v55, v53, v51
	v_min_u32_e32 v51, v53, v51
	v_max_u32_e32 v53, v50, v48
	v_min_u32_e32 v48, v50, v48
	v_max_u32_e32 v50, v52, v59
	s_waitcnt vmcnt(2)
	v_mfma_f32_32x32x16_bf16 v[0:15], v[36:39], v[20:23], v[0:15]
	v_min_u32_e32 v52, v52, v59
	v_max_u32_e32 v59, v57, v61
	v_min_u32_e32 v57, v57, v61
	v_max_u32_e32 v61, v56, v60
	v_min_u32_e32 v56, v56, v60
	v_max_u32_e32 v60, v58, v62
	v_min_u32_e32 v58, v58, v62
	s_waitcnt vmcnt(1)
	v_mfma_f32_32x32x16_bf16 v[0:15], v[40:43], v[28:31], v[0:15]
	v_min_u32_e32 v62, v63, v84
	v_min_u32_e32 v85, v49, v54
	v_min_u32_e32 v86, v55, v53
	v_min_u32_e32 v88, v50, v59
	v_min_u32_e32 v89, v52, v57
	v_min_u32_e32 v90, v61, v60
	v_min_u32_e32 v87, v51, v48
	s_waitcnt vmcnt(0)
	v_mfma_f32_32x32x16_bf16 v[0:15], v[44:47], v[16:19], v[0:15]
	v_min_u32_e32 v91, v56, v58
	s_nop 10
	v_not_b32_e32 v36, v0
	v_or_b32_e32 v37, 0x80000000, v0
	v_cmp_gt_i32_e32 vcc, 0, v0
	v_or_b32_e32 v38, 0x80000000, v3
	v_not_b32_e32 v39, v7
	v_cndmask_b32_e32 v0, v37, v36, vcc
	v_not_b32_e32 v36, v1
	v_or_b32_e32 v37, 0x80000000, v1
	v_cmp_gt_i32_e32 vcc, 0, v1
	v_or_b32_e32 v40, 0x80000000, v7
	v_or_b32_e32 v41, 0x80000000, v4
	v_cndmask_b32_e32 v1, v37, v36, vcc
	v_not_b32_e32 v37, v3
	v_cmp_gt_i32_e32 vcc, 0, v3
	v_not_b32_e32 v43, v15
	v_or_b32_e32 v44, 0x80000000, v15
	v_cndmask_b32_e32 v3, v38, v37, vcc
	v_not_b32_e32 v37, v2
	v_or_b32_e32 v38, 0x80000000, v2
	v_cmp_gt_i32_e32 vcc, 0, v2
	v_or_b32_e32 v45, 0x80000000, v12
	v_not_b32_e32 v46, v8
	v_cndmask_b32_e32 v2, v38, v37, vcc
	v_cmp_gt_i32_e32 vcc, 0, v7
	v_or_b32_e32 v47, 0x80000000, v8
	v_or_b32_e32 v92, 0x80000000, v11
	v_cndmask_b32_e32 v7, v40, v39, vcc
	v_not_b32_e32 v39, v6
	v_or_b32_e32 v40, 0x80000000, v6
	v_cmp_gt_i32_e32 vcc, 0, v6
	v_and_or_b32 v0, v0, s96, v134
	v_and_or_b32 v1, v1, s96, v135
	v_cndmask_b32_e32 v6, v40, v39, vcc
	v_not_b32_e32 v40, v4
	v_cmp_gt_i32_e32 vcc, 0, v4
	v_and_or_b32 v3, v3, s96, v137
	v_and_or_b32 v2, v2, s96, v136
	v_cndmask_b32_e32 v4, v41, v40, vcc
	v_not_b32_e32 v40, v5
	v_or_b32_e32 v41, 0x80000000, v5
	v_cmp_gt_i32_e32 vcc, 0, v5
	v_and_or_b32 v7, v7, s96, v141
	v_and_or_b32 v6, v6, s96, v140
	v_cndmask_b32_e32 v5, v41, v40, vcc
	v_cmp_gt_i32_e32 vcc, 0, v15
	v_and_or_b32 v4, v4, s96, v138
	v_and_or_b32 v5, v5, s96, v139
	v_cndmask_b32_e32 v15, v44, v43, vcc
	v_not_b32_e32 v43, v14
	v_or_b32_e32 v44, 0x80000000, v14
	v_cmp_gt_i32_e32 vcc, 0, v14
	v_and_or_b32 v15, v15, s96, v149
	v_max_u32_e32 v36, v0, v1
	v_cndmask_b32_e32 v14, v44, v43, vcc
	v_not_b32_e32 v44, v12
	v_cmp_gt_i32_e32 vcc, 0, v12
	v_and_or_b32 v14, v14, s96, v148
	v_min_u32_e32 v37, v3, v2
	v_cndmask_b32_e32 v12, v45, v44, vcc
	v_not_b32_e32 v44, v13
	v_or_b32_e32 v45, 0x80000000, v13
	v_cmp_gt_i32_e32 vcc, 0, v13
	v_and_or_b32 v12, v12, s96, v146
	v_min_u32_e32 v0, v0, v1
	v_cndmask_b32_e32 v13, v45, v44, vcc
	v_cmp_gt_i32_e32 vcc, 0, v8
	v_and_or_b32 v13, v13, s96, v147
	v_max_u32_e32 v1, v3, v2
	v_cndmask_b32_e32 v8, v47, v46, vcc
	v_not_b32_e32 v46, v9
	v_or_b32_e32 v47, 0x80000000, v9
	v_cmp_gt_i32_e32 vcc, 0, v9
	v_and_or_b32 v8, v8, s96, v142
	v_max_u32_e32 v39, v7, v6
	v_cndmask_b32_e32 v9, v47, v46, vcc
	v_not_b32_e32 v47, v11
	v_cmp_gt_i32_e32 vcc, 0, v11
	v_and_or_b32 v9, v9, s96, v143
	v_min_u32_e32 v40, v4, v5
	v_cndmask_b32_e32 v11, v92, v47, vcc
	v_not_b32_e32 v47, v10
	v_or_b32_e32 v92, 0x80000000, v10
	v_cmp_gt_i32_e32 vcc, 0, v10
	v_and_or_b32 v11, v11, s96, v145
	v_min_u32_e32 v6, v7, v6
	v_cndmask_b32_e32 v10, v92, v47, vcc
	v_and_or_b32 v10, v10, s96, v144
	v_max_u32_e32 v4, v4, v5
	v_max_u32_e32 v43, v15, v14
	v_min_u32_e32 v44, v12, v13
	v_min_u32_e32 v14, v15, v14
	v_max_u32_e32 v12, v12, v13
	v_max_u32_e32 v46, v8, v9
	v_min_u32_e32 v47, v11, v10
	v_min_u32_e32 v8, v8, v9
	v_max_u32_e32 v9, v11, v10
	v_max_u32_e32 v38, v36, v37
	v_max_u32_e32 v2, v0, v1
	v_min_u32_e32 v41, v39, v40
	v_min_u32_e32 v5, v6, v4
	v_min_u32_e32 v36, v36, v37
	v_min_u32_e32 v0, v0, v1
	v_max_u32_e32 v37, v39, v40
	v_max_u32_e32 v4, v6, v4
	v_max_u32_e32 v45, v43, v44
	v_max_u32_e32 v13, v14, v12
	v_min_u32_e32 v92, v46, v47
	v_min_u32_e32 v10, v8, v9
	v_min_u32_e32 v43, v43, v44
	v_min_u32_e32 v12, v14, v12
	v_max_u32_e32 v44, v46, v47
	v_max_u32_e32 v8, v8, v9
	v_max_u32_e32 v3, v38, v2
	v_min_u32_e32 v7, v41, v5
	v_max_u32_e32 v1, v36, v0
	v_min_u32_e32 v6, v37, v4
	v_min_u32_e32 v2, v38, v2
	v_max_u32_e32 v5, v41, v5
	v_min_u32_e32 v0, v36, v0
	v_max_u32_e32 v4, v37, v4
	v_max_u32_e32 v15, v45, v13
	v_min_u32_e32 v11, v92, v10
	v_max_u32_e32 v14, v43, v12
	v_min_u32_e32 v9, v44, v8
	v_min_u32_e32 v13, v45, v13
	v_max_u32_e32 v10, v92, v10
	v_min_u32_e32 v12, v43, v12
	v_max_u32_e32 v8, v44, v8
	v_max_u32_e32 v42, v3, v7
	v_max_u32_e32 v39, v1, v6
	v_max_u32_e32 v38, v2, v5
	v_max_u32_e32 v36, v0, v4
	v_min_u32_e32 v93, v15, v11
	v_min_u32_e32 v46, v14, v9
	v_min_u32_e32 v45, v13, v10
	v_min_u32_e32 v43, v12, v8
	v_min_u32_e32 v3, v3, v7
	v_min_u32_e32 v1, v1, v6
	v_min_u32_e32 v2, v2, v5
	v_min_u32_e32 v0, v0, v4
	v_max_u32_e32 v5, v15, v11
	v_max_u32_e32 v9, v14, v9
	v_max_u32_e32 v10, v13, v10
	v_max_u32_e32 v8, v12, v8
	v_max_u32_e32 v40, v42, v39
	v_max_u32_e32 v37, v38, v36
	v_min_u32_e32 v47, v93, v46
	v_min_u32_e32 v44, v45, v43
	v_max_u32_e32 v6, v3, v1
	v_max_u32_e32 v4, v2, v0
	v_min_u32_e32 v11, v5, v9
	v_min_u32_e32 v12, v10, v8
	v_min_u32_e32 v39, v42, v39
	v_min_u32_e32 v36, v38, v36
	v_max_u32_e32 v42, v93, v46
	v_max_u32_e32 v43, v45, v43
	v_min_u32_e32 v1, v3, v1
	v_min_u32_e32 v0, v2, v0
	v_max_u32_e32 v2, v5, v9
	v_max_u32_e32 v3, v10, v8
	v_max_u32_e32 v41, v40, v37
	v_min_u32_e32 v92, v47, v44
	v_max_u32_e32 v7, v6, v4
	v_min_u32_e32 v13, v11, v12
	v_max_u32_e32 v38, v39, v36
	v_min_u32_e32 v45, v42, v43
	v_min_u32_e32 v40, v40, v37
	v_max_u32_e32 v44, v47, v44
	v_min_u32_e32 v6, v6, v4
	v_max_u32_e32 v11, v11, v12
	v_min_u32_e32 v39, v39, v36
	v_max_u32_e32 v42, v42, v43
	v_min_u32_e32 v43, v1, v0
	v_max_u32_e32 v47, v2, v3
	v_max_u32_e32 v93, v1, v0
	v_min_u32_e32 v8, v2, v3
	v_min_u32_e32 v37, v40, v44
	v_min_u32_e32 v4, v6, v11
	v_min_u32_e32 v36, v39, v42
	v_min_u32_e32 v0, v43, v47
	v_min_u32_e32 v94, v41, v92
	v_min_u32_e32 v14, v7, v13
	v_min_u32_e32 v46, v38, v45
	v_min_u32_e32 v5, v93, v8
	v_min_u32_e32 v12, v37, v4
	v_min_u32_e32 v1, v36, v0
	v_min_u32_e32 v9, v46, v5
	v_min_u32_e32 v95, v12, v1
	v_max_u32_e32 v12, v12, v1
	v_max_u32_e32 v1, v94, v14
	v_max_u32_e32 v2, v46, v5
	v_max_u32_e32 v3, v37, v4
	v_max_u32_e32 v0, v36, v0
	v_lshl_add_u64 v[4:5], v[34:35], 0, v[80:81]
	v_min_u32_e32 v15, v94, v14
	v_min_u32_e32 v14, v1, v2
	v_min_u32_e32 v46, v3, v0
	v_max_u32_e32 v97, v1, v2
	v_max_u32_e32 v98, v3, v0
	global_load_dwordx4 v[0:3], v[4:5], off
	global_load_dwordx4 v[34:37], v[4:5], off offset:32
	v_max_u32_e32 v92, v41, v92
	v_max_u32_e32 v45, v38, v45
	v_max_u32_e32 v201, v40, v44
	v_max_u32_e32 v202, v39, v42
	global_load_dwordx4 v[38:41], v[4:5], off offset:64
	v_max_u32_e32 v6, v6, v11
	v_max_u32_e32 v47, v43, v47
	v_max_u32_e32 v8, v93, v8
	v_min_u32_e32 v11, v201, v6
	v_min_u32_e32 v42, v202, v47
	v_min_u32_e32 v93, v45, v8
	v_min_u32_e32 v203, v11, v42
	v_max_u32_e32 v11, v11, v42
	v_max_u32_e32 v8, v45, v8
	global_load_dwordx4 v[42:45], v[4:5], off offset:96
	v_max_u32_e32 v7, v7, v13
	v_min_u32_e32 v13, v92, v7
	v_max_u32_e32 v7, v92, v7
	v_max_u32_e32 v5, v201, v6
	v_max_u32_e32 v6, v202, v47
	v_min_u32_e32 v10, v15, v9
	v_max_u32_e32 v9, v15, v9
	v_min_u32_e32 v200, v13, v93
	v_max_u32_e32 v13, v13, v93
	v_min_u32_e32 v4, v7, v8
	v_min_u32_e32 v47, v5, v6
	v_max_u32_e32 v7, v7, v8
	v_max_u32_e32 v5, v5, v6
	v_min_u32_e32 v96, v10, v95
	v_min_u32_e32 v15, v9, v12
	v_min_u32_e32 v94, v14, v46
	v_min_u32_e32 v99, v97, v98
	v_min_u32_e32 v204, v200, v203
	v_min_u32_e32 v93, v13, v11
	v_min_u32_e32 v92, v4, v47
	v_min_u32_e32 v6, v7, v5
	v_max3_u32 v8, v63, v84, v96
	v_max3_u32 v10, v62, v10, v95
	v_max3_u32 v15, v49, v54, v15
	v_max3_u32 v9, v85, v9, v12
	v_max3_u32 v12, v55, v53, v94
	v_max3_u32 v14, v86, v14, v46
	v_max3_u32 v46, v51, v48, v99
	v_max3_u32 v49, v50, v59, v204
	v_max3_u32 v50, v88, v200, v203
	v_max3_u32 v51, v52, v57, v93
	v_max3_u32 v11, v89, v13, v11
	v_max3_u32 v13, v61, v60, v92
	v_max3_u32 v4, v90, v4, v47
	v_max3_u32 v6, v56, v58, v6
	v_max3_u32 v48, v87, v97, v98
	v_max3_u32 v5, v91, v7, v5
	v_max_u32_e32 v7, v8, v49
	v_min_u32_e32 v8, v8, v49
	v_max_u32_e32 v47, v10, v50
	v_min_u32_e32 v10, v10, v50
	v_max_u32_e32 v49, v15, v51
	v_max_u32_e32 v50, v9, v11
	v_min_u32_e32 v9, v9, v11
	v_max_u32_e32 v11, v12, v13
	v_min_u32_e32 v12, v12, v13
	v_max_u32_e32 v13, v14, v4
	v_min_u32_e32 v4, v14, v4
	v_max_u32_e32 v14, v46, v6
	v_min_u32_e32 v15, v15, v51
	v_min_u32_e32 v6, v46, v6
	v_max_u32_e32 v46, v48, v5
	v_min_u32_e32 v5, v48, v5
	v_max_u32_e32 v48, v7, v11
	v_min_u32_e32 v51, v7, v11
	v_max_u32_e32 v7, v49, v14
	v_max_u32_e32 v52, v47, v13
	v_min_u32_e32 v47, v47, v13
	v_min_u32_e32 v49, v49, v14
	v_max_u32_e32 v53, v50, v46
	v_min_u32_e32 v46, v50, v46
	v_max_u32_e32 v50, v8, v12
	v_min_u32_e32 v54, v8, v12
	v_max_u32_e32 v55, v10, v4
	v_min_u32_e32 v56, v10, v4
	v_max_u32_e32 v57, v15, v6
	v_min_u32_e32 v58, v15, v6
	v_max_u32_e32 v59, v9, v5
	v_min_u32_e32 v60, v9, v5
	v_max_u32_e32 v61, v48, v7
	v_min_u32_e32 v48, v48, v7
	s_waitcnt vmcnt(3)
	v_mfma_f32_32x32x16_bf16 v[0:15], v[0:3], v[24:27], 0
	v_max_u32_e32 v25, v51, v49
	v_min_u32_e32 v26, v51, v49
	v_max_u32_e32 v27, v47, v46
	v_min_u32_e32 v46, v47, v46
	v_max_u32_e32 v47, v50, v57
	v_min_u32_e32 v49, v50, v57
	v_max_u32_e32 v62, v52, v53
	s_waitcnt vmcnt(2)
	v_mfma_f32_32x32x16_bf16 v[0:15], v[34:37], v[20:23], v[0:15]
	v_min_u32_e32 v24, v52, v53
	v_max_u32_e32 v22, v54, v58
	v_min_u32_e32 v23, v54, v58
	v_max_u32_e32 v20, v55, v59
	v_min_u32_e32 v21, v55, v59
	v_max_u32_e32 v34, v56, v60
	v_min_u32_e32 v36, v56, v60
	s_waitcnt vmcnt(1)
	v_mfma_f32_32x32x16_bf16 v[0:15], v[38:41], v[28:31], v[0:15]
	v_min_u32_e32 v31, v47, v20
	v_min_u32_e32 v29, v25, v27
	v_min_u32_e32 v39, v22, v34
	v_min_u32_e32 v28, v48, v24
	v_min_u32_e32 v38, v49, v21
	v_min_u32_e32 v37, v61, v62
	v_min_u32_e32 v30, v26, v46
	s_waitcnt vmcnt(0)
	v_mfma_f32_32x32x16_bf16 v[0:15], v[42:45], v[16:19], v[0:15]
	v_min_u32_e32 v40, v23, v36
	s_nop 10
	v_not_b32_e32 v16, v0
	v_or_b32_e32 v17, 0x80000000, v0
	v_cmp_gt_i32_e32 vcc, 0, v0
	v_or_b32_e32 v18, 0x80000000, v3
	v_not_b32_e32 v19, v7
	v_cndmask_b32_e32 v0, v17, v16, vcc
	v_not_b32_e32 v16, v1
	v_or_b32_e32 v17, 0x80000000, v1
	v_cmp_gt_i32_e32 vcc, 0, v1
	v_or_b32_e32 v35, 0x80000000, v7
	v_or_b32_e32 v41, 0x80000000, v4
	v_cndmask_b32_e32 v1, v17, v16, vcc
	v_not_b32_e32 v17, v3
	v_cmp_gt_i32_e32 vcc, 0, v3
	v_not_b32_e32 v43, v15
	v_or_b32_e32 v44, 0x80000000, v15
	v_cndmask_b32_e32 v3, v18, v17, vcc
	v_not_b32_e32 v17, v2
	v_or_b32_e32 v18, 0x80000000, v2
	v_cmp_gt_i32_e32 vcc, 0, v2
	v_or_b32_e32 v45, 0x80000000, v12
	v_not_b32_e32 v50, v8
	v_cndmask_b32_e32 v2, v18, v17, vcc
	v_cmp_gt_i32_e32 vcc, 0, v7
	v_or_b32_e32 v51, 0x80000000, v8
	v_or_b32_e32 v52, 0x80000000, v11
	v_cndmask_b32_e32 v7, v35, v19, vcc
	v_not_b32_e32 v19, v6
	v_or_b32_e32 v35, 0x80000000, v6
	v_cmp_gt_i32_e32 vcc, 0, v6
	v_and_or_b32 v0, v0, s96, v150
	v_and_or_b32 v1, v1, s96, v151
	v_cndmask_b32_e32 v6, v35, v19, vcc
	v_not_b32_e32 v35, v4
	v_cmp_gt_i32_e32 vcc, 0, v4
	v_and_or_b32 v3, v3, s96, v153
	v_and_or_b32 v2, v2, s96, v152
	v_cndmask_b32_e32 v4, v41, v35, vcc
	v_not_b32_e32 v35, v5
	v_or_b32_e32 v41, 0x80000000, v5
	v_cmp_gt_i32_e32 vcc, 0, v5
	v_and_or_b32 v7, v7, s96, v158
	v_and_or_b32 v6, v6, s96, v157
	v_cndmask_b32_e32 v5, v41, v35, vcc
	v_cmp_gt_i32_e32 vcc, 0, v15
	v_and_or_b32 v4, v4, s96, v155
	v_and_or_b32 v5, v5, s96, v156
	v_cndmask_b32_e32 v15, v44, v43, vcc
	v_not_b32_e32 v43, v14
	v_or_b32_e32 v44, 0x80000000, v14
	v_cmp_gt_i32_e32 vcc, 0, v14
	v_and_or_b32 v15, v15, s96, v166
	v_max_u32_e32 v16, v0, v1
	v_cndmask_b32_e32 v14, v44, v43, vcc
	v_not_b32_e32 v44, v12
	v_cmp_gt_i32_e32 vcc, 0, v12
	v_and_or_b32 v14, v14, s96, v165
	v_min_u32_e32 v17, v3, v2
	v_cndmask_b32_e32 v12, v45, v44, vcc
	v_not_b32_e32 v44, v13
	v_or_b32_e32 v45, 0x80000000, v13
	v_cmp_gt_i32_e32 vcc, 0, v13
	v_and_or_b32 v12, v12, s96, v163
	v_min_u32_e32 v0, v0, v1
	v_cndmask_b32_e32 v13, v45, v44, vcc
	v_cmp_gt_i32_e32 vcc, 0, v8
	v_and_or_b32 v13, v13, s96, v164
	v_max_u32_e32 v1, v3, v2
	v_cndmask_b32_e32 v8, v51, v50, vcc
	v_not_b32_e32 v50, v9
	v_or_b32_e32 v51, 0x80000000, v9
	v_cmp_gt_i32_e32 vcc, 0, v9
	v_and_or_b32 v8, v8, s96, v159
	v_max_u32_e32 v19, v7, v6
	v_cndmask_b32_e32 v9, v51, v50, vcc
	v_not_b32_e32 v51, v11
	v_cmp_gt_i32_e32 vcc, 0, v11
	v_and_or_b32 v9, v9, s96, v160
	v_min_u32_e32 v35, v4, v5
	v_cndmask_b32_e32 v11, v52, v51, vcc
	v_not_b32_e32 v51, v10
	v_or_b32_e32 v52, 0x80000000, v10
	v_cmp_gt_i32_e32 vcc, 0, v10
	v_and_or_b32 v11, v11, s96, v162
	v_min_u32_e32 v6, v7, v6
	v_cndmask_b32_e32 v10, v52, v51, vcc
	v_and_or_b32 v10, v10, s96, v161
	v_max_u32_e32 v4, v4, v5
	v_max_u32_e32 v43, v15, v14
	v_min_u32_e32 v44, v12, v13
	v_min_u32_e32 v14, v15, v14
	v_max_u32_e32 v12, v12, v13
	v_max_u32_e32 v50, v8, v9
	v_min_u32_e32 v51, v11, v10
	v_min_u32_e32 v8, v8, v9
	v_max_u32_e32 v9, v11, v10
	v_max_u32_e32 v18, v16, v17
	v_max_u32_e32 v2, v0, v1
	v_min_u32_e32 v41, v19, v35
	v_min_u32_e32 v5, v6, v4
	v_min_u32_e32 v16, v16, v17
	v_min_u32_e32 v0, v0, v1
	v_max_u32_e32 v17, v19, v35
	v_max_u32_e32 v4, v6, v4
	v_max_u32_e32 v45, v43, v44
	v_max_u32_e32 v13, v14, v12
	v_min_u32_e32 v52, v50, v51
	v_min_u32_e32 v10, v8, v9
	v_min_u32_e32 v43, v43, v44
	v_min_u32_e32 v12, v14, v12
	v_max_u32_e32 v44, v50, v51
	v_max_u32_e32 v8, v8, v9
	v_max_u32_e32 v3, v18, v2
	v_min_u32_e32 v7, v41, v5
	v_max_u32_e32 v1, v16, v0
	v_min_u32_e32 v6, v17, v4
	v_min_u32_e32 v2, v18, v2
	v_max_u32_e32 v5, v41, v5
	v_min_u32_e32 v0, v16, v0
	v_max_u32_e32 v4, v17, v4
	v_max_u32_e32 v15, v45, v13
	v_min_u32_e32 v11, v52, v10
	v_max_u32_e32 v14, v43, v12
	v_min_u32_e32 v9, v44, v8
	v_min_u32_e32 v13, v45, v13
	v_max_u32_e32 v10, v52, v10
	v_min_u32_e32 v12, v43, v12
	v_max_u32_e32 v8, v44, v8
	v_max_u32_e32 v42, v3, v7
	v_max_u32_e32 v19, v1, v6
	v_max_u32_e32 v18, v2, v5
	v_max_u32_e32 v16, v0, v4
	v_min_u32_e32 v53, v15, v11
	v_min_u32_e32 v50, v14, v9
	v_min_u32_e32 v45, v13, v10
	v_min_u32_e32 v43, v12, v8
	v_min_u32_e32 v3, v3, v7
	v_min_u32_e32 v1, v1, v6
	v_min_u32_e32 v2, v2, v5
	v_min_u32_e32 v0, v0, v4
	v_max_u32_e32 v7, v15, v11
	v_max_u32_e32 v9, v14, v9
	v_max_u32_e32 v10, v13, v10
	v_max_u32_e32 v8, v12, v8
	v_max_u32_e32 v35, v42, v19
	v_max_u32_e32 v17, v18, v16
	v_min_u32_e32 v51, v53, v50
	v_min_u32_e32 v44, v45, v43
	v_max_u32_e32 v6, v3, v1
	v_max_u32_e32 v4, v2, v0
	v_min_u32_e32 v11, v7, v9
	v_min_u32_e32 v12, v10, v8
	v_min_u32_e32 v19, v42, v19
	v_min_u32_e32 v16, v18, v16
	v_max_u32_e32 v42, v53, v50
	v_max_u32_e32 v43, v45, v43
	v_min_u32_e32 v1, v3, v1
	v_min_u32_e32 v0, v2, v0
	v_max_u32_e32 v3, v7, v9
	v_max_u32_e32 v7, v10, v8
	v_max_u32_e32 v41, v35, v17
	v_min_u32_e32 v52, v51, v44
	v_max_u32_e32 v5, v6, v4
	v_min_u32_e32 v13, v11, v12
	v_max_u32_e32 v18, v19, v16
	v_min_u32_e32 v45, v42, v43
	v_max_u32_e32 v2, v1, v0
	v_min_u32_e32 v8, v3, v7
	v_min_u32_e32 v17, v35, v17
	v_max_u32_e32 v35, v51, v44
	v_min_u32_e32 v4, v6, v4
	v_max_u32_e32 v6, v11, v12
	v_min_u32_e32 v16, v19, v16
	v_max_u32_e32 v19, v42, v43
	v_min_u32_e32 v0, v1, v0
	v_max_u32_e32 v1, v3, v7
	v_min_u32_e32 v54, v41, v52
	v_min_u32_e32 v14, v5, v13
	v_min_u32_e32 v50, v18, v45
	v_min_u32_e32 v9, v2, v8
	v_min_u32_e32 v44, v17, v35
	v_min_u32_e32 v11, v4, v6
	v_min_u32_e32 v42, v16, v19
	v_min_u32_e32 v3, v0, v1
	v_max_u32_e32 v41, v41, v52
	v_max_u32_e32 v5, v5, v13
	v_max_u32_e32 v18, v18, v45
	v_max_u32_e32 v2, v2, v8
	v_max_u32_e32 v17, v17, v35
	v_max_u32_e32 v4, v4, v6
	v_max_u32_e32 v16, v16, v19
	v_max_u32_e32 v0, v0, v1
	v_min_u32_e32 v13, v41, v5
	v_min_u32_e32 v8, v18, v2
	v_min_u32_e32 v6, v17, v4
	v_min_u32_e32 v19, v16, v0
	v_min_u32_e32 v15, v54, v14
	v_min_u32_e32 v10, v50, v9
	v_min_u32_e32 v12, v44, v11
	v_min_u32_e32 v7, v42, v3
	v_min_u32_e32 v45, v13, v8
	v_min_u32_e32 v52, v6, v19
	v_max_u32_e32 v14, v54, v14
	v_max_u32_e32 v9, v50, v9
	v_max_u32_e32 v11, v44, v11
	v_max_u32_e32 v42, v42, v3
	v_min_u32_e32 v1, v45, v52
	v_min_u32_e32 v50, v14, v9
	v_min_u32_e32 v44, v11, v42
	v_max3_u32 v20, v47, v20, v1
	v_min_u32_e32 v1, v50, v44
	v_max3_u32 v25, v25, v27, v1
	v_max_u32_e32 v27, v41, v5
	v_max_u32_e32 v41, v18, v2
	v_max_u32_e32 v55, v17, v4
	v_max_u32_e32 v56, v16, v0
	v_min_u32_e32 v54, v27, v41
	v_min_u32_e32 v57, v55, v56
	v_min_u32_e32 v0, v54, v57
	v_min_u32_e32 v53, v15, v10
	v_min_u32_e32 v43, v12, v7
	v_max3_u32 v22, v22, v34, v0
	v_max_u32_e32 v10, v15, v10
	v_max_u32_e32 v7, v12, v7
	v_lshl_add_u64 v[34:35], v[72:73], 0, s[0:1]
	v_min_u32_e32 v0, v10, v7
	v_lshl_add_u64 v[4:5], v[34:35], 0, v[74:75]
	v_max3_u32 v12, v48, v24, v0
	global_load_dwordx4 v[0:3], v[4:5], off
	v_max_u32_e32 v6, v6, v19
	global_load_dwordx4 v[16:19], v[4:5], off offset:32
	global_load_dwordx4 v[86:89], v[4:5], off offset:64
	global_load_dwordx4 v[90:93], v[4:5], off offset:96
	v_max_u32_e32 v8, v13, v8
	v_min_u32_e32 v13, v8, v6
	v_max_u32_e32 v9, v14, v9
	v_max_u32_e32 v11, v11, v42
	v_max3_u32 v13, v49, v21, v13
	v_min_u32_e32 v14, v9, v11
	v_max_u32_e32 v21, v27, v41
	v_max_u32_e32 v24, v55, v56
	v_min_u32_e32 v51, v53, v43
	v_max3_u32 v14, v26, v46, v14
	v_min_u32_e32 v26, v21, v24
	v_max3_u32 v51, v61, v62, v51
	v_max3_u32 v23, v23, v36, v26
	v_max3_u32 v27, v37, v53, v43
	v_max3_u32 v31, v31, v45, v52
	v_max3_u32 v29, v29, v50, v44
	v_max3_u32 v37, v39, v54, v57
	v_max3_u32 v7, v28, v10, v7
	v_max3_u32 v6, v38, v8, v6
	v_max3_u32 v9, v30, v9, v11
	v_max3_u32 v10, v40, v21, v24
	v_min_u32_e32 v47, v51, v20
	v_min_u32_e32 v58, v25, v22
	v_min_u32_e32 v15, v12, v13
	v_min_u32_e32 v46, v27, v31
	v_min_u32_e32 v8, v7, v6
	v_max_u32_e32 v20, v51, v20
	v_max_u32_e32 v22, v25, v22
	v_max_u32_e32 v12, v12, v13
	v_max_u32_e32 v13, v14, v23
	v_max_u32_e32 v25, v27, v31
	v_max_u32_e32 v27, v29, v37
	v_max_u32_e32 v6, v7, v6
	v_max_u32_e32 v7, v9, v10
	v_min_u32_e32 v26, v14, v23
	v_min_u32_e32 v4, v29, v37
	v_min_u32_e32 v11, v9, v10
	v_max_u32_e32 v24, v20, v22
	v_max_u32_e32 v14, v12, v13
	v_max_u32_e32 v29, v25, v27
	v_max_u32_e32 v9, v6, v7
	v_max_u32_e32 v23, v24, v14
	v_max_u32_e32 v10, v29, v9
	v_max_u32_e32 v42, v23, v10
	v_min_u32_e32 v38, v23, v10
	v_min_u32_e32 v10, v24, v14
	v_min_u32_e32 v9, v29, v9
	v_max_u32_e32 v41, v10, v9
	v_min_u32_e32 v37, v10, v9
	v_min_u32_e32 v9, v20, v22
	v_min_u32_e32 v10, v12, v13
	v_min_u32_e32 v13, v25, v27
	v_min_u32_e32 v6, v6, v7
	v_max_u32_e32 v12, v9, v10
	v_max_u32_e32 v7, v13, v6
	v_max_u32_e32 v45, v12, v7
	v_min_u32_e32 v40, v12, v7
	v_min_u32_e32 v7, v9, v10
	v_min_u32_e32 v6, v13, v6
	v_min_u32_e32 v48, v15, v26
	v_max_u32_e32 v43, v7, v6
	v_min_u32_e32 v39, v7, v6
	v_max_u32_e32 v7, v15, v26
	ds_read_b128 v[24:27], v199 offset:128
	v_min_u32_e32 v5, v46, v4
	v_min_u32_e32 v21, v8, v11
	v_max_u32_e32 v6, v47, v58
	v_max_u32_e32 v4, v46, v4
	v_max_u32_e32 v8, v8, v11
	v_max_u32_e32 v9, v6, v7
	v_max_u32_e32 v10, v4, v8
	v_min_u32_e32 v6, v6, v7
	v_min_u32_e32 v4, v4, v8
	v_min_u32_e32 v28, v5, v21
	v_max_u32_e32 v52, v9, v10
	v_min_u32_e32 v46, v9, v10
	v_max_u32_e32 v49, v6, v4
	v_min_u32_e32 v44, v6, v4
	v_max_u32_e32 v30, v5, v21
	ds_read_b128 v[20:23], v199 offset:160
	s_waitcnt vmcnt(3) lgkmcnt(1)
	v_mfma_f32_32x32x16_bf16 v[0:15], v[0:3], v[24:27], 0
	v_min_u32_e32 v59, v47, v58
	v_min_u32_e32 v55, v59, v48
	v_max_u32_e32 v29, v59, v48
	v_min_u32_e32 v36, v55, v28
	v_max_u32_e32 v57, v29, v30
	v_min_u32_e32 v48, v29, v30
	v_max_u32_e32 v54, v55, v28
	s_waitcnt vmcnt(2) lgkmcnt(0)
	v_mfma_f32_32x32x16_bf16 v[0:15], v[16:19], v[20:23], v[0:15]
	ds_read_b128 v[28:31], v199 offset:192
	ds_read_b128 v[16:19], v199 offset:224
	ds_bpermute_b32 v47, v33, v42
	ds_bpermute_b32 v55, v33, v38
	ds_bpermute_b32 v51, v33, v41
	ds_bpermute_b32 v61, v33, v37
	ds_bpermute_b32 v50, v33, v45
	s_waitcnt vmcnt(1) lgkmcnt(6)
	v_mfma_f32_32x32x16_bf16 v[0:15], v[86:89], v[28:31], v[0:15]
	ds_bpermute_b32 v60, v33, v40
	ds_bpermute_b32 v56, v33, v43
	ds_bpermute_b32 v84, v33, v39
	ds_bpermute_b32 v53, v33, v52
	ds_bpermute_b32 v62, v33, v46
	ds_bpermute_b32 v59, v33, v49
	ds_bpermute_b32 v86, v33, v44
	s_waitcnt vmcnt(0) lgkmcnt(12)
	v_mfma_f32_32x32x16_bf16 v[0:15], v[90:93], v[16:19], v[0:15]
	ds_bpermute_b32 v58, v33, v57
	ds_bpermute_b32 v85, v33, v48
	ds_bpermute_b32 v63, v33, v54
	ds_bpermute_b32 v87, v33, v36
	s_waitcnt lgkmcnt(9)
	v_max_u32_e32 v46, v46, v56
	s_waitcnt lgkmcnt(5)
	v_max_u32_e32 v40, v40, v59
	s_waitcnt lgkmcnt(3)
	v_max_u32_e32 v37, v37, v58
	s_nop 1
	v_not_b32_e32 v88, v0
	v_or_b32_e32 v89, 0x80000000, v0
	v_cmp_gt_i32_e32 vcc, 0, v0
	v_or_b32_e32 v90, 0x80000000, v3
	v_or_b32_e32 v91, 0x80000000, v7
	v_cndmask_b32_e32 v0, v89, v88, vcc
	v_not_b32_e32 v88, v1
	v_or_b32_e32 v89, 0x80000000, v1
	v_cmp_gt_i32_e32 vcc, 0, v1
	v_and_or_b32 v0, v0, s96, v102
	v_or_b32_e32 v93, 0x80000000, v4
	v_cndmask_b32_e32 v1, v89, v88, vcc
	v_not_b32_e32 v89, v3
	v_cmp_gt_i32_e32 vcc, 0, v3
	v_and_or_b32 v1, v1, s96, v103
	v_max_u32_e32 v88, v0, v1
	v_cndmask_b32_e32 v3, v90, v89, vcc
	v_not_b32_e32 v89, v2
	v_or_b32_e32 v90, 0x80000000, v2
	v_cmp_gt_i32_e32 vcc, 0, v2
	v_and_or_b32 v3, v3, s96, v105
	v_min_u32_e32 v0, v0, v1
	v_cndmask_b32_e32 v2, v90, v89, vcc
	v_and_or_b32 v2, v2, s96, v104
	v_min_u32_e32 v89, v3, v2
	v_max_u32_e32 v1, v3, v2
	v_not_b32_e32 v3, v7
	v_cmp_gt_i32_e32 vcc, 0, v7
	v_not_b32_e32 v7, v6
	v_max_u32_e32 v90, v88, v89
	v_cndmask_b32_e32 v3, v91, v3, vcc
	v_or_b32_e32 v91, 0x80000000, v6
	v_cmp_gt_i32_e32 vcc, 0, v6
	v_and_or_b32 v3, v3, s96, v109
	v_max_u32_e32 v2, v0, v1
	v_cndmask_b32_e32 v6, v91, v7, vcc
	v_not_b32_e32 v91, v4
	v_cmp_gt_i32_e32 vcc, 0, v4
	v_and_or_b32 v6, v6, s96, v108
	v_max_u32_e32 v7, v3, v6
	v_cndmask_b32_e32 v4, v93, v91, vcc
	v_not_b32_e32 v91, v5
	v_or_b32_e32 v93, 0x80000000, v5
	v_cmp_gt_i32_e32 vcc, 0, v5
	v_and_or_b32 v4, v4, s96, v106
	v_min_u32_e32 v3, v3, v6
	v_cndmask_b32_e32 v5, v93, v91, vcc
	v_and_or_b32 v5, v5, s96, v107
	v_min_u32_e32 v91, v4, v5
	v_max_u32_e32 v4, v4, v5
	v_min_u32_e32 v5, v3, v4
	v_min_u32_e32 v88, v88, v89
	v_min_u32_e32 v0, v0, v1
	v_max_u32_e32 v1, v7, v91
	v_max_u32_e32 v3, v3, v4
	v_min_u32_e32 v93, v7, v91
	v_max_u32_e32 v94, v88, v0
	v_min_u32_e32 v7, v1, v3
	v_min_u32_e32 v98, v88, v0
	v_max_u32_e32 v99, v1, v3
	v_not_b32_e32 v0, v15
	v_or_b32_e32 v1, 0x80000000, v15
	v_cmp_gt_i32_e32 vcc, 0, v15
	v_max_u32_e32 v92, v90, v2
	v_min_u32_e32 v96, v90, v2
	v_cndmask_b32_e32 v0, v1, v0, vcc
	v_not_b32_e32 v1, v14
	v_or_b32_e32 v2, 0x80000000, v14
	v_cmp_gt_i32_e32 vcc, 0, v14
	v_not_b32_e32 v3, v12
	v_or_b32_e32 v4, 0x80000000, v12
	v_cndmask_b32_e32 v1, v2, v1, vcc
	v_cmp_gt_i32_e32 vcc, 0, v12
	v_min_u32_e32 v6, v93, v5
	v_max_u32_e32 v97, v93, v5
	v_cndmask_b32_e32 v3, v4, v3, vcc
	v_not_b32_e32 v4, v13
	v_or_b32_e32 v5, 0x80000000, v13
	v_cmp_gt_i32_e32 vcc, 0, v13
	v_and_or_b32 v0, v0, s96, v117
	v_and_or_b32 v1, v1, s96, v116
	v_cndmask_b32_e32 v4, v5, v4, vcc
	v_and_or_b32 v3, v3, s96, v114
	v_and_or_b32 v4, v4, s96, v115
	v_max_u32_e32 v2, v0, v1
	v_min_u32_e32 v5, v3, v4
	v_min_u32_e32 v0, v0, v1
	v_max_u32_e32 v1, v3, v4
	v_not_b32_e32 v3, v8
	v_or_b32_e32 v4, 0x80000000, v8
	v_cmp_gt_i32_e32 vcc, 0, v8
	v_or_b32_e32 v8, 0x80000000, v9
	v_or_b32_e32 v15, 0x80000000, v11
	v_cndmask_b32_e32 v3, v4, v3, vcc
	v_not_b32_e32 v4, v9
	v_cmp_gt_i32_e32 vcc, 0, v9
	v_not_b32_e32 v9, v11
	v_and_or_b32 v3, v3, s96, v110
	v_cndmask_b32_e32 v4, v8, v4, vcc
	v_cmp_gt_i32_e32 vcc, 0, v11
	v_not_b32_e32 v11, v10
	v_and_or_b32 v4, v4, s96, v111
	v_cndmask_b32_e32 v9, v15, v9, vcc
	v_or_b32_e32 v15, 0x80000000, v10
	v_cmp_gt_i32_e32 vcc, 0, v10
	v_and_or_b32 v9, v9, s96, v113
	v_max_u32_e32 v8, v3, v4
	v_cndmask_b32_e32 v10, v15, v11, vcc
	v_and_or_b32 v10, v10, s96, v112
	v_min_u32_e32 v11, v9, v10
	v_min_u32_e32 v3, v3, v4
	v_max_u32_e32 v4, v9, v10
	v_max_u32_e32 v12, v2, v5
	v_min_u32_e32 v15, v8, v11
	v_min_u32_e32 v9, v3, v4
	v_min_u32_e32 v88, v2, v5
	v_max_u32_e32 v8, v8, v11
	v_max_u32_e32 v11, v3, v4
	v_lshl_add_u64 v[4:5], v[34:35], 0, v[76:77]
	v_max_u32_e32 v13, v0, v1
	v_min_u32_e32 v89, v0, v1
	global_load_dwordx4 v[0:3], v[4:5], off
	v_min_u32_e32 v10, v15, v9
	v_max_u32_e32 v208, v88, v89
	v_max_u32_e32 v9, v15, v9
	v_min_u32_e32 v15, v88, v89
	global_load_dwordx4 v[88:91], v[4:5], off offset:32
	v_max_u32_e32 v200, v92, v6
	v_max_u32_e32 v201, v94, v7
	v_min_u32_e32 v6, v92, v6
	v_min_u32_e32 v7, v94, v7
	global_load_dwordx4 v[92:95], v[4:5], off offset:64
	v_max_u32_e32 v203, v96, v97
	v_max_u32_e32 v204, v98, v99
	v_min_u32_e32 v216, v96, v97
	v_min_u32_e32 v217, v98, v99
	global_load_dwordx4 v[96:99], v[4:5], off offset:96
	v_max_u32_e32 v14, v12, v13
	v_min_u32_e32 v209, v8, v11
	v_min_u32_e32 v12, v12, v13
	v_max_u32_e32 v8, v8, v11
	v_min_u32_e32 v207, v14, v10
	v_min_u32_e32 v210, v208, v209
	v_min_u32_e32 v13, v12, v9
	v_min_u32_e32 v11, v15, v8
	v_max_u32_e32 v10, v14, v10
	v_max_u32_e32 v14, v208, v209
	v_max_u32_e32 v5, v12, v9
	v_max_u32_e32 v8, v15, v8
	v_max_u32_e32 v202, v200, v201
	v_max_u32_e32 v205, v203, v204
	v_min_u32_e32 v211, v207, v210
	v_min_u32_e32 v212, v13, v11
	v_max_u32_e32 v215, v6, v7
	v_max_u32_e32 v218, v216, v217
	v_min_u32_e32 v4, v10, v14
	v_min_u32_e32 v9, v5, v8
	v_min_u32_e32 v200, v200, v201
	v_min_u32_e32 v201, v203, v204
	v_max_u32_e32 v204, v207, v210
	v_max_u32_e32 v11, v13, v11
	v_min_u32_e32 v6, v6, v7
	v_min_u32_e32 v7, v216, v217
	v_max_u32_e32 v10, v10, v14
	v_max_u32_e32 v5, v5, v8
	v_max_u32_e32 v206, v202, v205
	v_min_u32_e32 v213, v211, v212
	v_max_u32_e32 v219, v215, v218
	v_min_u32_e32 v12, v4, v9
	v_max_u32_e32 v203, v200, v201
	v_min_u32_e32 v13, v204, v11
	v_max_u32_e32 v209, v6, v7
	v_min_u32_e32 v8, v10, v5
	v_min_u32_e32 v202, v202, v205
	v_max_u32_e32 v205, v211, v212
	v_min_u32_e32 v212, v215, v218
	v_max_u32_e32 v215, v4, v9
	v_min_u32_e32 v200, v200, v201
	v_max_u32_e32 v201, v204, v11
	v_min_u32_e32 v204, v6, v7
	v_max_u32_e32 v217, v10, v5
	v_min_u32_e32 v214, v206, v213
	v_min_u32_e32 v15, v219, v12
	v_min_u32_e32 v207, v203, v13
	v_min_u32_e32 v14, v209, v8
	v_min_u32_e32 v211, v202, v205
	v_min_u32_e32 v4, v212, v215
	v_min_u32_e32 v11, v200, v201
	v_min_u32_e32 v5, v204, v217
	v_min_u32_e32 v208, v214, v15
	v_min_u32_e32 v210, v207, v14
	v_min_u32_e32 v9, v211, v4
	v_min_u32_e32 v6, v11, v5
	v_min_u32_e32 v216, v208, v210
	v_min_u32_e32 v218, v9, v6
	v_max_u32_e32 v208, v208, v210
	v_max_u32_e32 v210, v9, v6
	v_max_u32_e32 v6, v214, v15
	v_max_u32_e32 v7, v207, v14
	v_max_u32_e32 v4, v211, v4
	v_max_u32_e32 v5, v11, v5
	v_min_u32_e32 v207, v6, v7
	v_min_u32_e32 v211, v4, v5
	v_max_u32_e32 v222, v6, v7
	v_max_u32_e32 v223, v4, v5
	v_max_u32_e32 v206, v206, v213
	v_max_u32_e32 v213, v219, v12
	v_max_u32_e32 v203, v203, v13
	v_max_u32_e32 v209, v209, v8
	s_waitcnt vmcnt(3)
	v_mfma_f32_32x32x16_bf16 v[0:15], v[0:3], v[24:27], 0
	v_max_u32_e32 v202, v202, v205
	v_max_u32_e32 v205, v212, v215
	v_min_u32_e32 v225, v203, v209
	v_min_u32_e32 v212, v202, v205
	v_max_u32_e32 v200, v200, v201
	v_max_u32_e32 v201, v204, v217
	v_min_u32_e32 v204, v200, v201
	s_waitcnt vmcnt(2)
	v_mfma_f32_32x32x16_bf16 v[0:15], v[88:91], v[20:23], v[0:15]
	v_max_u32_e32 v88, v206, v213
	v_max_u32_e32 v89, v203, v209
	v_min_u32_e32 v203, v88, v89
	v_max_u32_e32 v90, v202, v205
	v_max_u32_e32 v202, v88, v89
	v_max_u32_e32 v91, v200, v201
	v_min_u32_e32 v200, v90, v91
	s_waitcnt vmcnt(1)
	v_mfma_f32_32x32x16_bf16 v[0:15], v[92:95], v[28:31], v[0:15]
	v_max_u32_e32 v205, v90, v91
	v_min_u32_e32 v219, v206, v213
	v_min_u32_e32 v226, v219, v225
	v_max_u32_e32 v219, v219, v225
	v_min_u32_e32 v215, v212, v204
	v_max_u32_e32 v204, v212, v204
	v_min_u32_e32 v221, v208, v210
	s_waitcnt vmcnt(0)
	v_mfma_f32_32x32x16_bf16 v[0:15], v[96:99], v[16:19], v[0:15]
	v_min_u32_e32 v214, v207, v211
	v_min_u32_e32 v224, v222, v223
	v_min_u32_e32 v212, v219, v204
	v_min_u32_e32 v201, v203, v200
	v_min_u32_e32 v206, v202, v205
	v_min_u32_e32 v220, v216, v218
	v_min_u32_e32 v217, v226, v215
	s_nop 4
	v_not_b32_e32 v88, v0
	v_or_b32_e32 v89, 0x80000000, v0
	v_cmp_gt_i32_e32 vcc, 0, v0
	v_or_b32_e32 v90, 0x80000000, v3
	v_not_b32_e32 v91, v7
	v_cndmask_b32_e32 v0, v89, v88, vcc
	v_not_b32_e32 v88, v1
	v_or_b32_e32 v89, 0x80000000, v1
	v_cmp_gt_i32_e32 vcc, 0, v1
	v_or_b32_e32 v92, 0x80000000, v7
	v_or_b32_e32 v93, 0x80000000, v4
	v_cndmask_b32_e32 v1, v89, v88, vcc
	v_not_b32_e32 v89, v3
	v_cmp_gt_i32_e32 vcc, 0, v3
	v_not_b32_e32 v95, v15
	v_or_b32_e32 v96, 0x80000000, v15
	v_cndmask_b32_e32 v3, v90, v89, vcc
	v_not_b32_e32 v89, v2
	v_or_b32_e32 v90, 0x80000000, v2
	v_cmp_gt_i32_e32 vcc, 0, v2
	v_or_b32_e32 v97, 0x80000000, v12
	v_not_b32_e32 v98, v8
	v_cndmask_b32_e32 v2, v90, v89, vcc
	v_cmp_gt_i32_e32 vcc, 0, v7
	v_or_b32_e32 v99, 0x80000000, v8
	v_or_b32_e32 v209, 0x80000000, v11
	v_cndmask_b32_e32 v7, v92, v91, vcc
	v_not_b32_e32 v91, v6
	v_or_b32_e32 v92, 0x80000000, v6
	v_cmp_gt_i32_e32 vcc, 0, v6
	v_and_or_b32 v0, v0, s96, v118
	v_and_or_b32 v1, v1, s96, v119
	v_cndmask_b32_e32 v6, v92, v91, vcc
	v_not_b32_e32 v92, v4
	v_cmp_gt_i32_e32 vcc, 0, v4
	v_and_or_b32 v3, v3, s96, v121
	v_and_or_b32 v2, v2, s96, v120
	v_cndmask_b32_e32 v4, v93, v92, vcc
	v_not_b32_e32 v92, v5
	v_or_b32_e32 v93, 0x80000000, v5
	v_cmp_gt_i32_e32 vcc, 0, v5
	v_and_or_b32 v7, v7, s96, v125
	v_and_or_b32 v6, v6, s96, v124
	v_cndmask_b32_e32 v5, v93, v92, vcc
	v_cmp_gt_i32_e32 vcc, 0, v15
	v_and_or_b32 v4, v4, s96, v122
	v_and_or_b32 v5, v5, s96, v123
	v_cndmask_b32_e32 v15, v96, v95, vcc
	v_not_b32_e32 v95, v14
	v_or_b32_e32 v96, 0x80000000, v14
	v_cmp_gt_i32_e32 vcc, 0, v14
	v_and_or_b32 v15, v15, s96, v133
	v_max_u32_e32 v88, v0, v1
	v_cndmask_b32_e32 v14, v96, v95, vcc
	v_not_b32_e32 v96, v12
	v_cmp_gt_i32_e32 vcc, 0, v12
	v_and_or_b32 v14, v14, s96, v132
	v_min_u32_e32 v89, v3, v2
	v_cndmask_b32_e32 v12, v97, v96, vcc
	v_not_b32_e32 v96, v13
	v_or_b32_e32 v97, 0x80000000, v13
	v_cmp_gt_i32_e32 vcc, 0, v13
	v_and_or_b32 v12, v12, s96, v130
	v_min_u32_e32 v0, v0, v1
	v_cndmask_b32_e32 v13, v97, v96, vcc
	v_cmp_gt_i32_e32 vcc, 0, v8
	v_and_or_b32 v13, v13, s96, v131
	v_max_u32_e32 v1, v3, v2
	v_cndmask_b32_e32 v8, v99, v98, vcc
	v_not_b32_e32 v98, v9
	v_or_b32_e32 v99, 0x80000000, v9
	v_cmp_gt_i32_e32 vcc, 0, v9
	v_and_or_b32 v8, v8, s96, v126
	v_max_u32_e32 v91, v7, v6
	v_cndmask_b32_e32 v9, v99, v98, vcc
	v_not_b32_e32 v99, v11
	v_cmp_gt_i32_e32 vcc, 0, v11
	v_and_or_b32 v9, v9, s96, v127
	v_min_u32_e32 v92, v4, v5
	v_cndmask_b32_e32 v11, v209, v99, vcc
	v_not_b32_e32 v99, v10
	v_or_b32_e32 v209, 0x80000000, v10
	v_cmp_gt_i32_e32 vcc, 0, v10
	v_and_or_b32 v11, v11, s96, v129
	v_min_u32_e32 v6, v7, v6
	v_cndmask_b32_e32 v10, v209, v99, vcc
	v_and_or_b32 v10, v10, s96, v128
	v_max_u32_e32 v4, v4, v5
	v_max_u32_e32 v95, v15, v14
	v_min_u32_e32 v96, v12, v13
	v_min_u32_e32 v14, v15, v14
	v_max_u32_e32 v12, v12, v13
	v_max_u32_e32 v98, v8, v9
	v_min_u32_e32 v99, v11, v10
	v_min_u32_e32 v8, v8, v9
	v_max_u32_e32 v9, v11, v10
	v_max_u32_e32 v90, v88, v89
	v_max_u32_e32 v2, v0, v1
	v_min_u32_e32 v93, v91, v92
	v_min_u32_e32 v5, v6, v4
	v_min_u32_e32 v88, v88, v89
	v_min_u32_e32 v0, v0, v1
	v_max_u32_e32 v89, v91, v92
	v_max_u32_e32 v4, v6, v4
	v_max_u32_e32 v97, v95, v96
	v_max_u32_e32 v13, v14, v12
	v_min_u32_e32 v209, v98, v99
	v_min_u32_e32 v10, v8, v9
	v_min_u32_e32 v95, v95, v96
	v_min_u32_e32 v12, v14, v12
	v_max_u32_e32 v96, v98, v99
	v_max_u32_e32 v8, v8, v9
	v_max_u32_e32 v3, v90, v2
	v_min_u32_e32 v7, v93, v5
	v_max_u32_e32 v1, v88, v0
	v_min_u32_e32 v6, v89, v4
	v_min_u32_e32 v2, v90, v2
	v_max_u32_e32 v5, v93, v5
	v_min_u32_e32 v0, v88, v0
	v_max_u32_e32 v4, v89, v4
	v_max_u32_e32 v15, v97, v13
	v_min_u32_e32 v11, v209, v10
	v_max_u32_e32 v14, v95, v12
	v_min_u32_e32 v9, v96, v8
	v_min_u32_e32 v13, v97, v13
	v_max_u32_e32 v10, v209, v10
	v_min_u32_e32 v12, v95, v12
	v_max_u32_e32 v8, v96, v8
	v_max_u32_e32 v94, v3, v7
	v_max_u32_e32 v91, v1, v6
	v_max_u32_e32 v90, v2, v5
	v_max_u32_e32 v88, v0, v4
	v_min_u32_e32 v213, v15, v11
	v_min_u32_e32 v98, v14, v9
	v_min_u32_e32 v97, v13, v10
	v_min_u32_e32 v95, v12, v8
	v_min_u32_e32 v3, v3, v7
	v_min_u32_e32 v1, v1, v6
	v_min_u32_e32 v2, v2, v5
	v_min_u32_e32 v0, v0, v4
	v_max_u32_e32 v5, v15, v11
	v_max_u32_e32 v9, v14, v9
	v_max_u32_e32 v10, v13, v10
	v_max_u32_e32 v8, v12, v8
	v_max_u32_e32 v92, v94, v91
	v_max_u32_e32 v89, v90, v88
	v_min_u32_e32 v99, v213, v98
	v_min_u32_e32 v96, v97, v95
	v_max_u32_e32 v6, v3, v1
	v_max_u32_e32 v4, v2, v0
	v_min_u32_e32 v11, v5, v9
	v_min_u32_e32 v12, v10, v8
	v_min_u32_e32 v91, v94, v91
	v_min_u32_e32 v88, v90, v88
	v_max_u32_e32 v94, v213, v98
	v_max_u32_e32 v95, v97, v95
	v_min_u32_e32 v1, v3, v1
	v_min_u32_e32 v0, v2, v0
	v_max_u32_e32 v2, v5, v9
	v_max_u32_e32 v3, v10, v8
	v_max_u32_e32 v93, v92, v89
	v_min_u32_e32 v209, v99, v96
	v_max_u32_e32 v7, v6, v4
	v_min_u32_e32 v13, v11, v12
	v_min_u32_e32 v97, v94, v95
	v_min_u32_e32 v92, v92, v89
	v_max_u32_e32 v96, v99, v96
	v_min_u32_e32 v6, v6, v4
	v_max_u32_e32 v11, v11, v12
	v_min_u32_e32 v99, v91, v88
	v_max_u32_e32 v94, v94, v95
	v_min_u32_e32 v95, v1, v0
	v_max_u32_e32 v227, v2, v3
	v_max_u32_e32 v90, v91, v88
	v_max_u32_e32 v213, v1, v0
	v_min_u32_e32 v8, v2, v3
	v_min_u32_e32 v89, v92, v96
	v_min_u32_e32 v4, v6, v11
	v_min_u32_e32 v88, v99, v94
	v_min_u32_e32 v0, v95, v227
	v_min_u32_e32 v225, v93, v209
	v_min_u32_e32 v14, v7, v13
	v_min_u32_e32 v98, v90, v97
	v_min_u32_e32 v5, v213, v8
	v_min_u32_e32 v12, v89, v4
	v_min_u32_e32 v1, v88, v0
	v_min_u32_e32 v9, v98, v5
	v_min_u32_e32 v228, v12, v1
	v_max_u32_e32 v12, v12, v1
	v_max_u32_e32 v1, v225, v14
	v_max_u32_e32 v2, v98, v5
	v_max_u32_e32 v3, v89, v4
	v_max_u32_e32 v0, v88, v0
	v_lshl_add_u64 v[4:5], v[34:35], 0, v[78:79]
	v_min_u32_e32 v15, v225, v14
	v_min_u32_e32 v14, v1, v2
	v_min_u32_e32 v225, v3, v0
	v_max_u32_e32 v231, v1, v2
	v_max_u32_e32 v232, v3, v0
	global_load_dwordx4 v[0:3], v[4:5], off
	v_max_u32_e32 v97, v90, v97
	global_load_dwordx4 v[88:91], v[4:5], off offset:32
	v_max_u32_e32 v98, v93, v209
	v_max_u32_e32 v234, v92, v96
	v_max_u32_e32 v235, v99, v94
	v_max_u32_e32 v227, v95, v227
	global_load_dwordx4 v[92:95], v[4:5], off offset:64
	v_max_u32_e32 v6, v6, v11
	v_max_u32_e32 v7, v7, v13
	v_max_u32_e32 v8, v213, v8
	v_min_u32_e32 v11, v234, v6
	v_min_u32_e32 v96, v235, v227
	v_min_u32_e32 v13, v98, v7
	v_min_u32_e32 v209, v97, v8
	v_min_u32_e32 v236, v11, v96
	v_max_u32_e32 v11, v11, v96
	v_max_u32_e32 v7, v98, v7
	v_max_u32_e32 v8, v97, v8
	global_load_dwordx4 v[96:99], v[4:5], off offset:96
	v_max_u32_e32 v5, v234, v6
	v_max_u32_e32 v6, v235, v227
	v_min_u32_e32 v10, v15, v9
	v_max_u32_e32 v9, v15, v9
	v_min_u32_e32 v213, v13, v209
	v_max_u32_e32 v13, v13, v209
	v_min_u32_e32 v4, v7, v8
	v_min_u32_e32 v227, v5, v6
	v_max_u32_e32 v7, v7, v8
	v_max_u32_e32 v5, v5, v6
	v_min_u32_e32 v229, v10, v228
	v_min_u32_e32 v15, v9, v12
	v_min_u32_e32 v230, v14, v225
	v_min_u32_e32 v233, v231, v232
	v_min_u32_e32 v237, v213, v236
	v_min_u32_e32 v209, v13, v11
	v_min_u32_e32 v234, v4, v227
	v_min_u32_e32 v6, v7, v5
	v_max3_u32 v8, v202, v205, v229
	v_max3_u32 v10, v206, v10, v228
	v_max3_u32 v15, v203, v200, v15
	v_max3_u32 v9, v201, v9, v12
	v_max3_u32 v12, v219, v204, v230
	v_max3_u32 v14, v212, v14, v225
	v_max3_u32 v200, v226, v215, v233
	v_max3_u32 v202, v222, v223, v237
	v_max3_u32 v203, v224, v213, v236
	v_max3_u32 v204, v207, v211, v209
	v_max3_u32 v11, v214, v13, v11
	v_max3_u32 v13, v208, v210, v234
	v_max3_u32 v4, v221, v4, v227
	v_max3_u32 v6, v216, v218, v6
	v_max3_u32 v201, v217, v231, v232
	v_max3_u32 v5, v220, v7, v5
	v_max_u32_e32 v7, v8, v202
	v_min_u32_e32 v8, v8, v202
	v_max_u32_e32 v202, v10, v203
	v_min_u32_e32 v10, v10, v203
	v_max_u32_e32 v203, v15, v204
	v_min_u32_e32 v15, v15, v204
	v_max_u32_e32 v204, v9, v11
	v_min_u32_e32 v9, v9, v11
	v_max_u32_e32 v11, v12, v13
	v_min_u32_e32 v12, v12, v13
	v_max_u32_e32 v13, v14, v4
	v_min_u32_e32 v4, v14, v4
	v_max_u32_e32 v14, v200, v6
	v_min_u32_e32 v6, v200, v6
	v_max_u32_e32 v200, v201, v5
	v_min_u32_e32 v5, v201, v5
	v_max_u32_e32 v201, v7, v11
	v_min_u32_e32 v205, v7, v11
	v_max_u32_e32 v7, v203, v14
	v_max_u32_e32 v206, v202, v13
	v_min_u32_e32 v202, v202, v13
	v_min_u32_e32 v203, v203, v14
	v_max_u32_e32 v207, v204, v200
	v_min_u32_e32 v200, v204, v200
	v_max_u32_e32 v204, v8, v12
	v_min_u32_e32 v208, v8, v12
	v_max_u32_e32 v209, v10, v4
	v_min_u32_e32 v210, v10, v4
	v_max_u32_e32 v211, v15, v6
	v_min_u32_e32 v212, v15, v6
	v_max_u32_e32 v213, v9, v5
	v_min_u32_e32 v214, v9, v5
	v_max_u32_e32 v215, v201, v7
	v_min_u32_e32 v201, v201, v7
	s_waitcnt vmcnt(3)
	v_mfma_f32_32x32x16_bf16 v[0:15], v[0:3], v[24:27], 0
	v_max_u32_e32 v216, v206, v207
	v_min_u32_e32 v206, v206, v207
	v_max_u32_e32 v207, v205, v203
	v_min_u32_e32 v203, v205, v203
	v_max_u32_e32 v205, v202, v200
	v_min_u32_e32 v200, v202, v200
	v_max_u32_e32 v202, v204, v211
	s_waitcnt vmcnt(2)
	v_mfma_f32_32x32x16_bf16 v[0:15], v[88:91], v[20:23], v[0:15]
	v_min_u32_e32 v204, v204, v211
	v_max_u32_e32 v211, v209, v213
	v_min_u32_e32 v209, v209, v213
	v_max_u32_e32 v213, v208, v212
	v_min_u32_e32 v208, v208, v212
	v_max_u32_e32 v212, v210, v214
	v_min_u32_e32 v210, v210, v214
	s_waitcnt vmcnt(1)
	v_mfma_f32_32x32x16_bf16 v[0:15], v[92:95], v[28:31], v[0:15]
	v_min_u32_e32 v214, v215, v216
	v_min_u32_e32 v217, v201, v206
	v_min_u32_e32 v218, v207, v205
	v_min_u32_e32 v220, v202, v211
	v_min_u32_e32 v221, v204, v209
	v_min_u32_e32 v222, v213, v212
	v_min_u32_e32 v219, v203, v200
	s_waitcnt vmcnt(0)
	v_mfma_f32_32x32x16_bf16 v[0:15], v[96:99], v[16:19], v[0:15]
	v_min_u32_e32 v223, v208, v210
	v_max_u32_e32 v44, v44, v50
	v_max_u32_e32 v39, v39, v53
	v_max_u32_e32 v36, v36, v47
	v_max_u32_e32 v47, v39, v36
	v_min_u32_e32 v36, v39, v36
	s_nop 5
	v_not_b32_e32 v88, v0
	v_or_b32_e32 v89, 0x80000000, v0
	v_cmp_gt_i32_e32 vcc, 0, v0
	v_or_b32_e32 v90, 0x80000000, v3
	v_not_b32_e32 v91, v7
	v_cndmask_b32_e32 v0, v89, v88, vcc
	v_not_b32_e32 v88, v1
	v_or_b32_e32 v89, 0x80000000, v1
	v_cmp_gt_i32_e32 vcc, 0, v1
	v_or_b32_e32 v92, 0x80000000, v7
	v_or_b32_e32 v93, 0x80000000, v4
	v_cndmask_b32_e32 v1, v89, v88, vcc
	v_not_b32_e32 v89, v3
	v_cmp_gt_i32_e32 vcc, 0, v3
	v_not_b32_e32 v95, v15
	v_or_b32_e32 v96, 0x80000000, v15
	v_cndmask_b32_e32 v3, v90, v89, vcc
	v_not_b32_e32 v89, v2
	v_or_b32_e32 v90, 0x80000000, v2
	v_cmp_gt_i32_e32 vcc, 0, v2
	v_or_b32_e32 v97, 0x80000000, v12
	v_not_b32_e32 v98, v8
	v_cndmask_b32_e32 v2, v90, v89, vcc
	v_cmp_gt_i32_e32 vcc, 0, v7
	v_or_b32_e32 v99, 0x80000000, v8
	v_or_b32_e32 v224, 0x80000000, v11
	v_cndmask_b32_e32 v7, v92, v91, vcc
	v_not_b32_e32 v91, v6
	v_or_b32_e32 v92, 0x80000000, v6
	v_cmp_gt_i32_e32 vcc, 0, v6
	v_and_or_b32 v0, v0, s96, v134
	v_and_or_b32 v1, v1, s96, v135
	v_cndmask_b32_e32 v6, v92, v91, vcc
	v_not_b32_e32 v92, v4
	v_cmp_gt_i32_e32 vcc, 0, v4
	v_and_or_b32 v3, v3, s96, v137
	v_and_or_b32 v2, v2, s96, v136
	v_cndmask_b32_e32 v4, v93, v92, vcc
	v_not_b32_e32 v92, v5
	v_or_b32_e32 v93, 0x80000000, v5
	v_cmp_gt_i32_e32 vcc, 0, v5
	v_and_or_b32 v7, v7, s96, v141
	v_and_or_b32 v6, v6, s96, v140
	v_cndmask_b32_e32 v5, v93, v92, vcc
	v_cmp_gt_i32_e32 vcc, 0, v15
	v_and_or_b32 v4, v4, s96, v138
	v_and_or_b32 v5, v5, s96, v139
	v_cndmask_b32_e32 v15, v96, v95, vcc
	v_not_b32_e32 v95, v14
	v_or_b32_e32 v96, 0x80000000, v14
	v_cmp_gt_i32_e32 vcc, 0, v14
	v_and_or_b32 v15, v15, s96, v149
	v_max_u32_e32 v88, v0, v1
	v_cndmask_b32_e32 v14, v96, v95, vcc
	v_not_b32_e32 v96, v12
	v_cmp_gt_i32_e32 vcc, 0, v12
	v_and_or_b32 v14, v14, s96, v148
	v_min_u32_e32 v89, v3, v2
	v_cndmask_b32_e32 v12, v97, v96, vcc
	v_not_b32_e32 v96, v13
	v_or_b32_e32 v97, 0x80000000, v13
	v_cmp_gt_i32_e32 vcc, 0, v13
	v_and_or_b32 v12, v12, s96, v146
	v_min_u32_e32 v0, v0, v1
	v_cndmask_b32_e32 v13, v97, v96, vcc
	v_cmp_gt_i32_e32 vcc, 0, v8
	v_and_or_b32 v13, v13, s96, v147
	v_max_u32_e32 v1, v3, v2
	v_cndmask_b32_e32 v8, v99, v98, vcc
	v_not_b32_e32 v98, v9
	v_or_b32_e32 v99, 0x80000000, v9
	v_cmp_gt_i32_e32 vcc, 0, v9
	v_and_or_b32 v8, v8, s96, v142
	v_max_u32_e32 v91, v7, v6
	v_cndmask_b32_e32 v9, v99, v98, vcc
	v_not_b32_e32 v99, v11
	v_cmp_gt_i32_e32 vcc, 0, v11
	v_and_or_b32 v9, v9, s96, v143
	v_min_u32_e32 v92, v4, v5
	v_cndmask_b32_e32 v11, v224, v99, vcc
	v_not_b32_e32 v99, v10
	v_or_b32_e32 v224, 0x80000000, v10
	v_cmp_gt_i32_e32 vcc, 0, v10
	v_and_or_b32 v11, v11, s96, v145
	v_min_u32_e32 v6, v7, v6
	v_cndmask_b32_e32 v10, v224, v99, vcc
	v_and_or_b32 v10, v10, s96, v144
	v_max_u32_e32 v4, v4, v5
	v_max_u32_e32 v95, v15, v14
	v_min_u32_e32 v96, v12, v13
	v_min_u32_e32 v14, v15, v14
	v_max_u32_e32 v12, v12, v13
	v_max_u32_e32 v98, v8, v9
	v_min_u32_e32 v99, v11, v10
	v_min_u32_e32 v8, v8, v9
	v_max_u32_e32 v9, v11, v10
	v_max_u32_e32 v90, v88, v89
	v_max_u32_e32 v2, v0, v1
	v_min_u32_e32 v93, v91, v92
	v_min_u32_e32 v5, v6, v4
	v_min_u32_e32 v88, v88, v89
	v_min_u32_e32 v0, v0, v1
	v_max_u32_e32 v89, v91, v92
	v_max_u32_e32 v4, v6, v4
	v_max_u32_e32 v97, v95, v96
	v_max_u32_e32 v13, v14, v12
	v_min_u32_e32 v224, v98, v99
	v_min_u32_e32 v10, v8, v9
	v_min_u32_e32 v95, v95, v96
	v_min_u32_e32 v12, v14, v12
	v_max_u32_e32 v96, v98, v99
	v_max_u32_e32 v8, v8, v9
	v_max_u32_e32 v3, v90, v2
	v_min_u32_e32 v7, v93, v5
	v_max_u32_e32 v1, v88, v0
	v_min_u32_e32 v6, v89, v4
	v_min_u32_e32 v2, v90, v2
	v_max_u32_e32 v5, v93, v5
	v_min_u32_e32 v0, v88, v0
	v_max_u32_e32 v4, v89, v4
	v_max_u32_e32 v15, v97, v13
	v_min_u32_e32 v11, v224, v10
	v_max_u32_e32 v14, v95, v12
	v_min_u32_e32 v9, v96, v8
	v_min_u32_e32 v13, v97, v13
	v_max_u32_e32 v10, v224, v10
	v_min_u32_e32 v12, v95, v12
	v_max_u32_e32 v8, v96, v8
	v_max_u32_e32 v94, v3, v7
	v_max_u32_e32 v91, v1, v6
	v_max_u32_e32 v90, v2, v5
	v_max_u32_e32 v88, v0, v4
	v_min_u32_e32 v225, v15, v11
	v_min_u32_e32 v98, v14, v9
	v_min_u32_e32 v97, v13, v10
	v_min_u32_e32 v95, v12, v8
	v_min_u32_e32 v3, v3, v7
	v_min_u32_e32 v1, v1, v6
	v_min_u32_e32 v2, v2, v5
	v_min_u32_e32 v0, v0, v4
	v_max_u32_e32 v5, v15, v11
	v_max_u32_e32 v9, v14, v9
	v_max_u32_e32 v10, v13, v10
	v_max_u32_e32 v8, v12, v8
	v_max_u32_e32 v92, v94, v91
	v_max_u32_e32 v89, v90, v88
	v_min_u32_e32 v99, v225, v98
	v_min_u32_e32 v96, v97, v95
	v_max_u32_e32 v6, v3, v1
	v_max_u32_e32 v4, v2, v0
	v_min_u32_e32 v11, v5, v9
	v_min_u32_e32 v12, v10, v8
	v_min_u32_e32 v91, v94, v91
	v_min_u32_e32 v88, v90, v88
	v_max_u32_e32 v94, v225, v98
	v_max_u32_e32 v95, v97, v95
	v_min_u32_e32 v1, v3, v1
	v_min_u32_e32 v0, v2, v0
	v_max_u32_e32 v2, v5, v9
	v_max_u32_e32 v3, v10, v8
	v_max_u32_e32 v93, v92, v89
	v_min_u32_e32 v224, v99, v96
	v_max_u32_e32 v7, v6, v4
	v_min_u32_e32 v13, v11, v12
	v_min_u32_e32 v97, v94, v95
	v_min_u32_e32 v92, v92, v89
	v_max_u32_e32 v96, v99, v96
	v_min_u32_e32 v6, v6, v4
	v_max_u32_e32 v11, v11, v12
	v_min_u32_e32 v99, v91, v88
	v_max_u32_e32 v94, v94, v95
	v_min_u32_e32 v95, v1, v0
	v_max_u32_e32 v227, v2, v3
	v_max_u32_e32 v90, v91, v88
	v_max_u32_e32 v225, v1, v0
	v_min_u32_e32 v8, v2, v3
	v_min_u32_e32 v89, v92, v96
	v_min_u32_e32 v4, v6, v11
	v_min_u32_e32 v88, v99, v94
	v_min_u32_e32 v0, v95, v227
	v_min_u32_e32 v226, v93, v224
	v_min_u32_e32 v14, v7, v13
	v_min_u32_e32 v98, v90, v97
	v_min_u32_e32 v5, v225, v8
	v_min_u32_e32 v12, v89, v4
	v_min_u32_e32 v1, v88, v0
	v_min_u32_e32 v9, v98, v5
	v_min_u32_e32 v228, v12, v1
	v_max_u32_e32 v12, v12, v1
	v_max_u32_e32 v1, v226, v14
	v_max_u32_e32 v2, v98, v5
	v_max_u32_e32 v3, v89, v4
	v_max_u32_e32 v0, v88, v0
	v_lshl_add_u64 v[4:5], v[34:35], 0, v[80:81]
	v_min_u32_e32 v15, v226, v14
	v_min_u32_e32 v14, v1, v2
	v_min_u32_e32 v226, v3, v0
	v_max_u32_e32 v231, v1, v2
	v_max_u32_e32 v232, v3, v0
	global_load_dwordx4 v[0:3], v[4:5], off
	v_max_u32_e32 v97, v90, v97
	global_load_dwordx4 v[88:91], v[4:5], off offset:32
	v_max_u32_e32 v35, v93, v224
	v_max_u32_e32 v8, v225, v8
	v_max_u32_e32 v225, v92, v96
	v_max_u32_e32 v233, v99, v94
	v_max_u32_e32 v227, v95, v227
	global_load_dwordx4 v[92:95], v[4:5], off offset:64
	v_max_u32_e32 v7, v7, v13
	v_max_u32_e32 v6, v6, v11
	v_min_u32_e32 v13, v35, v7
	v_min_u32_e32 v98, v97, v8
	v_min_u32_e32 v11, v225, v6
	v_min_u32_e32 v96, v233, v227
	v_min_u32_e32 v224, v13, v98
	v_min_u32_e32 v234, v11, v96
	v_max_u32_e32 v13, v13, v98
	v_max_u32_e32 v11, v11, v96
	v_max_u32_e32 v8, v97, v8
	global_load_dwordx4 v[96:99], v[4:5], off offset:96
	v_max_u32_e32 v7, v35, v7
	v_max_u32_e32 v5, v225, v6
	v_max_u32_e32 v6, v233, v227
	v_min_u32_e32 v10, v15, v9
	v_max_u32_e32 v9, v15, v9
	v_min_u32_e32 v4, v7, v8
	v_min_u32_e32 v35, v5, v6
	v_max_u32_e32 v7, v7, v8
	v_max_u32_e32 v5, v5, v6
	v_min_u32_e32 v229, v10, v228
	v_min_u32_e32 v15, v9, v12
	v_min_u32_e32 v230, v14, v226
	v_min_u32_e32 v34, v231, v232
	v_min_u32_e32 v235, v224, v234
	v_min_u32_e32 v236, v13, v11
	v_min_u32_e32 v225, v4, v35
	v_min_u32_e32 v6, v7, v5
	v_max3_u32 v8, v215, v216, v229
	v_max3_u32 v10, v214, v10, v228
	v_max3_u32 v15, v201, v206, v15
	v_max3_u32 v9, v217, v9, v12
	v_max3_u32 v12, v207, v205, v230
	v_max3_u32 v14, v218, v14, v226
	v_max3_u32 v34, v203, v200, v34
	v_max3_u32 v201, v202, v211, v235
	v_max3_u32 v202, v220, v224, v234
	v_max3_u32 v203, v204, v209, v236
	v_max3_u32 v11, v221, v13, v11
	v_max3_u32 v13, v213, v212, v225
	v_max3_u32 v4, v222, v4, v35
	v_max3_u32 v6, v208, v210, v6
	v_max3_u32 v200, v219, v231, v232
	v_max3_u32 v5, v223, v7, v5
	v_max_u32_e32 v7, v8, v201
	v_min_u32_e32 v8, v8, v201
	v_max_u32_e32 v35, v10, v202
	v_min_u32_e32 v10, v10, v202
	v_max_u32_e32 v201, v15, v203
	v_max_u32_e32 v202, v9, v11
	v_min_u32_e32 v9, v9, v11
	v_max_u32_e32 v11, v12, v13
	v_min_u32_e32 v12, v12, v13
	v_max_u32_e32 v13, v14, v4
	v_min_u32_e32 v4, v14, v4
	v_max_u32_e32 v14, v34, v6
	v_min_u32_e32 v15, v15, v203
	v_min_u32_e32 v6, v34, v6
	v_max_u32_e32 v34, v200, v5
	v_min_u32_e32 v5, v200, v5
	v_max_u32_e32 v200, v7, v11
	v_min_u32_e32 v203, v7, v11
	v_max_u32_e32 v7, v201, v14
	v_max_u32_e32 v204, v35, v13
	v_min_u32_e32 v35, v35, v13
	v_min_u32_e32 v201, v201, v14
	v_max_u32_e32 v205, v202, v34
	v_min_u32_e32 v34, v202, v34
	v_max_u32_e32 v202, v8, v12
	v_min_u32_e32 v206, v8, v12
	v_max_u32_e32 v207, v10, v4
	v_min_u32_e32 v208, v10, v4
	v_max_u32_e32 v209, v15, v6
	v_min_u32_e32 v210, v15, v6
	v_max_u32_e32 v211, v9, v5
	v_min_u32_e32 v212, v9, v5
	v_max_u32_e32 v213, v200, v7
	v_min_u32_e32 v200, v200, v7
	s_waitcnt vmcnt(3)
	v_mfma_f32_32x32x16_bf16 v[0:15], v[0:3], v[24:27], 0
	v_max_u32_e32 v25, v203, v201
	v_min_u32_e32 v26, v203, v201
	v_max_u32_e32 v27, v35, v34
	v_min_u32_e32 v34, v35, v34
	v_max_u32_e32 v35, v202, v209
	v_min_u32_e32 v201, v202, v209
	v_max_u32_e32 v214, v204, v205
	s_waitcnt vmcnt(2)
	v_mfma_f32_32x32x16_bf16 v[0:15], v[88:91], v[20:23], v[0:15]
	v_min_u32_e32 v24, v204, v205
	v_max_u32_e32 v22, v206, v210
	v_min_u32_e32 v23, v206, v210
	v_max_u32_e32 v20, v207, v211
	v_min_u32_e32 v21, v207, v211
	v_max_u32_e32 v88, v208, v212
	v_min_u32_e32 v89, v208, v212
	s_waitcnt vmcnt(1)
	v_mfma_f32_32x32x16_bf16 v[0:15], v[92:95], v[28:31], v[0:15]
	v_min_u32_e32 v31, v35, v20
	v_min_u32_e32 v90, v213, v214
	v_min_u32_e32 v28, v200, v24
	v_min_u32_e32 v29, v25, v27
	v_min_u32_e32 v30, v26, v34
	v_min_u32_e32 v91, v201, v21
	v_min_u32_e32 v92, v22, v88
	s_waitcnt vmcnt(0)
	v_mfma_f32_32x32x16_bf16 v[0:15], v[96:99], v[16:19], v[0:15]
	v_min_u32_e32 v93, v23, v89
	s_nop 10
	v_not_b32_e32 v16, v0
	v_or_b32_e32 v17, 0x80000000, v0
	v_cmp_gt_i32_e32 vcc, 0, v0
	v_or_b32_e32 v18, 0x80000000, v3
	v_not_b32_e32 v19, v7
	v_cndmask_b32_e32 v0, v17, v16, vcc
	v_not_b32_e32 v16, v1
	v_or_b32_e32 v17, 0x80000000, v1
	v_cmp_gt_i32_e32 vcc, 0, v1
	v_or_b32_e32 v94, 0x80000000, v7
	v_or_b32_e32 v95, 0x80000000, v4
	v_cndmask_b32_e32 v1, v17, v16, vcc
	v_not_b32_e32 v17, v3
	v_cmp_gt_i32_e32 vcc, 0, v3
	v_not_b32_e32 v97, v15
	v_or_b32_e32 v98, 0x80000000, v15
	v_cndmask_b32_e32 v3, v18, v17, vcc
	v_not_b32_e32 v17, v2
	v_or_b32_e32 v18, 0x80000000, v2
	v_cmp_gt_i32_e32 vcc, 0, v2
	v_or_b32_e32 v99, 0x80000000, v12
	v_not_b32_e32 v202, v8
	v_cndmask_b32_e32 v2, v18, v17, vcc
	v_cmp_gt_i32_e32 vcc, 0, v7
	v_or_b32_e32 v203, 0x80000000, v8
	v_or_b32_e32 v204, 0x80000000, v11
	v_cndmask_b32_e32 v7, v94, v19, vcc
	v_not_b32_e32 v19, v6
	v_or_b32_e32 v94, 0x80000000, v6
	v_cmp_gt_i32_e32 vcc, 0, v6
	v_and_or_b32 v0, v0, s96, v150
	v_and_or_b32 v1, v1, s96, v151
	v_cndmask_b32_e32 v6, v94, v19, vcc
	v_not_b32_e32 v94, v4
	v_cmp_gt_i32_e32 vcc, 0, v4
	v_and_or_b32 v3, v3, s96, v153
	v_and_or_b32 v2, v2, s96, v152
	v_cndmask_b32_e32 v4, v95, v94, vcc
	v_not_b32_e32 v94, v5
	v_or_b32_e32 v95, 0x80000000, v5
	v_cmp_gt_i32_e32 vcc, 0, v5
	v_and_or_b32 v7, v7, s96, v158
	v_and_or_b32 v6, v6, s96, v157
	v_cndmask_b32_e32 v5, v95, v94, vcc
	v_cmp_gt_i32_e32 vcc, 0, v15
	v_and_or_b32 v4, v4, s96, v155
	v_and_or_b32 v5, v5, s96, v156
	v_cndmask_b32_e32 v15, v98, v97, vcc
	v_not_b32_e32 v97, v14
	v_or_b32_e32 v98, 0x80000000, v14
	v_cmp_gt_i32_e32 vcc, 0, v14
	v_and_or_b32 v15, v15, s96, v166
	v_max_u32_e32 v16, v0, v1
	v_cndmask_b32_e32 v14, v98, v97, vcc
	v_not_b32_e32 v98, v12
	v_cmp_gt_i32_e32 vcc, 0, v12
	v_and_or_b32 v14, v14, s96, v165
	v_min_u32_e32 v17, v3, v2
	v_cndmask_b32_e32 v12, v99, v98, vcc
	v_not_b32_e32 v98, v13
	v_or_b32_e32 v99, 0x80000000, v13
	v_cmp_gt_i32_e32 vcc, 0, v13
	v_and_or_b32 v12, v12, s96, v163
	v_min_u32_e32 v0, v0, v1
	v_cndmask_b32_e32 v13, v99, v98, vcc
	v_cmp_gt_i32_e32 vcc, 0, v8
	v_and_or_b32 v13, v13, s96, v164
	v_max_u32_e32 v1, v3, v2
	v_cndmask_b32_e32 v8, v203, v202, vcc
	v_not_b32_e32 v202, v9
	v_or_b32_e32 v203, 0x80000000, v9
	v_cmp_gt_i32_e32 vcc, 0, v9
	v_and_or_b32 v8, v8, s96, v159
	v_max_u32_e32 v19, v7, v6
	v_cndmask_b32_e32 v9, v203, v202, vcc
	v_not_b32_e32 v203, v11
	v_cmp_gt_i32_e32 vcc, 0, v11
	v_and_or_b32 v9, v9, s96, v160
	v_min_u32_e32 v94, v4, v5
	v_cndmask_b32_e32 v11, v204, v203, vcc
	v_not_b32_e32 v203, v10
	v_or_b32_e32 v204, 0x80000000, v10
	v_cmp_gt_i32_e32 vcc, 0, v10
	v_and_or_b32 v11, v11, s96, v162
	v_min_u32_e32 v6, v7, v6
	v_cndmask_b32_e32 v10, v204, v203, vcc
	v_and_or_b32 v10, v10, s96, v161
	v_max_u32_e32 v4, v4, v5
	v_max_u32_e32 v97, v15, v14
	v_min_u32_e32 v98, v12, v13
	v_min_u32_e32 v14, v15, v14
	v_max_u32_e32 v12, v12, v13
	v_max_u32_e32 v202, v8, v9
	v_min_u32_e32 v203, v11, v10
	v_min_u32_e32 v8, v8, v9
	v_max_u32_e32 v9, v11, v10
	v_max_u32_e32 v18, v16, v17
	v_max_u32_e32 v2, v0, v1
	v_min_u32_e32 v95, v19, v94
	v_min_u32_e32 v5, v6, v4
	v_min_u32_e32 v16, v16, v17
	v_min_u32_e32 v0, v0, v1
	v_max_u32_e32 v17, v19, v94
	v_max_u32_e32 v4, v6, v4
	v_max_u32_e32 v99, v97, v98
	v_max_u32_e32 v13, v14, v12
	v_min_u32_e32 v204, v202, v203
	v_min_u32_e32 v10, v8, v9
	v_min_u32_e32 v97, v97, v98
	v_min_u32_e32 v12, v14, v12
	v_max_u32_e32 v98, v202, v203
	v_max_u32_e32 v8, v8, v9
	v_max_u32_e32 v3, v18, v2
	v_min_u32_e32 v7, v95, v5
	v_max_u32_e32 v1, v16, v0
	v_min_u32_e32 v6, v17, v4
	v_min_u32_e32 v2, v18, v2
	v_max_u32_e32 v5, v95, v5
	v_min_u32_e32 v0, v16, v0
	v_max_u32_e32 v4, v17, v4
	v_max_u32_e32 v15, v99, v13
	v_min_u32_e32 v11, v204, v10
	v_max_u32_e32 v14, v97, v12
	v_min_u32_e32 v9, v98, v8
	v_min_u32_e32 v13, v99, v13
	v_max_u32_e32 v10, v204, v10
	v_min_u32_e32 v12, v97, v12
	v_max_u32_e32 v8, v98, v8
	v_max_u32_e32 v96, v3, v7
	v_max_u32_e32 v19, v1, v6
	v_max_u32_e32 v18, v2, v5
	v_max_u32_e32 v16, v0, v4
	v_min_u32_e32 v205, v15, v11
	v_min_u32_e32 v202, v14, v9
	v_min_u32_e32 v99, v13, v10
	v_min_u32_e32 v97, v12, v8
	v_min_u32_e32 v3, v3, v7
	v_min_u32_e32 v1, v1, v6
	v_min_u32_e32 v2, v2, v5
	v_min_u32_e32 v0, v0, v4
	v_max_u32_e32 v7, v15, v11
	v_max_u32_e32 v9, v14, v9
	v_max_u32_e32 v10, v13, v10
	v_max_u32_e32 v8, v12, v8
	v_max_u32_e32 v94, v96, v19
	v_max_u32_e32 v17, v18, v16
	v_min_u32_e32 v203, v205, v202
	v_min_u32_e32 v98, v99, v97
	v_max_u32_e32 v6, v3, v1
	v_max_u32_e32 v4, v2, v0
	v_min_u32_e32 v11, v7, v9
	v_min_u32_e32 v12, v10, v8
	v_min_u32_e32 v19, v96, v19
	v_min_u32_e32 v16, v18, v16
	v_max_u32_e32 v96, v205, v202
	v_max_u32_e32 v97, v99, v97
	v_min_u32_e32 v1, v3, v1
	v_min_u32_e32 v0, v2, v0
	v_max_u32_e32 v3, v7, v9
	v_max_u32_e32 v7, v10, v8
	v_max_u32_e32 v95, v94, v17
	v_min_u32_e32 v204, v203, v98
	v_max_u32_e32 v5, v6, v4
	v_min_u32_e32 v13, v11, v12
	v_max_u32_e32 v18, v19, v16
	v_min_u32_e32 v99, v96, v97
	v_max_u32_e32 v2, v1, v0
	v_min_u32_e32 v8, v3, v7
	v_min_u32_e32 v17, v94, v17
	v_max_u32_e32 v94, v203, v98
	v_min_u32_e32 v4, v6, v4
	v_max_u32_e32 v6, v11, v12
	v_min_u32_e32 v16, v19, v16
	v_max_u32_e32 v19, v96, v97
	v_min_u32_e32 v0, v1, v0
	v_max_u32_e32 v1, v3, v7
	v_min_u32_e32 v206, v95, v204
	v_min_u32_e32 v14, v5, v13
	v_min_u32_e32 v202, v18, v99
	v_min_u32_e32 v9, v2, v8
	v_min_u32_e32 v98, v17, v94
	v_min_u32_e32 v11, v4, v6
	v_min_u32_e32 v96, v16, v19
	v_min_u32_e32 v3, v0, v1
	v_max_u32_e32 v95, v95, v204
	v_max_u32_e32 v5, v5, v13
	v_max_u32_e32 v18, v18, v99
	v_max_u32_e32 v2, v2, v8
	v_max_u32_e32 v17, v17, v94
	v_max_u32_e32 v4, v4, v6
	v_max_u32_e32 v16, v16, v19
	v_max_u32_e32 v0, v0, v1
	v_min_u32_e32 v13, v95, v5
	v_min_u32_e32 v8, v18, v2
	v_min_u32_e32 v6, v17, v4
	v_min_u32_e32 v1, v16, v0
	v_min_u32_e32 v99, v13, v8
	v_min_u32_e32 v19, v6, v1
	v_min_u32_e32 v15, v206, v14
	v_min_u32_e32 v10, v202, v9
	v_min_u32_e32 v12, v98, v11
	v_min_u32_e32 v7, v96, v3
	v_min_u32_e32 v94, v99, v19
	v_max_u32_e32 v14, v206, v14
	v_max_u32_e32 v9, v202, v9
	v_max_u32_e32 v11, v98, v11
	v_max_u32_e32 v3, v96, v3
	v_max_u32_e32 v5, v95, v5
	v_max_u32_e32 v2, v18, v2
	v_max_u32_e32 v4, v17, v4
	v_max_u32_e32 v0, v16, v0
	v_min_u32_e32 v205, v15, v10
	v_min_u32_e32 v97, v12, v7
	v_max3_u32 v20, v35, v20, v94
	v_min_u32_e32 v94, v14, v9
	v_min_u32_e32 v96, v11, v3
	v_min_u32_e32 v18, v5, v2
	v_min_u32_e32 v16, v4, v0
	v_max_u32_e32 v10, v15, v10
	v_max_u32_e32 v7, v12, v7
	v_max_u32_e32 v8, v13, v8
	v_max_u32_e32 v1, v6, v1
	v_max_u32_e32 v9, v14, v9
	v_max_u32_e32 v3, v11, v3
	v_max_u32_e32 v2, v5, v2
	v_max_u32_e32 v0, v4, v0
	v_min_u32_e32 v203, v205, v97
	v_min_u32_e32 v98, v94, v96
	v_min_u32_e32 v17, v18, v16
	v_min_u32_e32 v12, v10, v7
	v_min_u32_e32 v6, v8, v1
	v_min_u32_e32 v11, v9, v3
	v_min_u32_e32 v4, v2, v0
	v_max3_u32 v203, v213, v214, v203
	v_max3_u32 v25, v25, v27, v98
	v_max3_u32 v17, v22, v88, v17
	v_max3_u32 v12, v200, v24, v12
	v_max3_u32 v6, v201, v21, v6
	v_max3_u32 v11, v26, v34, v11
	v_max3_u32 v4, v23, v89, v4
	v_max3_u32 v21, v90, v205, v97
	v_max3_u32 v19, v31, v99, v19
	v_max3_u32 v24, v29, v94, v96
	v_max3_u32 v16, v92, v18, v16
	v_max3_u32 v7, v28, v10, v7
	v_max3_u32 v1, v91, v8, v1
	v_max3_u32 v3, v30, v9, v3
	v_max3_u32 v0, v93, v2, v0
	v_min_u32_e32 v35, v203, v20
	v_min_u32_e32 v22, v25, v17
	v_min_u32_e32 v13, v12, v6
	v_min_u32_e32 v5, v11, v4
	v_min_u32_e32 v23, v21, v19
	v_min_u32_e32 v18, v24, v16
	v_min_u32_e32 v8, v7, v1
	v_min_u32_e32 v2, v3, v0
	v_max_u32_e32 v20, v203, v20
	v_max_u32_e32 v17, v25, v17
	v_max_u32_e32 v6, v12, v6
	v_max_u32_e32 v4, v11, v4
	v_max_u32_e32 v19, v21, v19
	v_max_u32_e32 v16, v24, v16
	v_max_u32_e32 v1, v7, v1
	v_max_u32_e32 v0, v3, v0
	v_max_u32_e32 v25, v20, v17
	v_max_u32_e32 v11, v6, v4
	v_max_u32_e32 v21, v19, v16
	v_max_u32_e32 v3, v1, v0
	v_max_u32_e32 v12, v25, v11
	v_max_u32_e32 v7, v21, v3
	v_min_u32_e32 v11, v25, v11
	v_min_u32_e32 v3, v21, v3
	v_max_u32_e32 v24, v12, v7
	v_min_u32_e32 v7, v12, v7
	v_max_u32_e32 v12, v11, v3
	v_min_u32_e32 v3, v11, v3
	v_min_u32_e32 v11, v20, v17
	v_min_u32_e32 v4, v6, v4
	v_min_u32_e32 v16, v19, v16
	v_min_u32_e32 v0, v1, v0
	v_max_u32_e32 v6, v11, v4
	v_max_u32_e32 v1, v16, v0
	v_min_u32_e32 v4, v11, v4
	v_min_u32_e32 v0, v16, v0
	v_min_u32_e32 v14, v13, v5
	v_min_u32_e32 v9, v8, v2
	v_max_u32_e32 v17, v6, v1
	v_min_u32_e32 v1, v6, v1
	v_max_u32_e32 v6, v4, v0
	v_min_u32_e32 v0, v4, v0
	v_max_u32_e32 v4, v35, v22
	v_max_u32_e32 v5, v13, v5
	v_max_u32_e32 v13, v23, v18
	v_max_u32_e32 v2, v8, v2
	v_min_u32_e32 v27, v35, v22
	v_min_u32_e32 v26, v23, v18
	v_max_u32_e32 v11, v4, v5
	v_max_u32_e32 v8, v13, v2
	v_min_u32_e32 v4, v4, v5
	v_min_u32_e32 v2, v13, v2
	v_min_u32_e32 v15, v27, v14
	v_min_u32_e32 v10, v26, v9
	v_max_u32_e32 v5, v4, v2
	v_min_u32_e32 v2, v4, v2
	v_max_u32_e32 v4, v27, v14
	v_max_u32_e32 v9, v26, v9
	v_min_u32_e32 v28, v15, v10
	v_max_u32_e32 v16, v11, v8
	v_min_u32_e32 v8, v11, v8
	v_max_u32_e32 v11, v4, v9
	v_min_u32_e32 v4, v4, v9
	v_max_u32_e32 v9, v15, v10
	ds_bpermute_b32 v10, v33, v24
	ds_bpermute_b32 v13, v33, v7
	ds_bpermute_b32 v14, v33, v12
	ds_bpermute_b32 v15, v33, v3
	ds_bpermute_b32 v18, v33, v17
	ds_bpermute_b32 v19, v33, v1
	ds_bpermute_b32 v20, v33, v6
	ds_bpermute_b32 v21, v33, v0
	ds_bpermute_b32 v22, v33, v16
	ds_bpermute_b32 v23, v33, v8
	ds_bpermute_b32 v25, v33, v5
	ds_bpermute_b32 v26, v33, v28
	ds_bpermute_b32 v27, v33, v9
	ds_bpermute_b32 v29, v33, v4
	ds_bpermute_b32 v30, v33, v11
	ds_bpermute_b32 v31, v33, v2
	s_waitcnt lgkmcnt(4)
	v_max_u32_e32 v24, v24, v26
	s_waitcnt lgkmcnt(3)
	v_max_u32_e32 v7, v7, v27
	s_waitcnt lgkmcnt(2)
	v_max_u32_e32 v12, v12, v29
	s_waitcnt lgkmcnt(1)
	v_max_u32_e32 v3, v3, v30
	s_waitcnt lgkmcnt(0)
	v_max_u32_e32 v17, v17, v31
	v_max_u32_e32 v1, v1, v25
	v_max_u32_e32 v6, v6, v23
	v_max_u32_e32 v0, v0, v22
	v_max_u32_e32 v16, v16, v21
	v_max_u32_e32 v8, v8, v20
	v_max_u32_e32 v5, v5, v19
	v_max_u32_e32 v2, v2, v18
	v_max_u32_e32 v11, v11, v15
	v_max_u32_e32 v4, v4, v14
	v_max_u32_e32 v9, v9, v13
	v_max_u32_e32 v10, v28, v10
	v_max_u32_e32 v13, v24, v16
	v_min_u32_e32 v14, v24, v16
	v_max_u32_e32 v15, v7, v8
	v_min_u32_e32 v7, v7, v8
	v_max_u32_e32 v8, v12, v5
	v_min_u32_e32 v5, v12, v5
	v_max_u32_e32 v12, v3, v2
	v_min_u32_e32 v2, v3, v2
	v_max_u32_e32 v3, v17, v11
	v_max_u32_e32 v16, v1, v4
	v_min_u32_e32 v1, v1, v4
	v_max_u32_e32 v4, v6, v9
	v_min_u32_e32 v6, v6, v9
	v_max_u32_e32 v9, v0, v10
	v_min_u32_e32 v11, v17, v11
	v_min_u32_e32 v0, v0, v10
	v_max_u32_e32 v10, v13, v3
	v_min_u32_e32 v3, v13, v3
	v_max_u32_e32 v13, v15, v16
	v_min_u32_e32 v15, v15, v16
	v_max_u32_e32 v16, v8, v4
	v_min_u32_e32 v4, v8, v4
	v_max_u32_e32 v8, v12, v9
	v_min_u32_e32 v9, v12, v9
	v_max_u32_e32 v12, v14, v11
	v_min_u32_e32 v11, v14, v11
	v_max_u32_e32 v14, v7, v1
	v_min_u32_e32 v7, v7, v1
	v_max_u32_e32 v1, v5, v6
	v_min_u32_e32 v6, v5, v6
	v_max_u32_e32 v5, v2, v0
	v_min_u32_e32 v0, v2, v0
	v_max_u32_e32 v2, v10, v16
	v_min_u32_e32 v10, v10, v16
	v_max_u32_e32 v16, v13, v8
	v_min_u32_e32 v8, v13, v8
	v_max_u32_e32 v13, v3, v4
	v_min_u32_e32 v3, v3, v4
	v_max_u32_e32 v4, v15, v9
	v_min_u32_e32 v9, v15, v9
	v_max_u32_e32 v15, v12, v1
	v_min_u32_e32 v1, v12, v1
	v_max_u32_e32 v12, v14, v5
	v_max_u32_e32 v20, v3, v9
	v_max_u32_e32 v88, v11, v6
	v_min_u32_e32 v89, v11, v6
	v_max_u32_e32 v90, v7, v0
	v_min_u32_e32 v91, v7, v0
	v_max_u32_e32 v17, v2, v16
	v_min_u32_e32 v22, v2, v16
	v_max_u32_e32 v19, v13, v4
	v_min_u32_e32 v24, v13, v4
	v_max_u32_e32 v21, v15, v12
	v_min_u32_e32 v26, v15, v12
	v_and_b32_e32 v0, 0x7fffff80, v20
	v_bitop3_b32 v2, v20, s94, v20 bitop3:0xcf
	v_cmp_gt_i32_e32 vcc, 0, v20
	v_max_u32_e32 v11, v42, v87
	v_max_u32_e32 v12, v52, v84
	v_max_u32_e32 v13, v45, v86
	v_max_u32_e32 v15, v57, v61
	v_max_u32_e32 v30, v41, v85
	v_max_u32_e32 v31, v49, v60
	v_max_u32_e32 v34, v43, v62
	v_max_u32_e32 v42, v54, v55
	v_max_u32_e32 v45, v38, v63
	v_max_u32_e32 v54, v48, v51
	v_min_u32_e32 v5, v14, v5
	v_max_u32_e32 v18, v10, v8
	v_min_u32_e32 v23, v10, v8
	v_cndmask_b32_e32 v10, v2, v0, vcc
	v_and_b32_e32 v0, 0x7fffff80, v26
	v_bitop3_b32 v2, v26, s94, v26 bitop3:0xcf
	v_cmp_gt_i32_e32 vcc, 0, v26
	v_max_u32_e32 v14, v11, v12
	v_max_u32_e32 v35, v13, v15
	v_max_u32_e32 v41, v30, v31
	v_max_u32_e32 v43, v34, v42
	v_max_u32_e32 v55, v45, v46
	v_max_u32_e32 v56, v40, v54
	v_max_u32_e32 v57, v37, v44
	v_cndmask_b32_e32 v4, v2, v0, vcc
	v_max_u32_e32 v2, v14, v35
	v_max_u32_e32 v6, v41, v43
	v_max_u32_e32 v7, v55, v56
	v_max_u32_e32 v8, v57, v47
	v_min_u32_e32 v25, v3, v9
	v_min_u32_e32 v3, v2, v6
	v_min_u32_e32 v9, v7, v8
	v_min_u32_e32 v27, v3, v9
	v_and_b32_e32 v0, 0x7fffff80, v27
	v_bitop3_b32 v16, v27, s94, v27 bitop3:0xcf
	v_cmp_gt_i32_e32 vcc, 0, v27
	v_max_u32_e32 v28, v3, v9
	v_and_b32_e32 v3, 0x7fffff80, v23
	v_cndmask_b32_e32 v0, v16, v0, vcc
	v_and_b32_e32 v16, 0xffffff80, v23
	v_and_b32_e32 v29, 0xffffff80, v28
	v_xor_b32_e32 v16, -1, v16
	v_cmp_gt_i32_e32 vcc, 0, v23
	v_and_b32_e32 v9, 0x7fffff80, v28
	v_xor_b32_e32 v29, -1, v29
	v_cndmask_b32_e32 v3, v16, v3, vcc
	v_cmp_gt_i32_e32 vcc, 0, v28
	v_max_u32_e32 v58, v2, v6
	v_max_u32_e32 v59, v7, v8
	v_cndmask_b32_e32 v38, v29, v9, vcc
	v_min_u32_e32 v29, v58, v59
	v_and_b32_e32 v7, 0xffffff80, v18
	v_and_b32_e32 v2, 0x7fffff80, v18
	v_and_b32_e32 v8, 0xffffff80, v29
	v_xor_b32_e32 v7, -1, v7
	v_cmp_gt_i32_e32 vcc, 0, v18
	v_and_b32_e32 v6, 0x7fffff80, v29
	v_xor_b32_e32 v8, -1, v8
	v_cndmask_b32_e32 v2, v7, v2, vcc
	v_cmp_gt_i32_e32 vcc, 0, v29
	v_min_u32_e32 v11, v11, v12
	v_min_u32_e32 v15, v13, v15
	v_cndmask_b32_e32 v16, v8, v6, vcc
	v_pk_add_f32 v[6:7], v[38:39], v[2:3] op_sel_hi:[0,1]
	v_not_b32_e32 v8, v7
	v_or_b32_e32 v9, 0x80000000, v7
	v_cmp_gt_i32_e32 vcc, 0, v7
	v_min_u32_e32 v62, v30, v31
	v_min_u32_e32 v63, v34, v42
	v_cndmask_b32_e32 v7, v9, v8, vcc
	v_and_b32_e32 v7, 0xffffff00, v7
	v_or_b32_e32 v7, 0xdc, v7
	v_cndmask_b32_e64 v48, 0, v7, s[10:11]
	v_not_b32_e32 v7, v6
	v_or_b32_e32 v8, 0x80000000, v6
	v_cmp_gt_i32_e32 vcc, 0, v6
	v_and_b32_e32 v9, 0x7fffff80, v19
	v_min_u32_e32 v45, v45, v46
	v_cndmask_b32_e32 v6, v8, v7, vcc
	v_and_b32_e32 v6, 0xffffff00, v6
	v_or_b32_e32 v6, 0xdd, v6
	v_cndmask_b32_e64 v49, 0, v6, s[10:11]
	v_and_b32_e32 v6, 0xffffff80, v24
	v_and_b32_e32 v7, 0xffffff80, v19
	v_and_b32_e32 v8, 0x7fffff80, v24
	v_xor_b32_e32 v6, -1, v6
	v_cmp_gt_i32_e32 vcc, 0, v24
	v_xor_b32_e32 v50, -1, v7
	v_min_u32_e32 v46, v40, v54
	v_cndmask_b32_e32 v7, v6, v8, vcc
	v_cmp_gt_i32_e32 vcc, 0, v19
	v_min_u32_e32 v37, v37, v44
	v_min_u32_e32 v60, v11, v15
	v_cndmask_b32_e32 v6, v50, v9, vcc
	v_pk_add_f32 v[8:9], v[16:17], v[6:7] op_sel_hi:[0,1]
	v_not_b32_e32 v50, v9
	v_or_b32_e32 v51, 0x80000000, v9
	v_cmp_gt_i32_e32 vcc, 0, v9
	v_min_u32_e32 v84, v62, v63
	v_min_u32_e32 v85, v45, v46
	v_cndmask_b32_e32 v9, v51, v50, vcc
	v_and_b32_e32 v9, 0xffffff00, v9
	v_or_b32_e32 v9, 0xea, v9
	v_cndmask_b32_e64 v50, 0, v9, s[10:11]
	v_not_b32_e32 v9, v8
	v_or_b32_e32 v51, 0x80000000, v8
	v_cmp_gt_i32_e32 vcc, 0, v8
	v_min_u32_e32 v39, v37, v36
	v_max_u32_e32 v34, v58, v59
	v_cndmask_b32_e32 v8, v51, v9, vcc
	v_and_b32_e32 v8, 0xffffff00, v8
	v_or_b32_e32 v8, 0xeb, v8
	v_cndmask_b32_e64 v51, 0, v8, s[10:11]
	v_pk_add_f32 v[8:9], v[16:17], v[2:3] op_sel_hi:[0,1]
	v_not_b32_e32 v52, v9
	v_or_b32_e32 v53, 0x80000000, v9
	v_cmp_gt_i32_e32 vcc, 0, v9
	v_max_u32_e32 v11, v11, v15
	v_max_u32_e32 v15, v37, v36
	v_cndmask_b32_e32 v9, v53, v52, vcc
	v_and_b32_e32 v9, 0xffffff00, v9
	v_or_b32_e32 v9, 0xec, v9
	v_cndmask_b32_e64 v52, 0, v9, s[10:11]
	v_not_b32_e32 v9, v8
	v_or_b32_e32 v53, 0x80000000, v8
	v_cmp_gt_i32_e32 vcc, 0, v8
	v_min_u32_e32 v37, v14, v35
	v_and_b32_e32 v14, 0xffffff80, v25
	v_cndmask_b32_e32 v8, v53, v9, vcc
	v_and_b32_e32 v8, 0xffffff00, v8
	v_or_b32_e32 v8, 0xed, v8
	v_cndmask_b32_e64 v53, 0, v8, s[10:11]
	v_min_u32_e32 v8, v60, v84
	v_min_u32_e32 v9, v85, v39
	v_min_u32_e32 v30, v8, v9
	v_and_b32_e32 v12, 0x7fffff80, v30
	v_bitop3_b32 v13, v30, s94, v30 bitop3:0xcf
	v_cmp_gt_i32_e32 vcc, 0, v30
	v_max_u32_e32 v31, v8, v9
	v_and_b32_e32 v8, 0x7fffff80, v31
	v_cndmask_b32_e32 v40, v13, v12, vcc
	v_bitop3_b32 v9, v31, s94, v31 bitop3:0xcf
	v_cmp_gt_i32_e32 vcc, 0, v31
	v_and_b32_e32 v13, 0xffffff80, v34
	v_and_b32_e32 v12, 0x7fffff80, v34
	v_cndmask_b32_e32 v42, v9, v8, vcc
	v_and_b32_e32 v9, 0xffffff80, v22
	v_and_b32_e32 v8, 0x7fffff80, v22
	v_xor_b32_e32 v9, -1, v9
	v_cmp_gt_i32_e32 vcc, 0, v22
	v_xor_b32_e32 v13, -1, v13
	v_xor_b32_e32 v14, -1, v14
	v_cndmask_b32_e32 v9, v9, v8, vcc
	v_cmp_gt_i32_e32 vcc, 0, v34
	s_nop 1
	v_cndmask_b32_e32 v8, v13, v12, vcc
	v_mov_b32_e32 v12, v9
	v_mov_b32_e32 v13, v2
	v_pk_add_f32 v[12:13], v[0:1], v[12:13] op_sel_hi:[0,1]
	v_not_b32_e32 v44, v13
	v_or_b32_e32 v54, 0x80000000, v13
	v_cmp_gt_i32_e32 vcc, 0, v13
	s_nop 1
	v_cndmask_b32_e32 v13, v54, v44, vcc
	v_and_b32_e32 v13, 0xffffff00, v13
	v_or_b32_e32 v61, 0xcd, v13
	v_not_b32_e32 v13, v12
	v_or_b32_e32 v44, 0x80000000, v12
	v_cmp_gt_i32_e32 vcc, 0, v12
	s_nop 1
	v_cndmask_b32_e32 v12, v44, v13, vcc
	v_and_b32_e32 v12, 0xffffff00, v12
	v_or_b32_e32 v12, 0xce, v12
	v_cndmask_b32_e64 v54, 0, v12, s[10:11]
	v_max_u32_e32 v44, v60, v84
	v_max_u32_e32 v84, v85, v39
	v_max_u32_e32 v12, v62, v63
	v_min_u32_e32 v39, v41, v43
	v_min_u32_e32 v41, v55, v56
	v_min_u32_e32 v43, v57, v47
	v_min_u32_e32 v85, v11, v12
	v_max_u32_e32 v86, v11, v12
	v_min_u32_e32 v11, v37, v39
	v_min_u32_e32 v12, v41, v43
	v_max_u32_e32 v13, v45, v46
	v_max_u32_e32 v36, v11, v12
	v_min_u32_e32 v45, v13, v15
	v_max_u32_e32 v87, v13, v15
	v_and_b32_e32 v13, 0xffffff80, v36
	v_min_u32_e32 v35, v11, v12
	v_and_b32_e32 v11, 0x7fffff80, v36
	v_xor_b32_e32 v13, -1, v13
	v_cmp_gt_i32_e32 vcc, 0, v36
	v_and_b32_e32 v12, 0x7fffff80, v25
	v_max_u32_e32 v94, v37, v39
	v_cndmask_b32_e32 v15, v13, v11, vcc
	v_cmp_gt_i32_e32 vcc, 0, v25
	v_max_u32_e32 v95, v41, v43
	v_mov_b32_e32 v39, v0
	v_cndmask_b32_e32 v14, v14, v12, vcc
	v_mov_b32_e32 v11, v14
	v_pk_add_f32 v[12:13], v[16:17], v[10:11] op_sel_hi:[0,1]
	v_not_b32_e32 v11, v12
	v_or_b32_e32 v46, 0x80000000, v12
	v_cmp_gt_i32_e32 vcc, 0, v12
	v_or_b32_e32 v12, 0x80000000, v13
	v_add_f32_e32 v10, v8, v10
	v_cndmask_b32_e32 v11, v46, v11, vcc
	v_and_b32_e32 v11, 0xffffff00, v11
	v_or_b32_e32 v11, 0xe9, v11
	v_cndmask_b32_e64 v55, 0, v11, s[10:11]
	v_not_b32_e32 v11, v13
	v_cmp_gt_i32_e32 vcc, 0, v13
	v_mov_b32_e32 v43, v16
	s_nop 0
	v_cndmask_b32_e32 v11, v12, v11, vcc
	v_and_b32_e32 v11, 0xffffff00, v11
	v_or_b32_e32 v11, 0xe8, v11
	v_pk_add_f32 v[12:13], v[14:15], v[8:9]
	v_cndmask_b32_e64 v56, 0, v11, s[10:11]
	v_not_b32_e32 v11, v12
	v_or_b32_e32 v14, 0x80000000, v12
	v_cmp_gt_i32_e32 vcc, 0, v12
	v_not_b32_e32 v12, v13
	s_nop 0
	v_cndmask_b32_e32 v11, v14, v11, vcc
	v_or_b32_e32 v14, 0x80000000, v13
	v_cmp_gt_i32_e32 vcc, 0, v13
	v_and_b32_e32 v11, 0xffffff00, v11
	v_or_b32_e32 v11, 0xf8, v11
	v_cndmask_b32_e32 v12, v14, v12, vcc
	v_and_b32_e32 v12, 0xffffff00, v12
	v_or_b32_e32 v12, 0x9e, v12
	v_cndmask_b32_e64 v92, v12, v11, s[10:11]
	v_not_b32_e32 v11, v10
	v_or_b32_e32 v12, 0x80000000, v10
	v_cmp_gt_i32_e32 vcc, 0, v10
	v_min_u32_e32 v14, v94, v95
	v_and_b32_e32 v13, 0xffffff80, v14
	v_cndmask_b32_e32 v10, v12, v11, vcc
	v_and_b32_e32 v10, 0xffffff00, v10
	v_and_b32_e32 v11, 0xffffff80, v17
	v_or_b32_e32 v93, 0xf9, v10
	v_and_b32_e32 v10, 0x7fffff80, v17
	v_xor_b32_e32 v11, -1, v11
	v_cmp_gt_i32_e32 vcc, 0, v17
	v_and_b32_e32 v12, 0x7fffff80, v14
	v_xor_b32_e32 v13, -1, v13
	v_cndmask_b32_e32 v11, v11, v10, vcc
	v_cmp_gt_i32_e32 vcc, 0, v14
	s_nop 1
	v_cndmask_b32_e32 v10, v13, v12, vcc
	v_mov_b32_e32 v12, v6
	v_mov_b32_e32 v13, v11
	v_pk_add_f32 v[12:13], v[38:39], v[12:13]
	v_pk_mov_b32 v[62:63], v[10:11], v[8:9] op_sel:[1,0]
	v_not_b32_e32 v37, v12
	v_or_b32_e32 v39, 0x80000000, v12
	v_cmp_gt_i32_e32 vcc, 0, v12
	s_nop 1
	v_cndmask_b32_e32 v12, v39, v37, vcc
	v_and_b32_e32 v12, 0xffffff00, v12
	v_or_b32_e32 v12, 0xdb, v12
	v_cndmask_b32_e64 v57, 0, v12, s[10:11]
	v_not_b32_e32 v12, v13
	v_or_b32_e32 v37, 0x80000000, v13
	v_cmp_gt_i32_e32 vcc, 0, v13
	v_mov_b32_e32 v13, v9
	s_nop 0
	v_cndmask_b32_e32 v12, v37, v12, vcc
	v_and_b32_e32 v12, 0xffffff00, v12
	v_or_b32_e32 v12, 0xcf, v12
	v_cndmask_b32_e64 v58, 0, v12, s[10:11]
	v_mov_b32_e32 v12, v11
	v_pk_add_f32 v[38:39], v[38:39], v[12:13] op_sel_hi:[0,1]
	v_not_b32_e32 v37, v39
	v_or_b32_e32 v41, 0x80000000, v39
	v_cmp_gt_i32_e32 vcc, 0, v39
	v_or_b32_e32 v39, 0x80000000, v38
	s_nop 0
	v_cndmask_b32_e32 v37, v41, v37, vcc
	v_and_b32_e32 v37, 0xffffff00, v37
	v_or_b32_e32 v37, 0xde, v37
	v_cndmask_b32_e64 v59, 0, v37, s[10:11]
	v_not_b32_e32 v37, v38
	v_cmp_gt_i32_e32 vcc, 0, v38
	v_mov_b32_e32 v41, v16
	v_mov_b32_e32 v16, v11
	v_cndmask_b32_e32 v37, v39, v37, vcc
	v_and_b32_e32 v37, 0xffffff00, v37
	v_or_b32_e32 v37, 0xdf, v37
	v_pk_add_f32 v[38:39], v[40:41], v[12:13]
	v_cndmask_b32_e64 v60, 0, v37, s[10:11]
	v_not_b32_e32 v37, v39
	v_or_b32_e32 v40, 0x80000000, v39
	v_cmp_gt_i32_e32 vcc, 0, v39
	v_not_b32_e32 v39, v38
	s_nop 0
	v_cndmask_b32_e32 v37, v40, v37, vcc
	v_or_b32_e32 v40, 0x80000000, v38
	v_cmp_gt_i32_e32 vcc, 0, v38
	v_and_b32_e32 v37, 0xffffff00, v37
	v_or_b32_e32 v37, 0xee, v37
	v_cndmask_b32_e32 v38, v40, v39, vcc
	v_and_or_b32 v40, v38, s97, 15
	v_pk_add_f32 v[38:39], v[42:43], v[16:17] op_sel_hi:[1,0]
	v_cndmask_b32_e64 v97, v40, v37, s[10:11]
	v_not_b32_e32 v16, v39
	v_or_b32_e32 v41, 0x80000000, v39
	v_cmp_gt_i32_e32 vcc, 0, v39
	v_not_b32_e32 v39, v38
	v_min_u32_e32 v37, v44, v84
	v_cndmask_b32_e32 v16, v41, v16, vcc
	v_or_b32_e32 v41, 0x80000000, v38
	v_cmp_gt_i32_e32 vcc, 0, v38
	v_and_b32_e32 v16, 0xffffff00, v16
	v_or_b32_e32 v16, 0xef, v16
	v_cndmask_b32_e32 v38, v41, v39, vcc
	v_and_or_b32 v38, v38, s97, 31
	v_cndmask_b32_e64 v96, v38, v16, s[10:11]
	v_min_u32_e32 v16, v89, v91
	v_and_b32_e32 v39, 0xffffff80, v16
	v_and_b32_e32 v38, 0x7fffff80, v16
	v_and_b32_e32 v41, 0xffffff80, v37
	v_xor_b32_e32 v39, -1, v39
	v_cmp_gt_i32_e32 vcc, 0, v16
	v_and_b32_e32 v40, 0x7fffff80, v37
	v_xor_b32_e32 v41, -1, v41
	v_cndmask_b32_e32 v39, v39, v38, vcc
	v_cmp_gt_i32_e32 vcc, 0, v37
	s_nop 1
	v_cndmask_b32_e32 v38, v41, v40, vcc
	v_pk_add_f32 v[38:39], v[38:39], v[62:63]
	s_nop 0
	v_not_b32_e32 v40, v39
	v_or_b32_e32 v41, 0x80000000, v39
	v_cmp_gt_i32_e32 vcc, 0, v39
	s_nop 1
	v_cndmask_b32_e32 v39, v41, v40, vcc
	v_not_b32_e32 v40, v38
	v_or_b32_e32 v41, 0x80000000, v38
	v_cmp_gt_i32_e32 vcc, 0, v38
	v_and_b32_e32 v39, 0xffffff00, v39
	v_or_b32_e32 v39, 0xf0, v39
	v_cndmask_b32_e32 v38, v41, v40, vcc
	v_and_or_b32 v38, v38, s97, 47
	v_cndmask_b32_e64 v98, v38, v39, s[10:11]
	v_max_u32_e32 v38, v89, v91
	v_max_u32_e32 v39, v44, v84
	v_and_b32_e32 v41, 0xffffff80, v38
	v_and_b32_e32 v40, 0x7fffff80, v38
	v_and_b32_e32 v43, 0xffffff80, v39
	v_xor_b32_e32 v41, -1, v41
	v_cmp_gt_i32_e32 vcc, 0, v38
	v_and_b32_e32 v42, 0x7fffff80, v39
	v_xor_b32_e32 v43, -1, v43
	v_cndmask_b32_e32 v41, v41, v40, vcc
	v_cmp_gt_i32_e32 vcc, 0, v39
	s_nop 1
	v_cndmask_b32_e32 v40, v43, v42, vcc
	v_pk_add_f32 v[40:41], v[40:41], v[62:63]
	s_nop 0
	v_not_b32_e32 v42, v41
	v_or_b32_e32 v43, 0x80000000, v41
	v_cmp_gt_i32_e32 vcc, 0, v41
	s_nop 1
	v_cndmask_b32_e32 v41, v43, v42, vcc
	v_not_b32_e32 v42, v40
	v_or_b32_e32 v43, 0x80000000, v40
	v_cmp_gt_i32_e32 vcc, 0, v40
	v_and_b32_e32 v41, 0xffffff00, v41
	v_or_b32_e32 v41, 0xf1, v41
	v_cndmask_b32_e32 v40, v43, v42, vcc
	v_and_or_b32 v40, v40, s97, 63
	v_cndmask_b32_e64 v89, v40, v41, s[10:11]
	v_min_u32_e32 v40, v88, v90
	v_min_u32_e32 v41, v85, v45
	v_and_b32_e32 v43, 0xffffff80, v40
	v_and_b32_e32 v42, 0x7fffff80, v40
	v_and_b32_e32 v46, 0xffffff80, v41
	v_xor_b32_e32 v43, -1, v43
	v_cmp_gt_i32_e32 vcc, 0, v40
	v_and_b32_e32 v44, 0x7fffff80, v41
	v_xor_b32_e32 v46, -1, v46
	v_cndmask_b32_e32 v43, v43, v42, vcc
	v_cmp_gt_i32_e32 vcc, 0, v41
	s_nop 1
	v_cndmask_b32_e32 v42, v46, v44, vcc
	v_pk_add_f32 v[42:43], v[42:43], v[62:63]
	s_nop 0
	v_not_b32_e32 v44, v43
	v_or_b32_e32 v46, 0x80000000, v43
	v_cmp_gt_i32_e32 vcc, 0, v43
	s_nop 1
	v_cndmask_b32_e32 v43, v46, v44, vcc
	v_not_b32_e32 v44, v42
	v_or_b32_e32 v46, 0x80000000, v42
	v_cmp_gt_i32_e32 vcc, 0, v42
	v_and_b32_e32 v43, 0xffffff00, v43
	v_or_b32_e32 v43, 0xf2, v43
	v_cndmask_b32_e32 v42, v46, v44, vcc
	v_and_b32_e32 v42, 0xffffff00, v42
	v_or_b32_e32 v42, 0x4f, v42
	v_cndmask_b32_e64 v91, v42, v43, s[10:11]
	v_max_u32_e32 v42, v88, v90
	v_max_u32_e32 v43, v85, v45
	v_and_b32_e32 v45, 0xffffff80, v42
	v_and_b32_e32 v44, 0x7fffff80, v42
	v_and_b32_e32 v47, 0xffffff80, v43
	v_xor_b32_e32 v45, -1, v45
	v_cmp_gt_i32_e32 vcc, 0, v42
	v_and_b32_e32 v46, 0x7fffff80, v43
	v_xor_b32_e32 v47, -1, v47
	v_cndmask_b32_e32 v45, v45, v44, vcc
	v_cmp_gt_i32_e32 vcc, 0, v43
	s_nop 1
	v_cndmask_b32_e32 v44, v47, v46, vcc
	v_pk_add_f32 v[44:45], v[44:45], v[62:63]
	s_nop 0
	v_not_b32_e32 v46, v45
	v_or_b32_e32 v47, 0x80000000, v45
	v_cmp_gt_i32_e32 vcc, 0, v45
	s_nop 1
	v_cndmask_b32_e32 v45, v47, v46, vcc
	v_not_b32_e32 v46, v44
	v_or_b32_e32 v47, 0x80000000, v44
	v_cmp_gt_i32_e32 vcc, 0, v44
	v_and_b32_e32 v45, 0xffffff00, v45
	v_or_b32_e32 v45, 0xf3, v45
	v_cndmask_b32_e32 v44, v47, v46, vcc
	v_and_b32_e32 v44, 0xffffff00, v44
	v_or_b32_e32 v44, 0x5f, v44
	v_cndmask_b32_e64 v88, v44, v45, s[10:11]
	v_min_u32_e32 v44, v1, v5
	v_min_u32_e32 v45, v86, v87
	v_and_b32_e32 v47, 0xffffff80, v44
	v_and_b32_e32 v46, 0x7fffff80, v44
	v_and_b32_e32 v85, 0xffffff80, v45
	v_xor_b32_e32 v47, -1, v47
	v_cmp_gt_i32_e32 vcc, 0, v44
	v_and_b32_e32 v84, 0x7fffff80, v45
	v_xor_b32_e32 v85, -1, v85
	v_cndmask_b32_e32 v47, v47, v46, vcc
	v_cmp_gt_i32_e32 vcc, 0, v45
	s_nop 1
	v_cndmask_b32_e32 v46, v85, v84, vcc
	v_pk_add_f32 v[46:47], v[46:47], v[62:63]
	s_nop 0
	v_not_b32_e32 v84, v47
	v_or_b32_e32 v85, 0x80000000, v47
	v_cmp_gt_i32_e32 vcc, 0, v47
	s_nop 1
	v_cndmask_b32_e32 v47, v85, v84, vcc
	v_not_b32_e32 v84, v46
	v_or_b32_e32 v85, 0x80000000, v46
	v_cmp_gt_i32_e32 vcc, 0, v46
	v_and_b32_e32 v47, 0xffffff00, v47
	v_or_b32_e32 v47, 0xf4, v47
	v_cndmask_b32_e32 v46, v85, v84, vcc
	v_and_b32_e32 v46, 0xffffff00, v46
	v_or_b32_e32 v46, 0x6f, v46
	v_cndmask_b32_e64 v90, v46, v47, s[10:11]
	v_max_u32_e32 v46, v1, v5
	v_max_u32_e32 v47, v86, v87
	v_and_b32_e32 v84, 0xffffff80, v46
	v_and_b32_e32 v1, 0x7fffff80, v46
	v_and_b32_e32 v85, 0xffffff80, v47
	v_xor_b32_e32 v84, -1, v84
	v_cmp_gt_i32_e32 vcc, 0, v46
	v_and_b32_e32 v5, 0x7fffff80, v47
	v_xor_b32_e32 v86, -1, v85
	v_cndmask_b32_e32 v85, v84, v1, vcc
	v_cmp_gt_i32_e32 vcc, 0, v47
	s_nop 1
	v_cndmask_b32_e32 v84, v86, v5, vcc
	v_pk_add_f32 v[84:85], v[84:85], v[62:63]
	s_nop 0
	v_not_b32_e32 v1, v85
	v_or_b32_e32 v5, 0x80000000, v85
	v_cmp_gt_i32_e32 vcc, 0, v85
	v_or_b32_e32 v85, 0x80000000, v84
	s_nop 0
	v_cndmask_b32_e32 v1, v5, v1, vcc
	v_not_b32_e32 v5, v84
	v_cmp_gt_i32_e32 vcc, 0, v84
	v_and_b32_e32 v1, 0xffffff00, v1
	v_or_b32_e32 v1, 0xf5, v1
	v_cndmask_b32_e32 v5, v85, v5, vcc
	v_and_b32_e32 v5, 0xffffff00, v5
	v_or_b32_e32 v5, 0x7f, v5
	v_and_b32_e32 v84, 0xffffff80, v21
	v_cndmask_b32_e64 v86, v5, v1, s[10:11]
	v_and_b32_e32 v1, 0x7fffff80, v21
	v_and_b32_e32 v85, 0xffffff80, v35
	v_xor_b32_e32 v84, -1, v84
	v_cmp_gt_i32_e32 vcc, 0, v21
	v_and_b32_e32 v5, 0x7fffff80, v35
	v_xor_b32_e32 v87, -1, v85
	v_cndmask_b32_e32 v85, v84, v1, vcc
	v_cmp_gt_i32_e32 vcc, 0, v35
	s_nop 1
	v_cndmask_b32_e32 v84, v87, v5, vcc
	v_mov_b32_e32 v5, v84
	v_pk_add_f32 v[4:5], v[4:5], v[8:9]
	s_nop 0
	v_not_b32_e32 v1, v4
	v_or_b32_e32 v87, 0x80000000, v4
	v_cmp_gt_i32_e32 vcc, 0, v4
	v_not_b32_e32 v4, v5
	s_nop 0
	v_cndmask_b32_e32 v1, v87, v1, vcc
	v_or_b32_e32 v87, 0x80000000, v5
	v_cmp_gt_i32_e32 vcc, 0, v5
	v_and_b32_e32 v1, 0xffffff00, v1
	v_or_b32_e32 v1, 0xf6, v1
	v_cndmask_b32_e32 v4, v87, v4, vcc
	v_and_b32_e32 v4, 0xffffff00, v4
	v_or_b32_e32 v4, 0x8e, v4
	v_cndmask_b32_e64 v87, v4, v1, s[10:11]
	v_pk_add_f32 v[4:5], v[84:85], v[62:63]
	s_nop 0
	v_not_b32_e32 v1, v5
	v_or_b32_e32 v62, 0x80000000, v5
	v_cmp_gt_i32_e32 vcc, 0, v5
	v_not_b32_e32 v5, v4
	s_nop 0
	v_cndmask_b32_e32 v1, v62, v1, vcc
	v_or_b32_e32 v62, 0x80000000, v4
	v_cmp_gt_i32_e32 vcc, 0, v4
	v_and_b32_e32 v1, 0xffffff00, v1
	v_or_b32_e32 v1, 0xf7, v1
	v_cndmask_b32_e32 v4, v62, v5, vcc
	v_and_b32_e32 v4, 0xffffff00, v4
	v_or_b32_e32 v4, 0x8f, v4
	v_cndmask_b32_e64 v84, v4, v1, s[10:11]
	v_add_f32_e32 v1, v15, v11
	v_not_b32_e32 v4, v1
	v_or_b32_e32 v5, 0x80000000, v1
	v_cmp_gt_i32_e32 vcc, 0, v1
	s_nop 1
	v_cndmask_b32_e32 v1, v5, v4, vcc
	v_and_b32_e32 v1, 0xffffff00, v1
	v_pk_mov_b32 v[4:5], v[6:7], v[10:11] op_sel:[1,0]
	v_or_b32_e32 v1, 0x9f, v1
	v_pk_add_f32 v[4:5], v[8:9], v[4:5]
	v_cndmask_b32_e64 v15, v1, v93, s[10:11]
	v_not_b32_e32 v1, v4
	v_or_b32_e32 v62, 0x80000000, v4
	v_cmp_gt_i32_e32 vcc, 0, v4
	v_not_b32_e32 v4, v5
	v_pk_mov_b32 v[6:7], v[10:11], v[6:7] op_sel:[1,0]
	v_cndmask_b32_e32 v1, v62, v1, vcc
	v_or_b32_e32 v62, 0x80000000, v5
	v_cmp_gt_i32_e32 vcc, 0, v5
	v_and_b32_e32 v1, 0xffffff00, v1
	v_or_b32_e32 v1, 0xfa, v1
	v_cndmask_b32_e32 v4, v62, v4, vcc
	v_and_b32_e32 v4, 0xffffff00, v4
	v_or_b32_e32 v4, 0xae, v4
	v_cndmask_b32_e64 v85, v4, v1, s[10:11]
	v_mov_b32_e32 v4, v10
	v_mov_b32_e32 v5, v8
	v_pk_add_f32 v[4:5], v[4:5], v[6:7]
	v_max_u32_e32 v7, v94, v95
	v_not_b32_e32 v1, v5
	v_or_b32_e32 v6, 0x80000000, v5
	v_cmp_gt_i32_e32 vcc, 0, v5
	v_not_b32_e32 v5, v4
	v_max_u32_e32 v94, v52, v53
	v_cndmask_b32_e32 v1, v6, v1, vcc
	v_or_b32_e32 v6, 0x80000000, v4
	v_cmp_gt_i32_e32 vcc, 0, v4
	v_and_b32_e32 v1, 0xffffff00, v1
	v_or_b32_e32 v1, 0xfb, v1
	v_cndmask_b32_e32 v4, v6, v5, vcc
	v_and_b32_e32 v4, 0xffffff00, v4
	v_or_b32_e32 v4, 0xaf, v4
	v_cndmask_b32_e64 v6, v4, v1, s[10:11]
	v_and_b32_e32 v1, 0x7fffff80, v7
	v_bitop3_b32 v4, v7, s94, v7 bitop3:0xcf
	v_cmp_gt_i32_e32 vcc, 0, v7
	v_mov_b32_e32 v5, v8
	v_min_u32_e32 v52, v52, v53
	v_cndmask_b32_e32 v4, v4, v1, vcc
	v_pk_add_f32 v[62:63], v[4:5], v[2:3]
	v_max_u32_e32 v53, v51, v50
	v_not_b32_e32 v1, v63
	v_or_b32_e32 v10, 0x80000000, v63
	v_cmp_gt_i32_e32 vcc, 0, v63
	v_or_b32_e32 v63, 0x80000000, v62
	v_min_u32_e32 v50, v51, v50
	v_cndmask_b32_e32 v1, v10, v1, vcc
	v_not_b32_e32 v10, v62
	v_cmp_gt_i32_e32 vcc, 0, v62
	v_and_b32_e32 v1, 0xffffff00, v1
	v_mov_b32_e32 v62, v2
	v_cndmask_b32_e32 v10, v63, v10, vcc
	v_and_b32_e32 v10, 0xffffff00, v10
	v_mov_b32_e32 v63, v4
	v_or_b32_e32 v1, 0xfc, v1
	v_or_b32_e32 v10, 0xbd, v10
	v_pk_add_f32 v[62:63], v[62:63], v[8:9]
	v_cndmask_b32_e64 v93, v10, v1, s[10:11]
	v_not_b32_e32 v1, v62
	v_or_b32_e32 v2, 0x80000000, v62
	v_cmp_gt_i32_e32 vcc, 0, v62
	v_or_b32_e32 v9, 0x80000000, v63
	v_pk_add_f32 v[4:5], v[4:5], v[12:13]
	v_cndmask_b32_e32 v1, v2, v1, vcc
	v_not_b32_e32 v2, v63
	v_cmp_gt_i32_e32 vcc, 0, v63
	v_and_b32_e32 v1, 0xffffff00, v1
	v_or_b32_e32 v1, 0xfd, v1
	v_cndmask_b32_e32 v2, v9, v2, vcc
	v_and_b32_e32 v2, 0xffffff00, v2
	v_or_b32_e32 v2, 0xbe, v2
	v_cndmask_b32_e64 v2, v2, v1, s[10:11]
	v_not_b32_e32 v1, v5
	v_or_b32_e32 v9, 0x80000000, v5
	v_cmp_gt_i32_e32 vcc, 0, v5
	v_not_b32_e32 v5, v4
	v_mov_b32_e32 v10, v3
	v_cndmask_b32_e32 v1, v9, v1, vcc
	v_or_b32_e32 v9, 0x80000000, v4
	v_cmp_gt_i32_e32 vcc, 0, v4
	v_and_b32_e32 v1, 0xffffff00, v1
	v_or_b32_e32 v1, 0xfe, v1
	v_cndmask_b32_e32 v4, v9, v5, vcc
	v_and_b32_e32 v4, 0xffffff00, v4
	v_or_b32_e32 v4, 0xbf, v4
	v_cndmask_b32_e64 v4, v4, v1, s[10:11]
	v_mov_b32_e32 v1, v8
	v_pk_add_f32 v[0:1], v[0:1], v[10:11]
	v_max_u32_e32 v8, v92, v15
	v_not_b32_e32 v3, v1
	v_or_b32_e32 v5, 0x80000000, v1
	v_cmp_gt_i32_e32 vcc, 0, v1
	v_min_u32_e32 v9, v92, v15
	v_max_u32_e32 v10, v84, v87
	v_cndmask_b32_e32 v1, v5, v3, vcc
	v_not_b32_e32 v3, v0
	v_or_b32_e32 v5, 0x80000000, v0
	v_cmp_gt_i32_e32 vcc, 0, v0
	v_or_b32_e32 v1, 0xff, v1
	v_min_u32_e32 v11, v84, v87
	v_cndmask_b32_e32 v0, v5, v3, vcc
	v_and_b32_e32 v0, 0xffffff00, v0
	v_or_b32_e32 v0, 0xcc, v0
	v_cndmask_b32_e64 v0, v0, v1, s[10:11]
	v_cndmask_b32_e64 v1, 0, v61, s[10:11]
	v_max_u32_e32 v3, v0, v4
	v_min_u32_e32 v0, v0, v4
	v_max_u32_e32 v4, v93, v2
	v_min_u32_e32 v2, v93, v2
	v_max_u32_e32 v5, v6, v85
	v_min_u32_e32 v6, v6, v85
	v_max_u32_e32 v12, v90, v86
	v_min_u32_e32 v13, v90, v86
	v_max_u32_e32 v15, v88, v91
	v_min_u32_e32 v61, v88, v91
	v_max_u32_e32 v62, v98, v89
	v_min_u32_e32 v63, v98, v89
	v_max_u32_e32 v92, v96, v97
	v_min_u32_e32 v93, v96, v97
	v_max_u32_e32 v51, v56, v55
	v_min_u32_e32 v55, v56, v55
	v_max_u32_e32 v56, v60, v59
	v_min_u32_e32 v59, v60, v59
	v_max_u32_e32 v60, v48, v49
	v_min_u32_e32 v48, v48, v49
	v_max_u32_e32 v49, v57, v58
	v_min_u32_e32 v57, v57, v58
	v_max_u32_e32 v58, v1, v54
	v_min_u32_e32 v1, v1, v54
	v_max_u32_e32 v84, v3, v2
	v_min_u32_e32 v2, v3, v2
	v_max_u32_e32 v3, v0, v4
	v_min_u32_e32 v0, v0, v4
	v_max_u32_e32 v4, v9, v5
	v_min_u32_e32 v5, v9, v5
	v_max_u32_e32 v9, v8, v6
	v_min_u32_e32 v6, v8, v6
	v_max_u32_e32 v8, v10, v13
	v_min_u32_e32 v10, v10, v13
	v_max_u32_e32 v13, v11, v12
	v_min_u32_e32 v11, v11, v12
	v_max_u32_e32 v12, v63, v15
	v_min_u32_e32 v15, v63, v15
	v_max_u32_e32 v63, v62, v61
	v_min_u32_e32 v61, v62, v61
	v_max_u32_e32 v54, v92, v52
	v_min_u32_e32 v52, v92, v52
	v_max_u32_e32 v92, v93, v94
	v_min_u32_e32 v93, v93, v94
	v_max_u32_e32 v94, v55, v53
	v_min_u32_e32 v53, v55, v53
	v_max_u32_e32 v55, v51, v50
	v_min_u32_e32 v50, v51, v50
	v_max_u32_e32 v51, v56, v48
	v_min_u32_e32 v48, v56, v48
	v_max_u32_e32 v56, v59, v60
	v_min_u32_e32 v59, v59, v60
	v_max_u32_e32 v60, v1, v49
	v_min_u32_e32 v1, v1, v49
	v_max_u32_e32 v49, v58, v57
	v_min_u32_e32 v57, v58, v57
	v_max_u32_e32 v62, v84, v3
	v_min_u32_e32 v3, v84, v3
	v_max_u32_e32 v84, v2, v0
	v_min_u32_e32 v0, v2, v0
	v_max_u32_e32 v2, v6, v5
	v_min_u32_e32 v5, v6, v5
	v_max_u32_e32 v6, v9, v4
	v_min_u32_e32 v4, v9, v4
	v_max_u32_e32 v9, v8, v13
	v_min_u32_e32 v8, v8, v13
	v_max_u32_e32 v13, v10, v11
	v_min_u32_e32 v10, v10, v11
	v_max_u32_e32 v11, v61, v15
	v_min_u32_e32 v15, v61, v15
	v_max_u32_e32 v61, v63, v12
	v_min_u32_e32 v12, v63, v12
	v_max_u32_e32 v58, v54, v92
	v_min_u32_e32 v54, v54, v92
	v_max_u32_e32 v92, v52, v93
	v_min_u32_e32 v52, v52, v93
	v_max_u32_e32 v93, v50, v53
	v_min_u32_e32 v50, v50, v53
	v_max_u32_e32 v53, v55, v94
	v_min_u32_e32 v55, v55, v94
	v_max_u32_e32 v94, v51, v56
	v_min_u32_e32 v51, v51, v56
	v_max_u32_e32 v56, v48, v59
	v_min_u32_e32 v48, v48, v59
	v_max_u32_e32 v59, v57, v1
	v_min_u32_e32 v1, v57, v1
	v_max_u32_e32 v57, v49, v60
	v_min_u32_e32 v49, v49, v60
	v_max_u32_e32 v63, v62, v5
	v_min_u32_e32 v5, v62, v5
	v_max_u32_e32 v62, v3, v2
	v_min_u32_e32 v2, v3, v2
	v_max_u32_e32 v3, v84, v4
	v_min_u32_e32 v4, v84, v4
	v_max_u32_e32 v84, v0, v6
	v_min_u32_e32 v0, v0, v6
	v_max_u32_e32 v6, v15, v9
	v_min_u32_e32 v9, v15, v9
	v_max_u32_e32 v15, v11, v8
	v_min_u32_e32 v8, v11, v8
	v_max_u32_e32 v11, v12, v13
	v_min_u32_e32 v12, v12, v13
	v_max_u32_e32 v13, v61, v10
	v_min_u32_e32 v10, v61, v10
	v_max_u32_e32 v60, v58, v50
	v_min_u32_e32 v50, v58, v50
	v_max_u32_e32 v58, v54, v93
	v_min_u32_e32 v54, v54, v93
	v_max_u32_e32 v93, v92, v55
	v_min_u32_e32 v55, v92, v55
	v_max_u32_e32 v92, v52, v53
	v_min_u32_e32 v52, v52, v53
	v_max_u32_e32 v53, v1, v94
	v_min_u32_e32 v1, v1, v94
	v_max_u32_e32 v94, v59, v51
	v_min_u32_e32 v51, v59, v51
	v_max_u32_e32 v59, v49, v56
	v_min_u32_e32 v49, v49, v56
	v_max_u32_e32 v56, v57, v48
	v_min_u32_e32 v48, v57, v48
	v_max_u32_e32 v61, v63, v3
	v_min_u32_e32 v3, v63, v3
	v_max_u32_e32 v63, v62, v84
	v_min_u32_e32 v62, v62, v84
	v_max_u32_e32 v84, v5, v4
	v_min_u32_e32 v4, v5, v4
	v_max_u32_e32 v5, v2, v0
	v_min_u32_e32 v0, v2, v0
	v_max_u32_e32 v2, v12, v9
	v_min_u32_e32 v9, v12, v9
	v_max_u32_e32 v12, v10, v8
	v_min_u32_e32 v8, v10, v8
	v_max_u32_e32 v10, v11, v6
	v_min_u32_e32 v6, v11, v6
	v_max_u32_e32 v11, v13, v15
	v_min_u32_e32 v13, v13, v15
	v_max_u32_e32 v57, v60, v93
	v_min_u32_e32 v60, v60, v93
	v_max_u32_e32 v93, v58, v92
	v_min_u32_e32 v58, v58, v92
	v_max_u32_e32 v92, v50, v55
	v_min_u32_e32 v50, v50, v55
	v_max_u32_e32 v55, v54, v52
	v_min_u32_e32 v52, v54, v52
	v_max_u32_e32 v54, v49, v1
	v_min_u32_e32 v1, v49, v1
	v_max_u32_e32 v49, v48, v51
	v_min_u32_e32 v48, v48, v51
	v_max_u32_e32 v51, v59, v53
	v_min_u32_e32 v53, v59, v53
	v_max_u32_e32 v59, v56, v94
	v_min_u32_e32 v56, v56, v94
	v_max_u32_e32 v15, v61, v63
	v_min_u32_e32 v61, v61, v63
	v_max_u32_e32 v63, v3, v62
	v_min_u32_e32 v3, v3, v62
	v_max_u32_e32 v62, v84, v5
	v_min_u32_e32 v5, v84, v5
	v_max_u32_e32 v84, v4, v0
	v_min_u32_e32 v0, v4, v0
	v_max_u32_e32 v4, v8, v9
	v_min_u32_e32 v8, v8, v9
	v_max_u32_e32 v9, v12, v2
	v_min_u32_e32 v2, v12, v2
	v_max_u32_e32 v12, v13, v6
	v_min_u32_e32 v6, v13, v6
	v_max_u32_e32 v13, v11, v10
	v_min_u32_e32 v10, v11, v10
	v_max_u32_e32 v94, v57, v93
	v_min_u32_e32 v57, v57, v93
	v_max_u32_e32 v93, v60, v58
	v_min_u32_e32 v58, v60, v58
	v_max_u32_e32 v60, v92, v55
	v_min_u32_e32 v55, v92, v55
	v_max_u32_e32 v92, v50, v52
	v_min_u32_e32 v50, v50, v52
	v_max_u32_e32 v52, v48, v1
	v_min_u32_e32 v1, v48, v1
	v_max_u32_e32 v48, v49, v54
	v_min_u32_e32 v49, v49, v54
	v_max_u32_e32 v54, v56, v53
	v_min_u32_e32 v53, v56, v53
	v_max_u32_e32 v56, v59, v51
	v_min_u32_e32 v51, v59, v51
	v_max_u32_e32 v11, v15, v8
	v_min_u32_e32 v8, v15, v8
	v_max_u32_e32 v15, v61, v4
	v_min_u32_e32 v4, v61, v4
	v_max_u32_e32 v61, v63, v2
	v_min_u32_e32 v2, v63, v2
	v_max_u32_e32 v63, v3, v9
	v_min_u32_e32 v3, v3, v9
	v_max_u32_e32 v9, v62, v6
	v_min_u32_e32 v6, v62, v6
	v_max_u32_e32 v62, v5, v12
	v_min_u32_e32 v5, v5, v12
	v_max_u32_e32 v12, v84, v10
	v_min_u32_e32 v10, v84, v10
	v_max_u32_e32 v84, v0, v13
	v_min_u32_e32 v0, v0, v13
	v_max_u32_e32 v59, v94, v1
	v_min_u32_e32 v1, v94, v1
	v_max_u32_e32 v94, v57, v52
	v_min_u32_e32 v52, v57, v52
	v_max_u32_e32 v57, v93, v49
	v_min_u32_e32 v49, v93, v49
	v_max_u32_e32 v93, v58, v48
	v_min_u32_e32 v48, v58, v48
	v_max_u32_e32 v58, v60, v53
	v_min_u32_e32 v53, v60, v53
	v_max_u32_e32 v60, v55, v54
	v_min_u32_e32 v54, v55, v54
	v_max_u32_e32 v55, v92, v51
	v_min_u32_e32 v51, v92, v51
	v_max_u32_e32 v92, v50, v56
	v_min_u32_e32 v50, v50, v56
	v_max_u32_e32 v13, v11, v9
	v_min_u32_e32 v9, v11, v9
	v_max_u32_e32 v11, v15, v62
	v_min_u32_e32 v15, v15, v62
	v_max_u32_e32 v62, v61, v12
	v_min_u32_e32 v12, v61, v12
	v_max_u32_e32 v61, v63, v84
	v_min_u32_e32 v63, v63, v84
	v_max_u32_e32 v84, v8, v6
	v_min_u32_e32 v6, v8, v6
	v_max_u32_e32 v8, v4, v5
	v_min_u32_e32 v4, v4, v5
	v_max_u32_e32 v5, v2, v10
	v_min_u32_e32 v2, v2, v10
	v_max_u32_e32 v10, v3, v0
	v_min_u32_e32 v0, v3, v0
	v_max_u32_e32 v56, v59, v58
	v_min_u32_e32 v58, v59, v58
	v_max_u32_e32 v59, v94, v60
	v_min_u32_e32 v60, v94, v60
	v_max_u32_e32 v94, v57, v55
	v_min_u32_e32 v55, v57, v55
	v_max_u32_e32 v57, v93, v92
	v_min_u32_e32 v92, v93, v92
	v_max_u32_e32 v93, v1, v53
	v_min_u32_e32 v1, v1, v53
	v_max_u32_e32 v53, v52, v54
	v_min_u32_e32 v52, v52, v54
	v_max_u32_e32 v54, v49, v51
	v_min_u32_e32 v49, v49, v51
	v_max_u32_e32 v51, v48, v50
	v_min_u32_e32 v48, v48, v50
	v_max_u32_e32 v3, v13, v62
	v_min_u32_e32 v13, v13, v62
	v_max_u32_e32 v62, v11, v61
	v_min_u32_e32 v11, v11, v61
	v_max_u32_e32 v61, v9, v12
	v_min_u32_e32 v9, v9, v12
	v_max_u32_e32 v12, v15, v63
	v_min_u32_e32 v15, v15, v63
	v_max_u32_e32 v63, v84, v5
	v_min_u32_e32 v5, v84, v5
	v_max_u32_e32 v84, v8, v10
	v_min_u32_e32 v8, v8, v10
	v_max_u32_e32 v10, v6, v2
	v_min_u32_e32 v2, v6, v2
	v_max_u32_e32 v6, v4, v0
	v_min_u32_e32 v0, v4, v0
	v_max_u32_e32 v50, v56, v94
	v_min_u32_e32 v56, v56, v94
	v_max_u32_e32 v94, v59, v57
	v_min_u32_e32 v57, v59, v57
	v_max_u32_e32 v59, v58, v55
	v_min_u32_e32 v55, v58, v55
	v_max_u32_e32 v58, v60, v92
	v_min_u32_e32 v60, v60, v92
	v_max_u32_e32 v92, v93, v54
	v_min_u32_e32 v54, v93, v54
	v_max_u32_e32 v93, v53, v51
	v_min_u32_e32 v51, v53, v51
	v_max_u32_e32 v53, v1, v49
	v_min_u32_e32 v1, v1, v49
	v_max_u32_e32 v49, v52, v48
	v_min_u32_e32 v48, v52, v48
	v_min_u32_e32 v4, v3, v62
	v_min_u32_e32 v85, v13, v11
	v_min_u32_e32 v86, v61, v12
	v_min_u32_e32 v87, v9, v15
	v_min_u32_e32 v88, v63, v84
	v_min_u32_e32 v89, v5, v8
	v_min_u32_e32 v90, v10, v6
	v_min_u32_e32 v91, v2, v0
	v_min_u32_e32 v52, v50, v94
	v_min_u32_e32 v95, v56, v57
	v_min_u32_e32 v96, v59, v58
	v_min_u32_e32 v97, v55, v60
	v_min_u32_e32 v98, v92, v93
	v_min_u32_e32 v99, v54, v51
	v_min_u32_e32 v200, v53, v49
	v_min_u32_e32 v201, v1, v48
	v_max3_u32 v3, v3, v62, v201
	v_max3_u32 v1, v4, v1, v48
	v_max3_u32 v4, v13, v11, v200
	v_max3_u32 v11, v85, v53, v49
	v_max3_u32 v12, v61, v12, v99
	v_max3_u32 v13, v86, v54, v51
	v_max3_u32 v9, v9, v15, v98
	v_max3_u32 v15, v87, v92, v93
	v_max3_u32 v48, v63, v84, v97
	v_max3_u32 v49, v88, v55, v60
	v_max3_u32 v5, v5, v8, v96
	v_max3_u32 v8, v89, v59, v58
	v_max3_u32 v6, v10, v6, v95
	v_max3_u32 v10, v90, v56, v57
	v_max3_u32 v0, v2, v0, v52
	v_max3_u32 v2, v91, v50, v94
	v_max_u32_e32 v50, v3, v48
	v_min_u32_e32 v3, v3, v48
	v_max_u32_e32 v48, v1, v49
	v_min_u32_e32 v1, v1, v49
	v_max_u32_e32 v49, v4, v5
	v_min_u32_e32 v4, v4, v5
	v_max_u32_e32 v5, v11, v8
	v_min_u32_e32 v8, v11, v8
	v_max_u32_e32 v11, v12, v6
	v_min_u32_e32 v6, v12, v6
	v_max_u32_e32 v12, v13, v10
	v_min_u32_e32 v10, v13, v10
	v_max_u32_e32 v13, v9, v0
	v_min_u32_e32 v0, v9, v0
	v_max_u32_e32 v9, v15, v2
	v_min_u32_e32 v2, v15, v2
	v_max_u32_e32 v15, v50, v11
	v_min_u32_e32 v11, v50, v11
	v_max_u32_e32 v50, v48, v12
	v_min_u32_e32 v12, v48, v12
	v_max_u32_e32 v48, v49, v13
	v_min_u32_e32 v13, v49, v13
	v_max_u32_e32 v49, v5, v9
	v_min_u32_e32 v5, v5, v9
	v_max_u32_e32 v9, v3, v6
	v_min_u32_e32 v3, v3, v6
	v_max_u32_e32 v6, v1, v10
	v_min_u32_e32 v1, v1, v10
	v_max_u32_e32 v10, v4, v0
	v_min_u32_e32 v0, v4, v0
	v_max_u32_e32 v4, v8, v2
	v_min_u32_e32 v2, v8, v2
	v_max_u32_e32 v8, v15, v48
	v_min_u32_e32 v15, v15, v48
	v_max_u32_e32 v48, v50, v49
	v_min_u32_e32 v49, v50, v49
	v_max_u32_e32 v50, v11, v13
	v_min_u32_e32 v11, v11, v13
	v_max_u32_e32 v13, v12, v5
	v_min_u32_e32 v5, v12, v5
	v_max_u32_e32 v12, v9, v10
	v_min_u32_e32 v9, v9, v10
	v_max_u32_e32 v10, v6, v4
	v_min_u32_e32 v4, v6, v4
	v_max_u32_e32 v6, v3, v0
	v_min_u32_e32 v0, v3, v0
	v_max_u32_e32 v3, v1, v2
	v_min_u32_e32 v1, v1, v2
	v_max_u32_e32 v2, v8, v48
	v_min_u32_e32 v8, v8, v48
	v_max_u32_e32 v48, v15, v49
	v_min_u32_e32 v15, v15, v49
	v_max_u32_e32 v49, v50, v13
	v_min_u32_e32 v13, v50, v13
	v_max_u32_e32 v50, v11, v5
	v_min_u32_e32 v5, v11, v5
	v_max_u32_e32 v11, v12, v10
	v_min_u32_e32 v10, v12, v10
	v_max_u32_e32 v12, v9, v4
	v_min_u32_e32 v4, v9, v4
	v_max_u32_e32 v9, v6, v3
	v_min_u32_e32 v3, v6, v3
	v_max_u32_e32 v6, v0, v1
	v_min_u32_e32 v0, v0, v1
	ds_bpermute_b32 v1, v33, v2
	ds_bpermute_b32 v51, v33, v8
	ds_bpermute_b32 v52, v33, v48
	ds_bpermute_b32 v53, v33, v15
	ds_bpermute_b32 v54, v33, v49
	ds_bpermute_b32 v55, v33, v13
	ds_bpermute_b32 v56, v33, v50
	ds_bpermute_b32 v57, v33, v5
	ds_bpermute_b32 v58, v33, v11
	ds_bpermute_b32 v59, v33, v10
	ds_bpermute_b32 v60, v33, v12
	ds_bpermute_b32 v61, v33, v0
	ds_bpermute_b32 v62, v33, v6
	ds_bpermute_b32 v63, v33, v3
	ds_bpermute_b32 v84, v33, v9
	ds_bpermute_b32 v85, v33, v4
	s_waitcnt lgkmcnt(4)
	v_max_u32_e32 v2, v2, v61
	s_waitcnt lgkmcnt(3)
	v_max_u32_e32 v8, v8, v62
	s_waitcnt lgkmcnt(2)
	v_max_u32_e32 v48, v48, v63
	s_waitcnt lgkmcnt(1)
	v_max_u32_e32 v15, v15, v84
	s_waitcnt lgkmcnt(0)
	v_max_u32_e32 v49, v49, v85
	v_max_u32_e32 v13, v13, v60
	v_max_u32_e32 v50, v50, v59
	v_max_u32_e32 v5, v5, v58
	v_max_u32_e32 v11, v11, v57
	v_max_u32_e32 v10, v10, v56
	v_max_u32_e32 v12, v12, v55
	v_max_u32_e32 v4, v4, v54
	v_max_u32_e32 v9, v9, v53
	v_max_u32_e32 v3, v3, v52
	v_max_u32_e32 v6, v6, v51
	v_max_u32_e32 v0, v0, v1
	v_max_u32_e32 v1, v2, v11
	v_min_u32_e32 v2, v2, v11
	v_max_u32_e32 v11, v8, v10
	v_min_u32_e32 v8, v8, v10
	v_max_u32_e32 v10, v48, v12
	v_min_u32_e32 v12, v48, v12
	v_max_u32_e32 v48, v15, v4
	v_min_u32_e32 v4, v15, v4
	v_max_u32_e32 v15, v49, v9
	v_min_u32_e32 v9, v49, v9
	v_max_u32_e32 v49, v13, v3
	v_min_u32_e32 v3, v13, v3
	v_max_u32_e32 v13, v50, v6
	v_min_u32_e32 v6, v50, v6
	v_max_u32_e32 v50, v5, v0
	v_min_u32_e32 v0, v5, v0
	v_max_u32_e32 v5, v1, v15
	v_min_u32_e32 v1, v1, v15
	v_max_u32_e32 v15, v11, v49
	v_min_u32_e32 v11, v11, v49
	v_max_u32_e32 v49, v10, v13
	v_min_u32_e32 v10, v10, v13
	v_max_u32_e32 v13, v48, v50
	v_min_u32_e32 v48, v48, v50
	v_max_u32_e32 v50, v2, v9
	v_min_u32_e32 v2, v2, v9
	v_max_u32_e32 v9, v8, v3
	v_min_u32_e32 v3, v8, v3
	v_max_u32_e32 v8, v12, v6
	v_min_u32_e32 v6, v12, v6
	v_max_u32_e32 v12, v4, v0
	v_min_u32_e32 v0, v4, v0
	v_max_u32_e32 v4, v5, v49
	v_min_u32_e32 v5, v5, v49
	v_max_u32_e32 v49, v15, v13
	v_min_u32_e32 v13, v15, v13
	v_max_u32_e32 v15, v1, v10
	v_min_u32_e32 v1, v1, v10
	v_max_u32_e32 v10, v11, v48
	v_min_u32_e32 v11, v11, v48
	v_max_u32_e32 v48, v50, v8
	v_max_u32_e32 v51, v9, v12
	v_min_u32_e32 v50, v50, v8
	v_min_u32_e32 v9, v9, v12
	v_max_u32_e32 v12, v2, v6
	v_min_u32_e32 v2, v2, v6
	v_max_u32_e32 v6, v3, v0
	v_min_u32_e32 v0, v3, v0
	v_max_u32_e32 v8, v4, v49
	v_min_u32_e32 v3, v4, v49
	v_max_u32_e32 v4, v5, v13
	v_min_u32_e32 v5, v5, v13
	v_max_u32_e32 v13, v15, v10
	v_min_u32_e32 v10, v15, v10
	v_max_u32_e32 v15, v1, v11
	v_min_u32_e32 v11, v1, v11
	v_max_u32_e32 v1, v48, v51
	v_cndmask_b32_e64 v1, v1, v8, s[10:11]
	v_min_u32_e32 v48, v48, v51
	v_max_u32_e32 v49, v50, v9
	v_min_u32_e32 v9, v50, v9
	v_max_u32_e32 v50, v12, v6
	v_min_u32_e32 v6, v12, v6
	v_max_u32_e32 v12, v2, v0
	v_min_u32_e32 v51, v2, v0
	v_bitop3_b32 v2, v1, 16, v1 bitop3:0xc
	v_bitop3_b32 v54, v1, 1, v1 bitop3:0xc
	v_bitop3_b32 v52, v1, 32, v1 bitop3:0xc
	v_bitop3_b32 v55, v1, 2, v1 bitop3:0xc
	v_cmp_eq_u32_e32 vcc, 0, v2
	v_cmp_eq_u32_e64 s[0:1], 0, v54
	v_bitop3_b32 v53, v1, 64, v1 bitop3:0xc
	v_cndmask_b32_e32 v2, v29, v34, vcc
	v_cndmask_b32_e64 v54, v22, v17, s[0:1]
	v_cndmask_b32_e32 v58, v27, v28, vcc
	v_cndmask_b32_e64 v59, v23, v18, s[0:1]
	v_cndmask_b32_e32 v60, v14, v7, vcc
	v_cndmask_b32_e64 v61, v24, v19, s[0:1]
	v_cndmask_b32_e32 v62, v35, v36, vcc
	v_cndmask_b32_e64 v63, v25, v20, s[0:1]
	v_cndmask_b32_e32 v84, v45, v47, vcc
	v_cndmask_b32_e64 v85, v26, v21, s[0:1]
	v_cndmask_b32_e32 v86, v41, v43, vcc
	v_cndmask_b32_e64 v87, v44, v46, s[0:1]
	v_cndmask_b32_e32 v88, v37, v39, vcc
	v_cndmask_b32_e64 v89, v40, v42, s[0:1]
	v_cndmask_b32_e32 v90, v30, v31, vcc
	v_cndmask_b32_e64 v91, v16, v38, s[0:1]
	v_cmp_eq_u32_e32 vcc, 0, v52
	v_cmp_eq_u32_e64 s[0:1], 0, v55
	v_bitop3_b32 v56, v1, 4, v1 bitop3:0xc
	v_cndmask_b32_e32 v2, v58, v2, vcc
	v_cndmask_b32_e64 v52, v59, v54, s[0:1]
	v_cndmask_b32_e32 v54, v62, v60, vcc
	v_cndmask_b32_e32 v58, v86, v84, vcc
	v_cndmask_b32_e32 v60, v90, v88, vcc
	v_cmp_eq_u32_e32 vcc, 0, v53
	v_bitop3_b32 v0, v1, s16, v1 bitop3:0xc
	v_cndmask_b32_e64 v55, v63, v61, s[0:1]
	v_cndmask_b32_e64 v59, v87, v85, s[0:1]
	v_cndmask_b32_e64 v61, v91, v89, s[0:1]
	v_cndmask_b32_e32 v2, v54, v2, vcc
	v_cndmask_b32_e32 v53, v60, v58, vcc
	v_cmp_eq_u32_e32 vcc, 0, v56
	v_bitop3_b32 v57, v1, 8, v1 bitop3:0xc
	v_cndmask_b32_e64 v6, v6, v10, s[10:11]
	v_cndmask_b32_e32 v52, v55, v52, vcc
	v_cndmask_b32_e32 v54, v61, v59, vcc
	v_cmp_gt_u32_e32 vcc, s17, v0
	v_bitop3_b32 v10, v6, 32, v6 bitop3:0xc
	s_nop 0
	v_cndmask_b32_e32 v0, v53, v2, vcc
	v_cmp_eq_u32_e32 vcc, 0, v57
	v_lshlrev_b32_e32 v0, 7, v0
	v_and_b32_e32 v0, 0x3f80, v0
	v_cndmask_b32_e32 v2, v54, v52, vcc
	v_and_b32_e32 v2, 0x7f, v2
	v_bitop3_b32 v0, v0, s92, v2 bitop3:0x36
	v_and_b32_e32 v2, 0x7fffff00, v1
	v_bitop3_b32 v52, v1, s16, v1 bitop3:0xcf
	v_cmp_gt_i32_e32 vcc, 0, v1
	s_nop 1
	v_cndmask_b32_e32 v52, v52, v2, vcc
	v_cndmask_b32_e64 v2, v48, v3, s[10:11]
	v_bitop3_b32 v3, v2, 16, v2 bitop3:0xc
	v_bitop3_b32 v54, v2, 1, v2 bitop3:0xc
	v_bitop3_b32 v48, v2, 32, v2 bitop3:0xc
	v_bitop3_b32 v55, v2, 2, v2 bitop3:0xc
	v_cmp_eq_u32_e32 vcc, 0, v3
	v_cmp_eq_u32_e64 s[0:1], 0, v54
	v_bitop3_b32 v53, v2, 64, v2 bitop3:0xc
	v_cndmask_b32_e32 v3, v29, v34, vcc
	v_cndmask_b32_e64 v54, v22, v17, s[0:1]
	v_cndmask_b32_e32 v58, v27, v28, vcc
	v_cndmask_b32_e64 v59, v23, v18, s[0:1]
	v_cndmask_b32_e32 v60, v14, v7, vcc
	v_cndmask_b32_e64 v61, v24, v19, s[0:1]
	v_cndmask_b32_e32 v62, v35, v36, vcc
	v_cndmask_b32_e64 v63, v25, v20, s[0:1]
	v_cndmask_b32_e32 v84, v45, v47, vcc
	v_cndmask_b32_e64 v85, v26, v21, s[0:1]
	v_cndmask_b32_e32 v86, v41, v43, vcc
	v_cndmask_b32_e64 v87, v44, v46, s[0:1]
	v_cndmask_b32_e32 v88, v37, v39, vcc
	v_cndmask_b32_e64 v89, v40, v42, s[0:1]
	v_cndmask_b32_e32 v90, v30, v31, vcc
	v_cndmask_b32_e64 v91, v16, v38, s[0:1]
	v_cmp_eq_u32_e32 vcc, 0, v48
	v_cmp_eq_u32_e64 s[0:1], 0, v55
	v_bitop3_b32 v56, v2, 4, v2 bitop3:0xc
	v_cndmask_b32_e32 v3, v58, v3, vcc
	v_cndmask_b32_e64 v48, v59, v54, s[0:1]
	v_cndmask_b32_e32 v54, v62, v60, vcc
	v_cndmask_b32_e32 v58, v86, v84, vcc
	v_cndmask_b32_e32 v60, v90, v88, vcc
	v_cmp_eq_u32_e32 vcc, 0, v53
	v_bitop3_b32 v1, v2, s16, v2 bitop3:0xc
	v_cndmask_b32_e64 v55, v63, v61, s[0:1]
	v_cndmask_b32_e64 v59, v87, v85, s[0:1]
	v_cndmask_b32_e64 v61, v91, v89, s[0:1]
	v_cndmask_b32_e32 v3, v54, v3, vcc
	v_cndmask_b32_e32 v53, v60, v58, vcc
	v_cmp_eq_u32_e32 vcc, 0, v56
	v_bitop3_b32 v57, v2, 8, v2 bitop3:0xc
	s_nop 0
	v_cndmask_b32_e32 v48, v55, v48, vcc
	v_cndmask_b32_e32 v54, v61, v59, vcc
	v_cmp_gt_u32_e32 vcc, s17, v1
	s_nop 1
	v_cndmask_b32_e32 v1, v53, v3, vcc
	v_cmp_eq_u32_e32 vcc, 0, v57
	v_lshlrev_b32_e32 v1, 7, v1
	v_and_b32_e32 v1, 0x3f80, v1
	v_cndmask_b32_e32 v3, v54, v48, vcc
	v_and_b32_e32 v3, 0x7f, v3
	v_bitop3_b32 v1, v1, s92, v3 bitop3:0x36
	v_and_b32_e32 v3, 0x7fffff00, v2
	v_bitop3_b32 v48, v2, s16, v2 bitop3:0xcf
	v_cmp_gt_i32_e32 vcc, 0, v2
	s_nop 1
	v_cndmask_b32_e32 v48, v48, v3, vcc
	v_cndmask_b32_e64 v3, v49, v4, s[10:11]
	v_bitop3_b32 v4, v3, 16, v3 bitop3:0xc
	v_bitop3_b32 v54, v3, 1, v3 bitop3:0xc
	v_bitop3_b32 v49, v3, 32, v3 bitop3:0xc
	v_bitop3_b32 v55, v3, 2, v3 bitop3:0xc
	v_cmp_eq_u32_e32 vcc, 0, v4
	v_cmp_eq_u32_e64 s[0:1], 0, v54
	v_bitop3_b32 v53, v3, 64, v3 bitop3:0xc
	v_cndmask_b32_e32 v4, v29, v34, vcc
	v_cndmask_b32_e64 v54, v22, v17, s[0:1]
	v_cndmask_b32_e32 v58, v27, v28, vcc
	v_cndmask_b32_e64 v59, v23, v18, s[0:1]
	v_cndmask_b32_e32 v60, v14, v7, vcc
	v_cndmask_b32_e64 v61, v24, v19, s[0:1]
	v_cndmask_b32_e32 v62, v35, v36, vcc
	v_cndmask_b32_e64 v63, v25, v20, s[0:1]
	v_cndmask_b32_e32 v84, v45, v47, vcc
	v_cndmask_b32_e64 v85, v26, v21, s[0:1]
	v_cndmask_b32_e32 v86, v41, v43, vcc
	v_cndmask_b32_e64 v87, v44, v46, s[0:1]
	v_cndmask_b32_e32 v88, v37, v39, vcc
	v_cndmask_b32_e64 v89, v40, v42, s[0:1]
	v_cndmask_b32_e32 v90, v30, v31, vcc
	v_cndmask_b32_e64 v91, v16, v38, s[0:1]
	v_cmp_eq_u32_e32 vcc, 0, v49
	v_cmp_eq_u32_e64 s[0:1], 0, v55
	v_bitop3_b32 v56, v3, 4, v3 bitop3:0xc
	v_cndmask_b32_e32 v4, v58, v4, vcc
	v_cndmask_b32_e64 v49, v59, v54, s[0:1]
	v_cndmask_b32_e32 v54, v62, v60, vcc
	v_cndmask_b32_e32 v58, v86, v84, vcc
	v_cndmask_b32_e32 v60, v90, v88, vcc
	v_cmp_eq_u32_e32 vcc, 0, v53
	v_bitop3_b32 v2, v3, s16, v3 bitop3:0xc
	v_cndmask_b32_e64 v55, v63, v61, s[0:1]
	v_cndmask_b32_e64 v59, v87, v85, s[0:1]
	v_cndmask_b32_e64 v61, v91, v89, s[0:1]
	v_cndmask_b32_e32 v4, v54, v4, vcc
	v_cndmask_b32_e32 v53, v60, v58, vcc
	v_cmp_eq_u32_e32 vcc, 0, v56
	v_bitop3_b32 v57, v3, 8, v3 bitop3:0xc
	s_nop 0
	v_cndmask_b32_e32 v49, v55, v49, vcc
	v_cndmask_b32_e32 v54, v61, v59, vcc
	v_cmp_gt_u32_e32 vcc, s17, v2
	s_nop 1
	v_cndmask_b32_e32 v2, v53, v4, vcc
	v_cmp_eq_u32_e32 vcc, 0, v57
	v_lshlrev_b32_e32 v2, 7, v2
	v_and_b32_e32 v2, 0x3f80, v2
	v_cndmask_b32_e32 v4, v54, v49, vcc
	v_and_b32_e32 v4, 0x7f, v4
	v_bitop3_b32 v2, v2, s92, v4 bitop3:0x36
	v_and_b32_e32 v4, 0x7fffff00, v3
	v_bitop3_b32 v49, v3, s16, v3 bitop3:0xcf
	v_cmp_gt_i32_e32 vcc, 0, v3
	s_nop 1
	v_cndmask_b32_e32 v49, v49, v4, vcc
	v_cndmask_b32_e64 v4, v9, v5, s[10:11]
	v_bitop3_b32 v5, v4, 16, v4 bitop3:0xc
	v_bitop3_b32 v54, v4, 1, v4 bitop3:0xc
	v_bitop3_b32 v9, v4, 32, v4 bitop3:0xc
	v_bitop3_b32 v55, v4, 2, v4 bitop3:0xc
	v_cmp_eq_u32_e32 vcc, 0, v5
	v_cmp_eq_u32_e64 s[0:1], 0, v54
	v_bitop3_b32 v53, v4, 64, v4 bitop3:0xc
	v_cndmask_b32_e32 v5, v29, v34, vcc
	v_cndmask_b32_e64 v54, v22, v17, s[0:1]
	v_cndmask_b32_e32 v58, v27, v28, vcc
	v_cndmask_b32_e64 v59, v23, v18, s[0:1]
	v_cndmask_b32_e32 v60, v14, v7, vcc
	v_cndmask_b32_e64 v61, v24, v19, s[0:1]
	v_cndmask_b32_e32 v62, v35, v36, vcc
	v_cndmask_b32_e64 v63, v25, v20, s[0:1]
	v_cndmask_b32_e32 v84, v45, v47, vcc
	v_cndmask_b32_e64 v85, v26, v21, s[0:1]
	v_cndmask_b32_e32 v86, v41, v43, vcc
	v_cndmask_b32_e64 v87, v44, v46, s[0:1]
	v_cndmask_b32_e32 v88, v37, v39, vcc
	v_cndmask_b32_e64 v89, v40, v42, s[0:1]
	v_cndmask_b32_e32 v90, v30, v31, vcc
	v_cndmask_b32_e64 v91, v16, v38, s[0:1]
	v_cmp_eq_u32_e32 vcc, 0, v9
	v_cmp_eq_u32_e64 s[0:1], 0, v55
	v_bitop3_b32 v56, v4, 4, v4 bitop3:0xc
	v_cndmask_b32_e32 v5, v58, v5, vcc
	v_cndmask_b32_e64 v9, v59, v54, s[0:1]
	v_cndmask_b32_e32 v54, v62, v60, vcc
	v_cndmask_b32_e32 v58, v86, v84, vcc
	v_cndmask_b32_e32 v60, v90, v88, vcc
	v_cmp_eq_u32_e32 vcc, 0, v53
	v_bitop3_b32 v3, v4, s16, v4 bitop3:0xc
	v_cndmask_b32_e64 v55, v63, v61, s[0:1]
	v_cndmask_b32_e64 v59, v87, v85, s[0:1]
	v_cndmask_b32_e64 v61, v91, v89, s[0:1]
	v_cndmask_b32_e32 v5, v54, v5, vcc
	v_cndmask_b32_e32 v53, v60, v58, vcc
	v_cmp_eq_u32_e32 vcc, 0, v56
	v_bitop3_b32 v57, v4, 8, v4 bitop3:0xc
	s_nop 0
	v_cndmask_b32_e32 v9, v55, v9, vcc
	v_cndmask_b32_e32 v54, v61, v59, vcc
	v_cmp_gt_u32_e32 vcc, s17, v3
	s_nop 1
	v_cndmask_b32_e32 v3, v53, v5, vcc
	v_cmp_eq_u32_e32 vcc, 0, v57
	v_lshlrev_b32_e32 v3, 7, v3
	v_and_b32_e32 v3, 0x3f80, v3
	v_cndmask_b32_e32 v5, v54, v9, vcc
	v_and_b32_e32 v5, 0x7f, v5
	v_bitop3_b32 v3, v3, s92, v5 bitop3:0x36
	v_and_b32_e32 v5, 0x7fffff00, v4
	v_bitop3_b32 v9, v4, s16, v4 bitop3:0xcf
	v_cmp_gt_i32_e32 vcc, 0, v4
	s_nop 1
	v_cndmask_b32_e32 v53, v9, v5, vcc
	v_cndmask_b32_e64 v5, v50, v13, s[10:11]
	v_bitop3_b32 v9, v5, 16, v5 bitop3:0xc
	v_bitop3_b32 v54, v5, 1, v5 bitop3:0xc
	v_bitop3_b32 v13, v5, 32, v5 bitop3:0xc
	v_bitop3_b32 v55, v5, 2, v5 bitop3:0xc
	v_cmp_eq_u32_e32 vcc, 0, v9
	v_cmp_eq_u32_e64 s[0:1], 0, v54
	v_bitop3_b32 v50, v5, 64, v5 bitop3:0xc
	v_cndmask_b32_e32 v9, v29, v34, vcc
	v_cndmask_b32_e64 v54, v22, v17, s[0:1]
	v_cndmask_b32_e32 v58, v27, v28, vcc
	v_cndmask_b32_e64 v59, v23, v18, s[0:1]
	v_cndmask_b32_e32 v60, v14, v7, vcc
	v_cndmask_b32_e64 v61, v24, v19, s[0:1]
	v_cndmask_b32_e32 v62, v35, v36, vcc
	v_cndmask_b32_e64 v63, v25, v20, s[0:1]
	v_cndmask_b32_e32 v84, v45, v47, vcc
	v_cndmask_b32_e64 v85, v26, v21, s[0:1]
	v_cndmask_b32_e32 v86, v41, v43, vcc
	v_cndmask_b32_e64 v87, v44, v46, s[0:1]
	v_cndmask_b32_e32 v88, v37, v39, vcc
	v_cndmask_b32_e64 v89, v40, v42, s[0:1]
	v_cndmask_b32_e32 v90, v30, v31, vcc
	v_cndmask_b32_e64 v91, v16, v38, s[0:1]
	v_cmp_eq_u32_e32 vcc, 0, v13
	v_cmp_eq_u32_e64 s[0:1], 0, v55
	v_bitop3_b32 v56, v5, 4, v5 bitop3:0xc
	v_cndmask_b32_e32 v9, v58, v9, vcc
	v_cndmask_b32_e64 v13, v59, v54, s[0:1]
	v_cndmask_b32_e32 v54, v62, v60, vcc
	v_cndmask_b32_e32 v58, v86, v84, vcc
	v_cndmask_b32_e32 v60, v90, v88, vcc
	v_cmp_eq_u32_e32 vcc, 0, v50
	v_bitop3_b32 v4, v5, s16, v5 bitop3:0xc
	v_cndmask_b32_e64 v55, v63, v61, s[0:1]
	v_cndmask_b32_e64 v59, v87, v85, s[0:1]
	v_cndmask_b32_e64 v61, v91, v89, s[0:1]
	v_cndmask_b32_e32 v9, v54, v9, vcc
	v_cndmask_b32_e32 v50, v60, v58, vcc
	v_cmp_eq_u32_e32 vcc, 0, v56
	v_bitop3_b32 v57, v5, 8, v5 bitop3:0xc
	v_bitop3_b32 v56, v6, 4, v6 bitop3:0xc
	v_cndmask_b32_e32 v13, v55, v13, vcc
	v_cndmask_b32_e32 v54, v61, v59, vcc
	v_cmp_gt_u32_e32 vcc, s17, v4
	v_bitop3_b32 v55, v6, 2, v6 bitop3:0xc
	s_nop 0
	v_cndmask_b32_e32 v4, v50, v9, vcc
	v_cmp_eq_u32_e32 vcc, 0, v57
	v_lshlrev_b32_e32 v4, 7, v4
	v_and_b32_e32 v4, 0x3f80, v4
	v_cndmask_b32_e32 v9, v54, v13, vcc
	v_and_b32_e32 v9, 0x7f, v9
	v_bitop3_b32 v4, v4, s92, v9 bitop3:0x36
	v_and_b32_e32 v9, 0x7fffff00, v5
	v_bitop3_b32 v13, v5, s16, v5 bitop3:0xcf
	v_cmp_gt_i32_e32 vcc, 0, v5
	v_bitop3_b32 v54, v6, 1, v6 bitop3:0xc
	v_cmp_eq_u32_e64 s[0:1], 0, v54
	v_cndmask_b32_e32 v13, v13, v9, vcc
	v_bitop3_b32 v9, v6, 16, v6 bitop3:0xc
	v_cmp_eq_u32_e32 vcc, 0, v9
	v_bitop3_b32 v50, v6, 64, v6 bitop3:0xc
	v_cndmask_b32_e64 v54, v22, v17, s[0:1]
	v_cndmask_b32_e32 v9, v29, v34, vcc
	v_cndmask_b32_e32 v58, v27, v28, vcc
	v_cndmask_b32_e64 v59, v23, v18, s[0:1]
	v_cndmask_b32_e32 v60, v14, v7, vcc
	v_cndmask_b32_e64 v61, v24, v19, s[0:1]
	v_cndmask_b32_e32 v62, v35, v36, vcc
	v_cndmask_b32_e64 v63, v25, v20, s[0:1]
	v_cndmask_b32_e32 v84, v45, v47, vcc
	v_cndmask_b32_e64 v85, v26, v21, s[0:1]
	v_cndmask_b32_e32 v86, v41, v43, vcc
	v_cndmask_b32_e64 v87, v44, v46, s[0:1]
	v_cndmask_b32_e32 v88, v37, v39, vcc
	v_cndmask_b32_e64 v89, v40, v42, s[0:1]
	v_cndmask_b32_e32 v90, v30, v31, vcc
	v_cndmask_b32_e64 v91, v16, v38, s[0:1]
	v_cmp_eq_u32_e32 vcc, 0, v10
	v_cmp_eq_u32_e64 s[0:1], 0, v55
	v_bitop3_b32 v5, v6, s16, v6 bitop3:0xc
	v_cndmask_b32_e32 v9, v58, v9, vcc
	v_cndmask_b32_e64 v10, v59, v54, s[0:1]
	v_cndmask_b32_e32 v54, v62, v60, vcc
	v_cndmask_b32_e32 v58, v86, v84, vcc
	v_cndmask_b32_e32 v60, v90, v88, vcc
	v_cmp_eq_u32_e32 vcc, 0, v50
	v_cndmask_b32_e64 v55, v63, v61, s[0:1]
	v_cndmask_b32_e64 v59, v87, v85, s[0:1]
	v_cndmask_b32_e64 v61, v91, v89, s[0:1]
	v_cndmask_b32_e32 v9, v54, v9, vcc
	v_cndmask_b32_e32 v50, v60, v58, vcc
	v_cmp_eq_u32_e32 vcc, 0, v56
	v_bitop3_b32 v57, v6, 8, v6 bitop3:0xc
	s_nop 0
	v_cndmask_b32_e32 v10, v55, v10, vcc
	v_cndmask_b32_e32 v54, v61, v59, vcc
	v_cmp_gt_u32_e32 vcc, s17, v5
	s_nop 1
	v_cndmask_b32_e32 v5, v50, v9, vcc
	v_cmp_eq_u32_e32 vcc, 0, v57
	v_lshlrev_b32_e32 v5, 7, v5
	v_and_b32_e32 v5, 0x3f80, v5
	v_cndmask_b32_e32 v9, v54, v10, vcc
	v_and_b32_e32 v9, 0x7f, v9
	v_bitop3_b32 v5, v5, s92, v9 bitop3:0x36
	v_and_b32_e32 v9, 0x7fffff00, v6
	v_bitop3_b32 v10, v6, s16, v6 bitop3:0xcf
	v_cmp_gt_i32_e32 vcc, 0, v6
	s_nop 1
	v_cndmask_b32_e32 v50, v10, v9, vcc
	v_cndmask_b32_e64 v9, v12, v15, s[10:11]
	v_bitop3_b32 v10, v9, 16, v9 bitop3:0xc
	v_bitop3_b32 v54, v9, 1, v9 bitop3:0xc
	v_bitop3_b32 v12, v9, 32, v9 bitop3:0xc
	v_bitop3_b32 v55, v9, 2, v9 bitop3:0xc
	v_cmp_eq_u32_e32 vcc, 0, v10
	v_cmp_eq_u32_e64 s[0:1], 0, v54
	v_bitop3_b32 v15, v9, 64, v9 bitop3:0xc
	v_cndmask_b32_e32 v10, v29, v34, vcc
	v_cndmask_b32_e64 v54, v22, v17, s[0:1]
	v_cndmask_b32_e32 v58, v27, v28, vcc
	v_cndmask_b32_e64 v59, v23, v18, s[0:1]
	v_cndmask_b32_e32 v60, v14, v7, vcc
	v_cndmask_b32_e64 v61, v24, v19, s[0:1]
	v_cndmask_b32_e32 v62, v35, v36, vcc
	v_cndmask_b32_e64 v63, v25, v20, s[0:1]
	v_cndmask_b32_e32 v84, v45, v47, vcc
	v_cndmask_b32_e64 v85, v26, v21, s[0:1]
	v_cndmask_b32_e32 v86, v41, v43, vcc
	v_cndmask_b32_e64 v87, v44, v46, s[0:1]
	v_cndmask_b32_e32 v88, v37, v39, vcc
	v_cndmask_b32_e64 v89, v40, v42, s[0:1]
	v_cndmask_b32_e32 v90, v30, v31, vcc
	v_cndmask_b32_e64 v91, v16, v38, s[0:1]
	v_cmp_eq_u32_e32 vcc, 0, v12
	v_cmp_eq_u32_e64 s[0:1], 0, v55
	v_bitop3_b32 v56, v9, 4, v9 bitop3:0xc
	v_cndmask_b32_e32 v10, v58, v10, vcc
	v_cndmask_b32_e64 v12, v59, v54, s[0:1]
	v_cndmask_b32_e32 v54, v62, v60, vcc
	v_cndmask_b32_e32 v58, v86, v84, vcc
	v_cndmask_b32_e32 v60, v90, v88, vcc
	v_cmp_eq_u32_e32 vcc, 0, v15
	v_bitop3_b32 v6, v9, s16, v9 bitop3:0xc
	v_cndmask_b32_e64 v55, v63, v61, s[0:1]
	v_cndmask_b32_e64 v59, v87, v85, s[0:1]
	v_cndmask_b32_e64 v61, v91, v89, s[0:1]
	v_cndmask_b32_e32 v10, v54, v10, vcc
	v_cndmask_b32_e32 v15, v60, v58, vcc
	v_cmp_eq_u32_e32 vcc, 0, v56
	v_bitop3_b32 v57, v9, 8, v9 bitop3:0xc
	s_nop 0
	v_cndmask_b32_e32 v12, v55, v12, vcc
	v_cndmask_b32_e32 v54, v61, v59, vcc
	v_cmp_gt_u32_e32 vcc, s17, v6
	s_nop 1
	v_cndmask_b32_e32 v6, v15, v10, vcc
	v_cmp_eq_u32_e32 vcc, 0, v57
	v_lshlrev_b32_e32 v6, 7, v6
	v_and_b32_e32 v6, 0x3f80, v6
	v_cndmask_b32_e32 v10, v54, v12, vcc
	v_and_b32_e32 v10, 0x7f, v10
	v_bitop3_b32 v6, v6, s92, v10 bitop3:0x36
	v_and_b32_e32 v10, 0x7fffff00, v9
	v_bitop3_b32 v12, v9, s16, v9 bitop3:0xcf
	v_cmp_gt_i32_e32 vcc, 0, v9
	v_cndmask_b32_e64 v9, v51, v11, s[10:11]
	v_bitop3_b32 v54, v9, 1, v9 bitop3:0xc
	v_cndmask_b32_e32 v15, v12, v10, vcc
	v_bitop3_b32 v10, v9, 16, v9 bitop3:0xc
	v_bitop3_b32 v11, v9, 32, v9 bitop3:0xc
	v_bitop3_b32 v55, v9, 2, v9 bitop3:0xc
	v_cmp_eq_u32_e32 vcc, 0, v10
	v_cmp_eq_u32_e64 s[0:1], 0, v54
	v_bitop3_b32 v12, v9, 64, v9 bitop3:0xc
	v_cndmask_b32_e32 v10, v29, v34, vcc
	v_cndmask_b32_e64 v17, v22, v17, s[0:1]
	v_cndmask_b32_e32 v22, v27, v28, vcc
	v_cndmask_b32_e64 v18, v23, v18, s[0:1]
	v_cndmask_b32_e32 v7, v14, v7, vcc
	v_cndmask_b32_e64 v14, v24, v19, s[0:1]
	v_cndmask_b32_e32 v19, v35, v36, vcc
	v_cndmask_b32_e64 v20, v25, v20, s[0:1]
	v_cndmask_b32_e32 v23, v45, v47, vcc
	v_cndmask_b32_e64 v21, v26, v21, s[0:1]
	v_cndmask_b32_e32 v24, v41, v43, vcc
	v_cndmask_b32_e64 v25, v44, v46, s[0:1]
	v_cndmask_b32_e32 v26, v37, v39, vcc
	v_cndmask_b32_e64 v27, v40, v42, s[0:1]
	v_cndmask_b32_e32 v28, v30, v31, vcc
	v_cndmask_b32_e64 v16, v16, v38, s[0:1]
	v_cmp_eq_u32_e32 vcc, 0, v11
	v_cmp_eq_u32_e64 s[0:1], 0, v55
	v_bitop3_b32 v56, v9, 4, v9 bitop3:0xc
	v_cndmask_b32_e32 v10, v22, v10, vcc
	v_cndmask_b32_e64 v11, v18, v17, s[0:1]
	v_cndmask_b32_e32 v7, v19, v7, vcc
	v_cndmask_b32_e32 v17, v24, v23, vcc
	v_cndmask_b32_e32 v19, v28, v26, vcc
	v_cmp_eq_u32_e32 vcc, 0, v12
	v_cndmask_b32_e64 v14, v20, v14, s[0:1]
	v_cndmask_b32_e64 v18, v25, v21, s[0:1]
	v_cndmask_b32_e32 v7, v7, v10, vcc
	v_cndmask_b32_e32 v17, v19, v17, vcc
	v_cmp_eq_u32_e32 vcc, 0, v56
	v_cndmask_b32_e64 v16, v16, v27, s[0:1]
	v_and_b32_e32 v10, 0xffffff00, v8
	v_cndmask_b32_e32 v19, v14, v11, vcc
	v_and_b32_e32 v11, 0xffffff00, v9
	v_cndmask_b32_e32 v16, v16, v18, vcc
	v_and_b32_e32 v14, 0x7fffff00, v9
	v_xor_b32_e32 v11, -1, v11
	v_cmp_gt_i32_e32 vcc, 0, v9
	v_and_b32_e32 v12, 0x7fffff00, v8
	v_xor_b32_e32 v10, -1, v10
	v_cndmask_b32_e32 v18, v11, v14, vcc
	v_cmp_gt_i32_e32 vcc, 0, v8
	v_bitop3_b32 v51, v9, s16, v9 bitop3:0xc
	v_bitop3_b32 v57, v9, 8, v9 bitop3:0xc
	v_cndmask_b32_e32 v20, v10, v12, vcc
	v_sub_f32_e32 v8, v52, v20
	v_mul_f32_e32 v8, 0x3fb8aa3b, v8
	v_sub_f32_e32 v9, v48, v20
	v_exp_f32_e32 v8, v8
	v_mul_f32_e32 v9, 0x3fb8aa3b, v9
	v_sub_f32_e32 v10, v49, v20
	v_exp_f32_e32 v9, v9
	v_mul_f32_e32 v10, 0x3fb8aa3b, v10
	v_sub_f32_e32 v11, v53, v20
	v_exp_f32_e32 v10, v10
	v_mul_f32_e32 v11, 0x3fb8aa3b, v11
	v_exp_f32_e32 v11, v11
	v_add_f32_e32 v12, 0, v8
	v_add_f32_e32 v12, v9, v12
	v_add_f32_e32 v12, v10, v12
	v_add_f32_e32 v21, v11, v12
	v_sub_f32_e32 v12, v13, v20
	v_mul_f32_e32 v12, 0x3fb8aa3b, v12
	v_sub_f32_e32 v13, v50, v20
	v_exp_f32_e32 v12, v12
	v_mul_f32_e32 v13, 0x3fb8aa3b, v13
	v_sub_f32_e32 v14, v15, v20
	v_exp_f32_e32 v13, v13
	v_mul_f32_e32 v14, 0x3fb8aa3b, v14
	v_sub_f32_e32 v15, v18, v20
	v_exp_f32_e32 v14, v14
	v_mul_f32_e32 v15, 0x3fb8aa3b, v15
	v_exp_f32_e32 v15, v15
	v_add_f32_e32 v18, v12, v21
	v_add_f32_e32 v18, v13, v18
	v_add_f32_e32 v18, v14, v18
	v_add_f32_e32 v18, v15, v18
	ds_bpermute_b32 v20, v33, v18
	v_cmp_gt_u32_e32 vcc, s17, v51
	v_ashrrev_i32_e32 v33, 31, v32
	s_nop 0
	v_cndmask_b32_e32 v7, v17, v7, vcc
	s_waitcnt lgkmcnt(0)
	v_add_f32_e32 v17, v18, v20
	v_cmp_eq_u32_e32 vcc, 0, v57
	v_div_scale_f32 v18, s[0:1], v17, v17, 1.0
	s_nop 0
	v_cndmask_b32_e32 v16, v16, v19, vcc
	v_rcp_f32_e32 v19, v18
	v_lshlrev_b32_e32 v7, 7, v7
	v_and_b32_e32 v7, 0x3f80, v7
	v_and_b32_e32 v16, 0x7f, v16
	v_bitop3_b32 v7, v7, s92, v16 bitop3:0x36
	v_fma_f32 v16, -v18, v19, 1.0
	v_fmac_f32_e32 v19, v16, v19
	v_div_scale_f32 v16, vcc, 1.0, v17, 1.0
	v_mul_f32_e32 v20, v16, v19
	v_fma_f32 v21, -v18, v20, v16
	v_fmac_f32_e32 v20, v21, v19
	v_fma_f32 v16, -v18, v20, v16
	s_lshl_b32 s0, s93, 4
	v_div_fmas_f32 v16, v16, v19, v20
	v_lshlrev_b64 v[18:19], 9, v[32:33]
	s_ashr_i32 s1, s0, 31
	v_lshl_add_u64 v[20:21], s[46:47], 0, v[18:19]
	s_lshl_b64 s[0:1], s[0:1], 2
	v_lshl_add_u64 v[18:19], s[44:45], 0, v[18:19]
	v_lshl_add_u64 v[20:21], v[20:21], 0, s[0:1]
	v_lshl_add_u64 v[18:19], v[18:19], 0, s[0:1]
	s_add_i32 s0, s2, s95
	v_div_fixup_f32 v16, v16, v17, 1.0
	v_lshl_add_u64 v[20:21], v[20:21], 0, v[82:83]
	s_cmpk_lt_i32 s0, 0x400
	v_lshl_add_u64 v[18:19], v[18:19], 0, v[82:83]
	v_pk_mul_f32 v[10:11], v[10:11], v[16:17] op_sel_hi:[1,0]
	v_pk_mul_f32 v[8:9], v[8:9], v[16:17] op_sel_hi:[1,0]
	global_store_dwordx4 v[20:21], v[0:3], off
	global_store_dwordx4 v[18:19], v[8:11], off
	s_nop 0
	v_pk_mul_f32 v[2:3], v[14:15], v[16:17] op_sel_hi:[1,0]
	v_pk_mul_f32 v[0:1], v[12:13], v[16:17] op_sel_hi:[1,0]
	global_store_dwordx4 v[20:21], v[4:7], off offset:16
	global_store_dwordx4 v[18:19], v[0:3], off offset:16
	s_barrier
	s_cbranch_scc0 .LBB0_346

.LBB0_436:
	s_mul_hi_i32 s10, s70, 0x2aaaaaab
	s_lshr_b32 s11, s10, 31
	s_ashr_i32 s10, s10, 2
	s_add_i32 s11, s10, s11
	s_lshl_b32 s10, s11, 7
	s_mul_i32 s14, s11, 0xffffffe8
	s_mulk_i32 s11, 0xf400
	s_add_i32 s71, s70, s14
	s_add_i32 s14, s3, s11
	s_ashr_i32 s11, s10, 31
	v_readlane_b32 s52, v245, 37
	s_lshl_b64 s[28:29], s[10:11], 11
	v_readlane_b32 s64, v245, 49
	v_readlane_b32 s65, v245, 50
	s_add_u32 s28, s64, s28
	s_addc_u32 s29, s65, s29
	s_ashr_i32 s15, s14, 31
	v_readlane_b32 s54, v245, 39
	s_lshl_b64 s[34:35], s[14:15], 11
	v_readlane_b32 s55, v245, 40
	s_add_u32 s34, s54, s34
	s_addc_u32 s35, s55, s35
	v_readfirstlane_b32 s82, v92
	v_mov_b32_e32 v2, s35
	v_mov_b32_e32 v3, s29
	v_mov_b32_e32 v4, s34
	v_mov_b32_e32 v5, s28
	s_add_u32 s98, s28, 0x80
	s_addc_u32 s99, s29, 0
	v_lshl_add_u64 v[76:77], s[28:29], 0, v[64:65]
	s_mov_b32 m0, s82
	v_cndmask_b32_e64 v1, v2, v3, s[4:5]
	v_cndmask_b32_e64 v0, v4, v5, s[4:5]
	v_readfirstlane_b32 s83, v95
	global_load_lds_dwordx4 v[76:77], off
	v_lshl_add_u64 v[78:79], v[0:1], 0, v[66:67]
	s_mov_b32 m0, s83
	v_cndmask_b32_e64 v1, v2, v3, s[6:7]
	v_cndmask_b32_e64 v0, v4, v5, s[6:7]
	v_readfirstlane_b32 s84, v96
	global_load_lds_dwordx4 v[78:79], off
	v_lshl_add_u64 v[80:81], v[0:1], 0, v[68:69]
	s_mov_b32 m0, s84
	v_cndmask_b32_e64 v1, v2, v3, s[8:9]
	v_cndmask_b32_e64 v0, v4, v5, s[8:9]
	v_readfirstlane_b32 s86, v97
	global_load_lds_dwordx4 v[80:81], off
	v_lshl_add_u64 v[84:85], v[0:1], 0, v[70:71]
	s_mov_b32 m0, s86
	v_readfirstlane_b32 s87, v98
	global_load_lds_dwordx4 v[84:85], off
	s_add_u32 s100, s34, 0x80
	s_addc_u32 s101, s35, 0
	v_lshl_add_u64 v[86:87], s[34:35], 0, v[64:65]
	s_mov_b32 m0, s87
	v_readfirstlane_b32 s90, v99
	global_load_lds_dwordx4 v[86:87], off
	v_lshl_add_u64 v[88:89], s[34:35], 0, v[66:67]
	s_mov_b32 m0, s90
	v_readfirstlane_b32 s91, v100
	global_load_lds_dwordx4 v[88:89], off
	v_lshl_add_u64 v[90:91], s[34:35], 0, v[68:69]
	s_mov_b32 m0, s91
	v_readfirstlane_b32 s85, v101
	global_load_lds_dwordx4 v[90:91], off
	v_lshl_add_u64 v[82:83], s[34:35], 0, v[70:71]
	s_mov_b32 m0, s85
	v_readfirstlane_b32 s15, v102
	global_load_lds_dwordx4 v[82:83], off
	s_mov_b32 m0, s15
	v_readfirstlane_b32 s28, v103
	s_waitcnt vmcnt(0)
	s_waitcnt vmcnt(0) lgkmcnt(0)
	s_barrier
	global_load_lds_dwordx4 v64, s[98:99]
	s_mov_b32 m0, s28
	v_readfirstlane_b32 s29, v104
	global_load_lds_dwordx4 v66, s[98:99]
	s_mov_b32 m0, s29
	v_readfirstlane_b32 s35, v105
	global_load_lds_dwordx4 v68, s[98:99]
	s_mov_b32 m0, s35
	v_readfirstlane_b32 s72, v106
	global_load_lds_dwordx4 v70, s[98:99]
	s_mov_b32 m0, s72
	v_readfirstlane_b32 s73, v107
	global_load_lds_dwordx4 v64, s[100:101]
	s_mov_b32 m0, s73
	v_readfirstlane_b32 s11, v108
	global_load_lds_dwordx4 v66, s[100:101]
	ds_read_b128 v[0:3], v111 offset:16384
	ds_read_b128 v[24:27], v111 offset:20480
	s_mov_b32 m0, s11
	v_readfirstlane_b32 s34, v109
	global_load_lds_dwordx4 v68, s[100:101]
	s_mov_b32 m0, s34
	ds_read_b128 v[16:19], v110
	global_load_lds_dwordx4 v70, s[100:101]
	s_add_u32 s98, s98, 0x80
	s_addc_u32 s99, s99, 0
	s_add_u32 s100, s100, 0x80
	s_addc_u32 s101, s101, 0
	ds_read_b128 v[20:23], v110 offset:4096
	s_waitcnt lgkmcnt(0)
	v_mfma_f32_32x32x16_bf16 v[32:47], v[0:3], v[16:19], 0
	ds_read_b128 v[118:121], v113 offset:16384
	ds_read_b128 v[122:125], v112
	ds_read_b128 v[126:129], v112 offset:4096
	s_mov_b32 m0, s82
	s_cmp_lt_i32 s71, 0
	v_readlane_b32 s53, v245, 38
	v_readlane_b32 s56, v245, 41
	v_readlane_b32 s57, v245, 42
	v_mfma_f32_32x32x16_bf16 v[0:15], v[0:3], v[20:23], 0
	v_readlane_b32 s58, v245, 43
	v_readlane_b32 s59, v245, 44
	v_readlane_b32 s60, v245, 45
	v_readlane_b32 s61, v245, 46
	v_readlane_b32 s62, v245, 47
	v_readlane_b32 s63, v245, 48
	v_readlane_b32 s66, v245, 51
	s_waitcnt lgkmcnt(0)
	v_mfma_f32_32x32x16_bf16 v[32:47], v[118:121], v[122:125], v[32:47]
	v_readlane_b32 s67, v245, 52
	v_mfma_f32_32x32x16_bf16 v[0:15], v[118:121], v[126:129], v[0:15]
	ds_read_b128 v[118:121], v113 offset:20480
	v_mfma_f32_32x32x16_bf16 v[48:63], v[24:27], v[16:19], 0
	v_mfma_f32_32x32x16_bf16 v[16:31], v[24:27], v[20:23], 0
	s_waitcnt lgkmcnt(0)
	v_mfma_f32_32x32x16_bf16 v[48:63], v[118:121], v[122:125], v[48:63]
	v_mfma_f32_32x32x16_bf16 v[16:31], v[118:121], v[126:129], v[16:31]
	ds_read_b128 v[118:121], v115 offset:16384
	ds_read_b128 v[122:125], v114
	ds_read_b128 v[126:129], v114 offset:4096
	s_waitcnt lgkmcnt(0)
	v_mfma_f32_32x32x16_bf16 v[32:47], v[118:121], v[122:125], v[32:47]
	v_mfma_f32_32x32x16_bf16 v[0:15], v[118:121], v[126:129], v[0:15]
	ds_read_b128 v[118:121], v115 offset:20480
	s_waitcnt lgkmcnt(0)
	v_mfma_f32_32x32x16_bf16 v[48:63], v[118:121], v[122:125], v[48:63]
	v_mfma_f32_32x32x16_bf16 v[16:31], v[118:121], v[126:129], v[16:31]
	ds_read_b128 v[118:121], v117 offset:16384
	ds_read_b128 v[122:125], v116
	ds_read_b128 v[126:129], v116 offset:4096
	s_waitcnt lgkmcnt(0)
	v_mfma_f32_32x32x16_bf16 v[32:47], v[118:121], v[122:125], v[32:47]
	v_mfma_f32_32x32x16_bf16 v[0:15], v[118:121], v[126:129], v[0:15]
	ds_read_b128 v[118:121], v117 offset:20480
	s_waitcnt vmcnt(0)
	s_waitcnt vmcnt(0) lgkmcnt(0)
	s_barrier
	v_mfma_f32_32x32x16_bf16 v[48:63], v[118:121], v[122:125], v[48:63]
	v_mfma_f32_32x32x16_bf16 v[16:31], v[118:121], v[126:129], v[16:31]
	global_load_lds_dwordx4 v64, s[98:99]
	s_mov_b32 m0, s83
	s_nop 0
	global_load_lds_dwordx4 v66, s[98:99]
	s_mov_b32 m0, s84
	s_nop 0
	global_load_lds_dwordx4 v68, s[98:99]
	s_mov_b32 m0, s86
	s_nop 0
	global_load_lds_dwordx4 v70, s[98:99]
	s_mov_b32 m0, s87
	s_nop 0
	global_load_lds_dwordx4 v64, s[100:101]
	s_mov_b32 m0, s90
	s_nop 0
	global_load_lds_dwordx4 v66, s[100:101]
	s_mov_b32 m0, s91
	s_nop 0
	global_load_lds_dwordx4 v68, s[100:101]
	ds_read_b128 v[118:121], v111 offset:49152
	s_mov_b32 m0, s85
	s_nop 0
	global_load_lds_dwordx4 v70, s[100:101]
	s_add_u32 s98, s98, 0x80
	s_addc_u32 s99, s99, 0
	s_add_u32 s100, s100, 0x80
	s_addc_u32 s101, s101, 0
	ds_read_b128 v[122:125], v110 offset:32768
	ds_read_b128 v[126:129], v110 offset:36864
	s_waitcnt lgkmcnt(0)
	v_mfma_f32_32x32x16_bf16 v[32:47], v[118:121], v[122:125], v[32:47]
	s_mov_b32 m0, s15
	v_mfma_f32_32x32x16_bf16 v[0:15], v[118:121], v[126:129], v[0:15]
	ds_read_b128 v[118:121], v111 offset:53248
	s_waitcnt lgkmcnt(0)
	v_mfma_f32_32x32x16_bf16 v[48:63], v[118:121], v[122:125], v[48:63]
	v_mfma_f32_32x32x16_bf16 v[16:31], v[118:121], v[126:129], v[16:31]
	ds_read_b128 v[118:121], v113 offset:49152
	ds_read_b128 v[122:125], v112 offset:32768
	ds_read_b128 v[126:129], v112 offset:36864
	s_waitcnt lgkmcnt(0)
	v_mfma_f32_32x32x16_bf16 v[32:47], v[118:121], v[122:125], v[32:47]
	v_mfma_f32_32x32x16_bf16 v[0:15], v[118:121], v[126:129], v[0:15]
	ds_read_b128 v[118:121], v113 offset:53248
	s_waitcnt lgkmcnt(0)
	v_mfma_f32_32x32x16_bf16 v[48:63], v[118:121], v[122:125], v[48:63]
	v_mfma_f32_32x32x16_bf16 v[16:31], v[118:121], v[126:129], v[16:31]
	ds_read_b128 v[118:121], v115 offset:49152
	ds_read_b128 v[122:125], v114 offset:32768
	ds_read_b128 v[126:129], v114 offset:36864
	s_waitcnt lgkmcnt(0)
	v_mfma_f32_32x32x16_bf16 v[32:47], v[118:121], v[122:125], v[32:47]
	v_mfma_f32_32x32x16_bf16 v[0:15], v[118:121], v[126:129], v[0:15]
	ds_read_b128 v[118:121], v115 offset:53248
	s_waitcnt lgkmcnt(0)
	v_mfma_f32_32x32x16_bf16 v[48:63], v[118:121], v[122:125], v[48:63]
	v_mfma_f32_32x32x16_bf16 v[16:31], v[118:121], v[126:129], v[16:31]
	ds_read_b128 v[118:121], v117 offset:49152
	ds_read_b128 v[122:125], v116 offset:32768
	ds_read_b128 v[126:129], v116 offset:36864
	s_waitcnt lgkmcnt(0)
	v_mfma_f32_32x32x16_bf16 v[32:47], v[118:121], v[122:125], v[32:47]
	v_mfma_f32_32x32x16_bf16 v[0:15], v[118:121], v[126:129], v[0:15]
	ds_read_b128 v[118:121], v117 offset:53248
	s_waitcnt vmcnt(0)
	s_waitcnt vmcnt(0) lgkmcnt(0)
	s_barrier
	v_mfma_f32_32x32x16_bf16 v[48:63], v[118:121], v[122:125], v[48:63]
	v_mfma_f32_32x32x16_bf16 v[16:31], v[118:121], v[126:129], v[16:31]
	global_load_lds_dwordx4 v64, s[98:99]
	s_mov_b32 m0, s28
	s_nop 0
	global_load_lds_dwordx4 v66, s[98:99]
	s_mov_b32 m0, s29
	s_nop 0
	global_load_lds_dwordx4 v68, s[98:99]
	s_mov_b32 m0, s35
	s_nop 0
	global_load_lds_dwordx4 v70, s[98:99]
	s_mov_b32 m0, s72
	s_nop 0
	global_load_lds_dwordx4 v64, s[100:101]
	s_mov_b32 m0, s73
	s_nop 0
	global_load_lds_dwordx4 v66, s[100:101]
	ds_read_b128 v[118:121], v111 offset:16384
	s_mov_b32 m0, s11
	s_nop 0
	global_load_lds_dwordx4 v68, s[100:101]
	s_mov_b32 m0, s34
	ds_read_b128 v[122:125], v110
	global_load_lds_dwordx4 v70, s[100:101]
	s_add_u32 s98, s98, 0x80
	s_addc_u32 s99, s99, 0
	s_add_u32 s100, s100, 0x80
	s_addc_u32 s101, s101, 0
	ds_read_b128 v[126:129], v110 offset:4096
	s_waitcnt lgkmcnt(0)
	v_mfma_f32_32x32x16_bf16 v[32:47], v[118:121], v[122:125], v[32:47]
	s_mov_b32 m0, s82
	v_mfma_f32_32x32x16_bf16 v[0:15], v[118:121], v[126:129], v[0:15]
	ds_read_b128 v[118:121], v111 offset:20480
	s_waitcnt lgkmcnt(0)
	v_mfma_f32_32x32x16_bf16 v[48:63], v[118:121], v[122:125], v[48:63]
	v_mfma_f32_32x32x16_bf16 v[16:31], v[118:121], v[126:129], v[16:31]
	ds_read_b128 v[118:121], v113 offset:16384
	ds_read_b128 v[122:125], v112
	ds_read_b128 v[126:129], v112 offset:4096
	s_waitcnt lgkmcnt(0)
	v_mfma_f32_32x32x16_bf16 v[32:47], v[118:121], v[122:125], v[32:47]
	v_mfma_f32_32x32x16_bf16 v[0:15], v[118:121], v[126:129], v[0:15]
	ds_read_b128 v[118:121], v113 offset:20480
	s_waitcnt lgkmcnt(0)
	v_mfma_f32_32x32x16_bf16 v[48:63], v[118:121], v[122:125], v[48:63]
	v_mfma_f32_32x32x16_bf16 v[16:31], v[118:121], v[126:129], v[16:31]
	ds_read_b128 v[118:121], v115 offset:16384
	ds_read_b128 v[122:125], v114
	ds_read_b128 v[126:129], v114 offset:4096
	s_waitcnt lgkmcnt(0)
	v_mfma_f32_32x32x16_bf16 v[32:47], v[118:121], v[122:125], v[32:47]
	v_mfma_f32_32x32x16_bf16 v[0:15], v[118:121], v[126:129], v[0:15]
	ds_read_b128 v[118:121], v115 offset:20480
	s_waitcnt lgkmcnt(0)
	v_mfma_f32_32x32x16_bf16 v[48:63], v[118:121], v[122:125], v[48:63]
	v_mfma_f32_32x32x16_bf16 v[16:31], v[118:121], v[126:129], v[16:31]
	ds_read_b128 v[118:121], v117 offset:16384
	ds_read_b128 v[122:125], v116
	ds_read_b128 v[126:129], v116 offset:4096
	s_waitcnt lgkmcnt(0)
	v_mfma_f32_32x32x16_bf16 v[32:47], v[118:121], v[122:125], v[32:47]
	v_mfma_f32_32x32x16_bf16 v[0:15], v[118:121], v[126:129], v[0:15]
	ds_read_b128 v[118:121], v117 offset:20480
	s_waitcnt vmcnt(0)
	s_waitcnt vmcnt(0) lgkmcnt(0)
	s_barrier
	v_mfma_f32_32x32x16_bf16 v[48:63], v[118:121], v[122:125], v[48:63]
	v_mfma_f32_32x32x16_bf16 v[16:31], v[118:121], v[126:129], v[16:31]
	global_load_lds_dwordx4 v64, s[98:99]
	s_mov_b32 m0, s83
	s_nop 0
	global_load_lds_dwordx4 v66, s[98:99]
	s_mov_b32 m0, s84
	s_nop 0
	global_load_lds_dwordx4 v68, s[98:99]
	s_mov_b32 m0, s86
	s_nop 0
	global_load_lds_dwordx4 v70, s[98:99]
	s_mov_b32 m0, s87
	s_nop 0
	global_load_lds_dwordx4 v64, s[100:101]
	s_mov_b32 m0, s90
	s_nop 0
	global_load_lds_dwordx4 v66, s[100:101]
	s_mov_b32 m0, s91
	s_nop 0
	global_load_lds_dwordx4 v68, s[100:101]
	ds_read_b128 v[118:121], v111 offset:49152
	s_mov_b32 m0, s85
	s_nop 0
	global_load_lds_dwordx4 v70, s[100:101]
	s_add_u32 s98, s98, 0x80
	s_addc_u32 s99, s99, 0
	s_add_u32 s100, s100, 0x80
	s_addc_u32 s101, s101, 0
	ds_read_b128 v[122:125], v110 offset:32768
	ds_read_b128 v[126:129], v110 offset:36864
	s_waitcnt lgkmcnt(0)
	v_mfma_f32_32x32x16_bf16 v[32:47], v[118:121], v[122:125], v[32:47]
	s_mov_b32 m0, s15
	v_mfma_f32_32x32x16_bf16 v[0:15], v[118:121], v[126:129], v[0:15]
	ds_read_b128 v[118:121], v111 offset:53248
	s_waitcnt lgkmcnt(0)
	v_mfma_f32_32x32x16_bf16 v[48:63], v[118:121], v[122:125], v[48:63]
	v_mfma_f32_32x32x16_bf16 v[16:31], v[118:121], v[126:129], v[16:31]
	ds_read_b128 v[118:121], v113 offset:49152
	ds_read_b128 v[122:125], v112 offset:32768
	ds_read_b128 v[126:129], v112 offset:36864
	s_waitcnt lgkmcnt(0)
	v_mfma_f32_32x32x16_bf16 v[32:47], v[118:121], v[122:125], v[32:47]
	v_mfma_f32_32x32x16_bf16 v[0:15], v[118:121], v[126:129], v[0:15]
	ds_read_b128 v[118:121], v113 offset:53248
	s_waitcnt lgkmcnt(0)
	v_mfma_f32_32x32x16_bf16 v[48:63], v[118:121], v[122:125], v[48:63]
	v_mfma_f32_32x32x16_bf16 v[16:31], v[118:121], v[126:129], v[16:31]
	ds_read_b128 v[118:121], v115 offset:49152
	ds_read_b128 v[122:125], v114 offset:32768
	ds_read_b128 v[126:129], v114 offset:36864
	s_waitcnt lgkmcnt(0)
	v_mfma_f32_32x32x16_bf16 v[32:47], v[118:121], v[122:125], v[32:47]
	v_mfma_f32_32x32x16_bf16 v[0:15], v[118:121], v[126:129], v[0:15]
	ds_read_b128 v[118:121], v115 offset:53248
	s_waitcnt lgkmcnt(0)
	v_mfma_f32_32x32x16_bf16 v[48:63], v[118:121], v[122:125], v[48:63]
	v_mfma_f32_32x32x16_bf16 v[16:31], v[118:121], v[126:129], v[16:31]
	ds_read_b128 v[118:121], v117 offset:49152
	ds_read_b128 v[122:125], v116 offset:32768
	ds_read_b128 v[126:129], v116 offset:36864
	s_waitcnt lgkmcnt(0)
	v_mfma_f32_32x32x16_bf16 v[32:47], v[118:121], v[122:125], v[32:47]
	v_mfma_f32_32x32x16_bf16 v[0:15], v[118:121], v[126:129], v[0:15]
	ds_read_b128 v[118:121], v117 offset:53248
	s_waitcnt vmcnt(0)
	s_waitcnt vmcnt(0) lgkmcnt(0)
	s_barrier
	v_mfma_f32_32x32x16_bf16 v[48:63], v[118:121], v[122:125], v[48:63]
	v_mfma_f32_32x32x16_bf16 v[16:31], v[118:121], v[126:129], v[16:31]
	global_load_lds_dwordx4 v64, s[98:99]
	s_mov_b32 m0, s28
	s_nop 0
	global_load_lds_dwordx4 v66, s[98:99]
	s_mov_b32 m0, s29
	s_nop 0
	global_load_lds_dwordx4 v68, s[98:99]
	s_mov_b32 m0, s35
	s_nop 0
	global_load_lds_dwordx4 v70, s[98:99]
	s_mov_b32 m0, s72
	s_nop 0
	global_load_lds_dwordx4 v64, s[100:101]
	s_mov_b32 m0, s73
	s_nop 0
	global_load_lds_dwordx4 v66, s[100:101]
	ds_read_b128 v[118:121], v111 offset:16384
	s_mov_b32 m0, s11
	s_nop 0
	global_load_lds_dwordx4 v68, s[100:101]
	s_mov_b32 m0, s34
	ds_read_b128 v[122:125], v110
	global_load_lds_dwordx4 v70, s[100:101]
	s_add_u32 s98, s98, 0x80
	s_addc_u32 s99, s99, 0
	s_add_u32 s100, s100, 0x80
	s_addc_u32 s101, s101, 0
	ds_read_b128 v[126:129], v110 offset:4096
	s_waitcnt lgkmcnt(0)
	v_mfma_f32_32x32x16_bf16 v[32:47], v[118:121], v[122:125], v[32:47]
	s_mov_b32 m0, s82
	v_mfma_f32_32x32x16_bf16 v[0:15], v[118:121], v[126:129], v[0:15]
	ds_read_b128 v[118:121], v111 offset:20480
	s_waitcnt lgkmcnt(0)
	v_mfma_f32_32x32x16_bf16 v[48:63], v[118:121], v[122:125], v[48:63]
	v_mfma_f32_32x32x16_bf16 v[16:31], v[118:121], v[126:129], v[16:31]
	ds_read_b128 v[118:121], v113 offset:16384
	ds_read_b128 v[122:125], v112
	ds_read_b128 v[126:129], v112 offset:4096
	s_waitcnt lgkmcnt(0)
	v_mfma_f32_32x32x16_bf16 v[32:47], v[118:121], v[122:125], v[32:47]
	v_mfma_f32_32x32x16_bf16 v[0:15], v[118:121], v[126:129], v[0:15]
	ds_read_b128 v[118:121], v113 offset:20480
	s_waitcnt lgkmcnt(0)
	v_mfma_f32_32x32x16_bf16 v[48:63], v[118:121], v[122:125], v[48:63]
	v_mfma_f32_32x32x16_bf16 v[16:31], v[118:121], v[126:129], v[16:31]
	ds_read_b128 v[118:121], v115 offset:16384
	ds_read_b128 v[122:125], v114
	ds_read_b128 v[126:129], v114 offset:4096
	s_waitcnt lgkmcnt(0)
	v_mfma_f32_32x32x16_bf16 v[32:47], v[118:121], v[122:125], v[32:47]
	v_mfma_f32_32x32x16_bf16 v[0:15], v[118:121], v[126:129], v[0:15]
	ds_read_b128 v[118:121], v115 offset:20480
	s_waitcnt lgkmcnt(0)
	v_mfma_f32_32x32x16_bf16 v[48:63], v[118:121], v[122:125], v[48:63]
	v_mfma_f32_32x32x16_bf16 v[16:31], v[118:121], v[126:129], v[16:31]
	ds_read_b128 v[118:121], v117 offset:16384
	ds_read_b128 v[122:125], v116
	ds_read_b128 v[126:129], v116 offset:4096
	s_waitcnt lgkmcnt(0)
	v_mfma_f32_32x32x16_bf16 v[32:47], v[118:121], v[122:125], v[32:47]
	v_mfma_f32_32x32x16_bf16 v[0:15], v[118:121], v[126:129], v[0:15]
	ds_read_b128 v[118:121], v117 offset:20480
	s_waitcnt vmcnt(0)
	s_waitcnt vmcnt(0) lgkmcnt(0)
	s_barrier
	v_mfma_f32_32x32x16_bf16 v[48:63], v[118:121], v[122:125], v[48:63]
	v_mfma_f32_32x32x16_bf16 v[16:31], v[118:121], v[126:129], v[16:31]
	global_load_lds_dwordx4 v64, s[98:99]
	s_mov_b32 m0, s83
	s_nop 0
	global_load_lds_dwordx4 v66, s[98:99]
	s_mov_b32 m0, s84
	s_nop 0
	global_load_lds_dwordx4 v68, s[98:99]
	s_mov_b32 m0, s86
	s_nop 0
	global_load_lds_dwordx4 v70, s[98:99]
	s_mov_b32 m0, s87
	s_nop 0
	global_load_lds_dwordx4 v64, s[100:101]
	s_mov_b32 m0, s90
	s_nop 0
	global_load_lds_dwordx4 v66, s[100:101]
	s_mov_b32 m0, s91
	s_nop 0
	global_load_lds_dwordx4 v68, s[100:101]
	ds_read_b128 v[118:121], v111 offset:49152
	s_mov_b32 m0, s85
	s_nop 0
	global_load_lds_dwordx4 v70, s[100:101]
	s_add_u32 s98, s98, 0x80
	s_addc_u32 s99, s99, 0
	s_add_u32 s100, s100, 0x80
	s_addc_u32 s101, s101, 0
	ds_read_b128 v[122:125], v110 offset:32768
	ds_read_b128 v[126:129], v110 offset:36864
	s_waitcnt lgkmcnt(0)
	v_mfma_f32_32x32x16_bf16 v[32:47], v[118:121], v[122:125], v[32:47]
	s_mov_b32 m0, s15
	v_mfma_f32_32x32x16_bf16 v[0:15], v[118:121], v[126:129], v[0:15]
	ds_read_b128 v[118:121], v111 offset:53248
	s_waitcnt lgkmcnt(0)
	v_mfma_f32_32x32x16_bf16 v[48:63], v[118:121], v[122:125], v[48:63]
	v_mfma_f32_32x32x16_bf16 v[16:31], v[118:121], v[126:129], v[16:31]
	ds_read_b128 v[118:121], v113 offset:49152
	ds_read_b128 v[122:125], v112 offset:32768
	ds_read_b128 v[126:129], v112 offset:36864
	s_waitcnt lgkmcnt(0)
	v_mfma_f32_32x32x16_bf16 v[32:47], v[118:121], v[122:125], v[32:47]
	v_mfma_f32_32x32x16_bf16 v[0:15], v[118:121], v[126:129], v[0:15]
	ds_read_b128 v[118:121], v113 offset:53248
	s_waitcnt lgkmcnt(0)
	v_mfma_f32_32x32x16_bf16 v[48:63], v[118:121], v[122:125], v[48:63]
	v_mfma_f32_32x32x16_bf16 v[16:31], v[118:121], v[126:129], v[16:31]
	ds_read_b128 v[118:121], v115 offset:49152
	ds_read_b128 v[122:125], v114 offset:32768
	ds_read_b128 v[126:129], v114 offset:36864
	s_waitcnt lgkmcnt(0)
	v_mfma_f32_32x32x16_bf16 v[32:47], v[118:121], v[122:125], v[32:47]
	v_mfma_f32_32x32x16_bf16 v[0:15], v[118:121], v[126:129], v[0:15]
	ds_read_b128 v[118:121], v115 offset:53248
	s_waitcnt lgkmcnt(0)
	v_mfma_f32_32x32x16_bf16 v[48:63], v[118:121], v[122:125], v[48:63]
	v_mfma_f32_32x32x16_bf16 v[16:31], v[118:121], v[126:129], v[16:31]
	ds_read_b128 v[118:121], v117 offset:49152
	ds_read_b128 v[122:125], v116 offset:32768
	ds_read_b128 v[126:129], v116 offset:36864
	s_waitcnt lgkmcnt(0)
	v_mfma_f32_32x32x16_bf16 v[32:47], v[118:121], v[122:125], v[32:47]
	v_mfma_f32_32x32x16_bf16 v[0:15], v[118:121], v[126:129], v[0:15]
	ds_read_b128 v[118:121], v117 offset:53248
	s_waitcnt vmcnt(0)
	s_waitcnt vmcnt(0) lgkmcnt(0)
	s_barrier
	v_mfma_f32_32x32x16_bf16 v[48:63], v[118:121], v[122:125], v[48:63]
	v_mfma_f32_32x32x16_bf16 v[16:31], v[118:121], v[126:129], v[16:31]
	global_load_lds_dwordx4 v64, s[98:99]
	s_mov_b32 m0, s28
	s_nop 0
	global_load_lds_dwordx4 v66, s[98:99]
	s_mov_b32 m0, s29
	s_nop 0
	global_load_lds_dwordx4 v68, s[98:99]
	s_mov_b32 m0, s35
	s_nop 0
	global_load_lds_dwordx4 v70, s[98:99]
	s_mov_b32 m0, s72
	s_nop 0
	global_load_lds_dwordx4 v64, s[100:101]
	s_mov_b32 m0, s73
	s_nop 0
	global_load_lds_dwordx4 v66, s[100:101]
	ds_read_b128 v[118:121], v111 offset:16384
	s_mov_b32 m0, s11
	s_nop 0
	global_load_lds_dwordx4 v68, s[100:101]
	s_mov_b32 m0, s34
	ds_read_b128 v[122:125], v110
	global_load_lds_dwordx4 v70, s[100:101]
	s_add_u32 s98, s98, 0x80
	s_addc_u32 s99, s99, 0
	s_add_u32 s100, s100, 0x80
	s_addc_u32 s101, s101, 0
	ds_read_b128 v[126:129], v110 offset:4096
	s_waitcnt lgkmcnt(0)
	v_mfma_f32_32x32x16_bf16 v[32:47], v[118:121], v[122:125], v[32:47]
	s_mov_b32 m0, s82
	v_readfirstlane_b32 s82, v108
	v_mfma_f32_32x32x16_bf16 v[0:15], v[118:121], v[126:129], v[0:15]
	ds_read_b128 v[118:121], v111 offset:20480
	s_waitcnt lgkmcnt(0)
	v_mfma_f32_32x32x16_bf16 v[48:63], v[118:121], v[122:125], v[48:63]
	v_mfma_f32_32x32x16_bf16 v[16:31], v[118:121], v[126:129], v[16:31]
	ds_read_b128 v[118:121], v113 offset:16384
	ds_read_b128 v[122:125], v112
	ds_read_b128 v[126:129], v112 offset:4096
	s_waitcnt lgkmcnt(0)
	v_mfma_f32_32x32x16_bf16 v[32:47], v[118:121], v[122:125], v[32:47]
	v_mfma_f32_32x32x16_bf16 v[0:15], v[118:121], v[126:129], v[0:15]
	ds_read_b128 v[118:121], v113 offset:20480
	s_waitcnt lgkmcnt(0)
	v_mfma_f32_32x32x16_bf16 v[48:63], v[118:121], v[122:125], v[48:63]
	v_mfma_f32_32x32x16_bf16 v[16:31], v[118:121], v[126:129], v[16:31]
	ds_read_b128 v[118:121], v115 offset:16384
	ds_read_b128 v[122:125], v114
	ds_read_b128 v[126:129], v114 offset:4096
	s_waitcnt lgkmcnt(0)
	v_mfma_f32_32x32x16_bf16 v[32:47], v[118:121], v[122:125], v[32:47]
	v_mfma_f32_32x32x16_bf16 v[0:15], v[118:121], v[126:129], v[0:15]
	ds_read_b128 v[118:121], v115 offset:20480
	s_waitcnt lgkmcnt(0)
	v_mfma_f32_32x32x16_bf16 v[48:63], v[118:121], v[122:125], v[48:63]
	v_mfma_f32_32x32x16_bf16 v[16:31], v[118:121], v[126:129], v[16:31]
	ds_read_b128 v[118:121], v117 offset:16384
	ds_read_b128 v[122:125], v116
	ds_read_b128 v[126:129], v116 offset:4096
	s_waitcnt lgkmcnt(0)
	v_mfma_f32_32x32x16_bf16 v[32:47], v[118:121], v[122:125], v[32:47]
	v_mfma_f32_32x32x16_bf16 v[0:15], v[118:121], v[126:129], v[0:15]
	ds_read_b128 v[118:121], v117 offset:20480
	s_waitcnt vmcnt(0)
	s_waitcnt vmcnt(0) lgkmcnt(0)
	s_barrier
	v_mfma_f32_32x32x16_bf16 v[48:63], v[118:121], v[122:125], v[48:63]
	v_mfma_f32_32x32x16_bf16 v[16:31], v[118:121], v[126:129], v[16:31]
	global_load_lds_dwordx4 v64, s[98:99]
	s_mov_b32 m0, s83
	v_readfirstlane_b32 s83, v102
	global_load_lds_dwordx4 v66, s[98:99]
	s_mov_b32 m0, s84
	v_readfirstlane_b32 s84, v103
	global_load_lds_dwordx4 v68, s[98:99]
	s_mov_b32 m0, s86
	v_readfirstlane_b32 s86, v109
	global_load_lds_dwordx4 v70, s[98:99]
	s_mov_b32 m0, s87
	v_readfirstlane_b32 s87, v105
	global_load_lds_dwordx4 v64, s[100:101]
	s_mov_b32 m0, s90
	v_readfirstlane_b32 s90, v106
	global_load_lds_dwordx4 v66, s[100:101]
	s_mov_b32 m0, s91
	v_readfirstlane_b32 s91, v107
	global_load_lds_dwordx4 v68, s[100:101]
	ds_read_b128 v[118:121], v111 offset:49152
	s_mov_b32 m0, s85
	v_readfirstlane_b32 s85, v104
	global_load_lds_dwordx4 v70, s[100:101]
	s_add_u32 s98, s98, 0x80
	s_addc_u32 s99, s99, 0
	s_add_u32 s100, s100, 0x80
	s_addc_u32 s101, s101, 0
	ds_read_b128 v[122:125], v110 offset:32768
	ds_read_b128 v[126:129], v110 offset:36864
	s_waitcnt lgkmcnt(0)
	v_mfma_f32_32x32x16_bf16 v[32:47], v[118:121], v[122:125], v[32:47]
	s_mov_b32 m0, s15
	v_readfirstlane_b32 s15, v95
	v_mfma_f32_32x32x16_bf16 v[0:15], v[118:121], v[126:129], v[0:15]
	ds_read_b128 v[118:121], v111 offset:53248
	s_waitcnt lgkmcnt(0)
	v_mfma_f32_32x32x16_bf16 v[48:63], v[118:121], v[122:125], v[48:63]
	v_mfma_f32_32x32x16_bf16 v[16:31], v[118:121], v[126:129], v[16:31]
	ds_read_b128 v[118:121], v113 offset:49152
	ds_read_b128 v[122:125], v112 offset:32768
	ds_read_b128 v[126:129], v112 offset:36864
	s_waitcnt lgkmcnt(0)
	v_mfma_f32_32x32x16_bf16 v[32:47], v[118:121], v[122:125], v[32:47]
	v_mfma_f32_32x32x16_bf16 v[0:15], v[118:121], v[126:129], v[0:15]
	ds_read_b128 v[118:121], v113 offset:53248
	s_waitcnt lgkmcnt(0)
	v_mfma_f32_32x32x16_bf16 v[48:63], v[118:121], v[122:125], v[48:63]
	v_mfma_f32_32x32x16_bf16 v[16:31], v[118:121], v[126:129], v[16:31]
	ds_read_b128 v[118:121], v115 offset:49152
	ds_read_b128 v[122:125], v114 offset:32768
	ds_read_b128 v[126:129], v114 offset:36864
	s_waitcnt lgkmcnt(0)
	v_mfma_f32_32x32x16_bf16 v[32:47], v[118:121], v[122:125], v[32:47]
	v_mfma_f32_32x32x16_bf16 v[0:15], v[118:121], v[126:129], v[0:15]
	ds_read_b128 v[118:121], v115 offset:53248
	s_waitcnt lgkmcnt(0)
	v_mfma_f32_32x32x16_bf16 v[48:63], v[118:121], v[122:125], v[48:63]
	v_mfma_f32_32x32x16_bf16 v[16:31], v[118:121], v[126:129], v[16:31]
	ds_read_b128 v[118:121], v117 offset:49152
	ds_read_b128 v[122:125], v116 offset:32768
	ds_read_b128 v[126:129], v116 offset:36864
	s_waitcnt lgkmcnt(0)
	v_mfma_f32_32x32x16_bf16 v[32:47], v[118:121], v[122:125], v[32:47]
	v_mfma_f32_32x32x16_bf16 v[0:15], v[118:121], v[126:129], v[0:15]
	ds_read_b128 v[118:121], v117 offset:53248
	s_waitcnt vmcnt(0)
	s_waitcnt vmcnt(0) lgkmcnt(0)
	s_barrier
	v_mfma_f32_32x32x16_bf16 v[48:63], v[118:121], v[122:125], v[48:63]
	v_mfma_f32_32x32x16_bf16 v[16:31], v[118:121], v[126:129], v[16:31]
	global_load_lds_dwordx4 v64, s[98:99]
	s_mov_b32 m0, s28
	s_nop 0
	global_load_lds_dwordx4 v66, s[98:99]
	s_mov_b32 m0, s29
	v_readfirstlane_b32 s28, v96
	global_load_lds_dwordx4 v68, s[98:99]
	s_mov_b32 m0, s35
	v_readfirstlane_b32 s35, v98
	global_load_lds_dwordx4 v70, s[98:99]
	s_mov_b32 m0, s72
	v_readfirstlane_b32 s72, v99
	global_load_lds_dwordx4 v64, s[100:101]
	s_mov_b32 m0, s73
	v_readfirstlane_b32 s73, v100
	global_load_lds_dwordx4 v66, s[100:101]
	ds_read_b128 v[118:121], v111 offset:16384
	s_mov_b32 m0, s11
	v_readfirstlane_b32 s11, v92
	global_load_lds_dwordx4 v68, s[100:101]
	s_mov_b32 m0, s34
	ds_read_b128 v[122:125], v110
	global_load_lds_dwordx4 v70, s[100:101]
	s_add_u32 s98, s98, 0x80
	s_addc_u32 s99, s99, 0
	s_add_u32 s100, s100, 0x80
	s_addc_u32 s101, s101, 0
	ds_read_b128 v[126:129], v110 offset:4096
	s_waitcnt lgkmcnt(0)
	v_mfma_f32_32x32x16_bf16 v[32:47], v[118:121], v[122:125], v[32:47]
	s_mov_b32 m0, s11
	v_readfirstlane_b32 s34, v97
	v_readfirstlane_b32 s29, v101
	v_mfma_f32_32x32x16_bf16 v[0:15], v[118:121], v[126:129], v[0:15]
	ds_read_b128 v[118:121], v111 offset:20480
	s_waitcnt lgkmcnt(0)
	v_mfma_f32_32x32x16_bf16 v[48:63], v[118:121], v[122:125], v[48:63]
	v_mfma_f32_32x32x16_bf16 v[16:31], v[118:121], v[126:129], v[16:31]
	ds_read_b128 v[118:121], v113 offset:16384
	ds_read_b128 v[122:125], v112
	ds_read_b128 v[126:129], v112 offset:4096
	s_waitcnt lgkmcnt(0)
	v_mfma_f32_32x32x16_bf16 v[32:47], v[118:121], v[122:125], v[32:47]
	v_mfma_f32_32x32x16_bf16 v[0:15], v[118:121], v[126:129], v[0:15]
	ds_read_b128 v[118:121], v113 offset:20480
	s_waitcnt lgkmcnt(0)
	v_mfma_f32_32x32x16_bf16 v[48:63], v[118:121], v[122:125], v[48:63]
	v_mfma_f32_32x32x16_bf16 v[16:31], v[118:121], v[126:129], v[16:31]
	ds_read_b128 v[118:121], v115 offset:16384
	ds_read_b128 v[122:125], v114
	ds_read_b128 v[126:129], v114 offset:4096
	s_waitcnt lgkmcnt(0)
	v_mfma_f32_32x32x16_bf16 v[32:47], v[118:121], v[122:125], v[32:47]
	v_mfma_f32_32x32x16_bf16 v[0:15], v[118:121], v[126:129], v[0:15]
	ds_read_b128 v[118:121], v115 offset:20480
	s_waitcnt lgkmcnt(0)
	v_mfma_f32_32x32x16_bf16 v[48:63], v[118:121], v[122:125], v[48:63]
	v_mfma_f32_32x32x16_bf16 v[16:31], v[118:121], v[126:129], v[16:31]
	ds_read_b128 v[118:121], v117 offset:16384
	ds_read_b128 v[122:125], v116
	ds_read_b128 v[126:129], v116 offset:4096
	s_waitcnt lgkmcnt(0)
	v_mfma_f32_32x32x16_bf16 v[32:47], v[118:121], v[122:125], v[32:47]
	v_mfma_f32_32x32x16_bf16 v[0:15], v[118:121], v[126:129], v[0:15]
	ds_read_b128 v[118:121], v117 offset:20480
	s_waitcnt vmcnt(0)
	s_waitcnt vmcnt(0) lgkmcnt(0)
	s_barrier
	v_mfma_f32_32x32x16_bf16 v[48:63], v[118:121], v[122:125], v[48:63]
	v_mfma_f32_32x32x16_bf16 v[16:31], v[118:121], v[126:129], v[16:31]
	global_load_lds_dwordx4 v64, s[98:99]
	s_mov_b32 m0, s15
	s_nop 0
	global_load_lds_dwordx4 v66, s[98:99]
	s_mov_b32 m0, s28
	s_nop 0
	global_load_lds_dwordx4 v68, s[98:99]
	s_mov_b32 m0, s34
	s_nop 0
	global_load_lds_dwordx4 v70, s[98:99]
	s_mov_b32 m0, s35
	s_nop 0
	global_load_lds_dwordx4 v64, s[100:101]
	s_mov_b32 m0, s72
	s_nop 0
	global_load_lds_dwordx4 v66, s[100:101]
	s_mov_b32 m0, s73
	s_nop 0
	global_load_lds_dwordx4 v68, s[100:101]
	ds_read_b128 v[118:121], v111 offset:49152
	s_mov_b32 m0, s29
	s_nop 0
	global_load_lds_dwordx4 v70, s[100:101]
	s_add_u32 s98, s98, 0x80
	s_addc_u32 s99, s99, 0
	s_add_u32 s100, s100, 0x80
	s_addc_u32 s101, s101, 0
	ds_read_b128 v[122:125], v110 offset:32768
	ds_read_b128 v[126:129], v110 offset:36864
	s_waitcnt lgkmcnt(0)
	v_mfma_f32_32x32x16_bf16 v[32:47], v[118:121], v[122:125], v[32:47]
	s_mov_b32 m0, s83
	v_mfma_f32_32x32x16_bf16 v[0:15], v[118:121], v[126:129], v[0:15]
	ds_read_b128 v[118:121], v111 offset:53248
	s_waitcnt lgkmcnt(0)
	v_mfma_f32_32x32x16_bf16 v[48:63], v[118:121], v[122:125], v[48:63]
	v_mfma_f32_32x32x16_bf16 v[16:31], v[118:121], v[126:129], v[16:31]
	ds_read_b128 v[118:121], v113 offset:49152
	ds_read_b128 v[122:125], v112 offset:32768
	ds_read_b128 v[126:129], v112 offset:36864
	s_waitcnt lgkmcnt(0)
	v_mfma_f32_32x32x16_bf16 v[32:47], v[118:121], v[122:125], v[32:47]
	v_mfma_f32_32x32x16_bf16 v[0:15], v[118:121], v[126:129], v[0:15]
	ds_read_b128 v[118:121], v113 offset:53248
	s_waitcnt lgkmcnt(0)
	v_mfma_f32_32x32x16_bf16 v[48:63], v[118:121], v[122:125], v[48:63]
	v_mfma_f32_32x32x16_bf16 v[16:31], v[118:121], v[126:129], v[16:31]
	ds_read_b128 v[118:121], v115 offset:49152
	ds_read_b128 v[122:125], v114 offset:32768
	ds_read_b128 v[126:129], v114 offset:36864
	s_waitcnt lgkmcnt(0)
	v_mfma_f32_32x32x16_bf16 v[32:47], v[118:121], v[122:125], v[32:47]
	v_mfma_f32_32x32x16_bf16 v[0:15], v[118:121], v[126:129], v[0:15]
	ds_read_b128 v[118:121], v115 offset:53248
	s_waitcnt lgkmcnt(0)
	v_mfma_f32_32x32x16_bf16 v[48:63], v[118:121], v[122:125], v[48:63]
	v_mfma_f32_32x32x16_bf16 v[16:31], v[118:121], v[126:129], v[16:31]
	ds_read_b128 v[118:121], v117 offset:49152
	ds_read_b128 v[122:125], v116 offset:32768
	ds_read_b128 v[126:129], v116 offset:36864
	s_waitcnt lgkmcnt(0)
	v_mfma_f32_32x32x16_bf16 v[32:47], v[118:121], v[122:125], v[32:47]
	v_mfma_f32_32x32x16_bf16 v[0:15], v[118:121], v[126:129], v[0:15]
	ds_read_b128 v[118:121], v117 offset:53248
	s_waitcnt vmcnt(0)
	s_waitcnt vmcnt(0) lgkmcnt(0)
	s_barrier
	v_mfma_f32_32x32x16_bf16 v[48:63], v[118:121], v[122:125], v[48:63]
	v_mfma_f32_32x32x16_bf16 v[16:31], v[118:121], v[126:129], v[16:31]
	global_load_lds_dwordx4 v64, s[98:99]
	s_mov_b32 m0, s84
	s_nop 0
	global_load_lds_dwordx4 v66, s[98:99]
	s_mov_b32 m0, s85
	s_nop 0
	global_load_lds_dwordx4 v68, s[98:99]
	s_mov_b32 m0, s87
	s_nop 0
	global_load_lds_dwordx4 v70, s[98:99]
	s_mov_b32 m0, s90
	s_nop 0
	global_load_lds_dwordx4 v64, s[100:101]
	s_mov_b32 m0, s91
	s_nop 0
	global_load_lds_dwordx4 v66, s[100:101]
	ds_read_b128 v[118:121], v111 offset:16384
	s_mov_b32 m0, s82
	s_nop 0
	global_load_lds_dwordx4 v68, s[100:101]
	s_mov_b32 m0, s86
	ds_read_b128 v[122:125], v110
	global_load_lds_dwordx4 v70, s[100:101]
	s_add_u32 s98, s98, 0x80
	s_addc_u32 s99, s99, 0
	s_add_u32 s100, s100, 0x80
	s_addc_u32 s101, s101, 0
	ds_read_b128 v[126:129], v110 offset:4096
	s_waitcnt lgkmcnt(0)
	v_mfma_f32_32x32x16_bf16 v[32:47], v[118:121], v[122:125], v[32:47]
	s_mov_b32 m0, s11
	v_mfma_f32_32x32x16_bf16 v[0:15], v[118:121], v[126:129], v[0:15]
	ds_read_b128 v[118:121], v111 offset:20480
	s_waitcnt lgkmcnt(0)
	v_mfma_f32_32x32x16_bf16 v[48:63], v[118:121], v[122:125], v[48:63]
	v_mfma_f32_32x32x16_bf16 v[16:31], v[118:121], v[126:129], v[16:31]
	ds_read_b128 v[118:121], v113 offset:16384
	ds_read_b128 v[122:125], v112
	ds_read_b128 v[126:129], v112 offset:4096
	s_waitcnt lgkmcnt(0)
	v_mfma_f32_32x32x16_bf16 v[32:47], v[118:121], v[122:125], v[32:47]
	v_mfma_f32_32x32x16_bf16 v[0:15], v[118:121], v[126:129], v[0:15]
	ds_read_b128 v[118:121], v113 offset:20480
	s_waitcnt lgkmcnt(0)
	v_mfma_f32_32x32x16_bf16 v[48:63], v[118:121], v[122:125], v[48:63]
	v_mfma_f32_32x32x16_bf16 v[16:31], v[118:121], v[126:129], v[16:31]
	ds_read_b128 v[118:121], v115 offset:16384
	ds_read_b128 v[122:125], v114
	ds_read_b128 v[126:129], v114 offset:4096
	s_waitcnt lgkmcnt(0)
	v_mfma_f32_32x32x16_bf16 v[32:47], v[118:121], v[122:125], v[32:47]
	v_mfma_f32_32x32x16_bf16 v[0:15], v[118:121], v[126:129], v[0:15]
	ds_read_b128 v[118:121], v115 offset:20480
	s_waitcnt lgkmcnt(0)
	v_mfma_f32_32x32x16_bf16 v[48:63], v[118:121], v[122:125], v[48:63]
	v_mfma_f32_32x32x16_bf16 v[16:31], v[118:121], v[126:129], v[16:31]
	ds_read_b128 v[118:121], v117 offset:16384
	ds_read_b128 v[122:125], v116
	ds_read_b128 v[126:129], v116 offset:4096
	s_waitcnt lgkmcnt(0)
	v_mfma_f32_32x32x16_bf16 v[32:47], v[118:121], v[122:125], v[32:47]
	v_mfma_f32_32x32x16_bf16 v[0:15], v[118:121], v[126:129], v[0:15]
	ds_read_b128 v[118:121], v117 offset:20480
	s_waitcnt vmcnt(0)
	s_waitcnt vmcnt(0) lgkmcnt(0)
	s_barrier
	v_mfma_f32_32x32x16_bf16 v[48:63], v[118:121], v[122:125], v[48:63]
	v_mfma_f32_32x32x16_bf16 v[16:31], v[118:121], v[126:129], v[16:31]
	global_load_lds_dwordx4 v64, s[98:99]
	s_mov_b32 m0, s15
	s_nop 0
	global_load_lds_dwordx4 v66, s[98:99]
	s_mov_b32 m0, s28
	s_nop 0
	global_load_lds_dwordx4 v68, s[98:99]
	s_mov_b32 m0, s34
	s_nop 0
	global_load_lds_dwordx4 v70, s[98:99]
	s_mov_b32 m0, s35
	s_nop 0
	global_load_lds_dwordx4 v64, s[100:101]
	s_mov_b32 m0, s72
	s_nop 0
	global_load_lds_dwordx4 v66, s[100:101]
	s_mov_b32 m0, s73
	s_nop 0
	global_load_lds_dwordx4 v68, s[100:101]
	ds_read_b128 v[118:121], v111 offset:49152
	s_mov_b32 m0, s29
	s_nop 0
	global_load_lds_dwordx4 v70, s[100:101]
	s_add_u32 s98, s98, 0x80
	s_addc_u32 s99, s99, 0
	s_add_u32 s100, s100, 0x80
	s_addc_u32 s101, s101, 0
	ds_read_b128 v[122:125], v110 offset:32768
	ds_read_b128 v[126:129], v110 offset:36864
	s_waitcnt lgkmcnt(0)
	v_mfma_f32_32x32x16_bf16 v[32:47], v[118:121], v[122:125], v[32:47]
	s_mov_b32 m0, s83
	v_mfma_f32_32x32x16_bf16 v[0:15], v[118:121], v[126:129], v[0:15]
	ds_read_b128 v[118:121], v111 offset:53248
	s_waitcnt lgkmcnt(0)
	v_mfma_f32_32x32x16_bf16 v[48:63], v[118:121], v[122:125], v[48:63]
	v_mfma_f32_32x32x16_bf16 v[16:31], v[118:121], v[126:129], v[16:31]
	ds_read_b128 v[118:121], v113 offset:49152
	ds_read_b128 v[122:125], v112 offset:32768
	ds_read_b128 v[126:129], v112 offset:36864
	s_waitcnt lgkmcnt(0)
	v_mfma_f32_32x32x16_bf16 v[32:47], v[118:121], v[122:125], v[32:47]
	v_mfma_f32_32x32x16_bf16 v[0:15], v[118:121], v[126:129], v[0:15]
	ds_read_b128 v[118:121], v113 offset:53248
	s_waitcnt lgkmcnt(0)
	v_mfma_f32_32x32x16_bf16 v[48:63], v[118:121], v[122:125], v[48:63]
	v_mfma_f32_32x32x16_bf16 v[16:31], v[118:121], v[126:129], v[16:31]
	ds_read_b128 v[118:121], v115 offset:49152
	ds_read_b128 v[122:125], v114 offset:32768
	ds_read_b128 v[126:129], v114 offset:36864
	s_waitcnt lgkmcnt(0)
	v_mfma_f32_32x32x16_bf16 v[32:47], v[118:121], v[122:125], v[32:47]
	v_mfma_f32_32x32x16_bf16 v[0:15], v[118:121], v[126:129], v[0:15]
	ds_read_b128 v[118:121], v115 offset:53248
	s_waitcnt lgkmcnt(0)
	v_mfma_f32_32x32x16_bf16 v[48:63], v[118:121], v[122:125], v[48:63]
	v_mfma_f32_32x32x16_bf16 v[16:31], v[118:121], v[126:129], v[16:31]
	ds_read_b128 v[118:121], v117 offset:49152
	ds_read_b128 v[122:125], v116 offset:32768
	ds_read_b128 v[126:129], v116 offset:36864
	s_waitcnt lgkmcnt(0)
	v_mfma_f32_32x32x16_bf16 v[32:47], v[118:121], v[122:125], v[32:47]
	v_mfma_f32_32x32x16_bf16 v[0:15], v[118:121], v[126:129], v[0:15]
	ds_read_b128 v[118:121], v117 offset:53248
	s_waitcnt vmcnt(0)
	s_waitcnt vmcnt(0) lgkmcnt(0)
	s_barrier
	v_mfma_f32_32x32x16_bf16 v[48:63], v[118:121], v[122:125], v[48:63]
	v_mfma_f32_32x32x16_bf16 v[16:31], v[118:121], v[126:129], v[16:31]
	global_load_lds_dwordx4 v64, s[98:99]
	s_mov_b32 m0, s84
	s_nop 0
	global_load_lds_dwordx4 v66, s[98:99]
	s_mov_b32 m0, s85
	s_nop 0
	global_load_lds_dwordx4 v68, s[98:99]
	s_mov_b32 m0, s87
	s_nop 0
	global_load_lds_dwordx4 v70, s[98:99]
	s_mov_b32 m0, s90
	s_nop 0
	global_load_lds_dwordx4 v64, s[100:101]
	s_mov_b32 m0, s91
	s_nop 0
	global_load_lds_dwordx4 v66, s[100:101]
	ds_read_b128 v[118:121], v111 offset:16384
	s_mov_b32 m0, s82
	s_nop 0
	global_load_lds_dwordx4 v68, s[100:101]
	s_mov_b32 m0, s86
	ds_read_b128 v[122:125], v110
	global_load_lds_dwordx4 v70, s[100:101]
	s_add_u32 s98, s98, 0x80
	s_addc_u32 s99, s99, 0
	s_add_u32 s100, s100, 0x80
	s_addc_u32 s101, s101, 0
	ds_read_b128 v[126:129], v110 offset:4096
	s_waitcnt lgkmcnt(0)
	v_mfma_f32_32x32x16_bf16 v[32:47], v[118:121], v[122:125], v[32:47]
	s_mov_b32 m0, s11
	v_mfma_f32_32x32x16_bf16 v[0:15], v[118:121], v[126:129], v[0:15]
	ds_read_b128 v[118:121], v111 offset:20480
	s_waitcnt lgkmcnt(0)
	v_mfma_f32_32x32x16_bf16 v[48:63], v[118:121], v[122:125], v[48:63]
	v_mfma_f32_32x32x16_bf16 v[16:31], v[118:121], v[126:129], v[16:31]
	ds_read_b128 v[118:121], v113 offset:16384
	ds_read_b128 v[122:125], v112
	ds_read_b128 v[126:129], v112 offset:4096
	s_waitcnt lgkmcnt(0)
	v_mfma_f32_32x32x16_bf16 v[32:47], v[118:121], v[122:125], v[32:47]
	v_mfma_f32_32x32x16_bf16 v[0:15], v[118:121], v[126:129], v[0:15]
	ds_read_b128 v[118:121], v113 offset:20480
	s_waitcnt lgkmcnt(0)
	v_mfma_f32_32x32x16_bf16 v[48:63], v[118:121], v[122:125], v[48:63]
	v_mfma_f32_32x32x16_bf16 v[16:31], v[118:121], v[126:129], v[16:31]
	ds_read_b128 v[118:121], v115 offset:16384
	ds_read_b128 v[122:125], v114
	ds_read_b128 v[126:129], v114 offset:4096
	s_waitcnt lgkmcnt(0)
	v_mfma_f32_32x32x16_bf16 v[32:47], v[118:121], v[122:125], v[32:47]
	v_mfma_f32_32x32x16_bf16 v[0:15], v[118:121], v[126:129], v[0:15]
	ds_read_b128 v[118:121], v115 offset:20480
	s_waitcnt lgkmcnt(0)
	v_mfma_f32_32x32x16_bf16 v[48:63], v[118:121], v[122:125], v[48:63]
	v_mfma_f32_32x32x16_bf16 v[16:31], v[118:121], v[126:129], v[16:31]
	ds_read_b128 v[118:121], v117 offset:16384
	ds_read_b128 v[122:125], v116
	ds_read_b128 v[126:129], v116 offset:4096
	s_waitcnt lgkmcnt(0)
	v_mfma_f32_32x32x16_bf16 v[32:47], v[118:121], v[122:125], v[32:47]
	v_mfma_f32_32x32x16_bf16 v[0:15], v[118:121], v[126:129], v[0:15]
	ds_read_b128 v[118:121], v117 offset:20480
	s_waitcnt vmcnt(0)
	s_waitcnt vmcnt(0) lgkmcnt(0)
	s_barrier
	v_mfma_f32_32x32x16_bf16 v[48:63], v[118:121], v[122:125], v[48:63]
	v_mfma_f32_32x32x16_bf16 v[16:31], v[118:121], v[126:129], v[16:31]
	global_load_lds_dwordx4 v64, s[98:99]
	s_mov_b32 m0, s15
	s_nop 0
	global_load_lds_dwordx4 v66, s[98:99]
	s_mov_b32 m0, s28
	s_nop 0
	global_load_lds_dwordx4 v68, s[98:99]
	s_mov_b32 m0, s34
	s_nop 0
	global_load_lds_dwordx4 v70, s[98:99]
	s_mov_b32 m0, s35
	s_nop 0
	global_load_lds_dwordx4 v64, s[100:101]
	s_mov_b32 m0, s72
	s_nop 0
	global_load_lds_dwordx4 v66, s[100:101]
	s_mov_b32 m0, s73
	s_nop 0
	global_load_lds_dwordx4 v68, s[100:101]
	ds_read_b128 v[118:121], v111 offset:49152
	s_mov_b32 m0, s29
	s_nop 0
	global_load_lds_dwordx4 v70, s[100:101]
	s_add_u32 s98, s98, 0x80
	s_addc_u32 s99, s99, 0
	s_add_u32 s100, s100, 0x80
	s_addc_u32 s101, s101, 0
	ds_read_b128 v[122:125], v110 offset:32768
	ds_read_b128 v[126:129], v110 offset:36864
	s_waitcnt lgkmcnt(0)
	v_mfma_f32_32x32x16_bf16 v[32:47], v[118:121], v[122:125], v[32:47]
	s_mov_b32 m0, s83
	v_mfma_f32_32x32x16_bf16 v[0:15], v[118:121], v[126:129], v[0:15]
	ds_read_b128 v[118:121], v111 offset:53248
	s_waitcnt lgkmcnt(0)
	v_mfma_f32_32x32x16_bf16 v[48:63], v[118:121], v[122:125], v[48:63]
	v_mfma_f32_32x32x16_bf16 v[16:31], v[118:121], v[126:129], v[16:31]
	ds_read_b128 v[118:121], v113 offset:49152
	ds_read_b128 v[122:125], v112 offset:32768
	ds_read_b128 v[126:129], v112 offset:36864
	s_waitcnt lgkmcnt(0)
	v_mfma_f32_32x32x16_bf16 v[32:47], v[118:121], v[122:125], v[32:47]
	v_mfma_f32_32x32x16_bf16 v[0:15], v[118:121], v[126:129], v[0:15]
	ds_read_b128 v[118:121], v113 offset:53248
	s_waitcnt lgkmcnt(0)
	v_mfma_f32_32x32x16_bf16 v[48:63], v[118:121], v[122:125], v[48:63]
	v_mfma_f32_32x32x16_bf16 v[16:31], v[118:121], v[126:129], v[16:31]
	ds_read_b128 v[118:121], v115 offset:49152
	ds_read_b128 v[122:125], v114 offset:32768
	ds_read_b128 v[126:129], v114 offset:36864
	s_waitcnt lgkmcnt(0)
	v_mfma_f32_32x32x16_bf16 v[32:47], v[118:121], v[122:125], v[32:47]
	v_mfma_f32_32x32x16_bf16 v[0:15], v[118:121], v[126:129], v[0:15]
	ds_read_b128 v[118:121], v115 offset:53248
	s_waitcnt lgkmcnt(0)
	v_mfma_f32_32x32x16_bf16 v[48:63], v[118:121], v[122:125], v[48:63]
	v_mfma_f32_32x32x16_bf16 v[16:31], v[118:121], v[126:129], v[16:31]
	ds_read_b128 v[118:121], v117 offset:49152
	ds_read_b128 v[122:125], v116 offset:32768
	ds_read_b128 v[126:129], v116 offset:36864
	s_waitcnt lgkmcnt(0)
	v_mfma_f32_32x32x16_bf16 v[32:47], v[118:121], v[122:125], v[32:47]
	v_mfma_f32_32x32x16_bf16 v[0:15], v[118:121], v[126:129], v[0:15]
	ds_read_b128 v[118:121], v117 offset:53248
	s_waitcnt vmcnt(0)
	s_waitcnt vmcnt(0) lgkmcnt(0)
	s_barrier
	global_load_lds_dwordx4 v64, s[98:99]
	s_mov_b32 m0, s84
	v_mfma_f32_32x32x16_bf16 v[48:63], v[118:121], v[122:125], v[48:63]
	global_load_lds_dwordx4 v66, s[98:99]
	s_mov_b32 m0, s85
	s_nop 0
	global_load_lds_dwordx4 v68, s[98:99]
	s_mov_b32 m0, s87
	v_mfma_f32_32x32x16_bf16 v[16:31], v[118:121], v[126:129], v[16:31]
	global_load_lds_dwordx4 v70, s[98:99]
	s_mov_b32 m0, s90
	s_nop 0
	global_load_lds_dwordx4 v64, s[100:101]
	s_mov_b32 m0, s91
	s_nop 0
	global_load_lds_dwordx4 v66, s[100:101]
	ds_read_b128 v[76:79], v111 offset:16384
	s_mov_b32 m0, s82
	s_cmp_lt_i32 s71, 0
	s_cselect_b64 s[82:83], -1, 0
	global_load_lds_dwordx4 v68, s[100:101]
	s_mov_b32 m0, s86
	ds_read_b128 v[84:87], v110
	global_load_lds_dwordx4 v70, s[100:101]
	ds_read_b128 v[80:83], v110 offset:4096
	s_waitcnt lgkmcnt(0)
	v_mfma_f32_32x32x16_bf16 v[32:47], v[76:79], v[84:87], v[32:47]
	s_cmp_gt_i32 s71, -1
	v_mfma_f32_32x32x16_bf16 v[0:15], v[76:79], v[80:83], v[0:15]
	ds_read_b128 v[76:79], v111 offset:20480
	s_waitcnt lgkmcnt(0)
	v_mfma_f32_32x32x16_bf16 v[48:63], v[76:79], v[84:87], v[48:63]
	v_mfma_f32_32x32x16_bf16 v[16:31], v[76:79], v[80:83], v[16:31]
	ds_read_b128 v[76:79], v113 offset:16384
	ds_read_b128 v[80:83], v112
	ds_read_b128 v[84:87], v112 offset:4096
	s_waitcnt lgkmcnt(0)
	v_mfma_f32_32x32x16_bf16 v[32:47], v[76:79], v[80:83], v[32:47]
	v_mfma_f32_32x32x16_bf16 v[0:15], v[76:79], v[84:87], v[0:15]
	ds_read_b128 v[76:79], v113 offset:20480
	s_waitcnt lgkmcnt(0)
	v_mfma_f32_32x32x16_bf16 v[48:63], v[76:79], v[80:83], v[48:63]
	v_mfma_f32_32x32x16_bf16 v[16:31], v[76:79], v[84:87], v[16:31]
	ds_read_b128 v[76:79], v115 offset:16384
	ds_read_b128 v[80:83], v114
	ds_read_b128 v[84:87], v114 offset:4096
	s_waitcnt lgkmcnt(0)
	v_mfma_f32_32x32x16_bf16 v[32:47], v[76:79], v[80:83], v[32:47]
	v_mfma_f32_32x32x16_bf16 v[0:15], v[76:79], v[84:87], v[0:15]
	ds_read_b128 v[76:79], v115 offset:20480
	s_waitcnt lgkmcnt(0)
	v_mfma_f32_32x32x16_bf16 v[48:63], v[76:79], v[80:83], v[48:63]
	v_mfma_f32_32x32x16_bf16 v[16:31], v[76:79], v[84:87], v[16:31]
	ds_read_b128 v[76:79], v117 offset:16384
	ds_read_b128 v[80:83], v116
	ds_read_b128 v[84:87], v116 offset:4096
	s_waitcnt lgkmcnt(0)
	v_mfma_f32_32x32x16_bf16 v[32:47], v[76:79], v[80:83], v[32:47]
	v_mfma_f32_32x32x16_bf16 v[0:15], v[76:79], v[84:87], v[0:15]
	ds_read_b128 v[76:79], v117 offset:20480
	s_waitcnt vmcnt(0)
	s_waitcnt vmcnt(0) lgkmcnt(0)
	s_barrier
	v_mfma_f32_32x32x16_bf16 v[48:63], v[76:79], v[80:83], v[48:63]
	v_mfma_f32_32x32x16_bf16 v[16:31], v[76:79], v[84:87], v[16:31]
	ds_read_b128 v[76:79], v111 offset:49152
	ds_read_b128 v[80:83], v110 offset:32768
	ds_read_b128 v[84:87], v110 offset:36864
	s_waitcnt lgkmcnt(1)
	v_mfma_f32_32x32x16_bf16 v[32:47], v[76:79], v[80:83], v[32:47]
	s_waitcnt lgkmcnt(0)
	v_mfma_f32_32x32x16_bf16 v[0:15], v[76:79], v[84:87], v[0:15]
	ds_read_b128 v[76:79], v111 offset:53248
	s_waitcnt lgkmcnt(0)
	v_mfma_f32_32x32x16_bf16 v[48:63], v[76:79], v[80:83], v[48:63]
	v_mfma_f32_32x32x16_bf16 v[16:31], v[76:79], v[84:87], v[16:31]
	ds_read_b128 v[76:79], v113 offset:49152
	ds_read_b128 v[80:83], v112 offset:32768
	ds_read_b128 v[84:87], v112 offset:36864
	s_waitcnt lgkmcnt(1)
	v_mfma_f32_32x32x16_bf16 v[32:47], v[76:79], v[80:83], v[32:47]
	s_waitcnt lgkmcnt(0)
	v_mfma_f32_32x32x16_bf16 v[0:15], v[76:79], v[84:87], v[0:15]
	ds_read_b128 v[76:79], v113 offset:53248
	s_waitcnt lgkmcnt(0)
	v_mfma_f32_32x32x16_bf16 v[48:63], v[76:79], v[80:83], v[48:63]
	v_mfma_f32_32x32x16_bf16 v[16:31], v[76:79], v[84:87], v[16:31]
	ds_read_b128 v[76:79], v115 offset:49152
	ds_read_b128 v[80:83], v114 offset:32768
	ds_read_b128 v[84:87], v114 offset:36864
	s_waitcnt lgkmcnt(1)
	v_mfma_f32_32x32x16_bf16 v[32:47], v[76:79], v[80:83], v[32:47]
	s_waitcnt lgkmcnt(0)
	v_mfma_f32_32x32x16_bf16 v[0:15], v[76:79], v[84:87], v[0:15]
	ds_read_b128 v[76:79], v115 offset:53248
	s_waitcnt lgkmcnt(0)
	v_mfma_f32_32x32x16_bf16 v[48:63], v[76:79], v[80:83], v[48:63]
	v_mfma_f32_32x32x16_bf16 v[16:31], v[76:79], v[84:87], v[16:31]
	ds_read_b128 v[76:79], v117 offset:49152
	ds_read_b128 v[80:83], v116 offset:32768
	ds_read_b128 v[84:87], v116 offset:36864
	ds_read_b128 v[88:91], v117 offset:53248
	s_waitcnt vmcnt(0)
	s_waitcnt lgkmcnt(0)
	s_barrier
	v_mfma_f32_32x32x16_bf16 v[32:47], v[76:79], v[80:83], v[32:47]
	v_mfma_f32_32x32x16_bf16 v[0:15], v[76:79], v[84:87], v[0:15]
	v_add_u32_e32 v78, s10, v93
	v_lshlrev_b32_e32 v72, 8, v78
	v_and_b32_e32 v72, 0x1fdf00, v72
	v_lshl_add_u64 v[76:77], v[74:75], 0, v[72:73]
	v_mfma_f32_32x32x16_bf16 v[48:63], v[88:91], v[80:83], v[48:63]
	v_mfma_f32_32x32x16_bf16 v[16:31], v[88:91], v[84:87], v[16:31]
	s_cbranch_scc0 .LBB0_444
	v_cndmask_b32_e64 v72, 0, 1, s[82:83]
	v_cmp_ne_u32_e64 s[10:11], 1, v72
	s_andn2_b64 vcc, exec, s[82:83]
	s_cbranch_vccz .LBB0_445

.LBB0_561:
	s_lshl_b32 s80, s28, 7
	v_readlane_b32 s44, v245, 59
	s_ashr_i32 s81, s80, 31
	v_readlane_b32 s45, v245, 60
	s_lshl_b32 s82, s29, 7
	s_lshl_b64 s[28:29], s[80:81], 11
	v_readlane_b32 s46, v245, 61
	v_readlane_b32 s47, v245, 62
	v_readlane_b32 s48, v245, 63
	v_readlane_b32 s49, v244, 0
	s_mov_b64 s[36:37], s[44:45]
	v_readlane_b32 s52, v244, 3
	v_readlane_b32 s53, v244, 4
	v_readlane_b32 s54, v244, 5
	v_readlane_b32 s55, v244, 6
	v_readlane_b32 s56, v244, 7
	v_readlane_b32 s57, v244, 8
	v_readlane_b32 s58, v244, 9
	v_readlane_b32 s59, v244, 10
	s_add_u32 s34, s36, s28
	s_addc_u32 s35, s37, s29
	s_ashr_i32 s83, s82, 31
	v_readlane_b32 s52, v245, 37
	s_lshl_b64 s[28:29], s[82:83], 11
	v_readlane_b32 s56, v245, 41
	v_readlane_b32 s57, v245, 42
	s_add_u32 s70, s56, s28
	s_addc_u32 s71, s57, s29
	v_readfirstlane_b32 s29, v88
	v_mov_b32_e32 v2, s71
	v_mov_b32_e32 v3, s35
	v_mov_b32_e32 v4, s70
	v_mov_b32_e32 v5, s34
	s_add_u32 s98, s34, 0x80
	s_addc_u32 s99, s35, 0
	v_lshl_add_u64 v[72:73], s[34:35], 0, v[64:65]
	s_mov_b32 m0, s29
	v_cndmask_b32_e64 v1, v2, v3, s[4:5]
	v_cndmask_b32_e64 v0, v4, v5, s[4:5]
	v_readfirstlane_b32 s84, v91
	global_load_lds_dwordx4 v[72:73], off
	v_lshl_add_u64 v[74:75], v[0:1], 0, v[66:67]
	s_mov_b32 m0, s84
	v_cndmask_b32_e64 v1, v2, v3, s[6:7]
	v_cndmask_b32_e64 v0, v4, v5, s[6:7]
	v_readfirstlane_b32 s85, v92
	global_load_lds_dwordx4 v[74:75], off
	v_lshl_add_u64 v[76:77], v[0:1], 0, v[68:69]
	s_mov_b32 m0, s85
	v_cndmask_b32_e64 v1, v2, v3, s[8:9]
	v_cndmask_b32_e64 v0, v4, v5, s[8:9]
	v_readfirstlane_b32 s86, v93
	global_load_lds_dwordx4 v[76:77], off
	v_lshl_add_u64 v[78:79], v[0:1], 0, v[70:71]
	s_mov_b32 m0, s86
	v_readfirstlane_b32 s87, v94
	global_load_lds_dwordx4 v[78:79], off
	s_add_u32 s100, s70, 0x80
	s_addc_u32 s101, s71, 0
	v_lshl_add_u64 v[80:81], s[70:71], 0, v[64:65]
	s_mov_b32 m0, s87
	v_readfirstlane_b32 s89, v95
	global_load_lds_dwordx4 v[80:81], off
	v_lshl_add_u64 v[82:83], s[70:71], 0, v[66:67]
	s_mov_b32 m0, s89
	v_readfirstlane_b32 s90, v96
	global_load_lds_dwordx4 v[82:83], off
	v_lshl_add_u64 v[84:85], s[70:71], 0, v[68:69]
	s_mov_b32 m0, s90
	v_readfirstlane_b32 s91, v97
	global_load_lds_dwordx4 v[84:85], off
	v_lshl_add_u64 v[86:87], s[70:71], 0, v[70:71]
	s_mov_b32 m0, s91
	v_readfirstlane_b32 s70, v98
	global_load_lds_dwordx4 v[86:87], off
	s_mov_b32 m0, s70
	v_readfirstlane_b32 s71, v99
	s_waitcnt vmcnt(0)
	s_waitcnt vmcnt(0) lgkmcnt(0)
	s_barrier
	global_load_lds_dwordx4 v64, s[98:99]
	s_mov_b32 m0, s71
	v_readfirstlane_b32 s72, v100
	global_load_lds_dwordx4 v66, s[98:99]
	s_mov_b32 m0, s72
	v_readfirstlane_b32 s73, v101
	global_load_lds_dwordx4 v68, s[98:99]
	s_mov_b32 m0, s73
	v_readfirstlane_b32 s81, v102
	global_load_lds_dwordx4 v70, s[98:99]
	s_mov_b32 m0, s81
	v_readfirstlane_b32 s83, v103
	global_load_lds_dwordx4 v64, s[100:101]
	s_mov_b32 m0, s83
	v_readfirstlane_b32 s88, v104
	global_load_lds_dwordx4 v66, s[100:101]
	s_mov_b32 m0, s88
	v_readfirstlane_b32 s28, v105
	global_load_lds_dwordx4 v68, s[100:101]
	s_mov_b32 m0, s28
	v_readfirstlane_b32 s34, v92
	global_load_lds_dwordx4 v70, s[100:101]
	s_add_u32 s98, s98, 0x80
	s_addc_u32 s99, s99, 0
	s_add_u32 s100, s100, 0x80
	s_addc_u32 s101, s101, 0
	ds_read_b128 v[0:3], v106
	ds_read_b128 v[4:7], v107 offset:16384
	ds_read_b128 v[8:11], v106 offset:4096
	ds_read_b128 v[12:15], v107 offset:20480
	s_waitcnt lgkmcnt(0)
	v_mfma_f32_32x32x16_bf16 v[48:63], v[4:7], v[0:3], 0
	ds_read_b128 v[114:117], v108
	ds_read_b128 v[118:121], v109 offset:16384
	ds_read_b128 v[122:125], v108 offset:4096
	ds_read_b128 v[126:129], v109 offset:20480
	s_mov_b32 m0, s29
	v_readfirstlane_b32 s35, v93
	s_mov_b64 s[40:41], s[48:49]
	s_mov_b64 s[38:39], s[46:47]
	v_readlane_b32 s50, v244, 1
	v_readlane_b32 s51, v244, 2
	v_mfma_f32_32x32x16_bf16 v[32:47], v[12:15], v[0:3], 0
	v_readlane_b32 s53, v245, 38
	v_readlane_b32 s54, v245, 39
	v_readlane_b32 s55, v245, 40
	v_readlane_b32 s58, v245, 43
	v_readlane_b32 s59, v245, 44
	v_readlane_b32 s60, v245, 45
	v_readlane_b32 s61, v245, 46
	v_mfma_f32_32x32x16_bf16 v[16:31], v[4:7], v[8:11], 0
	v_readlane_b32 s62, v245, 47
	v_readlane_b32 s63, v245, 48
	v_readlane_b32 s64, v245, 49
	v_readlane_b32 s65, v245, 50
	v_readlane_b32 s66, v245, 51
	v_readlane_b32 s67, v245, 52
	v_mfma_f32_32x32x16_bf16 v[0:15], v[12:15], v[8:11], 0
	s_waitcnt lgkmcnt(0)
	v_mfma_f32_32x32x16_bf16 v[48:63], v[118:121], v[114:117], v[48:63]
	v_mfma_f32_32x32x16_bf16 v[32:47], v[126:129], v[114:117], v[32:47]
	v_mfma_f32_32x32x16_bf16 v[16:31], v[118:121], v[122:125], v[16:31]
	v_mfma_f32_32x32x16_bf16 v[0:15], v[126:129], v[122:125], v[0:15]
	ds_read_b128 v[114:117], v110
	ds_read_b128 v[118:121], v111 offset:16384
	ds_read_b128 v[122:125], v110 offset:4096
	ds_read_b128 v[126:129], v111 offset:20480
	s_waitcnt lgkmcnt(0)
	v_mfma_f32_32x32x16_bf16 v[48:63], v[118:121], v[114:117], v[48:63]
	v_mfma_f32_32x32x16_bf16 v[32:47], v[126:129], v[114:117], v[32:47]
	v_mfma_f32_32x32x16_bf16 v[16:31], v[118:121], v[122:125], v[16:31]
	v_mfma_f32_32x32x16_bf16 v[0:15], v[126:129], v[122:125], v[0:15]
	ds_read_b128 v[114:117], v112
	ds_read_b128 v[118:121], v113 offset:16384
	ds_read_b128 v[122:125], v112 offset:4096
	ds_read_b128 v[126:129], v113 offset:20480
	s_waitcnt vmcnt(0)
	s_waitcnt vmcnt(0) lgkmcnt(0)
	s_barrier
	v_mfma_f32_32x32x16_bf16 v[48:63], v[118:121], v[114:117], v[48:63]
	v_mfma_f32_32x32x16_bf16 v[32:47], v[126:129], v[114:117], v[32:47]
	global_load_lds_dwordx4 v64, s[98:99]
	s_mov_b32 m0, s84
	s_nop 0
	global_load_lds_dwordx4 v66, s[98:99]
	s_mov_b32 m0, s85
	v_mfma_f32_32x32x16_bf16 v[16:31], v[118:121], v[122:125], v[16:31]
	global_load_lds_dwordx4 v68, s[98:99]
	s_mov_b32 m0, s86
	s_nop 0
	global_load_lds_dwordx4 v70, s[98:99]
	s_mov_b32 m0, s87
	v_mfma_f32_32x32x16_bf16 v[0:15], v[126:129], v[122:125], v[0:15]
	global_load_lds_dwordx4 v64, s[100:101]
	s_mov_b32 m0, s89
	s_nop 0
	global_load_lds_dwordx4 v66, s[100:101]
	s_mov_b32 m0, s90
	s_nop 0
	global_load_lds_dwordx4 v68, s[100:101]
	s_mov_b32 m0, s91
	s_nop 0
	global_load_lds_dwordx4 v70, s[100:101]
	s_add_u32 s98, s98, 0x80
	s_addc_u32 s99, s99, 0
	s_add_u32 s100, s100, 0x80
	s_addc_u32 s101, s101, 0
	ds_read_b128 v[114:117], v106 offset:32768
	ds_read_b128 v[118:121], v107 offset:49152
	ds_read_b128 v[122:125], v106 offset:36864
	ds_read_b128 v[126:129], v107 offset:53248
	s_waitcnt lgkmcnt(0)
	v_mfma_f32_32x32x16_bf16 v[48:63], v[118:121], v[114:117], v[48:63]
	s_mov_b32 m0, s70
	v_mfma_f32_32x32x16_bf16 v[32:47], v[126:129], v[114:117], v[32:47]
	v_mfma_f32_32x32x16_bf16 v[16:31], v[118:121], v[122:125], v[16:31]
	v_mfma_f32_32x32x16_bf16 v[0:15], v[126:129], v[122:125], v[0:15]
	ds_read_b128 v[114:117], v108 offset:32768
	ds_read_b128 v[118:121], v109 offset:49152
	ds_read_b128 v[122:125], v108 offset:36864
	ds_read_b128 v[126:129], v109 offset:53248
	s_waitcnt lgkmcnt(0)
	v_mfma_f32_32x32x16_bf16 v[48:63], v[118:121], v[114:117], v[48:63]
	v_mfma_f32_32x32x16_bf16 v[32:47], v[126:129], v[114:117], v[32:47]
	v_mfma_f32_32x32x16_bf16 v[16:31], v[118:121], v[122:125], v[16:31]
	v_mfma_f32_32x32x16_bf16 v[0:15], v[126:129], v[122:125], v[0:15]
	ds_read_b128 v[114:117], v110 offset:32768
	ds_read_b128 v[118:121], v111 offset:49152
	ds_read_b128 v[122:125], v110 offset:36864
	ds_read_b128 v[126:129], v111 offset:53248
	s_waitcnt lgkmcnt(0)
	v_mfma_f32_32x32x16_bf16 v[48:63], v[118:121], v[114:117], v[48:63]
	v_mfma_f32_32x32x16_bf16 v[32:47], v[126:129], v[114:117], v[32:47]
	v_mfma_f32_32x32x16_bf16 v[16:31], v[118:121], v[122:125], v[16:31]
	v_mfma_f32_32x32x16_bf16 v[0:15], v[126:129], v[122:125], v[0:15]
	ds_read_b128 v[114:117], v112 offset:32768
	ds_read_b128 v[118:121], v113 offset:49152
	ds_read_b128 v[122:125], v112 offset:36864
	ds_read_b128 v[126:129], v113 offset:53248
	s_waitcnt vmcnt(0)
	s_waitcnt vmcnt(0) lgkmcnt(0)
	s_barrier
	v_mfma_f32_32x32x16_bf16 v[48:63], v[118:121], v[114:117], v[48:63]
	v_mfma_f32_32x32x16_bf16 v[32:47], v[126:129], v[114:117], v[32:47]
	global_load_lds_dwordx4 v64, s[98:99]
	s_mov_b32 m0, s71
	s_nop 0
	global_load_lds_dwordx4 v66, s[98:99]
	s_mov_b32 m0, s72
	v_mfma_f32_32x32x16_bf16 v[16:31], v[118:121], v[122:125], v[16:31]
	global_load_lds_dwordx4 v68, s[98:99]
	s_mov_b32 m0, s73
	s_nop 0
	global_load_lds_dwordx4 v70, s[98:99]
	s_mov_b32 m0, s81
	v_mfma_f32_32x32x16_bf16 v[0:15], v[126:129], v[122:125], v[0:15]
	global_load_lds_dwordx4 v64, s[100:101]
	s_mov_b32 m0, s83
	s_nop 0
	global_load_lds_dwordx4 v66, s[100:101]
	s_mov_b32 m0, s88
	s_nop 0
	global_load_lds_dwordx4 v68, s[100:101]
	s_mov_b32 m0, s28
	s_nop 0
	global_load_lds_dwordx4 v70, s[100:101]
	s_add_u32 s98, s98, 0x80
	s_addc_u32 s99, s99, 0
	s_add_u32 s100, s100, 0x80
	s_addc_u32 s101, s101, 0
	ds_read_b128 v[114:117], v106
	ds_read_b128 v[118:121], v107 offset:16384
	ds_read_b128 v[122:125], v106 offset:4096
	ds_read_b128 v[126:129], v107 offset:20480
	s_waitcnt lgkmcnt(0)
	v_mfma_f32_32x32x16_bf16 v[48:63], v[118:121], v[114:117], v[48:63]
	s_mov_b32 m0, s29
	v_mfma_f32_32x32x16_bf16 v[32:47], v[126:129], v[114:117], v[32:47]
	v_mfma_f32_32x32x16_bf16 v[16:31], v[118:121], v[122:125], v[16:31]
	v_mfma_f32_32x32x16_bf16 v[0:15], v[126:129], v[122:125], v[0:15]
	ds_read_b128 v[114:117], v108
	ds_read_b128 v[118:121], v109 offset:16384
	ds_read_b128 v[122:125], v108 offset:4096
	ds_read_b128 v[126:129], v109 offset:20480
	s_waitcnt lgkmcnt(0)
	v_mfma_f32_32x32x16_bf16 v[48:63], v[118:121], v[114:117], v[48:63]
	v_mfma_f32_32x32x16_bf16 v[32:47], v[126:129], v[114:117], v[32:47]
	v_mfma_f32_32x32x16_bf16 v[16:31], v[118:121], v[122:125], v[16:31]
	v_mfma_f32_32x32x16_bf16 v[0:15], v[126:129], v[122:125], v[0:15]
	ds_read_b128 v[114:117], v110
	ds_read_b128 v[118:121], v111 offset:16384
	ds_read_b128 v[122:125], v110 offset:4096
	ds_read_b128 v[126:129], v111 offset:20480
	s_waitcnt lgkmcnt(0)
	v_mfma_f32_32x32x16_bf16 v[48:63], v[118:121], v[114:117], v[48:63]
	v_mfma_f32_32x32x16_bf16 v[32:47], v[126:129], v[114:117], v[32:47]
	v_mfma_f32_32x32x16_bf16 v[16:31], v[118:121], v[122:125], v[16:31]
	v_mfma_f32_32x32x16_bf16 v[0:15], v[126:129], v[122:125], v[0:15]
	ds_read_b128 v[114:117], v112
	ds_read_b128 v[118:121], v113 offset:16384
	ds_read_b128 v[122:125], v112 offset:4096
	ds_read_b128 v[126:129], v113 offset:20480
	s_waitcnt vmcnt(0)
	s_waitcnt vmcnt(0) lgkmcnt(0)
	s_barrier
	v_mfma_f32_32x32x16_bf16 v[48:63], v[118:121], v[114:117], v[48:63]
	v_mfma_f32_32x32x16_bf16 v[32:47], v[126:129], v[114:117], v[32:47]
	global_load_lds_dwordx4 v64, s[98:99]
	s_mov_b32 m0, s84
	s_nop 0
	global_load_lds_dwordx4 v66, s[98:99]
	s_mov_b32 m0, s85
	v_mfma_f32_32x32x16_bf16 v[16:31], v[118:121], v[122:125], v[16:31]
	global_load_lds_dwordx4 v68, s[98:99]
	s_mov_b32 m0, s86
	s_nop 0
	global_load_lds_dwordx4 v70, s[98:99]
	s_mov_b32 m0, s87
	v_mfma_f32_32x32x16_bf16 v[0:15], v[126:129], v[122:125], v[0:15]
	global_load_lds_dwordx4 v64, s[100:101]
	s_mov_b32 m0, s89
	s_nop 0
	global_load_lds_dwordx4 v66, s[100:101]
	s_mov_b32 m0, s90
	s_nop 0
	global_load_lds_dwordx4 v68, s[100:101]
	s_mov_b32 m0, s91
	s_nop 0
	global_load_lds_dwordx4 v70, s[100:101]
	s_add_u32 s98, s98, 0x80
	s_addc_u32 s99, s99, 0
	s_add_u32 s100, s100, 0x80
	s_addc_u32 s101, s101, 0
	ds_read_b128 v[114:117], v106 offset:32768
	ds_read_b128 v[118:121], v107 offset:49152
	ds_read_b128 v[122:125], v106 offset:36864
	ds_read_b128 v[126:129], v107 offset:53248
	s_waitcnt lgkmcnt(0)
	v_mfma_f32_32x32x16_bf16 v[48:63], v[118:121], v[114:117], v[48:63]
	s_mov_b32 m0, s70
	v_mfma_f32_32x32x16_bf16 v[32:47], v[126:129], v[114:117], v[32:47]
	v_mfma_f32_32x32x16_bf16 v[16:31], v[118:121], v[122:125], v[16:31]
	v_mfma_f32_32x32x16_bf16 v[0:15], v[126:129], v[122:125], v[0:15]
	ds_read_b128 v[114:117], v108 offset:32768
	ds_read_b128 v[118:121], v109 offset:49152
	ds_read_b128 v[122:125], v108 offset:36864
	ds_read_b128 v[126:129], v109 offset:53248
	s_waitcnt lgkmcnt(0)
	v_mfma_f32_32x32x16_bf16 v[48:63], v[118:121], v[114:117], v[48:63]
	v_mfma_f32_32x32x16_bf16 v[32:47], v[126:129], v[114:117], v[32:47]
	v_mfma_f32_32x32x16_bf16 v[16:31], v[118:121], v[122:125], v[16:31]
	v_mfma_f32_32x32x16_bf16 v[0:15], v[126:129], v[122:125], v[0:15]
	ds_read_b128 v[114:117], v110 offset:32768
	ds_read_b128 v[118:121], v111 offset:49152
	ds_read_b128 v[122:125], v110 offset:36864
	ds_read_b128 v[126:129], v111 offset:53248
	s_waitcnt lgkmcnt(0)
	v_mfma_f32_32x32x16_bf16 v[48:63], v[118:121], v[114:117], v[48:63]
	v_mfma_f32_32x32x16_bf16 v[32:47], v[126:129], v[114:117], v[32:47]
	v_mfma_f32_32x32x16_bf16 v[16:31], v[118:121], v[122:125], v[16:31]
	v_mfma_f32_32x32x16_bf16 v[0:15], v[126:129], v[122:125], v[0:15]
	ds_read_b128 v[114:117], v112 offset:32768
	ds_read_b128 v[118:121], v113 offset:49152
	ds_read_b128 v[122:125], v112 offset:36864
	ds_read_b128 v[126:129], v113 offset:53248
	s_waitcnt vmcnt(0)
	s_waitcnt vmcnt(0) lgkmcnt(0)
	s_barrier
	v_mfma_f32_32x32x16_bf16 v[48:63], v[118:121], v[114:117], v[48:63]
	v_mfma_f32_32x32x16_bf16 v[32:47], v[126:129], v[114:117], v[32:47]
	global_load_lds_dwordx4 v64, s[98:99]
	s_mov_b32 m0, s71
	s_nop 0
	global_load_lds_dwordx4 v66, s[98:99]
	s_mov_b32 m0, s72
	v_mfma_f32_32x32x16_bf16 v[16:31], v[118:121], v[122:125], v[16:31]
	global_load_lds_dwordx4 v68, s[98:99]
	s_mov_b32 m0, s73
	s_nop 0
	global_load_lds_dwordx4 v70, s[98:99]
	s_mov_b32 m0, s81
	v_mfma_f32_32x32x16_bf16 v[0:15], v[126:129], v[122:125], v[0:15]
	global_load_lds_dwordx4 v64, s[100:101]
	s_mov_b32 m0, s83
	s_nop 0
	global_load_lds_dwordx4 v66, s[100:101]
	s_mov_b32 m0, s88
	s_nop 0
	global_load_lds_dwordx4 v68, s[100:101]
	s_mov_b32 m0, s28
	s_nop 0
	global_load_lds_dwordx4 v70, s[100:101]
	s_add_u32 s98, s98, 0x80
	s_addc_u32 s99, s99, 0
	s_add_u32 s100, s100, 0x80
	s_addc_u32 s101, s101, 0
	ds_read_b128 v[114:117], v106
	ds_read_b128 v[118:121], v107 offset:16384
	ds_read_b128 v[122:125], v106 offset:4096
	ds_read_b128 v[126:129], v107 offset:20480
	s_waitcnt lgkmcnt(0)
	v_mfma_f32_32x32x16_bf16 v[48:63], v[118:121], v[114:117], v[48:63]
	s_mov_b32 m0, s29
	v_mfma_f32_32x32x16_bf16 v[32:47], v[126:129], v[114:117], v[32:47]
	v_mfma_f32_32x32x16_bf16 v[16:31], v[118:121], v[122:125], v[16:31]
	v_mfma_f32_32x32x16_bf16 v[0:15], v[126:129], v[122:125], v[0:15]
	ds_read_b128 v[114:117], v108
	ds_read_b128 v[118:121], v109 offset:16384
	ds_read_b128 v[122:125], v108 offset:4096
	ds_read_b128 v[126:129], v109 offset:20480
	s_waitcnt lgkmcnt(0)
	v_mfma_f32_32x32x16_bf16 v[48:63], v[118:121], v[114:117], v[48:63]
	v_mfma_f32_32x32x16_bf16 v[32:47], v[126:129], v[114:117], v[32:47]
	v_mfma_f32_32x32x16_bf16 v[16:31], v[118:121], v[122:125], v[16:31]
	v_mfma_f32_32x32x16_bf16 v[0:15], v[126:129], v[122:125], v[0:15]
	ds_read_b128 v[114:117], v110
	ds_read_b128 v[118:121], v111 offset:16384
	ds_read_b128 v[122:125], v110 offset:4096
	ds_read_b128 v[126:129], v111 offset:20480
	s_waitcnt lgkmcnt(0)
	v_mfma_f32_32x32x16_bf16 v[48:63], v[118:121], v[114:117], v[48:63]
	v_mfma_f32_32x32x16_bf16 v[32:47], v[126:129], v[114:117], v[32:47]
	v_mfma_f32_32x32x16_bf16 v[16:31], v[118:121], v[122:125], v[16:31]
	v_mfma_f32_32x32x16_bf16 v[0:15], v[126:129], v[122:125], v[0:15]
	ds_read_b128 v[114:117], v112
	ds_read_b128 v[118:121], v113 offset:16384
	ds_read_b128 v[122:125], v112 offset:4096
	ds_read_b128 v[126:129], v113 offset:20480
	s_waitcnt vmcnt(0)
	s_waitcnt vmcnt(0) lgkmcnt(0)
	s_barrier
	v_mfma_f32_32x32x16_bf16 v[48:63], v[118:121], v[114:117], v[48:63]
	v_mfma_f32_32x32x16_bf16 v[32:47], v[126:129], v[114:117], v[32:47]
	global_load_lds_dwordx4 v64, s[98:99]
	s_mov_b32 m0, s84
	s_nop 0
	global_load_lds_dwordx4 v66, s[98:99]
	s_mov_b32 m0, s85
	v_mfma_f32_32x32x16_bf16 v[16:31], v[118:121], v[122:125], v[16:31]
	global_load_lds_dwordx4 v68, s[98:99]
	s_mov_b32 m0, s86
	s_nop 0
	global_load_lds_dwordx4 v70, s[98:99]
	s_mov_b32 m0, s87
	v_mfma_f32_32x32x16_bf16 v[0:15], v[126:129], v[122:125], v[0:15]
	global_load_lds_dwordx4 v64, s[100:101]
	s_mov_b32 m0, s89
	s_nop 0
	global_load_lds_dwordx4 v66, s[100:101]
	s_mov_b32 m0, s90
	s_nop 0
	global_load_lds_dwordx4 v68, s[100:101]
	s_mov_b32 m0, s91
	s_nop 0
	global_load_lds_dwordx4 v70, s[100:101]
	s_add_u32 s98, s98, 0x80
	s_addc_u32 s99, s99, 0
	s_add_u32 s100, s100, 0x80
	s_addc_u32 s101, s101, 0
	ds_read_b128 v[114:117], v106 offset:32768
	ds_read_b128 v[118:121], v107 offset:49152
	ds_read_b128 v[122:125], v106 offset:36864
	ds_read_b128 v[126:129], v107 offset:53248
	s_waitcnt lgkmcnt(0)
	v_mfma_f32_32x32x16_bf16 v[48:63], v[118:121], v[114:117], v[48:63]
	s_mov_b32 m0, s70
	v_mfma_f32_32x32x16_bf16 v[32:47], v[126:129], v[114:117], v[32:47]
	v_mfma_f32_32x32x16_bf16 v[16:31], v[118:121], v[122:125], v[16:31]
	v_mfma_f32_32x32x16_bf16 v[0:15], v[126:129], v[122:125], v[0:15]
	ds_read_b128 v[114:117], v108 offset:32768
	ds_read_b128 v[118:121], v109 offset:49152
	ds_read_b128 v[122:125], v108 offset:36864
	ds_read_b128 v[126:129], v109 offset:53248
	s_waitcnt lgkmcnt(0)
	v_mfma_f32_32x32x16_bf16 v[48:63], v[118:121], v[114:117], v[48:63]
	v_mfma_f32_32x32x16_bf16 v[32:47], v[126:129], v[114:117], v[32:47]
	v_mfma_f32_32x32x16_bf16 v[16:31], v[118:121], v[122:125], v[16:31]
	v_mfma_f32_32x32x16_bf16 v[0:15], v[126:129], v[122:125], v[0:15]
	ds_read_b128 v[114:117], v110 offset:32768
	ds_read_b128 v[118:121], v111 offset:49152
	ds_read_b128 v[122:125], v110 offset:36864
	ds_read_b128 v[126:129], v111 offset:53248
	s_waitcnt lgkmcnt(0)
	v_mfma_f32_32x32x16_bf16 v[48:63], v[118:121], v[114:117], v[48:63]
	v_mfma_f32_32x32x16_bf16 v[32:47], v[126:129], v[114:117], v[32:47]
	v_mfma_f32_32x32x16_bf16 v[16:31], v[118:121], v[122:125], v[16:31]
	v_mfma_f32_32x32x16_bf16 v[0:15], v[126:129], v[122:125], v[0:15]
	ds_read_b128 v[114:117], v112 offset:32768
	ds_read_b128 v[118:121], v113 offset:49152
	ds_read_b128 v[122:125], v112 offset:36864
	ds_read_b128 v[126:129], v113 offset:53248
	s_waitcnt vmcnt(0)
	s_waitcnt vmcnt(0) lgkmcnt(0)
	s_barrier
	v_mfma_f32_32x32x16_bf16 v[48:63], v[118:121], v[114:117], v[48:63]
	v_mfma_f32_32x32x16_bf16 v[32:47], v[126:129], v[114:117], v[32:47]
	global_load_lds_dwordx4 v64, s[98:99]
	s_mov_b32 m0, s71
	s_nop 0
	global_load_lds_dwordx4 v66, s[98:99]
	s_mov_b32 m0, s72
	v_mfma_f32_32x32x16_bf16 v[16:31], v[118:121], v[122:125], v[16:31]
	global_load_lds_dwordx4 v68, s[98:99]
	s_mov_b32 m0, s73
	s_nop 0
	global_load_lds_dwordx4 v70, s[98:99]
	s_mov_b32 m0, s81
	v_mfma_f32_32x32x16_bf16 v[0:15], v[126:129], v[122:125], v[0:15]
	global_load_lds_dwordx4 v64, s[100:101]
	s_mov_b32 m0, s83
	s_nop 0
	global_load_lds_dwordx4 v66, s[100:101]
	s_mov_b32 m0, s88
	s_nop 0
	global_load_lds_dwordx4 v68, s[100:101]
	s_mov_b32 m0, s28
	s_nop 0
	global_load_lds_dwordx4 v70, s[100:101]
	s_add_u32 s98, s98, 0x80
	s_addc_u32 s99, s99, 0
	s_add_u32 s100, s100, 0x80
	s_addc_u32 s101, s101, 0
	ds_read_b128 v[114:117], v106
	ds_read_b128 v[118:121], v107 offset:16384
	ds_read_b128 v[122:125], v106 offset:4096
	ds_read_b128 v[126:129], v107 offset:20480
	s_waitcnt lgkmcnt(0)
	v_mfma_f32_32x32x16_bf16 v[48:63], v[118:121], v[114:117], v[48:63]
	s_mov_b32 m0, s29
	v_readfirstlane_b32 s29, v91
	v_mfma_f32_32x32x16_bf16 v[32:47], v[126:129], v[114:117], v[32:47]
	v_mfma_f32_32x32x16_bf16 v[16:31], v[118:121], v[122:125], v[16:31]
	v_mfma_f32_32x32x16_bf16 v[0:15], v[126:129], v[122:125], v[0:15]
	ds_read_b128 v[114:117], v108
	ds_read_b128 v[118:121], v109 offset:16384
	ds_read_b128 v[122:125], v108 offset:4096
	ds_read_b128 v[126:129], v109 offset:20480
	s_waitcnt lgkmcnt(0)
	v_mfma_f32_32x32x16_bf16 v[48:63], v[118:121], v[114:117], v[48:63]
	v_mfma_f32_32x32x16_bf16 v[32:47], v[126:129], v[114:117], v[32:47]
	v_mfma_f32_32x32x16_bf16 v[16:31], v[118:121], v[122:125], v[16:31]
	v_mfma_f32_32x32x16_bf16 v[0:15], v[126:129], v[122:125], v[0:15]
	ds_read_b128 v[114:117], v110
	ds_read_b128 v[118:121], v111 offset:16384
	ds_read_b128 v[122:125], v110 offset:4096
	ds_read_b128 v[126:129], v111 offset:20480
	s_waitcnt lgkmcnt(0)
	v_mfma_f32_32x32x16_bf16 v[48:63], v[118:121], v[114:117], v[48:63]
	v_mfma_f32_32x32x16_bf16 v[32:47], v[126:129], v[114:117], v[32:47]
	v_mfma_f32_32x32x16_bf16 v[16:31], v[118:121], v[122:125], v[16:31]
	v_mfma_f32_32x32x16_bf16 v[0:15], v[126:129], v[122:125], v[0:15]
	ds_read_b128 v[114:117], v112
	ds_read_b128 v[118:121], v113 offset:16384
	ds_read_b128 v[122:125], v112 offset:4096
	ds_read_b128 v[126:129], v113 offset:20480
	s_waitcnt vmcnt(0)
	s_waitcnt vmcnt(0) lgkmcnt(0)
	s_barrier
	v_mfma_f32_32x32x16_bf16 v[48:63], v[118:121], v[114:117], v[48:63]
	v_mfma_f32_32x32x16_bf16 v[32:47], v[126:129], v[114:117], v[32:47]
	global_load_lds_dwordx4 v64, s[98:99]
	s_mov_b32 m0, s84
	v_readfirstlane_b32 s84, v100
	global_load_lds_dwordx4 v66, s[98:99]
	s_mov_b32 m0, s85
	v_mfma_f32_32x32x16_bf16 v[16:31], v[118:121], v[122:125], v[16:31]
	global_load_lds_dwordx4 v68, s[98:99]
	s_mov_b32 m0, s86
	v_readfirstlane_b32 s85, v101
	global_load_lds_dwordx4 v70, s[98:99]
	s_mov_b32 m0, s87
	v_mfma_f32_32x32x16_bf16 v[0:15], v[126:129], v[122:125], v[0:15]
	global_load_lds_dwordx4 v64, s[100:101]
	s_mov_b32 m0, s89
	v_readfirstlane_b32 s86, v102
	global_load_lds_dwordx4 v66, s[100:101]
	s_mov_b32 m0, s90
	v_readfirstlane_b32 s87, v103
	global_load_lds_dwordx4 v68, s[100:101]
	s_mov_b32 m0, s91
	v_readfirstlane_b32 s89, v105
	global_load_lds_dwordx4 v70, s[100:101]
	s_add_u32 s98, s98, 0x80
	s_addc_u32 s99, s99, 0
	s_add_u32 s100, s100, 0x80
	s_addc_u32 s101, s101, 0
	ds_read_b128 v[114:117], v106 offset:32768
	ds_read_b128 v[118:121], v107 offset:49152
	ds_read_b128 v[122:125], v106 offset:36864
	ds_read_b128 v[126:129], v107 offset:53248
	s_waitcnt lgkmcnt(0)
	v_mfma_f32_32x32x16_bf16 v[48:63], v[118:121], v[114:117], v[48:63]
	s_mov_b32 m0, s70
	v_readfirstlane_b32 s70, v94
	v_mfma_f32_32x32x16_bf16 v[32:47], v[126:129], v[114:117], v[32:47]
	v_mfma_f32_32x32x16_bf16 v[16:31], v[118:121], v[122:125], v[16:31]
	v_mfma_f32_32x32x16_bf16 v[0:15], v[126:129], v[122:125], v[0:15]
	ds_read_b128 v[114:117], v108 offset:32768
	ds_read_b128 v[118:121], v109 offset:49152
	ds_read_b128 v[122:125], v108 offset:36864
	ds_read_b128 v[126:129], v109 offset:53248
	s_waitcnt lgkmcnt(0)
	v_mfma_f32_32x32x16_bf16 v[48:63], v[118:121], v[114:117], v[48:63]
	v_mfma_f32_32x32x16_bf16 v[32:47], v[126:129], v[114:117], v[32:47]
	v_mfma_f32_32x32x16_bf16 v[16:31], v[118:121], v[122:125], v[16:31]
	v_mfma_f32_32x32x16_bf16 v[0:15], v[126:129], v[122:125], v[0:15]
	ds_read_b128 v[114:117], v110 offset:32768
	ds_read_b128 v[118:121], v111 offset:49152
	ds_read_b128 v[122:125], v110 offset:36864
	ds_read_b128 v[126:129], v111 offset:53248
	s_waitcnt lgkmcnt(0)
	v_mfma_f32_32x32x16_bf16 v[48:63], v[118:121], v[114:117], v[48:63]
	v_mfma_f32_32x32x16_bf16 v[32:47], v[126:129], v[114:117], v[32:47]
	v_mfma_f32_32x32x16_bf16 v[16:31], v[118:121], v[122:125], v[16:31]
	v_mfma_f32_32x32x16_bf16 v[0:15], v[126:129], v[122:125], v[0:15]
	ds_read_b128 v[114:117], v112 offset:32768
	ds_read_b128 v[118:121], v113 offset:49152
	ds_read_b128 v[122:125], v112 offset:36864
	ds_read_b128 v[126:129], v113 offset:53248
	s_waitcnt vmcnt(0)
	s_waitcnt vmcnt(0) lgkmcnt(0)
	s_barrier
	v_mfma_f32_32x32x16_bf16 v[48:63], v[118:121], v[114:117], v[48:63]
	v_mfma_f32_32x32x16_bf16 v[32:47], v[126:129], v[114:117], v[32:47]
	global_load_lds_dwordx4 v64, s[98:99]
	s_mov_b32 m0, s71
	v_readfirstlane_b32 s71, v95
	global_load_lds_dwordx4 v66, s[98:99]
	s_mov_b32 m0, s72
	v_mfma_f32_32x32x16_bf16 v[16:31], v[118:121], v[122:125], v[16:31]
	global_load_lds_dwordx4 v68, s[98:99]
	s_mov_b32 m0, s73
	v_readfirstlane_b32 s72, v96
	global_load_lds_dwordx4 v70, s[98:99]
	s_mov_b32 m0, s81
	v_mfma_f32_32x32x16_bf16 v[0:15], v[126:129], v[122:125], v[0:15]
	global_load_lds_dwordx4 v64, s[100:101]
	s_mov_b32 m0, s83
	v_readfirstlane_b32 s73, v97
	global_load_lds_dwordx4 v66, s[100:101]
	s_mov_b32 m0, s88
	v_readfirstlane_b32 s81, v98
	global_load_lds_dwordx4 v68, s[100:101]
	s_mov_b32 m0, s28
	v_readfirstlane_b32 s28, v88
	global_load_lds_dwordx4 v70, s[100:101]
	s_add_u32 s98, s98, 0x80
	s_addc_u32 s99, s99, 0
	s_add_u32 s100, s100, 0x80
	s_addc_u32 s101, s101, 0
	ds_read_b128 v[114:117], v106
	ds_read_b128 v[118:121], v107 offset:16384
	ds_read_b128 v[122:125], v106 offset:4096
	ds_read_b128 v[126:129], v107 offset:20480
	s_waitcnt lgkmcnt(0)
	v_mfma_f32_32x32x16_bf16 v[48:63], v[118:121], v[114:117], v[48:63]
	s_mov_b32 m0, s28
	v_readfirstlane_b32 s83, v99
	v_readfirstlane_b32 s88, v104
	v_mfma_f32_32x32x16_bf16 v[32:47], v[126:129], v[114:117], v[32:47]
	v_mfma_f32_32x32x16_bf16 v[16:31], v[118:121], v[122:125], v[16:31]
	v_mfma_f32_32x32x16_bf16 v[0:15], v[126:129], v[122:125], v[0:15]
	ds_read_b128 v[114:117], v108
	ds_read_b128 v[118:121], v109 offset:16384
	ds_read_b128 v[122:125], v108 offset:4096
	ds_read_b128 v[126:129], v109 offset:20480
	s_waitcnt lgkmcnt(0)
	v_mfma_f32_32x32x16_bf16 v[48:63], v[118:121], v[114:117], v[48:63]
	v_mfma_f32_32x32x16_bf16 v[32:47], v[126:129], v[114:117], v[32:47]
	v_mfma_f32_32x32x16_bf16 v[16:31], v[118:121], v[122:125], v[16:31]
	v_mfma_f32_32x32x16_bf16 v[0:15], v[126:129], v[122:125], v[0:15]
	ds_read_b128 v[114:117], v110
	ds_read_b128 v[118:121], v111 offset:16384
	ds_read_b128 v[122:125], v110 offset:4096
	ds_read_b128 v[126:129], v111 offset:20480
	s_waitcnt lgkmcnt(0)
	v_mfma_f32_32x32x16_bf16 v[48:63], v[118:121], v[114:117], v[48:63]
	v_mfma_f32_32x32x16_bf16 v[32:47], v[126:129], v[114:117], v[32:47]
	v_mfma_f32_32x32x16_bf16 v[16:31], v[118:121], v[122:125], v[16:31]
	v_mfma_f32_32x32x16_bf16 v[0:15], v[126:129], v[122:125], v[0:15]
	ds_read_b128 v[114:117], v112
	ds_read_b128 v[118:121], v113 offset:16384
	ds_read_b128 v[122:125], v112 offset:4096
	ds_read_b128 v[126:129], v113 offset:20480
	s_waitcnt vmcnt(0)
	s_waitcnt vmcnt(0) lgkmcnt(0)
	s_barrier
	v_mfma_f32_32x32x16_bf16 v[48:63], v[118:121], v[114:117], v[48:63]
	v_mfma_f32_32x32x16_bf16 v[32:47], v[126:129], v[114:117], v[32:47]
	global_load_lds_dwordx4 v64, s[98:99]
	s_mov_b32 m0, s29
	s_nop 0
	global_load_lds_dwordx4 v66, s[98:99]
	s_mov_b32 m0, s34
	v_mfma_f32_32x32x16_bf16 v[16:31], v[118:121], v[122:125], v[16:31]
	global_load_lds_dwordx4 v68, s[98:99]
	s_mov_b32 m0, s35
	s_nop 0
	global_load_lds_dwordx4 v70, s[98:99]
	s_mov_b32 m0, s70
	v_mfma_f32_32x32x16_bf16 v[0:15], v[126:129], v[122:125], v[0:15]
	global_load_lds_dwordx4 v64, s[100:101]
	s_mov_b32 m0, s71
	s_nop 0
	global_load_lds_dwordx4 v66, s[100:101]
	s_mov_b32 m0, s72
	s_nop 0
	global_load_lds_dwordx4 v68, s[100:101]
	s_mov_b32 m0, s73
	s_nop 0
	global_load_lds_dwordx4 v70, s[100:101]
	s_add_u32 s98, s98, 0x80
	s_addc_u32 s99, s99, 0
	s_add_u32 s100, s100, 0x80
	s_addc_u32 s101, s101, 0
	ds_read_b128 v[114:117], v106 offset:32768
	ds_read_b128 v[118:121], v107 offset:49152
	ds_read_b128 v[122:125], v106 offset:36864
	ds_read_b128 v[126:129], v107 offset:53248
	s_waitcnt lgkmcnt(0)
	v_mfma_f32_32x32x16_bf16 v[48:63], v[118:121], v[114:117], v[48:63]
	s_mov_b32 m0, s81
	v_mfma_f32_32x32x16_bf16 v[32:47], v[126:129], v[114:117], v[32:47]
	v_mfma_f32_32x32x16_bf16 v[16:31], v[118:121], v[122:125], v[16:31]
	v_mfma_f32_32x32x16_bf16 v[0:15], v[126:129], v[122:125], v[0:15]
	ds_read_b128 v[114:117], v108 offset:32768
	ds_read_b128 v[118:121], v109 offset:49152
	ds_read_b128 v[122:125], v108 offset:36864
	ds_read_b128 v[126:129], v109 offset:53248
	s_waitcnt lgkmcnt(0)
	v_mfma_f32_32x32x16_bf16 v[48:63], v[118:121], v[114:117], v[48:63]
	v_mfma_f32_32x32x16_bf16 v[32:47], v[126:129], v[114:117], v[32:47]
	v_mfma_f32_32x32x16_bf16 v[16:31], v[118:121], v[122:125], v[16:31]
	v_mfma_f32_32x32x16_bf16 v[0:15], v[126:129], v[122:125], v[0:15]
	ds_read_b128 v[114:117], v110 offset:32768
	ds_read_b128 v[118:121], v111 offset:49152
	ds_read_b128 v[122:125], v110 offset:36864
	ds_read_b128 v[126:129], v111 offset:53248
	s_waitcnt lgkmcnt(0)
	v_mfma_f32_32x32x16_bf16 v[48:63], v[118:121], v[114:117], v[48:63]
	v_mfma_f32_32x32x16_bf16 v[32:47], v[126:129], v[114:117], v[32:47]
	v_mfma_f32_32x32x16_bf16 v[16:31], v[118:121], v[122:125], v[16:31]
	v_mfma_f32_32x32x16_bf16 v[0:15], v[126:129], v[122:125], v[0:15]
	ds_read_b128 v[114:117], v112 offset:32768
	ds_read_b128 v[118:121], v113 offset:49152
	ds_read_b128 v[122:125], v112 offset:36864
	ds_read_b128 v[126:129], v113 offset:53248
	s_waitcnt vmcnt(0)
	s_waitcnt vmcnt(0) lgkmcnt(0)
	s_barrier
	v_mfma_f32_32x32x16_bf16 v[48:63], v[118:121], v[114:117], v[48:63]
	v_mfma_f32_32x32x16_bf16 v[32:47], v[126:129], v[114:117], v[32:47]
	global_load_lds_dwordx4 v64, s[98:99]
	s_mov_b32 m0, s83
	s_nop 0
	global_load_lds_dwordx4 v66, s[98:99]
	s_mov_b32 m0, s84
	v_mfma_f32_32x32x16_bf16 v[16:31], v[118:121], v[122:125], v[16:31]
	global_load_lds_dwordx4 v68, s[98:99]
	s_mov_b32 m0, s85
	s_nop 0
	global_load_lds_dwordx4 v70, s[98:99]
	s_mov_b32 m0, s86
	v_mfma_f32_32x32x16_bf16 v[0:15], v[126:129], v[122:125], v[0:15]
	global_load_lds_dwordx4 v64, s[100:101]
	s_mov_b32 m0, s87
	s_nop 0
	global_load_lds_dwordx4 v66, s[100:101]
	s_mov_b32 m0, s88
	s_nop 0
	global_load_lds_dwordx4 v68, s[100:101]
	s_mov_b32 m0, s89
	s_nop 0
	global_load_lds_dwordx4 v70, s[100:101]
	s_add_u32 s98, s98, 0x80
	s_addc_u32 s99, s99, 0
	s_add_u32 s100, s100, 0x80
	s_addc_u32 s101, s101, 0
	ds_read_b128 v[114:117], v106
	ds_read_b128 v[118:121], v107 offset:16384
	ds_read_b128 v[122:125], v106 offset:4096
	ds_read_b128 v[126:129], v107 offset:20480
	s_waitcnt lgkmcnt(0)
	v_mfma_f32_32x32x16_bf16 v[48:63], v[118:121], v[114:117], v[48:63]
	s_mov_b32 m0, s28
	v_mfma_f32_32x32x16_bf16 v[32:47], v[126:129], v[114:117], v[32:47]
	v_mfma_f32_32x32x16_bf16 v[16:31], v[118:121], v[122:125], v[16:31]
	v_mfma_f32_32x32x16_bf16 v[0:15], v[126:129], v[122:125], v[0:15]
	ds_read_b128 v[114:117], v108
	ds_read_b128 v[118:121], v109 offset:16384
	ds_read_b128 v[122:125], v108 offset:4096
	ds_read_b128 v[126:129], v109 offset:20480
	s_waitcnt lgkmcnt(0)
	v_mfma_f32_32x32x16_bf16 v[48:63], v[118:121], v[114:117], v[48:63]
	v_mfma_f32_32x32x16_bf16 v[32:47], v[126:129], v[114:117], v[32:47]
	v_mfma_f32_32x32x16_bf16 v[16:31], v[118:121], v[122:125], v[16:31]
	v_mfma_f32_32x32x16_bf16 v[0:15], v[126:129], v[122:125], v[0:15]
	ds_read_b128 v[114:117], v110
	ds_read_b128 v[118:121], v111 offset:16384
	ds_read_b128 v[122:125], v110 offset:4096
	ds_read_b128 v[126:129], v111 offset:20480
	s_waitcnt lgkmcnt(0)
	v_mfma_f32_32x32x16_bf16 v[48:63], v[118:121], v[114:117], v[48:63]
	v_mfma_f32_32x32x16_bf16 v[32:47], v[126:129], v[114:117], v[32:47]
	v_mfma_f32_32x32x16_bf16 v[16:31], v[118:121], v[122:125], v[16:31]
	v_mfma_f32_32x32x16_bf16 v[0:15], v[126:129], v[122:125], v[0:15]
	ds_read_b128 v[114:117], v112
	ds_read_b128 v[118:121], v113 offset:16384
	ds_read_b128 v[122:125], v112 offset:4096
	ds_read_b128 v[126:129], v113 offset:20480
	s_waitcnt vmcnt(0)
	s_waitcnt vmcnt(0) lgkmcnt(0)
	s_barrier
	v_mfma_f32_32x32x16_bf16 v[48:63], v[118:121], v[114:117], v[48:63]
	v_mfma_f32_32x32x16_bf16 v[32:47], v[126:129], v[114:117], v[32:47]
	global_load_lds_dwordx4 v64, s[98:99]
	s_mov_b32 m0, s29
	s_nop 0
	global_load_lds_dwordx4 v66, s[98:99]
	s_mov_b32 m0, s34
	v_mfma_f32_32x32x16_bf16 v[16:31], v[118:121], v[122:125], v[16:31]
	global_load_lds_dwordx4 v68, s[98:99]
	s_mov_b32 m0, s35
	s_nop 0
	global_load_lds_dwordx4 v70, s[98:99]
	s_mov_b32 m0, s70
	v_mfma_f32_32x32x16_bf16 v[0:15], v[126:129], v[122:125], v[0:15]
	global_load_lds_dwordx4 v64, s[100:101]
	s_mov_b32 m0, s71
	s_nop 0
	global_load_lds_dwordx4 v66, s[100:101]
	s_mov_b32 m0, s72
	s_nop 0
	global_load_lds_dwordx4 v68, s[100:101]
	s_mov_b32 m0, s73
	s_nop 0
	global_load_lds_dwordx4 v70, s[100:101]
	s_add_u32 s98, s98, 0x80
	s_addc_u32 s99, s99, 0
	s_add_u32 s100, s100, 0x80
	s_addc_u32 s101, s101, 0
	ds_read_b128 v[114:117], v106 offset:32768
	ds_read_b128 v[118:121], v107 offset:49152
	ds_read_b128 v[122:125], v106 offset:36864
	ds_read_b128 v[126:129], v107 offset:53248
	s_waitcnt lgkmcnt(0)
	v_mfma_f32_32x32x16_bf16 v[48:63], v[118:121], v[114:117], v[48:63]
	s_mov_b32 m0, s81
	v_mfma_f32_32x32x16_bf16 v[32:47], v[126:129], v[114:117], v[32:47]
	v_mfma_f32_32x32x16_bf16 v[16:31], v[118:121], v[122:125], v[16:31]
	v_mfma_f32_32x32x16_bf16 v[0:15], v[126:129], v[122:125], v[0:15]
	ds_read_b128 v[114:117], v108 offset:32768
	ds_read_b128 v[118:121], v109 offset:49152
	ds_read_b128 v[122:125], v108 offset:36864
	ds_read_b128 v[126:129], v109 offset:53248
	s_waitcnt lgkmcnt(0)
	v_mfma_f32_32x32x16_bf16 v[48:63], v[118:121], v[114:117], v[48:63]
	v_mfma_f32_32x32x16_bf16 v[32:47], v[126:129], v[114:117], v[32:47]
	v_mfma_f32_32x32x16_bf16 v[16:31], v[118:121], v[122:125], v[16:31]
	v_mfma_f32_32x32x16_bf16 v[0:15], v[126:129], v[122:125], v[0:15]
	ds_read_b128 v[114:117], v110 offset:32768
	ds_read_b128 v[118:121], v111 offset:49152
	ds_read_b128 v[122:125], v110 offset:36864
	ds_read_b128 v[126:129], v111 offset:53248
	s_waitcnt lgkmcnt(0)
	v_mfma_f32_32x32x16_bf16 v[48:63], v[118:121], v[114:117], v[48:63]
	v_mfma_f32_32x32x16_bf16 v[32:47], v[126:129], v[114:117], v[32:47]
	v_mfma_f32_32x32x16_bf16 v[16:31], v[118:121], v[122:125], v[16:31]
	v_mfma_f32_32x32x16_bf16 v[0:15], v[126:129], v[122:125], v[0:15]
	ds_read_b128 v[114:117], v112 offset:32768
	ds_read_b128 v[118:121], v113 offset:49152
	ds_read_b128 v[122:125], v112 offset:36864
	ds_read_b128 v[126:129], v113 offset:53248
	s_waitcnt vmcnt(0)
	s_waitcnt vmcnt(0) lgkmcnt(0)
	s_barrier
	v_mfma_f32_32x32x16_bf16 v[48:63], v[118:121], v[114:117], v[48:63]
	v_mfma_f32_32x32x16_bf16 v[32:47], v[126:129], v[114:117], v[32:47]
	global_load_lds_dwordx4 v64, s[98:99]
	s_mov_b32 m0, s83
	s_nop 0
	global_load_lds_dwordx4 v66, s[98:99]
	s_mov_b32 m0, s84
	v_mfma_f32_32x32x16_bf16 v[16:31], v[118:121], v[122:125], v[16:31]
	global_load_lds_dwordx4 v68, s[98:99]
	s_mov_b32 m0, s85
	s_nop 0
	global_load_lds_dwordx4 v70, s[98:99]
	s_mov_b32 m0, s86
	v_mfma_f32_32x32x16_bf16 v[0:15], v[126:129], v[122:125], v[0:15]
	global_load_lds_dwordx4 v64, s[100:101]
	s_mov_b32 m0, s87
	s_nop 0
	global_load_lds_dwordx4 v66, s[100:101]
	s_mov_b32 m0, s88
	s_nop 0
	global_load_lds_dwordx4 v68, s[100:101]
	s_mov_b32 m0, s89
	s_nop 0
	global_load_lds_dwordx4 v70, s[100:101]
	s_add_u32 s98, s98, 0x80
	s_addc_u32 s99, s99, 0
	s_add_u32 s100, s100, 0x80
	s_addc_u32 s101, s101, 0
	ds_read_b128 v[114:117], v106
	ds_read_b128 v[118:121], v107 offset:16384
	ds_read_b128 v[122:125], v106 offset:4096
	ds_read_b128 v[126:129], v107 offset:20480
	s_waitcnt lgkmcnt(0)
	v_mfma_f32_32x32x16_bf16 v[48:63], v[118:121], v[114:117], v[48:63]
	s_mov_b32 m0, s28
	v_mfma_f32_32x32x16_bf16 v[32:47], v[126:129], v[114:117], v[32:47]
	v_mfma_f32_32x32x16_bf16 v[16:31], v[118:121], v[122:125], v[16:31]
	v_mfma_f32_32x32x16_bf16 v[0:15], v[126:129], v[122:125], v[0:15]
	ds_read_b128 v[114:117], v108
	ds_read_b128 v[118:121], v109 offset:16384
	ds_read_b128 v[122:125], v108 offset:4096
	ds_read_b128 v[126:129], v109 offset:20480
	s_waitcnt lgkmcnt(0)
	v_mfma_f32_32x32x16_bf16 v[48:63], v[118:121], v[114:117], v[48:63]
	v_mfma_f32_32x32x16_bf16 v[32:47], v[126:129], v[114:117], v[32:47]
	v_mfma_f32_32x32x16_bf16 v[16:31], v[118:121], v[122:125], v[16:31]
	v_mfma_f32_32x32x16_bf16 v[0:15], v[126:129], v[122:125], v[0:15]
	ds_read_b128 v[114:117], v110
	ds_read_b128 v[118:121], v111 offset:16384
	ds_read_b128 v[122:125], v110 offset:4096
	ds_read_b128 v[126:129], v111 offset:20480
	s_waitcnt lgkmcnt(0)
	v_mfma_f32_32x32x16_bf16 v[48:63], v[118:121], v[114:117], v[48:63]
	v_mfma_f32_32x32x16_bf16 v[32:47], v[126:129], v[114:117], v[32:47]
	v_mfma_f32_32x32x16_bf16 v[16:31], v[118:121], v[122:125], v[16:31]
	v_mfma_f32_32x32x16_bf16 v[0:15], v[126:129], v[122:125], v[0:15]
	ds_read_b128 v[114:117], v112
	ds_read_b128 v[118:121], v113 offset:16384
	ds_read_b128 v[122:125], v112 offset:4096
	ds_read_b128 v[126:129], v113 offset:20480
	s_waitcnt vmcnt(0)
	s_waitcnt vmcnt(0) lgkmcnt(0)
	s_barrier
	v_mfma_f32_32x32x16_bf16 v[48:63], v[118:121], v[114:117], v[48:63]
	v_mfma_f32_32x32x16_bf16 v[32:47], v[126:129], v[114:117], v[32:47]
	global_load_lds_dwordx4 v64, s[98:99]
	s_mov_b32 m0, s29
	s_nop 0
	global_load_lds_dwordx4 v66, s[98:99]
	s_mov_b32 m0, s34
	v_mfma_f32_32x32x16_bf16 v[16:31], v[118:121], v[122:125], v[16:31]
	global_load_lds_dwordx4 v68, s[98:99]
	s_mov_b32 m0, s35
	s_nop 0
	global_load_lds_dwordx4 v70, s[98:99]
	s_mov_b32 m0, s70
	v_mfma_f32_32x32x16_bf16 v[0:15], v[126:129], v[122:125], v[0:15]
	global_load_lds_dwordx4 v64, s[100:101]
	s_mov_b32 m0, s71
	s_nop 0
	global_load_lds_dwordx4 v66, s[100:101]
	s_mov_b32 m0, s72
	s_nop 0
	global_load_lds_dwordx4 v68, s[100:101]
	s_mov_b32 m0, s73
	s_nop 0
	global_load_lds_dwordx4 v70, s[100:101]
	s_add_u32 s98, s98, 0x80
	s_addc_u32 s99, s99, 0
	s_add_u32 s100, s100, 0x80
	s_addc_u32 s101, s101, 0
	ds_read_b128 v[114:117], v106 offset:32768
	ds_read_b128 v[118:121], v107 offset:49152
	ds_read_b128 v[122:125], v106 offset:36864
	ds_read_b128 v[126:129], v107 offset:53248
	s_waitcnt lgkmcnt(0)
	v_mfma_f32_32x32x16_bf16 v[16:31], v[118:121], v[122:125], v[16:31]
	s_mov_b32 m0, s81
	v_mfma_f32_32x32x16_bf16 v[0:15], v[126:129], v[122:125], v[0:15]
	v_mfma_f32_32x32x16_bf16 v[32:47], v[126:129], v[114:117], v[32:47]
	v_mfma_f32_32x32x16_bf16 v[48:63], v[118:121], v[114:117], v[48:63]
	ds_read_b128 v[114:117], v108 offset:32768
	ds_read_b128 v[118:121], v109 offset:49152
	ds_read_b128 v[122:125], v108 offset:36864
	ds_read_b128 v[126:129], v109 offset:53248
	s_waitcnt lgkmcnt(0)
	v_mfma_f32_32x32x16_bf16 v[16:31], v[118:121], v[122:125], v[16:31]
	v_mfma_f32_32x32x16_bf16 v[0:15], v[126:129], v[122:125], v[0:15]
	v_mfma_f32_32x32x16_bf16 v[32:47], v[126:129], v[114:117], v[32:47]
	v_mfma_f32_32x32x16_bf16 v[48:63], v[118:121], v[114:117], v[48:63]
	ds_read_b128 v[114:117], v110 offset:32768
	ds_read_b128 v[118:121], v111 offset:49152
	ds_read_b128 v[122:125], v110 offset:36864
	ds_read_b128 v[126:129], v111 offset:53248
	s_waitcnt lgkmcnt(0)
	v_mfma_f32_32x32x16_bf16 v[16:31], v[118:121], v[122:125], v[16:31]
	v_mfma_f32_32x32x16_bf16 v[0:15], v[126:129], v[122:125], v[0:15]
	v_mfma_f32_32x32x16_bf16 v[32:47], v[126:129], v[114:117], v[32:47]
	v_mfma_f32_32x32x16_bf16 v[48:63], v[118:121], v[114:117], v[48:63]
	ds_read_b128 v[114:117], v112 offset:32768
	ds_read_b128 v[118:121], v113 offset:49152
	ds_read_b128 v[122:125], v112 offset:36864
	ds_read_b128 v[126:129], v113 offset:53248
	s_waitcnt vmcnt(0)
	s_waitcnt vmcnt(0) lgkmcnt(0)
	s_barrier
	global_load_lds_dwordx4 v64, s[98:99]
	s_mov_b32 m0, s83
	v_mfma_f32_32x32x16_bf16 v[16:31], v[118:121], v[122:125], v[16:31]
	global_load_lds_dwordx4 v66, s[98:99]
	s_mov_b32 m0, s84
	s_nop 0
	global_load_lds_dwordx4 v68, s[98:99]
	s_mov_b32 m0, s85
	v_mfma_f32_32x32x16_bf16 v[0:15], v[126:129], v[122:125], v[0:15]
	global_load_lds_dwordx4 v70, s[98:99]
	s_mov_b32 m0, s86
	s_nop 0
	global_load_lds_dwordx4 v64, s[100:101]
	s_mov_b32 m0, s87
	v_mfma_f32_32x32x16_bf16 v[32:47], v[126:129], v[114:117], v[32:47]
	global_load_lds_dwordx4 v66, s[100:101]
	s_mov_b32 m0, s88
	s_nop 0
	global_load_lds_dwordx4 v68, s[100:101]
	s_mov_b32 m0, s89
	v_mfma_f32_32x32x16_bf16 v[48:63], v[118:121], v[114:117], v[48:63]
	global_load_lds_dwordx4 v70, s[100:101]
	ds_read_b128 v[72:75], v106
	ds_read_b128 v[76:79], v107 offset:16384
	ds_read_b128 v[80:83], v106 offset:4096
	ds_read_b128 v[84:87], v107 offset:20480
	s_waitcnt lgkmcnt(0)
	v_mfma_f32_32x32x16_bf16 v[16:31], v[76:79], v[80:83], v[16:31]
	v_mfma_f32_32x32x16_bf16 v[0:15], v[84:87], v[80:83], v[0:15]
	v_mfma_f32_32x32x16_bf16 v[32:47], v[84:87], v[72:75], v[32:47]
	v_mfma_f32_32x32x16_bf16 v[48:63], v[76:79], v[72:75], v[48:63]
	ds_read_b128 v[72:75], v108
	ds_read_b128 v[76:79], v109 offset:16384
	ds_read_b128 v[80:83], v108 offset:4096
	ds_read_b128 v[84:87], v109 offset:20480
	s_waitcnt lgkmcnt(0)
	v_mfma_f32_32x32x16_bf16 v[16:31], v[76:79], v[80:83], v[16:31]
	v_mfma_f32_32x32x16_bf16 v[0:15], v[84:87], v[80:83], v[0:15]
	v_mfma_f32_32x32x16_bf16 v[32:47], v[84:87], v[72:75], v[32:47]
	v_mfma_f32_32x32x16_bf16 v[48:63], v[76:79], v[72:75], v[48:63]
	ds_read_b128 v[72:75], v110
	ds_read_b128 v[76:79], v111 offset:16384
	ds_read_b128 v[80:83], v110 offset:4096
	ds_read_b128 v[84:87], v111 offset:20480
	s_waitcnt lgkmcnt(0)
	v_mfma_f32_32x32x16_bf16 v[16:31], v[76:79], v[80:83], v[16:31]
	v_mfma_f32_32x32x16_bf16 v[0:15], v[84:87], v[80:83], v[0:15]
	v_mfma_f32_32x32x16_bf16 v[32:47], v[84:87], v[72:75], v[32:47]
	v_mfma_f32_32x32x16_bf16 v[48:63], v[76:79], v[72:75], v[48:63]
	ds_read_b128 v[72:75], v112
	ds_read_b128 v[76:79], v113 offset:16384
	ds_read_b128 v[80:83], v112 offset:4096
	ds_read_b128 v[84:87], v113 offset:20480
	s_waitcnt vmcnt(0)
	s_waitcnt vmcnt(0) lgkmcnt(0)
	s_barrier
	v_mfma_f32_32x32x16_bf16 v[16:31], v[76:79], v[80:83], v[16:31]
	v_mfma_f32_32x32x16_bf16 v[0:15], v[84:87], v[80:83], v[0:15]
	v_mfma_f32_32x32x16_bf16 v[32:47], v[84:87], v[72:75], v[32:47]
	v_mfma_f32_32x32x16_bf16 v[48:63], v[76:79], v[72:75], v[48:63]
	ds_read_b128 v[72:75], v113 offset:53248
	ds_read_b128 v[76:79], v112 offset:36864
	ds_read_b128 v[80:83], v113 offset:49152
	ds_read_b128 v[84:87], v112 offset:32768
	ds_read_b128 v[114:117], v111 offset:53248
	ds_read_b128 v[118:121], v110 offset:36864
	ds_read_b128 v[122:125], v111 offset:49152
	ds_read_b128 v[126:129], v110 offset:32768
	ds_read_b128 v[130:133], v109 offset:53248
	ds_read_b128 v[134:137], v108 offset:36864
	ds_read_b128 v[138:141], v109 offset:49152
	ds_read_b128 v[142:145], v108 offset:32768
	ds_read_b128 v[146:149], v107 offset:53248
	ds_read_b128 v[150:153], v106 offset:36864
	ds_read_b128 v[156:159], v107 offset:49152
	ds_read_b128 v[160:163], v106 offset:32768
	s_waitcnt vmcnt(0)
	s_waitcnt lgkmcnt(0)
	s_barrier
	v_mfma_f32_32x32x16_bf16 v[16:31], v[156:159], v[150:153], v[16:31]
	v_mfma_f32_32x32x16_bf16 v[0:15], v[146:149], v[150:153], v[0:15]
	v_mfma_f32_32x32x16_bf16 v[32:47], v[146:149], v[160:163], v[32:47]
	v_mfma_f32_32x32x16_bf16 v[48:63], v[156:159], v[160:163], v[48:63]
	v_mfma_f32_32x32x16_bf16 v[16:31], v[138:141], v[134:137], v[16:31]
	v_mfma_f32_32x32x16_bf16 v[0:15], v[130:133], v[134:137], v[0:15]
	v_mfma_f32_32x32x16_bf16 v[32:47], v[130:133], v[142:145], v[32:47]
	v_mfma_f32_32x32x16_bf16 v[48:63], v[138:141], v[142:145], v[48:63]
	v_mfma_f32_32x32x16_bf16 v[16:31], v[122:125], v[118:121], v[16:31]
	v_mfma_f32_32x32x16_bf16 v[0:15], v[114:117], v[118:121], v[0:15]
	v_mfma_f32_32x32x16_bf16 v[32:47], v[114:117], v[126:129], v[32:47]
	v_mfma_f32_32x32x16_bf16 v[48:63], v[122:125], v[126:129], v[48:63]
	v_mfma_f32_32x32x16_bf16 v[16:31], v[80:83], v[76:79], v[16:31]
	v_mfma_f32_32x32x16_bf16 v[0:15], v[72:75], v[76:79], v[0:15]
	v_add_u32_e32 v76, s80, v89
	v_ashrrev_i32_e32 v77, 31, v76
	v_mfma_f32_32x32x16_bf16 v[32:47], v[72:75], v[84:87], v[32:47]
	v_or_b32_e32 v72, s82, v90
	v_lshlrev_b64 v[74:75], 12, v[76:77]
	v_ashrrev_i32_e32 v73, 31, v72
	v_lshl_add_u64 v[78:79], s[40:41], 0, v[74:75]
	v_mfma_f32_32x32x16_bf16 v[48:63], v[80:83], v[84:87], v[48:63]
	v_lshlrev_b64 v[82:83], 2, v[72:73]
	v_lshl_add_u64 v[78:79], v[78:79], 0, v[82:83]
	v_lshl_add_u64 v[80:81], s[38:39], 0, v[74:75]
	global_load_dwordx4 v[72:75], v[78:79], off
	s_waitcnt vmcnt(0)
	s_nop 6
	v_pk_fma_f32 v[50:51], v[74:75], s[78:79], v[50:51] op_sel_hi:[1,0,1]
	v_pk_fma_f32 v[48:49], v[72:73], s[78:79], v[48:49] op_sel_hi:[1,0,1]
	v_lshl_add_u64 v[72:73], v[80:81], 0, v[82:83]
	global_store_dwordx4 v[72:73], v[48:51], off
	global_load_dwordx4 v[48:51], v[78:79], off offset:32
	s_waitcnt vmcnt(0)
	v_pk_fma_f32 v[48:49], v[48:49], s[78:79], v[52:53] op_sel_hi:[1,0,1]
	v_pk_fma_f32 v[50:51], v[50:51], s[78:79], v[54:55] op_sel_hi:[1,0,1]
	global_store_dwordx4 v[72:73], v[48:51], off offset:32
	global_load_dwordx4 v[48:51], v[78:79], off offset:64
	s_waitcnt vmcnt(0)
	v_pk_fma_f32 v[48:49], v[48:49], s[78:79], v[56:57] op_sel_hi:[1,0,1]
	v_pk_fma_f32 v[50:51], v[50:51], s[78:79], v[58:59] op_sel_hi:[1,0,1]
	global_store_dwordx4 v[72:73], v[48:51], off offset:64
	global_load_dwordx4 v[48:51], v[78:79], off offset:96
	s_waitcnt vmcnt(0)
	v_pk_fma_f32 v[48:49], v[48:49], s[78:79], v[60:61] op_sel_hi:[1,0,1]
	v_pk_fma_f32 v[50:51], v[50:51], s[78:79], v[62:63] op_sel_hi:[1,0,1]
	global_store_dwordx4 v[72:73], v[48:51], off offset:96
	global_load_dwordx4 v[48:51], v[78:79], off offset:128
	s_waitcnt vmcnt(0)
	v_pk_fma_f32 v[34:35], v[50:51], s[78:79], v[34:35] op_sel_hi:[1,0,1]
	v_pk_fma_f32 v[32:33], v[48:49], s[78:79], v[32:33] op_sel_hi:[1,0,1]
	global_store_dwordx4 v[72:73], v[32:35], off offset:128
	global_load_dwordx4 v[32:35], v[78:79], off offset:160
	s_waitcnt vmcnt(0)
	v_pk_fma_f32 v[32:33], v[32:33], s[78:79], v[36:37] op_sel_hi:[1,0,1]
	v_pk_fma_f32 v[34:35], v[34:35], s[78:79], v[38:39] op_sel_hi:[1,0,1]
	global_store_dwordx4 v[72:73], v[32:35], off offset:160
	global_load_dwordx4 v[32:35], v[78:79], off offset:192
	s_waitcnt vmcnt(0)
	v_pk_fma_f32 v[32:33], v[32:33], s[78:79], v[40:41] op_sel_hi:[1,0,1]
	v_pk_fma_f32 v[34:35], v[34:35], s[78:79], v[42:43] op_sel_hi:[1,0,1]
	global_store_dwordx4 v[72:73], v[32:35], off offset:192
	global_load_dwordx4 v[32:35], v[78:79], off offset:224
	s_waitcnt vmcnt(0)
	v_pk_fma_f32 v[32:33], v[32:33], s[78:79], v[44:45] op_sel_hi:[1,0,1]
	v_pk_fma_f32 v[34:35], v[34:35], s[78:79], v[46:47] op_sel_hi:[1,0,1]
	global_store_dwordx4 v[72:73], v[32:35], off offset:224
	s_nop 1
	v_or_b32_e32 v32, 32, v76
	v_ashrrev_i32_e32 v33, 31, v32
	v_lshlrev_b64 v[32:33], 12, v[32:33]
	v_lshl_add_u64 v[34:35], s[40:41], 0, v[32:33]
	v_lshl_add_u64 v[38:39], v[34:35], 0, v[82:83]
	v_lshl_add_u64 v[36:37], s[38:39], 0, v[32:33]
	global_load_dwordx4 v[32:35], v[38:39], off
	s_waitcnt vmcnt(0)
	v_pk_fma_f32 v[18:19], v[34:35], s[78:79], v[18:19] op_sel_hi:[1,0,1]
	v_pk_fma_f32 v[16:17], v[32:33], s[78:79], v[16:17] op_sel_hi:[1,0,1]
	v_lshl_add_u64 v[32:33], v[36:37], 0, v[82:83]
	global_store_dwordx4 v[32:33], v[16:19], off
	global_load_dwordx4 v[16:19], v[38:39], off offset:32
	s_waitcnt vmcnt(0)
	v_pk_fma_f32 v[16:17], v[16:17], s[78:79], v[20:21] op_sel_hi:[1,0,1]
	v_pk_fma_f32 v[18:19], v[18:19], s[78:79], v[22:23] op_sel_hi:[1,0,1]
	global_store_dwordx4 v[32:33], v[16:19], off offset:32
	global_load_dwordx4 v[16:19], v[38:39], off offset:64
	s_waitcnt vmcnt(0)
	v_pk_fma_f32 v[16:17], v[16:17], s[78:79], v[24:25] op_sel_hi:[1,0,1]
	v_pk_fma_f32 v[18:19], v[18:19], s[78:79], v[26:27] op_sel_hi:[1,0,1]
	global_store_dwordx4 v[32:33], v[16:19], off offset:64
	global_load_dwordx4 v[16:19], v[38:39], off offset:96
	s_waitcnt vmcnt(0)
	v_pk_fma_f32 v[16:17], v[16:17], s[78:79], v[28:29] op_sel_hi:[1,0,1]
	v_pk_fma_f32 v[18:19], v[18:19], s[78:79], v[30:31] op_sel_hi:[1,0,1]
	global_store_dwordx4 v[32:33], v[16:19], off offset:96
	global_load_dwordx4 v[16:19], v[38:39], off offset:128
	s_waitcnt vmcnt(0)
	v_pk_fma_f32 v[2:3], v[18:19], s[78:79], v[2:3] op_sel_hi:[1,0,1]
	v_pk_fma_f32 v[0:1], v[16:17], s[78:79], v[0:1] op_sel_hi:[1,0,1]
	global_store_dwordx4 v[32:33], v[0:3], off offset:128
	global_load_dwordx4 v[0:3], v[38:39], off offset:160
	s_waitcnt vmcnt(0)
	v_pk_fma_f32 v[0:1], v[0:1], s[78:79], v[4:5] op_sel_hi:[1,0,1]
	v_pk_fma_f32 v[2:3], v[2:3], s[78:79], v[6:7] op_sel_hi:[1,0,1]
	global_store_dwordx4 v[32:33], v[0:3], off offset:160
	global_load_dwordx4 v[0:3], v[38:39], off offset:192
	s_waitcnt vmcnt(0)
	v_pk_fma_f32 v[0:1], v[0:1], s[78:79], v[8:9] op_sel_hi:[1,0,1]
	v_pk_fma_f32 v[2:3], v[2:3], s[78:79], v[10:11] op_sel_hi:[1,0,1]
	global_store_dwordx4 v[32:33], v[0:3], off offset:192
	global_load_dwordx4 v[0:3], v[38:39], off offset:224
	s_waitcnt vmcnt(0)
	v_pk_fma_f32 v[0:1], v[0:1], s[78:79], v[12:13] op_sel_hi:[1,0,1]
	v_pk_fma_f32 v[2:3], v[2:3], s[78:79], v[14:15] op_sel_hi:[1,0,1]
	s_add_i32 s79, s79, s33
	s_add_i32 s28, s2, s79
	s_cmpk_lt_i32 s28, 0x400
	global_store_dwordx4 v[32:33], v[0:3], off offset:224
	s_cbranch_scc0 .LBB0_564

.LBB0_652:
	s_lshl_b32 s68, s16, 7
	s_ashr_i32 s69, s68, 31
	v_readlane_b32 s52, v245, 37
	s_lshl_b32 s28, s83, 7
	s_lshl_b64 s[34:35], s[68:69], 11
	v_readlane_b32 s64, v245, 49
	v_readlane_b32 s65, v245, 50
	s_add_u32 s34, s64, s34
	s_addc_u32 s35, s65, s35
	s_ashr_i32 s29, s28, 31
	s_lshl_b64 s[28:29], s[28:29], 11
	s_add_u32 s28, s3, s28
	s_addc_u32 s29, s14, s29
	v_mov_b32_e32 v2, s35
	v_mov_b32_e32 v3, s34
	v_mov_b32_e32 v4, s29
	v_mov_b32_e32 v5, s28
	v_readfirstlane_b32 s72, v100
	s_add_u32 s98, s34, 0x80
	s_addc_u32 s99, s35, 0
	v_lshl_add_u64 v[84:85], s[34:35], 0, v[64:65]
	s_mov_b32 m0, s72
	v_cndmask_b32_e64 v1, v4, v2, s[4:5]
	v_cndmask_b32_e64 v0, v5, v3, s[4:5]
	v_readfirstlane_b32 s84, v167
	global_load_lds_dwordx4 v[84:85], off
	v_lshl_add_u64 v[94:95], v[0:1], 0, v[66:67]
	s_mov_b32 m0, s84
	v_cndmask_b32_e64 v1, v4, v2, s[6:7]
	v_cndmask_b32_e64 v0, v5, v3, s[6:7]
	v_readfirstlane_b32 s85, v168
	global_load_lds_dwordx4 v[94:95], off
	v_lshl_add_u64 v[96:97], v[0:1], 0, v[68:69]
	s_mov_b32 m0, s85
	v_cndmask_b32_e64 v1, v4, v2, s[8:9]
	v_cndmask_b32_e64 v0, v5, v3, s[8:9]
	v_readfirstlane_b32 s89, v169
	global_load_lds_dwordx4 v[96:97], off
	v_lshl_add_u64 v[98:99], v[0:1], 0, v[70:71]
	s_mov_b32 m0, s89
	v_readfirstlane_b32 s88, v170
	s_add_u32 s100, s28, 0x80
	s_addc_u32 s101, s29, 0
	v_lshl_add_u64 v[88:89], s[28:29], 0, v[64:65]
	global_load_lds_dwordx4 v[98:99], off
	s_mov_b32 m0, s88
	v_readfirstlane_b32 s87, v171
	v_lshl_add_u64 v[90:91], s[28:29], 0, v[66:67]
	global_load_lds_dwordx4 v[88:89], off
	s_mov_b32 m0, s87
	v_readfirstlane_b32 s86, v172
	v_lshl_add_u64 v[92:93], s[28:29], 0, v[68:69]
	global_load_lds_dwordx4 v[90:91], off
	s_mov_b32 m0, s86
	v_readfirstlane_b32 s73, v173
	v_lshl_add_u64 v[86:87], s[28:29], 0, v[70:71]
	global_load_lds_dwordx4 v[92:93], off
	s_mov_b32 m0, s73
	v_readfirstlane_b32 s16, v174
	global_load_lds_dwordx4 v[86:87], off
	s_mov_b32 m0, s16
	v_readfirstlane_b32 s29, v175
	s_waitcnt vmcnt(0)
	s_waitcnt vmcnt(0) lgkmcnt(0)
	s_barrier
	global_load_lds_dwordx4 v64, s[98:99]
	s_mov_b32 m0, s29
	v_readfirstlane_b32 s28, v176
	global_load_lds_dwordx4 v66, s[98:99]
	s_mov_b32 m0, s28
	v_readfirstlane_b32 s69, v177
	global_load_lds_dwordx4 v68, s[98:99]
	s_mov_b32 m0, s69
	v_readfirstlane_b32 s35, v178
	global_load_lds_dwordx4 v70, s[98:99]
	s_mov_b32 m0, s35
	v_readfirstlane_b32 s70, v179
	global_load_lds_dwordx4 v64, s[100:101]
	s_mov_b32 m0, s70
	v_readfirstlane_b32 s71, v180
	global_load_lds_dwordx4 v66, s[100:101]
	ds_read_b128 v[0:3], v183 offset:16384
	s_mov_b32 m0, s71
	v_readfirstlane_b32 s34, v181
	global_load_lds_dwordx4 v68, s[100:101]
	s_mov_b32 m0, s34
	ds_read_b128 v[4:7], v182
	global_load_lds_dwordx4 v70, s[100:101]
	s_add_u32 s98, s98, 0x80
	s_addc_u32 s99, s99, 0
	s_add_u32 s100, s100, 0x80
	s_addc_u32 s101, s101, 0
	ds_read_b128 v[8:11], v184
	s_waitcnt lgkmcnt(0)
	v_mfma_f32_32x32x16_bf16 v[48:63], v[0:3], v[4:7], 0
	s_mov_b32 m0, s72
	v_cmp_lt_i32_e32 vcc, v197, v198
	v_readlane_b32 s53, v245, 38
	v_readlane_b32 s54, v245, 39
	v_readlane_b32 s55, v245, 40
	v_mfma_f32_32x32x16_bf16 v[16:31], v[0:3], v[8:11], 0
	ds_read_b128 v[0:3], v183 offset:20480
	ds_read_b128 v[200:203], v186 offset:16384
	ds_read_b128 v[204:207], v185
	ds_read_b128 v[208:211], v187
	v_readlane_b32 s56, v245, 41
	v_readlane_b32 s57, v245, 42
	v_readlane_b32 s58, v245, 43
	v_readlane_b32 s59, v245, 44
	s_waitcnt lgkmcnt(0)
	v_mfma_f32_32x32x16_bf16 v[48:63], v[200:203], v[204:207], v[48:63]
	v_readlane_b32 s60, v245, 45
	v_readlane_b32 s61, v245, 46
	v_readlane_b32 s62, v245, 47
	v_readlane_b32 s63, v245, 48
	v_readlane_b32 s66, v245, 51
	v_readlane_b32 s67, v245, 52
	v_readlane_b32 s52, v245, 59
	v_mfma_f32_32x32x16_bf16 v[16:31], v[200:203], v[208:211], v[16:31]
	ds_read_b128 v[200:203], v186 offset:20480
	v_readlane_b32 s60, v244, 3
	v_readlane_b32 s61, v244, 4
	v_readlane_b32 s62, v244, 5
	v_readlane_b32 s63, v244, 6
	v_readlane_b32 s64, v244, 7
	v_readlane_b32 s65, v244, 8
	v_mfma_f32_32x32x16_bf16 v[32:47], v[0:3], v[4:7], 0
	s_mov_b64 s[44:45], s[60:61]
	s_mov_b64 s[46:47], s[62:63]
	s_add_i32 s82, s82, s33
	v_readlane_b32 s53, v245, 60
	v_readlane_b32 s54, v245, 61
	v_readlane_b32 s55, v245, 62
	v_readlane_b32 s56, v245, 63
	v_mfma_f32_32x32x16_bf16 v[0:15], v[0:3], v[8:11], 0
	v_readlane_b32 s57, v244, 0
	v_readlane_b32 s58, v244, 1
	v_readlane_b32 s59, v244, 2
	v_readlane_b32 s66, v244, 9
	v_readlane_b32 s67, v244, 10
	s_mov_b64 s[48:49], s[64:65]
	s_waitcnt lgkmcnt(0)
	v_mfma_f32_32x32x16_bf16 v[32:47], v[200:203], v[204:207], v[32:47]
	v_mfma_f32_32x32x16_bf16 v[0:15], v[200:203], v[208:211], v[0:15]
	ds_read_b128 v[200:203], v189 offset:16384
	ds_read_b128 v[204:207], v188
	ds_read_b128 v[208:211], v190
	s_waitcnt lgkmcnt(0)
	v_mfma_f32_32x32x16_bf16 v[48:63], v[200:203], v[204:207], v[48:63]
	v_mfma_f32_32x32x16_bf16 v[16:31], v[200:203], v[208:211], v[16:31]
	ds_read_b128 v[200:203], v189 offset:20480
	s_waitcnt lgkmcnt(0)
	v_mfma_f32_32x32x16_bf16 v[32:47], v[200:203], v[204:207], v[32:47]
	v_mfma_f32_32x32x16_bf16 v[0:15], v[200:203], v[208:211], v[0:15]
	ds_read_b128 v[200:203], v192 offset:16384
	ds_read_b128 v[204:207], v191
	ds_read_b128 v[208:211], v193
	s_waitcnt lgkmcnt(0)
	v_mfma_f32_32x32x16_bf16 v[48:63], v[200:203], v[204:207], v[48:63]
	v_mfma_f32_32x32x16_bf16 v[16:31], v[200:203], v[208:211], v[16:31]
	ds_read_b128 v[200:203], v192 offset:20480
	s_waitcnt vmcnt(0)
	s_waitcnt vmcnt(0) lgkmcnt(0)
	s_barrier
	v_mfma_f32_32x32x16_bf16 v[32:47], v[200:203], v[204:207], v[32:47]
	v_mfma_f32_32x32x16_bf16 v[0:15], v[200:203], v[208:211], v[0:15]
	global_load_lds_dwordx4 v64, s[98:99]
	s_mov_b32 m0, s84
	s_nop 0
	global_load_lds_dwordx4 v66, s[98:99]
	s_mov_b32 m0, s85
	s_nop 0
	global_load_lds_dwordx4 v68, s[98:99]
	s_mov_b32 m0, s89
	s_nop 0
	global_load_lds_dwordx4 v70, s[98:99]
	s_mov_b32 m0, s88
	s_nop 0
	global_load_lds_dwordx4 v64, s[100:101]
	s_mov_b32 m0, s87
	s_nop 0
	global_load_lds_dwordx4 v66, s[100:101]
	s_mov_b32 m0, s86
	s_nop 0
	global_load_lds_dwordx4 v68, s[100:101]
	ds_read_b128 v[200:203], v183 offset:49152
	s_mov_b32 m0, s73
	s_nop 0
	global_load_lds_dwordx4 v70, s[100:101]
	s_add_u32 s98, s98, 0x80
	s_addc_u32 s99, s99, 0
	s_add_u32 s100, s100, 0x80
	s_addc_u32 s101, s101, 0
	ds_read_b128 v[204:207], v182 offset:32768
	ds_read_b128 v[208:211], v184 offset:32768
	s_waitcnt lgkmcnt(0)
	v_mfma_f32_32x32x16_bf16 v[48:63], v[200:203], v[204:207], v[48:63]
	s_mov_b32 m0, s16
	v_mfma_f32_32x32x16_bf16 v[16:31], v[200:203], v[208:211], v[16:31]
	ds_read_b128 v[200:203], v183 offset:53248
	s_waitcnt lgkmcnt(0)
	v_mfma_f32_32x32x16_bf16 v[32:47], v[200:203], v[204:207], v[32:47]
	v_mfma_f32_32x32x16_bf16 v[0:15], v[200:203], v[208:211], v[0:15]
	ds_read_b128 v[200:203], v186 offset:49152
	ds_read_b128 v[204:207], v185 offset:32768
	ds_read_b128 v[208:211], v187 offset:32768
	s_waitcnt lgkmcnt(0)
	v_mfma_f32_32x32x16_bf16 v[48:63], v[200:203], v[204:207], v[48:63]
	v_mfma_f32_32x32x16_bf16 v[16:31], v[200:203], v[208:211], v[16:31]
	ds_read_b128 v[200:203], v186 offset:53248
	s_waitcnt lgkmcnt(0)
	v_mfma_f32_32x32x16_bf16 v[32:47], v[200:203], v[204:207], v[32:47]
	v_mfma_f32_32x32x16_bf16 v[0:15], v[200:203], v[208:211], v[0:15]
	ds_read_b128 v[200:203], v189 offset:49152
	ds_read_b128 v[204:207], v188 offset:32768
	ds_read_b128 v[208:211], v190 offset:32768
	s_waitcnt lgkmcnt(0)
	v_mfma_f32_32x32x16_bf16 v[48:63], v[200:203], v[204:207], v[48:63]
	v_mfma_f32_32x32x16_bf16 v[16:31], v[200:203], v[208:211], v[16:31]
	ds_read_b128 v[200:203], v189 offset:53248
	s_waitcnt lgkmcnt(0)
	v_mfma_f32_32x32x16_bf16 v[32:47], v[200:203], v[204:207], v[32:47]
	ds_read_b128 v[204:207], v192 offset:49152
	ds_read_b128 v[212:215], v191 offset:32768
	v_mfma_f32_32x32x16_bf16 v[0:15], v[200:203], v[208:211], v[0:15]
	ds_read_b128 v[200:203], v193 offset:32768
	ds_read_b128 v[208:211], v192 offset:53248
	s_waitcnt vmcnt(0)
	s_waitcnt vmcnt(0) lgkmcnt(0)
	s_barrier
	global_load_lds_dwordx4 v64, s[98:99]
	s_mov_b32 m0, s29
	v_mfma_f32_32x32x16_bf16 v[48:63], v[204:207], v[212:215], v[48:63]
	global_load_lds_dwordx4 v66, s[98:99]
	s_mov_b32 m0, s28
	s_nop 0
	global_load_lds_dwordx4 v68, s[98:99]
	v_mfma_f32_32x32x16_bf16 v[16:31], v[204:207], v[200:203], v[16:31]
	s_mov_b32 m0, s69
	s_nop 0
	global_load_lds_dwordx4 v70, s[98:99]
	s_mov_b32 m0, s35
	v_mfma_f32_32x32x16_bf16 v[32:47], v[208:211], v[212:215], v[32:47]
	global_load_lds_dwordx4 v64, s[100:101]
	s_mov_b32 m0, s70
	s_nop 0
	global_load_lds_dwordx4 v66, s[100:101]
	ds_read_b128 v[204:207], v183 offset:16384
	s_mov_b32 m0, s71
	v_mfma_f32_32x32x16_bf16 v[0:15], v[208:211], v[200:203], v[0:15]
	global_load_lds_dwordx4 v68, s[100:101]
	s_mov_b32 m0, s34
	ds_read_b128 v[200:203], v182
	global_load_lds_dwordx4 v70, s[100:101]
	s_add_u32 s98, s98, 0x80
	s_addc_u32 s99, s99, 0
	s_add_u32 s100, s100, 0x80
	s_addc_u32 s101, s101, 0
	ds_read_b128 v[208:211], v184
	s_waitcnt lgkmcnt(0)
	v_mfma_f32_32x32x16_bf16 v[48:63], v[204:207], v[200:203], v[48:63]
	s_mov_b32 m0, s72
	v_mfma_f32_32x32x16_bf16 v[16:31], v[204:207], v[208:211], v[16:31]
	ds_read_b128 v[204:207], v183 offset:20480
	s_waitcnt lgkmcnt(0)
	v_mfma_f32_32x32x16_bf16 v[32:47], v[204:207], v[200:203], v[32:47]
	v_mfma_f32_32x32x16_bf16 v[0:15], v[204:207], v[208:211], v[0:15]
	ds_read_b128 v[200:203], v186 offset:16384
	ds_read_b128 v[204:207], v185
	ds_read_b128 v[208:211], v187
	s_waitcnt lgkmcnt(0)
	v_mfma_f32_32x32x16_bf16 v[48:63], v[200:203], v[204:207], v[48:63]
	v_mfma_f32_32x32x16_bf16 v[16:31], v[200:203], v[208:211], v[16:31]
	ds_read_b128 v[200:203], v186 offset:20480
	s_waitcnt lgkmcnt(0)
	v_mfma_f32_32x32x16_bf16 v[32:47], v[200:203], v[204:207], v[32:47]
	v_mfma_f32_32x32x16_bf16 v[0:15], v[200:203], v[208:211], v[0:15]
	ds_read_b128 v[200:203], v189 offset:16384
	ds_read_b128 v[204:207], v188
	ds_read_b128 v[208:211], v190
	s_waitcnt lgkmcnt(0)
	v_mfma_f32_32x32x16_bf16 v[48:63], v[200:203], v[204:207], v[48:63]
	v_mfma_f32_32x32x16_bf16 v[16:31], v[200:203], v[208:211], v[16:31]
	ds_read_b128 v[200:203], v189 offset:20480
	s_waitcnt lgkmcnt(0)
	v_mfma_f32_32x32x16_bf16 v[32:47], v[200:203], v[204:207], v[32:47]
	ds_read_b128 v[204:207], v191
	ds_read_b128 v[212:215], v193
	ds_read_b128 v[216:219], v192 offset:16384
	ds_read_b128 v[220:223], v192 offset:20480
	s_waitcnt vmcnt(0)
	s_waitcnt vmcnt(0) lgkmcnt(0)
	s_barrier
	v_mfma_f32_32x32x16_bf16 v[0:15], v[200:203], v[208:211], v[0:15]
	global_load_lds_dwordx4 v64, s[98:99]
	s_mov_b32 m0, s84
	s_nop 0
	global_load_lds_dwordx4 v66, s[98:99]
	s_mov_b32 m0, s85
	v_mfma_f32_32x32x16_bf16 v[48:63], v[216:219], v[204:207], v[48:63]
	global_load_lds_dwordx4 v68, s[98:99]
	s_mov_b32 m0, s89
	s_nop 0
	global_load_lds_dwordx4 v70, s[98:99]
	s_mov_b32 m0, s88
	v_mfma_f32_32x32x16_bf16 v[16:31], v[216:219], v[212:215], v[16:31]
	global_load_lds_dwordx4 v64, s[100:101]
	s_mov_b32 m0, s87
	s_nop 0
	global_load_lds_dwordx4 v66, s[100:101]
	s_mov_b32 m0, s86
	v_mfma_f32_32x32x16_bf16 v[32:47], v[220:223], v[204:207], v[32:47]
	global_load_lds_dwordx4 v68, s[100:101]
	ds_read_b128 v[200:203], v183 offset:49152
	s_mov_b32 m0, s73
	s_nop 0
	global_load_lds_dwordx4 v70, s[100:101]
	s_add_u32 s98, s98, 0x80
	s_addc_u32 s99, s99, 0
	s_add_u32 s100, s100, 0x80
	s_addc_u32 s101, s101, 0
	ds_read_b128 v[204:207], v182 offset:32768
	ds_read_b128 v[208:211], v184 offset:32768
	s_waitcnt lgkmcnt(0)
	v_mfma_f32_32x32x16_bf16 v[48:63], v[200:203], v[204:207], v[48:63]
	s_mov_b32 m0, s16
	v_mfma_f32_32x32x16_bf16 v[16:31], v[200:203], v[208:211], v[16:31]
	ds_read_b128 v[200:203], v183 offset:53248
	v_mfma_f32_32x32x16_bf16 v[0:15], v[220:223], v[212:215], v[0:15]
	s_waitcnt lgkmcnt(0)
	v_mfma_f32_32x32x16_bf16 v[32:47], v[200:203], v[204:207], v[32:47]
	v_mfma_f32_32x32x16_bf16 v[0:15], v[200:203], v[208:211], v[0:15]
	ds_read_b128 v[200:203], v186 offset:49152
	ds_read_b128 v[204:207], v185 offset:32768
	ds_read_b128 v[208:211], v187 offset:32768
	s_waitcnt lgkmcnt(0)
	v_mfma_f32_32x32x16_bf16 v[48:63], v[200:203], v[204:207], v[48:63]
	v_mfma_f32_32x32x16_bf16 v[16:31], v[200:203], v[208:211], v[16:31]
	ds_read_b128 v[200:203], v186 offset:53248
	s_waitcnt lgkmcnt(0)
	v_mfma_f32_32x32x16_bf16 v[32:47], v[200:203], v[204:207], v[32:47]
	v_mfma_f32_32x32x16_bf16 v[0:15], v[200:203], v[208:211], v[0:15]
	ds_read_b128 v[200:203], v189 offset:49152
	ds_read_b128 v[204:207], v188 offset:32768
	ds_read_b128 v[208:211], v190 offset:32768
	s_waitcnt lgkmcnt(0)
	v_mfma_f32_32x32x16_bf16 v[48:63], v[200:203], v[204:207], v[48:63]
	v_mfma_f32_32x32x16_bf16 v[16:31], v[200:203], v[208:211], v[16:31]
	ds_read_b128 v[200:203], v189 offset:53248
	s_waitcnt lgkmcnt(0)
	v_mfma_f32_32x32x16_bf16 v[32:47], v[200:203], v[204:207], v[32:47]
	ds_read_b128 v[204:207], v192 offset:49152
	ds_read_b128 v[212:215], v191 offset:32768
	v_mfma_f32_32x32x16_bf16 v[0:15], v[200:203], v[208:211], v[0:15]
	ds_read_b128 v[200:203], v193 offset:32768
	ds_read_b128 v[208:211], v192 offset:53248
	s_waitcnt vmcnt(0)
	s_waitcnt vmcnt(0) lgkmcnt(0)
	s_barrier
	global_load_lds_dwordx4 v64, s[98:99]
	s_mov_b32 m0, s29
	v_mfma_f32_32x32x16_bf16 v[48:63], v[204:207], v[212:215], v[48:63]
	global_load_lds_dwordx4 v66, s[98:99]
	s_mov_b32 m0, s28
	s_nop 0
	global_load_lds_dwordx4 v68, s[98:99]
	v_mfma_f32_32x32x16_bf16 v[16:31], v[204:207], v[200:203], v[16:31]
	s_mov_b32 m0, s69
	s_nop 0
	global_load_lds_dwordx4 v70, s[98:99]
	s_mov_b32 m0, s35
	v_mfma_f32_32x32x16_bf16 v[32:47], v[208:211], v[212:215], v[32:47]
	global_load_lds_dwordx4 v64, s[100:101]
	s_mov_b32 m0, s70
	s_nop 0
	global_load_lds_dwordx4 v66, s[100:101]
	ds_read_b128 v[204:207], v183 offset:16384
	s_mov_b32 m0, s71
	v_mfma_f32_32x32x16_bf16 v[0:15], v[208:211], v[200:203], v[0:15]
	global_load_lds_dwordx4 v68, s[100:101]
	s_mov_b32 m0, s34
	ds_read_b128 v[200:203], v182
	global_load_lds_dwordx4 v70, s[100:101]
	s_add_u32 s98, s98, 0x80
	s_addc_u32 s99, s99, 0
	s_add_u32 s100, s100, 0x80
	s_addc_u32 s101, s101, 0
	ds_read_b128 v[208:211], v184
	s_waitcnt lgkmcnt(0)
	v_mfma_f32_32x32x16_bf16 v[48:63], v[204:207], v[200:203], v[48:63]
	s_mov_b32 m0, s72
	v_mfma_f32_32x32x16_bf16 v[16:31], v[204:207], v[208:211], v[16:31]
	ds_read_b128 v[204:207], v183 offset:20480
	s_waitcnt lgkmcnt(0)
	v_mfma_f32_32x32x16_bf16 v[32:47], v[204:207], v[200:203], v[32:47]
	v_mfma_f32_32x32x16_bf16 v[0:15], v[204:207], v[208:211], v[0:15]
	ds_read_b128 v[200:203], v186 offset:16384
	ds_read_b128 v[204:207], v185
	ds_read_b128 v[208:211], v187
	s_waitcnt lgkmcnt(0)
	v_mfma_f32_32x32x16_bf16 v[48:63], v[200:203], v[204:207], v[48:63]
	v_mfma_f32_32x32x16_bf16 v[16:31], v[200:203], v[208:211], v[16:31]
	ds_read_b128 v[200:203], v186 offset:20480
	s_waitcnt lgkmcnt(0)
	v_mfma_f32_32x32x16_bf16 v[32:47], v[200:203], v[204:207], v[32:47]
	v_mfma_f32_32x32x16_bf16 v[0:15], v[200:203], v[208:211], v[0:15]
	ds_read_b128 v[200:203], v189 offset:16384
	ds_read_b128 v[204:207], v188
	ds_read_b128 v[208:211], v190
	s_waitcnt lgkmcnt(0)
	v_mfma_f32_32x32x16_bf16 v[48:63], v[200:203], v[204:207], v[48:63]
	v_mfma_f32_32x32x16_bf16 v[16:31], v[200:203], v[208:211], v[16:31]
	ds_read_b128 v[200:203], v189 offset:20480
	s_waitcnt lgkmcnt(0)
	v_mfma_f32_32x32x16_bf16 v[32:47], v[200:203], v[204:207], v[32:47]
	ds_read_b128 v[204:207], v191
	ds_read_b128 v[212:215], v193
	ds_read_b128 v[216:219], v192 offset:16384
	ds_read_b128 v[220:223], v192 offset:20480
	s_waitcnt vmcnt(0)
	s_waitcnt vmcnt(0) lgkmcnt(0)
	s_barrier
	v_mfma_f32_32x32x16_bf16 v[0:15], v[200:203], v[208:211], v[0:15]
	global_load_lds_dwordx4 v64, s[98:99]
	s_mov_b32 m0, s84
	s_nop 0
	global_load_lds_dwordx4 v66, s[98:99]
	s_mov_b32 m0, s85
	v_mfma_f32_32x32x16_bf16 v[48:63], v[216:219], v[204:207], v[48:63]
	global_load_lds_dwordx4 v68, s[98:99]
	s_mov_b32 m0, s89
	s_nop 0
	global_load_lds_dwordx4 v70, s[98:99]
	s_mov_b32 m0, s88
	v_mfma_f32_32x32x16_bf16 v[16:31], v[216:219], v[212:215], v[16:31]
	global_load_lds_dwordx4 v64, s[100:101]
	s_mov_b32 m0, s87
	s_nop 0
	global_load_lds_dwordx4 v66, s[100:101]
	s_mov_b32 m0, s86
	v_mfma_f32_32x32x16_bf16 v[32:47], v[220:223], v[204:207], v[32:47]
	global_load_lds_dwordx4 v68, s[100:101]
	ds_read_b128 v[200:203], v183 offset:49152
	s_mov_b32 m0, s73
	s_nop 0
	global_load_lds_dwordx4 v70, s[100:101]
	s_add_u32 s98, s98, 0x80
	s_addc_u32 s99, s99, 0
	s_add_u32 s100, s100, 0x80
	s_addc_u32 s101, s101, 0
	ds_read_b128 v[204:207], v182 offset:32768
	ds_read_b128 v[208:211], v184 offset:32768
	s_waitcnt lgkmcnt(0)
	v_mfma_f32_32x32x16_bf16 v[48:63], v[200:203], v[204:207], v[48:63]
	s_mov_b32 m0, s16
	v_mfma_f32_32x32x16_bf16 v[16:31], v[200:203], v[208:211], v[16:31]
	ds_read_b128 v[200:203], v183 offset:53248
	v_mfma_f32_32x32x16_bf16 v[0:15], v[220:223], v[212:215], v[0:15]
	s_waitcnt lgkmcnt(0)
	v_mfma_f32_32x32x16_bf16 v[32:47], v[200:203], v[204:207], v[32:47]
	v_mfma_f32_32x32x16_bf16 v[0:15], v[200:203], v[208:211], v[0:15]
	ds_read_b128 v[200:203], v186 offset:49152
	ds_read_b128 v[204:207], v185 offset:32768
	ds_read_b128 v[208:211], v187 offset:32768
	s_waitcnt lgkmcnt(0)
	v_mfma_f32_32x32x16_bf16 v[48:63], v[200:203], v[204:207], v[48:63]
	v_mfma_f32_32x32x16_bf16 v[16:31], v[200:203], v[208:211], v[16:31]
	ds_read_b128 v[200:203], v186 offset:53248
	s_waitcnt lgkmcnt(0)
	v_mfma_f32_32x32x16_bf16 v[32:47], v[200:203], v[204:207], v[32:47]
	v_mfma_f32_32x32x16_bf16 v[0:15], v[200:203], v[208:211], v[0:15]
	ds_read_b128 v[200:203], v189 offset:49152
	ds_read_b128 v[204:207], v188 offset:32768
	ds_read_b128 v[208:211], v190 offset:32768
	s_waitcnt lgkmcnt(0)
	v_mfma_f32_32x32x16_bf16 v[48:63], v[200:203], v[204:207], v[48:63]
	v_mfma_f32_32x32x16_bf16 v[16:31], v[200:203], v[208:211], v[16:31]
	ds_read_b128 v[200:203], v189 offset:53248
	s_waitcnt lgkmcnt(0)
	v_mfma_f32_32x32x16_bf16 v[32:47], v[200:203], v[204:207], v[32:47]
	ds_read_b128 v[204:207], v192 offset:49152
	ds_read_b128 v[212:215], v191 offset:32768
	v_mfma_f32_32x32x16_bf16 v[0:15], v[200:203], v[208:211], v[0:15]
	ds_read_b128 v[200:203], v193 offset:32768
	ds_read_b128 v[208:211], v192 offset:53248
	s_waitcnt vmcnt(0)
	s_waitcnt vmcnt(0) lgkmcnt(0)
	s_barrier
	global_load_lds_dwordx4 v64, s[98:99]
	s_mov_b32 m0, s29
	v_mfma_f32_32x32x16_bf16 v[48:63], v[204:207], v[212:215], v[48:63]
	global_load_lds_dwordx4 v66, s[98:99]
	s_mov_b32 m0, s28
	s_nop 0
	global_load_lds_dwordx4 v68, s[98:99]
	v_mfma_f32_32x32x16_bf16 v[16:31], v[204:207], v[200:203], v[16:31]
	s_mov_b32 m0, s69
	s_nop 0
	global_load_lds_dwordx4 v70, s[98:99]
	s_mov_b32 m0, s35
	v_mfma_f32_32x32x16_bf16 v[32:47], v[208:211], v[212:215], v[32:47]
	global_load_lds_dwordx4 v64, s[100:101]
	s_mov_b32 m0, s70
	s_nop 0
	global_load_lds_dwordx4 v66, s[100:101]
	ds_read_b128 v[204:207], v183 offset:16384
	s_mov_b32 m0, s71
	v_mfma_f32_32x32x16_bf16 v[0:15], v[208:211], v[200:203], v[0:15]
	global_load_lds_dwordx4 v68, s[100:101]
	s_mov_b32 m0, s34
	ds_read_b128 v[200:203], v182
	global_load_lds_dwordx4 v70, s[100:101]
	s_add_u32 s98, s98, 0x80
	s_addc_u32 s99, s99, 0
	s_add_u32 s100, s100, 0x80
	s_addc_u32 s101, s101, 0
	ds_read_b128 v[208:211], v184
	s_waitcnt lgkmcnt(0)
	v_mfma_f32_32x32x16_bf16 v[48:63], v[204:207], v[200:203], v[48:63]
	s_mov_b32 m0, s72
	v_readfirstlane_b32 s72, v173
	v_mfma_f32_32x32x16_bf16 v[16:31], v[204:207], v[208:211], v[16:31]
	ds_read_b128 v[204:207], v183 offset:20480
	s_waitcnt lgkmcnt(0)
	v_mfma_f32_32x32x16_bf16 v[32:47], v[204:207], v[200:203], v[32:47]
	v_mfma_f32_32x32x16_bf16 v[0:15], v[204:207], v[208:211], v[0:15]
	ds_read_b128 v[200:203], v186 offset:16384
	ds_read_b128 v[204:207], v185
	ds_read_b128 v[208:211], v187
	s_waitcnt lgkmcnt(0)
	v_mfma_f32_32x32x16_bf16 v[48:63], v[200:203], v[204:207], v[48:63]
	v_mfma_f32_32x32x16_bf16 v[16:31], v[200:203], v[208:211], v[16:31]
	ds_read_b128 v[200:203], v186 offset:20480
	s_waitcnt lgkmcnt(0)
	v_mfma_f32_32x32x16_bf16 v[32:47], v[200:203], v[204:207], v[32:47]
	v_mfma_f32_32x32x16_bf16 v[0:15], v[200:203], v[208:211], v[0:15]
	ds_read_b128 v[200:203], v189 offset:16384
	ds_read_b128 v[204:207], v188
	ds_read_b128 v[208:211], v190
	s_waitcnt lgkmcnt(0)
	v_mfma_f32_32x32x16_bf16 v[48:63], v[200:203], v[204:207], v[48:63]
	v_mfma_f32_32x32x16_bf16 v[16:31], v[200:203], v[208:211], v[16:31]
	ds_read_b128 v[200:203], v189 offset:20480
	s_waitcnt lgkmcnt(0)
	v_mfma_f32_32x32x16_bf16 v[32:47], v[200:203], v[204:207], v[32:47]
	ds_read_b128 v[204:207], v191
	ds_read_b128 v[212:215], v193
	ds_read_b128 v[216:219], v192 offset:16384
	ds_read_b128 v[220:223], v192 offset:20480
	s_waitcnt vmcnt(0)
	s_waitcnt vmcnt(0) lgkmcnt(0)
	s_barrier
	v_mfma_f32_32x32x16_bf16 v[0:15], v[200:203], v[208:211], v[0:15]
	global_load_lds_dwordx4 v64, s[98:99]
	s_mov_b32 m0, s84
	v_readfirstlane_b32 s84, v175
	global_load_lds_dwordx4 v66, s[98:99]
	s_mov_b32 m0, s85
	v_mfma_f32_32x32x16_bf16 v[48:63], v[216:219], v[204:207], v[48:63]
	global_load_lds_dwordx4 v68, s[98:99]
	s_mov_b32 m0, s89
	v_readfirstlane_b32 s85, v178
	global_load_lds_dwordx4 v70, s[98:99]
	s_mov_b32 m0, s88
	v_mfma_f32_32x32x16_bf16 v[16:31], v[216:219], v[212:215], v[16:31]
	global_load_lds_dwordx4 v64, s[100:101]
	s_mov_b32 m0, s87
	s_nop 0
	global_load_lds_dwordx4 v66, s[100:101]
	s_mov_b32 m0, s86
	v_mfma_f32_32x32x16_bf16 v[32:47], v[220:223], v[204:207], v[32:47]
	global_load_lds_dwordx4 v68, s[100:101]
	ds_read_b128 v[200:203], v183 offset:49152
	s_mov_b32 m0, s73
	v_readfirstlane_b32 s73, v176
	global_load_lds_dwordx4 v70, s[100:101]
	s_add_u32 s98, s98, 0x80
	s_addc_u32 s99, s99, 0
	s_add_u32 s100, s100, 0x80
	s_addc_u32 s101, s101, 0
	ds_read_b128 v[204:207], v182 offset:32768
	ds_read_b128 v[208:211], v184 offset:32768
	s_waitcnt lgkmcnt(0)
	v_mfma_f32_32x32x16_bf16 v[48:63], v[200:203], v[204:207], v[48:63]
	s_mov_b32 m0, s16
	v_readfirstlane_b32 s16, v100
	v_readfirstlane_b32 s86, v177
	v_readfirstlane_b32 s87, v179
	v_readfirstlane_b32 s88, v180
	v_readfirstlane_b32 s89, v181
	v_mfma_f32_32x32x16_bf16 v[16:31], v[200:203], v[208:211], v[16:31]
	ds_read_b128 v[200:203], v183 offset:53248
	v_mfma_f32_32x32x16_bf16 v[0:15], v[220:223], v[212:215], v[0:15]
	s_waitcnt lgkmcnt(0)
	v_mfma_f32_32x32x16_bf16 v[32:47], v[200:203], v[204:207], v[32:47]
	v_mfma_f32_32x32x16_bf16 v[0:15], v[200:203], v[208:211], v[0:15]
	ds_read_b128 v[200:203], v186 offset:49152
	ds_read_b128 v[204:207], v185 offset:32768
	ds_read_b128 v[208:211], v187 offset:32768
	s_waitcnt lgkmcnt(0)
	v_mfma_f32_32x32x16_bf16 v[48:63], v[200:203], v[204:207], v[48:63]
	v_mfma_f32_32x32x16_bf16 v[16:31], v[200:203], v[208:211], v[16:31]
	ds_read_b128 v[200:203], v186 offset:53248
	s_waitcnt lgkmcnt(0)
	v_mfma_f32_32x32x16_bf16 v[32:47], v[200:203], v[204:207], v[32:47]
	v_mfma_f32_32x32x16_bf16 v[0:15], v[200:203], v[208:211], v[0:15]
	ds_read_b128 v[200:203], v189 offset:49152
	ds_read_b128 v[204:207], v188 offset:32768
	ds_read_b128 v[208:211], v190 offset:32768
	s_waitcnt lgkmcnt(0)
	v_mfma_f32_32x32x16_bf16 v[48:63], v[200:203], v[204:207], v[48:63]
	v_mfma_f32_32x32x16_bf16 v[16:31], v[200:203], v[208:211], v[16:31]
	ds_read_b128 v[200:203], v189 offset:53248
	s_waitcnt lgkmcnt(0)
	v_mfma_f32_32x32x16_bf16 v[32:47], v[200:203], v[204:207], v[32:47]
	ds_read_b128 v[204:207], v192 offset:49152
	ds_read_b128 v[212:215], v191 offset:32768
	v_mfma_f32_32x32x16_bf16 v[0:15], v[200:203], v[208:211], v[0:15]
	ds_read_b128 v[200:203], v193 offset:32768
	ds_read_b128 v[208:211], v192 offset:53248
	s_waitcnt vmcnt(0)
	s_waitcnt vmcnt(0) lgkmcnt(0)
	s_barrier
	global_load_lds_dwordx4 v64, s[98:99]
	s_mov_b32 m0, s29
	v_mfma_f32_32x32x16_bf16 v[48:63], v[204:207], v[212:215], v[48:63]
	global_load_lds_dwordx4 v66, s[98:99]
	s_mov_b32 m0, s28
	v_readfirstlane_b32 s28, v167
	global_load_lds_dwordx4 v68, s[98:99]
	v_mfma_f32_32x32x16_bf16 v[16:31], v[204:207], v[200:203], v[16:31]
	s_mov_b32 m0, s69
	v_readfirstlane_b32 s29, v169
	global_load_lds_dwordx4 v70, s[98:99]
	s_mov_b32 m0, s35
	v_mfma_f32_32x32x16_bf16 v[32:47], v[208:211], v[212:215], v[32:47]
	global_load_lds_dwordx4 v64, s[100:101]
	s_mov_b32 m0, s70
	s_nop 0
	global_load_lds_dwordx4 v66, s[100:101]
	ds_read_b128 v[204:207], v183 offset:16384
	s_mov_b32 m0, s71
	v_mfma_f32_32x32x16_bf16 v[0:15], v[208:211], v[200:203], v[0:15]
	global_load_lds_dwordx4 v68, s[100:101]
	s_mov_b32 m0, s34
	ds_read_b128 v[200:203], v182
	global_load_lds_dwordx4 v70, s[100:101]
	s_add_u32 s98, s98, 0x80
	s_addc_u32 s99, s99, 0
	s_add_u32 s100, s100, 0x80
	s_addc_u32 s101, s101, 0
	ds_read_b128 v[208:211], v184
	s_waitcnt lgkmcnt(0)
	v_mfma_f32_32x32x16_bf16 v[48:63], v[204:207], v[200:203], v[48:63]
	s_mov_b32 m0, s16
	v_readfirstlane_b32 s34, v168
	v_readfirstlane_b32 s69, v170
	v_readfirstlane_b32 s35, v171
	v_readfirstlane_b32 s70, v172
	v_readfirstlane_b32 s71, v174
	v_mfma_f32_32x32x16_bf16 v[16:31], v[204:207], v[208:211], v[16:31]
	ds_read_b128 v[204:207], v183 offset:20480
	s_waitcnt lgkmcnt(0)
	v_mfma_f32_32x32x16_bf16 v[32:47], v[204:207], v[200:203], v[32:47]
	v_mfma_f32_32x32x16_bf16 v[0:15], v[204:207], v[208:211], v[0:15]
	ds_read_b128 v[200:203], v186 offset:16384
	ds_read_b128 v[204:207], v185
	ds_read_b128 v[208:211], v187
	s_waitcnt lgkmcnt(0)
	v_mfma_f32_32x32x16_bf16 v[48:63], v[200:203], v[204:207], v[48:63]
	v_mfma_f32_32x32x16_bf16 v[16:31], v[200:203], v[208:211], v[16:31]
	ds_read_b128 v[200:203], v186 offset:20480
	s_waitcnt lgkmcnt(0)
	v_mfma_f32_32x32x16_bf16 v[32:47], v[200:203], v[204:207], v[32:47]
	v_mfma_f32_32x32x16_bf16 v[0:15], v[200:203], v[208:211], v[0:15]
	ds_read_b128 v[200:203], v189 offset:16384
	ds_read_b128 v[204:207], v188
	ds_read_b128 v[208:211], v190
	s_waitcnt lgkmcnt(0)
	v_mfma_f32_32x32x16_bf16 v[48:63], v[200:203], v[204:207], v[48:63]
	v_mfma_f32_32x32x16_bf16 v[16:31], v[200:203], v[208:211], v[16:31]
	ds_read_b128 v[200:203], v189 offset:20480
	ds_read_b128 v[212:215], v191
	ds_read_b128 v[216:219], v193
	ds_read_b128 v[220:223], v192 offset:16384
	s_waitcnt lgkmcnt(0)
	v_mfma_f32_32x32x16_bf16 v[32:47], v[200:203], v[204:207], v[32:47]
	ds_read_b128 v[204:207], v192 offset:20480
	s_waitcnt vmcnt(0)
	s_waitcnt vmcnt(0) lgkmcnt(0)
	s_barrier
	global_load_lds_dwordx4 v64, s[98:99]
	v_mfma_f32_32x32x16_bf16 v[0:15], v[200:203], v[208:211], v[0:15]
	s_mov_b32 m0, s28
	s_nop 0
	global_load_lds_dwordx4 v66, s[98:99]
	s_mov_b32 m0, s34
	v_mfma_f32_32x32x16_bf16 v[48:63], v[220:223], v[212:215], v[48:63]
	global_load_lds_dwordx4 v68, s[98:99]
	s_mov_b32 m0, s29
	s_nop 0
	global_load_lds_dwordx4 v70, s[98:99]
	s_mov_b32 m0, s69
	v_mfma_f32_32x32x16_bf16 v[16:31], v[220:223], v[216:219], v[16:31]
	global_load_lds_dwordx4 v64, s[100:101]
	s_mov_b32 m0, s35
	s_nop 0
	global_load_lds_dwordx4 v66, s[100:101]
	s_mov_b32 m0, s70
	v_mfma_f32_32x32x16_bf16 v[32:47], v[204:207], v[212:215], v[32:47]
	global_load_lds_dwordx4 v68, s[100:101]
	ds_read_b128 v[200:203], v183 offset:49152
	s_mov_b32 m0, s72
	s_nop 0
	global_load_lds_dwordx4 v70, s[100:101]
	s_add_u32 s98, s98, 0x80
	s_addc_u32 s99, s99, 0
	s_add_u32 s100, s100, 0x80
	s_addc_u32 s101, s101, 0
	v_mfma_f32_32x32x16_bf16 v[0:15], v[204:207], v[216:219], v[0:15]
	ds_read_b128 v[204:207], v182 offset:32768
	ds_read_b128 v[208:211], v184 offset:32768
	s_mov_b32 m0, s71
	s_waitcnt lgkmcnt(0)
	v_mfma_f32_32x32x16_bf16 v[48:63], v[200:203], v[204:207], v[48:63]
	v_mfma_f32_32x32x16_bf16 v[16:31], v[200:203], v[208:211], v[16:31]
	ds_read_b128 v[200:203], v183 offset:53248
	s_waitcnt lgkmcnt(0)
	v_mfma_f32_32x32x16_bf16 v[32:47], v[200:203], v[204:207], v[32:47]
	v_mfma_f32_32x32x16_bf16 v[0:15], v[200:203], v[208:211], v[0:15]
	ds_read_b128 v[200:203], v186 offset:49152
	ds_read_b128 v[204:207], v185 offset:32768
	ds_read_b128 v[208:211], v187 offset:32768
	s_waitcnt lgkmcnt(0)
	v_mfma_f32_32x32x16_bf16 v[48:63], v[200:203], v[204:207], v[48:63]
	v_mfma_f32_32x32x16_bf16 v[16:31], v[200:203], v[208:211], v[16:31]
	ds_read_b128 v[200:203], v186 offset:53248
	s_waitcnt lgkmcnt(0)
	v_mfma_f32_32x32x16_bf16 v[32:47], v[200:203], v[204:207], v[32:47]
	v_mfma_f32_32x32x16_bf16 v[0:15], v[200:203], v[208:211], v[0:15]
	ds_read_b128 v[200:203], v189 offset:49152
	ds_read_b128 v[204:207], v188 offset:32768
	ds_read_b128 v[208:211], v190 offset:32768
	s_waitcnt lgkmcnt(0)
	v_mfma_f32_32x32x16_bf16 v[48:63], v[200:203], v[204:207], v[48:63]
	v_mfma_f32_32x32x16_bf16 v[16:31], v[200:203], v[208:211], v[16:31]
	ds_read_b128 v[200:203], v189 offset:53248
	s_waitcnt lgkmcnt(0)
	v_mfma_f32_32x32x16_bf16 v[32:47], v[200:203], v[204:207], v[32:47]
	ds_read_b128 v[204:207], v191 offset:32768
	ds_read_b128 v[212:215], v193 offset:32768
	ds_read_b128 v[216:219], v192 offset:49152
	ds_read_b128 v[220:223], v192 offset:53248
	s_waitcnt vmcnt(0)
	s_waitcnt vmcnt(0) lgkmcnt(0)
	s_barrier
	v_mfma_f32_32x32x16_bf16 v[0:15], v[200:203], v[208:211], v[0:15]
	global_load_lds_dwordx4 v64, s[98:99]
	s_mov_b32 m0, s84
	s_nop 0
	global_load_lds_dwordx4 v66, s[98:99]
	s_mov_b32 m0, s73
	v_mfma_f32_32x32x16_bf16 v[48:63], v[216:219], v[204:207], v[48:63]
	global_load_lds_dwordx4 v68, s[98:99]
	s_mov_b32 m0, s86
	s_nop 0
	global_load_lds_dwordx4 v70, s[98:99]
	s_mov_b32 m0, s85
	v_mfma_f32_32x32x16_bf16 v[16:31], v[216:219], v[212:215], v[16:31]
	global_load_lds_dwordx4 v64, s[100:101]
	s_mov_b32 m0, s87
	s_nop 0
	global_load_lds_dwordx4 v66, s[100:101]
	ds_read_b128 v[200:203], v183 offset:16384
	v_mfma_f32_32x32x16_bf16 v[32:47], v[220:223], v[204:207], v[32:47]
	s_mov_b32 m0, s88
	s_nop 0
	global_load_lds_dwordx4 v68, s[100:101]
	s_mov_b32 m0, s89
	ds_read_b128 v[204:207], v182
	global_load_lds_dwordx4 v70, s[100:101]
	s_add_u32 s98, s98, 0x80
	s_addc_u32 s99, s99, 0
	s_add_u32 s100, s100, 0x80
	s_addc_u32 s101, s101, 0
	ds_read_b128 v[208:211], v184
	s_waitcnt lgkmcnt(0)
	v_mfma_f32_32x32x16_bf16 v[48:63], v[200:203], v[204:207], v[48:63]
	s_mov_b32 m0, s16
	v_mfma_f32_32x32x16_bf16 v[16:31], v[200:203], v[208:211], v[16:31]
	ds_read_b128 v[200:203], v183 offset:20480
	v_mfma_f32_32x32x16_bf16 v[0:15], v[220:223], v[212:215], v[0:15]
	s_waitcnt lgkmcnt(0)
	v_mfma_f32_32x32x16_bf16 v[32:47], v[200:203], v[204:207], v[32:47]
	v_mfma_f32_32x32x16_bf16 v[0:15], v[200:203], v[208:211], v[0:15]
	ds_read_b128 v[200:203], v186 offset:16384
	ds_read_b128 v[204:207], v185
	ds_read_b128 v[208:211], v187
	s_waitcnt lgkmcnt(0)
	v_mfma_f32_32x32x16_bf16 v[48:63], v[200:203], v[204:207], v[48:63]
	v_mfma_f32_32x32x16_bf16 v[16:31], v[200:203], v[208:211], v[16:31]
	ds_read_b128 v[200:203], v186 offset:20480
	s_waitcnt lgkmcnt(0)
	v_mfma_f32_32x32x16_bf16 v[32:47], v[200:203], v[204:207], v[32:47]
	v_mfma_f32_32x32x16_bf16 v[0:15], v[200:203], v[208:211], v[0:15]
	ds_read_b128 v[200:203], v189 offset:16384
	ds_read_b128 v[204:207], v188
	ds_read_b128 v[208:211], v190
	s_waitcnt lgkmcnt(0)
	v_mfma_f32_32x32x16_bf16 v[48:63], v[200:203], v[204:207], v[48:63]
	v_mfma_f32_32x32x16_bf16 v[16:31], v[200:203], v[208:211], v[16:31]
	ds_read_b128 v[200:203], v189 offset:20480
	s_waitcnt lgkmcnt(0)
	v_mfma_f32_32x32x16_bf16 v[32:47], v[200:203], v[204:207], v[32:47]
	ds_read_b128 v[204:207], v191
	ds_read_b128 v[212:215], v193
	ds_read_b128 v[216:219], v192 offset:16384
	ds_read_b128 v[220:223], v192 offset:20480
	s_waitcnt vmcnt(0)
	s_waitcnt vmcnt(0) lgkmcnt(0)
	s_barrier
	v_mfma_f32_32x32x16_bf16 v[0:15], v[200:203], v[208:211], v[0:15]
	global_load_lds_dwordx4 v64, s[98:99]
	s_mov_b32 m0, s28
	s_nop 0
	global_load_lds_dwordx4 v66, s[98:99]
	s_mov_b32 m0, s34
	v_mfma_f32_32x32x16_bf16 v[48:63], v[216:219], v[204:207], v[48:63]
	global_load_lds_dwordx4 v68, s[98:99]
	s_mov_b32 m0, s29
	s_nop 0
	global_load_lds_dwordx4 v70, s[98:99]
	s_mov_b32 m0, s69
	v_mfma_f32_32x32x16_bf16 v[16:31], v[216:219], v[212:215], v[16:31]
	global_load_lds_dwordx4 v64, s[100:101]
	s_mov_b32 m0, s35
	s_nop 0
	global_load_lds_dwordx4 v66, s[100:101]
	s_mov_b32 m0, s70
	v_mfma_f32_32x32x16_bf16 v[32:47], v[220:223], v[204:207], v[32:47]
	global_load_lds_dwordx4 v68, s[100:101]
	ds_read_b128 v[200:203], v183 offset:49152
	s_mov_b32 m0, s72
	s_nop 0
	global_load_lds_dwordx4 v70, s[100:101]
	s_add_u32 s98, s98, 0x80
	s_addc_u32 s99, s99, 0
	s_add_u32 s100, s100, 0x80
	s_addc_u32 s101, s101, 0
	ds_read_b128 v[204:207], v182 offset:32768
	ds_read_b128 v[208:211], v184 offset:32768
	s_waitcnt lgkmcnt(0)
	v_mfma_f32_32x32x16_bf16 v[48:63], v[200:203], v[204:207], v[48:63]
	s_mov_b32 m0, s71
	v_mfma_f32_32x32x16_bf16 v[16:31], v[200:203], v[208:211], v[16:31]
	ds_read_b128 v[200:203], v183 offset:53248
	v_mfma_f32_32x32x16_bf16 v[0:15], v[220:223], v[212:215], v[0:15]
	s_waitcnt lgkmcnt(0)
	v_mfma_f32_32x32x16_bf16 v[32:47], v[200:203], v[204:207], v[32:47]
	v_mfma_f32_32x32x16_bf16 v[0:15], v[200:203], v[208:211], v[0:15]
	ds_read_b128 v[200:203], v186 offset:49152
	ds_read_b128 v[204:207], v185 offset:32768
	ds_read_b128 v[208:211], v187 offset:32768
	s_waitcnt lgkmcnt(0)
	v_mfma_f32_32x32x16_bf16 v[48:63], v[200:203], v[204:207], v[48:63]
	v_mfma_f32_32x32x16_bf16 v[16:31], v[200:203], v[208:211], v[16:31]
	ds_read_b128 v[200:203], v186 offset:53248
	s_waitcnt lgkmcnt(0)
	v_mfma_f32_32x32x16_bf16 v[32:47], v[200:203], v[204:207], v[32:47]
	v_mfma_f32_32x32x16_bf16 v[0:15], v[200:203], v[208:211], v[0:15]
	ds_read_b128 v[200:203], v189 offset:49152
	ds_read_b128 v[204:207], v188 offset:32768
	ds_read_b128 v[208:211], v190 offset:32768
	s_waitcnt lgkmcnt(0)
	v_mfma_f32_32x32x16_bf16 v[48:63], v[200:203], v[204:207], v[48:63]
	v_mfma_f32_32x32x16_bf16 v[16:31], v[200:203], v[208:211], v[16:31]
	ds_read_b128 v[200:203], v189 offset:53248
	s_waitcnt lgkmcnt(0)
	v_mfma_f32_32x32x16_bf16 v[32:47], v[200:203], v[204:207], v[32:47]
	ds_read_b128 v[204:207], v192 offset:49152
	ds_read_b128 v[212:215], v191 offset:32768
	v_mfma_f32_32x32x16_bf16 v[0:15], v[200:203], v[208:211], v[0:15]
	ds_read_b128 v[200:203], v193 offset:32768
	ds_read_b128 v[208:211], v192 offset:53248
	s_waitcnt vmcnt(0)
	s_waitcnt vmcnt(0) lgkmcnt(0)
	s_barrier
	global_load_lds_dwordx4 v64, s[98:99]
	s_mov_b32 m0, s84
	v_mfma_f32_32x32x16_bf16 v[48:63], v[204:207], v[212:215], v[48:63]
	global_load_lds_dwordx4 v66, s[98:99]
	s_mov_b32 m0, s73
	s_nop 0
	global_load_lds_dwordx4 v68, s[98:99]
	v_mfma_f32_32x32x16_bf16 v[16:31], v[204:207], v[200:203], v[16:31]
	s_mov_b32 m0, s86
	s_nop 0
	global_load_lds_dwordx4 v70, s[98:99]
	s_mov_b32 m0, s85
	v_mfma_f32_32x32x16_bf16 v[32:47], v[208:211], v[212:215], v[32:47]
	global_load_lds_dwordx4 v64, s[100:101]
	s_mov_b32 m0, s87
	s_nop 0
	global_load_lds_dwordx4 v66, s[100:101]
	ds_read_b128 v[204:207], v183 offset:16384
	s_mov_b32 m0, s88
	v_mfma_f32_32x32x16_bf16 v[0:15], v[208:211], v[200:203], v[0:15]
	global_load_lds_dwordx4 v68, s[100:101]
	s_mov_b32 m0, s89
	ds_read_b128 v[200:203], v182
	global_load_lds_dwordx4 v70, s[100:101]
	s_add_u32 s98, s98, 0x80
	s_addc_u32 s99, s99, 0
	s_add_u32 s100, s100, 0x80
	s_addc_u32 s101, s101, 0
	ds_read_b128 v[208:211], v184
	s_waitcnt lgkmcnt(0)
	v_mfma_f32_32x32x16_bf16 v[48:63], v[204:207], v[200:203], v[48:63]
	s_mov_b32 m0, s16
	v_mfma_f32_32x32x16_bf16 v[16:31], v[204:207], v[208:211], v[16:31]
	ds_read_b128 v[204:207], v183 offset:20480
	s_waitcnt lgkmcnt(0)
	v_mfma_f32_32x32x16_bf16 v[32:47], v[204:207], v[200:203], v[32:47]
	v_mfma_f32_32x32x16_bf16 v[0:15], v[204:207], v[208:211], v[0:15]
	ds_read_b128 v[200:203], v186 offset:16384
	ds_read_b128 v[204:207], v185
	ds_read_b128 v[208:211], v187
	s_waitcnt lgkmcnt(0)
	v_mfma_f32_32x32x16_bf16 v[48:63], v[200:203], v[204:207], v[48:63]
	v_mfma_f32_32x32x16_bf16 v[16:31], v[200:203], v[208:211], v[16:31]
	ds_read_b128 v[200:203], v186 offset:20480
	s_waitcnt lgkmcnt(0)
	v_mfma_f32_32x32x16_bf16 v[32:47], v[200:203], v[204:207], v[32:47]
	v_mfma_f32_32x32x16_bf16 v[0:15], v[200:203], v[208:211], v[0:15]
	ds_read_b128 v[200:203], v189 offset:16384
	ds_read_b128 v[204:207], v188
	ds_read_b128 v[208:211], v190
	s_waitcnt lgkmcnt(0)
	v_mfma_f32_32x32x16_bf16 v[48:63], v[200:203], v[204:207], v[48:63]
	v_mfma_f32_32x32x16_bf16 v[16:31], v[200:203], v[208:211], v[16:31]
	ds_read_b128 v[200:203], v189 offset:20480
	s_waitcnt lgkmcnt(0)
	v_mfma_f32_32x32x16_bf16 v[32:47], v[200:203], v[204:207], v[32:47]
	ds_read_b128 v[204:207], v191
	ds_read_b128 v[212:215], v193
	ds_read_b128 v[216:219], v192 offset:16384
	ds_read_b128 v[220:223], v192 offset:20480
	s_waitcnt vmcnt(0)
	s_waitcnt vmcnt(0) lgkmcnt(0)
	s_barrier
	v_mfma_f32_32x32x16_bf16 v[0:15], v[200:203], v[208:211], v[0:15]
	global_load_lds_dwordx4 v64, s[98:99]
	s_mov_b32 m0, s28
	s_nop 0
	global_load_lds_dwordx4 v66, s[98:99]
	s_mov_b32 m0, s34
	v_mfma_f32_32x32x16_bf16 v[48:63], v[216:219], v[204:207], v[48:63]
	global_load_lds_dwordx4 v68, s[98:99]
	s_mov_b32 m0, s29
	s_nop 0
	global_load_lds_dwordx4 v70, s[98:99]
	s_mov_b32 m0, s69
	v_mfma_f32_32x32x16_bf16 v[16:31], v[216:219], v[212:215], v[16:31]
	global_load_lds_dwordx4 v64, s[100:101]
	s_mov_b32 m0, s35
	s_lshl_b32 s69, s83, 1
	global_load_lds_dwordx4 v66, s[100:101]
	s_mov_b32 m0, s70
	v_mfma_f32_32x32x16_bf16 v[32:47], v[220:223], v[204:207], v[32:47]
	global_load_lds_dwordx4 v68, s[100:101]
	ds_read_b128 v[200:203], v183 offset:49152
	s_mov_b32 m0, s72
	s_add_i32 s16, s69, 16
	global_load_lds_dwordx4 v70, s[100:101]
	s_add_u32 s98, s98, 0x80
	s_addc_u32 s99, s99, 0
	s_add_u32 s100, s100, 0x80
	s_addc_u32 s101, s101, 0
	ds_read_b128 v[204:207], v182 offset:32768
	ds_read_b128 v[208:211], v184 offset:32768
	s_waitcnt lgkmcnt(0)
	v_mfma_f32_32x32x16_bf16 v[48:63], v[200:203], v[204:207], v[48:63]
	s_mov_b32 m0, s71
	s_lshl_b64 s[28:29], s[16:17], 14
	s_add_i32 s16, s69, 17
	v_mfma_f32_32x32x16_bf16 v[16:31], v[200:203], v[208:211], v[16:31]
	ds_read_b128 v[200:203], v183 offset:53248
	v_mfma_f32_32x32x16_bf16 v[0:15], v[220:223], v[212:215], v[0:15]
	s_waitcnt lgkmcnt(0)
	v_mfma_f32_32x32x16_bf16 v[32:47], v[200:203], v[204:207], v[32:47]
	v_mfma_f32_32x32x16_bf16 v[0:15], v[200:203], v[208:211], v[0:15]
	ds_read_b128 v[200:203], v186 offset:49152
	ds_read_b128 v[204:207], v185 offset:32768
	ds_read_b128 v[208:211], v187 offset:32768
	s_waitcnt lgkmcnt(0)
	v_mfma_f32_32x32x16_bf16 v[48:63], v[200:203], v[204:207], v[48:63]
	v_mfma_f32_32x32x16_bf16 v[16:31], v[200:203], v[208:211], v[16:31]
	ds_read_b128 v[200:203], v186 offset:53248
	s_waitcnt lgkmcnt(0)
	v_mfma_f32_32x32x16_bf16 v[32:47], v[200:203], v[204:207], v[32:47]
	v_mfma_f32_32x32x16_bf16 v[0:15], v[200:203], v[208:211], v[0:15]
	ds_read_b128 v[200:203], v189 offset:49152
	ds_read_b128 v[204:207], v188 offset:32768
	ds_read_b128 v[208:211], v190 offset:32768
	s_waitcnt lgkmcnt(0)
	v_mfma_f32_32x32x16_bf16 v[48:63], v[200:203], v[204:207], v[48:63]
	v_mfma_f32_32x32x16_bf16 v[16:31], v[200:203], v[208:211], v[16:31]
	ds_read_b128 v[200:203], v189 offset:53248
	s_waitcnt lgkmcnt(0)
	v_mfma_f32_32x32x16_bf16 v[32:47], v[200:203], v[204:207], v[32:47]
	ds_read_b128 v[204:207], v192 offset:49152
	ds_read_b128 v[212:215], v191 offset:32768
	v_mfma_f32_32x32x16_bf16 v[0:15], v[200:203], v[208:211], v[0:15]
	ds_read_b128 v[200:203], v193 offset:32768
	ds_read_b128 v[208:211], v192 offset:53248
	s_waitcnt vmcnt(0)
	s_waitcnt vmcnt(0) lgkmcnt(0)
	s_barrier
	global_load_lds_dwordx4 v64, s[98:99]
	s_mov_b32 m0, s84
	v_mfma_f32_32x32x16_bf16 v[48:63], v[204:207], v[212:215], v[48:63]
	global_load_lds_dwordx4 v66, s[98:99]
	s_mov_b32 m0, s73
	s_nop 0
	global_load_lds_dwordx4 v68, s[98:99]
	s_mov_b32 m0, s86
	v_mfma_f32_32x32x16_bf16 v[16:31], v[204:207], v[200:203], v[16:31]
	global_load_lds_dwordx4 v70, s[98:99]
	s_mov_b32 m0, s85
	s_nop 0
	global_load_lds_dwordx4 v64, s[100:101]
	s_mov_b32 m0, s87
	ds_read_b128 v[88:91], v183 offset:16384
	global_load_lds_dwordx4 v66, s[100:101]
	s_mov_b32 m0, s88
	v_mfma_f32_32x32x16_bf16 v[32:47], v[208:211], v[212:215], v[32:47]
	global_load_lds_dwordx4 v68, s[100:101]
	s_mov_b32 m0, s89
	ds_read_b128 v[92:95], v182
	global_load_lds_dwordx4 v70, s[100:101]
	ds_read_b128 v[84:87], v184
	s_waitcnt lgkmcnt(0)
	v_mfma_f32_32x32x16_bf16 v[48:63], v[88:91], v[92:95], v[48:63]
	v_mfma_f32_32x32x16_bf16 v[16:31], v[88:91], v[84:87], v[16:31]
	ds_read_b128 v[88:91], v183 offset:20480
	v_mfma_f32_32x32x16_bf16 v[0:15], v[208:211], v[200:203], v[0:15]
	s_waitcnt lgkmcnt(0)
	v_mfma_f32_32x32x16_bf16 v[32:47], v[88:91], v[92:95], v[32:47]
	v_mfma_f32_32x32x16_bf16 v[0:15], v[88:91], v[84:87], v[0:15]
	ds_read_b128 v[84:87], v186 offset:16384
	ds_read_b128 v[88:91], v185
	ds_read_b128 v[92:95], v187
	s_waitcnt lgkmcnt(0)
	v_mfma_f32_32x32x16_bf16 v[48:63], v[84:87], v[88:91], v[48:63]
	v_mfma_f32_32x32x16_bf16 v[16:31], v[84:87], v[92:95], v[16:31]
	ds_read_b128 v[84:87], v186 offset:20480
	s_waitcnt lgkmcnt(0)
	v_mfma_f32_32x32x16_bf16 v[32:47], v[84:87], v[88:91], v[32:47]
	v_mfma_f32_32x32x16_bf16 v[0:15], v[84:87], v[92:95], v[0:15]
	ds_read_b128 v[84:87], v189 offset:16384
	ds_read_b128 v[88:91], v188
	ds_read_b128 v[92:95], v190
	s_waitcnt lgkmcnt(0)
	v_mfma_f32_32x32x16_bf16 v[48:63], v[84:87], v[88:91], v[48:63]
	v_mfma_f32_32x32x16_bf16 v[16:31], v[84:87], v[92:95], v[16:31]
	ds_read_b128 v[84:87], v189 offset:20480
	s_waitcnt lgkmcnt(0)
	v_mfma_f32_32x32x16_bf16 v[32:47], v[84:87], v[88:91], v[32:47]
	v_mfma_f32_32x32x16_bf16 v[0:15], v[84:87], v[92:95], v[0:15]
	ds_read_b128 v[84:87], v192 offset:16384
	ds_read_b128 v[88:91], v191
	ds_read_b128 v[92:95], v193
	s_waitcnt lgkmcnt(0)
	v_mfma_f32_32x32x16_bf16 v[48:63], v[84:87], v[88:91], v[48:63]
	v_mfma_f32_32x32x16_bf16 v[16:31], v[84:87], v[92:95], v[16:31]
	ds_read_b128 v[84:87], v192 offset:20480
	s_waitcnt vmcnt(0)
	s_waitcnt vmcnt(0) lgkmcnt(0)
	s_barrier
	v_mfma_f32_32x32x16_bf16 v[32:47], v[84:87], v[88:91], v[32:47]
	v_mfma_f32_32x32x16_bf16 v[0:15], v[84:87], v[92:95], v[0:15]
	ds_read_b128 v[84:87], v183 offset:49152
	ds_read_b128 v[88:91], v182 offset:32768
	ds_read_b128 v[92:95], v184 offset:32768
	s_waitcnt lgkmcnt(1)
	v_mfma_f32_32x32x16_bf16 v[48:63], v[84:87], v[88:91], v[48:63]
	s_waitcnt lgkmcnt(0)
	v_mfma_f32_32x32x16_bf16 v[16:31], v[84:87], v[92:95], v[16:31]
	ds_read_b128 v[84:87], v183 offset:53248
	s_waitcnt lgkmcnt(0)
	v_mfma_f32_32x32x16_bf16 v[32:47], v[84:87], v[88:91], v[32:47]
	v_mfma_f32_32x32x16_bf16 v[0:15], v[84:87], v[92:95], v[0:15]
	ds_read_b128 v[84:87], v186 offset:49152
	ds_read_b128 v[88:91], v185 offset:32768
	ds_read_b128 v[92:95], v187 offset:32768
	s_waitcnt lgkmcnt(1)
	v_mfma_f32_32x32x16_bf16 v[48:63], v[84:87], v[88:91], v[48:63]
	s_waitcnt lgkmcnt(0)
	v_mfma_f32_32x32x16_bf16 v[16:31], v[84:87], v[92:95], v[16:31]
	ds_read_b128 v[84:87], v186 offset:53248
	s_waitcnt lgkmcnt(0)
	v_mfma_f32_32x32x16_bf16 v[32:47], v[84:87], v[88:91], v[32:47]
	v_mfma_f32_32x32x16_bf16 v[0:15], v[84:87], v[92:95], v[0:15]
	ds_read_b128 v[86:89], v189 offset:49152
	ds_read_b128 v[90:93], v188 offset:32768
	ds_read_b128 v[94:97], v190 offset:32768
	v_lshl_add_u64 v[84:85], v[72:73], 0, s[28:29]
	s_lshl_b64 s[28:29], s[16:17], 14
	s_add_i32 s16, s2, s82
	s_waitcnt lgkmcnt(1)
	v_mfma_f32_32x32x16_bf16 v[48:63], v[86:89], v[90:93], v[48:63]
	s_waitcnt lgkmcnt(0)
	v_mfma_f32_32x32x16_bf16 v[16:31], v[86:89], v[94:97], v[16:31]
	ds_read_b128 v[86:89], v192 offset:49152
	ds_read_b128 v[200:203], v191 offset:32768
	ds_read_b128 v[204:207], v189 offset:53248
	ds_read_b128 v[208:211], v192 offset:53248
	ds_read_b128 v[212:215], v193 offset:32768
	s_waitcnt vmcnt(0)
	s_waitcnt lgkmcnt(0)
	s_barrier
	v_mfma_f32_32x32x16_bf16 v[32:47], v[204:207], v[90:93], v[32:47]
	v_mfma_f32_32x32x16_bf16 v[0:15], v[204:207], v[94:97], v[0:15]
	v_mfma_f32_32x32x16_bf16 v[48:63], v[86:89], v[200:203], v[48:63]
	v_mfma_f32_32x32x16_bf16 v[32:47], v[208:211], v[200:203], v[32:47]
	s_nop 10
	v_cvt_pk_bf16_f32 v48, v48, v49
	v_cvt_pk_bf16_f32 v49, v50, v51
	v_cvt_pk_bf16_f32 v50, v52, v53
	v_cvt_pk_bf16_f32 v51, v54, v55
	ds_write2_b64 v194, v[48:49], v[50:51] offset1:2
	v_cvt_pk_bf16_f32 v48, v56, v57
	v_cvt_pk_bf16_f32 v49, v58, v59
	v_mfma_f32_32x32x16_bf16 v[16:31], v[86:89], v[212:215], v[16:31]
	v_cvt_pk_bf16_f32 v32, v32, v33
	v_cvt_pk_bf16_f32 v33, v34, v35
	v_cvt_pk_bf16_f32 v34, v36, v37
	v_cvt_pk_bf16_f32 v35, v38, v39
	v_cvt_pk_bf16_f32 v50, v60, v61
	v_cvt_pk_bf16_f32 v51, v62, v63
	ds_write2_b64 v194, v[32:33], v[34:35] offset0:8 offset1:10
	v_mfma_f32_32x32x16_bf16 v[0:15], v[208:211], v[212:215], v[0:15]
	v_cvt_pk_bf16_f32 v32, v40, v41
	v_cvt_pk_bf16_f32 v33, v42, v43
	v_cvt_pk_bf16_f32 v34, v44, v45
	v_cvt_pk_bf16_f32 v35, v46, v47
	v_cvt_pk_bf16_f32 v16, v16, v17
	v_cvt_pk_bf16_f32 v17, v18, v19
	v_cvt_pk_bf16_f32 v18, v20, v21
	v_cvt_pk_bf16_f32 v19, v22, v23
	s_nop 3
	v_cvt_pk_bf16_f32 v0, v0, v1
	v_cvt_pk_bf16_f32 v1, v2, v3
	v_cvt_pk_bf16_f32 v2, v4, v5
	v_cvt_pk_bf16_f32 v3, v6, v7
	ds_write2_b64 v194, v[48:49], v[50:51] offset0:4 offset1:6
	ds_write2_b64 v194, v[32:33], v[34:35] offset0:12 offset1:14
	ds_write2_b64 v195, v[16:17], v[18:19] offset1:2
	v_cvt_pk_bf16_f32 v16, v24, v25
	v_cvt_pk_bf16_f32 v17, v26, v27
	v_cvt_pk_bf16_f32 v18, v28, v29
	v_cvt_pk_bf16_f32 v19, v30, v31
	ds_write2_b64 v195, v[0:1], v[2:3] offset0:8 offset1:10
	v_cvt_pk_bf16_f32 v0, v8, v9
	v_cvt_pk_bf16_f32 v1, v10, v11
	v_cvt_pk_bf16_f32 v2, v12, v13
	v_cvt_pk_bf16_f32 v3, v14, v15
	v_lshl_add_u64 v[32:33], v[84:85], 0, v[74:75]
	ds_write2_b64 v195, v[16:17], v[18:19] offset0:4 offset1:6
	ds_write2_b64 v195, v[0:1], v[2:3] offset0:12 offset1:14
	s_waitcnt lgkmcnt(0)
	s_barrier
	global_load_dwordx4 v[0:3], v[32:33], off
	global_load_dwordx4 v[16:19], v[32:33], off offset:32
	ds_read_b128 v[28:31], v199
	ds_read_b128 v[20:23], v199 offset:32
	s_waitcnt vmcnt(1) lgkmcnt(1)
	v_mfma_f32_32x32x16_bf16 v[0:15], v[0:3], v[28:31], 0
	global_load_dwordx4 v[34:37], v[32:33], off offset:96
	ds_read_b128 v[24:27], v199 offset:64
	s_waitcnt vmcnt(1) lgkmcnt(1)
	v_mfma_f32_32x32x16_bf16 v[0:15], v[16:19], v[20:23], v[0:15]
	global_load_dwordx4 v[16:19], v[32:33], off offset:64
	v_cndmask_b32_e32 v33, v196, v197, vcc
	v_lshlrev_b32_e32 v33, 2, v33
	v_add_u32_e32 v32, s68, v101
	s_waitcnt vmcnt(0) lgkmcnt(0)
	v_mfma_f32_32x32x16_bf16 v[0:15], v[16:19], v[24:27], v[0:15]
	ds_read_b128 v[16:19], v199 offset:96
	s_waitcnt lgkmcnt(0)
	v_mfma_f32_32x32x16_bf16 v[0:15], v[34:37], v[16:19], v[0:15]
	s_nop 11
	v_not_b32_e32 v34, v0
	v_or_b32_e32 v35, 0x80000000, v0
	v_cmp_gt_i32_e32 vcc, 0, v0
	v_or_b32_e32 v36, 0x80000000, v3
	v_or_b32_e32 v37, 0x80000000, v7
	v_cndmask_b32_e32 v0, v35, v34, vcc
	v_not_b32_e32 v34, v1
	v_or_b32_e32 v35, 0x80000000, v1
	v_cmp_gt_i32_e32 vcc, 0, v1
	v_and_or_b32 v0, v0, s77, v102
	v_or_b32_e32 v39, 0x80000000, v4
	v_cndmask_b32_e32 v1, v35, v34, vcc
	v_not_b32_e32 v35, v3
	v_cmp_gt_i32_e32 vcc, 0, v3
	v_and_or_b32 v1, v1, s77, v103
	v_max_u32_e32 v34, v0, v1
	v_cndmask_b32_e32 v3, v36, v35, vcc
	v_not_b32_e32 v35, v2
	v_or_b32_e32 v36, 0x80000000, v2
	v_cmp_gt_i32_e32 vcc, 0, v2
	v_and_or_b32 v3, v3, s77, v105
	v_min_u32_e32 v0, v0, v1
	v_cndmask_b32_e32 v2, v36, v35, vcc
	v_and_or_b32 v2, v2, s77, v104
	v_min_u32_e32 v35, v3, v2
	v_max_u32_e32 v1, v3, v2
	v_not_b32_e32 v3, v7
	v_cmp_gt_i32_e32 vcc, 0, v7
	v_not_b32_e32 v7, v6
	v_max_u32_e32 v36, v34, v35
	v_cndmask_b32_e32 v3, v37, v3, vcc
	v_or_b32_e32 v37, 0x80000000, v6
	v_cmp_gt_i32_e32 vcc, 0, v6
	v_and_or_b32 v3, v3, s77, v109
	v_max_u32_e32 v2, v0, v1
	v_cndmask_b32_e32 v6, v37, v7, vcc
	v_not_b32_e32 v37, v4
	v_cmp_gt_i32_e32 vcc, 0, v4
	v_and_or_b32 v6, v6, s77, v108
	v_max_u32_e32 v7, v3, v6
	v_cndmask_b32_e32 v4, v39, v37, vcc
	v_not_b32_e32 v37, v5
	v_or_b32_e32 v39, 0x80000000, v5
	v_cmp_gt_i32_e32 vcc, 0, v5
	v_and_or_b32 v4, v4, s77, v106
	v_min_u32_e32 v3, v3, v6
	v_cndmask_b32_e32 v5, v39, v37, vcc
	v_and_or_b32 v5, v5, s77, v107
	v_min_u32_e32 v37, v4, v5
	v_max_u32_e32 v4, v4, v5
	v_min_u32_e32 v5, v3, v4
	v_min_u32_e32 v34, v34, v35
	v_min_u32_e32 v0, v0, v1
	v_max_u32_e32 v1, v7, v37
	v_max_u32_e32 v3, v3, v4
	v_min_u32_e32 v39, v7, v37
	v_max_u32_e32 v40, v34, v0
	v_min_u32_e32 v7, v1, v3
	v_min_u32_e32 v44, v34, v0
	v_max_u32_e32 v45, v1, v3
	v_not_b32_e32 v0, v15
	v_or_b32_e32 v1, 0x80000000, v15
	v_cmp_gt_i32_e32 vcc, 0, v15
	v_max_u32_e32 v38, v36, v2
	v_min_u32_e32 v42, v36, v2
	v_cndmask_b32_e32 v0, v1, v0, vcc
	v_not_b32_e32 v1, v14
	v_or_b32_e32 v2, 0x80000000, v14
	v_cmp_gt_i32_e32 vcc, 0, v14
	v_not_b32_e32 v3, v12
	v_or_b32_e32 v4, 0x80000000, v12
	v_cndmask_b32_e32 v1, v2, v1, vcc
	v_cmp_gt_i32_e32 vcc, 0, v12
	v_min_u32_e32 v6, v39, v5
	v_max_u32_e32 v43, v39, v5
	v_cndmask_b32_e32 v3, v4, v3, vcc
	v_not_b32_e32 v4, v13
	v_or_b32_e32 v5, 0x80000000, v13
	v_cmp_gt_i32_e32 vcc, 0, v13
	v_and_or_b32 v0, v0, s77, v117
	v_and_or_b32 v1, v1, s77, v116
	v_cndmask_b32_e32 v4, v5, v4, vcc
	v_and_or_b32 v3, v3, s77, v114
	v_and_or_b32 v4, v4, s77, v115
	v_max_u32_e32 v2, v0, v1
	v_min_u32_e32 v5, v3, v4
	v_min_u32_e32 v0, v0, v1
	v_max_u32_e32 v1, v3, v4
	v_not_b32_e32 v3, v8
	v_or_b32_e32 v4, 0x80000000, v8
	v_cmp_gt_i32_e32 vcc, 0, v8
	v_or_b32_e32 v8, 0x80000000, v9
	v_or_b32_e32 v15, 0x80000000, v11
	v_cndmask_b32_e32 v3, v4, v3, vcc
	v_not_b32_e32 v4, v9
	v_cmp_gt_i32_e32 vcc, 0, v9
	v_not_b32_e32 v9, v11
	v_and_or_b32 v3, v3, s77, v110
	v_cndmask_b32_e32 v4, v8, v4, vcc
	v_cmp_gt_i32_e32 vcc, 0, v11
	v_not_b32_e32 v11, v10
	v_and_or_b32 v4, v4, s77, v111
	v_cndmask_b32_e32 v9, v15, v9, vcc
	v_or_b32_e32 v15, 0x80000000, v10
	v_cmp_gt_i32_e32 vcc, 0, v10
	v_and_or_b32 v9, v9, s77, v113
	v_max_u32_e32 v8, v3, v4
	v_cndmask_b32_e32 v10, v15, v11, vcc
	v_and_or_b32 v10, v10, s77, v112
	v_min_u32_e32 v11, v9, v10
	v_min_u32_e32 v3, v3, v4
	v_max_u32_e32 v4, v9, v10
	v_max_u32_e32 v12, v2, v5
	v_min_u32_e32 v15, v8, v11
	v_min_u32_e32 v9, v3, v4
	v_min_u32_e32 v34, v2, v5
	v_max_u32_e32 v8, v8, v11
	v_max_u32_e32 v11, v3, v4
	v_lshl_add_u64 v[4:5], v[84:85], 0, v[76:77]
	v_max_u32_e32 v13, v0, v1
	v_min_u32_e32 v35, v0, v1
	global_load_dwordx4 v[0:3], v[4:5], off
	v_min_u32_e32 v10, v15, v9
	v_max_u32_e32 v54, v34, v35
	v_max_u32_e32 v9, v15, v9
	v_min_u32_e32 v15, v34, v35
	global_load_dwordx4 v[34:37], v[4:5], off offset:32
	v_max_u32_e32 v46, v38, v6
	v_max_u32_e32 v47, v40, v7
	v_min_u32_e32 v6, v38, v6
	v_min_u32_e32 v7, v40, v7
	global_load_dwordx4 v[38:41], v[4:5], off offset:64
	v_max_u32_e32 v49, v42, v43
	v_max_u32_e32 v50, v44, v45
	v_min_u32_e32 v62, v42, v43
	v_min_u32_e32 v63, v44, v45
	global_load_dwordx4 v[42:45], v[4:5], off offset:96
	v_max_u32_e32 v14, v12, v13
	v_min_u32_e32 v55, v8, v11
	v_min_u32_e32 v12, v12, v13
	v_max_u32_e32 v8, v8, v11
	v_min_u32_e32 v53, v14, v10
	v_min_u32_e32 v56, v54, v55
	v_min_u32_e32 v13, v12, v9
	v_min_u32_e32 v11, v15, v8
	v_max_u32_e32 v10, v14, v10
	v_max_u32_e32 v14, v54, v55
	v_max_u32_e32 v5, v12, v9
	v_max_u32_e32 v8, v15, v8
	v_max_u32_e32 v48, v46, v47
	v_max_u32_e32 v51, v49, v50
	v_min_u32_e32 v57, v53, v56
	v_min_u32_e32 v58, v13, v11
	v_max_u32_e32 v61, v6, v7
	v_max_u32_e32 v86, v62, v63
	v_min_u32_e32 v4, v10, v14
	v_min_u32_e32 v9, v5, v8
	v_min_u32_e32 v46, v46, v47
	v_min_u32_e32 v47, v49, v50
	v_max_u32_e32 v50, v53, v56
	v_max_u32_e32 v11, v13, v11
	v_min_u32_e32 v6, v6, v7
	v_min_u32_e32 v7, v62, v63
	v_max_u32_e32 v10, v10, v14
	v_max_u32_e32 v5, v5, v8
	v_max_u32_e32 v52, v48, v51
	v_min_u32_e32 v59, v57, v58
	v_max_u32_e32 v87, v61, v86
	v_min_u32_e32 v12, v4, v9
	v_max_u32_e32 v49, v46, v47
	v_min_u32_e32 v13, v50, v11
	v_max_u32_e32 v55, v6, v7
	v_min_u32_e32 v8, v10, v5
	v_min_u32_e32 v48, v48, v51
	v_max_u32_e32 v51, v57, v58
	v_min_u32_e32 v58, v61, v86
	v_max_u32_e32 v61, v4, v9
	v_min_u32_e32 v46, v46, v47
	v_max_u32_e32 v47, v50, v11
	v_min_u32_e32 v50, v6, v7
	v_max_u32_e32 v63, v10, v5
	v_min_u32_e32 v60, v52, v59
	v_min_u32_e32 v15, v87, v12
	v_min_u32_e32 v53, v49, v13
	v_min_u32_e32 v14, v55, v8
	v_min_u32_e32 v57, v48, v51
	v_min_u32_e32 v4, v58, v61
	v_min_u32_e32 v11, v46, v47
	v_min_u32_e32 v5, v50, v63
	v_min_u32_e32 v54, v60, v15
	v_min_u32_e32 v56, v53, v14
	v_min_u32_e32 v9, v57, v4
	v_min_u32_e32 v6, v11, v5
	v_min_u32_e32 v62, v54, v56
	v_min_u32_e32 v86, v9, v6
	v_max_u32_e32 v54, v54, v56
	v_max_u32_e32 v56, v9, v6
	v_max_u32_e32 v6, v60, v15
	v_max_u32_e32 v7, v53, v14
	v_max_u32_e32 v4, v57, v4
	v_max_u32_e32 v5, v11, v5
	v_min_u32_e32 v53, v6, v7
	v_min_u32_e32 v57, v4, v5
	v_max_u32_e32 v90, v6, v7
	v_max_u32_e32 v91, v4, v5
	v_max_u32_e32 v52, v52, v59
	v_max_u32_e32 v59, v87, v12
	v_max_u32_e32 v49, v49, v13
	v_max_u32_e32 v55, v55, v8
	s_waitcnt vmcnt(3)
	v_mfma_f32_32x32x16_bf16 v[0:15], v[0:3], v[28:31], 0
	v_max_u32_e32 v48, v48, v51
	v_max_u32_e32 v51, v58, v61
	v_min_u32_e32 v93, v49, v55
	v_min_u32_e32 v58, v48, v51
	v_max_u32_e32 v46, v46, v47
	v_max_u32_e32 v47, v50, v63
	v_min_u32_e32 v50, v46, v47
	s_waitcnt vmcnt(2)
	v_mfma_f32_32x32x16_bf16 v[0:15], v[34:37], v[20:23], v[0:15]
	v_max_u32_e32 v34, v52, v59
	v_max_u32_e32 v35, v49, v55
	v_min_u32_e32 v49, v34, v35
	v_max_u32_e32 v36, v48, v51
	v_max_u32_e32 v48, v34, v35
	v_max_u32_e32 v37, v46, v47
	v_min_u32_e32 v46, v36, v37
	s_waitcnt vmcnt(1)
	v_mfma_f32_32x32x16_bf16 v[0:15], v[38:41], v[24:27], v[0:15]
	v_max_u32_e32 v51, v36, v37
	v_min_u32_e32 v87, v52, v59
	v_min_u32_e32 v94, v87, v93
	v_max_u32_e32 v87, v87, v93
	v_min_u32_e32 v61, v58, v50
	v_max_u32_e32 v50, v58, v50
	v_min_u32_e32 v89, v54, v56
	s_waitcnt vmcnt(0)
	v_mfma_f32_32x32x16_bf16 v[0:15], v[42:45], v[16:19], v[0:15]
	v_min_u32_e32 v60, v53, v57
	v_min_u32_e32 v92, v90, v91
	v_min_u32_e32 v58, v87, v50
	v_min_u32_e32 v47, v49, v46
	v_min_u32_e32 v52, v48, v51
	v_min_u32_e32 v88, v62, v86
	v_min_u32_e32 v63, v94, v61
	s_nop 4
	v_not_b32_e32 v34, v0
	v_or_b32_e32 v35, 0x80000000, v0
	v_cmp_gt_i32_e32 vcc, 0, v0
	v_or_b32_e32 v36, 0x80000000, v3
	v_not_b32_e32 v37, v7
	v_cndmask_b32_e32 v0, v35, v34, vcc
	v_not_b32_e32 v34, v1
	v_or_b32_e32 v35, 0x80000000, v1
	v_cmp_gt_i32_e32 vcc, 0, v1
	v_or_b32_e32 v38, 0x80000000, v7
	v_or_b32_e32 v39, 0x80000000, v4
	v_cndmask_b32_e32 v1, v35, v34, vcc
	v_not_b32_e32 v35, v3
	v_cmp_gt_i32_e32 vcc, 0, v3
	v_not_b32_e32 v41, v15
	v_or_b32_e32 v42, 0x80000000, v15
	v_cndmask_b32_e32 v3, v36, v35, vcc
	v_not_b32_e32 v35, v2
	v_or_b32_e32 v36, 0x80000000, v2
	v_cmp_gt_i32_e32 vcc, 0, v2
	v_or_b32_e32 v43, 0x80000000, v12
	v_not_b32_e32 v44, v8
	v_cndmask_b32_e32 v2, v36, v35, vcc
	v_cmp_gt_i32_e32 vcc, 0, v7
	v_or_b32_e32 v45, 0x80000000, v8
	v_or_b32_e32 v55, 0x80000000, v11
	v_cndmask_b32_e32 v7, v38, v37, vcc
	v_not_b32_e32 v37, v6
	v_or_b32_e32 v38, 0x80000000, v6
	v_cmp_gt_i32_e32 vcc, 0, v6
	v_and_or_b32 v0, v0, s77, v118
	v_and_or_b32 v1, v1, s77, v119
	v_cndmask_b32_e32 v6, v38, v37, vcc
	v_not_b32_e32 v38, v4
	v_cmp_gt_i32_e32 vcc, 0, v4
	v_and_or_b32 v3, v3, s77, v121
	v_and_or_b32 v2, v2, s77, v120
	v_cndmask_b32_e32 v4, v39, v38, vcc
	v_not_b32_e32 v38, v5
	v_or_b32_e32 v39, 0x80000000, v5
	v_cmp_gt_i32_e32 vcc, 0, v5
	v_and_or_b32 v7, v7, s77, v125
	v_and_or_b32 v6, v6, s77, v124
	v_cndmask_b32_e32 v5, v39, v38, vcc
	v_cmp_gt_i32_e32 vcc, 0, v15
	v_and_or_b32 v4, v4, s77, v122
	v_and_or_b32 v5, v5, s77, v123
	v_cndmask_b32_e32 v15, v42, v41, vcc
	v_not_b32_e32 v41, v14
	v_or_b32_e32 v42, 0x80000000, v14
	v_cmp_gt_i32_e32 vcc, 0, v14
	v_and_or_b32 v15, v15, s77, v133
	v_max_u32_e32 v34, v0, v1
	v_cndmask_b32_e32 v14, v42, v41, vcc
	v_not_b32_e32 v42, v12
	v_cmp_gt_i32_e32 vcc, 0, v12
	v_and_or_b32 v14, v14, s77, v132
	v_min_u32_e32 v35, v3, v2
	v_cndmask_b32_e32 v12, v43, v42, vcc
	v_not_b32_e32 v42, v13
	v_or_b32_e32 v43, 0x80000000, v13
	v_cmp_gt_i32_e32 vcc, 0, v13
	v_and_or_b32 v12, v12, s77, v130
	v_min_u32_e32 v0, v0, v1
	v_cndmask_b32_e32 v13, v43, v42, vcc
	v_cmp_gt_i32_e32 vcc, 0, v8
	v_and_or_b32 v13, v13, s77, v131
	v_max_u32_e32 v1, v3, v2
	v_cndmask_b32_e32 v8, v45, v44, vcc
	v_not_b32_e32 v44, v9
	v_or_b32_e32 v45, 0x80000000, v9
	v_cmp_gt_i32_e32 vcc, 0, v9
	v_and_or_b32 v8, v8, s77, v126
	v_max_u32_e32 v37, v7, v6
	v_cndmask_b32_e32 v9, v45, v44, vcc
	v_not_b32_e32 v45, v11
	v_cmp_gt_i32_e32 vcc, 0, v11
	v_and_or_b32 v9, v9, s77, v127
	v_min_u32_e32 v38, v4, v5
	v_cndmask_b32_e32 v11, v55, v45, vcc
	v_not_b32_e32 v45, v10
	v_or_b32_e32 v55, 0x80000000, v10
	v_cmp_gt_i32_e32 vcc, 0, v10
	v_and_or_b32 v11, v11, s77, v129
	v_min_u32_e32 v6, v7, v6
	v_cndmask_b32_e32 v10, v55, v45, vcc
	v_and_or_b32 v10, v10, s77, v128
	v_max_u32_e32 v4, v4, v5
	v_max_u32_e32 v41, v15, v14
	v_min_u32_e32 v42, v12, v13
	v_min_u32_e32 v14, v15, v14
	v_max_u32_e32 v12, v12, v13
	v_max_u32_e32 v44, v8, v9
	v_min_u32_e32 v45, v11, v10
	v_min_u32_e32 v8, v8, v9
	v_max_u32_e32 v9, v11, v10
	v_max_u32_e32 v36, v34, v35
	v_max_u32_e32 v2, v0, v1
	v_min_u32_e32 v39, v37, v38
	v_min_u32_e32 v5, v6, v4
	v_min_u32_e32 v34, v34, v35
	v_min_u32_e32 v0, v0, v1
	v_max_u32_e32 v35, v37, v38
	v_max_u32_e32 v4, v6, v4
	v_max_u32_e32 v43, v41, v42
	v_max_u32_e32 v13, v14, v12
	v_min_u32_e32 v55, v44, v45
	v_min_u32_e32 v10, v8, v9
	v_min_u32_e32 v41, v41, v42
	v_min_u32_e32 v12, v14, v12
	v_max_u32_e32 v42, v44, v45
	v_max_u32_e32 v8, v8, v9
	v_max_u32_e32 v3, v36, v2
	v_min_u32_e32 v7, v39, v5
	v_max_u32_e32 v1, v34, v0
	v_min_u32_e32 v6, v35, v4
	v_min_u32_e32 v2, v36, v2
	v_max_u32_e32 v5, v39, v5
	v_min_u32_e32 v0, v34, v0
	v_max_u32_e32 v4, v35, v4
	v_max_u32_e32 v15, v43, v13
	v_min_u32_e32 v11, v55, v10
	v_max_u32_e32 v14, v41, v12
	v_min_u32_e32 v9, v42, v8
	v_min_u32_e32 v13, v43, v13
	v_max_u32_e32 v10, v55, v10
	v_min_u32_e32 v12, v41, v12
	v_max_u32_e32 v8, v42, v8
	v_max_u32_e32 v40, v3, v7
	v_max_u32_e32 v37, v1, v6
	v_max_u32_e32 v36, v2, v5
	v_max_u32_e32 v34, v0, v4
	v_min_u32_e32 v59, v15, v11
	v_min_u32_e32 v44, v14, v9
	v_min_u32_e32 v43, v13, v10
	v_min_u32_e32 v41, v12, v8
	v_min_u32_e32 v3, v3, v7
	v_min_u32_e32 v1, v1, v6
	v_min_u32_e32 v2, v2, v5
	v_min_u32_e32 v0, v0, v4
	v_max_u32_e32 v5, v15, v11
	v_max_u32_e32 v9, v14, v9
	v_max_u32_e32 v10, v13, v10
	v_max_u32_e32 v8, v12, v8
	v_max_u32_e32 v38, v40, v37
	v_max_u32_e32 v35, v36, v34
	v_min_u32_e32 v45, v59, v44
	v_min_u32_e32 v42, v43, v41
	v_max_u32_e32 v6, v3, v1
	v_max_u32_e32 v4, v2, v0
	v_min_u32_e32 v11, v5, v9
	v_min_u32_e32 v12, v10, v8
	v_min_u32_e32 v37, v40, v37
	v_min_u32_e32 v34, v36, v34
	v_max_u32_e32 v40, v59, v44
	v_max_u32_e32 v41, v43, v41
	v_min_u32_e32 v1, v3, v1
	v_min_u32_e32 v0, v2, v0
	v_max_u32_e32 v2, v5, v9
	v_max_u32_e32 v3, v10, v8
	v_max_u32_e32 v39, v38, v35
	v_min_u32_e32 v55, v45, v42
	v_max_u32_e32 v7, v6, v4
	v_min_u32_e32 v13, v11, v12
	v_min_u32_e32 v43, v40, v41
	v_min_u32_e32 v38, v38, v35
	v_max_u32_e32 v42, v45, v42
	v_min_u32_e32 v6, v6, v4
	v_max_u32_e32 v11, v11, v12
	v_min_u32_e32 v45, v37, v34
	v_max_u32_e32 v40, v40, v41
	v_min_u32_e32 v41, v1, v0
	v_max_u32_e32 v95, v2, v3
	v_max_u32_e32 v36, v37, v34
	v_max_u32_e32 v59, v1, v0
	v_min_u32_e32 v8, v2, v3
	v_min_u32_e32 v35, v38, v42
	v_min_u32_e32 v4, v6, v11
	v_min_u32_e32 v34, v45, v40
	v_min_u32_e32 v0, v41, v95
	v_min_u32_e32 v93, v39, v55
	v_min_u32_e32 v14, v7, v13
	v_min_u32_e32 v44, v36, v43
	v_min_u32_e32 v5, v59, v8
	v_min_u32_e32 v12, v35, v4
	v_min_u32_e32 v1, v34, v0
	v_min_u32_e32 v9, v44, v5
	v_min_u32_e32 v96, v12, v1
	v_max_u32_e32 v12, v12, v1
	v_max_u32_e32 v1, v93, v14
	v_max_u32_e32 v2, v44, v5
	v_max_u32_e32 v3, v35, v4
	v_max_u32_e32 v0, v34, v0
	v_lshl_add_u64 v[4:5], v[84:85], 0, v[78:79]
	v_min_u32_e32 v15, v93, v14
	v_min_u32_e32 v14, v1, v2
	v_min_u32_e32 v93, v3, v0
	v_max_u32_e32 v99, v1, v2
	v_max_u32_e32 v200, v3, v0
	global_load_dwordx4 v[0:3], v[4:5], off
	v_max_u32_e32 v43, v36, v43
	global_load_dwordx4 v[34:37], v[4:5], off offset:32
	v_max_u32_e32 v44, v39, v55
	v_max_u32_e32 v202, v38, v42
	v_max_u32_e32 v203, v45, v40
	v_max_u32_e32 v95, v41, v95
	global_load_dwordx4 v[38:41], v[4:5], off offset:64
	v_max_u32_e32 v6, v6, v11
	v_max_u32_e32 v7, v7, v13
	v_max_u32_e32 v8, v59, v8
	v_min_u32_e32 v11, v202, v6
	v_min_u32_e32 v42, v203, v95
	v_min_u32_e32 v13, v44, v7
	v_min_u32_e32 v55, v43, v8
	v_min_u32_e32 v204, v11, v42
	v_max_u32_e32 v11, v11, v42
	v_max_u32_e32 v7, v44, v7
	v_max_u32_e32 v8, v43, v8
	global_load_dwordx4 v[42:45], v[4:5], off offset:96
	v_max_u32_e32 v5, v202, v6
	v_max_u32_e32 v6, v203, v95
	v_min_u32_e32 v10, v15, v9
	v_max_u32_e32 v9, v15, v9
	v_min_u32_e32 v59, v13, v55
	v_max_u32_e32 v13, v13, v55
	v_min_u32_e32 v4, v7, v8
	v_min_u32_e32 v95, v5, v6
	v_max_u32_e32 v7, v7, v8
	v_max_u32_e32 v5, v5, v6
	v_min_u32_e32 v97, v10, v96
	v_min_u32_e32 v15, v9, v12
	v_min_u32_e32 v98, v14, v93
	v_min_u32_e32 v201, v99, v200
	v_min_u32_e32 v205, v59, v204
	v_min_u32_e32 v55, v13, v11
	v_min_u32_e32 v202, v4, v95
	v_min_u32_e32 v6, v7, v5
	v_max3_u32 v8, v48, v51, v97
	v_max3_u32 v10, v52, v10, v96
	v_max3_u32 v15, v49, v46, v15
	v_max3_u32 v9, v47, v9, v12
	v_max3_u32 v12, v87, v50, v98
	v_max3_u32 v14, v58, v14, v93
	v_max3_u32 v46, v94, v61, v201
	v_max3_u32 v48, v90, v91, v205
	v_max3_u32 v49, v92, v59, v204
	v_max3_u32 v50, v53, v57, v55
	v_max3_u32 v11, v60, v13, v11
	v_max3_u32 v13, v54, v56, v202
	v_max3_u32 v4, v89, v4, v95
	v_max3_u32 v6, v62, v86, v6
	v_max3_u32 v47, v63, v99, v200
	v_max3_u32 v5, v88, v7, v5
	v_max_u32_e32 v7, v8, v48
	v_min_u32_e32 v8, v8, v48
	v_max_u32_e32 v48, v10, v49
	v_min_u32_e32 v10, v10, v49
	v_max_u32_e32 v49, v15, v50
	v_min_u32_e32 v15, v15, v50
	v_max_u32_e32 v50, v9, v11
	v_min_u32_e32 v9, v9, v11
	v_max_u32_e32 v11, v12, v13
	v_min_u32_e32 v12, v12, v13
	v_max_u32_e32 v13, v14, v4
	v_min_u32_e32 v4, v14, v4
	v_max_u32_e32 v14, v46, v6
	v_min_u32_e32 v6, v46, v6
	v_max_u32_e32 v46, v47, v5
	v_min_u32_e32 v5, v47, v5
	v_max_u32_e32 v47, v7, v11
	v_min_u32_e32 v51, v7, v11
	v_max_u32_e32 v7, v49, v14
	v_max_u32_e32 v52, v48, v13
	v_min_u32_e32 v48, v48, v13
	v_min_u32_e32 v49, v49, v14
	v_max_u32_e32 v53, v50, v46
	v_min_u32_e32 v46, v50, v46
	v_max_u32_e32 v50, v8, v12
	v_min_u32_e32 v54, v8, v12
	v_max_u32_e32 v55, v10, v4
	v_min_u32_e32 v56, v10, v4
	v_max_u32_e32 v57, v15, v6
	v_min_u32_e32 v58, v15, v6
	v_max_u32_e32 v59, v9, v5
	v_min_u32_e32 v60, v9, v5
	v_max_u32_e32 v61, v47, v7
	v_min_u32_e32 v47, v47, v7
	s_waitcnt vmcnt(3)
	v_mfma_f32_32x32x16_bf16 v[0:15], v[0:3], v[28:31], 0
	v_max_u32_e32 v62, v52, v53
	v_min_u32_e32 v52, v52, v53
	v_max_u32_e32 v53, v51, v49
	v_min_u32_e32 v49, v51, v49
	v_max_u32_e32 v51, v48, v46
	v_min_u32_e32 v46, v48, v46
	v_max_u32_e32 v48, v50, v57
	s_waitcnt vmcnt(2)
	v_mfma_f32_32x32x16_bf16 v[0:15], v[34:37], v[20:23], v[0:15]
	v_min_u32_e32 v50, v50, v57
	v_max_u32_e32 v57, v55, v59
	v_min_u32_e32 v55, v55, v59
	v_max_u32_e32 v59, v54, v58
	v_min_u32_e32 v54, v54, v58
	v_max_u32_e32 v58, v56, v60
	v_min_u32_e32 v56, v56, v60
	s_waitcnt vmcnt(1)
	v_mfma_f32_32x32x16_bf16 v[0:15], v[38:41], v[24:27], v[0:15]
	v_min_u32_e32 v60, v61, v62
	v_min_u32_e32 v63, v47, v52
	v_min_u32_e32 v86, v53, v51
	v_min_u32_e32 v88, v48, v57
	v_min_u32_e32 v89, v50, v55
	v_min_u32_e32 v90, v59, v58
	v_min_u32_e32 v87, v49, v46
	s_waitcnt vmcnt(0)
	v_mfma_f32_32x32x16_bf16 v[0:15], v[42:45], v[16:19], v[0:15]
	v_min_u32_e32 v91, v54, v56
	s_nop 10
	v_not_b32_e32 v34, v0
	v_or_b32_e32 v35, 0x80000000, v0
	v_cmp_gt_i32_e32 vcc, 0, v0
	v_or_b32_e32 v36, 0x80000000, v3
	v_not_b32_e32 v37, v7
	v_cndmask_b32_e32 v0, v35, v34, vcc
	v_not_b32_e32 v34, v1
	v_or_b32_e32 v35, 0x80000000, v1
	v_cmp_gt_i32_e32 vcc, 0, v1
	v_or_b32_e32 v38, 0x80000000, v7
	v_or_b32_e32 v39, 0x80000000, v4
	v_cndmask_b32_e32 v1, v35, v34, vcc
	v_not_b32_e32 v35, v3
	v_cmp_gt_i32_e32 vcc, 0, v3
	v_not_b32_e32 v41, v15
	v_or_b32_e32 v42, 0x80000000, v15
	v_cndmask_b32_e32 v3, v36, v35, vcc
	v_not_b32_e32 v35, v2
	v_or_b32_e32 v36, 0x80000000, v2
	v_cmp_gt_i32_e32 vcc, 0, v2
	v_or_b32_e32 v43, 0x80000000, v12
	v_not_b32_e32 v44, v8
	v_cndmask_b32_e32 v2, v36, v35, vcc
	v_cmp_gt_i32_e32 vcc, 0, v7
	v_or_b32_e32 v45, 0x80000000, v8
	v_or_b32_e32 v92, 0x80000000, v11
	v_cndmask_b32_e32 v7, v38, v37, vcc
	v_not_b32_e32 v37, v6
	v_or_b32_e32 v38, 0x80000000, v6
	v_cmp_gt_i32_e32 vcc, 0, v6
	v_and_or_b32 v0, v0, s77, v134
	v_and_or_b32 v1, v1, s77, v135
	v_cndmask_b32_e32 v6, v38, v37, vcc
	v_not_b32_e32 v38, v4
	v_cmp_gt_i32_e32 vcc, 0, v4
	v_and_or_b32 v3, v3, s77, v137
	v_and_or_b32 v2, v2, s77, v136
	v_cndmask_b32_e32 v4, v39, v38, vcc
	v_not_b32_e32 v38, v5
	v_or_b32_e32 v39, 0x80000000, v5
	v_cmp_gt_i32_e32 vcc, 0, v5
	v_and_or_b32 v7, v7, s77, v141
	v_and_or_b32 v6, v6, s77, v140
	v_cndmask_b32_e32 v5, v39, v38, vcc
	v_cmp_gt_i32_e32 vcc, 0, v15
	v_and_or_b32 v4, v4, s77, v138
	v_and_or_b32 v5, v5, s77, v139
	v_cndmask_b32_e32 v15, v42, v41, vcc
	v_not_b32_e32 v41, v14
	v_or_b32_e32 v42, 0x80000000, v14
	v_cmp_gt_i32_e32 vcc, 0, v14
	v_and_or_b32 v15, v15, s77, v149
	v_max_u32_e32 v34, v0, v1
	v_cndmask_b32_e32 v14, v42, v41, vcc
	v_not_b32_e32 v42, v12
	v_cmp_gt_i32_e32 vcc, 0, v12
	v_and_or_b32 v14, v14, s77, v148
	v_min_u32_e32 v35, v3, v2
	v_cndmask_b32_e32 v12, v43, v42, vcc
	v_not_b32_e32 v42, v13
	v_or_b32_e32 v43, 0x80000000, v13
	v_cmp_gt_i32_e32 vcc, 0, v13
	v_and_or_b32 v12, v12, s77, v146
	v_min_u32_e32 v0, v0, v1
	v_cndmask_b32_e32 v13, v43, v42, vcc
	v_cmp_gt_i32_e32 vcc, 0, v8
	v_and_or_b32 v13, v13, s77, v147
	v_max_u32_e32 v1, v3, v2
	v_cndmask_b32_e32 v8, v45, v44, vcc
	v_not_b32_e32 v44, v9
	v_or_b32_e32 v45, 0x80000000, v9
	v_cmp_gt_i32_e32 vcc, 0, v9
	v_and_or_b32 v8, v8, s77, v142
	v_max_u32_e32 v37, v7, v6
	v_cndmask_b32_e32 v9, v45, v44, vcc
	v_not_b32_e32 v45, v11
	v_cmp_gt_i32_e32 vcc, 0, v11
	v_and_or_b32 v9, v9, s77, v143
	v_min_u32_e32 v38, v4, v5
	v_cndmask_b32_e32 v11, v92, v45, vcc
	v_not_b32_e32 v45, v10
	v_or_b32_e32 v92, 0x80000000, v10
	v_cmp_gt_i32_e32 vcc, 0, v10
	v_and_or_b32 v11, v11, s77, v145
	v_min_u32_e32 v6, v7, v6
	v_cndmask_b32_e32 v10, v92, v45, vcc
	v_and_or_b32 v10, v10, s77, v144
	v_max_u32_e32 v4, v4, v5
	v_max_u32_e32 v41, v15, v14
	v_min_u32_e32 v42, v12, v13
	v_min_u32_e32 v14, v15, v14
	v_max_u32_e32 v12, v12, v13
	v_max_u32_e32 v44, v8, v9
	v_min_u32_e32 v45, v11, v10
	v_min_u32_e32 v8, v8, v9
	v_max_u32_e32 v9, v11, v10
	v_max_u32_e32 v36, v34, v35
	v_max_u32_e32 v2, v0, v1
	v_min_u32_e32 v39, v37, v38
	v_min_u32_e32 v5, v6, v4
	v_min_u32_e32 v34, v34, v35
	v_min_u32_e32 v0, v0, v1
	v_max_u32_e32 v35, v37, v38
	v_max_u32_e32 v4, v6, v4
	v_max_u32_e32 v43, v41, v42
	v_max_u32_e32 v13, v14, v12
	v_min_u32_e32 v92, v44, v45
	v_min_u32_e32 v10, v8, v9
	v_min_u32_e32 v41, v41, v42
	v_min_u32_e32 v12, v14, v12
	v_max_u32_e32 v42, v44, v45
	v_max_u32_e32 v8, v8, v9
	v_max_u32_e32 v3, v36, v2
	v_min_u32_e32 v7, v39, v5
	v_max_u32_e32 v1, v34, v0
	v_min_u32_e32 v6, v35, v4
	v_min_u32_e32 v2, v36, v2
	v_max_u32_e32 v5, v39, v5
	v_min_u32_e32 v0, v34, v0
	v_max_u32_e32 v4, v35, v4
	v_max_u32_e32 v15, v43, v13
	v_min_u32_e32 v11, v92, v10
	v_max_u32_e32 v14, v41, v12
	v_min_u32_e32 v9, v42, v8
	v_min_u32_e32 v13, v43, v13
	v_max_u32_e32 v10, v92, v10
	v_min_u32_e32 v12, v41, v12
	v_max_u32_e32 v8, v42, v8
	v_max_u32_e32 v40, v3, v7
	v_max_u32_e32 v37, v1, v6
	v_max_u32_e32 v36, v2, v5
	v_max_u32_e32 v34, v0, v4
	v_min_u32_e32 v93, v15, v11
	v_min_u32_e32 v44, v14, v9
	v_min_u32_e32 v43, v13, v10
	v_min_u32_e32 v41, v12, v8
	v_min_u32_e32 v3, v3, v7
	v_min_u32_e32 v1, v1, v6
	v_min_u32_e32 v2, v2, v5
	v_min_u32_e32 v0, v0, v4
	v_max_u32_e32 v5, v15, v11
	v_max_u32_e32 v9, v14, v9
	v_max_u32_e32 v10, v13, v10
	v_max_u32_e32 v8, v12, v8
	v_max_u32_e32 v38, v40, v37
	v_max_u32_e32 v35, v36, v34
	v_min_u32_e32 v45, v93, v44
	v_min_u32_e32 v42, v43, v41
	v_max_u32_e32 v6, v3, v1
	v_max_u32_e32 v4, v2, v0
	v_min_u32_e32 v11, v5, v9
	v_min_u32_e32 v12, v10, v8
	v_min_u32_e32 v37, v40, v37
	v_min_u32_e32 v34, v36, v34
	v_max_u32_e32 v40, v93, v44
	v_max_u32_e32 v41, v43, v41
	v_min_u32_e32 v1, v3, v1
	v_min_u32_e32 v0, v2, v0
	v_max_u32_e32 v2, v5, v9
	v_max_u32_e32 v3, v10, v8
	v_max_u32_e32 v39, v38, v35
	v_min_u32_e32 v92, v45, v42
	v_max_u32_e32 v7, v6, v4
	v_min_u32_e32 v13, v11, v12
	v_min_u32_e32 v43, v40, v41
	v_min_u32_e32 v38, v38, v35
	v_max_u32_e32 v42, v45, v42
	v_min_u32_e32 v6, v6, v4
	v_max_u32_e32 v11, v11, v12
	v_min_u32_e32 v45, v37, v34
	v_max_u32_e32 v40, v40, v41
	v_min_u32_e32 v41, v1, v0
	v_max_u32_e32 v95, v2, v3
	v_max_u32_e32 v36, v37, v34
	v_max_u32_e32 v93, v1, v0
	v_min_u32_e32 v8, v2, v3
	v_min_u32_e32 v35, v38, v42
	v_min_u32_e32 v4, v6, v11
	v_min_u32_e32 v34, v45, v40
	v_min_u32_e32 v0, v41, v95
	v_min_u32_e32 v94, v39, v92
	v_min_u32_e32 v14, v7, v13
	v_min_u32_e32 v44, v36, v43
	v_min_u32_e32 v5, v93, v8
	v_min_u32_e32 v12, v35, v4
	v_min_u32_e32 v1, v34, v0
	v_min_u32_e32 v9, v44, v5
	v_min_u32_e32 v96, v12, v1
	v_max_u32_e32 v12, v12, v1
	v_max_u32_e32 v1, v94, v14
	v_max_u32_e32 v2, v44, v5
	v_max_u32_e32 v3, v35, v4
	v_max_u32_e32 v0, v34, v0
	v_lshl_add_u64 v[4:5], v[84:85], 0, v[80:81]
	v_min_u32_e32 v15, v94, v14
	v_min_u32_e32 v14, v1, v2
	v_min_u32_e32 v94, v3, v0
	v_max_u32_e32 v99, v1, v2
	v_max_u32_e32 v200, v3, v0
	global_load_dwordx4 v[0:3], v[4:5], off
	v_max_u32_e32 v43, v36, v43
	global_load_dwordx4 v[34:37], v[4:5], off offset:32
	v_max_u32_e32 v44, v39, v92
	v_max_u32_e32 v8, v93, v8
	v_max_u32_e32 v93, v38, v42
	v_max_u32_e32 v201, v45, v40
	v_max_u32_e32 v95, v41, v95
	global_load_dwordx4 v[38:41], v[4:5], off offset:64
	v_max_u32_e32 v6, v6, v11
	v_max_u32_e32 v7, v7, v13
	v_min_u32_e32 v11, v93, v6
	v_min_u32_e32 v42, v201, v95
	v_min_u32_e32 v13, v44, v7
	v_min_u32_e32 v85, v43, v8
	v_min_u32_e32 v202, v11, v42
	v_max_u32_e32 v11, v11, v42
	v_max_u32_e32 v7, v44, v7
	v_max_u32_e32 v8, v43, v8
	global_load_dwordx4 v[42:45], v[4:5], off offset:96
	v_max_u32_e32 v5, v93, v6
	v_max_u32_e32 v6, v201, v95
	v_min_u32_e32 v10, v15, v9
	v_max_u32_e32 v9, v15, v9
	v_min_u32_e32 v92, v13, v85
	v_max_u32_e32 v13, v13, v85
	v_min_u32_e32 v4, v7, v8
	v_min_u32_e32 v93, v5, v6
	v_max_u32_e32 v7, v7, v8
	v_max_u32_e32 v5, v5, v6
	v_min_u32_e32 v97, v10, v96
	v_min_u32_e32 v15, v9, v12
	v_min_u32_e32 v98, v14, v94
	v_min_u32_e32 v84, v99, v200
	v_min_u32_e32 v203, v92, v202
	v_min_u32_e32 v85, v13, v11
	v_min_u32_e32 v95, v4, v93
	v_min_u32_e32 v6, v7, v5
	v_max3_u32 v8, v61, v62, v97
	v_max3_u32 v10, v60, v10, v96
	v_max3_u32 v15, v47, v52, v15
	v_max3_u32 v9, v63, v9, v12
	v_max3_u32 v12, v53, v51, v98
	v_max3_u32 v14, v86, v14, v94
	v_max3_u32 v46, v49, v46, v84
	v_max3_u32 v48, v48, v57, v203
	v_max3_u32 v49, v88, v92, v202
	v_max3_u32 v50, v50, v55, v85
	v_max3_u32 v11, v89, v13, v11
	v_max3_u32 v13, v59, v58, v95
	v_max3_u32 v4, v90, v4, v93
	v_max3_u32 v6, v54, v56, v6
	v_max3_u32 v47, v87, v99, v200
	v_max3_u32 v5, v91, v7, v5
	v_max_u32_e32 v7, v8, v48
	v_min_u32_e32 v8, v8, v48
	v_max_u32_e32 v48, v10, v49
	v_min_u32_e32 v10, v10, v49
	v_max_u32_e32 v49, v15, v50
	v_min_u32_e32 v15, v15, v50
	v_max_u32_e32 v50, v9, v11
	v_min_u32_e32 v9, v9, v11
	v_max_u32_e32 v11, v12, v13
	v_min_u32_e32 v12, v12, v13
	v_max_u32_e32 v13, v14, v4
	v_min_u32_e32 v4, v14, v4
	v_max_u32_e32 v14, v46, v6
	v_min_u32_e32 v6, v46, v6
	v_max_u32_e32 v46, v47, v5
	v_min_u32_e32 v5, v47, v5
	v_max_u32_e32 v47, v7, v11
	v_min_u32_e32 v51, v7, v11
	v_max_u32_e32 v7, v49, v14
	v_max_u32_e32 v52, v48, v13
	v_min_u32_e32 v48, v48, v13
	v_min_u32_e32 v49, v49, v14
	v_max_u32_e32 v53, v50, v46
	v_min_u32_e32 v46, v50, v46
	v_max_u32_e32 v50, v8, v12
	v_min_u32_e32 v54, v8, v12
	v_max_u32_e32 v55, v10, v4
	v_min_u32_e32 v56, v10, v4
	v_max_u32_e32 v57, v15, v6
	v_min_u32_e32 v58, v15, v6
	v_max_u32_e32 v59, v9, v5
	v_min_u32_e32 v60, v9, v5
	v_max_u32_e32 v61, v47, v7
	v_min_u32_e32 v47, v47, v7
	s_waitcnt vmcnt(3)
	v_mfma_f32_32x32x16_bf16 v[0:15], v[0:3], v[28:31], 0
	v_max_u32_e32 v29, v51, v49
	v_min_u32_e32 v30, v51, v49
	v_max_u32_e32 v31, v48, v46
	v_min_u32_e32 v46, v48, v46
	v_max_u32_e32 v48, v50, v57
	v_min_u32_e32 v49, v50, v57
	v_max_u32_e32 v62, v52, v53
	s_waitcnt vmcnt(2)
	v_mfma_f32_32x32x16_bf16 v[0:15], v[34:37], v[20:23], v[0:15]
	v_min_u32_e32 v28, v52, v53
	v_max_u32_e32 v22, v54, v58
	v_min_u32_e32 v23, v54, v58
	v_max_u32_e32 v20, v55, v59
	v_min_u32_e32 v21, v55, v59
	v_max_u32_e32 v34, v56, v60
	v_min_u32_e32 v36, v56, v60
	s_waitcnt vmcnt(1)
	v_mfma_f32_32x32x16_bf16 v[0:15], v[38:41], v[24:27], v[0:15]
	v_min_u32_e32 v27, v48, v20
	v_min_u32_e32 v25, v29, v31
	v_min_u32_e32 v39, v22, v34
	v_min_u32_e32 v24, v47, v28
	v_min_u32_e32 v38, v49, v21
	v_min_u32_e32 v37, v61, v62
	v_min_u32_e32 v26, v30, v46
	s_waitcnt vmcnt(0)
	v_mfma_f32_32x32x16_bf16 v[0:15], v[42:45], v[16:19], v[0:15]
	v_min_u32_e32 v40, v23, v36
	s_nop 10
	v_not_b32_e32 v16, v0
	v_or_b32_e32 v17, 0x80000000, v0
	v_cmp_gt_i32_e32 vcc, 0, v0
	v_or_b32_e32 v18, 0x80000000, v3
	v_not_b32_e32 v19, v7
	v_cndmask_b32_e32 v0, v17, v16, vcc
	v_not_b32_e32 v16, v1
	v_or_b32_e32 v17, 0x80000000, v1
	v_cmp_gt_i32_e32 vcc, 0, v1
	v_or_b32_e32 v35, 0x80000000, v7
	v_or_b32_e32 v41, 0x80000000, v4
	v_cndmask_b32_e32 v1, v17, v16, vcc
	v_not_b32_e32 v17, v3
	v_cmp_gt_i32_e32 vcc, 0, v3
	v_not_b32_e32 v43, v15
	v_or_b32_e32 v44, 0x80000000, v15
	v_cndmask_b32_e32 v3, v18, v17, vcc
	v_not_b32_e32 v17, v2
	v_or_b32_e32 v18, 0x80000000, v2
	v_cmp_gt_i32_e32 vcc, 0, v2
	v_or_b32_e32 v45, 0x80000000, v12
	v_not_b32_e32 v50, v8
	v_cndmask_b32_e32 v2, v18, v17, vcc
	v_cmp_gt_i32_e32 vcc, 0, v7
	v_or_b32_e32 v51, 0x80000000, v8
	v_or_b32_e32 v52, 0x80000000, v11
	v_cndmask_b32_e32 v7, v35, v19, vcc
	v_not_b32_e32 v19, v6
	v_or_b32_e32 v35, 0x80000000, v6
	v_cmp_gt_i32_e32 vcc, 0, v6
	v_and_or_b32 v0, v0, s77, v150
	v_and_or_b32 v1, v1, s77, v151
	v_cndmask_b32_e32 v6, v35, v19, vcc
	v_not_b32_e32 v35, v4
	v_cmp_gt_i32_e32 vcc, 0, v4
	v_and_or_b32 v3, v3, s77, v153
	v_and_or_b32 v2, v2, s77, v152
	v_cndmask_b32_e32 v4, v41, v35, vcc
	v_not_b32_e32 v35, v5
	v_or_b32_e32 v41, 0x80000000, v5
	v_cmp_gt_i32_e32 vcc, 0, v5
	v_and_or_b32 v7, v7, s77, v158
	v_and_or_b32 v6, v6, s77, v157
	v_cndmask_b32_e32 v5, v41, v35, vcc
	v_cmp_gt_i32_e32 vcc, 0, v15
	v_and_or_b32 v4, v4, s77, v155
	v_and_or_b32 v5, v5, s77, v156
	v_cndmask_b32_e32 v15, v44, v43, vcc
	v_not_b32_e32 v43, v14
	v_or_b32_e32 v44, 0x80000000, v14
	v_cmp_gt_i32_e32 vcc, 0, v14
	v_and_or_b32 v15, v15, s77, v166
	v_max_u32_e32 v16, v0, v1
	v_cndmask_b32_e32 v14, v44, v43, vcc
	v_not_b32_e32 v44, v12
	v_cmp_gt_i32_e32 vcc, 0, v12
	v_and_or_b32 v14, v14, s77, v165
	v_min_u32_e32 v17, v3, v2
	v_cndmask_b32_e32 v12, v45, v44, vcc
	v_not_b32_e32 v44, v13
	v_or_b32_e32 v45, 0x80000000, v13
	v_cmp_gt_i32_e32 vcc, 0, v13
	v_and_or_b32 v12, v12, s77, v163
	v_min_u32_e32 v0, v0, v1
	v_cndmask_b32_e32 v13, v45, v44, vcc
	v_cmp_gt_i32_e32 vcc, 0, v8
	v_and_or_b32 v13, v13, s77, v164
	v_max_u32_e32 v1, v3, v2
	v_cndmask_b32_e32 v8, v51, v50, vcc
	v_not_b32_e32 v50, v9
	v_or_b32_e32 v51, 0x80000000, v9
	v_cmp_gt_i32_e32 vcc, 0, v9
	v_and_or_b32 v8, v8, s77, v159
	v_max_u32_e32 v19, v7, v6
	v_cndmask_b32_e32 v9, v51, v50, vcc
	v_not_b32_e32 v51, v11
	v_cmp_gt_i32_e32 vcc, 0, v11
	v_and_or_b32 v9, v9, s77, v160
	v_min_u32_e32 v35, v4, v5
	v_cndmask_b32_e32 v11, v52, v51, vcc
	v_not_b32_e32 v51, v10
	v_or_b32_e32 v52, 0x80000000, v10
	v_cmp_gt_i32_e32 vcc, 0, v10
	v_and_or_b32 v11, v11, s77, v162
	v_min_u32_e32 v6, v7, v6
	v_cndmask_b32_e32 v10, v52, v51, vcc
	v_and_or_b32 v10, v10, s77, v161
	v_max_u32_e32 v4, v4, v5
	v_max_u32_e32 v43, v15, v14
	v_min_u32_e32 v44, v12, v13
	v_min_u32_e32 v14, v15, v14
	v_max_u32_e32 v12, v12, v13
	v_max_u32_e32 v50, v8, v9
	v_min_u32_e32 v51, v11, v10
	v_min_u32_e32 v8, v8, v9
	v_max_u32_e32 v9, v11, v10
	v_max_u32_e32 v18, v16, v17
	v_max_u32_e32 v2, v0, v1
	v_min_u32_e32 v41, v19, v35
	v_min_u32_e32 v5, v6, v4
	v_min_u32_e32 v16, v16, v17
	v_min_u32_e32 v0, v0, v1
	v_max_u32_e32 v17, v19, v35
	v_max_u32_e32 v4, v6, v4
	v_max_u32_e32 v45, v43, v44
	v_max_u32_e32 v13, v14, v12
	v_min_u32_e32 v52, v50, v51
	v_min_u32_e32 v10, v8, v9
	v_min_u32_e32 v43, v43, v44
	v_min_u32_e32 v12, v14, v12
	v_max_u32_e32 v44, v50, v51
	v_max_u32_e32 v8, v8, v9
	v_max_u32_e32 v3, v18, v2
	v_min_u32_e32 v7, v41, v5
	v_max_u32_e32 v1, v16, v0
	v_min_u32_e32 v6, v17, v4
	v_min_u32_e32 v2, v18, v2
	v_max_u32_e32 v5, v41, v5
	v_min_u32_e32 v0, v16, v0
	v_max_u32_e32 v4, v17, v4
	v_max_u32_e32 v15, v45, v13
	v_min_u32_e32 v11, v52, v10
	v_max_u32_e32 v14, v43, v12
	v_min_u32_e32 v9, v44, v8
	v_min_u32_e32 v13, v45, v13
	v_max_u32_e32 v10, v52, v10
	v_min_u32_e32 v12, v43, v12
	v_max_u32_e32 v8, v44, v8
	v_max_u32_e32 v42, v3, v7
	v_max_u32_e32 v19, v1, v6
	v_max_u32_e32 v18, v2, v5
	v_max_u32_e32 v16, v0, v4
	v_min_u32_e32 v53, v15, v11
	v_min_u32_e32 v50, v14, v9
	v_min_u32_e32 v45, v13, v10
	v_min_u32_e32 v43, v12, v8
	v_min_u32_e32 v3, v3, v7
	v_min_u32_e32 v1, v1, v6
	v_min_u32_e32 v2, v2, v5
	v_min_u32_e32 v0, v0, v4
	v_max_u32_e32 v7, v15, v11
	v_max_u32_e32 v9, v14, v9
	v_max_u32_e32 v10, v13, v10
	v_max_u32_e32 v8, v12, v8
	v_max_u32_e32 v35, v42, v19
	v_max_u32_e32 v17, v18, v16
	v_min_u32_e32 v51, v53, v50
	v_min_u32_e32 v44, v45, v43
	v_max_u32_e32 v6, v3, v1
	v_max_u32_e32 v4, v2, v0
	v_min_u32_e32 v11, v7, v9
	v_min_u32_e32 v12, v10, v8
	v_min_u32_e32 v19, v42, v19
	v_min_u32_e32 v16, v18, v16
	v_max_u32_e32 v42, v53, v50
	v_max_u32_e32 v43, v45, v43
	v_min_u32_e32 v1, v3, v1
	v_min_u32_e32 v0, v2, v0
	v_max_u32_e32 v3, v7, v9
	v_max_u32_e32 v7, v10, v8
	v_max_u32_e32 v41, v35, v17
	v_min_u32_e32 v52, v51, v44
	v_max_u32_e32 v5, v6, v4
	v_min_u32_e32 v13, v11, v12
	v_max_u32_e32 v18, v19, v16
	v_min_u32_e32 v45, v42, v43
	v_max_u32_e32 v2, v1, v0
	v_min_u32_e32 v8, v3, v7
	v_min_u32_e32 v17, v35, v17
	v_max_u32_e32 v35, v51, v44
	v_min_u32_e32 v4, v6, v4
	v_max_u32_e32 v6, v11, v12
	v_min_u32_e32 v16, v19, v16
	v_max_u32_e32 v19, v42, v43
	v_min_u32_e32 v0, v1, v0
	v_max_u32_e32 v1, v3, v7
	v_min_u32_e32 v54, v41, v52
	v_min_u32_e32 v14, v5, v13
	v_min_u32_e32 v50, v18, v45
	v_min_u32_e32 v9, v2, v8
	v_min_u32_e32 v44, v17, v35
	v_min_u32_e32 v11, v4, v6
	v_min_u32_e32 v42, v16, v19
	v_min_u32_e32 v3, v0, v1
	v_max_u32_e32 v41, v41, v52
	v_max_u32_e32 v5, v5, v13
	v_max_u32_e32 v18, v18, v45
	v_max_u32_e32 v2, v2, v8
	v_max_u32_e32 v17, v17, v35
	v_max_u32_e32 v4, v4, v6
	v_max_u32_e32 v16, v16, v19
	v_max_u32_e32 v0, v0, v1
	v_min_u32_e32 v13, v41, v5
	v_min_u32_e32 v8, v18, v2
	v_min_u32_e32 v6, v17, v4
	v_min_u32_e32 v19, v16, v0
	v_min_u32_e32 v15, v54, v14
	v_min_u32_e32 v10, v50, v9
	v_min_u32_e32 v12, v44, v11
	v_min_u32_e32 v7, v42, v3
	v_min_u32_e32 v45, v13, v8
	v_min_u32_e32 v52, v6, v19
	v_max_u32_e32 v14, v54, v14
	v_max_u32_e32 v9, v50, v9
	v_max_u32_e32 v11, v44, v11
	v_max_u32_e32 v42, v42, v3
	v_min_u32_e32 v1, v45, v52
	v_min_u32_e32 v50, v14, v9
	v_min_u32_e32 v44, v11, v42
	v_max3_u32 v20, v48, v20, v1
	v_min_u32_e32 v1, v50, v44
	v_max3_u32 v29, v29, v31, v1
	v_max_u32_e32 v31, v41, v5
	v_max_u32_e32 v41, v18, v2
	v_max_u32_e32 v55, v17, v4
	v_max_u32_e32 v56, v16, v0
	v_min_u32_e32 v54, v31, v41
	v_min_u32_e32 v57, v55, v56
	v_min_u32_e32 v0, v54, v57
	v_min_u32_e32 v53, v15, v10
	v_min_u32_e32 v43, v12, v7
	v_max3_u32 v22, v22, v34, v0
	v_max_u32_e32 v10, v15, v10
	v_max_u32_e32 v7, v12, v7
	v_lshl_add_u64 v[34:35], v[72:73], 0, s[28:29]
	v_min_u32_e32 v0, v10, v7
	v_lshl_add_u64 v[4:5], v[34:35], 0, v[74:75]
	v_max3_u32 v12, v47, v28, v0
	global_load_dwordx4 v[0:3], v[4:5], off
	v_max_u32_e32 v6, v6, v19
	global_load_dwordx4 v[16:19], v[4:5], off offset:32
	global_load_dwordx4 v[86:89], v[4:5], off offset:64
	global_load_dwordx4 v[90:93], v[4:5], off offset:96
	v_max_u32_e32 v8, v13, v8
	v_min_u32_e32 v13, v8, v6
	v_max_u32_e32 v9, v14, v9
	v_max_u32_e32 v11, v11, v42
	v_max3_u32 v13, v49, v21, v13
	v_min_u32_e32 v14, v9, v11
	v_max_u32_e32 v21, v31, v41
	v_max_u32_e32 v28, v55, v56
	v_min_u32_e32 v51, v53, v43
	v_max3_u32 v14, v30, v46, v14
	v_min_u32_e32 v30, v21, v28
	v_max3_u32 v51, v61, v62, v51
	v_max3_u32 v23, v23, v36, v30
	v_max3_u32 v37, v37, v53, v43
	v_max3_u32 v27, v27, v45, v52
	v_max3_u32 v25, v25, v50, v44
	v_max3_u32 v39, v39, v54, v57
	v_max3_u32 v7, v24, v10, v7
	v_max3_u32 v6, v38, v8, v6
	v_max3_u32 v9, v26, v9, v11
	v_max3_u32 v10, v40, v21, v28
	v_min_u32_e32 v48, v51, v20
	v_min_u32_e32 v58, v29, v22
	v_min_u32_e32 v15, v12, v13
	v_min_u32_e32 v4, v25, v39
	v_min_u32_e32 v8, v7, v6
	v_max_u32_e32 v20, v51, v20
	v_max_u32_e32 v22, v29, v22
	v_max_u32_e32 v12, v12, v13
	v_max_u32_e32 v13, v14, v23
	v_max_u32_e32 v26, v37, v27
	v_max_u32_e32 v25, v25, v39
	v_max_u32_e32 v6, v7, v6
	v_max_u32_e32 v7, v9, v10
	v_min_u32_e32 v30, v14, v23
	v_min_u32_e32 v46, v37, v27
	v_min_u32_e32 v11, v9, v10
	v_max_u32_e32 v24, v20, v22
	v_max_u32_e32 v14, v12, v13
	v_max_u32_e32 v27, v26, v25
	v_max_u32_e32 v9, v6, v7
	v_max_u32_e32 v23, v24, v14
	v_max_u32_e32 v10, v27, v9
	v_max_u32_e32 v42, v23, v10
	v_min_u32_e32 v38, v23, v10
	v_min_u32_e32 v10, v24, v14
	v_min_u32_e32 v9, v27, v9
	v_max_u32_e32 v41, v10, v9
	v_min_u32_e32 v37, v10, v9
	v_min_u32_e32 v9, v20, v22
	v_min_u32_e32 v10, v12, v13
	v_min_u32_e32 v13, v26, v25
	v_min_u32_e32 v6, v6, v7
	ds_read_b128 v[24:27], v199 offset:128
	v_max_u32_e32 v12, v9, v10
	v_max_u32_e32 v7, v13, v6
	v_max_u32_e32 v45, v12, v7
	v_min_u32_e32 v40, v12, v7
	v_min_u32_e32 v7, v9, v10
	v_min_u32_e32 v6, v13, v6
	v_min_u32_e32 v5, v46, v4
	v_min_u32_e32 v21, v8, v11
	v_max_u32_e32 v43, v7, v6
	v_min_u32_e32 v39, v7, v6
	v_max_u32_e32 v6, v48, v58
	v_max_u32_e32 v7, v15, v30
	v_max_u32_e32 v4, v46, v4
	v_max_u32_e32 v8, v8, v11
	v_max_u32_e32 v9, v6, v7
	v_max_u32_e32 v10, v4, v8
	v_min_u32_e32 v6, v6, v7
	v_min_u32_e32 v4, v4, v8
	v_min_u32_e32 v31, v15, v30
	v_min_u32_e32 v28, v5, v21
	v_max_u32_e32 v52, v9, v10
	v_min_u32_e32 v46, v9, v10
	v_max_u32_e32 v49, v6, v4
	v_min_u32_e32 v44, v6, v4
	v_max_u32_e32 v30, v5, v21
	ds_read_b128 v[20:23], v199 offset:160
	s_waitcnt vmcnt(3) lgkmcnt(1)
	v_mfma_f32_32x32x16_bf16 v[0:15], v[0:3], v[24:27], 0
	v_min_u32_e32 v59, v48, v58
	v_min_u32_e32 v47, v59, v31
	v_max_u32_e32 v29, v59, v31
	v_min_u32_e32 v36, v47, v28
	v_max_u32_e32 v57, v29, v30
	v_min_u32_e32 v48, v29, v30
	v_max_u32_e32 v54, v47, v28
	s_waitcnt vmcnt(2) lgkmcnt(0)
	v_mfma_f32_32x32x16_bf16 v[0:15], v[16:19], v[20:23], v[0:15]
	ds_read_b128 v[28:31], v199 offset:192
	ds_read_b128 v[16:19], v199 offset:224
	ds_bpermute_b32 v47, v33, v42
	ds_bpermute_b32 v55, v33, v38
	ds_bpermute_b32 v51, v33, v41
	ds_bpermute_b32 v61, v33, v37
	ds_bpermute_b32 v50, v33, v45
	s_waitcnt vmcnt(1) lgkmcnt(6)
	v_mfma_f32_32x32x16_bf16 v[0:15], v[86:89], v[28:31], v[0:15]
	ds_bpermute_b32 v60, v33, v40
	ds_bpermute_b32 v56, v33, v43
	ds_bpermute_b32 v84, v33, v39
	ds_bpermute_b32 v53, v33, v52
	ds_bpermute_b32 v62, v33, v46
	ds_bpermute_b32 v59, v33, v49
	ds_bpermute_b32 v86, v33, v44
	s_waitcnt vmcnt(0) lgkmcnt(12)
	v_mfma_f32_32x32x16_bf16 v[0:15], v[90:93], v[16:19], v[0:15]
	ds_bpermute_b32 v58, v33, v57
	ds_bpermute_b32 v85, v33, v48
	ds_bpermute_b32 v63, v33, v54
	ds_bpermute_b32 v87, v33, v36
	s_waitcnt lgkmcnt(9)
	v_max_u32_e32 v46, v46, v56
	s_waitcnt lgkmcnt(5)
	v_max_u32_e32 v40, v40, v59
	s_waitcnt lgkmcnt(3)
	v_max_u32_e32 v37, v37, v58
	s_nop 1
	v_not_b32_e32 v88, v0
	v_or_b32_e32 v89, 0x80000000, v0
	v_cmp_gt_i32_e32 vcc, 0, v0
	v_or_b32_e32 v90, 0x80000000, v3
	v_or_b32_e32 v91, 0x80000000, v7
	v_cndmask_b32_e32 v0, v89, v88, vcc
	v_not_b32_e32 v88, v1
	v_or_b32_e32 v89, 0x80000000, v1
	v_cmp_gt_i32_e32 vcc, 0, v1
	v_and_or_b32 v0, v0, s77, v102
	v_or_b32_e32 v93, 0x80000000, v4
	v_cndmask_b32_e32 v1, v89, v88, vcc
	v_not_b32_e32 v89, v3
	v_cmp_gt_i32_e32 vcc, 0, v3
	v_and_or_b32 v1, v1, s77, v103
	v_max_u32_e32 v88, v0, v1
	v_cndmask_b32_e32 v3, v90, v89, vcc
	v_not_b32_e32 v89, v2
	v_or_b32_e32 v90, 0x80000000, v2
	v_cmp_gt_i32_e32 vcc, 0, v2
	v_and_or_b32 v3, v3, s77, v105
	v_min_u32_e32 v0, v0, v1
	v_cndmask_b32_e32 v2, v90, v89, vcc
	v_and_or_b32 v2, v2, s77, v104
	v_min_u32_e32 v89, v3, v2
	v_max_u32_e32 v1, v3, v2
	v_not_b32_e32 v3, v7
	v_cmp_gt_i32_e32 vcc, 0, v7
	v_not_b32_e32 v7, v6
	v_max_u32_e32 v90, v88, v89
	v_cndmask_b32_e32 v3, v91, v3, vcc
	v_or_b32_e32 v91, 0x80000000, v6
	v_cmp_gt_i32_e32 vcc, 0, v6
	v_and_or_b32 v3, v3, s77, v109
	v_max_u32_e32 v2, v0, v1
	v_cndmask_b32_e32 v6, v91, v7, vcc
	v_not_b32_e32 v91, v4
	v_cmp_gt_i32_e32 vcc, 0, v4
	v_and_or_b32 v6, v6, s77, v108
	v_max_u32_e32 v7, v3, v6
	v_cndmask_b32_e32 v4, v93, v91, vcc
	v_not_b32_e32 v91, v5
	v_or_b32_e32 v93, 0x80000000, v5
	v_cmp_gt_i32_e32 vcc, 0, v5
	v_and_or_b32 v4, v4, s77, v106
	v_min_u32_e32 v3, v3, v6
	v_cndmask_b32_e32 v5, v93, v91, vcc
	v_and_or_b32 v5, v5, s77, v107
	v_min_u32_e32 v91, v4, v5
	v_max_u32_e32 v4, v4, v5
	v_min_u32_e32 v5, v3, v4
	v_min_u32_e32 v88, v88, v89
	v_min_u32_e32 v0, v0, v1
	v_max_u32_e32 v1, v7, v91
	v_max_u32_e32 v3, v3, v4
	v_min_u32_e32 v93, v7, v91
	v_max_u32_e32 v94, v88, v0
	v_min_u32_e32 v7, v1, v3
	v_min_u32_e32 v98, v88, v0
	v_max_u32_e32 v99, v1, v3
	v_not_b32_e32 v0, v15
	v_or_b32_e32 v1, 0x80000000, v15
	v_cmp_gt_i32_e32 vcc, 0, v15
	v_max_u32_e32 v92, v90, v2
	v_min_u32_e32 v96, v90, v2
	v_cndmask_b32_e32 v0, v1, v0, vcc
	v_not_b32_e32 v1, v14
	v_or_b32_e32 v2, 0x80000000, v14
	v_cmp_gt_i32_e32 vcc, 0, v14
	v_not_b32_e32 v3, v12
	v_or_b32_e32 v4, 0x80000000, v12
	v_cndmask_b32_e32 v1, v2, v1, vcc
	v_cmp_gt_i32_e32 vcc, 0, v12
	v_min_u32_e32 v6, v93, v5
	v_max_u32_e32 v97, v93, v5
	v_cndmask_b32_e32 v3, v4, v3, vcc
	v_not_b32_e32 v4, v13
	v_or_b32_e32 v5, 0x80000000, v13
	v_cmp_gt_i32_e32 vcc, 0, v13
	v_and_or_b32 v0, v0, s77, v117
	v_and_or_b32 v1, v1, s77, v116
	v_cndmask_b32_e32 v4, v5, v4, vcc
	v_and_or_b32 v3, v3, s77, v114
	v_and_or_b32 v4, v4, s77, v115
	v_max_u32_e32 v2, v0, v1
	v_min_u32_e32 v5, v3, v4
	v_min_u32_e32 v0, v0, v1
	v_max_u32_e32 v1, v3, v4
	v_not_b32_e32 v3, v8
	v_or_b32_e32 v4, 0x80000000, v8
	v_cmp_gt_i32_e32 vcc, 0, v8
	v_or_b32_e32 v8, 0x80000000, v9
	v_or_b32_e32 v15, 0x80000000, v11
	v_cndmask_b32_e32 v3, v4, v3, vcc
	v_not_b32_e32 v4, v9
	v_cmp_gt_i32_e32 vcc, 0, v9
	v_not_b32_e32 v9, v11
	v_and_or_b32 v3, v3, s77, v110
	v_cndmask_b32_e32 v4, v8, v4, vcc
	v_cmp_gt_i32_e32 vcc, 0, v11
	v_not_b32_e32 v11, v10
	v_and_or_b32 v4, v4, s77, v111
	v_cndmask_b32_e32 v9, v15, v9, vcc
	v_or_b32_e32 v15, 0x80000000, v10
	v_cmp_gt_i32_e32 vcc, 0, v10
	v_and_or_b32 v9, v9, s77, v113
	v_max_u32_e32 v8, v3, v4
	v_cndmask_b32_e32 v10, v15, v11, vcc
	v_and_or_b32 v10, v10, s77, v112
	v_min_u32_e32 v11, v9, v10
	v_min_u32_e32 v3, v3, v4
	v_max_u32_e32 v4, v9, v10
	v_max_u32_e32 v12, v2, v5
	v_min_u32_e32 v15, v8, v11
	v_min_u32_e32 v9, v3, v4
	v_min_u32_e32 v88, v2, v5
	v_max_u32_e32 v8, v8, v11
	v_max_u32_e32 v11, v3, v4
	v_lshl_add_u64 v[4:5], v[34:35], 0, v[76:77]
	v_max_u32_e32 v13, v0, v1
	v_min_u32_e32 v89, v0, v1
	global_load_dwordx4 v[0:3], v[4:5], off
	v_min_u32_e32 v10, v15, v9
	v_max_u32_e32 v208, v88, v89
	v_max_u32_e32 v9, v15, v9
	v_min_u32_e32 v15, v88, v89
	global_load_dwordx4 v[88:91], v[4:5], off offset:32
	v_max_u32_e32 v200, v92, v6
	v_max_u32_e32 v201, v94, v7
	v_min_u32_e32 v6, v92, v6
	v_min_u32_e32 v7, v94, v7
	global_load_dwordx4 v[92:95], v[4:5], off offset:64
	v_max_u32_e32 v203, v96, v97
	v_max_u32_e32 v204, v98, v99
	v_min_u32_e32 v216, v96, v97
	v_min_u32_e32 v217, v98, v99
	global_load_dwordx4 v[96:99], v[4:5], off offset:96
	v_max_u32_e32 v14, v12, v13
	v_min_u32_e32 v209, v8, v11
	v_min_u32_e32 v12, v12, v13
	v_max_u32_e32 v8, v8, v11
	v_min_u32_e32 v207, v14, v10
	v_min_u32_e32 v210, v208, v209
	v_min_u32_e32 v13, v12, v9
	v_min_u32_e32 v11, v15, v8
	v_max_u32_e32 v10, v14, v10
	v_max_u32_e32 v14, v208, v209
	v_max_u32_e32 v5, v12, v9
	v_max_u32_e32 v8, v15, v8
	v_max_u32_e32 v202, v200, v201
	v_max_u32_e32 v205, v203, v204
	v_min_u32_e32 v211, v207, v210
	v_min_u32_e32 v212, v13, v11
	v_max_u32_e32 v215, v6, v7
	v_max_u32_e32 v218, v216, v217
	v_min_u32_e32 v4, v10, v14
	v_min_u32_e32 v9, v5, v8
	v_min_u32_e32 v200, v200, v201
	v_min_u32_e32 v201, v203, v204
	v_max_u32_e32 v204, v207, v210
	v_max_u32_e32 v11, v13, v11
	v_min_u32_e32 v6, v6, v7
	v_min_u32_e32 v7, v216, v217
	v_max_u32_e32 v10, v10, v14
	v_max_u32_e32 v5, v5, v8
	v_max_u32_e32 v206, v202, v205
	v_min_u32_e32 v213, v211, v212
	v_max_u32_e32 v219, v215, v218
	v_min_u32_e32 v12, v4, v9
	v_max_u32_e32 v203, v200, v201
	v_min_u32_e32 v13, v204, v11
	v_max_u32_e32 v209, v6, v7
	v_min_u32_e32 v8, v10, v5
	v_min_u32_e32 v202, v202, v205
	v_max_u32_e32 v205, v211, v212
	v_min_u32_e32 v212, v215, v218
	v_max_u32_e32 v215, v4, v9
	v_min_u32_e32 v200, v200, v201
	v_max_u32_e32 v201, v204, v11
	v_min_u32_e32 v204, v6, v7
	v_max_u32_e32 v217, v10, v5
	v_min_u32_e32 v214, v206, v213
	v_min_u32_e32 v15, v219, v12
	v_min_u32_e32 v207, v203, v13
	v_min_u32_e32 v14, v209, v8
	v_min_u32_e32 v211, v202, v205
	v_min_u32_e32 v4, v212, v215
	v_min_u32_e32 v11, v200, v201
	v_min_u32_e32 v5, v204, v217
	v_min_u32_e32 v208, v214, v15
	v_min_u32_e32 v210, v207, v14
	v_min_u32_e32 v9, v211, v4
	v_min_u32_e32 v6, v11, v5
	v_min_u32_e32 v216, v208, v210
	v_min_u32_e32 v218, v9, v6
	v_max_u32_e32 v208, v208, v210
	v_max_u32_e32 v210, v9, v6
	v_max_u32_e32 v6, v214, v15
	v_max_u32_e32 v7, v207, v14
	v_max_u32_e32 v4, v211, v4
	v_max_u32_e32 v5, v11, v5
	v_min_u32_e32 v207, v6, v7
	v_min_u32_e32 v211, v4, v5
	v_max_u32_e32 v222, v6, v7
	v_max_u32_e32 v223, v4, v5
	v_max_u32_e32 v206, v206, v213
	v_max_u32_e32 v213, v219, v12
	v_max_u32_e32 v203, v203, v13
	v_max_u32_e32 v209, v209, v8
	s_waitcnt vmcnt(3)
	v_mfma_f32_32x32x16_bf16 v[0:15], v[0:3], v[24:27], 0
	v_max_u32_e32 v202, v202, v205
	v_max_u32_e32 v205, v212, v215
	v_min_u32_e32 v225, v203, v209
	v_min_u32_e32 v212, v202, v205
	v_max_u32_e32 v200, v200, v201
	v_max_u32_e32 v201, v204, v217
	v_min_u32_e32 v204, v200, v201
	s_waitcnt vmcnt(2)
	v_mfma_f32_32x32x16_bf16 v[0:15], v[88:91], v[20:23], v[0:15]
	v_max_u32_e32 v88, v206, v213
	v_max_u32_e32 v89, v203, v209
	v_min_u32_e32 v203, v88, v89
	v_max_u32_e32 v90, v202, v205
	v_max_u32_e32 v202, v88, v89
	v_max_u32_e32 v91, v200, v201
	v_min_u32_e32 v200, v90, v91
	s_waitcnt vmcnt(1)
	v_mfma_f32_32x32x16_bf16 v[0:15], v[92:95], v[28:31], v[0:15]
	v_max_u32_e32 v205, v90, v91
	v_min_u32_e32 v219, v206, v213
	v_min_u32_e32 v226, v219, v225
	v_max_u32_e32 v219, v219, v225
	v_min_u32_e32 v215, v212, v204
	v_max_u32_e32 v204, v212, v204
	v_min_u32_e32 v221, v208, v210
	s_waitcnt vmcnt(0)
	v_mfma_f32_32x32x16_bf16 v[0:15], v[96:99], v[16:19], v[0:15]
	v_min_u32_e32 v214, v207, v211
	v_min_u32_e32 v224, v222, v223
	v_min_u32_e32 v212, v219, v204
	v_min_u32_e32 v201, v203, v200
	v_min_u32_e32 v206, v202, v205
	v_min_u32_e32 v220, v216, v218
	v_min_u32_e32 v217, v226, v215
	s_nop 4
	v_not_b32_e32 v88, v0
	v_or_b32_e32 v89, 0x80000000, v0
	v_cmp_gt_i32_e32 vcc, 0, v0
	v_or_b32_e32 v90, 0x80000000, v3
	v_not_b32_e32 v91, v7
	v_cndmask_b32_e32 v0, v89, v88, vcc
	v_not_b32_e32 v88, v1
	v_or_b32_e32 v89, 0x80000000, v1
	v_cmp_gt_i32_e32 vcc, 0, v1
	v_or_b32_e32 v92, 0x80000000, v7
	v_or_b32_e32 v93, 0x80000000, v4
	v_cndmask_b32_e32 v1, v89, v88, vcc
	v_not_b32_e32 v89, v3
	v_cmp_gt_i32_e32 vcc, 0, v3
	v_not_b32_e32 v95, v15
	v_or_b32_e32 v96, 0x80000000, v15
	v_cndmask_b32_e32 v3, v90, v89, vcc
	v_not_b32_e32 v89, v2
	v_or_b32_e32 v90, 0x80000000, v2
	v_cmp_gt_i32_e32 vcc, 0, v2
	v_or_b32_e32 v97, 0x80000000, v12
	v_not_b32_e32 v98, v8
	v_cndmask_b32_e32 v2, v90, v89, vcc
	v_cmp_gt_i32_e32 vcc, 0, v7
	v_or_b32_e32 v99, 0x80000000, v8
	v_or_b32_e32 v209, 0x80000000, v11
	v_cndmask_b32_e32 v7, v92, v91, vcc
	v_not_b32_e32 v91, v6
	v_or_b32_e32 v92, 0x80000000, v6
	v_cmp_gt_i32_e32 vcc, 0, v6
	v_and_or_b32 v0, v0, s77, v118
	v_and_or_b32 v1, v1, s77, v119
	v_cndmask_b32_e32 v6, v92, v91, vcc
	v_not_b32_e32 v92, v4
	v_cmp_gt_i32_e32 vcc, 0, v4
	v_and_or_b32 v3, v3, s77, v121
	v_and_or_b32 v2, v2, s77, v120
	v_cndmask_b32_e32 v4, v93, v92, vcc
	v_not_b32_e32 v92, v5
	v_or_b32_e32 v93, 0x80000000, v5
	v_cmp_gt_i32_e32 vcc, 0, v5
	v_and_or_b32 v7, v7, s77, v125
	v_and_or_b32 v6, v6, s77, v124
	v_cndmask_b32_e32 v5, v93, v92, vcc
	v_cmp_gt_i32_e32 vcc, 0, v15
	v_and_or_b32 v4, v4, s77, v122
	v_and_or_b32 v5, v5, s77, v123
	v_cndmask_b32_e32 v15, v96, v95, vcc
	v_not_b32_e32 v95, v14
	v_or_b32_e32 v96, 0x80000000, v14
	v_cmp_gt_i32_e32 vcc, 0, v14
	v_and_or_b32 v15, v15, s77, v133
	v_max_u32_e32 v88, v0, v1
	v_cndmask_b32_e32 v14, v96, v95, vcc
	v_not_b32_e32 v96, v12
	v_cmp_gt_i32_e32 vcc, 0, v12
	v_and_or_b32 v14, v14, s77, v132
	v_min_u32_e32 v89, v3, v2
	v_cndmask_b32_e32 v12, v97, v96, vcc
	v_not_b32_e32 v96, v13
	v_or_b32_e32 v97, 0x80000000, v13
	v_cmp_gt_i32_e32 vcc, 0, v13
	v_and_or_b32 v12, v12, s77, v130
	v_min_u32_e32 v0, v0, v1
	v_cndmask_b32_e32 v13, v97, v96, vcc
	v_cmp_gt_i32_e32 vcc, 0, v8
	v_and_or_b32 v13, v13, s77, v131
	v_max_u32_e32 v1, v3, v2
	v_cndmask_b32_e32 v8, v99, v98, vcc
	v_not_b32_e32 v98, v9
	v_or_b32_e32 v99, 0x80000000, v9
	v_cmp_gt_i32_e32 vcc, 0, v9
	v_and_or_b32 v8, v8, s77, v126
	v_max_u32_e32 v91, v7, v6
	v_cndmask_b32_e32 v9, v99, v98, vcc
	v_not_b32_e32 v99, v11
	v_cmp_gt_i32_e32 vcc, 0, v11
	v_and_or_b32 v9, v9, s77, v127
	v_min_u32_e32 v92, v4, v5
	v_cndmask_b32_e32 v11, v209, v99, vcc
	v_not_b32_e32 v99, v10
	v_or_b32_e32 v209, 0x80000000, v10
	v_cmp_gt_i32_e32 vcc, 0, v10
	v_and_or_b32 v11, v11, s77, v129
	v_min_u32_e32 v6, v7, v6
	v_cndmask_b32_e32 v10, v209, v99, vcc
	v_and_or_b32 v10, v10, s77, v128
	v_max_u32_e32 v4, v4, v5
	v_max_u32_e32 v95, v15, v14
	v_min_u32_e32 v96, v12, v13
	v_min_u32_e32 v14, v15, v14
	v_max_u32_e32 v12, v12, v13
	v_max_u32_e32 v98, v8, v9
	v_min_u32_e32 v99, v11, v10
	v_min_u32_e32 v8, v8, v9
	v_max_u32_e32 v9, v11, v10
	v_max_u32_e32 v90, v88, v89
	v_max_u32_e32 v2, v0, v1
	v_min_u32_e32 v93, v91, v92
	v_min_u32_e32 v5, v6, v4
	v_min_u32_e32 v88, v88, v89
	v_min_u32_e32 v0, v0, v1
	v_max_u32_e32 v89, v91, v92
	v_max_u32_e32 v4, v6, v4
	v_max_u32_e32 v97, v95, v96
	v_max_u32_e32 v13, v14, v12
	v_min_u32_e32 v209, v98, v99
	v_min_u32_e32 v10, v8, v9
	v_min_u32_e32 v95, v95, v96
	v_min_u32_e32 v12, v14, v12
	v_max_u32_e32 v96, v98, v99
	v_max_u32_e32 v8, v8, v9
	v_max_u32_e32 v3, v90, v2
	v_min_u32_e32 v7, v93, v5
	v_max_u32_e32 v1, v88, v0
	v_min_u32_e32 v6, v89, v4
	v_min_u32_e32 v2, v90, v2
	v_max_u32_e32 v5, v93, v5
	v_min_u32_e32 v0, v88, v0
	v_max_u32_e32 v4, v89, v4
	v_max_u32_e32 v15, v97, v13
	v_min_u32_e32 v11, v209, v10
	v_max_u32_e32 v14, v95, v12
	v_min_u32_e32 v9, v96, v8
	v_min_u32_e32 v13, v97, v13
	v_max_u32_e32 v10, v209, v10
	v_min_u32_e32 v12, v95, v12
	v_max_u32_e32 v8, v96, v8
	v_max_u32_e32 v94, v3, v7
	v_max_u32_e32 v91, v1, v6
	v_max_u32_e32 v90, v2, v5
	v_max_u32_e32 v88, v0, v4
	v_min_u32_e32 v213, v15, v11
	v_min_u32_e32 v98, v14, v9
	v_min_u32_e32 v97, v13, v10
	v_min_u32_e32 v95, v12, v8
	v_min_u32_e32 v3, v3, v7
	v_min_u32_e32 v1, v1, v6
	v_min_u32_e32 v2, v2, v5
	v_min_u32_e32 v0, v0, v4
	v_max_u32_e32 v5, v15, v11
	v_max_u32_e32 v9, v14, v9
	v_max_u32_e32 v10, v13, v10
	v_max_u32_e32 v8, v12, v8
	v_max_u32_e32 v92, v94, v91
	v_max_u32_e32 v89, v90, v88
	v_min_u32_e32 v99, v213, v98
	v_min_u32_e32 v96, v97, v95
	v_max_u32_e32 v6, v3, v1
	v_max_u32_e32 v4, v2, v0
	v_min_u32_e32 v11, v5, v9
	v_min_u32_e32 v12, v10, v8
	v_min_u32_e32 v91, v94, v91
	v_min_u32_e32 v88, v90, v88
	v_max_u32_e32 v94, v213, v98
	v_max_u32_e32 v95, v97, v95
	v_min_u32_e32 v1, v3, v1
	v_min_u32_e32 v0, v2, v0
	v_max_u32_e32 v2, v5, v9
	v_max_u32_e32 v3, v10, v8
	v_max_u32_e32 v93, v92, v89
	v_min_u32_e32 v209, v99, v96
	v_max_u32_e32 v7, v6, v4
	v_min_u32_e32 v13, v11, v12
	v_min_u32_e32 v97, v94, v95
	v_min_u32_e32 v92, v92, v89
	v_max_u32_e32 v96, v99, v96
	v_min_u32_e32 v6, v6, v4
	v_max_u32_e32 v11, v11, v12
	v_min_u32_e32 v99, v91, v88
	v_max_u32_e32 v94, v94, v95
	v_min_u32_e32 v95, v1, v0
	v_max_u32_e32 v227, v2, v3
	v_max_u32_e32 v90, v91, v88
	v_max_u32_e32 v213, v1, v0
	v_min_u32_e32 v8, v2, v3
	v_min_u32_e32 v89, v92, v96
	v_min_u32_e32 v4, v6, v11
	v_min_u32_e32 v88, v99, v94
	v_min_u32_e32 v0, v95, v227
	v_min_u32_e32 v225, v93, v209
	v_min_u32_e32 v14, v7, v13
	v_min_u32_e32 v98, v90, v97
	v_min_u32_e32 v5, v213, v8
	v_min_u32_e32 v12, v89, v4
	v_min_u32_e32 v1, v88, v0
	v_min_u32_e32 v9, v98, v5
	v_min_u32_e32 v228, v12, v1
	v_max_u32_e32 v12, v12, v1
	v_max_u32_e32 v1, v225, v14
	v_max_u32_e32 v2, v98, v5
	v_max_u32_e32 v3, v89, v4
	v_max_u32_e32 v0, v88, v0
	v_lshl_add_u64 v[4:5], v[34:35], 0, v[78:79]
	v_min_u32_e32 v15, v225, v14
	v_min_u32_e32 v14, v1, v2
	v_min_u32_e32 v225, v3, v0
	v_max_u32_e32 v231, v1, v2
	v_max_u32_e32 v232, v3, v0
	global_load_dwordx4 v[0:3], v[4:5], off
	v_max_u32_e32 v97, v90, v97
	global_load_dwordx4 v[88:91], v[4:5], off offset:32
	v_max_u32_e32 v98, v93, v209
	v_max_u32_e32 v234, v92, v96
	v_max_u32_e32 v235, v99, v94
	v_max_u32_e32 v227, v95, v227
	global_load_dwordx4 v[92:95], v[4:5], off offset:64
	v_max_u32_e32 v6, v6, v11
	v_max_u32_e32 v7, v7, v13
	v_max_u32_e32 v8, v213, v8
	v_min_u32_e32 v11, v234, v6
	v_min_u32_e32 v96, v235, v227
	v_min_u32_e32 v13, v98, v7
	v_min_u32_e32 v209, v97, v8
	v_min_u32_e32 v236, v11, v96
	v_max_u32_e32 v11, v11, v96
	v_max_u32_e32 v7, v98, v7
	v_max_u32_e32 v8, v97, v8
	global_load_dwordx4 v[96:99], v[4:5], off offset:96
	v_max_u32_e32 v5, v234, v6
	v_max_u32_e32 v6, v235, v227
	v_min_u32_e32 v10, v15, v9
	v_max_u32_e32 v9, v15, v9
	v_min_u32_e32 v213, v13, v209
	v_max_u32_e32 v13, v13, v209
	v_min_u32_e32 v4, v7, v8
	v_min_u32_e32 v227, v5, v6
	v_max_u32_e32 v7, v7, v8
	v_max_u32_e32 v5, v5, v6
	v_min_u32_e32 v229, v10, v228
	v_min_u32_e32 v15, v9, v12
	v_min_u32_e32 v230, v14, v225
	v_min_u32_e32 v233, v231, v232
	v_min_u32_e32 v237, v213, v236
	v_min_u32_e32 v209, v13, v11
	v_min_u32_e32 v234, v4, v227
	v_min_u32_e32 v6, v7, v5
	v_max3_u32 v8, v202, v205, v229
	v_max3_u32 v10, v206, v10, v228
	v_max3_u32 v15, v203, v200, v15
	v_max3_u32 v9, v201, v9, v12
	v_max3_u32 v12, v219, v204, v230
	v_max3_u32 v14, v212, v14, v225
	v_max3_u32 v200, v226, v215, v233
	v_max3_u32 v202, v222, v223, v237
	v_max3_u32 v203, v224, v213, v236
	v_max3_u32 v204, v207, v211, v209
	v_max3_u32 v11, v214, v13, v11
	v_max3_u32 v13, v208, v210, v234
	v_max3_u32 v4, v221, v4, v227
	v_max3_u32 v6, v216, v218, v6
	v_max3_u32 v201, v217, v231, v232
	v_max3_u32 v5, v220, v7, v5
	v_max_u32_e32 v7, v8, v202
	v_min_u32_e32 v8, v8, v202
	v_max_u32_e32 v202, v10, v203
	v_min_u32_e32 v10, v10, v203
	v_max_u32_e32 v203, v15, v204
	v_min_u32_e32 v15, v15, v204
	v_max_u32_e32 v204, v9, v11
	v_min_u32_e32 v9, v9, v11
	v_max_u32_e32 v11, v12, v13
	v_min_u32_e32 v12, v12, v13
	v_max_u32_e32 v13, v14, v4
	v_min_u32_e32 v4, v14, v4
	v_max_u32_e32 v14, v200, v6
	v_min_u32_e32 v6, v200, v6
	v_max_u32_e32 v200, v201, v5
	v_min_u32_e32 v5, v201, v5
	v_max_u32_e32 v201, v7, v11
	v_min_u32_e32 v205, v7, v11
	v_max_u32_e32 v7, v203, v14
	v_max_u32_e32 v206, v202, v13
	v_min_u32_e32 v202, v202, v13
	v_min_u32_e32 v203, v203, v14
	v_max_u32_e32 v207, v204, v200
	v_min_u32_e32 v200, v204, v200
	v_max_u32_e32 v204, v8, v12
	v_min_u32_e32 v208, v8, v12
	v_max_u32_e32 v209, v10, v4
	v_min_u32_e32 v210, v10, v4
	v_max_u32_e32 v211, v15, v6
	v_min_u32_e32 v212, v15, v6
	v_max_u32_e32 v213, v9, v5
	v_min_u32_e32 v214, v9, v5
	v_max_u32_e32 v215, v201, v7
	v_min_u32_e32 v201, v201, v7
	s_waitcnt vmcnt(3)
	v_mfma_f32_32x32x16_bf16 v[0:15], v[0:3], v[24:27], 0
	v_max_u32_e32 v216, v206, v207
	v_min_u32_e32 v206, v206, v207
	v_max_u32_e32 v207, v205, v203
	v_min_u32_e32 v203, v205, v203
	v_max_u32_e32 v205, v202, v200
	v_min_u32_e32 v200, v202, v200
	v_max_u32_e32 v202, v204, v211
	s_waitcnt vmcnt(2)
	v_mfma_f32_32x32x16_bf16 v[0:15], v[88:91], v[20:23], v[0:15]
	v_min_u32_e32 v204, v204, v211
	v_max_u32_e32 v211, v209, v213
	v_min_u32_e32 v209, v209, v213
	v_max_u32_e32 v213, v208, v212
	v_min_u32_e32 v208, v208, v212
	v_max_u32_e32 v212, v210, v214
	v_min_u32_e32 v210, v210, v214
	s_waitcnt vmcnt(1)
	v_mfma_f32_32x32x16_bf16 v[0:15], v[92:95], v[28:31], v[0:15]
	v_min_u32_e32 v214, v215, v216
	v_min_u32_e32 v217, v201, v206
	v_min_u32_e32 v218, v207, v205
	v_min_u32_e32 v220, v202, v211
	v_min_u32_e32 v221, v204, v209
	v_min_u32_e32 v222, v213, v212
	v_min_u32_e32 v219, v203, v200
	s_waitcnt vmcnt(0)
	v_mfma_f32_32x32x16_bf16 v[0:15], v[96:99], v[16:19], v[0:15]
	v_min_u32_e32 v223, v208, v210
	v_max_u32_e32 v44, v44, v50
	v_max_u32_e32 v39, v39, v53
	v_max_u32_e32 v36, v36, v47
	v_max_u32_e32 v47, v39, v36
	v_min_u32_e32 v36, v39, v36
	s_nop 5
	v_not_b32_e32 v88, v0
	v_or_b32_e32 v89, 0x80000000, v0
	v_cmp_gt_i32_e32 vcc, 0, v0
	v_or_b32_e32 v90, 0x80000000, v3
	v_not_b32_e32 v91, v7
	v_cndmask_b32_e32 v0, v89, v88, vcc
	v_not_b32_e32 v88, v1
	v_or_b32_e32 v89, 0x80000000, v1
	v_cmp_gt_i32_e32 vcc, 0, v1
	v_or_b32_e32 v92, 0x80000000, v7
	v_or_b32_e32 v93, 0x80000000, v4
	v_cndmask_b32_e32 v1, v89, v88, vcc
	v_not_b32_e32 v89, v3
	v_cmp_gt_i32_e32 vcc, 0, v3
	v_not_b32_e32 v95, v15
	v_or_b32_e32 v96, 0x80000000, v15
	v_cndmask_b32_e32 v3, v90, v89, vcc
	v_not_b32_e32 v89, v2
	v_or_b32_e32 v90, 0x80000000, v2
	v_cmp_gt_i32_e32 vcc, 0, v2
	v_or_b32_e32 v97, 0x80000000, v12
	v_not_b32_e32 v98, v8
	v_cndmask_b32_e32 v2, v90, v89, vcc
	v_cmp_gt_i32_e32 vcc, 0, v7
	v_or_b32_e32 v99, 0x80000000, v8
	v_or_b32_e32 v224, 0x80000000, v11
	v_cndmask_b32_e32 v7, v92, v91, vcc
	v_not_b32_e32 v91, v6
	v_or_b32_e32 v92, 0x80000000, v6
	v_cmp_gt_i32_e32 vcc, 0, v6
	v_and_or_b32 v0, v0, s77, v134
	v_and_or_b32 v1, v1, s77, v135
	v_cndmask_b32_e32 v6, v92, v91, vcc
	v_not_b32_e32 v92, v4
	v_cmp_gt_i32_e32 vcc, 0, v4
	v_and_or_b32 v3, v3, s77, v137
	v_and_or_b32 v2, v2, s77, v136
	v_cndmask_b32_e32 v4, v93, v92, vcc
	v_not_b32_e32 v92, v5
	v_or_b32_e32 v93, 0x80000000, v5
	v_cmp_gt_i32_e32 vcc, 0, v5
	v_and_or_b32 v7, v7, s77, v141
	v_and_or_b32 v6, v6, s77, v140
	v_cndmask_b32_e32 v5, v93, v92, vcc
	v_cmp_gt_i32_e32 vcc, 0, v15
	v_and_or_b32 v4, v4, s77, v138
	v_and_or_b32 v5, v5, s77, v139
	v_cndmask_b32_e32 v15, v96, v95, vcc
	v_not_b32_e32 v95, v14
	v_or_b32_e32 v96, 0x80000000, v14
	v_cmp_gt_i32_e32 vcc, 0, v14
	v_and_or_b32 v15, v15, s77, v149
	v_max_u32_e32 v88, v0, v1
	v_cndmask_b32_e32 v14, v96, v95, vcc
	v_not_b32_e32 v96, v12
	v_cmp_gt_i32_e32 vcc, 0, v12
	v_and_or_b32 v14, v14, s77, v148
	v_min_u32_e32 v89, v3, v2
	v_cndmask_b32_e32 v12, v97, v96, vcc
	v_not_b32_e32 v96, v13
	v_or_b32_e32 v97, 0x80000000, v13
	v_cmp_gt_i32_e32 vcc, 0, v13
	v_and_or_b32 v12, v12, s77, v146
	v_min_u32_e32 v0, v0, v1
	v_cndmask_b32_e32 v13, v97, v96, vcc
	v_cmp_gt_i32_e32 vcc, 0, v8
	v_and_or_b32 v13, v13, s77, v147
	v_max_u32_e32 v1, v3, v2
	v_cndmask_b32_e32 v8, v99, v98, vcc
	v_not_b32_e32 v98, v9
	v_or_b32_e32 v99, 0x80000000, v9
	v_cmp_gt_i32_e32 vcc, 0, v9
	v_and_or_b32 v8, v8, s77, v142
	v_max_u32_e32 v91, v7, v6
	v_cndmask_b32_e32 v9, v99, v98, vcc
	v_not_b32_e32 v99, v11
	v_cmp_gt_i32_e32 vcc, 0, v11
	v_and_or_b32 v9, v9, s77, v143
	v_min_u32_e32 v92, v4, v5
	v_cndmask_b32_e32 v11, v224, v99, vcc
	v_not_b32_e32 v99, v10
	v_or_b32_e32 v224, 0x80000000, v10
	v_cmp_gt_i32_e32 vcc, 0, v10
	v_and_or_b32 v11, v11, s77, v145
	v_min_u32_e32 v6, v7, v6
	v_cndmask_b32_e32 v10, v224, v99, vcc
	v_and_or_b32 v10, v10, s77, v144
	v_max_u32_e32 v4, v4, v5
	v_max_u32_e32 v95, v15, v14
	v_min_u32_e32 v96, v12, v13
	v_min_u32_e32 v14, v15, v14
	v_max_u32_e32 v12, v12, v13
	v_max_u32_e32 v98, v8, v9
	v_min_u32_e32 v99, v11, v10
	v_min_u32_e32 v8, v8, v9
	v_max_u32_e32 v9, v11, v10
	v_max_u32_e32 v90, v88, v89
	v_max_u32_e32 v2, v0, v1
	v_min_u32_e32 v93, v91, v92
	v_min_u32_e32 v5, v6, v4
	v_min_u32_e32 v88, v88, v89
	v_min_u32_e32 v0, v0, v1
	v_max_u32_e32 v89, v91, v92
	v_max_u32_e32 v4, v6, v4
	v_max_u32_e32 v97, v95, v96
	v_max_u32_e32 v13, v14, v12
	v_min_u32_e32 v224, v98, v99
	v_min_u32_e32 v10, v8, v9
	v_min_u32_e32 v95, v95, v96
	v_min_u32_e32 v12, v14, v12
	v_max_u32_e32 v96, v98, v99
	v_max_u32_e32 v8, v8, v9
	v_max_u32_e32 v3, v90, v2
	v_min_u32_e32 v7, v93, v5
	v_max_u32_e32 v1, v88, v0
	v_min_u32_e32 v6, v89, v4
	v_min_u32_e32 v2, v90, v2
	v_max_u32_e32 v5, v93, v5
	v_min_u32_e32 v0, v88, v0
	v_max_u32_e32 v4, v89, v4
	v_max_u32_e32 v15, v97, v13
	v_min_u32_e32 v11, v224, v10
	v_max_u32_e32 v14, v95, v12
	v_min_u32_e32 v9, v96, v8
	v_min_u32_e32 v13, v97, v13
	v_max_u32_e32 v10, v224, v10
	v_min_u32_e32 v12, v95, v12
	v_max_u32_e32 v8, v96, v8
	v_max_u32_e32 v94, v3, v7
	v_max_u32_e32 v91, v1, v6
	v_max_u32_e32 v90, v2, v5
	v_max_u32_e32 v88, v0, v4
	v_min_u32_e32 v225, v15, v11
	v_min_u32_e32 v98, v14, v9
	v_min_u32_e32 v97, v13, v10
	v_min_u32_e32 v95, v12, v8
	v_min_u32_e32 v3, v3, v7
	v_min_u32_e32 v1, v1, v6
	v_min_u32_e32 v2, v2, v5
	v_min_u32_e32 v0, v0, v4
	v_max_u32_e32 v5, v15, v11
	v_max_u32_e32 v9, v14, v9
	v_max_u32_e32 v10, v13, v10
	v_max_u32_e32 v8, v12, v8
	v_max_u32_e32 v92, v94, v91
	v_max_u32_e32 v89, v90, v88
	v_min_u32_e32 v99, v225, v98
	v_min_u32_e32 v96, v97, v95
	v_max_u32_e32 v6, v3, v1
	v_max_u32_e32 v4, v2, v0
	v_min_u32_e32 v11, v5, v9
	v_min_u32_e32 v12, v10, v8
	v_min_u32_e32 v91, v94, v91
	v_min_u32_e32 v88, v90, v88
	v_max_u32_e32 v94, v225, v98
	v_max_u32_e32 v95, v97, v95
	v_min_u32_e32 v1, v3, v1
	v_min_u32_e32 v0, v2, v0
	v_max_u32_e32 v2, v5, v9
	v_max_u32_e32 v3, v10, v8
	v_max_u32_e32 v93, v92, v89
	v_min_u32_e32 v224, v99, v96
	v_max_u32_e32 v7, v6, v4
	v_min_u32_e32 v13, v11, v12
	v_min_u32_e32 v97, v94, v95
	v_min_u32_e32 v92, v92, v89
	v_max_u32_e32 v96, v99, v96
	v_min_u32_e32 v6, v6, v4
	v_max_u32_e32 v11, v11, v12
	v_min_u32_e32 v99, v91, v88
	v_max_u32_e32 v94, v94, v95
	v_min_u32_e32 v95, v1, v0
	v_max_u32_e32 v227, v2, v3
	v_max_u32_e32 v90, v91, v88
	v_max_u32_e32 v225, v1, v0
	v_min_u32_e32 v8, v2, v3
	v_min_u32_e32 v89, v92, v96
	v_min_u32_e32 v4, v6, v11
	v_min_u32_e32 v88, v99, v94
	v_min_u32_e32 v0, v95, v227
	v_min_u32_e32 v226, v93, v224
	v_min_u32_e32 v14, v7, v13
	v_min_u32_e32 v98, v90, v97
	v_min_u32_e32 v5, v225, v8
	v_min_u32_e32 v12, v89, v4
	v_min_u32_e32 v1, v88, v0
	v_min_u32_e32 v9, v98, v5
	v_min_u32_e32 v228, v12, v1
	v_max_u32_e32 v12, v12, v1
	v_max_u32_e32 v1, v226, v14
	v_max_u32_e32 v2, v98, v5
	v_max_u32_e32 v3, v89, v4
	v_max_u32_e32 v0, v88, v0
	v_lshl_add_u64 v[4:5], v[34:35], 0, v[80:81]
	v_min_u32_e32 v15, v226, v14
	v_min_u32_e32 v14, v1, v2
	v_min_u32_e32 v226, v3, v0
	v_max_u32_e32 v231, v1, v2
	v_max_u32_e32 v232, v3, v0
	global_load_dwordx4 v[0:3], v[4:5], off
	v_max_u32_e32 v97, v90, v97
	global_load_dwordx4 v[88:91], v[4:5], off offset:32
	v_max_u32_e32 v35, v93, v224
	v_max_u32_e32 v8, v225, v8
	v_max_u32_e32 v225, v92, v96
	v_max_u32_e32 v233, v99, v94
	v_max_u32_e32 v227, v95, v227
	global_load_dwordx4 v[92:95], v[4:5], off offset:64
	v_max_u32_e32 v7, v7, v13
	v_max_u32_e32 v6, v6, v11
	v_min_u32_e32 v13, v35, v7
	v_min_u32_e32 v98, v97, v8
	v_min_u32_e32 v11, v225, v6
	v_min_u32_e32 v96, v233, v227
	v_min_u32_e32 v224, v13, v98
	v_min_u32_e32 v234, v11, v96
	v_max_u32_e32 v13, v13, v98
	v_max_u32_e32 v11, v11, v96
	v_max_u32_e32 v8, v97, v8
	global_load_dwordx4 v[96:99], v[4:5], off offset:96
	v_max_u32_e32 v7, v35, v7
	v_max_u32_e32 v5, v225, v6
	v_max_u32_e32 v6, v233, v227
	v_min_u32_e32 v10, v15, v9
	v_max_u32_e32 v9, v15, v9
	v_min_u32_e32 v4, v7, v8
	v_min_u32_e32 v35, v5, v6
	v_max_u32_e32 v7, v7, v8
	v_max_u32_e32 v5, v5, v6
	v_min_u32_e32 v229, v10, v228
	v_min_u32_e32 v15, v9, v12
	v_min_u32_e32 v230, v14, v226
	v_min_u32_e32 v34, v231, v232
	v_min_u32_e32 v235, v224, v234
	v_min_u32_e32 v236, v13, v11
	v_min_u32_e32 v225, v4, v35
	v_min_u32_e32 v6, v7, v5
	v_max3_u32 v8, v215, v216, v229
	v_max3_u32 v10, v214, v10, v228
	v_max3_u32 v15, v201, v206, v15
	v_max3_u32 v9, v217, v9, v12
	v_max3_u32 v12, v207, v205, v230
	v_max3_u32 v14, v218, v14, v226
	v_max3_u32 v34, v203, v200, v34
	v_max3_u32 v201, v202, v211, v235
	v_max3_u32 v202, v220, v224, v234
	v_max3_u32 v203, v204, v209, v236
	v_max3_u32 v11, v221, v13, v11
	v_max3_u32 v13, v213, v212, v225
	v_max3_u32 v4, v222, v4, v35
	v_max3_u32 v6, v208, v210, v6
	v_max3_u32 v200, v219, v231, v232
	v_max3_u32 v5, v223, v7, v5
	v_max_u32_e32 v7, v8, v201
	v_min_u32_e32 v8, v8, v201
	v_max_u32_e32 v35, v10, v202
	v_min_u32_e32 v10, v10, v202
	v_max_u32_e32 v201, v15, v203
	v_max_u32_e32 v202, v9, v11
	v_min_u32_e32 v9, v9, v11
	v_max_u32_e32 v11, v12, v13
	v_min_u32_e32 v12, v12, v13
	v_max_u32_e32 v13, v14, v4
	v_min_u32_e32 v4, v14, v4
	v_max_u32_e32 v14, v34, v6
	v_min_u32_e32 v15, v15, v203
	v_min_u32_e32 v6, v34, v6
	v_max_u32_e32 v34, v200, v5
	v_min_u32_e32 v5, v200, v5
	v_max_u32_e32 v200, v7, v11
	v_min_u32_e32 v203, v7, v11
	v_max_u32_e32 v7, v201, v14
	v_max_u32_e32 v204, v35, v13
	v_min_u32_e32 v35, v35, v13
	v_min_u32_e32 v201, v201, v14
	v_max_u32_e32 v205, v202, v34
	v_min_u32_e32 v34, v202, v34
	v_max_u32_e32 v202, v8, v12
	v_min_u32_e32 v206, v8, v12
	v_max_u32_e32 v207, v10, v4
	v_min_u32_e32 v208, v10, v4
	v_max_u32_e32 v209, v15, v6
	v_min_u32_e32 v210, v15, v6
	v_max_u32_e32 v211, v9, v5
	v_min_u32_e32 v212, v9, v5
	v_max_u32_e32 v213, v200, v7
	v_min_u32_e32 v200, v200, v7
	s_waitcnt vmcnt(3)
	v_mfma_f32_32x32x16_bf16 v[0:15], v[0:3], v[24:27], 0
	v_max_u32_e32 v25, v203, v201
	v_min_u32_e32 v26, v203, v201
	v_max_u32_e32 v27, v35, v34
	v_min_u32_e32 v34, v35, v34
	v_max_u32_e32 v35, v202, v209
	v_min_u32_e32 v201, v202, v209
	v_max_u32_e32 v214, v204, v205
	s_waitcnt vmcnt(2)
	v_mfma_f32_32x32x16_bf16 v[0:15], v[88:91], v[20:23], v[0:15]
	v_min_u32_e32 v24, v204, v205
	v_max_u32_e32 v22, v206, v210
	v_min_u32_e32 v23, v206, v210
	v_max_u32_e32 v20, v207, v211
	v_min_u32_e32 v21, v207, v211
	v_max_u32_e32 v88, v208, v212
	v_min_u32_e32 v89, v208, v212
	s_waitcnt vmcnt(1)
	v_mfma_f32_32x32x16_bf16 v[0:15], v[92:95], v[28:31], v[0:15]
	v_min_u32_e32 v31, v35, v20
	v_min_u32_e32 v90, v213, v214
	v_min_u32_e32 v28, v200, v24
	v_min_u32_e32 v29, v25, v27
	v_min_u32_e32 v30, v26, v34
	v_min_u32_e32 v91, v201, v21
	v_min_u32_e32 v92, v22, v88
	s_waitcnt vmcnt(0)
	v_mfma_f32_32x32x16_bf16 v[0:15], v[96:99], v[16:19], v[0:15]
	v_min_u32_e32 v93, v23, v89
	s_nop 10
	v_not_b32_e32 v16, v0
	v_or_b32_e32 v17, 0x80000000, v0
	v_cmp_gt_i32_e32 vcc, 0, v0
	v_or_b32_e32 v18, 0x80000000, v3
	v_not_b32_e32 v19, v7
	v_cndmask_b32_e32 v0, v17, v16, vcc
	v_not_b32_e32 v16, v1
	v_or_b32_e32 v17, 0x80000000, v1
	v_cmp_gt_i32_e32 vcc, 0, v1
	v_or_b32_e32 v94, 0x80000000, v7
	v_or_b32_e32 v95, 0x80000000, v4
	v_cndmask_b32_e32 v1, v17, v16, vcc
	v_not_b32_e32 v17, v3
	v_cmp_gt_i32_e32 vcc, 0, v3
	v_not_b32_e32 v97, v15
	v_or_b32_e32 v98, 0x80000000, v15
	v_cndmask_b32_e32 v3, v18, v17, vcc
	v_not_b32_e32 v17, v2
	v_or_b32_e32 v18, 0x80000000, v2
	v_cmp_gt_i32_e32 vcc, 0, v2
	v_or_b32_e32 v99, 0x80000000, v12
	v_not_b32_e32 v202, v8
	v_cndmask_b32_e32 v2, v18, v17, vcc
	v_cmp_gt_i32_e32 vcc, 0, v7
	v_or_b32_e32 v203, 0x80000000, v8
	v_or_b32_e32 v204, 0x80000000, v11
	v_cndmask_b32_e32 v7, v94, v19, vcc
	v_not_b32_e32 v19, v6
	v_or_b32_e32 v94, 0x80000000, v6
	v_cmp_gt_i32_e32 vcc, 0, v6
	v_and_or_b32 v0, v0, s77, v150
	v_and_or_b32 v1, v1, s77, v151
	v_cndmask_b32_e32 v6, v94, v19, vcc
	v_not_b32_e32 v94, v4
	v_cmp_gt_i32_e32 vcc, 0, v4
	v_and_or_b32 v3, v3, s77, v153
	v_and_or_b32 v2, v2, s77, v152
	v_cndmask_b32_e32 v4, v95, v94, vcc
	v_not_b32_e32 v94, v5
	v_or_b32_e32 v95, 0x80000000, v5
	v_cmp_gt_i32_e32 vcc, 0, v5
	v_and_or_b32 v7, v7, s77, v158
	v_and_or_b32 v6, v6, s77, v157
	v_cndmask_b32_e32 v5, v95, v94, vcc
	v_cmp_gt_i32_e32 vcc, 0, v15
	v_and_or_b32 v4, v4, s77, v155
	v_and_or_b32 v5, v5, s77, v156
	v_cndmask_b32_e32 v15, v98, v97, vcc
	v_not_b32_e32 v97, v14
	v_or_b32_e32 v98, 0x80000000, v14
	v_cmp_gt_i32_e32 vcc, 0, v14
	v_and_or_b32 v15, v15, s77, v166
	v_max_u32_e32 v16, v0, v1
	v_cndmask_b32_e32 v14, v98, v97, vcc
	v_not_b32_e32 v98, v12
	v_cmp_gt_i32_e32 vcc, 0, v12
	v_and_or_b32 v14, v14, s77, v165
	v_min_u32_e32 v17, v3, v2
	v_cndmask_b32_e32 v12, v99, v98, vcc
	v_not_b32_e32 v98, v13
	v_or_b32_e32 v99, 0x80000000, v13
	v_cmp_gt_i32_e32 vcc, 0, v13
	v_and_or_b32 v12, v12, s77, v163
	v_min_u32_e32 v0, v0, v1
	v_cndmask_b32_e32 v13, v99, v98, vcc
	v_cmp_gt_i32_e32 vcc, 0, v8
	v_and_or_b32 v13, v13, s77, v164
	v_max_u32_e32 v1, v3, v2
	v_cndmask_b32_e32 v8, v203, v202, vcc
	v_not_b32_e32 v202, v9
	v_or_b32_e32 v203, 0x80000000, v9
	v_cmp_gt_i32_e32 vcc, 0, v9
	v_and_or_b32 v8, v8, s77, v159
	v_max_u32_e32 v19, v7, v6
	v_cndmask_b32_e32 v9, v203, v202, vcc
	v_not_b32_e32 v203, v11
	v_cmp_gt_i32_e32 vcc, 0, v11
	v_and_or_b32 v9, v9, s77, v160
	v_min_u32_e32 v94, v4, v5
	v_cndmask_b32_e32 v11, v204, v203, vcc
	v_not_b32_e32 v203, v10
	v_or_b32_e32 v204, 0x80000000, v10
	v_cmp_gt_i32_e32 vcc, 0, v10
	v_and_or_b32 v11, v11, s77, v162
	v_min_u32_e32 v6, v7, v6
	v_cndmask_b32_e32 v10, v204, v203, vcc
	v_and_or_b32 v10, v10, s77, v161
	v_max_u32_e32 v4, v4, v5
	v_max_u32_e32 v97, v15, v14
	v_min_u32_e32 v98, v12, v13
	v_min_u32_e32 v14, v15, v14
	v_max_u32_e32 v12, v12, v13
	v_max_u32_e32 v202, v8, v9
	v_min_u32_e32 v203, v11, v10
	v_min_u32_e32 v8, v8, v9
	v_max_u32_e32 v9, v11, v10
	v_max_u32_e32 v18, v16, v17
	v_max_u32_e32 v2, v0, v1
	v_min_u32_e32 v95, v19, v94
	v_min_u32_e32 v5, v6, v4
	v_min_u32_e32 v16, v16, v17
	v_min_u32_e32 v0, v0, v1
	v_max_u32_e32 v17, v19, v94
	v_max_u32_e32 v4, v6, v4
	v_max_u32_e32 v99, v97, v98
	v_max_u32_e32 v13, v14, v12
	v_min_u32_e32 v204, v202, v203
	v_min_u32_e32 v10, v8, v9
	v_min_u32_e32 v97, v97, v98
	v_min_u32_e32 v12, v14, v12
	v_max_u32_e32 v98, v202, v203
	v_max_u32_e32 v8, v8, v9
	v_max_u32_e32 v3, v18, v2
	v_min_u32_e32 v7, v95, v5
	v_max_u32_e32 v1, v16, v0
	v_min_u32_e32 v6, v17, v4
	v_min_u32_e32 v2, v18, v2
	v_max_u32_e32 v5, v95, v5
	v_min_u32_e32 v0, v16, v0
	v_max_u32_e32 v4, v17, v4
	v_max_u32_e32 v15, v99, v13
	v_min_u32_e32 v11, v204, v10
	v_max_u32_e32 v14, v97, v12
	v_min_u32_e32 v9, v98, v8
	v_min_u32_e32 v13, v99, v13
	v_max_u32_e32 v10, v204, v10
	v_min_u32_e32 v12, v97, v12
	v_max_u32_e32 v8, v98, v8
	v_max_u32_e32 v96, v3, v7
	v_max_u32_e32 v19, v1, v6
	v_max_u32_e32 v18, v2, v5
	v_max_u32_e32 v16, v0, v4
	v_min_u32_e32 v205, v15, v11
	v_min_u32_e32 v202, v14, v9
	v_min_u32_e32 v99, v13, v10
	v_min_u32_e32 v97, v12, v8
	v_min_u32_e32 v3, v3, v7
	v_min_u32_e32 v1, v1, v6
	v_min_u32_e32 v2, v2, v5
	v_min_u32_e32 v0, v0, v4
	v_max_u32_e32 v7, v15, v11
	v_max_u32_e32 v9, v14, v9
	v_max_u32_e32 v10, v13, v10
	v_max_u32_e32 v8, v12, v8
	v_max_u32_e32 v94, v96, v19
	v_max_u32_e32 v17, v18, v16
	v_min_u32_e32 v203, v205, v202
	v_min_u32_e32 v98, v99, v97
	v_max_u32_e32 v6, v3, v1
	v_max_u32_e32 v4, v2, v0
	v_min_u32_e32 v11, v7, v9
	v_min_u32_e32 v12, v10, v8
	v_min_u32_e32 v19, v96, v19
	v_min_u32_e32 v16, v18, v16
	v_max_u32_e32 v96, v205, v202
	v_max_u32_e32 v97, v99, v97
	v_min_u32_e32 v1, v3, v1
	v_min_u32_e32 v0, v2, v0
	v_max_u32_e32 v3, v7, v9
	v_max_u32_e32 v7, v10, v8
	v_max_u32_e32 v95, v94, v17
	v_min_u32_e32 v204, v203, v98
	v_max_u32_e32 v5, v6, v4
	v_min_u32_e32 v13, v11, v12
	v_max_u32_e32 v18, v19, v16
	v_min_u32_e32 v99, v96, v97
	v_max_u32_e32 v2, v1, v0
	v_min_u32_e32 v8, v3, v7
	v_min_u32_e32 v17, v94, v17
	v_max_u32_e32 v94, v203, v98
	v_min_u32_e32 v4, v6, v4
	v_max_u32_e32 v6, v11, v12
	v_min_u32_e32 v16, v19, v16
	v_max_u32_e32 v19, v96, v97
	v_min_u32_e32 v0, v1, v0
	v_max_u32_e32 v1, v3, v7
	v_min_u32_e32 v206, v95, v204
	v_min_u32_e32 v14, v5, v13
	v_min_u32_e32 v202, v18, v99
	v_min_u32_e32 v9, v2, v8
	v_min_u32_e32 v98, v17, v94
	v_min_u32_e32 v11, v4, v6
	v_min_u32_e32 v96, v16, v19
	v_min_u32_e32 v3, v0, v1
	v_max_u32_e32 v95, v95, v204
	v_max_u32_e32 v5, v5, v13
	v_max_u32_e32 v18, v18, v99
	v_max_u32_e32 v2, v2, v8
	v_max_u32_e32 v17, v17, v94
	v_max_u32_e32 v4, v4, v6
	v_max_u32_e32 v16, v16, v19
	v_max_u32_e32 v0, v0, v1
	v_min_u32_e32 v13, v95, v5
	v_min_u32_e32 v8, v18, v2
	v_min_u32_e32 v6, v17, v4
	v_min_u32_e32 v1, v16, v0
	v_min_u32_e32 v99, v13, v8
	v_min_u32_e32 v19, v6, v1
	v_min_u32_e32 v15, v206, v14
	v_min_u32_e32 v10, v202, v9
	v_min_u32_e32 v12, v98, v11
	v_min_u32_e32 v7, v96, v3
	v_min_u32_e32 v94, v99, v19
	v_max_u32_e32 v14, v206, v14
	v_max_u32_e32 v9, v202, v9
	v_max_u32_e32 v11, v98, v11
	v_max_u32_e32 v3, v96, v3
	v_max_u32_e32 v5, v95, v5
	v_max_u32_e32 v2, v18, v2
	v_max_u32_e32 v4, v17, v4
	v_max_u32_e32 v0, v16, v0
	v_min_u32_e32 v205, v15, v10
	v_min_u32_e32 v97, v12, v7
	v_max3_u32 v20, v35, v20, v94
	v_min_u32_e32 v94, v14, v9
	v_min_u32_e32 v96, v11, v3
	v_min_u32_e32 v18, v5, v2
	v_min_u32_e32 v16, v4, v0
	v_max_u32_e32 v10, v15, v10
	v_max_u32_e32 v7, v12, v7
	v_max_u32_e32 v8, v13, v8
	v_max_u32_e32 v1, v6, v1
	v_max_u32_e32 v9, v14, v9
	v_max_u32_e32 v3, v11, v3
	v_max_u32_e32 v2, v5, v2
	v_max_u32_e32 v0, v4, v0
	v_min_u32_e32 v203, v205, v97
	v_min_u32_e32 v98, v94, v96
	v_min_u32_e32 v17, v18, v16
	v_min_u32_e32 v12, v10, v7
	v_min_u32_e32 v6, v8, v1
	v_min_u32_e32 v11, v9, v3
	v_min_u32_e32 v4, v2, v0
	v_max3_u32 v203, v213, v214, v203
	v_max3_u32 v25, v25, v27, v98
	v_max3_u32 v17, v22, v88, v17
	v_max3_u32 v12, v200, v24, v12
	v_max3_u32 v6, v201, v21, v6
	v_max3_u32 v11, v26, v34, v11
	v_max3_u32 v4, v23, v89, v4
	v_max3_u32 v21, v90, v205, v97
	v_max3_u32 v19, v31, v99, v19
	v_max3_u32 v24, v29, v94, v96
	v_max3_u32 v16, v92, v18, v16
	v_max3_u32 v7, v28, v10, v7
	v_max3_u32 v1, v91, v8, v1
	v_max3_u32 v3, v30, v9, v3
	v_max3_u32 v0, v93, v2, v0
	v_min_u32_e32 v35, v203, v20
	v_min_u32_e32 v22, v25, v17
	v_min_u32_e32 v13, v12, v6
	v_min_u32_e32 v5, v11, v4
	v_min_u32_e32 v23, v21, v19
	v_min_u32_e32 v18, v24, v16
	v_min_u32_e32 v8, v7, v1
	v_min_u32_e32 v2, v3, v0
	v_max_u32_e32 v20, v203, v20
	v_max_u32_e32 v17, v25, v17
	v_max_u32_e32 v6, v12, v6
	v_max_u32_e32 v4, v11, v4
	v_max_u32_e32 v19, v21, v19
	v_max_u32_e32 v16, v24, v16
	v_max_u32_e32 v1, v7, v1
	v_max_u32_e32 v0, v3, v0
	v_max_u32_e32 v25, v20, v17
	v_max_u32_e32 v11, v6, v4
	v_max_u32_e32 v21, v19, v16
	v_max_u32_e32 v3, v1, v0
	v_max_u32_e32 v12, v25, v11
	v_max_u32_e32 v7, v21, v3
	v_min_u32_e32 v11, v25, v11
	v_min_u32_e32 v3, v21, v3
	v_max_u32_e32 v24, v12, v7
	v_min_u32_e32 v7, v12, v7
	v_max_u32_e32 v12, v11, v3
	v_min_u32_e32 v3, v11, v3
	v_min_u32_e32 v11, v20, v17
	v_min_u32_e32 v4, v6, v4
	v_min_u32_e32 v16, v19, v16
	v_min_u32_e32 v0, v1, v0
	v_max_u32_e32 v6, v11, v4
	v_max_u32_e32 v1, v16, v0
	v_min_u32_e32 v4, v11, v4
	v_min_u32_e32 v0, v16, v0
	v_min_u32_e32 v14, v13, v5
	v_min_u32_e32 v9, v8, v2
	v_max_u32_e32 v17, v6, v1
	v_min_u32_e32 v1, v6, v1
	v_max_u32_e32 v6, v4, v0
	v_min_u32_e32 v0, v4, v0
	v_max_u32_e32 v4, v35, v22
	v_max_u32_e32 v5, v13, v5
	v_max_u32_e32 v13, v23, v18
	v_max_u32_e32 v2, v8, v2
	v_min_u32_e32 v27, v35, v22
	v_min_u32_e32 v26, v23, v18
	v_max_u32_e32 v11, v4, v5
	v_max_u32_e32 v8, v13, v2
	v_min_u32_e32 v4, v4, v5
	v_min_u32_e32 v2, v13, v2
	v_min_u32_e32 v15, v27, v14
	v_min_u32_e32 v10, v26, v9
	v_max_u32_e32 v5, v4, v2
	v_min_u32_e32 v2, v4, v2
	v_max_u32_e32 v4, v27, v14
	v_max_u32_e32 v9, v26, v9
	v_min_u32_e32 v28, v15, v10
	v_max_u32_e32 v16, v11, v8
	v_min_u32_e32 v8, v11, v8
	v_max_u32_e32 v11, v4, v9
	v_min_u32_e32 v4, v4, v9
	v_max_u32_e32 v9, v15, v10
	ds_bpermute_b32 v10, v33, v24
	ds_bpermute_b32 v13, v33, v7
	ds_bpermute_b32 v14, v33, v12
	ds_bpermute_b32 v15, v33, v3
	ds_bpermute_b32 v18, v33, v17
	ds_bpermute_b32 v19, v33, v1
	ds_bpermute_b32 v20, v33, v6
	ds_bpermute_b32 v21, v33, v0
	ds_bpermute_b32 v22, v33, v16
	ds_bpermute_b32 v23, v33, v8
	ds_bpermute_b32 v25, v33, v5
	ds_bpermute_b32 v26, v33, v28
	ds_bpermute_b32 v27, v33, v9
	ds_bpermute_b32 v29, v33, v4
	ds_bpermute_b32 v30, v33, v11
	ds_bpermute_b32 v31, v33, v2
	s_waitcnt lgkmcnt(4)
	v_max_u32_e32 v24, v24, v26
	s_waitcnt lgkmcnt(3)
	v_max_u32_e32 v7, v7, v27
	s_waitcnt lgkmcnt(2)
	v_max_u32_e32 v12, v12, v29
	s_waitcnt lgkmcnt(1)
	v_max_u32_e32 v3, v3, v30
	s_waitcnt lgkmcnt(0)
	v_max_u32_e32 v17, v17, v31
	v_max_u32_e32 v1, v1, v25
	v_max_u32_e32 v6, v6, v23
	v_max_u32_e32 v0, v0, v22
	v_max_u32_e32 v16, v16, v21
	v_max_u32_e32 v8, v8, v20
	v_max_u32_e32 v5, v5, v19
	v_max_u32_e32 v2, v2, v18
	v_max_u32_e32 v11, v11, v15
	v_max_u32_e32 v4, v4, v14
	v_max_u32_e32 v9, v9, v13
	v_max_u32_e32 v10, v28, v10
	v_max_u32_e32 v13, v24, v16
	v_min_u32_e32 v14, v24, v16
	v_max_u32_e32 v15, v7, v8
	v_min_u32_e32 v7, v7, v8
	v_max_u32_e32 v8, v12, v5
	v_min_u32_e32 v5, v12, v5
	v_max_u32_e32 v12, v3, v2
	v_min_u32_e32 v2, v3, v2
	v_max_u32_e32 v3, v17, v11
	v_max_u32_e32 v16, v1, v4
	v_min_u32_e32 v1, v1, v4
	v_max_u32_e32 v4, v6, v9
	v_min_u32_e32 v6, v6, v9
	v_max_u32_e32 v9, v0, v10
	v_min_u32_e32 v11, v17, v11
	v_min_u32_e32 v0, v0, v10
	v_max_u32_e32 v10, v13, v3
	v_min_u32_e32 v3, v13, v3
	v_max_u32_e32 v13, v15, v16
	v_min_u32_e32 v15, v15, v16
	v_max_u32_e32 v16, v8, v4
	v_min_u32_e32 v4, v8, v4
	v_max_u32_e32 v8, v12, v9
	v_min_u32_e32 v9, v12, v9
	v_max_u32_e32 v12, v14, v11
	v_min_u32_e32 v11, v14, v11
	v_max_u32_e32 v14, v7, v1
	v_min_u32_e32 v7, v7, v1
	v_max_u32_e32 v1, v5, v6
	v_min_u32_e32 v6, v5, v6
	v_max_u32_e32 v5, v2, v0
	v_min_u32_e32 v0, v2, v0
	v_max_u32_e32 v2, v10, v16
	v_min_u32_e32 v10, v10, v16
	v_max_u32_e32 v16, v13, v8
	v_min_u32_e32 v8, v13, v8
	v_max_u32_e32 v13, v3, v4
	v_min_u32_e32 v3, v3, v4
	v_max_u32_e32 v4, v15, v9
	v_min_u32_e32 v9, v15, v9
	v_max_u32_e32 v15, v12, v1
	v_min_u32_e32 v1, v12, v1
	v_max_u32_e32 v12, v14, v5
	v_max_u32_e32 v23, v3, v9
	v_max_u32_e32 v88, v11, v6
	v_min_u32_e32 v89, v11, v6
	v_max_u32_e32 v90, v7, v0
	v_min_u32_e32 v91, v7, v0
	v_max_u32_e32 v17, v2, v16
	v_min_u32_e32 v18, v2, v16
	v_max_u32_e32 v21, v13, v4
	v_min_u32_e32 v22, v13, v4
	v_max_u32_e32 v25, v15, v12
	v_min_u32_e32 v26, v15, v12
	v_and_b32_e32 v0, 0x7fffff80, v23
	v_bitop3_b32 v2, v23, s76, v23 bitop3:0xcf
	v_cmp_gt_i32_e32 vcc, 0, v23
	v_max_u32_e32 v11, v42, v87
	v_max_u32_e32 v12, v52, v84
	v_max_u32_e32 v13, v45, v86
	v_max_u32_e32 v15, v57, v61
	v_max_u32_e32 v30, v41, v85
	v_max_u32_e32 v31, v49, v60
	v_max_u32_e32 v34, v43, v62
	v_max_u32_e32 v42, v54, v55
	v_max_u32_e32 v45, v38, v63
	v_max_u32_e32 v54, v48, v51
	v_min_u32_e32 v5, v14, v5
	v_max_u32_e32 v19, v10, v8
	v_min_u32_e32 v20, v10, v8
	v_cndmask_b32_e32 v10, v2, v0, vcc
	v_and_b32_e32 v0, 0x7fffff80, v26
	v_bitop3_b32 v2, v26, s76, v26 bitop3:0xcf
	v_cmp_gt_i32_e32 vcc, 0, v26
	v_max_u32_e32 v14, v11, v12
	v_max_u32_e32 v35, v13, v15
	v_max_u32_e32 v41, v30, v31
	v_max_u32_e32 v43, v34, v42
	v_max_u32_e32 v55, v45, v46
	v_max_u32_e32 v56, v40, v54
	v_max_u32_e32 v57, v37, v44
	v_cndmask_b32_e32 v4, v2, v0, vcc
	v_max_u32_e32 v2, v14, v35
	v_max_u32_e32 v6, v41, v43
	v_max_u32_e32 v7, v55, v56
	v_max_u32_e32 v8, v57, v47
	v_min_u32_e32 v24, v3, v9
	v_min_u32_e32 v3, v2, v6
	v_min_u32_e32 v9, v7, v8
	v_min_u32_e32 v27, v3, v9
	v_and_b32_e32 v0, 0x7fffff80, v27
	v_bitop3_b32 v16, v27, s76, v27 bitop3:0xcf
	v_cmp_gt_i32_e32 vcc, 0, v27
	v_max_u32_e32 v28, v3, v9
	v_and_b32_e32 v3, 0x7fffff80, v20
	v_cndmask_b32_e32 v0, v16, v0, vcc
	v_and_b32_e32 v16, 0xffffff80, v20
	v_and_b32_e32 v29, 0xffffff80, v28
	v_xor_b32_e32 v16, -1, v16
	v_cmp_gt_i32_e32 vcc, 0, v20
	v_and_b32_e32 v9, 0x7fffff80, v28
	v_xor_b32_e32 v29, -1, v29
	v_cndmask_b32_e32 v3, v16, v3, vcc
	v_cmp_gt_i32_e32 vcc, 0, v28
	v_max_u32_e32 v58, v2, v6
	v_max_u32_e32 v59, v7, v8
	v_cndmask_b32_e32 v38, v29, v9, vcc
	v_min_u32_e32 v29, v58, v59
	v_and_b32_e32 v7, 0xffffff80, v19
	v_and_b32_e32 v2, 0x7fffff80, v19
	v_and_b32_e32 v8, 0xffffff80, v29
	v_xor_b32_e32 v7, -1, v7
	v_cmp_gt_i32_e32 vcc, 0, v19
	v_and_b32_e32 v6, 0x7fffff80, v29
	v_xor_b32_e32 v8, -1, v8
	v_cndmask_b32_e32 v2, v7, v2, vcc
	v_cmp_gt_i32_e32 vcc, 0, v29
	v_min_u32_e32 v11, v11, v12
	v_min_u32_e32 v15, v13, v15
	v_cndmask_b32_e32 v16, v8, v6, vcc
	v_pk_add_f32 v[6:7], v[38:39], v[2:3] op_sel_hi:[0,1]
	v_not_b32_e32 v8, v7
	v_or_b32_e32 v9, 0x80000000, v7
	v_cmp_gt_i32_e32 vcc, 0, v7
	v_min_u32_e32 v62, v30, v31
	v_min_u32_e32 v63, v34, v42
	v_cndmask_b32_e32 v7, v9, v8, vcc
	v_and_b32_e32 v7, 0xffffff00, v7
	v_or_b32_e32 v7, 0xdc, v7
	v_cndmask_b32_e64 v48, 0, v7, s[10:11]
	v_not_b32_e32 v7, v6
	v_or_b32_e32 v8, 0x80000000, v6
	v_cmp_gt_i32_e32 vcc, 0, v6
	v_and_b32_e32 v9, 0x7fffff80, v21
	v_min_u32_e32 v45, v45, v46
	v_cndmask_b32_e32 v6, v8, v7, vcc
	v_and_b32_e32 v6, 0xffffff00, v6
	v_or_b32_e32 v6, 0xdd, v6
	v_cndmask_b32_e64 v49, 0, v6, s[10:11]
	v_and_b32_e32 v6, 0xffffff80, v22
	v_and_b32_e32 v7, 0xffffff80, v21
	v_and_b32_e32 v8, 0x7fffff80, v22
	v_xor_b32_e32 v6, -1, v6
	v_cmp_gt_i32_e32 vcc, 0, v22
	v_xor_b32_e32 v50, -1, v7
	v_min_u32_e32 v46, v40, v54
	v_cndmask_b32_e32 v7, v6, v8, vcc
	v_cmp_gt_i32_e32 vcc, 0, v21
	v_min_u32_e32 v37, v37, v44
	v_min_u32_e32 v60, v11, v15
	v_cndmask_b32_e32 v6, v50, v9, vcc
	v_pk_add_f32 v[8:9], v[16:17], v[6:7] op_sel_hi:[0,1]
	v_not_b32_e32 v50, v9
	v_or_b32_e32 v51, 0x80000000, v9
	v_cmp_gt_i32_e32 vcc, 0, v9
	v_min_u32_e32 v84, v62, v63
	v_min_u32_e32 v85, v45, v46
	v_cndmask_b32_e32 v9, v51, v50, vcc
	v_and_b32_e32 v9, 0xffffff00, v9
	v_or_b32_e32 v9, 0xea, v9
	v_cndmask_b32_e64 v50, 0, v9, s[10:11]
	v_not_b32_e32 v9, v8
	v_or_b32_e32 v51, 0x80000000, v8
	v_cmp_gt_i32_e32 vcc, 0, v8
	v_min_u32_e32 v39, v37, v36
	v_max_u32_e32 v34, v58, v59
	v_cndmask_b32_e32 v8, v51, v9, vcc
	v_and_b32_e32 v8, 0xffffff00, v8
	v_or_b32_e32 v8, 0xeb, v8
	v_cndmask_b32_e64 v51, 0, v8, s[10:11]
	v_pk_add_f32 v[8:9], v[16:17], v[2:3] op_sel_hi:[0,1]
	v_not_b32_e32 v52, v9
	v_or_b32_e32 v53, 0x80000000, v9
	v_cmp_gt_i32_e32 vcc, 0, v9
	v_max_u32_e32 v11, v11, v15
	v_max_u32_e32 v15, v37, v36
	v_cndmask_b32_e32 v9, v53, v52, vcc
	v_and_b32_e32 v9, 0xffffff00, v9
	v_or_b32_e32 v9, 0xec, v9
	v_cndmask_b32_e64 v52, 0, v9, s[10:11]
	v_not_b32_e32 v9, v8
	v_or_b32_e32 v53, 0x80000000, v8
	v_cmp_gt_i32_e32 vcc, 0, v8
	v_min_u32_e32 v37, v14, v35
	v_and_b32_e32 v14, 0xffffff80, v24
	v_cndmask_b32_e32 v8, v53, v9, vcc
	v_and_b32_e32 v8, 0xffffff00, v8
	v_or_b32_e32 v8, 0xed, v8
	v_cndmask_b32_e64 v53, 0, v8, s[10:11]
	v_min_u32_e32 v8, v60, v84
	v_min_u32_e32 v9, v85, v39
	v_min_u32_e32 v30, v8, v9
	v_and_b32_e32 v12, 0x7fffff80, v30
	v_bitop3_b32 v13, v30, s76, v30 bitop3:0xcf
	v_cmp_gt_i32_e32 vcc, 0, v30
	v_max_u32_e32 v31, v8, v9
	v_and_b32_e32 v8, 0x7fffff80, v31
	v_cndmask_b32_e32 v40, v13, v12, vcc
	v_bitop3_b32 v9, v31, s76, v31 bitop3:0xcf
	v_cmp_gt_i32_e32 vcc, 0, v31
	v_and_b32_e32 v13, 0xffffff80, v34
	v_and_b32_e32 v12, 0x7fffff80, v34
	v_cndmask_b32_e32 v42, v9, v8, vcc
	v_and_b32_e32 v9, 0xffffff80, v18
	v_and_b32_e32 v8, 0x7fffff80, v18
	v_xor_b32_e32 v9, -1, v9
	v_cmp_gt_i32_e32 vcc, 0, v18
	v_xor_b32_e32 v13, -1, v13
	v_xor_b32_e32 v14, -1, v14
	v_cndmask_b32_e32 v9, v9, v8, vcc
	v_cmp_gt_i32_e32 vcc, 0, v34
	s_nop 1
	v_cndmask_b32_e32 v8, v13, v12, vcc
	v_mov_b32_e32 v12, v9
	v_mov_b32_e32 v13, v2
	v_pk_add_f32 v[12:13], v[0:1], v[12:13] op_sel_hi:[0,1]
	v_not_b32_e32 v44, v13
	v_or_b32_e32 v54, 0x80000000, v13
	v_cmp_gt_i32_e32 vcc, 0, v13
	s_nop 1
	v_cndmask_b32_e32 v13, v54, v44, vcc
	v_and_b32_e32 v13, 0xffffff00, v13
	v_or_b32_e32 v61, 0xcd, v13
	v_not_b32_e32 v13, v12
	v_or_b32_e32 v44, 0x80000000, v12
	v_cmp_gt_i32_e32 vcc, 0, v12
	s_nop 1
	v_cndmask_b32_e32 v12, v44, v13, vcc
	v_and_b32_e32 v12, 0xffffff00, v12
	v_or_b32_e32 v12, 0xce, v12
	v_cndmask_b32_e64 v54, 0, v12, s[10:11]
	v_max_u32_e32 v44, v60, v84
	v_max_u32_e32 v84, v85, v39
	v_max_u32_e32 v12, v62, v63
	v_min_u32_e32 v39, v41, v43
	v_min_u32_e32 v41, v55, v56
	v_min_u32_e32 v43, v57, v47
	v_min_u32_e32 v85, v11, v12
	v_max_u32_e32 v86, v11, v12
	v_min_u32_e32 v11, v37, v39
	v_min_u32_e32 v12, v41, v43
	v_max_u32_e32 v13, v45, v46
	v_max_u32_e32 v36, v11, v12
	v_min_u32_e32 v45, v13, v15
	v_max_u32_e32 v87, v13, v15
	v_and_b32_e32 v13, 0xffffff80, v36
	v_min_u32_e32 v35, v11, v12
	v_and_b32_e32 v11, 0x7fffff80, v36
	v_xor_b32_e32 v13, -1, v13
	v_cmp_gt_i32_e32 vcc, 0, v36
	v_and_b32_e32 v12, 0x7fffff80, v24
	v_max_u32_e32 v94, v37, v39
	v_cndmask_b32_e32 v15, v13, v11, vcc
	v_cmp_gt_i32_e32 vcc, 0, v24
	v_max_u32_e32 v95, v41, v43
	v_mov_b32_e32 v39, v0
	v_cndmask_b32_e32 v14, v14, v12, vcc
	v_mov_b32_e32 v11, v14
	v_pk_add_f32 v[12:13], v[16:17], v[10:11] op_sel_hi:[0,1]
	v_not_b32_e32 v11, v12
	v_or_b32_e32 v46, 0x80000000, v12
	v_cmp_gt_i32_e32 vcc, 0, v12
	v_or_b32_e32 v12, 0x80000000, v13
	v_add_f32_e32 v10, v8, v10
	v_cndmask_b32_e32 v11, v46, v11, vcc
	v_and_b32_e32 v11, 0xffffff00, v11
	v_or_b32_e32 v11, 0xe9, v11
	v_cndmask_b32_e64 v55, 0, v11, s[10:11]
	v_not_b32_e32 v11, v13
	v_cmp_gt_i32_e32 vcc, 0, v13
	v_mov_b32_e32 v43, v16
	s_nop 0
	v_cndmask_b32_e32 v11, v12, v11, vcc
	v_and_b32_e32 v11, 0xffffff00, v11
	v_or_b32_e32 v11, 0xe8, v11
	v_pk_add_f32 v[12:13], v[14:15], v[8:9]
	v_cndmask_b32_e64 v56, 0, v11, s[10:11]
	v_not_b32_e32 v11, v12
	v_or_b32_e32 v14, 0x80000000, v12
	v_cmp_gt_i32_e32 vcc, 0, v12
	v_not_b32_e32 v12, v13
	s_nop 0
	v_cndmask_b32_e32 v11, v14, v11, vcc
	v_or_b32_e32 v14, 0x80000000, v13
	v_cmp_gt_i32_e32 vcc, 0, v13
	v_and_b32_e32 v11, 0xffffff00, v11
	v_or_b32_e32 v11, 0xf8, v11
	v_cndmask_b32_e32 v12, v14, v12, vcc
	v_and_b32_e32 v12, 0xffffff00, v12
	v_or_b32_e32 v12, 0x9e, v12
	v_cndmask_b32_e64 v92, v12, v11, s[10:11]
	v_not_b32_e32 v11, v10
	v_or_b32_e32 v12, 0x80000000, v10
	v_cmp_gt_i32_e32 vcc, 0, v10
	v_min_u32_e32 v14, v94, v95
	v_and_b32_e32 v13, 0xffffff80, v14
	v_cndmask_b32_e32 v10, v12, v11, vcc
	v_and_b32_e32 v10, 0xffffff00, v10
	v_and_b32_e32 v11, 0xffffff80, v17
	v_or_b32_e32 v93, 0xf9, v10
	v_and_b32_e32 v10, 0x7fffff80, v17
	v_xor_b32_e32 v11, -1, v11
	v_cmp_gt_i32_e32 vcc, 0, v17
	v_and_b32_e32 v12, 0x7fffff80, v14
	v_xor_b32_e32 v13, -1, v13
	v_cndmask_b32_e32 v11, v11, v10, vcc
	v_cmp_gt_i32_e32 vcc, 0, v14
	s_nop 1
	v_cndmask_b32_e32 v10, v13, v12, vcc
	v_mov_b32_e32 v12, v6
	v_mov_b32_e32 v13, v11
	v_pk_add_f32 v[12:13], v[38:39], v[12:13]
	v_pk_mov_b32 v[62:63], v[10:11], v[8:9] op_sel:[1,0]
	v_not_b32_e32 v37, v12
	v_or_b32_e32 v39, 0x80000000, v12
	v_cmp_gt_i32_e32 vcc, 0, v12
	s_nop 1
	v_cndmask_b32_e32 v12, v39, v37, vcc
	v_and_b32_e32 v12, 0xffffff00, v12
	v_or_b32_e32 v12, 0xdb, v12
	v_cndmask_b32_e64 v57, 0, v12, s[10:11]
	v_not_b32_e32 v12, v13
	v_or_b32_e32 v37, 0x80000000, v13
	v_cmp_gt_i32_e32 vcc, 0, v13
	v_mov_b32_e32 v13, v9
	s_nop 0
	v_cndmask_b32_e32 v12, v37, v12, vcc
	v_and_b32_e32 v12, 0xffffff00, v12
	v_or_b32_e32 v12, 0xcf, v12
	v_cndmask_b32_e64 v58, 0, v12, s[10:11]
	v_mov_b32_e32 v12, v11
	v_pk_add_f32 v[38:39], v[38:39], v[12:13] op_sel_hi:[0,1]
	v_not_b32_e32 v37, v39
	v_or_b32_e32 v41, 0x80000000, v39
	v_cmp_gt_i32_e32 vcc, 0, v39
	v_or_b32_e32 v39, 0x80000000, v38
	s_nop 0
	v_cndmask_b32_e32 v37, v41, v37, vcc
	v_and_b32_e32 v37, 0xffffff00, v37
	v_or_b32_e32 v37, 0xde, v37
	v_cndmask_b32_e64 v59, 0, v37, s[10:11]
	v_not_b32_e32 v37, v38
	v_cmp_gt_i32_e32 vcc, 0, v38
	v_mov_b32_e32 v41, v16
	v_mov_b32_e32 v16, v11
	v_cndmask_b32_e32 v37, v39, v37, vcc
	v_and_b32_e32 v37, 0xffffff00, v37
	v_or_b32_e32 v37, 0xdf, v37
	v_pk_add_f32 v[38:39], v[40:41], v[12:13]
	v_cndmask_b32_e64 v60, 0, v37, s[10:11]
	v_not_b32_e32 v37, v39
	v_or_b32_e32 v40, 0x80000000, v39
	v_cmp_gt_i32_e32 vcc, 0, v39
	v_not_b32_e32 v39, v38
	s_nop 0
	v_cndmask_b32_e32 v37, v40, v37, vcc
	v_or_b32_e32 v40, 0x80000000, v38
	v_cmp_gt_i32_e32 vcc, 0, v38
	v_and_b32_e32 v37, 0xffffff00, v37
	v_or_b32_e32 v37, 0xee, v37
	v_cndmask_b32_e32 v38, v40, v39, vcc
	v_and_or_b32 v40, v38, s78, 15
	v_pk_add_f32 v[38:39], v[42:43], v[16:17] op_sel_hi:[1,0]
	v_cndmask_b32_e64 v97, v40, v37, s[10:11]
	v_not_b32_e32 v16, v39
	v_or_b32_e32 v41, 0x80000000, v39
	v_cmp_gt_i32_e32 vcc, 0, v39
	v_not_b32_e32 v39, v38
	v_min_u32_e32 v37, v44, v84
	v_cndmask_b32_e32 v16, v41, v16, vcc
	v_or_b32_e32 v41, 0x80000000, v38
	v_cmp_gt_i32_e32 vcc, 0, v38
	v_and_b32_e32 v16, 0xffffff00, v16
	v_or_b32_e32 v16, 0xef, v16
	v_cndmask_b32_e32 v38, v41, v39, vcc
	v_and_or_b32 v38, v38, s78, 31
	v_cndmask_b32_e64 v96, v38, v16, s[10:11]
	v_min_u32_e32 v16, v89, v91
	v_and_b32_e32 v39, 0xffffff80, v16
	v_and_b32_e32 v38, 0x7fffff80, v16
	v_and_b32_e32 v41, 0xffffff80, v37
	v_xor_b32_e32 v39, -1, v39
	v_cmp_gt_i32_e32 vcc, 0, v16
	v_and_b32_e32 v40, 0x7fffff80, v37
	v_xor_b32_e32 v41, -1, v41
	v_cndmask_b32_e32 v39, v39, v38, vcc
	v_cmp_gt_i32_e32 vcc, 0, v37
	s_nop 1
	v_cndmask_b32_e32 v38, v41, v40, vcc
	v_pk_add_f32 v[38:39], v[38:39], v[62:63]
	s_nop 0
	v_not_b32_e32 v40, v39
	v_or_b32_e32 v41, 0x80000000, v39
	v_cmp_gt_i32_e32 vcc, 0, v39
	s_nop 1
	v_cndmask_b32_e32 v39, v41, v40, vcc
	v_not_b32_e32 v40, v38
	v_or_b32_e32 v41, 0x80000000, v38
	v_cmp_gt_i32_e32 vcc, 0, v38
	v_and_b32_e32 v39, 0xffffff00, v39
	v_or_b32_e32 v39, 0xf0, v39
	v_cndmask_b32_e32 v38, v41, v40, vcc
	v_and_or_b32 v38, v38, s78, 47
	v_cndmask_b32_e64 v98, v38, v39, s[10:11]
	v_max_u32_e32 v38, v89, v91
	v_max_u32_e32 v39, v44, v84
	v_and_b32_e32 v41, 0xffffff80, v38
	v_and_b32_e32 v40, 0x7fffff80, v38
	v_and_b32_e32 v43, 0xffffff80, v39
	v_xor_b32_e32 v41, -1, v41
	v_cmp_gt_i32_e32 vcc, 0, v38
	v_and_b32_e32 v42, 0x7fffff80, v39
	v_xor_b32_e32 v43, -1, v43
	v_cndmask_b32_e32 v41, v41, v40, vcc
	v_cmp_gt_i32_e32 vcc, 0, v39
	s_nop 1
	v_cndmask_b32_e32 v40, v43, v42, vcc
	v_pk_add_f32 v[40:41], v[40:41], v[62:63]
	s_nop 0
	v_not_b32_e32 v42, v41
	v_or_b32_e32 v43, 0x80000000, v41
	v_cmp_gt_i32_e32 vcc, 0, v41
	s_nop 1
	v_cndmask_b32_e32 v41, v43, v42, vcc
	v_not_b32_e32 v42, v40
	v_or_b32_e32 v43, 0x80000000, v40
	v_cmp_gt_i32_e32 vcc, 0, v40
	v_and_b32_e32 v41, 0xffffff00, v41
	v_or_b32_e32 v41, 0xf1, v41
	v_cndmask_b32_e32 v40, v43, v42, vcc
	v_and_or_b32 v40, v40, s78, 63
	v_cndmask_b32_e64 v89, v40, v41, s[10:11]
	v_min_u32_e32 v40, v88, v90
	v_min_u32_e32 v41, v85, v45
	v_and_b32_e32 v43, 0xffffff80, v40
	v_and_b32_e32 v42, 0x7fffff80, v40
	v_and_b32_e32 v46, 0xffffff80, v41
	v_xor_b32_e32 v43, -1, v43
	v_cmp_gt_i32_e32 vcc, 0, v40
	v_and_b32_e32 v44, 0x7fffff80, v41
	v_xor_b32_e32 v46, -1, v46
	v_cndmask_b32_e32 v43, v43, v42, vcc
	v_cmp_gt_i32_e32 vcc, 0, v41
	s_nop 1
	v_cndmask_b32_e32 v42, v46, v44, vcc
	v_pk_add_f32 v[42:43], v[42:43], v[62:63]
	s_nop 0
	v_not_b32_e32 v44, v43
	v_or_b32_e32 v46, 0x80000000, v43
	v_cmp_gt_i32_e32 vcc, 0, v43
	s_nop 1
	v_cndmask_b32_e32 v43, v46, v44, vcc
	v_not_b32_e32 v44, v42
	v_or_b32_e32 v46, 0x80000000, v42
	v_cmp_gt_i32_e32 vcc, 0, v42
	v_and_b32_e32 v43, 0xffffff00, v43
	v_or_b32_e32 v43, 0xf2, v43
	v_cndmask_b32_e32 v42, v46, v44, vcc
	v_and_b32_e32 v42, 0xffffff00, v42
	v_or_b32_e32 v42, 0x4f, v42
	v_cndmask_b32_e64 v91, v42, v43, s[10:11]
	v_max_u32_e32 v42, v88, v90
	v_max_u32_e32 v43, v85, v45
	v_and_b32_e32 v45, 0xffffff80, v42
	v_and_b32_e32 v44, 0x7fffff80, v42
	v_and_b32_e32 v47, 0xffffff80, v43
	v_xor_b32_e32 v45, -1, v45
	v_cmp_gt_i32_e32 vcc, 0, v42
	v_and_b32_e32 v46, 0x7fffff80, v43
	v_xor_b32_e32 v47, -1, v47
	v_cndmask_b32_e32 v45, v45, v44, vcc
	v_cmp_gt_i32_e32 vcc, 0, v43
	s_nop 1
	v_cndmask_b32_e32 v44, v47, v46, vcc
	v_pk_add_f32 v[44:45], v[44:45], v[62:63]
	s_nop 0
	v_not_b32_e32 v46, v45
	v_or_b32_e32 v47, 0x80000000, v45
	v_cmp_gt_i32_e32 vcc, 0, v45
	s_nop 1
	v_cndmask_b32_e32 v45, v47, v46, vcc
	v_not_b32_e32 v46, v44
	v_or_b32_e32 v47, 0x80000000, v44
	v_cmp_gt_i32_e32 vcc, 0, v44
	v_and_b32_e32 v45, 0xffffff00, v45
	v_or_b32_e32 v45, 0xf3, v45
	v_cndmask_b32_e32 v44, v47, v46, vcc
	v_and_b32_e32 v44, 0xffffff00, v44
	v_or_b32_e32 v44, 0x5f, v44
	v_cndmask_b32_e64 v88, v44, v45, s[10:11]
	v_min_u32_e32 v44, v1, v5
	v_min_u32_e32 v45, v86, v87
	v_and_b32_e32 v47, 0xffffff80, v44
	v_and_b32_e32 v46, 0x7fffff80, v44
	v_and_b32_e32 v85, 0xffffff80, v45
	v_xor_b32_e32 v47, -1, v47
	v_cmp_gt_i32_e32 vcc, 0, v44
	v_and_b32_e32 v84, 0x7fffff80, v45
	v_xor_b32_e32 v85, -1, v85
	v_cndmask_b32_e32 v47, v47, v46, vcc
	v_cmp_gt_i32_e32 vcc, 0, v45
	s_nop 1
	v_cndmask_b32_e32 v46, v85, v84, vcc
	v_pk_add_f32 v[46:47], v[46:47], v[62:63]
	s_nop 0
	v_not_b32_e32 v84, v47
	v_or_b32_e32 v85, 0x80000000, v47
	v_cmp_gt_i32_e32 vcc, 0, v47
	s_nop 1
	v_cndmask_b32_e32 v47, v85, v84, vcc
	v_not_b32_e32 v84, v46
	v_or_b32_e32 v85, 0x80000000, v46
	v_cmp_gt_i32_e32 vcc, 0, v46
	v_and_b32_e32 v47, 0xffffff00, v47
	v_or_b32_e32 v47, 0xf4, v47
	v_cndmask_b32_e32 v46, v85, v84, vcc
	v_and_b32_e32 v46, 0xffffff00, v46
	v_or_b32_e32 v46, 0x6f, v46
	v_cndmask_b32_e64 v90, v46, v47, s[10:11]
	v_max_u32_e32 v46, v1, v5
	v_max_u32_e32 v47, v86, v87
	v_and_b32_e32 v84, 0xffffff80, v46
	v_and_b32_e32 v1, 0x7fffff80, v46
	v_and_b32_e32 v85, 0xffffff80, v47
	v_xor_b32_e32 v84, -1, v84
	v_cmp_gt_i32_e32 vcc, 0, v46
	v_and_b32_e32 v5, 0x7fffff80, v47
	v_xor_b32_e32 v86, -1, v85
	v_cndmask_b32_e32 v85, v84, v1, vcc
	v_cmp_gt_i32_e32 vcc, 0, v47
	s_nop 1
	v_cndmask_b32_e32 v84, v86, v5, vcc
	v_pk_add_f32 v[84:85], v[84:85], v[62:63]
	s_nop 0
	v_not_b32_e32 v1, v85
	v_or_b32_e32 v5, 0x80000000, v85
	v_cmp_gt_i32_e32 vcc, 0, v85
	v_or_b32_e32 v85, 0x80000000, v84
	s_nop 0
	v_cndmask_b32_e32 v1, v5, v1, vcc
	v_not_b32_e32 v5, v84
	v_cmp_gt_i32_e32 vcc, 0, v84
	v_and_b32_e32 v1, 0xffffff00, v1
	v_or_b32_e32 v1, 0xf5, v1
	v_cndmask_b32_e32 v5, v85, v5, vcc
	v_and_b32_e32 v5, 0xffffff00, v5
	v_or_b32_e32 v5, 0x7f, v5
	v_and_b32_e32 v84, 0xffffff80, v25
	v_cndmask_b32_e64 v86, v5, v1, s[10:11]
	v_and_b32_e32 v1, 0x7fffff80, v25
	v_and_b32_e32 v85, 0xffffff80, v35
	v_xor_b32_e32 v84, -1, v84
	v_cmp_gt_i32_e32 vcc, 0, v25
	v_and_b32_e32 v5, 0x7fffff80, v35
	v_xor_b32_e32 v87, -1, v85
	v_cndmask_b32_e32 v85, v84, v1, vcc
	v_cmp_gt_i32_e32 vcc, 0, v35
	s_nop 1
	v_cndmask_b32_e32 v84, v87, v5, vcc
	v_mov_b32_e32 v5, v84
	v_pk_add_f32 v[4:5], v[4:5], v[8:9]
	s_nop 0
	v_not_b32_e32 v1, v4
	v_or_b32_e32 v87, 0x80000000, v4
	v_cmp_gt_i32_e32 vcc, 0, v4
	v_not_b32_e32 v4, v5
	s_nop 0
	v_cndmask_b32_e32 v1, v87, v1, vcc
	v_or_b32_e32 v87, 0x80000000, v5
	v_cmp_gt_i32_e32 vcc, 0, v5
	v_and_b32_e32 v1, 0xffffff00, v1
	v_or_b32_e32 v1, 0xf6, v1
	v_cndmask_b32_e32 v4, v87, v4, vcc
	v_and_b32_e32 v4, 0xffffff00, v4
	v_or_b32_e32 v4, 0x8e, v4
	v_cndmask_b32_e64 v87, v4, v1, s[10:11]
	v_pk_add_f32 v[4:5], v[84:85], v[62:63]
	s_nop 0
	v_not_b32_e32 v1, v5
	v_or_b32_e32 v62, 0x80000000, v5
	v_cmp_gt_i32_e32 vcc, 0, v5
	v_not_b32_e32 v5, v4
	s_nop 0
	v_cndmask_b32_e32 v1, v62, v1, vcc
	v_or_b32_e32 v62, 0x80000000, v4
	v_cmp_gt_i32_e32 vcc, 0, v4
	v_and_b32_e32 v1, 0xffffff00, v1
	v_or_b32_e32 v1, 0xf7, v1
	v_cndmask_b32_e32 v4, v62, v5, vcc
	v_and_b32_e32 v4, 0xffffff00, v4
	v_or_b32_e32 v4, 0x8f, v4
	v_cndmask_b32_e64 v84, v4, v1, s[10:11]
	v_add_f32_e32 v1, v15, v11
	v_not_b32_e32 v4, v1
	v_or_b32_e32 v5, 0x80000000, v1
	v_cmp_gt_i32_e32 vcc, 0, v1
	s_nop 1
	v_cndmask_b32_e32 v1, v5, v4, vcc
	v_and_b32_e32 v1, 0xffffff00, v1
	v_pk_mov_b32 v[4:5], v[6:7], v[10:11] op_sel:[1,0]
	v_or_b32_e32 v1, 0x9f, v1
	v_pk_add_f32 v[4:5], v[8:9], v[4:5]
	v_cndmask_b32_e64 v15, v1, v93, s[10:11]
	v_not_b32_e32 v1, v4
	v_or_b32_e32 v62, 0x80000000, v4
	v_cmp_gt_i32_e32 vcc, 0, v4
	v_not_b32_e32 v4, v5
	v_pk_mov_b32 v[6:7], v[10:11], v[6:7] op_sel:[1,0]
	v_cndmask_b32_e32 v1, v62, v1, vcc
	v_or_b32_e32 v62, 0x80000000, v5
	v_cmp_gt_i32_e32 vcc, 0, v5
	v_and_b32_e32 v1, 0xffffff00, v1
	v_or_b32_e32 v1, 0xfa, v1
	v_cndmask_b32_e32 v4, v62, v4, vcc
	v_and_b32_e32 v4, 0xffffff00, v4
	v_or_b32_e32 v4, 0xae, v4
	v_cndmask_b32_e64 v85, v4, v1, s[10:11]
	v_mov_b32_e32 v4, v10
	v_mov_b32_e32 v5, v8
	v_pk_add_f32 v[4:5], v[4:5], v[6:7]
	v_max_u32_e32 v7, v94, v95
	v_not_b32_e32 v1, v5
	v_or_b32_e32 v6, 0x80000000, v5
	v_cmp_gt_i32_e32 vcc, 0, v5
	v_not_b32_e32 v5, v4
	v_max_u32_e32 v94, v52, v53
	v_cndmask_b32_e32 v1, v6, v1, vcc
	v_or_b32_e32 v6, 0x80000000, v4
	v_cmp_gt_i32_e32 vcc, 0, v4
	v_and_b32_e32 v1, 0xffffff00, v1
	v_or_b32_e32 v1, 0xfb, v1
	v_cndmask_b32_e32 v4, v6, v5, vcc
	v_and_b32_e32 v4, 0xffffff00, v4
	v_or_b32_e32 v4, 0xaf, v4
	v_cndmask_b32_e64 v6, v4, v1, s[10:11]
	v_and_b32_e32 v1, 0x7fffff80, v7
	v_bitop3_b32 v4, v7, s76, v7 bitop3:0xcf
	v_cmp_gt_i32_e32 vcc, 0, v7
	v_mov_b32_e32 v5, v8
	v_min_u32_e32 v52, v52, v53
	v_cndmask_b32_e32 v4, v4, v1, vcc
	v_pk_add_f32 v[62:63], v[4:5], v[2:3]
	v_max_u32_e32 v53, v51, v50
	v_not_b32_e32 v1, v63
	v_or_b32_e32 v10, 0x80000000, v63
	v_cmp_gt_i32_e32 vcc, 0, v63
	v_or_b32_e32 v63, 0x80000000, v62
	v_min_u32_e32 v50, v51, v50
	v_cndmask_b32_e32 v1, v10, v1, vcc
	v_not_b32_e32 v10, v62
	v_cmp_gt_i32_e32 vcc, 0, v62
	v_and_b32_e32 v1, 0xffffff00, v1
	v_mov_b32_e32 v62, v2
	v_cndmask_b32_e32 v10, v63, v10, vcc
	v_and_b32_e32 v10, 0xffffff00, v10
	v_mov_b32_e32 v63, v4
	v_or_b32_e32 v1, 0xfc, v1
	v_or_b32_e32 v10, 0xbd, v10
	v_pk_add_f32 v[62:63], v[62:63], v[8:9]
	v_cndmask_b32_e64 v93, v10, v1, s[10:11]
	v_not_b32_e32 v1, v62
	v_or_b32_e32 v2, 0x80000000, v62
	v_cmp_gt_i32_e32 vcc, 0, v62
	v_or_b32_e32 v9, 0x80000000, v63
	v_pk_add_f32 v[4:5], v[4:5], v[12:13]
	v_cndmask_b32_e32 v1, v2, v1, vcc
	v_not_b32_e32 v2, v63
	v_cmp_gt_i32_e32 vcc, 0, v63
	v_and_b32_e32 v1, 0xffffff00, v1
	v_or_b32_e32 v1, 0xfd, v1
	v_cndmask_b32_e32 v2, v9, v2, vcc
	v_and_b32_e32 v2, 0xffffff00, v2
	v_or_b32_e32 v2, 0xbe, v2
	v_cndmask_b32_e64 v2, v2, v1, s[10:11]
	v_not_b32_e32 v1, v5
	v_or_b32_e32 v9, 0x80000000, v5
	v_cmp_gt_i32_e32 vcc, 0, v5
	v_not_b32_e32 v5, v4
	v_mov_b32_e32 v10, v3
	v_cndmask_b32_e32 v1, v9, v1, vcc
	v_or_b32_e32 v9, 0x80000000, v4
	v_cmp_gt_i32_e32 vcc, 0, v4
	v_and_b32_e32 v1, 0xffffff00, v1
	v_or_b32_e32 v1, 0xfe, v1
	v_cndmask_b32_e32 v4, v9, v5, vcc
	v_and_b32_e32 v4, 0xffffff00, v4
	v_or_b32_e32 v4, 0xbf, v4
	v_cndmask_b32_e64 v4, v4, v1, s[10:11]
	v_mov_b32_e32 v1, v8
	v_pk_add_f32 v[0:1], v[0:1], v[10:11]
	v_max_u32_e32 v8, v92, v15
	v_not_b32_e32 v3, v1
	v_or_b32_e32 v5, 0x80000000, v1
	v_cmp_gt_i32_e32 vcc, 0, v1
	v_min_u32_e32 v9, v92, v15
	v_max_u32_e32 v10, v84, v87
	v_cndmask_b32_e32 v1, v5, v3, vcc
	v_not_b32_e32 v3, v0
	v_or_b32_e32 v5, 0x80000000, v0
	v_cmp_gt_i32_e32 vcc, 0, v0
	v_or_b32_e32 v1, 0xff, v1
	v_min_u32_e32 v11, v84, v87
	v_cndmask_b32_e32 v0, v5, v3, vcc
	v_and_b32_e32 v0, 0xffffff00, v0
	v_or_b32_e32 v0, 0xcc, v0
	v_cndmask_b32_e64 v0, v0, v1, s[10:11]
	v_cndmask_b32_e64 v1, 0, v61, s[10:11]
	v_max_u32_e32 v3, v0, v4
	v_min_u32_e32 v0, v0, v4
	v_max_u32_e32 v4, v93, v2
	v_min_u32_e32 v2, v93, v2
	v_max_u32_e32 v5, v6, v85
	v_min_u32_e32 v6, v6, v85
	v_max_u32_e32 v12, v90, v86
	v_min_u32_e32 v13, v90, v86
	v_max_u32_e32 v15, v88, v91
	v_min_u32_e32 v61, v88, v91
	v_max_u32_e32 v62, v98, v89
	v_min_u32_e32 v63, v98, v89
	v_max_u32_e32 v92, v96, v97
	v_min_u32_e32 v93, v96, v97
	v_max_u32_e32 v51, v56, v55
	v_min_u32_e32 v55, v56, v55
	v_max_u32_e32 v56, v60, v59
	v_min_u32_e32 v59, v60, v59
	v_max_u32_e32 v60, v48, v49
	v_min_u32_e32 v48, v48, v49
	v_max_u32_e32 v49, v57, v58
	v_min_u32_e32 v57, v57, v58
	v_max_u32_e32 v58, v1, v54
	v_min_u32_e32 v1, v1, v54
	v_max_u32_e32 v84, v3, v2
	v_min_u32_e32 v2, v3, v2
	v_max_u32_e32 v3, v0, v4
	v_min_u32_e32 v0, v0, v4
	v_max_u32_e32 v4, v9, v5
	v_min_u32_e32 v5, v9, v5
	v_max_u32_e32 v9, v8, v6
	v_min_u32_e32 v6, v8, v6
	v_max_u32_e32 v8, v10, v13
	v_min_u32_e32 v10, v10, v13
	v_max_u32_e32 v13, v11, v12
	v_min_u32_e32 v11, v11, v12
	v_max_u32_e32 v12, v63, v15
	v_min_u32_e32 v15, v63, v15
	v_max_u32_e32 v63, v62, v61
	v_min_u32_e32 v61, v62, v61
	v_max_u32_e32 v54, v92, v52
	v_min_u32_e32 v52, v92, v52
	v_max_u32_e32 v92, v93, v94
	v_min_u32_e32 v93, v93, v94
	v_max_u32_e32 v94, v55, v53
	v_min_u32_e32 v53, v55, v53
	v_max_u32_e32 v55, v51, v50
	v_min_u32_e32 v50, v51, v50
	v_max_u32_e32 v51, v56, v48
	v_min_u32_e32 v48, v56, v48
	v_max_u32_e32 v56, v59, v60
	v_min_u32_e32 v59, v59, v60
	v_max_u32_e32 v60, v1, v49
	v_min_u32_e32 v1, v1, v49
	v_max_u32_e32 v49, v58, v57
	v_min_u32_e32 v57, v58, v57
	v_max_u32_e32 v62, v84, v3
	v_min_u32_e32 v3, v84, v3
	v_max_u32_e32 v84, v2, v0
	v_min_u32_e32 v0, v2, v0
	v_max_u32_e32 v2, v6, v5
	v_min_u32_e32 v5, v6, v5
	v_max_u32_e32 v6, v9, v4
	v_min_u32_e32 v4, v9, v4
	v_max_u32_e32 v9, v8, v13
	v_min_u32_e32 v8, v8, v13
	v_max_u32_e32 v13, v10, v11
	v_min_u32_e32 v10, v10, v11
	v_max_u32_e32 v11, v61, v15
	v_min_u32_e32 v15, v61, v15
	v_max_u32_e32 v61, v63, v12
	v_min_u32_e32 v12, v63, v12
	v_max_u32_e32 v58, v54, v92
	v_min_u32_e32 v54, v54, v92
	v_max_u32_e32 v92, v52, v93
	v_min_u32_e32 v52, v52, v93
	v_max_u32_e32 v93, v50, v53
	v_min_u32_e32 v50, v50, v53
	v_max_u32_e32 v53, v55, v94
	v_min_u32_e32 v55, v55, v94
	v_max_u32_e32 v94, v51, v56
	v_min_u32_e32 v51, v51, v56
	v_max_u32_e32 v56, v48, v59
	v_min_u32_e32 v48, v48, v59
	v_max_u32_e32 v59, v57, v1
	v_min_u32_e32 v1, v57, v1
	v_max_u32_e32 v57, v49, v60
	v_min_u32_e32 v49, v49, v60
	v_max_u32_e32 v63, v62, v5
	v_min_u32_e32 v5, v62, v5
	v_max_u32_e32 v62, v3, v2
	v_min_u32_e32 v2, v3, v2
	v_max_u32_e32 v3, v84, v4
	v_min_u32_e32 v4, v84, v4
	v_max_u32_e32 v84, v0, v6
	v_min_u32_e32 v0, v0, v6
	v_max_u32_e32 v6, v15, v9
	v_min_u32_e32 v9, v15, v9
	v_max_u32_e32 v15, v11, v8
	v_min_u32_e32 v8, v11, v8
	v_max_u32_e32 v11, v12, v13
	v_min_u32_e32 v12, v12, v13
	v_max_u32_e32 v13, v61, v10
	v_min_u32_e32 v10, v61, v10
	v_max_u32_e32 v60, v58, v50
	v_min_u32_e32 v50, v58, v50
	v_max_u32_e32 v58, v54, v93
	v_min_u32_e32 v54, v54, v93
	v_max_u32_e32 v93, v92, v55
	v_min_u32_e32 v55, v92, v55
	v_max_u32_e32 v92, v52, v53
	v_min_u32_e32 v52, v52, v53
	v_max_u32_e32 v53, v1, v94
	v_min_u32_e32 v1, v1, v94
	v_max_u32_e32 v94, v59, v51
	v_min_u32_e32 v51, v59, v51
	v_max_u32_e32 v59, v49, v56
	v_min_u32_e32 v49, v49, v56
	v_max_u32_e32 v56, v57, v48
	v_min_u32_e32 v48, v57, v48
	v_max_u32_e32 v61, v63, v3
	v_min_u32_e32 v3, v63, v3
	v_max_u32_e32 v63, v62, v84
	v_min_u32_e32 v62, v62, v84
	v_max_u32_e32 v84, v5, v4
	v_min_u32_e32 v4, v5, v4
	v_max_u32_e32 v5, v2, v0
	v_min_u32_e32 v0, v2, v0
	v_max_u32_e32 v2, v12, v9
	v_min_u32_e32 v9, v12, v9
	v_max_u32_e32 v12, v10, v8
	v_min_u32_e32 v8, v10, v8
	v_max_u32_e32 v10, v11, v6
	v_min_u32_e32 v6, v11, v6
	v_max_u32_e32 v11, v13, v15
	v_min_u32_e32 v13, v13, v15
	v_max_u32_e32 v57, v60, v93
	v_min_u32_e32 v60, v60, v93
	v_max_u32_e32 v93, v58, v92
	v_min_u32_e32 v58, v58, v92
	v_max_u32_e32 v92, v50, v55
	v_min_u32_e32 v50, v50, v55
	v_max_u32_e32 v55, v54, v52
	v_min_u32_e32 v52, v54, v52
	v_max_u32_e32 v54, v49, v1
	v_min_u32_e32 v1, v49, v1
	v_max_u32_e32 v49, v48, v51
	v_min_u32_e32 v48, v48, v51
	v_max_u32_e32 v51, v59, v53
	v_min_u32_e32 v53, v59, v53
	v_max_u32_e32 v59, v56, v94
	v_min_u32_e32 v56, v56, v94
	v_max_u32_e32 v15, v61, v63
	v_min_u32_e32 v61, v61, v63
	v_max_u32_e32 v63, v3, v62
	v_min_u32_e32 v3, v3, v62
	v_max_u32_e32 v62, v84, v5
	v_min_u32_e32 v5, v84, v5
	v_max_u32_e32 v84, v4, v0
	v_min_u32_e32 v0, v4, v0
	v_max_u32_e32 v4, v8, v9
	v_min_u32_e32 v8, v8, v9
	v_max_u32_e32 v9, v12, v2
	v_min_u32_e32 v2, v12, v2
	v_max_u32_e32 v12, v13, v6
	v_min_u32_e32 v6, v13, v6
	v_max_u32_e32 v13, v11, v10
	v_min_u32_e32 v10, v11, v10
	v_max_u32_e32 v94, v57, v93
	v_min_u32_e32 v57, v57, v93
	v_max_u32_e32 v93, v60, v58
	v_min_u32_e32 v58, v60, v58
	v_max_u32_e32 v60, v92, v55
	v_min_u32_e32 v55, v92, v55
	v_max_u32_e32 v92, v50, v52
	v_min_u32_e32 v50, v50, v52
	v_max_u32_e32 v52, v48, v1
	v_min_u32_e32 v1, v48, v1
	v_max_u32_e32 v48, v49, v54
	v_min_u32_e32 v49, v49, v54
	v_max_u32_e32 v54, v56, v53
	v_min_u32_e32 v53, v56, v53
	v_max_u32_e32 v56, v59, v51
	v_min_u32_e32 v51, v59, v51
	v_max_u32_e32 v11, v15, v8
	v_min_u32_e32 v8, v15, v8
	v_max_u32_e32 v15, v61, v4
	v_min_u32_e32 v4, v61, v4
	v_max_u32_e32 v61, v63, v2
	v_min_u32_e32 v2, v63, v2
	v_max_u32_e32 v63, v3, v9
	v_min_u32_e32 v3, v3, v9
	v_max_u32_e32 v9, v62, v6
	v_min_u32_e32 v6, v62, v6
	v_max_u32_e32 v62, v5, v12
	v_min_u32_e32 v5, v5, v12
	v_max_u32_e32 v12, v84, v10
	v_min_u32_e32 v10, v84, v10
	v_max_u32_e32 v84, v0, v13
	v_min_u32_e32 v0, v0, v13
	v_max_u32_e32 v59, v94, v1
	v_min_u32_e32 v1, v94, v1
	v_max_u32_e32 v94, v57, v52
	v_min_u32_e32 v52, v57, v52
	v_max_u32_e32 v57, v93, v49
	v_min_u32_e32 v49, v93, v49
	v_max_u32_e32 v93, v58, v48
	v_min_u32_e32 v48, v58, v48
	v_max_u32_e32 v58, v60, v53
	v_min_u32_e32 v53, v60, v53
	v_max_u32_e32 v60, v55, v54
	v_min_u32_e32 v54, v55, v54
	v_max_u32_e32 v55, v92, v51
	v_min_u32_e32 v51, v92, v51
	v_max_u32_e32 v92, v50, v56
	v_min_u32_e32 v50, v50, v56
	v_max_u32_e32 v13, v11, v9
	v_min_u32_e32 v9, v11, v9
	v_max_u32_e32 v11, v15, v62
	v_min_u32_e32 v15, v15, v62
	v_max_u32_e32 v62, v61, v12
	v_min_u32_e32 v12, v61, v12
	v_max_u32_e32 v61, v63, v84
	v_min_u32_e32 v63, v63, v84
	v_max_u32_e32 v84, v8, v6
	v_min_u32_e32 v6, v8, v6
	v_max_u32_e32 v8, v4, v5
	v_min_u32_e32 v4, v4, v5
	v_max_u32_e32 v5, v2, v10
	v_min_u32_e32 v2, v2, v10
	v_max_u32_e32 v10, v3, v0
	v_min_u32_e32 v0, v3, v0
	v_max_u32_e32 v56, v59, v58
	v_min_u32_e32 v58, v59, v58
	v_max_u32_e32 v59, v94, v60
	v_min_u32_e32 v60, v94, v60
	v_max_u32_e32 v94, v57, v55
	v_min_u32_e32 v55, v57, v55
	v_max_u32_e32 v57, v93, v92
	v_min_u32_e32 v92, v93, v92
	v_max_u32_e32 v93, v1, v53
	v_min_u32_e32 v1, v1, v53
	v_max_u32_e32 v53, v52, v54
	v_min_u32_e32 v52, v52, v54
	v_max_u32_e32 v54, v49, v51
	v_min_u32_e32 v49, v49, v51
	v_max_u32_e32 v51, v48, v50
	v_min_u32_e32 v48, v48, v50
	v_max_u32_e32 v3, v13, v62
	v_min_u32_e32 v13, v13, v62
	v_max_u32_e32 v62, v11, v61
	v_min_u32_e32 v11, v11, v61
	v_max_u32_e32 v61, v9, v12
	v_min_u32_e32 v9, v9, v12
	v_max_u32_e32 v12, v15, v63
	v_min_u32_e32 v15, v15, v63
	v_max_u32_e32 v63, v84, v5
	v_min_u32_e32 v5, v84, v5
	v_max_u32_e32 v84, v8, v10
	v_min_u32_e32 v8, v8, v10
	v_max_u32_e32 v10, v6, v2
	v_min_u32_e32 v2, v6, v2
	v_max_u32_e32 v6, v4, v0
	v_min_u32_e32 v0, v4, v0
	v_max_u32_e32 v50, v56, v94
	v_min_u32_e32 v56, v56, v94
	v_max_u32_e32 v94, v59, v57
	v_min_u32_e32 v57, v59, v57
	v_max_u32_e32 v59, v58, v55
	v_min_u32_e32 v55, v58, v55
	v_max_u32_e32 v58, v60, v92
	v_min_u32_e32 v60, v60, v92
	v_max_u32_e32 v92, v93, v54
	v_min_u32_e32 v54, v93, v54
	v_max_u32_e32 v93, v53, v51
	v_min_u32_e32 v51, v53, v51
	v_max_u32_e32 v53, v1, v49
	v_min_u32_e32 v1, v1, v49
	v_max_u32_e32 v49, v52, v48
	v_min_u32_e32 v48, v52, v48
	v_min_u32_e32 v4, v3, v62
	v_min_u32_e32 v85, v13, v11
	v_min_u32_e32 v86, v61, v12
	v_min_u32_e32 v87, v9, v15
	v_min_u32_e32 v88, v63, v84
	v_min_u32_e32 v89, v5, v8
	v_min_u32_e32 v90, v10, v6
	v_min_u32_e32 v91, v2, v0
	v_min_u32_e32 v52, v50, v94
	v_min_u32_e32 v95, v56, v57
	v_min_u32_e32 v96, v59, v58
	v_min_u32_e32 v97, v55, v60
	v_min_u32_e32 v98, v92, v93
	v_min_u32_e32 v99, v54, v51
	v_min_u32_e32 v200, v53, v49
	v_min_u32_e32 v201, v1, v48
	v_max3_u32 v3, v3, v62, v201
	v_max3_u32 v1, v4, v1, v48
	v_max3_u32 v4, v13, v11, v200
	v_max3_u32 v11, v85, v53, v49
	v_max3_u32 v12, v61, v12, v99
	v_max3_u32 v13, v86, v54, v51
	v_max3_u32 v9, v9, v15, v98
	v_max3_u32 v15, v87, v92, v93
	v_max3_u32 v48, v63, v84, v97
	v_max3_u32 v49, v88, v55, v60
	v_max3_u32 v5, v5, v8, v96
	v_max3_u32 v8, v89, v59, v58
	v_max3_u32 v6, v10, v6, v95
	v_max3_u32 v10, v90, v56, v57
	v_max3_u32 v0, v2, v0, v52
	v_max3_u32 v2, v91, v50, v94
	v_max_u32_e32 v50, v3, v48
	v_min_u32_e32 v3, v3, v48
	v_max_u32_e32 v48, v1, v49
	v_min_u32_e32 v1, v1, v49
	v_max_u32_e32 v49, v4, v5
	v_min_u32_e32 v4, v4, v5
	v_max_u32_e32 v5, v11, v8
	v_min_u32_e32 v8, v11, v8
	v_max_u32_e32 v11, v12, v6
	v_min_u32_e32 v6, v12, v6
	v_max_u32_e32 v12, v13, v10
	v_min_u32_e32 v10, v13, v10
	v_max_u32_e32 v13, v9, v0
	v_min_u32_e32 v0, v9, v0
	v_max_u32_e32 v9, v15, v2
	v_min_u32_e32 v2, v15, v2
	v_max_u32_e32 v15, v50, v11
	v_min_u32_e32 v11, v50, v11
	v_max_u32_e32 v50, v48, v12
	v_min_u32_e32 v12, v48, v12
	v_max_u32_e32 v48, v49, v13
	v_min_u32_e32 v13, v49, v13
	v_max_u32_e32 v49, v5, v9
	v_min_u32_e32 v5, v5, v9
	v_max_u32_e32 v9, v3, v6
	v_min_u32_e32 v3, v3, v6
	v_max_u32_e32 v6, v1, v10
	v_min_u32_e32 v1, v1, v10
	v_max_u32_e32 v10, v4, v0
	v_min_u32_e32 v0, v4, v0
	v_max_u32_e32 v4, v8, v2
	v_min_u32_e32 v2, v8, v2
	v_max_u32_e32 v8, v15, v48
	v_min_u32_e32 v15, v15, v48
	v_max_u32_e32 v48, v50, v49
	v_min_u32_e32 v49, v50, v49
	v_max_u32_e32 v50, v11, v13
	v_min_u32_e32 v11, v11, v13
	v_max_u32_e32 v13, v12, v5
	v_min_u32_e32 v5, v12, v5
	v_max_u32_e32 v12, v9, v10
	v_min_u32_e32 v9, v9, v10
	v_max_u32_e32 v10, v6, v4
	v_min_u32_e32 v4, v6, v4
	v_max_u32_e32 v6, v3, v0
	v_min_u32_e32 v0, v3, v0
	v_max_u32_e32 v3, v1, v2
	v_min_u32_e32 v1, v1, v2
	v_max_u32_e32 v2, v8, v48
	v_min_u32_e32 v8, v8, v48
	v_max_u32_e32 v48, v15, v49
	v_min_u32_e32 v15, v15, v49
	v_max_u32_e32 v49, v50, v13
	v_min_u32_e32 v13, v50, v13
	v_max_u32_e32 v50, v11, v5
	v_min_u32_e32 v5, v11, v5
	v_max_u32_e32 v11, v12, v10
	v_min_u32_e32 v10, v12, v10
	v_max_u32_e32 v12, v9, v4
	v_min_u32_e32 v4, v9, v4
	v_max_u32_e32 v9, v6, v3
	v_min_u32_e32 v3, v6, v3
	v_max_u32_e32 v6, v0, v1
	v_min_u32_e32 v0, v0, v1
	ds_bpermute_b32 v1, v33, v2
	ds_bpermute_b32 v51, v33, v8
	ds_bpermute_b32 v52, v33, v48
	ds_bpermute_b32 v53, v33, v15
	ds_bpermute_b32 v54, v33, v49
	ds_bpermute_b32 v55, v33, v13
	ds_bpermute_b32 v56, v33, v50
	ds_bpermute_b32 v57, v33, v5
	ds_bpermute_b32 v58, v33, v11
	ds_bpermute_b32 v59, v33, v10
	ds_bpermute_b32 v60, v33, v12
	ds_bpermute_b32 v61, v33, v0
	ds_bpermute_b32 v62, v33, v6
	ds_bpermute_b32 v63, v33, v3
	ds_bpermute_b32 v84, v33, v9
	ds_bpermute_b32 v85, v33, v4
	s_waitcnt lgkmcnt(4)
	v_max_u32_e32 v2, v2, v61
	s_waitcnt lgkmcnt(3)
	v_max_u32_e32 v8, v8, v62
	s_waitcnt lgkmcnt(2)
	v_max_u32_e32 v48, v48, v63
	s_waitcnt lgkmcnt(1)
	v_max_u32_e32 v15, v15, v84
	s_waitcnt lgkmcnt(0)
	v_max_u32_e32 v49, v49, v85
	v_max_u32_e32 v13, v13, v60
	v_max_u32_e32 v50, v50, v59
	v_max_u32_e32 v5, v5, v58
	v_max_u32_e32 v11, v11, v57
	v_max_u32_e32 v10, v10, v56
	v_max_u32_e32 v12, v12, v55
	v_max_u32_e32 v4, v4, v54
	v_max_u32_e32 v9, v9, v53
	v_max_u32_e32 v3, v3, v52
	v_max_u32_e32 v6, v6, v51
	v_max_u32_e32 v0, v0, v1
	v_max_u32_e32 v1, v2, v11
	v_min_u32_e32 v2, v2, v11
	v_max_u32_e32 v11, v8, v10
	v_min_u32_e32 v8, v8, v10
	v_max_u32_e32 v10, v48, v12
	v_min_u32_e32 v12, v48, v12
	v_max_u32_e32 v48, v15, v4
	v_min_u32_e32 v4, v15, v4
	v_max_u32_e32 v15, v49, v9
	v_min_u32_e32 v9, v49, v9
	v_max_u32_e32 v49, v13, v3
	v_min_u32_e32 v3, v13, v3
	v_max_u32_e32 v13, v50, v6
	v_min_u32_e32 v6, v50, v6
	v_max_u32_e32 v50, v5, v0
	v_min_u32_e32 v0, v5, v0
	v_max_u32_e32 v5, v1, v15
	v_min_u32_e32 v1, v1, v15
	v_max_u32_e32 v15, v11, v49
	v_min_u32_e32 v11, v11, v49
	v_max_u32_e32 v49, v10, v13
	v_min_u32_e32 v10, v10, v13
	v_max_u32_e32 v13, v48, v50
	v_min_u32_e32 v48, v48, v50
	v_max_u32_e32 v50, v2, v9
	v_min_u32_e32 v2, v2, v9
	v_max_u32_e32 v9, v8, v3
	v_min_u32_e32 v3, v8, v3
	v_max_u32_e32 v8, v12, v6
	v_min_u32_e32 v6, v12, v6
	v_max_u32_e32 v12, v4, v0
	v_min_u32_e32 v0, v4, v0
	v_max_u32_e32 v4, v5, v49
	v_min_u32_e32 v5, v5, v49
	v_max_u32_e32 v49, v15, v13
	v_min_u32_e32 v13, v15, v13
	v_max_u32_e32 v15, v1, v10
	v_min_u32_e32 v1, v1, v10
	v_max_u32_e32 v10, v11, v48
	v_min_u32_e32 v11, v11, v48
	v_max_u32_e32 v48, v50, v8
	v_max_u32_e32 v51, v9, v12
	v_min_u32_e32 v50, v50, v8
	v_min_u32_e32 v12, v9, v12
	v_max_u32_e32 v52, v2, v6
	v_min_u32_e32 v2, v2, v6
	v_max_u32_e32 v6, v3, v0
	v_min_u32_e32 v0, v3, v0
	v_max_u32_e32 v8, v4, v49
	v_min_u32_e32 v3, v4, v49
	v_max_u32_e32 v49, v1, v11
	v_min_u32_e32 v9, v1, v11
	v_max_u32_e32 v1, v48, v51
	v_cndmask_b32_e64 v1, v1, v8, s[10:11]
	v_min_u32_e32 v48, v48, v51
	v_max_u32_e32 v51, v50, v12
	v_min_u32_e32 v12, v50, v12
	v_max_u32_e32 v50, v52, v6
	v_min_u32_e32 v6, v52, v6
	v_max_u32_e32 v52, v2, v0
	v_min_u32_e32 v11, v2, v0
	v_bitop3_b32 v2, v1, 16, v1 bitop3:0xc
	v_bitop3_b32 v54, v1, 1, v1 bitop3:0xc
	v_cmp_eq_u32_e32 vcc, 0, v2
	v_max_u32_e32 v4, v5, v13
	v_min_u32_e32 v5, v5, v13
	v_max_u32_e32 v13, v15, v10
	v_min_u32_e32 v15, v15, v10
	v_bitop3_b32 v10, v1, 32, v1 bitop3:0xc
	v_cndmask_b32_e32 v2, v29, v34, vcc
	v_cndmask_b32_e32 v58, v27, v28, vcc
	v_cndmask_b32_e32 v59, v14, v7, vcc
	v_cndmask_b32_e32 v60, v35, v36, vcc
	v_cndmask_b32_e32 v61, v45, v47, vcc
	v_cndmask_b32_e32 v62, v41, v43, vcc
	v_cndmask_b32_e32 v63, v37, v39, vcc
	v_cndmask_b32_e32 v84, v30, v31, vcc
	v_cmp_eq_u32_e32 vcc, 0, v54
	v_bitop3_b32 v55, v1, 2, v1 bitop3:0xc
	v_bitop3_b32 v53, v1, 64, v1 bitop3:0xc
	v_cndmask_b32_e32 v54, v18, v17, vcc
	v_cndmask_b32_e32 v85, v20, v19, vcc
	v_cndmask_b32_e32 v86, v22, v21, vcc
	v_cndmask_b32_e32 v87, v24, v23, vcc
	v_cndmask_b32_e32 v88, v26, v25, vcc
	v_cndmask_b32_e32 v89, v44, v46, vcc
	v_cndmask_b32_e32 v90, v40, v42, vcc
	v_cndmask_b32_e32 v91, v16, v38, vcc
	v_cmp_eq_u32_e32 vcc, 0, v10
	v_bitop3_b32 v56, v1, 4, v1 bitop3:0xc
	v_bitop3_b32 v0, v1, s79, v1 bitop3:0xc
	v_cndmask_b32_e32 v2, v58, v2, vcc
	v_cndmask_b32_e32 v10, v60, v59, vcc
	v_cndmask_b32_e32 v58, v62, v61, vcc
	v_cndmask_b32_e32 v59, v84, v63, vcc
	v_cmp_eq_u32_e32 vcc, 0, v55
	v_bitop3_b32 v57, v1, 8, v1 bitop3:0xc
	v_cndmask_b32_e64 v6, v6, v15, s[10:11]
	v_cndmask_b32_e32 v54, v85, v54, vcc
	v_cndmask_b32_e32 v55, v87, v86, vcc
	v_cndmask_b32_e32 v60, v89, v88, vcc
	v_cndmask_b32_e32 v61, v91, v90, vcc
	v_cmp_eq_u32_e32 vcc, 0, v53
	v_bitop3_b32 v15, v6, 16, v6 bitop3:0xc
	v_cndmask_b32_e64 v49, v52, v49, s[10:11]
	v_cndmask_b32_e32 v2, v10, v2, vcc
	v_cndmask_b32_e32 v10, v59, v58, vcc
	v_cmp_eq_u32_e32 vcc, 0, v56
	v_bitop3_b32 v52, v49, 32, v49 bitop3:0xc
	v_cndmask_b32_e64 v9, v11, v9, s[10:11]
	v_cndmask_b32_e32 v53, v55, v54, vcc
	v_cndmask_b32_e32 v54, v61, v60, vcc
	v_cmp_gt_u32_e32 vcc, s80, v0
	v_bitop3_b32 v11, v9, 16, v9 bitop3:0xc
	s_nop 0
	v_cndmask_b32_e32 v0, v10, v2, vcc
	v_cmp_eq_u32_e32 vcc, 0, v57
	v_lshlrev_b32_e32 v0, 7, v0
	v_and_b32_e32 v0, 0x3f80, v0
	v_cndmask_b32_e32 v2, v54, v53, vcc
	v_and_b32_e32 v2, 0x7f, v2
	v_bitop3_b32 v0, v0, s81, v2 bitop3:0x36
	v_and_b32_e32 v2, 0x7fffff00, v1
	v_bitop3_b32 v10, v1, s79, v1 bitop3:0xcf
	v_cmp_gt_i32_e32 vcc, 0, v1
	s_nop 1
	v_cndmask_b32_e32 v10, v10, v2, vcc
	v_cndmask_b32_e64 v2, v48, v3, s[10:11]
	v_bitop3_b32 v3, v2, 16, v2 bitop3:0xc
	v_bitop3_b32 v54, v2, 1, v2 bitop3:0xc
	v_cmp_eq_u32_e32 vcc, 0, v3
	v_bitop3_b32 v48, v2, 32, v2 bitop3:0xc
	v_bitop3_b32 v55, v2, 2, v2 bitop3:0xc
	v_cndmask_b32_e32 v3, v29, v34, vcc
	v_cndmask_b32_e32 v58, v27, v28, vcc
	v_cndmask_b32_e32 v59, v14, v7, vcc
	v_cndmask_b32_e32 v60, v35, v36, vcc
	v_cndmask_b32_e32 v61, v45, v47, vcc
	v_cndmask_b32_e32 v62, v41, v43, vcc
	v_cndmask_b32_e32 v63, v37, v39, vcc
	v_cndmask_b32_e32 v84, v30, v31, vcc
	v_cmp_eq_u32_e32 vcc, 0, v54
	v_bitop3_b32 v53, v2, 64, v2 bitop3:0xc
	v_bitop3_b32 v56, v2, 4, v2 bitop3:0xc
	v_cndmask_b32_e32 v54, v18, v17, vcc
	v_cndmask_b32_e32 v85, v20, v19, vcc
	v_cndmask_b32_e32 v86, v22, v21, vcc
	v_cndmask_b32_e32 v87, v24, v23, vcc
	v_cndmask_b32_e32 v88, v26, v25, vcc
	v_cndmask_b32_e32 v89, v44, v46, vcc
	v_cndmask_b32_e32 v90, v40, v42, vcc
	v_cndmask_b32_e32 v91, v16, v38, vcc
	v_cmp_eq_u32_e32 vcc, 0, v48
	v_bitop3_b32 v1, v2, s79, v2 bitop3:0xc
	v_bitop3_b32 v57, v2, 8, v2 bitop3:0xc
	v_cndmask_b32_e32 v3, v58, v3, vcc
	v_cndmask_b32_e32 v48, v60, v59, vcc
	v_cndmask_b32_e32 v58, v62, v61, vcc
	v_cndmask_b32_e32 v59, v84, v63, vcc
	v_cmp_eq_u32_e32 vcc, 0, v55
	s_nop 1
	v_cndmask_b32_e32 v54, v85, v54, vcc
	v_cndmask_b32_e32 v55, v87, v86, vcc
	v_cndmask_b32_e32 v60, v89, v88, vcc
	v_cndmask_b32_e32 v61, v91, v90, vcc
	v_cmp_eq_u32_e32 vcc, 0, v53
	s_nop 1
	v_cndmask_b32_e32 v3, v48, v3, vcc
	v_cndmask_b32_e32 v48, v59, v58, vcc
	v_cmp_eq_u32_e32 vcc, 0, v56
	s_nop 1
	v_cndmask_b32_e32 v53, v55, v54, vcc
	v_cndmask_b32_e32 v54, v61, v60, vcc
	v_cmp_gt_u32_e32 vcc, s80, v1
	s_nop 1
	v_cndmask_b32_e32 v1, v48, v3, vcc
	v_cmp_eq_u32_e32 vcc, 0, v57
	v_lshlrev_b32_e32 v1, 7, v1
	v_and_b32_e32 v1, 0x3f80, v1
	v_cndmask_b32_e32 v3, v54, v53, vcc
	v_and_b32_e32 v3, 0x7f, v3
	v_bitop3_b32 v1, v1, s81, v3 bitop3:0x36
	v_and_b32_e32 v3, 0x7fffff00, v2
	v_bitop3_b32 v48, v2, s79, v2 bitop3:0xcf
	v_cmp_gt_i32_e32 vcc, 0, v2
	s_nop 1
	v_cndmask_b32_e32 v48, v48, v3, vcc
	v_cndmask_b32_e64 v3, v51, v4, s[10:11]
	v_bitop3_b32 v4, v3, 16, v3 bitop3:0xc
	v_bitop3_b32 v54, v3, 1, v3 bitop3:0xc
	v_cmp_eq_u32_e32 vcc, 0, v4
	v_bitop3_b32 v51, v3, 32, v3 bitop3:0xc
	v_bitop3_b32 v55, v3, 2, v3 bitop3:0xc
	v_cndmask_b32_e32 v4, v29, v34, vcc
	v_cndmask_b32_e32 v58, v27, v28, vcc
	v_cndmask_b32_e32 v59, v14, v7, vcc
	v_cndmask_b32_e32 v60, v35, v36, vcc
	v_cndmask_b32_e32 v61, v45, v47, vcc
	v_cndmask_b32_e32 v62, v41, v43, vcc
	v_cndmask_b32_e32 v63, v37, v39, vcc
	v_cndmask_b32_e32 v84, v30, v31, vcc
	v_cmp_eq_u32_e32 vcc, 0, v54
	v_bitop3_b32 v53, v3, 64, v3 bitop3:0xc
	v_bitop3_b32 v56, v3, 4, v3 bitop3:0xc
	v_cndmask_b32_e32 v54, v18, v17, vcc
	v_cndmask_b32_e32 v85, v20, v19, vcc
	v_cndmask_b32_e32 v86, v22, v21, vcc
	v_cndmask_b32_e32 v87, v24, v23, vcc
	v_cndmask_b32_e32 v88, v26, v25, vcc
	v_cndmask_b32_e32 v89, v44, v46, vcc
	v_cndmask_b32_e32 v90, v40, v42, vcc
	v_cndmask_b32_e32 v91, v16, v38, vcc
	v_cmp_eq_u32_e32 vcc, 0, v51
	v_bitop3_b32 v2, v3, s79, v3 bitop3:0xc
	v_bitop3_b32 v57, v3, 8, v3 bitop3:0xc
	v_cndmask_b32_e32 v4, v58, v4, vcc
	v_cndmask_b32_e32 v51, v60, v59, vcc
	v_cndmask_b32_e32 v58, v62, v61, vcc
	v_cndmask_b32_e32 v59, v84, v63, vcc
	v_cmp_eq_u32_e32 vcc, 0, v55
	s_nop 1
	v_cndmask_b32_e32 v54, v85, v54, vcc
	v_cndmask_b32_e32 v55, v87, v86, vcc
	v_cndmask_b32_e32 v60, v89, v88, vcc
	v_cndmask_b32_e32 v61, v91, v90, vcc
	v_cmp_eq_u32_e32 vcc, 0, v53
	s_nop 1
	v_cndmask_b32_e32 v4, v51, v4, vcc
	v_cndmask_b32_e32 v51, v59, v58, vcc
	v_cmp_eq_u32_e32 vcc, 0, v56
	s_nop 1
	v_cndmask_b32_e32 v53, v55, v54, vcc
	v_cndmask_b32_e32 v54, v61, v60, vcc
	v_cmp_gt_u32_e32 vcc, s80, v2
	s_nop 1
	v_cndmask_b32_e32 v2, v51, v4, vcc
	v_cmp_eq_u32_e32 vcc, 0, v57
	v_lshlrev_b32_e32 v2, 7, v2
	v_and_b32_e32 v2, 0x3f80, v2
	v_cndmask_b32_e32 v4, v54, v53, vcc
	v_and_b32_e32 v4, 0x7f, v4
	v_bitop3_b32 v2, v2, s81, v4 bitop3:0x36
	v_and_b32_e32 v4, 0x7fffff00, v3
	v_bitop3_b32 v51, v3, s79, v3 bitop3:0xcf
	v_cmp_gt_i32_e32 vcc, 0, v3
	s_nop 1
	v_cndmask_b32_e32 v51, v51, v4, vcc
	v_cndmask_b32_e64 v4, v12, v5, s[10:11]
	v_bitop3_b32 v5, v4, 16, v4 bitop3:0xc
	v_bitop3_b32 v54, v4, 1, v4 bitop3:0xc
	v_cmp_eq_u32_e32 vcc, 0, v5
	v_bitop3_b32 v12, v4, 32, v4 bitop3:0xc
	v_bitop3_b32 v55, v4, 2, v4 bitop3:0xc
	v_cndmask_b32_e32 v5, v29, v34, vcc
	v_cndmask_b32_e32 v58, v27, v28, vcc
	v_cndmask_b32_e32 v59, v14, v7, vcc
	v_cndmask_b32_e32 v60, v35, v36, vcc
	v_cndmask_b32_e32 v61, v45, v47, vcc
	v_cndmask_b32_e32 v62, v41, v43, vcc
	v_cndmask_b32_e32 v63, v37, v39, vcc
	v_cndmask_b32_e32 v84, v30, v31, vcc
	v_cmp_eq_u32_e32 vcc, 0, v54
	v_bitop3_b32 v53, v4, 64, v4 bitop3:0xc
	v_bitop3_b32 v56, v4, 4, v4 bitop3:0xc
	v_cndmask_b32_e32 v54, v18, v17, vcc
	v_cndmask_b32_e32 v85, v20, v19, vcc
	v_cndmask_b32_e32 v86, v22, v21, vcc
	v_cndmask_b32_e32 v87, v24, v23, vcc
	v_cndmask_b32_e32 v88, v26, v25, vcc
	v_cndmask_b32_e32 v89, v44, v46, vcc
	v_cndmask_b32_e32 v90, v40, v42, vcc
	v_cndmask_b32_e32 v91, v16, v38, vcc
	v_cmp_eq_u32_e32 vcc, 0, v12
	v_bitop3_b32 v3, v4, s79, v4 bitop3:0xc
	v_bitop3_b32 v57, v4, 8, v4 bitop3:0xc
	v_cndmask_b32_e32 v5, v58, v5, vcc
	v_cndmask_b32_e32 v12, v60, v59, vcc
	v_cndmask_b32_e32 v58, v62, v61, vcc
	v_cndmask_b32_e32 v59, v84, v63, vcc
	v_cmp_eq_u32_e32 vcc, 0, v55
	s_nop 1
	v_cndmask_b32_e32 v54, v85, v54, vcc
	v_cndmask_b32_e32 v55, v87, v86, vcc
	v_cndmask_b32_e32 v60, v89, v88, vcc
	v_cndmask_b32_e32 v61, v91, v90, vcc
	v_cmp_eq_u32_e32 vcc, 0, v53
	s_nop 1
	v_cndmask_b32_e32 v5, v12, v5, vcc
	v_cndmask_b32_e32 v12, v59, v58, vcc
	v_cmp_eq_u32_e32 vcc, 0, v56
	s_nop 1
	v_cndmask_b32_e32 v53, v55, v54, vcc
	v_cndmask_b32_e32 v54, v61, v60, vcc
	v_cmp_gt_u32_e32 vcc, s80, v3
	s_nop 1
	v_cndmask_b32_e32 v3, v12, v5, vcc
	v_cmp_eq_u32_e32 vcc, 0, v57
	v_lshlrev_b32_e32 v3, 7, v3
	v_and_b32_e32 v3, 0x3f80, v3
	v_cndmask_b32_e32 v5, v54, v53, vcc
	v_and_b32_e32 v5, 0x7f, v5
	v_bitop3_b32 v3, v3, s81, v5 bitop3:0x36
	v_and_b32_e32 v5, 0x7fffff00, v4
	v_bitop3_b32 v12, v4, s79, v4 bitop3:0xcf
	v_cmp_gt_i32_e32 vcc, 0, v4
	s_nop 1
	v_cndmask_b32_e32 v12, v12, v5, vcc
	v_cndmask_b32_e64 v5, v50, v13, s[10:11]
	v_bitop3_b32 v13, v5, 16, v5 bitop3:0xc
	v_bitop3_b32 v54, v5, 1, v5 bitop3:0xc
	v_cmp_eq_u32_e32 vcc, 0, v13
	v_bitop3_b32 v50, v5, 32, v5 bitop3:0xc
	v_bitop3_b32 v55, v5, 2, v5 bitop3:0xc
	v_cndmask_b32_e32 v13, v29, v34, vcc
	v_cndmask_b32_e32 v58, v27, v28, vcc
	v_cndmask_b32_e32 v59, v14, v7, vcc
	v_cndmask_b32_e32 v60, v35, v36, vcc
	v_cndmask_b32_e32 v61, v45, v47, vcc
	v_cndmask_b32_e32 v62, v41, v43, vcc
	v_cndmask_b32_e32 v63, v37, v39, vcc
	v_cndmask_b32_e32 v84, v30, v31, vcc
	v_cmp_eq_u32_e32 vcc, 0, v54
	v_bitop3_b32 v53, v5, 64, v5 bitop3:0xc
	v_bitop3_b32 v56, v5, 4, v5 bitop3:0xc
	v_cndmask_b32_e32 v54, v18, v17, vcc
	v_cndmask_b32_e32 v85, v20, v19, vcc
	v_cndmask_b32_e32 v86, v22, v21, vcc
	v_cndmask_b32_e32 v87, v24, v23, vcc
	v_cndmask_b32_e32 v88, v26, v25, vcc
	v_cndmask_b32_e32 v89, v44, v46, vcc
	v_cndmask_b32_e32 v90, v40, v42, vcc
	v_cndmask_b32_e32 v91, v16, v38, vcc
	v_cmp_eq_u32_e32 vcc, 0, v50
	v_bitop3_b32 v4, v5, s79, v5 bitop3:0xc
	v_bitop3_b32 v57, v5, 8, v5 bitop3:0xc
	v_cndmask_b32_e32 v13, v58, v13, vcc
	v_cndmask_b32_e32 v50, v60, v59, vcc
	v_cndmask_b32_e32 v58, v62, v61, vcc
	v_cndmask_b32_e32 v59, v84, v63, vcc
	v_cmp_eq_u32_e32 vcc, 0, v55
	s_nop 1
	v_cndmask_b32_e32 v54, v85, v54, vcc
	v_cndmask_b32_e32 v55, v87, v86, vcc
	v_cndmask_b32_e32 v60, v89, v88, vcc
	v_cndmask_b32_e32 v61, v91, v90, vcc
	v_cmp_eq_u32_e32 vcc, 0, v53
	s_nop 1
	v_cndmask_b32_e32 v13, v50, v13, vcc
	v_cndmask_b32_e32 v50, v59, v58, vcc
	v_cmp_eq_u32_e32 vcc, 0, v56
	v_bitop3_b32 v56, v6, 4, v6 bitop3:0xc
	s_nop 0
	v_cndmask_b32_e32 v53, v55, v54, vcc
	v_cndmask_b32_e32 v54, v61, v60, vcc
	v_cmp_gt_u32_e32 vcc, s80, v4
	v_bitop3_b32 v55, v6, 2, v6 bitop3:0xc
	s_nop 0
	v_cndmask_b32_e32 v4, v50, v13, vcc
	v_cmp_eq_u32_e32 vcc, 0, v57
	v_lshlrev_b32_e32 v4, 7, v4
	v_and_b32_e32 v4, 0x3f80, v4
	v_cndmask_b32_e32 v13, v54, v53, vcc
	v_and_b32_e32 v13, 0x7f, v13
	v_bitop3_b32 v4, v4, s81, v13 bitop3:0x36
	v_and_b32_e32 v13, 0x7fffff00, v5
	v_bitop3_b32 v50, v5, s79, v5 bitop3:0xcf
	v_cmp_gt_i32_e32 vcc, 0, v5
	v_bitop3_b32 v54, v6, 1, v6 bitop3:0xc
	v_bitop3_b32 v53, v6, 64, v6 bitop3:0xc
	v_cndmask_b32_e32 v13, v50, v13, vcc
	v_cmp_eq_u32_e32 vcc, 0, v15
	v_bitop3_b32 v50, v6, 32, v6 bitop3:0xc
	v_bitop3_b32 v5, v6, s79, v6 bitop3:0xc
	v_cndmask_b32_e32 v15, v29, v34, vcc
	v_cndmask_b32_e32 v58, v27, v28, vcc
	v_cndmask_b32_e32 v59, v14, v7, vcc
	v_cndmask_b32_e32 v60, v35, v36, vcc
	v_cndmask_b32_e32 v61, v45, v47, vcc
	v_cndmask_b32_e32 v62, v41, v43, vcc
	v_cndmask_b32_e32 v63, v37, v39, vcc
	v_cndmask_b32_e32 v84, v30, v31, vcc
	v_cmp_eq_u32_e32 vcc, 0, v54
	v_bitop3_b32 v57, v6, 8, v6 bitop3:0xc
	s_nop 0
	v_cndmask_b32_e32 v54, v18, v17, vcc
	v_cndmask_b32_e32 v85, v20, v19, vcc
	v_cndmask_b32_e32 v86, v22, v21, vcc
	v_cndmask_b32_e32 v87, v24, v23, vcc
	v_cndmask_b32_e32 v88, v26, v25, vcc
	v_cndmask_b32_e32 v89, v44, v46, vcc
	v_cndmask_b32_e32 v90, v40, v42, vcc
	v_cndmask_b32_e32 v91, v16, v38, vcc
	v_cmp_eq_u32_e32 vcc, 0, v50
	s_nop 1
	v_cndmask_b32_e32 v15, v58, v15, vcc
	v_cndmask_b32_e32 v50, v60, v59, vcc
	v_cndmask_b32_e32 v58, v62, v61, vcc
	v_cndmask_b32_e32 v59, v84, v63, vcc
	v_cmp_eq_u32_e32 vcc, 0, v55
	s_nop 1
	v_cndmask_b32_e32 v54, v85, v54, vcc
	v_cndmask_b32_e32 v55, v87, v86, vcc
	v_cndmask_b32_e32 v60, v89, v88, vcc
	v_cndmask_b32_e32 v61, v91, v90, vcc
	v_cmp_eq_u32_e32 vcc, 0, v53
	s_nop 1
	v_cndmask_b32_e32 v15, v50, v15, vcc
	v_cndmask_b32_e32 v50, v59, v58, vcc
	v_cmp_eq_u32_e32 vcc, 0, v56
	v_bitop3_b32 v56, v49, 4, v49 bitop3:0xc
	s_nop 0
	v_cndmask_b32_e32 v53, v55, v54, vcc
	v_cndmask_b32_e32 v54, v61, v60, vcc
	v_cmp_gt_u32_e32 vcc, s80, v5
	v_bitop3_b32 v55, v49, 2, v49 bitop3:0xc
	s_nop 0
	v_cndmask_b32_e32 v5, v50, v15, vcc
	v_cmp_eq_u32_e32 vcc, 0, v57
	v_lshlrev_b32_e32 v5, 7, v5
	v_and_b32_e32 v5, 0x3f80, v5
	v_cndmask_b32_e32 v15, v54, v53, vcc
	v_and_b32_e32 v15, 0x7f, v15
	v_bitop3_b32 v5, v5, s81, v15 bitop3:0x36
	v_and_b32_e32 v15, 0x7fffff00, v6
	v_bitop3_b32 v50, v6, s79, v6 bitop3:0xcf
	v_cmp_gt_i32_e32 vcc, 0, v6
	v_bitop3_b32 v54, v49, 1, v49 bitop3:0xc
	v_bitop3_b32 v53, v49, 64, v49 bitop3:0xc
	v_cndmask_b32_e32 v15, v50, v15, vcc
	v_bitop3_b32 v50, v49, 16, v49 bitop3:0xc
	v_cmp_eq_u32_e32 vcc, 0, v50
	v_bitop3_b32 v6, v49, s79, v49 bitop3:0xc
	v_bitop3_b32 v57, v49, 8, v49 bitop3:0xc
	v_cndmask_b32_e32 v50, v29, v34, vcc
	v_cndmask_b32_e32 v58, v27, v28, vcc
	v_cndmask_b32_e32 v59, v14, v7, vcc
	v_cndmask_b32_e32 v60, v35, v36, vcc
	v_cndmask_b32_e32 v61, v45, v47, vcc
	v_cndmask_b32_e32 v62, v41, v43, vcc
	v_cndmask_b32_e32 v63, v37, v39, vcc
	v_cndmask_b32_e32 v84, v30, v31, vcc
	v_cmp_eq_u32_e32 vcc, 0, v54
	s_nop 1
	v_cndmask_b32_e32 v54, v18, v17, vcc
	v_cndmask_b32_e32 v85, v20, v19, vcc
	v_cndmask_b32_e32 v86, v22, v21, vcc
	v_cndmask_b32_e32 v87, v24, v23, vcc
	v_cndmask_b32_e32 v88, v26, v25, vcc
	v_cndmask_b32_e32 v89, v44, v46, vcc
	v_cndmask_b32_e32 v90, v40, v42, vcc
	v_cndmask_b32_e32 v91, v16, v38, vcc
	v_cmp_eq_u32_e32 vcc, 0, v52
	s_nop 1
	v_cndmask_b32_e32 v50, v58, v50, vcc
	v_cndmask_b32_e32 v52, v60, v59, vcc
	v_cndmask_b32_e32 v58, v62, v61, vcc
	v_cndmask_b32_e32 v59, v84, v63, vcc
	v_cmp_eq_u32_e32 vcc, 0, v55
	s_nop 1
	v_cndmask_b32_e32 v54, v85, v54, vcc
	v_cndmask_b32_e32 v55, v87, v86, vcc
	v_cndmask_b32_e32 v60, v89, v88, vcc
	v_cndmask_b32_e32 v61, v91, v90, vcc
	v_cmp_eq_u32_e32 vcc, 0, v53
	s_nop 1
	v_cndmask_b32_e32 v50, v52, v50, vcc
	v_cndmask_b32_e32 v52, v59, v58, vcc
	v_cmp_eq_u32_e32 vcc, 0, v56
	v_bitop3_b32 v56, v9, 4, v9 bitop3:0xc
	s_nop 0
	v_cndmask_b32_e32 v53, v55, v54, vcc
	v_cndmask_b32_e32 v54, v61, v60, vcc
	v_cmp_gt_u32_e32 vcc, s80, v6
	v_bitop3_b32 v55, v9, 2, v9 bitop3:0xc
	s_nop 0
	v_cndmask_b32_e32 v6, v52, v50, vcc
	v_cmp_eq_u32_e32 vcc, 0, v57
	v_lshlrev_b32_e32 v6, 7, v6
	v_and_b32_e32 v6, 0x3f80, v6
	v_cndmask_b32_e32 v50, v54, v53, vcc
	v_and_b32_e32 v50, 0x7f, v50
	v_bitop3_b32 v6, v6, s81, v50 bitop3:0x36
	v_and_b32_e32 v50, 0x7fffff00, v49
	v_bitop3_b32 v52, v49, s79, v49 bitop3:0xcf
	v_cmp_gt_i32_e32 vcc, 0, v49
	v_bitop3_b32 v54, v9, 1, v9 bitop3:0xc
	v_bitop3_b32 v53, v9, 64, v9 bitop3:0xc
	v_cndmask_b32_e32 v49, v52, v50, vcc
	v_cmp_eq_u32_e32 vcc, 0, v11
	v_bitop3_b32 v52, v9, 32, v9 bitop3:0xc
	v_bitop3_b32 v50, v9, s79, v9 bitop3:0xc
	v_cndmask_b32_e32 v11, v29, v34, vcc
	v_cndmask_b32_e32 v27, v27, v28, vcc
	v_cndmask_b32_e32 v7, v14, v7, vcc
	v_cndmask_b32_e32 v14, v35, v36, vcc
	v_cndmask_b32_e32 v28, v45, v47, vcc
	v_cndmask_b32_e32 v29, v41, v43, vcc
	v_cndmask_b32_e32 v34, v37, v39, vcc
	v_cndmask_b32_e32 v30, v30, v31, vcc
	v_cmp_eq_u32_e32 vcc, 0, v54
	v_bitop3_b32 v57, v9, 8, v9 bitop3:0xc
	s_nop 0
	v_cndmask_b32_e32 v17, v18, v17, vcc
	v_cndmask_b32_e32 v18, v20, v19, vcc
	v_cndmask_b32_e32 v19, v22, v21, vcc
	v_cndmask_b32_e32 v20, v24, v23, vcc
	v_cndmask_b32_e32 v21, v26, v25, vcc
	v_cndmask_b32_e32 v22, v44, v46, vcc
	v_cndmask_b32_e32 v23, v40, v42, vcc
	v_cndmask_b32_e32 v16, v16, v38, vcc
	v_cmp_eq_u32_e32 vcc, 0, v52
	s_nop 1
	v_cndmask_b32_e32 v11, v27, v11, vcc
	v_cndmask_b32_e32 v7, v14, v7, vcc
	v_cndmask_b32_e32 v14, v29, v28, vcc
	v_cndmask_b32_e32 v24, v30, v34, vcc
	v_cmp_eq_u32_e32 vcc, 0, v55
	s_nop 1
	v_cndmask_b32_e32 v17, v18, v17, vcc
	v_cndmask_b32_e32 v18, v20, v19, vcc
	v_cndmask_b32_e32 v19, v22, v21, vcc
	v_cndmask_b32_e32 v16, v16, v23, vcc
	v_cmp_eq_u32_e32 vcc, 0, v53
	s_nop 1
	v_cndmask_b32_e32 v7, v7, v11, vcc
	v_cndmask_b32_e32 v20, v24, v14, vcc
	v_cmp_eq_u32_e32 vcc, 0, v56
	v_and_b32_e32 v14, 0xffffff00, v9
	v_and_b32_e32 v11, 0xffffff00, v8
	v_cndmask_b32_e32 v17, v18, v17, vcc
	v_cndmask_b32_e32 v16, v16, v19, vcc
	v_and_b32_e32 v19, 0x7fffff00, v9
	v_xor_b32_e32 v14, -1, v14
	v_cmp_gt_i32_e32 vcc, 0, v9
	v_and_b32_e32 v18, 0x7fffff00, v8
	v_xor_b32_e32 v11, -1, v11
	v_cndmask_b32_e32 v19, v14, v19, vcc
	v_cmp_gt_i32_e32 vcc, 0, v8
	s_nop 1
	v_cndmask_b32_e32 v18, v11, v18, vcc
	v_sub_f32_e32 v8, v10, v18
	v_mul_f32_e32 v8, 0x3fb8aa3b, v8
	v_sub_f32_e32 v9, v48, v18
	v_exp_f32_e32 v8, v8
	v_mul_f32_e32 v9, 0x3fb8aa3b, v9
	v_sub_f32_e32 v10, v51, v18
	v_exp_f32_e32 v9, v9
	v_mul_f32_e32 v10, 0x3fb8aa3b, v10
	v_sub_f32_e32 v11, v12, v18
	v_exp_f32_e32 v10, v10
	v_mul_f32_e32 v11, 0x3fb8aa3b, v11
	v_exp_f32_e32 v11, v11
	v_add_f32_e32 v12, 0, v8
	v_add_f32_e32 v12, v9, v12
	v_add_f32_e32 v12, v10, v12
	v_add_f32_e32 v21, v11, v12
	v_sub_f32_e32 v12, v13, v18
	v_mul_f32_e32 v12, 0x3fb8aa3b, v12
	v_sub_f32_e32 v13, v15, v18
	v_exp_f32_e32 v12, v12
	v_mul_f32_e32 v13, 0x3fb8aa3b, v13
	v_sub_f32_e32 v14, v49, v18
	v_exp_f32_e32 v13, v13
	v_mul_f32_e32 v14, 0x3fb8aa3b, v14
	v_sub_f32_e32 v15, v19, v18
	v_exp_f32_e32 v14, v14
	v_mul_f32_e32 v15, 0x3fb8aa3b, v15
	v_exp_f32_e32 v15, v15
	v_add_f32_e32 v18, v12, v21
	v_add_f32_e32 v18, v13, v18
	v_add_f32_e32 v18, v14, v18
	v_add_f32_e32 v18, v15, v18
	ds_bpermute_b32 v19, v33, v18
	v_cmp_gt_u32_e32 vcc, s80, v50
	v_ashrrev_i32_e32 v33, 31, v32
	s_nop 0
	v_cndmask_b32_e32 v7, v20, v7, vcc
	v_cmp_eq_u32_e32 vcc, 0, v57
	v_lshlrev_b32_e32 v7, 7, v7
	v_and_b32_e32 v7, 0x3f80, v7
	v_cndmask_b32_e32 v16, v16, v17, vcc
	s_waitcnt lgkmcnt(0)
	v_add_f32_e32 v17, v18, v19
	v_div_scale_f32 v18, s[28:29], v17, v17, 1.0
	v_rcp_f32_e32 v19, v18
	v_and_b32_e32 v16, 0x7f, v16
	v_bitop3_b32 v7, v7, s81, v16 bitop3:0x36
	s_lshl_b32 s28, s83, 4
	v_fma_f32 v16, -v18, v19, 1.0
	v_fmac_f32_e32 v19, v16, v19
	v_div_scale_f32 v16, vcc, 1.0, v17, 1.0
	v_mul_f32_e32 v20, v16, v19
	v_fma_f32 v21, -v18, v20, v16
	v_fmac_f32_e32 v20, v21, v19
	v_fma_f32 v16, -v18, v20, v16
	v_div_fmas_f32 v16, v16, v19, v20
	v_lshlrev_b64 v[18:19], 9, v[32:33]
	s_ashr_i32 s29, s28, 31
	v_lshl_add_u64 v[20:21], s[46:47], 0, v[18:19]
	s_lshl_b64 s[28:29], s[28:29], 2
	v_lshl_add_u64 v[20:21], v[20:21], 0, s[28:29]
	v_lshl_add_u64 v[18:19], s[44:45], 0, v[18:19]
	v_div_fixup_f32 v16, v16, v17, 1.0
	v_lshl_add_u64 v[20:21], v[20:21], 0, v[82:83]
	v_lshl_add_u64 v[18:19], v[18:19], 0, s[28:29]
	s_cmpk_lt_i32 s16, 0x400
	v_lshl_add_u64 v[18:19], v[18:19], 0, v[82:83]
	v_pk_mul_f32 v[10:11], v[10:11], v[16:17] op_sel_hi:[1,0]
	v_pk_mul_f32 v[8:9], v[8:9], v[16:17] op_sel_hi:[1,0]
	global_store_dwordx4 v[20:21], v[0:3], off
	global_store_dwordx4 v[18:19], v[8:11], off
	s_nop 0
	v_pk_mul_f32 v[2:3], v[14:15], v[16:17] op_sel_hi:[1,0]
	v_pk_mul_f32 v[0:1], v[12:13], v[16:17] op_sel_hi:[1,0]
	global_store_dwordx4 v[20:21], v[4:7], off offset:16
	global_store_dwordx4 v[18:19], v[0:3], off offset:16
	s_barrier
	s_cbranch_scc0 .LBB0_655
